# packed f32 VALU ops (v_pk_mul/add/fma_f32) replaced by the two equivalent scalar f32 ops everywhere outside the MLA loops; bit-identical
# speedup vs baseline: 1.0030x; 1.0030x over previous
.LBB0_36:
	s_or_b64 exec, exec, s[4:5]
	v_cndmask_b32_e64 v3, 0, 1, s[52:53]
	v_cmp_ne_u32_e64 s[8:9], 1, v3
	s_andn2_b64 vcc, exec, s[52:53]
	s_cbranch_vccnz .LBB0_38
	v_ashrrev_i32_e32 v29, 31, v28
	v_lshl_add_u64 v[4:5], v[28:29], 2, s[86:87]
	global_load_dwordx2 v[4:5], v[4:5], off
	s_waitcnt vmcnt(0)
	v_mul_f32_e32 v12, v12, v4
	v_mul_f32_e32 v13, v13, v4
	v_mul_f32_e32 v10, v10, v4
	v_mul_f32_e32 v11, v11, v4
	v_mul_f32_e32 v8, v8, v5
	v_mul_f32_e32 v9, v9, v5
	v_mul_f32_e32 v6, v6, v5
	v_mul_f32_e32 v7, v7, v5

.LBB0_40:
	s_or_b64 exec, exec, s[4:5]
	s_and_b64 vcc, exec, s[8:9]
	s_cbranch_vccnz .LBB0_42
	v_ashrrev_i32_e32 v31, 31, v30
	v_lshl_add_u64 v[4:5], v[30:31], 2, s[86:87]
	global_load_dwordx2 v[4:5], v[4:5], off
	s_waitcnt vmcnt(0)
	v_mul_f32_e32 v12, v12, v4
	v_mul_f32_e32 v13, v13, v4
	v_mul_f32_e32 v10, v10, v4
	v_mul_f32_e32 v11, v11, v4
	v_mul_f32_e32 v8, v8, v5
	v_mul_f32_e32 v9, v9, v5
	v_mul_f32_e32 v6, v6, v5
	v_mul_f32_e32 v7, v7, v5

.LBB0_48:
	s_or_b64 exec, exec, s[4:5]
	s_and_b64 vcc, exec, s[8:9]
	s_cbranch_vccnz .LBB0_33
	v_ashrrev_i32_e32 v31, 31, v30
	v_lshl_add_u64 v[4:5], v[30:31], 2, s[86:87]
	global_load_dwordx2 v[4:5], v[4:5], off
	s_waitcnt vmcnt(0)
	v_mul_f32_e32 v12, v12, v4
	v_mul_f32_e32 v13, v13, v4
	v_mul_f32_e32 v10, v10, v4
	v_mul_f32_e32 v11, v11, v4
	v_mul_f32_e32 v8, v8, v5
	v_mul_f32_e32 v9, v9, v5
	v_mul_f32_e32 v6, v6, v5
	v_mul_f32_e32 v7, v7, v5
	s_branch .LBB0_33

.LBB0_59:
	s_or_b64 exec, exec, s[4:5]
	v_cndmask_b32_e64 v3, 0, 1, s[54:55]
	v_cmp_ne_u32_e64 s[8:9], 1, v3
	s_andn2_b64 vcc, exec, s[54:55]
	s_cbranch_vccnz .LBB0_61
	v_lshl_add_u64 v[4:5], v[28:29], 2, s[86:87]
	global_load_dwordx2 v[4:5], v[4:5], off
	s_waitcnt vmcnt(0)
	v_mul_f32_e32 v12, v12, v4
	v_mul_f32_e32 v13, v13, v4
	v_mul_f32_e32 v10, v10, v4
	v_mul_f32_e32 v11, v11, v4
	v_mul_f32_e32 v8, v8, v5
	v_mul_f32_e32 v9, v9, v5
	v_mul_f32_e32 v6, v6, v5
	v_mul_f32_e32 v7, v7, v5

.LBB0_63:
	s_or_b64 exec, exec, s[4:5]
	s_and_b64 vcc, exec, s[8:9]
	s_cbranch_vccnz .LBB0_65
	v_lshl_add_u64 v[4:5], v[30:31], 2, s[86:87]
	global_load_dwordx2 v[4:5], v[4:5], off
	s_waitcnt vmcnt(0)
	v_mul_f32_e32 v12, v12, v4
	v_mul_f32_e32 v13, v13, v4
	v_mul_f32_e32 v10, v10, v4
	v_mul_f32_e32 v11, v11, v4
	v_mul_f32_e32 v8, v8, v5
	v_mul_f32_e32 v9, v9, v5
	v_mul_f32_e32 v6, v6, v5
	v_mul_f32_e32 v7, v7, v5

.LBB0_71:
	s_or_b64 exec, exec, s[4:5]
	s_and_b64 vcc, exec, s[8:9]
	s_cbranch_vccnz .LBB0_56
	v_lshl_add_u64 v[4:5], v[30:31], 2, s[86:87]
	global_load_dwordx2 v[4:5], v[4:5], off
	s_waitcnt vmcnt(0)
	v_mul_f32_e32 v12, v12, v4
	v_mul_f32_e32 v13, v13, v4
	v_mul_f32_e32 v10, v10, v4
	v_mul_f32_e32 v11, v11, v4
	v_mul_f32_e32 v8, v8, v5
	v_mul_f32_e32 v9, v9, v5
	v_mul_f32_e32 v6, v6, v5
	v_mul_f32_e32 v7, v7, v5
	s_branch .LBB0_56

.LBB0_82:
	s_or_b64 exec, exec, s[4:5]
	v_cndmask_b32_e64 v3, 0, 1, s[56:57]
	v_cmp_ne_u32_e64 s[8:9], 1, v3
	s_andn2_b64 vcc, exec, s[56:57]
	s_cbranch_vccnz .LBB0_84
	v_mov_b32_e32 v4, v28
	v_mov_b32_e32 v5, v2
	v_cmp_lt_i32_e32 vcc, s14, v28
	v_lshl_add_u64 v[4:5], v[4:5], 2, s[88:89]
	v_lshl_add_u64 v[30:31], v[4:5], 0, s[60:61]
	v_lshl_add_u64 v[44:45], v[28:29], 2, s[86:87]
	s_and_b64 vcc, s[58:59], vcc
	v_cndmask_b32_e32 v31, v45, v31, vcc
	v_cndmask_b32_e32 v30, v44, v30, vcc
	v_cmp_lt_i32_e32 vcc, s15, v28
	v_lshl_add_u64 v[4:5], v[4:5], 0, s[62:63]
	v_lshl_add_u64 v[44:45], v[44:45], 0, 4
	s_and_b64 vcc, s[58:59], vcc
	v_cndmask_b32_e32 v5, v45, v5, vcc
	v_cndmask_b32_e32 v4, v44, v4, vcc
	global_load_dword v30, v[30:31], off
	s_waitcnt vmcnt(0)
	v_mul_f32_e32 v12, v12, v30
	v_mul_f32_e32 v13, v13, v30
	global_load_dword v4, v[4:5], off
	v_mul_f32_e32 v10, v10, v30
	v_mul_f32_e32 v11, v11, v30
	s_waitcnt vmcnt(0)
	v_mul_f32_e32 v8, v8, v4
	v_mul_f32_e32 v9, v9, v4
	v_mul_f32_e32 v6, v6, v4
	v_mul_f32_e32 v7, v7, v4

.LBB0_86:
	s_or_b64 exec, exec, s[4:5]
	s_and_b64 vcc, exec, s[8:9]
	s_cbranch_vccnz .LBB0_88
	v_mov_b32_e32 v4, v30
	v_mov_b32_e32 v5, v2
	v_cmp_lt_i32_e32 vcc, s14, v30
	v_lshl_add_u64 v[4:5], v[4:5], 2, s[88:89]
	v_lshl_add_u64 v[44:45], v[4:5], 0, s[60:61]
	v_lshl_add_u64 v[46:47], v[30:31], 2, s[86:87]
	s_and_b64 vcc, s[58:59], vcc
	v_cndmask_b32_e32 v45, v47, v45, vcc
	v_cndmask_b32_e32 v44, v46, v44, vcc
	v_cmp_lt_i32_e32 vcc, s15, v30
	v_lshl_add_u64 v[4:5], v[4:5], 0, s[62:63]
	v_lshl_add_u64 v[30:31], v[46:47], 0, 4
	s_and_b64 vcc, s[58:59], vcc
	v_cndmask_b32_e32 v5, v31, v5, vcc
	v_cndmask_b32_e32 v4, v30, v4, vcc
	global_load_dword v44, v[44:45], off
	s_waitcnt vmcnt(0)
	v_mul_f32_e32 v12, v12, v44
	v_mul_f32_e32 v13, v13, v44
	global_load_dword v4, v[4:5], off
	v_mul_f32_e32 v10, v10, v44
	v_mul_f32_e32 v11, v11, v44
	s_waitcnt vmcnt(0)
	v_mul_f32_e32 v8, v8, v4
	v_mul_f32_e32 v9, v9, v4
	v_mul_f32_e32 v6, v6, v4
	v_mul_f32_e32 v7, v7, v4

.LBB0_94:
	s_or_b64 exec, exec, s[4:5]
	s_and_b64 vcc, exec, s[8:9]
	s_cbranch_vccnz .LBB0_79
	v_mov_b32_e32 v4, v30
	v_mov_b32_e32 v5, v2
	v_cmp_lt_i32_e32 vcc, s14, v30
	v_lshl_add_u64 v[4:5], v[4:5], 2, s[88:89]
	v_lshl_add_u64 v[28:29], v[4:5], 0, s[60:61]
	v_lshl_add_u64 v[44:45], v[30:31], 2, s[86:87]
	s_and_b64 vcc, s[58:59], vcc
	v_cndmask_b32_e32 v29, v45, v29, vcc
	v_cndmask_b32_e32 v28, v44, v28, vcc
	v_cmp_lt_i32_e32 vcc, s15, v30
	v_lshl_add_u64 v[4:5], v[4:5], 0, s[62:63]
	v_lshl_add_u64 v[30:31], v[44:45], 0, 4
	s_and_b64 vcc, s[58:59], vcc
	v_cndmask_b32_e32 v5, v31, v5, vcc
	v_cndmask_b32_e32 v4, v30, v4, vcc
	global_load_dword v28, v[28:29], off
	s_waitcnt vmcnt(0)
	v_mul_f32_e32 v12, v12, v28
	v_mul_f32_e32 v13, v13, v28
	global_load_dword v4, v[4:5], off
	v_mul_f32_e32 v10, v10, v28
	v_mul_f32_e32 v11, v11, v28
	s_waitcnt vmcnt(0)
	v_mul_f32_e32 v8, v8, v4
	v_mul_f32_e32 v9, v9, v4
	v_mul_f32_e32 v6, v6, v4
	v_mul_f32_e32 v7, v7, v4
	s_branch .LBB0_79

.LBB0_211:
	s_add_u32 s52, s72, vcc_lo
	s_addc_u32 s53, s73, vcc_hi
	v_lshlrev_b64 v[144:145], 2, v[134:135]
	v_lshl_add_u64 v[146:147], s[52:53], 0, v[144:145]
	v_mad_i64_i32 v[148:149], s[52:53], s92, v142, 0
	s_add_u32 s96, s72, s96
	v_lshlrev_b64 v[154:155], 2, v[148:149]
	v_lshl_add_u64 v[148:149], v[146:147], 0, v[154:155]
	s_addc_u32 s97, s73, s97
	global_load_dwordx4 v[150:153], v[148:149], off
	v_lshl_add_u64 v[148:149], s[96:97], 0, v[144:145]
	v_lshl_add_u64 v[144:145], v[148:149], 0, v[154:155]
	global_load_dwordx4 v[166:169], v[144:145], off
	v_mov_b32_e32 v134, v143
	v_ashrrev_i32_e32 v143, 31, v142
	s_mov_b64 s[52:53], -1
	v_lshl_add_u64 v[144:145], v[134:135], 1, s[10:11]
	s_and_b64 vcc, exec, s[94:95]
	s_waitcnt vmcnt(0)
	v_mul_f32_e32 v154, v124, v152
	v_mul_f32_e32 v155, v125, v153
	v_mul_f32_e32 v156, v122, v150
	v_mul_f32_e32 v157, v123, v151
	v_mul_f32_e32 v152, v128, v152
	v_mul_f32_e32 v153, v129, v153
	v_mul_f32_e32 v158, v126, v150
	v_mul_f32_e32 v159, v127, v151
	v_fma_f32 v150, v128, v168, -v154
	v_fma_f32 v151, v129, v169, -v155
	v_fma_f32 v156, v126, v166, -v156
	v_fma_f32 v157, v127, v167, -v157
	v_fmac_f32_e32 v152, v124, v168
	v_fmac_f32_e32 v153, v125, v169
	v_fma_f32 v154, v122, v166, v158
	v_fma_f32 v155, v123, v167, v159
	s_cbranch_vccz .LBB0_213
	v_mul_lo_u32 v165, s91, v142
	v_mul_lo_u32 v168, s90, v143
	v_mad_u64_u32 v[166:167], s[10:11], s90, v142, 0
	v_add3_u32 v167, v167, v168, v165
	v_lshl_add_u64 v[166:167], v[166:167], 1, v[144:145]
	s_lshl_b32 s26, s92, 1
	v_cvt_pk_bf16_f32 v158, v156, v157
	v_cvt_pk_bf16_f32 v159, v150, v151
	global_store_dwordx2 v[166:167], v[158:159], off
	v_lshl_add_u64 v[166:167], v[166:167], 0, s[26:27]
	v_cvt_pk_bf16_f32 v158, v154, v155
	v_cvt_pk_bf16_f32 v159, v152, v153
	global_store_dwordx2 v[166:167], v[158:159], off
	s_mov_b64 s[52:53], 0

.LBB0_215:
	v_or_b32_e32 v150, 16, v142
	v_mad_i64_i32 v[152:153], s[10:11], s92, v150, 0
	v_lshlrev_b64 v[156:157], 2, v[152:153]
	v_lshl_add_u64 v[152:153], v[146:147], 0, v[156:157]
	global_load_dwordx4 v[152:155], v[152:153], off
	v_lshl_add_u64 v[156:157], v[148:149], 0, v[156:157]
	global_load_dwordx4 v[166:169], v[156:157], off
	v_cndmask_b32_e64 v143, 0, 1, s[94:95]
	v_ashrrev_i32_e32 v151, 31, v150
	v_cmp_ne_u32_e64 s[10:11], 1, v143
	s_andn2_b64 vcc, exec, s[94:95]
	s_mov_b64 s[52:53], -1
	s_waitcnt vmcnt(1)
	v_mul_f32_e32 v156, v116, v154
	v_mul_f32_e32 v157, v117, v155
	v_mul_f32_e32 v158, v114, v152
	v_mul_f32_e32 v159, v115, v153
	v_mul_f32_e32 v154, v120, v154
	v_mul_f32_e32 v155, v121, v155
	v_mul_f32_e32 v170, v118, v152
	v_mul_f32_e32 v171, v119, v153
	s_waitcnt vmcnt(0)
	v_fma_f32 v152, v120, v168, -v156
	v_fma_f32 v153, v121, v169, -v157
	v_fma_f32 v158, v118, v166, -v158
	v_fma_f32 v159, v119, v167, -v159
	v_fmac_f32_e32 v154, v116, v168
	v_fmac_f32_e32 v155, v117, v169
	v_fma_f32 v156, v114, v166, v170
	v_fma_f32 v157, v115, v167, v171
	s_cbranch_vccnz .LBB0_217
	v_mul_lo_u32 v143, s91, v150
	v_mul_lo_u32 v165, s90, v151
	v_mad_u64_u32 v[168:169], s[52:53], s90, v150, 0
	v_add3_u32 v169, v169, v165, v143
	v_lshl_add_u64 v[168:169], v[168:169], 1, v[144:145]
	s_lshl_b32 s26, s92, 1
	v_cvt_pk_bf16_f32 v166, v158, v159
	v_cvt_pk_bf16_f32 v167, v152, v153
	global_store_dwordx2 v[168:169], v[166:167], off
	v_lshl_add_u64 v[168:169], v[168:169], 0, s[26:27]
	s_mov_b64 s[52:53], 0
	v_cvt_pk_bf16_f32 v166, v156, v157
	v_cvt_pk_bf16_f32 v167, v154, v155
	global_store_dwordx2 v[168:169], v[166:167], off

.LBB0_219:
	v_or_b32_e32 v150, 32, v142
	v_mad_i64_i32 v[152:153], s[52:53], s92, v150, 0
	v_lshlrev_b64 v[156:157], 2, v[152:153]
	v_lshl_add_u64 v[152:153], v[146:147], 0, v[156:157]
	global_load_dwordx4 v[152:155], v[152:153], off
	v_lshl_add_u64 v[156:157], v[148:149], 0, v[156:157]
	global_load_dwordx4 v[166:169], v[156:157], off
	s_and_b64 vcc, exec, s[10:11]
	v_ashrrev_i32_e32 v151, 31, v150
	s_mov_b64 s[52:53], -1
	s_waitcnt vmcnt(1)
	v_mul_f32_e32 v156, v108, v154
	v_mul_f32_e32 v157, v109, v155
	v_mul_f32_e32 v158, v106, v152
	v_mul_f32_e32 v159, v107, v153
	v_mul_f32_e32 v154, v112, v154
	v_mul_f32_e32 v155, v113, v155
	v_mul_f32_e32 v170, v110, v152
	v_mul_f32_e32 v171, v111, v153
	s_waitcnt vmcnt(0)
	v_fma_f32 v152, v112, v168, -v156
	v_fma_f32 v153, v113, v169, -v157
	v_fma_f32 v158, v110, v166, -v158
	v_fma_f32 v159, v111, v167, -v159
	v_fmac_f32_e32 v154, v108, v168
	v_fmac_f32_e32 v155, v109, v169
	v_fma_f32 v156, v106, v166, v170
	v_fma_f32 v157, v107, v167, v171
	s_cbranch_vccnz .LBB0_221
	v_mul_lo_u32 v143, s91, v150
	v_mul_lo_u32 v165, s90, v151
	v_mad_u64_u32 v[168:169], s[52:53], s90, v150, 0
	v_add3_u32 v169, v169, v165, v143
	v_lshl_add_u64 v[168:169], v[168:169], 1, v[144:145]
	s_lshl_b32 s26, s92, 1
	v_cvt_pk_bf16_f32 v166, v158, v159
	v_cvt_pk_bf16_f32 v167, v152, v153
	global_store_dwordx2 v[168:169], v[166:167], off
	v_lshl_add_u64 v[168:169], v[168:169], 0, s[26:27]
	s_mov_b64 s[52:53], 0
	v_cvt_pk_bf16_f32 v166, v156, v157
	v_cvt_pk_bf16_f32 v167, v154, v155
	global_store_dwordx2 v[168:169], v[166:167], off

.LBB0_223:
	v_or_b32_e32 v150, 48, v142
	v_mad_i64_i32 v[152:153], s[52:53], s92, v150, 0
	v_lshlrev_b64 v[156:157], 2, v[152:153]
	v_lshl_add_u64 v[152:153], v[146:147], 0, v[156:157]
	global_load_dwordx4 v[152:155], v[152:153], off
	v_lshl_add_u64 v[156:157], v[148:149], 0, v[156:157]
	global_load_dwordx4 v[166:169], v[156:157], off
	s_and_b64 vcc, exec, s[10:11]
	v_ashrrev_i32_e32 v151, 31, v150
	s_mov_b64 s[52:53], -1
	s_waitcnt vmcnt(1)
	v_mul_f32_e32 v156, v100, v154
	v_mul_f32_e32 v157, v101, v155
	v_mul_f32_e32 v158, v98, v152
	v_mul_f32_e32 v159, v99, v153
	v_mul_f32_e32 v154, v104, v154
	v_mul_f32_e32 v155, v105, v155
	v_mul_f32_e32 v170, v102, v152
	v_mul_f32_e32 v171, v103, v153
	s_waitcnt vmcnt(0)
	v_fma_f32 v152, v104, v168, -v156
	v_fma_f32 v153, v105, v169, -v157
	v_fma_f32 v158, v102, v166, -v158
	v_fma_f32 v159, v103, v167, -v159
	v_fmac_f32_e32 v154, v100, v168
	v_fmac_f32_e32 v155, v101, v169
	v_fma_f32 v156, v98, v166, v170
	v_fma_f32 v157, v99, v167, v171
	s_cbranch_vccnz .LBB0_225
	v_mul_lo_u32 v143, s91, v150
	v_mul_lo_u32 v165, s90, v151
	v_mad_u64_u32 v[168:169], s[52:53], s90, v150, 0
	v_add3_u32 v169, v169, v165, v143
	v_lshl_add_u64 v[168:169], v[168:169], 1, v[144:145]
	s_lshl_b32 s26, s92, 1
	v_cvt_pk_bf16_f32 v166, v158, v159
	v_cvt_pk_bf16_f32 v167, v152, v153
	global_store_dwordx2 v[168:169], v[166:167], off
	v_lshl_add_u64 v[168:169], v[168:169], 0, s[26:27]
	s_mov_b64 s[52:53], 0
	v_cvt_pk_bf16_f32 v166, v156, v157
	v_cvt_pk_bf16_f32 v167, v154, v155
	global_store_dwordx2 v[168:169], v[166:167], off

.LBB0_227:
	v_add_u32_e32 v150, 0x80, v142
	v_mad_i64_i32 v[152:153], s[52:53], s92, v150, 0
	v_lshlrev_b64 v[156:157], 2, v[152:153]
	v_lshl_add_u64 v[152:153], v[146:147], 0, v[156:157]
	global_load_dwordx4 v[152:155], v[152:153], off
	v_lshl_add_u64 v[156:157], v[148:149], 0, v[156:157]
	global_load_dwordx4 v[166:169], v[156:157], off
	s_and_b64 vcc, exec, s[10:11]
	v_ashrrev_i32_e32 v151, 31, v150
	s_mov_b64 s[52:53], -1
	s_waitcnt vmcnt(1)
	v_mul_f32_e32 v156, v92, v154
	v_mul_f32_e32 v157, v93, v155
	v_mul_f32_e32 v158, v90, v152
	v_mul_f32_e32 v159, v91, v153
	v_mul_f32_e32 v154, v96, v154
	v_mul_f32_e32 v155, v97, v155
	v_mul_f32_e32 v170, v94, v152
	v_mul_f32_e32 v171, v95, v153
	s_waitcnt vmcnt(0)
	v_fma_f32 v152, v96, v168, -v156
	v_fma_f32 v153, v97, v169, -v157
	v_fma_f32 v158, v94, v166, -v158
	v_fma_f32 v159, v95, v167, -v159
	v_fmac_f32_e32 v154, v92, v168
	v_fmac_f32_e32 v155, v93, v169
	v_fma_f32 v156, v90, v166, v170
	v_fma_f32 v157, v91, v167, v171
	s_cbranch_vccnz .LBB0_229
	v_mul_lo_u32 v143, s91, v150
	v_mul_lo_u32 v165, s90, v151
	v_mad_u64_u32 v[168:169], s[52:53], s90, v150, 0
	v_add3_u32 v169, v169, v165, v143
	v_lshl_add_u64 v[168:169], v[168:169], 1, v[144:145]
	s_lshl_b32 s26, s92, 1
	v_cvt_pk_bf16_f32 v166, v158, v159
	v_cvt_pk_bf16_f32 v167, v152, v153
	global_store_dwordx2 v[168:169], v[166:167], off
	v_lshl_add_u64 v[168:169], v[168:169], 0, s[26:27]
	s_mov_b64 s[52:53], 0
	v_cvt_pk_bf16_f32 v166, v156, v157
	v_cvt_pk_bf16_f32 v167, v154, v155
	global_store_dwordx2 v[168:169], v[166:167], off

.LBB0_231:
	v_add_u32_e32 v150, 0x90, v142
	v_mad_i64_i32 v[152:153], s[52:53], s92, v150, 0
	v_lshlrev_b64 v[156:157], 2, v[152:153]
	v_lshl_add_u64 v[152:153], v[146:147], 0, v[156:157]
	global_load_dwordx4 v[152:155], v[152:153], off
	v_lshl_add_u64 v[156:157], v[148:149], 0, v[156:157]
	global_load_dwordx4 v[166:169], v[156:157], off
	s_and_b64 vcc, exec, s[10:11]
	v_ashrrev_i32_e32 v151, 31, v150
	s_mov_b64 s[52:53], -1
	s_waitcnt vmcnt(1)
	v_mul_f32_e32 v156, v84, v154
	v_mul_f32_e32 v157, v85, v155
	v_mul_f32_e32 v158, v82, v152
	v_mul_f32_e32 v159, v83, v153
	v_mul_f32_e32 v154, v88, v154
	v_mul_f32_e32 v155, v89, v155
	v_mul_f32_e32 v170, v86, v152
	v_mul_f32_e32 v171, v87, v153
	s_waitcnt vmcnt(0)
	v_fma_f32 v152, v88, v168, -v156
	v_fma_f32 v153, v89, v169, -v157
	v_fma_f32 v158, v86, v166, -v158
	v_fma_f32 v159, v87, v167, -v159
	v_fmac_f32_e32 v154, v84, v168
	v_fmac_f32_e32 v155, v85, v169
	v_fma_f32 v156, v82, v166, v170
	v_fma_f32 v157, v83, v167, v171
	s_cbranch_vccnz .LBB0_233
	v_mul_lo_u32 v143, s91, v150
	v_mul_lo_u32 v165, s90, v151
	v_mad_u64_u32 v[168:169], s[52:53], s90, v150, 0
	v_add3_u32 v169, v169, v165, v143
	v_lshl_add_u64 v[168:169], v[168:169], 1, v[144:145]
	s_lshl_b32 s26, s92, 1
	v_cvt_pk_bf16_f32 v166, v158, v159
	v_cvt_pk_bf16_f32 v167, v152, v153
	global_store_dwordx2 v[168:169], v[166:167], off
	v_lshl_add_u64 v[168:169], v[168:169], 0, s[26:27]
	s_mov_b64 s[52:53], 0
	v_cvt_pk_bf16_f32 v166, v156, v157
	v_cvt_pk_bf16_f32 v167, v154, v155
	global_store_dwordx2 v[168:169], v[166:167], off

.LBB0_235:
	v_add_u32_e32 v150, 0xa0, v142
	v_mad_i64_i32 v[152:153], s[52:53], s92, v150, 0
	v_lshlrev_b64 v[156:157], 2, v[152:153]
	v_lshl_add_u64 v[152:153], v[146:147], 0, v[156:157]
	global_load_dwordx4 v[152:155], v[152:153], off
	v_lshl_add_u64 v[156:157], v[148:149], 0, v[156:157]
	global_load_dwordx4 v[166:169], v[156:157], off
	s_and_b64 vcc, exec, s[10:11]
	v_ashrrev_i32_e32 v151, 31, v150
	s_mov_b64 s[52:53], -1
	s_waitcnt vmcnt(1)
	v_mul_f32_e32 v156, v76, v154
	v_mul_f32_e32 v157, v77, v155
	v_mul_f32_e32 v158, v74, v152
	v_mul_f32_e32 v159, v75, v153
	v_mul_f32_e32 v154, v80, v154
	v_mul_f32_e32 v155, v81, v155
	v_mul_f32_e32 v170, v78, v152
	v_mul_f32_e32 v171, v79, v153
	s_waitcnt vmcnt(0)
	v_fma_f32 v152, v80, v168, -v156
	v_fma_f32 v153, v81, v169, -v157
	v_fma_f32 v158, v78, v166, -v158
	v_fma_f32 v159, v79, v167, -v159
	v_fmac_f32_e32 v154, v76, v168
	v_fmac_f32_e32 v155, v77, v169
	v_fma_f32 v156, v74, v166, v170
	v_fma_f32 v157, v75, v167, v171
	s_cbranch_vccnz .LBB0_237
	v_mul_lo_u32 v143, s91, v150
	v_mul_lo_u32 v165, s90, v151
	v_mad_u64_u32 v[168:169], s[52:53], s90, v150, 0
	v_add3_u32 v169, v169, v165, v143
	v_lshl_add_u64 v[168:169], v[168:169], 1, v[144:145]
	s_lshl_b32 s26, s92, 1
	v_cvt_pk_bf16_f32 v166, v158, v159
	v_cvt_pk_bf16_f32 v167, v152, v153
	global_store_dwordx2 v[168:169], v[166:167], off
	v_lshl_add_u64 v[168:169], v[168:169], 0, s[26:27]
	s_mov_b64 s[52:53], 0
	v_cvt_pk_bf16_f32 v166, v156, v157
	v_cvt_pk_bf16_f32 v167, v154, v155
	global_store_dwordx2 v[168:169], v[166:167], off

.LBB0_239:
	v_add_u32_e32 v150, 0xb0, v142
	v_mad_i64_i32 v[152:153], s[52:53], s92, v150, 0
	v_lshlrev_b64 v[156:157], 2, v[152:153]
	v_lshl_add_u64 v[146:147], v[146:147], 0, v[156:157]
	global_load_dwordx4 v[152:155], v[146:147], off
	v_lshl_add_u64 v[146:147], v[148:149], 0, v[156:157]
	global_load_dwordx4 v[166:169], v[146:147], off
	s_and_b64 vcc, exec, s[10:11]
	v_ashrrev_i32_e32 v151, 31, v150
	s_mov_b64 s[10:11], -1
	s_waitcnt vmcnt(1)
	v_mul_f32_e32 v146, v68, v154
	v_mul_f32_e32 v147, v69, v155
	v_mul_f32_e32 v148, v66, v152
	v_mul_f32_e32 v149, v67, v153
	v_mul_f32_e32 v154, v72, v154
	v_mul_f32_e32 v155, v73, v155
	v_mul_f32_e32 v158, v70, v152
	v_mul_f32_e32 v159, v71, v153
	s_waitcnt vmcnt(0)
	v_fma_f32 v146, v72, v168, -v146
	v_fma_f32 v147, v73, v169, -v147
	v_fma_f32 v156, v70, v166, -v148
	v_fma_f32 v157, v71, v167, -v149
	v_fma_f32 v152, v68, v168, v154
	v_fma_f32 v153, v69, v169, v155
	v_fma_f32 v154, v66, v166, v158
	v_fma_f32 v155, v67, v167, v159
	s_cbranch_vccnz .LBB0_241
	v_mul_lo_u32 v143, s91, v150
	v_mul_lo_u32 v165, s90, v151
	v_mad_u64_u32 v[158:159], s[10:11], s90, v150, 0
	v_add3_u32 v159, v159, v165, v143
	v_lshl_add_u64 v[144:145], v[158:159], 1, v[144:145]
	s_lshl_b32 s26, s92, 1
	v_cvt_pk_bf16_f32 v148, v156, v157
	v_cvt_pk_bf16_f32 v149, v146, v147
	global_store_dwordx2 v[144:145], v[148:149], off
	v_lshl_add_u64 v[144:145], v[144:145], 0, s[26:27]
	s_mov_b64 s[10:11], 0
	v_cvt_pk_bf16_f32 v148, v154, v155
	v_cvt_pk_bf16_f32 v149, v152, v153
	global_store_dwordx2 v[144:145], v[148:149], off

.LBB0_277:
	v_lshlrev_b64 v[70:71], 2, v[134:135]
	v_lshl_add_u64 v[68:69], s[52:53], 0, v[70:71]
	v_mad_i64_i32 v[72:73], s[52:53], s92, v142, 0
	v_lshlrev_b64 v[76:77], 2, v[72:73]
	v_lshl_add_u64 v[72:73], v[68:69], 0, v[76:77]
	v_lshl_add_u64 v[70:71], s[96:97], 0, v[70:71]
	global_load_dwordx4 v[72:75], v[72:73], off
	v_lshl_add_u64 v[76:77], v[70:71], 0, v[76:77]
	global_load_dwordx4 v[80:83], v[76:77], off
	v_mov_b32_e32 v134, v66
	v_cndmask_b32_e64 v76, 0, 1, s[94:95]
	s_waitcnt lgkmcnt(0)
	v_lshl_add_u64 v[66:67], v[134:135], 1, s[10:11]
	v_cmp_ne_u32_e64 s[10:11], 1, v76
	v_ashrrev_i32_e32 v143, 31, v142
	s_andn2_b64 vcc, exec, s[94:95]
	s_mov_b64 s[52:53], -1
	s_waitcnt vmcnt(0)
	v_mul_f32_e32 v76, v60, v74
	v_mul_f32_e32 v77, v61, v75
	v_mul_f32_e32 v78, v58, v72
	v_mul_f32_e32 v79, v59, v73
	v_mul_f32_e32 v74, v64, v74
	v_mul_f32_e32 v75, v65, v75
	v_mul_f32_e32 v84, v62, v72
	v_mul_f32_e32 v85, v63, v73
	v_fma_f32 v72, v64, v82, -v76
	v_fma_f32 v73, v65, v83, -v77
	v_fma_f32 v78, v62, v80, -v78
	v_fma_f32 v79, v63, v81, -v79
	v_fmac_f32_e32 v74, v60, v82
	v_fmac_f32_e32 v75, v61, v83
	v_fma_f32 v76, v58, v80, v84
	v_fma_f32 v77, v59, v81, v85
	s_cbranch_vccnz .LBB0_279
	v_mul_lo_u32 v84, s91, v142
	v_mul_lo_u32 v85, s90, v143
	v_mad_u64_u32 v[82:83], s[52:53], s90, v142, 0
	v_add3_u32 v83, v83, v85, v84
	v_lshl_add_u64 v[82:83], v[82:83], 1, v[66:67]
	s_lshl_b32 s26, s92, 1
	v_cvt_pk_bf16_f32 v80, v78, v79
	v_cvt_pk_bf16_f32 v81, v72, v73
	global_store_dwordx2 v[82:83], v[80:81], off
	v_lshl_add_u64 v[82:83], v[82:83], 0, s[26:27]
	s_mov_b64 s[52:53], 0
	v_cvt_pk_bf16_f32 v80, v76, v77
	v_cvt_pk_bf16_f32 v81, v74, v75
	global_store_dwordx2 v[82:83], v[80:81], off

.LBB0_281:
	v_or_b32_e32 v72, 16, v142
	v_mad_i64_i32 v[74:75], s[52:53], s92, v72, 0
	v_lshlrev_b64 v[78:79], 2, v[74:75]
	v_lshl_add_u64 v[74:75], v[68:69], 0, v[78:79]
	global_load_dwordx4 v[74:77], v[74:75], off
	v_lshl_add_u64 v[78:79], v[70:71], 0, v[78:79]
	global_load_dwordx4 v[82:85], v[78:79], off
	s_and_b64 vcc, exec, s[10:11]
	v_ashrrev_i32_e32 v73, 31, v72
	s_mov_b64 s[52:53], -1
	s_waitcnt vmcnt(1)
	v_mul_f32_e32 v78, v52, v76
	v_mul_f32_e32 v79, v53, v77
	v_mul_f32_e32 v80, v50, v74
	v_mul_f32_e32 v81, v51, v75
	v_mul_f32_e32 v76, v56, v76
	v_mul_f32_e32 v77, v57, v77
	v_mul_f32_e32 v86, v54, v74
	v_mul_f32_e32 v87, v55, v75
	s_waitcnt vmcnt(0)
	v_fma_f32 v74, v56, v84, -v78
	v_fma_f32 v75, v57, v85, -v79
	v_fma_f32 v80, v54, v82, -v80
	v_fma_f32 v81, v55, v83, -v81
	v_fmac_f32_e32 v76, v52, v84
	v_fmac_f32_e32 v77, v53, v85
	v_fma_f32 v78, v50, v82, v86
	v_fma_f32 v79, v51, v83, v87
	s_cbranch_vccnz .LBB0_283
	v_mul_lo_u32 v86, s91, v72
	v_mul_lo_u32 v87, s90, v73
	v_mad_u64_u32 v[84:85], s[52:53], s90, v72, 0
	v_add3_u32 v85, v85, v87, v86
	v_lshl_add_u64 v[84:85], v[84:85], 1, v[66:67]
	s_lshl_b32 s26, s92, 1
	v_cvt_pk_bf16_f32 v82, v80, v81
	v_cvt_pk_bf16_f32 v83, v74, v75
	global_store_dwordx2 v[84:85], v[82:83], off
	v_lshl_add_u64 v[84:85], v[84:85], 0, s[26:27]
	s_mov_b64 s[52:53], 0
	v_cvt_pk_bf16_f32 v82, v78, v79
	v_cvt_pk_bf16_f32 v83, v76, v77
	global_store_dwordx2 v[84:85], v[82:83], off

.LBB0_285:
	v_or_b32_e32 v72, 32, v142
	v_mad_i64_i32 v[74:75], s[52:53], s92, v72, 0
	v_lshlrev_b64 v[78:79], 2, v[74:75]
	v_lshl_add_u64 v[74:75], v[68:69], 0, v[78:79]
	global_load_dwordx4 v[74:77], v[74:75], off
	v_lshl_add_u64 v[78:79], v[70:71], 0, v[78:79]
	global_load_dwordx4 v[82:85], v[78:79], off
	s_and_b64 vcc, exec, s[10:11]
	v_ashrrev_i32_e32 v73, 31, v72
	s_mov_b64 s[52:53], -1
	s_waitcnt vmcnt(1)
	v_mul_f32_e32 v78, v44, v76
	v_mul_f32_e32 v79, v45, v77
	v_mul_f32_e32 v80, v42, v74
	v_mul_f32_e32 v81, v43, v75
	v_mul_f32_e32 v76, v48, v76
	v_mul_f32_e32 v77, v49, v77
	v_mul_f32_e32 v86, v46, v74
	v_mul_f32_e32 v87, v47, v75
	s_waitcnt vmcnt(0)
	v_fma_f32 v74, v48, v84, -v78
	v_fma_f32 v75, v49, v85, -v79
	v_fma_f32 v80, v46, v82, -v80
	v_fma_f32 v81, v47, v83, -v81
	v_fmac_f32_e32 v76, v44, v84
	v_fmac_f32_e32 v77, v45, v85
	v_fma_f32 v78, v42, v82, v86
	v_fma_f32 v79, v43, v83, v87
	s_cbranch_vccnz .LBB0_287
	v_mul_lo_u32 v86, s91, v72
	v_mul_lo_u32 v87, s90, v73
	v_mad_u64_u32 v[84:85], s[52:53], s90, v72, 0
	v_add3_u32 v85, v85, v87, v86
	v_lshl_add_u64 v[84:85], v[84:85], 1, v[66:67]
	s_lshl_b32 s26, s92, 1
	v_cvt_pk_bf16_f32 v82, v80, v81
	v_cvt_pk_bf16_f32 v83, v74, v75
	global_store_dwordx2 v[84:85], v[82:83], off
	v_lshl_add_u64 v[84:85], v[84:85], 0, s[26:27]
	s_mov_b64 s[52:53], 0
	v_cvt_pk_bf16_f32 v82, v78, v79
	v_cvt_pk_bf16_f32 v83, v76, v77
	global_store_dwordx2 v[84:85], v[82:83], off

.LBB0_289:
	v_or_b32_e32 v72, 48, v142
	v_mad_i64_i32 v[74:75], s[52:53], s92, v72, 0
	v_lshlrev_b64 v[78:79], 2, v[74:75]
	v_lshl_add_u64 v[74:75], v[68:69], 0, v[78:79]
	global_load_dwordx4 v[74:77], v[74:75], off
	v_lshl_add_u64 v[78:79], v[70:71], 0, v[78:79]
	global_load_dwordx4 v[82:85], v[78:79], off
	s_and_b64 vcc, exec, s[10:11]
	v_ashrrev_i32_e32 v73, 31, v72
	s_mov_b64 s[52:53], -1
	s_waitcnt vmcnt(1)
	v_mul_f32_e32 v78, v36, v76
	v_mul_f32_e32 v79, v37, v77
	v_mul_f32_e32 v80, v34, v74
	v_mul_f32_e32 v81, v35, v75
	v_mul_f32_e32 v76, v40, v76
	v_mul_f32_e32 v77, v41, v77
	v_mul_f32_e32 v86, v38, v74
	v_mul_f32_e32 v87, v39, v75
	s_waitcnt vmcnt(0)
	v_fma_f32 v74, v40, v84, -v78
	v_fma_f32 v75, v41, v85, -v79
	v_fma_f32 v80, v38, v82, -v80
	v_fma_f32 v81, v39, v83, -v81
	v_fmac_f32_e32 v76, v36, v84
	v_fmac_f32_e32 v77, v37, v85
	v_fma_f32 v78, v34, v82, v86
	v_fma_f32 v79, v35, v83, v87
	s_cbranch_vccnz .LBB0_291
	v_mul_lo_u32 v86, s91, v72
	v_mul_lo_u32 v87, s90, v73
	v_mad_u64_u32 v[84:85], s[52:53], s90, v72, 0
	v_add3_u32 v85, v85, v87, v86
	v_lshl_add_u64 v[84:85], v[84:85], 1, v[66:67]
	s_lshl_b32 s26, s92, 1
	v_cvt_pk_bf16_f32 v82, v80, v81
	v_cvt_pk_bf16_f32 v83, v74, v75
	global_store_dwordx2 v[84:85], v[82:83], off
	v_lshl_add_u64 v[84:85], v[84:85], 0, s[26:27]
	s_mov_b64 s[52:53], 0
	v_cvt_pk_bf16_f32 v82, v78, v79
	v_cvt_pk_bf16_f32 v83, v76, v77
	global_store_dwordx2 v[84:85], v[82:83], off

.LBB0_293:
	v_add_u32_e32 v72, 0x80, v142
	v_mad_i64_i32 v[74:75], s[52:53], s92, v72, 0
	v_lshlrev_b64 v[78:79], 2, v[74:75]
	v_lshl_add_u64 v[74:75], v[68:69], 0, v[78:79]
	global_load_dwordx4 v[74:77], v[74:75], off
	v_lshl_add_u64 v[78:79], v[70:71], 0, v[78:79]
	global_load_dwordx4 v[82:85], v[78:79], off
	s_and_b64 vcc, exec, s[10:11]
	v_ashrrev_i32_e32 v73, 31, v72
	s_mov_b64 s[52:53], -1
	s_waitcnt vmcnt(1)
	v_mul_f32_e32 v78, v28, v76
	v_mul_f32_e32 v79, v29, v77
	v_mul_f32_e32 v80, v26, v74
	v_mul_f32_e32 v81, v27, v75
	v_mul_f32_e32 v76, v32, v76
	v_mul_f32_e32 v77, v33, v77
	v_mul_f32_e32 v86, v30, v74
	v_mul_f32_e32 v87, v31, v75
	s_waitcnt vmcnt(0)
	v_fma_f32 v74, v32, v84, -v78
	v_fma_f32 v75, v33, v85, -v79
	v_fma_f32 v80, v30, v82, -v80
	v_fma_f32 v81, v31, v83, -v81
	v_fmac_f32_e32 v76, v28, v84
	v_fmac_f32_e32 v77, v29, v85
	v_fma_f32 v78, v26, v82, v86
	v_fma_f32 v79, v27, v83, v87
	s_cbranch_vccnz .LBB0_295
	v_mul_lo_u32 v86, s91, v72
	v_mul_lo_u32 v87, s90, v73
	v_mad_u64_u32 v[84:85], s[52:53], s90, v72, 0
	v_add3_u32 v85, v85, v87, v86
	v_lshl_add_u64 v[84:85], v[84:85], 1, v[66:67]
	s_lshl_b32 s26, s92, 1
	v_cvt_pk_bf16_f32 v82, v80, v81
	v_cvt_pk_bf16_f32 v83, v74, v75
	global_store_dwordx2 v[84:85], v[82:83], off
	v_lshl_add_u64 v[84:85], v[84:85], 0, s[26:27]
	s_mov_b64 s[52:53], 0
	v_cvt_pk_bf16_f32 v82, v78, v79
	v_cvt_pk_bf16_f32 v83, v76, v77
	global_store_dwordx2 v[84:85], v[82:83], off

.LBB0_297:
	v_add_u32_e32 v72, 0x90, v142
	v_mad_i64_i32 v[74:75], s[52:53], s92, v72, 0
	v_lshlrev_b64 v[78:79], 2, v[74:75]
	v_lshl_add_u64 v[74:75], v[68:69], 0, v[78:79]
	global_load_dwordx4 v[74:77], v[74:75], off
	v_lshl_add_u64 v[78:79], v[70:71], 0, v[78:79]
	global_load_dwordx4 v[82:85], v[78:79], off
	s_and_b64 vcc, exec, s[10:11]
	v_ashrrev_i32_e32 v73, 31, v72
	s_mov_b64 s[52:53], -1
	s_waitcnt vmcnt(1)
	v_mul_f32_e32 v78, v20, v76
	v_mul_f32_e32 v79, v21, v77
	v_mul_f32_e32 v80, v18, v74
	v_mul_f32_e32 v81, v19, v75
	v_mul_f32_e32 v76, v24, v76
	v_mul_f32_e32 v77, v25, v77
	v_mul_f32_e32 v86, v22, v74
	v_mul_f32_e32 v87, v23, v75
	s_waitcnt vmcnt(0)
	v_fma_f32 v74, v24, v84, -v78
	v_fma_f32 v75, v25, v85, -v79
	v_fma_f32 v80, v22, v82, -v80
	v_fma_f32 v81, v23, v83, -v81
	v_fmac_f32_e32 v76, v20, v84
	v_fmac_f32_e32 v77, v21, v85
	v_fma_f32 v78, v18, v82, v86
	v_fma_f32 v79, v19, v83, v87
	s_cbranch_vccnz .LBB0_299
	v_mul_lo_u32 v86, s91, v72
	v_mul_lo_u32 v87, s90, v73
	v_mad_u64_u32 v[84:85], s[52:53], s90, v72, 0
	v_add3_u32 v85, v85, v87, v86
	v_lshl_add_u64 v[84:85], v[84:85], 1, v[66:67]
	s_lshl_b32 s26, s92, 1
	v_cvt_pk_bf16_f32 v82, v80, v81
	v_cvt_pk_bf16_f32 v83, v74, v75
	global_store_dwordx2 v[84:85], v[82:83], off
	v_lshl_add_u64 v[84:85], v[84:85], 0, s[26:27]
	s_mov_b64 s[52:53], 0
	v_cvt_pk_bf16_f32 v82, v78, v79
	v_cvt_pk_bf16_f32 v83, v76, v77
	global_store_dwordx2 v[84:85], v[82:83], off

.LBB0_301:
	v_add_u32_e32 v72, 0xa0, v142
	v_mad_i64_i32 v[74:75], s[52:53], s92, v72, 0
	v_lshlrev_b64 v[78:79], 2, v[74:75]
	v_lshl_add_u64 v[74:75], v[68:69], 0, v[78:79]
	global_load_dwordx4 v[74:77], v[74:75], off
	v_lshl_add_u64 v[78:79], v[70:71], 0, v[78:79]
	global_load_dwordx4 v[82:85], v[78:79], off
	s_and_b64 vcc, exec, s[10:11]
	v_ashrrev_i32_e32 v73, 31, v72
	s_mov_b64 s[52:53], -1
	s_waitcnt vmcnt(1)
	v_mul_f32_e32 v78, v12, v76
	v_mul_f32_e32 v79, v13, v77
	v_mul_f32_e32 v80, v10, v74
	v_mul_f32_e32 v81, v11, v75
	v_mul_f32_e32 v76, v16, v76
	v_mul_f32_e32 v77, v17, v77
	v_mul_f32_e32 v86, v14, v74
	v_mul_f32_e32 v87, v15, v75
	s_waitcnt vmcnt(0)
	v_fma_f32 v74, v16, v84, -v78
	v_fma_f32 v75, v17, v85, -v79
	v_fma_f32 v80, v14, v82, -v80
	v_fma_f32 v81, v15, v83, -v81
	v_fmac_f32_e32 v76, v12, v84
	v_fmac_f32_e32 v77, v13, v85
	v_fma_f32 v78, v10, v82, v86
	v_fma_f32 v79, v11, v83, v87
	s_cbranch_vccnz .LBB0_303
	v_mul_lo_u32 v86, s91, v72
	v_mul_lo_u32 v87, s90, v73
	v_mad_u64_u32 v[84:85], s[52:53], s90, v72, 0
	v_add3_u32 v85, v85, v87, v86
	v_lshl_add_u64 v[84:85], v[84:85], 1, v[66:67]
	s_lshl_b32 s26, s92, 1
	v_cvt_pk_bf16_f32 v82, v80, v81
	v_cvt_pk_bf16_f32 v83, v74, v75
	global_store_dwordx2 v[84:85], v[82:83], off
	v_lshl_add_u64 v[84:85], v[84:85], 0, s[26:27]
	s_mov_b64 s[52:53], 0
	v_cvt_pk_bf16_f32 v82, v78, v79
	v_cvt_pk_bf16_f32 v83, v76, v77
	global_store_dwordx2 v[84:85], v[82:83], off

.LBB0_305:
	v_add_u32_e32 v72, 0xb0, v142
	v_mad_i64_i32 v[74:75], s[52:53], s92, v72, 0
	v_lshlrev_b64 v[78:79], 2, v[74:75]
	v_lshl_add_u64 v[68:69], v[68:69], 0, v[78:79]
	global_load_dwordx4 v[74:77], v[68:69], off
	v_lshl_add_u64 v[68:69], v[70:71], 0, v[78:79]
	global_load_dwordx4 v[80:83], v[68:69], off
	s_and_b64 vcc, exec, s[10:11]
	v_ashrrev_i32_e32 v73, 31, v72
	s_mov_b64 s[10:11], -1
	s_waitcnt vmcnt(1)
	v_mul_f32_e32 v68, v4, v76
	v_mul_f32_e32 v69, v5, v77
	v_mul_f32_e32 v70, v2, v74
	v_mul_f32_e32 v71, v3, v75
	v_mul_f32_e32 v76, v8, v76
	v_mul_f32_e32 v77, v9, v77
	v_mul_f32_e32 v84, v6, v74
	v_mul_f32_e32 v85, v7, v75
	s_waitcnt vmcnt(0)
	v_fma_f32 v68, v8, v82, -v68
	v_fma_f32 v69, v9, v83, -v69
	v_fma_f32 v78, v6, v80, -v70
	v_fma_f32 v79, v7, v81, -v71
	v_fma_f32 v74, v4, v82, v76
	v_fma_f32 v75, v5, v83, v77
	v_fma_f32 v76, v2, v80, v84
	v_fma_f32 v77, v3, v81, v85
	s_cbranch_vccnz .LBB0_307
	v_mul_lo_u32 v82, s91, v72
	v_mul_lo_u32 v83, s90, v73
	v_mad_u64_u32 v[80:81], s[10:11], s90, v72, 0
	v_add3_u32 v81, v81, v83, v82
	v_lshl_add_u64 v[66:67], v[80:81], 1, v[66:67]
	s_lshl_b32 s26, s92, 1
	v_cvt_pk_bf16_f32 v70, v78, v79
	v_cvt_pk_bf16_f32 v71, v68, v69
	global_store_dwordx2 v[66:67], v[70:71], off
	v_lshl_add_u64 v[66:67], v[66:67], 0, s[26:27]
	s_mov_b64 s[10:11], 0
	v_cvt_pk_bf16_f32 v70, v76, v77
	v_cvt_pk_bf16_f32 v71, v74, v75
	global_store_dwordx2 v[66:67], v[70:71], off

.LBB0_437:
	s_add_u32 s4, s72, s4
	s_addc_u32 s5, s73, s5
	v_lshlrev_b64 v[140:141], 2, v[134:135]
	v_lshl_add_u64 v[142:143], s[4:5], 0, v[140:141]
	v_mad_i64_i32 v[144:145], s[4:5], s90, v138, 0
	s_add_u32 s94, s72, s94
	v_lshlrev_b64 v[150:151], 2, v[144:145]
	v_lshl_add_u64 v[144:145], v[142:143], 0, v[150:151]
	s_addc_u32 s95, s73, s95
	global_load_dwordx4 v[146:149], v[144:145], off
	v_lshl_add_u64 v[144:145], s[94:95], 0, v[140:141]
	v_lshl_add_u64 v[140:141], v[144:145], 0, v[150:151]
	global_load_dwordx4 v[162:165], v[140:141], off
	v_mov_b32_e32 v134, v139
	v_ashrrev_i32_e32 v139, 31, v138
	s_mov_b64 s[4:5], -1
	v_lshl_add_u64 v[140:141], v[134:135], 1, s[8:9]
	s_and_b64 vcc, exec, s[92:93]
	s_waitcnt vmcnt(0)
	v_mul_f32_e32 v150, v124, v148
	v_mul_f32_e32 v151, v125, v149
	v_mul_f32_e32 v152, v122, v146
	v_mul_f32_e32 v153, v123, v147
	v_mul_f32_e32 v148, v128, v148
	v_mul_f32_e32 v149, v129, v149
	v_mul_f32_e32 v154, v126, v146
	v_mul_f32_e32 v155, v127, v147
	v_fma_f32 v146, v128, v164, -v150
	v_fma_f32 v147, v129, v165, -v151
	v_fma_f32 v152, v126, v162, -v152
	v_fma_f32 v153, v127, v163, -v153
	v_fmac_f32_e32 v148, v124, v164
	v_fmac_f32_e32 v149, v125, v165
	v_fma_f32 v150, v122, v162, v154
	v_fma_f32 v151, v123, v163, v155
	s_cbranch_vccz .LBB0_439
	v_mul_lo_u32 v161, s89, v138
	v_mul_lo_u32 v164, s88, v139
	v_mad_u64_u32 v[162:163], s[4:5], s88, v138, 0
	v_add3_u32 v163, v163, v164, v161
	v_lshl_add_u64 v[162:163], v[162:163], 1, v[140:141]
	s_lshl_b32 s30, s90, 1
	v_cvt_pk_bf16_f32 v154, v152, v153
	v_cvt_pk_bf16_f32 v155, v146, v147
	global_store_dwordx2 v[162:163], v[154:155], off
	v_lshl_add_u64 v[162:163], v[162:163], 0, s[30:31]
	v_cvt_pk_bf16_f32 v154, v150, v151
	v_cvt_pk_bf16_f32 v155, v148, v149
	global_store_dwordx2 v[162:163], v[154:155], off
	s_mov_b64 s[4:5], 0

.LBB0_441:
	v_or_b32_e32 v146, 16, v138
	v_mad_i64_i32 v[148:149], s[4:5], s90, v146, 0
	v_lshlrev_b64 v[152:153], 2, v[148:149]
	v_lshl_add_u64 v[148:149], v[142:143], 0, v[152:153]
	global_load_dwordx4 v[148:151], v[148:149], off
	v_lshl_add_u64 v[152:153], v[144:145], 0, v[152:153]
	global_load_dwordx4 v[162:165], v[152:153], off
	v_cndmask_b32_e64 v139, 0, 1, s[92:93]
	v_ashrrev_i32_e32 v147, 31, v146
	v_cmp_ne_u32_e64 s[8:9], 1, v139
	s_andn2_b64 vcc, exec, s[92:93]
	s_mov_b64 s[4:5], -1
	s_waitcnt vmcnt(1)
	v_mul_f32_e32 v152, v116, v150
	v_mul_f32_e32 v153, v117, v151
	v_mul_f32_e32 v154, v114, v148
	v_mul_f32_e32 v155, v115, v149
	v_mul_f32_e32 v150, v120, v150
	v_mul_f32_e32 v151, v121, v151
	v_mul_f32_e32 v166, v118, v148
	v_mul_f32_e32 v167, v119, v149
	s_waitcnt vmcnt(0)
	v_fma_f32 v148, v120, v164, -v152
	v_fma_f32 v149, v121, v165, -v153
	v_fma_f32 v154, v118, v162, -v154
	v_fma_f32 v155, v119, v163, -v155
	v_fmac_f32_e32 v150, v116, v164
	v_fmac_f32_e32 v151, v117, v165
	v_fma_f32 v152, v114, v162, v166
	v_fma_f32 v153, v115, v163, v167
	s_cbranch_vccnz .LBB0_443
	v_mul_lo_u32 v139, s89, v146
	v_mul_lo_u32 v161, s88, v147
	v_mad_u64_u32 v[164:165], s[4:5], s88, v146, 0
	v_add3_u32 v165, v165, v161, v139
	v_lshl_add_u64 v[164:165], v[164:165], 1, v[140:141]
	s_lshl_b32 s30, s90, 1
	v_cvt_pk_bf16_f32 v162, v154, v155
	v_cvt_pk_bf16_f32 v163, v148, v149
	global_store_dwordx2 v[164:165], v[162:163], off
	v_lshl_add_u64 v[164:165], v[164:165], 0, s[30:31]
	s_mov_b64 s[4:5], 0
	v_cvt_pk_bf16_f32 v162, v152, v153
	v_cvt_pk_bf16_f32 v163, v150, v151
	global_store_dwordx2 v[164:165], v[162:163], off

.LBB0_445:
	v_or_b32_e32 v146, 32, v138
	v_mad_i64_i32 v[148:149], s[4:5], s90, v146, 0
	v_lshlrev_b64 v[152:153], 2, v[148:149]
	v_lshl_add_u64 v[148:149], v[142:143], 0, v[152:153]
	global_load_dwordx4 v[148:151], v[148:149], off
	v_lshl_add_u64 v[152:153], v[144:145], 0, v[152:153]
	global_load_dwordx4 v[162:165], v[152:153], off
	s_and_b64 vcc, exec, s[8:9]
	v_ashrrev_i32_e32 v147, 31, v146
	s_mov_b64 s[4:5], -1
	s_waitcnt vmcnt(1)
	v_mul_f32_e32 v152, v108, v150
	v_mul_f32_e32 v153, v109, v151
	v_mul_f32_e32 v154, v106, v148
	v_mul_f32_e32 v155, v107, v149
	v_mul_f32_e32 v150, v112, v150
	v_mul_f32_e32 v151, v113, v151
	v_mul_f32_e32 v166, v110, v148
	v_mul_f32_e32 v167, v111, v149
	s_waitcnt vmcnt(0)
	v_fma_f32 v148, v112, v164, -v152
	v_fma_f32 v149, v113, v165, -v153
	v_fma_f32 v154, v110, v162, -v154
	v_fma_f32 v155, v111, v163, -v155
	v_fmac_f32_e32 v150, v108, v164
	v_fmac_f32_e32 v151, v109, v165
	v_fma_f32 v152, v106, v162, v166
	v_fma_f32 v153, v107, v163, v167
	s_cbranch_vccnz .LBB0_447
	v_mul_lo_u32 v139, s89, v146
	v_mul_lo_u32 v161, s88, v147
	v_mad_u64_u32 v[164:165], s[4:5], s88, v146, 0
	v_add3_u32 v165, v165, v161, v139
	v_lshl_add_u64 v[164:165], v[164:165], 1, v[140:141]
	s_lshl_b32 s30, s90, 1
	v_cvt_pk_bf16_f32 v162, v154, v155
	v_cvt_pk_bf16_f32 v163, v148, v149
	global_store_dwordx2 v[164:165], v[162:163], off
	v_lshl_add_u64 v[164:165], v[164:165], 0, s[30:31]
	s_mov_b64 s[4:5], 0
	v_cvt_pk_bf16_f32 v162, v152, v153
	v_cvt_pk_bf16_f32 v163, v150, v151
	global_store_dwordx2 v[164:165], v[162:163], off

.LBB0_449:
	v_or_b32_e32 v146, 48, v138
	v_mad_i64_i32 v[148:149], s[4:5], s90, v146, 0
	v_lshlrev_b64 v[152:153], 2, v[148:149]
	v_lshl_add_u64 v[148:149], v[142:143], 0, v[152:153]
	global_load_dwordx4 v[148:151], v[148:149], off
	v_lshl_add_u64 v[152:153], v[144:145], 0, v[152:153]
	global_load_dwordx4 v[162:165], v[152:153], off
	s_and_b64 vcc, exec, s[8:9]
	v_ashrrev_i32_e32 v147, 31, v146
	s_mov_b64 s[4:5], -1
	s_waitcnt vmcnt(1)
	v_mul_f32_e32 v152, v100, v150
	v_mul_f32_e32 v153, v101, v151
	v_mul_f32_e32 v154, v98, v148
	v_mul_f32_e32 v155, v99, v149
	v_mul_f32_e32 v150, v104, v150
	v_mul_f32_e32 v151, v105, v151
	v_mul_f32_e32 v166, v102, v148
	v_mul_f32_e32 v167, v103, v149
	s_waitcnt vmcnt(0)
	v_fma_f32 v148, v104, v164, -v152
	v_fma_f32 v149, v105, v165, -v153
	v_fma_f32 v154, v102, v162, -v154
	v_fma_f32 v155, v103, v163, -v155
	v_fmac_f32_e32 v150, v100, v164
	v_fmac_f32_e32 v151, v101, v165
	v_fma_f32 v152, v98, v162, v166
	v_fma_f32 v153, v99, v163, v167
	s_cbranch_vccnz .LBB0_451
	v_mul_lo_u32 v139, s89, v146
	v_mul_lo_u32 v161, s88, v147
	v_mad_u64_u32 v[164:165], s[4:5], s88, v146, 0
	v_add3_u32 v165, v165, v161, v139
	v_lshl_add_u64 v[164:165], v[164:165], 1, v[140:141]
	s_lshl_b32 s30, s90, 1
	v_cvt_pk_bf16_f32 v162, v154, v155
	v_cvt_pk_bf16_f32 v163, v148, v149
	global_store_dwordx2 v[164:165], v[162:163], off
	v_lshl_add_u64 v[164:165], v[164:165], 0, s[30:31]
	s_mov_b64 s[4:5], 0
	v_cvt_pk_bf16_f32 v162, v152, v153
	v_cvt_pk_bf16_f32 v163, v150, v151
	global_store_dwordx2 v[164:165], v[162:163], off

.LBB0_453:
	v_add_u32_e32 v146, 0x80, v138
	v_mad_i64_i32 v[148:149], s[4:5], s90, v146, 0
	v_lshlrev_b64 v[152:153], 2, v[148:149]
	v_lshl_add_u64 v[148:149], v[142:143], 0, v[152:153]
	global_load_dwordx4 v[148:151], v[148:149], off
	v_lshl_add_u64 v[152:153], v[144:145], 0, v[152:153]
	global_load_dwordx4 v[162:165], v[152:153], off
	s_and_b64 vcc, exec, s[8:9]
	v_ashrrev_i32_e32 v147, 31, v146
	s_mov_b64 s[4:5], -1
	s_waitcnt vmcnt(1)
	v_mul_f32_e32 v152, v92, v150
	v_mul_f32_e32 v153, v93, v151
	v_mul_f32_e32 v154, v90, v148
	v_mul_f32_e32 v155, v91, v149
	v_mul_f32_e32 v150, v96, v150
	v_mul_f32_e32 v151, v97, v151
	v_mul_f32_e32 v166, v94, v148
	v_mul_f32_e32 v167, v95, v149
	s_waitcnt vmcnt(0)
	v_fma_f32 v148, v96, v164, -v152
	v_fma_f32 v149, v97, v165, -v153
	v_fma_f32 v154, v94, v162, -v154
	v_fma_f32 v155, v95, v163, -v155
	v_fmac_f32_e32 v150, v92, v164
	v_fmac_f32_e32 v151, v93, v165
	v_fma_f32 v152, v90, v162, v166
	v_fma_f32 v153, v91, v163, v167
	s_cbranch_vccnz .LBB0_455
	v_mul_lo_u32 v139, s89, v146
	v_mul_lo_u32 v161, s88, v147
	v_mad_u64_u32 v[164:165], s[4:5], s88, v146, 0
	v_add3_u32 v165, v165, v161, v139
	v_lshl_add_u64 v[164:165], v[164:165], 1, v[140:141]
	s_lshl_b32 s30, s90, 1
	v_cvt_pk_bf16_f32 v162, v154, v155
	v_cvt_pk_bf16_f32 v163, v148, v149
	global_store_dwordx2 v[164:165], v[162:163], off
	v_lshl_add_u64 v[164:165], v[164:165], 0, s[30:31]
	s_mov_b64 s[4:5], 0
	v_cvt_pk_bf16_f32 v162, v152, v153
	v_cvt_pk_bf16_f32 v163, v150, v151
	global_store_dwordx2 v[164:165], v[162:163], off

.LBB0_457:
	v_add_u32_e32 v146, 0x90, v138
	v_mad_i64_i32 v[148:149], s[4:5], s90, v146, 0
	v_lshlrev_b64 v[152:153], 2, v[148:149]
	v_lshl_add_u64 v[148:149], v[142:143], 0, v[152:153]
	global_load_dwordx4 v[148:151], v[148:149], off
	v_lshl_add_u64 v[152:153], v[144:145], 0, v[152:153]
	global_load_dwordx4 v[162:165], v[152:153], off
	s_and_b64 vcc, exec, s[8:9]
	v_ashrrev_i32_e32 v147, 31, v146
	s_mov_b64 s[4:5], -1
	s_waitcnt vmcnt(1)
	v_mul_f32_e32 v152, v84, v150
	v_mul_f32_e32 v153, v85, v151
	v_mul_f32_e32 v154, v82, v148
	v_mul_f32_e32 v155, v83, v149
	v_mul_f32_e32 v150, v88, v150
	v_mul_f32_e32 v151, v89, v151
	v_mul_f32_e32 v166, v86, v148
	v_mul_f32_e32 v167, v87, v149
	s_waitcnt vmcnt(0)
	v_fma_f32 v148, v88, v164, -v152
	v_fma_f32 v149, v89, v165, -v153
	v_fma_f32 v154, v86, v162, -v154
	v_fma_f32 v155, v87, v163, -v155
	v_fmac_f32_e32 v150, v84, v164
	v_fmac_f32_e32 v151, v85, v165
	v_fma_f32 v152, v82, v162, v166
	v_fma_f32 v153, v83, v163, v167
	s_cbranch_vccnz .LBB0_459
	v_mul_lo_u32 v139, s89, v146
	v_mul_lo_u32 v161, s88, v147
	v_mad_u64_u32 v[164:165], s[4:5], s88, v146, 0
	v_add3_u32 v165, v165, v161, v139
	v_lshl_add_u64 v[164:165], v[164:165], 1, v[140:141]
	s_lshl_b32 s30, s90, 1
	v_cvt_pk_bf16_f32 v162, v154, v155
	v_cvt_pk_bf16_f32 v163, v148, v149
	global_store_dwordx2 v[164:165], v[162:163], off
	v_lshl_add_u64 v[164:165], v[164:165], 0, s[30:31]
	s_mov_b64 s[4:5], 0
	v_cvt_pk_bf16_f32 v162, v152, v153
	v_cvt_pk_bf16_f32 v163, v150, v151
	global_store_dwordx2 v[164:165], v[162:163], off

.LBB0_461:
	v_add_u32_e32 v146, 0xa0, v138
	v_mad_i64_i32 v[148:149], s[4:5], s90, v146, 0
	v_lshlrev_b64 v[152:153], 2, v[148:149]
	v_lshl_add_u64 v[148:149], v[142:143], 0, v[152:153]
	global_load_dwordx4 v[148:151], v[148:149], off
	v_lshl_add_u64 v[152:153], v[144:145], 0, v[152:153]
	global_load_dwordx4 v[162:165], v[152:153], off
	s_and_b64 vcc, exec, s[8:9]
	v_ashrrev_i32_e32 v147, 31, v146
	s_mov_b64 s[4:5], -1
	s_waitcnt vmcnt(1)
	v_mul_f32_e32 v152, v76, v150
	v_mul_f32_e32 v153, v77, v151
	v_mul_f32_e32 v154, v74, v148
	v_mul_f32_e32 v155, v75, v149
	v_mul_f32_e32 v150, v80, v150
	v_mul_f32_e32 v151, v81, v151
	v_mul_f32_e32 v166, v78, v148
	v_mul_f32_e32 v167, v79, v149
	s_waitcnt vmcnt(0)
	v_fma_f32 v148, v80, v164, -v152
	v_fma_f32 v149, v81, v165, -v153
	v_fma_f32 v154, v78, v162, -v154
	v_fma_f32 v155, v79, v163, -v155
	v_fmac_f32_e32 v150, v76, v164
	v_fmac_f32_e32 v151, v77, v165
	v_fma_f32 v152, v74, v162, v166
	v_fma_f32 v153, v75, v163, v167
	s_cbranch_vccnz .LBB0_463
	v_mul_lo_u32 v139, s89, v146
	v_mul_lo_u32 v161, s88, v147
	v_mad_u64_u32 v[164:165], s[4:5], s88, v146, 0
	v_add3_u32 v165, v165, v161, v139
	v_lshl_add_u64 v[164:165], v[164:165], 1, v[140:141]
	s_lshl_b32 s30, s90, 1
	v_cvt_pk_bf16_f32 v162, v154, v155
	v_cvt_pk_bf16_f32 v163, v148, v149
	global_store_dwordx2 v[164:165], v[162:163], off
	v_lshl_add_u64 v[164:165], v[164:165], 0, s[30:31]
	s_mov_b64 s[4:5], 0
	v_cvt_pk_bf16_f32 v162, v152, v153
	v_cvt_pk_bf16_f32 v163, v150, v151
	global_store_dwordx2 v[164:165], v[162:163], off

.LBB0_465:
	v_add_u32_e32 v146, 0xb0, v138
	v_mad_i64_i32 v[148:149], s[4:5], s90, v146, 0
	v_lshlrev_b64 v[152:153], 2, v[148:149]
	v_lshl_add_u64 v[142:143], v[142:143], 0, v[152:153]
	global_load_dwordx4 v[148:151], v[142:143], off
	v_lshl_add_u64 v[142:143], v[144:145], 0, v[152:153]
	global_load_dwordx4 v[162:165], v[142:143], off
	s_and_b64 vcc, exec, s[8:9]
	v_ashrrev_i32_e32 v147, 31, v146
	s_mov_b64 s[4:5], -1
	s_waitcnt vmcnt(1)
	v_mul_f32_e32 v142, v68, v150
	v_mul_f32_e32 v143, v69, v151
	v_mul_f32_e32 v144, v66, v148
	v_mul_f32_e32 v145, v67, v149
	v_mul_f32_e32 v150, v72, v150
	v_mul_f32_e32 v151, v73, v151
	v_mul_f32_e32 v154, v70, v148
	v_mul_f32_e32 v155, v71, v149
	s_waitcnt vmcnt(0)
	v_fma_f32 v142, v72, v164, -v142
	v_fma_f32 v143, v73, v165, -v143
	v_fma_f32 v152, v70, v162, -v144
	v_fma_f32 v153, v71, v163, -v145
	v_fma_f32 v148, v68, v164, v150
	v_fma_f32 v149, v69, v165, v151
	v_fma_f32 v150, v66, v162, v154
	v_fma_f32 v151, v67, v163, v155
	s_cbranch_vccnz .LBB0_467
	v_mul_lo_u32 v139, s89, v146
	v_mul_lo_u32 v161, s88, v147
	v_mad_u64_u32 v[154:155], s[4:5], s88, v146, 0
	v_add3_u32 v155, v155, v161, v139
	v_lshl_add_u64 v[140:141], v[154:155], 1, v[140:141]
	s_lshl_b32 s30, s90, 1
	v_cvt_pk_bf16_f32 v144, v152, v153
	v_cvt_pk_bf16_f32 v145, v142, v143
	global_store_dwordx2 v[140:141], v[144:145], off
	v_lshl_add_u64 v[140:141], v[140:141], 0, s[30:31]
	s_mov_b64 s[4:5], 0
	v_cvt_pk_bf16_f32 v144, v150, v151
	v_cvt_pk_bf16_f32 v145, v148, v149
	global_store_dwordx2 v[140:141], v[144:145], off

.LBB0_503:
	v_lshlrev_b64 v[70:71], 2, v[134:135]
	v_lshl_add_u64 v[68:69], s[4:5], 0, v[70:71]
	v_mad_i64_i32 v[72:73], s[4:5], s90, v138, 0
	v_lshlrev_b64 v[76:77], 2, v[72:73]
	v_lshl_add_u64 v[72:73], v[68:69], 0, v[76:77]
	v_lshl_add_u64 v[70:71], s[94:95], 0, v[70:71]
	global_load_dwordx4 v[72:75], v[72:73], off
	v_lshl_add_u64 v[76:77], v[70:71], 0, v[76:77]
	global_load_dwordx4 v[80:83], v[76:77], off
	v_mov_b32_e32 v134, v66
	v_cndmask_b32_e64 v76, 0, 1, s[92:93]
	s_waitcnt lgkmcnt(0)
	v_lshl_add_u64 v[66:67], v[134:135], 1, s[8:9]
	v_cmp_ne_u32_e64 s[8:9], 1, v76
	v_ashrrev_i32_e32 v139, 31, v138
	s_andn2_b64 vcc, exec, s[92:93]
	s_mov_b64 s[4:5], -1
	s_waitcnt vmcnt(0)
	v_mul_f32_e32 v76, v60, v74
	v_mul_f32_e32 v77, v61, v75
	v_mul_f32_e32 v78, v58, v72
	v_mul_f32_e32 v79, v59, v73
	v_mul_f32_e32 v74, v64, v74
	v_mul_f32_e32 v75, v65, v75
	v_mul_f32_e32 v84, v62, v72
	v_mul_f32_e32 v85, v63, v73
	v_fma_f32 v72, v64, v82, -v76
	v_fma_f32 v73, v65, v83, -v77
	v_fma_f32 v78, v62, v80, -v78
	v_fma_f32 v79, v63, v81, -v79
	v_fmac_f32_e32 v74, v60, v82
	v_fmac_f32_e32 v75, v61, v83
	v_fma_f32 v76, v58, v80, v84
	v_fma_f32 v77, v59, v81, v85
	s_cbranch_vccnz .LBB0_505
	v_mul_lo_u32 v84, s89, v138
	v_mul_lo_u32 v85, s88, v139
	v_mad_u64_u32 v[82:83], s[4:5], s88, v138, 0
	v_add3_u32 v83, v83, v85, v84
	v_lshl_add_u64 v[82:83], v[82:83], 1, v[66:67]
	s_lshl_b32 s30, s90, 1
	v_cvt_pk_bf16_f32 v80, v78, v79
	v_cvt_pk_bf16_f32 v81, v72, v73
	global_store_dwordx2 v[82:83], v[80:81], off
	v_lshl_add_u64 v[82:83], v[82:83], 0, s[30:31]
	s_mov_b64 s[4:5], 0
	v_cvt_pk_bf16_f32 v80, v76, v77
	v_cvt_pk_bf16_f32 v81, v74, v75
	global_store_dwordx2 v[82:83], v[80:81], off

.LBB0_507:
	v_or_b32_e32 v72, 16, v138
	v_mad_i64_i32 v[74:75], s[4:5], s90, v72, 0
	v_lshlrev_b64 v[78:79], 2, v[74:75]
	v_lshl_add_u64 v[74:75], v[68:69], 0, v[78:79]
	global_load_dwordx4 v[74:77], v[74:75], off
	v_lshl_add_u64 v[78:79], v[70:71], 0, v[78:79]
	global_load_dwordx4 v[82:85], v[78:79], off
	s_and_b64 vcc, exec, s[8:9]
	v_ashrrev_i32_e32 v73, 31, v72
	s_mov_b64 s[4:5], -1
	s_waitcnt vmcnt(1)
	v_mul_f32_e32 v78, v52, v76
	v_mul_f32_e32 v79, v53, v77
	v_mul_f32_e32 v80, v50, v74
	v_mul_f32_e32 v81, v51, v75
	v_mul_f32_e32 v76, v56, v76
	v_mul_f32_e32 v77, v57, v77
	v_mul_f32_e32 v86, v54, v74
	v_mul_f32_e32 v87, v55, v75
	s_waitcnt vmcnt(0)
	v_fma_f32 v74, v56, v84, -v78
	v_fma_f32 v75, v57, v85, -v79
	v_fma_f32 v80, v54, v82, -v80
	v_fma_f32 v81, v55, v83, -v81
	v_fmac_f32_e32 v76, v52, v84
	v_fmac_f32_e32 v77, v53, v85
	v_fma_f32 v78, v50, v82, v86
	v_fma_f32 v79, v51, v83, v87
	s_cbranch_vccnz .LBB0_509
	v_mul_lo_u32 v86, s89, v72
	v_mul_lo_u32 v87, s88, v73
	v_mad_u64_u32 v[84:85], s[4:5], s88, v72, 0
	v_add3_u32 v85, v85, v87, v86
	v_lshl_add_u64 v[84:85], v[84:85], 1, v[66:67]
	s_lshl_b32 s30, s90, 1
	v_cvt_pk_bf16_f32 v82, v80, v81
	v_cvt_pk_bf16_f32 v83, v74, v75
	global_store_dwordx2 v[84:85], v[82:83], off
	v_lshl_add_u64 v[84:85], v[84:85], 0, s[30:31]
	s_mov_b64 s[4:5], 0
	v_cvt_pk_bf16_f32 v82, v78, v79
	v_cvt_pk_bf16_f32 v83, v76, v77
	global_store_dwordx2 v[84:85], v[82:83], off

.LBB0_511:
	v_or_b32_e32 v72, 32, v138
	v_mad_i64_i32 v[74:75], s[4:5], s90, v72, 0
	v_lshlrev_b64 v[78:79], 2, v[74:75]
	v_lshl_add_u64 v[74:75], v[68:69], 0, v[78:79]
	global_load_dwordx4 v[74:77], v[74:75], off
	v_lshl_add_u64 v[78:79], v[70:71], 0, v[78:79]
	global_load_dwordx4 v[82:85], v[78:79], off
	s_and_b64 vcc, exec, s[8:9]
	v_ashrrev_i32_e32 v73, 31, v72
	s_mov_b64 s[4:5], -1
	s_waitcnt vmcnt(1)
	v_mul_f32_e32 v78, v44, v76
	v_mul_f32_e32 v79, v45, v77
	v_mul_f32_e32 v80, v42, v74
	v_mul_f32_e32 v81, v43, v75
	v_mul_f32_e32 v76, v48, v76
	v_mul_f32_e32 v77, v49, v77
	v_mul_f32_e32 v86, v46, v74
	v_mul_f32_e32 v87, v47, v75
	s_waitcnt vmcnt(0)
	v_fma_f32 v74, v48, v84, -v78
	v_fma_f32 v75, v49, v85, -v79
	v_fma_f32 v80, v46, v82, -v80
	v_fma_f32 v81, v47, v83, -v81
	v_fmac_f32_e32 v76, v44, v84
	v_fmac_f32_e32 v77, v45, v85
	v_fma_f32 v78, v42, v82, v86
	v_fma_f32 v79, v43, v83, v87
	s_cbranch_vccnz .LBB0_513
	v_mul_lo_u32 v86, s89, v72
	v_mul_lo_u32 v87, s88, v73
	v_mad_u64_u32 v[84:85], s[4:5], s88, v72, 0
	v_add3_u32 v85, v85, v87, v86
	v_lshl_add_u64 v[84:85], v[84:85], 1, v[66:67]
	s_lshl_b32 s30, s90, 1
	v_cvt_pk_bf16_f32 v82, v80, v81
	v_cvt_pk_bf16_f32 v83, v74, v75
	global_store_dwordx2 v[84:85], v[82:83], off
	v_lshl_add_u64 v[84:85], v[84:85], 0, s[30:31]
	s_mov_b64 s[4:5], 0
	v_cvt_pk_bf16_f32 v82, v78, v79
	v_cvt_pk_bf16_f32 v83, v76, v77
	global_store_dwordx2 v[84:85], v[82:83], off

.LBB0_515:
	v_or_b32_e32 v72, 48, v138
	v_mad_i64_i32 v[74:75], s[4:5], s90, v72, 0
	v_lshlrev_b64 v[78:79], 2, v[74:75]
	v_lshl_add_u64 v[74:75], v[68:69], 0, v[78:79]
	global_load_dwordx4 v[74:77], v[74:75], off
	v_lshl_add_u64 v[78:79], v[70:71], 0, v[78:79]
	global_load_dwordx4 v[82:85], v[78:79], off
	s_and_b64 vcc, exec, s[8:9]
	v_ashrrev_i32_e32 v73, 31, v72
	s_mov_b64 s[4:5], -1
	s_waitcnt vmcnt(1)
	v_mul_f32_e32 v78, v36, v76
	v_mul_f32_e32 v79, v37, v77
	v_mul_f32_e32 v80, v34, v74
	v_mul_f32_e32 v81, v35, v75
	v_mul_f32_e32 v76, v40, v76
	v_mul_f32_e32 v77, v41, v77
	v_mul_f32_e32 v86, v38, v74
	v_mul_f32_e32 v87, v39, v75
	s_waitcnt vmcnt(0)
	v_fma_f32 v74, v40, v84, -v78
	v_fma_f32 v75, v41, v85, -v79
	v_fma_f32 v80, v38, v82, -v80
	v_fma_f32 v81, v39, v83, -v81
	v_fmac_f32_e32 v76, v36, v84
	v_fmac_f32_e32 v77, v37, v85
	v_fma_f32 v78, v34, v82, v86
	v_fma_f32 v79, v35, v83, v87
	s_cbranch_vccnz .LBB0_517
	v_mul_lo_u32 v86, s89, v72
	v_mul_lo_u32 v87, s88, v73
	v_mad_u64_u32 v[84:85], s[4:5], s88, v72, 0
	v_add3_u32 v85, v85, v87, v86
	v_lshl_add_u64 v[84:85], v[84:85], 1, v[66:67]
	s_lshl_b32 s30, s90, 1
	v_cvt_pk_bf16_f32 v82, v80, v81
	v_cvt_pk_bf16_f32 v83, v74, v75
	global_store_dwordx2 v[84:85], v[82:83], off
	v_lshl_add_u64 v[84:85], v[84:85], 0, s[30:31]
	s_mov_b64 s[4:5], 0
	v_cvt_pk_bf16_f32 v82, v78, v79
	v_cvt_pk_bf16_f32 v83, v76, v77
	global_store_dwordx2 v[84:85], v[82:83], off

.LBB0_519:
	v_add_u32_e32 v72, 0x80, v138
	v_mad_i64_i32 v[74:75], s[4:5], s90, v72, 0
	v_lshlrev_b64 v[78:79], 2, v[74:75]
	v_lshl_add_u64 v[74:75], v[68:69], 0, v[78:79]
	global_load_dwordx4 v[74:77], v[74:75], off
	v_lshl_add_u64 v[78:79], v[70:71], 0, v[78:79]
	global_load_dwordx4 v[82:85], v[78:79], off
	s_and_b64 vcc, exec, s[8:9]
	v_ashrrev_i32_e32 v73, 31, v72
	s_mov_b64 s[4:5], -1
	s_waitcnt vmcnt(1)
	v_mul_f32_e32 v78, v28, v76
	v_mul_f32_e32 v79, v29, v77
	v_mul_f32_e32 v80, v26, v74
	v_mul_f32_e32 v81, v27, v75
	v_mul_f32_e32 v76, v32, v76
	v_mul_f32_e32 v77, v33, v77
	v_mul_f32_e32 v86, v30, v74
	v_mul_f32_e32 v87, v31, v75
	s_waitcnt vmcnt(0)
	v_fma_f32 v74, v32, v84, -v78
	v_fma_f32 v75, v33, v85, -v79
	v_fma_f32 v80, v30, v82, -v80
	v_fma_f32 v81, v31, v83, -v81
	v_fmac_f32_e32 v76, v28, v84
	v_fmac_f32_e32 v77, v29, v85
	v_fma_f32 v78, v26, v82, v86
	v_fma_f32 v79, v27, v83, v87
	s_cbranch_vccnz .LBB0_521
	v_mul_lo_u32 v86, s89, v72
	v_mul_lo_u32 v87, s88, v73
	v_mad_u64_u32 v[84:85], s[4:5], s88, v72, 0
	v_add3_u32 v85, v85, v87, v86
	v_lshl_add_u64 v[84:85], v[84:85], 1, v[66:67]
	s_lshl_b32 s30, s90, 1
	v_cvt_pk_bf16_f32 v82, v80, v81
	v_cvt_pk_bf16_f32 v83, v74, v75
	global_store_dwordx2 v[84:85], v[82:83], off
	v_lshl_add_u64 v[84:85], v[84:85], 0, s[30:31]
	s_mov_b64 s[4:5], 0
	v_cvt_pk_bf16_f32 v82, v78, v79
	v_cvt_pk_bf16_f32 v83, v76, v77
	global_store_dwordx2 v[84:85], v[82:83], off

.LBB0_523:
	v_add_u32_e32 v72, 0x90, v138
	v_mad_i64_i32 v[74:75], s[4:5], s90, v72, 0
	v_lshlrev_b64 v[78:79], 2, v[74:75]
	v_lshl_add_u64 v[74:75], v[68:69], 0, v[78:79]
	global_load_dwordx4 v[74:77], v[74:75], off
	v_lshl_add_u64 v[78:79], v[70:71], 0, v[78:79]
	global_load_dwordx4 v[82:85], v[78:79], off
	s_and_b64 vcc, exec, s[8:9]
	v_ashrrev_i32_e32 v73, 31, v72
	s_mov_b64 s[4:5], -1
	s_waitcnt vmcnt(1)
	v_mul_f32_e32 v78, v20, v76
	v_mul_f32_e32 v79, v21, v77
	v_mul_f32_e32 v80, v18, v74
	v_mul_f32_e32 v81, v19, v75
	v_mul_f32_e32 v76, v24, v76
	v_mul_f32_e32 v77, v25, v77
	v_mul_f32_e32 v86, v22, v74
	v_mul_f32_e32 v87, v23, v75
	s_waitcnt vmcnt(0)
	v_fma_f32 v74, v24, v84, -v78
	v_fma_f32 v75, v25, v85, -v79
	v_fma_f32 v80, v22, v82, -v80
	v_fma_f32 v81, v23, v83, -v81
	v_fmac_f32_e32 v76, v20, v84
	v_fmac_f32_e32 v77, v21, v85
	v_fma_f32 v78, v18, v82, v86
	v_fma_f32 v79, v19, v83, v87
	s_cbranch_vccnz .LBB0_525
	v_mul_lo_u32 v86, s89, v72
	v_mul_lo_u32 v87, s88, v73
	v_mad_u64_u32 v[84:85], s[4:5], s88, v72, 0
	v_add3_u32 v85, v85, v87, v86
	v_lshl_add_u64 v[84:85], v[84:85], 1, v[66:67]
	s_lshl_b32 s30, s90, 1
	v_cvt_pk_bf16_f32 v82, v80, v81
	v_cvt_pk_bf16_f32 v83, v74, v75
	global_store_dwordx2 v[84:85], v[82:83], off
	v_lshl_add_u64 v[84:85], v[84:85], 0, s[30:31]
	s_mov_b64 s[4:5], 0
	v_cvt_pk_bf16_f32 v82, v78, v79
	v_cvt_pk_bf16_f32 v83, v76, v77
	global_store_dwordx2 v[84:85], v[82:83], off

.LBB0_527:
	v_add_u32_e32 v72, 0xa0, v138
	v_mad_i64_i32 v[74:75], s[4:5], s90, v72, 0
	v_lshlrev_b64 v[78:79], 2, v[74:75]
	v_lshl_add_u64 v[74:75], v[68:69], 0, v[78:79]
	global_load_dwordx4 v[74:77], v[74:75], off
	v_lshl_add_u64 v[78:79], v[70:71], 0, v[78:79]
	global_load_dwordx4 v[82:85], v[78:79], off
	s_and_b64 vcc, exec, s[8:9]
	v_ashrrev_i32_e32 v73, 31, v72
	s_mov_b64 s[4:5], -1
	s_waitcnt vmcnt(1)
	v_mul_f32_e32 v78, v12, v76
	v_mul_f32_e32 v79, v13, v77
	v_mul_f32_e32 v80, v10, v74
	v_mul_f32_e32 v81, v11, v75
	v_mul_f32_e32 v76, v16, v76
	v_mul_f32_e32 v77, v17, v77
	v_mul_f32_e32 v86, v14, v74
	v_mul_f32_e32 v87, v15, v75
	s_waitcnt vmcnt(0)
	v_fma_f32 v74, v16, v84, -v78
	v_fma_f32 v75, v17, v85, -v79
	v_fma_f32 v80, v14, v82, -v80
	v_fma_f32 v81, v15, v83, -v81
	v_fmac_f32_e32 v76, v12, v84
	v_fmac_f32_e32 v77, v13, v85
	v_fma_f32 v78, v10, v82, v86
	v_fma_f32 v79, v11, v83, v87
	s_cbranch_vccnz .LBB0_529
	v_mul_lo_u32 v86, s89, v72
	v_mul_lo_u32 v87, s88, v73
	v_mad_u64_u32 v[84:85], s[4:5], s88, v72, 0
	v_add3_u32 v85, v85, v87, v86
	v_lshl_add_u64 v[84:85], v[84:85], 1, v[66:67]
	s_lshl_b32 s30, s90, 1
	v_cvt_pk_bf16_f32 v82, v80, v81
	v_cvt_pk_bf16_f32 v83, v74, v75
	global_store_dwordx2 v[84:85], v[82:83], off
	v_lshl_add_u64 v[84:85], v[84:85], 0, s[30:31]
	s_mov_b64 s[4:5], 0
	v_cvt_pk_bf16_f32 v82, v78, v79
	v_cvt_pk_bf16_f32 v83, v76, v77
	global_store_dwordx2 v[84:85], v[82:83], off

.LBB0_531:
	v_add_u32_e32 v72, 0xb0, v138
	v_mad_i64_i32 v[74:75], s[4:5], s90, v72, 0
	v_lshlrev_b64 v[78:79], 2, v[74:75]
	v_lshl_add_u64 v[68:69], v[68:69], 0, v[78:79]
	global_load_dwordx4 v[74:77], v[68:69], off
	v_lshl_add_u64 v[68:69], v[70:71], 0, v[78:79]
	global_load_dwordx4 v[80:83], v[68:69], off
	s_and_b64 vcc, exec, s[8:9]
	v_ashrrev_i32_e32 v73, 31, v72
	s_mov_b64 s[4:5], -1
	s_waitcnt vmcnt(1)
	v_mul_f32_e32 v68, v4, v76
	v_mul_f32_e32 v69, v5, v77
	v_mul_f32_e32 v70, v2, v74
	v_mul_f32_e32 v71, v3, v75
	v_mul_f32_e32 v76, v8, v76
	v_mul_f32_e32 v77, v9, v77
	v_mul_f32_e32 v84, v6, v74
	v_mul_f32_e32 v85, v7, v75
	s_waitcnt vmcnt(0)
	v_fma_f32 v68, v8, v82, -v68
	v_fma_f32 v69, v9, v83, -v69
	v_fma_f32 v78, v6, v80, -v70
	v_fma_f32 v79, v7, v81, -v71
	v_fma_f32 v74, v4, v82, v76
	v_fma_f32 v75, v5, v83, v77
	v_fma_f32 v76, v2, v80, v84
	v_fma_f32 v77, v3, v81, v85
	s_cbranch_vccnz .LBB0_533
	v_mul_lo_u32 v82, s89, v72
	v_mul_lo_u32 v83, s88, v73
	v_mad_u64_u32 v[80:81], s[4:5], s88, v72, 0
	v_add3_u32 v81, v81, v83, v82
	v_lshl_add_u64 v[66:67], v[80:81], 1, v[66:67]
	s_lshl_b32 s30, s90, 1
	v_cvt_pk_bf16_f32 v70, v78, v79
	v_cvt_pk_bf16_f32 v71, v68, v69
	global_store_dwordx2 v[66:67], v[70:71], off
	v_lshl_add_u64 v[66:67], v[66:67], 0, s[30:31]
	s_mov_b64 s[4:5], 0
	v_cvt_pk_bf16_f32 v70, v76, v77
	v_cvt_pk_bf16_f32 v71, v74, v75
	global_store_dwordx2 v[66:67], v[70:71], off

.LBB0_573:
	v_mov_b32_e32 v34, v0
	s_lshl_b32 s4, s6, 8
	s_add_i32 s4, s4, s91
	v_and_b32_e32 v139, 15, v34
	v_or_b32_e32 v140, s4, v139
	v_ashrrev_i32_e32 v141, 31, v140
	v_lshlrev_b64 v[142:143], 6, v[140:141]
	v_lshl_add_u64 v[154:155], s[30:31], 0, v[142:143]
	global_load_dwordx4 v[142:145], v[154:155], off offset:32
	global_load_dwordx4 v[146:149], v[154:155], off offset:48
	global_load_dwordx4 v[150:153], v[154:155], off
	global_load_dwordx4 v[186:189], v[154:155], off offset:16
	v_bfe_u32 v199, v34, 4, 2
	s_lshl_b32 s2, s2, 8
	s_waitcnt vmcnt(0)
	v_add_f32_e32 v144, v144, v148
	v_add_f32_e32 v145, v145, v149
	v_add_f32_e32 v142, v142, v146
	v_add_f32_e32 v143, v143, v147
	v_add_f32_e32 v152, v152, v188
	v_add_f32_e32 v153, v153, v189
	v_add_f32_e32 v150, v150, v186
	v_add_f32_e32 v151, v151, v187
	v_add_f32_e32 v144, v152, v144
	v_add_f32_e32 v145, v153, v145
	v_add_f32_e32 v142, v150, v142
	v_add_f32_e32 v143, v151, v143
	s_nop 0
	v_add_f32_e32 v34, v142, v143
	v_add_f32_e32 v142, v144, v145
	v_add_f32_e32 v34, v34, v142
	v_fmamk_f32 v34, v34, 0x3b000000, v169
	v_cmp_gt_f32_e32 vcc, s96, v34
	v_mul_f32_e32 v142, 0x4f800000, v34
	s_nop 0
	v_cndmask_b32_e32 v34, v34, v142, vcc
	v_sqrt_f32_e32 v142, v34
	s_nop 0
	v_add_u32_e32 v143, -1, v142
	v_fma_f32 v144, -v143, v142, v34
	v_cmp_ge_f32_e64 s[6:7], 0, v144
	v_add_u32_e32 v144, 1, v142
	s_nop 0
	v_cndmask_b32_e64 v143, v142, v143, s[6:7]
	v_fma_f32 v142, -v144, v142, v34
	v_cmp_lt_f32_e64 s[6:7], 0, v142
	s_nop 1
	v_cndmask_b32_e64 v142, v143, v144, s[6:7]
	v_mul_f32_e32 v143, 0x37800000, v142
	v_cndmask_b32_e32 v142, v142, v143, vcc
	v_cmp_class_f32_e32 vcc, v34, v173
	s_nop 1
	v_cndmask_b32_e32 v34, v142, v34, vcc
	v_div_scale_f32 v142, s[6:7], v34, v34, 1.0
	v_rcp_f32_e32 v143, v142
	s_nop 0
	v_fma_f32 v144, -v142, v143, 1.0
	v_fmac_f32_e32 v143, v144, v143
	v_div_scale_f32 v144, vcc, 1.0, v34, 1.0
	v_mul_f32_e32 v145, v144, v143
	v_fma_f32 v146, -v142, v145, v144
	v_fmac_f32_e32 v145, v146, v143
	v_fma_f32 v142, -v142, v145, v144
	v_div_fmas_f32 v142, v142, v143, v145
	v_div_fixup_f32 v202, v142, v34, 1.0
	v_or_b32_e32 v142, 16, v140
	v_ashrrev_i32_e32 v143, 31, v142
	v_lshlrev_b64 v[144:145], 6, v[142:143]
	v_lshl_add_u64 v[158:159], s[30:31], 0, v[144:145]
	global_load_dwordx4 v[144:147], v[158:159], off offset:32
	global_load_dwordx4 v[148:151], v[158:159], off offset:48
	global_load_dwordx4 v[152:155], v[158:159], off
	global_load_dwordx4 v[186:189], v[158:159], off offset:16
	v_mul_f32_e32 v184, 0x3f553b94, v202
	v_lshlrev_b64 v[182:183], 7, v[142:143]
	s_waitcnt vmcnt(2)
	v_add_f32_e32 v146, v146, v150
	v_add_f32_e32 v147, v147, v151
	v_add_f32_e32 v144, v144, v148
	v_add_f32_e32 v145, v145, v149
	s_waitcnt vmcnt(0)
	v_add_f32_e32 v154, v154, v188
	v_add_f32_e32 v155, v155, v189
	v_add_f32_e32 v152, v152, v186
	v_add_f32_e32 v153, v153, v187
	v_add_f32_e32 v146, v154, v146
	v_add_f32_e32 v147, v155, v147
	v_add_f32_e32 v144, v152, v144
	v_add_f32_e32 v145, v153, v145
	s_nop 0
	v_add_f32_e32 v34, v144, v145
	v_add_f32_e32 v144, v146, v147
	v_add_f32_e32 v34, v34, v144
	v_fmamk_f32 v34, v34, 0x3b000000, v169
	v_cmp_gt_f32_e32 vcc, s96, v34
	v_mul_f32_e32 v144, 0x4f800000, v34
	s_nop 0
	v_cndmask_b32_e32 v34, v34, v144, vcc
	v_sqrt_f32_e32 v144, v34
	s_nop 0
	v_add_u32_e32 v145, -1, v144
	v_fma_f32 v146, -v145, v144, v34
	v_cmp_ge_f32_e64 s[6:7], 0, v146
	v_add_u32_e32 v146, 1, v144
	s_nop 0
	v_cndmask_b32_e64 v145, v144, v145, s[6:7]
	v_fma_f32 v144, -v146, v144, v34
	v_cmp_lt_f32_e64 s[6:7], 0, v144
	s_nop 1
	v_cndmask_b32_e64 v144, v145, v146, s[6:7]
	v_mul_f32_e32 v145, 0x37800000, v144
	v_cndmask_b32_e32 v144, v144, v145, vcc
	v_cmp_class_f32_e32 vcc, v34, v173
	s_nop 1
	v_cndmask_b32_e32 v34, v144, v34, vcc
	v_div_scale_f32 v144, s[6:7], v34, v34, 1.0
	v_rcp_f32_e32 v145, v144
	s_nop 0
	v_fma_f32 v146, -v144, v145, 1.0
	v_fmac_f32_e32 v145, v146, v145
	v_div_scale_f32 v146, vcc, 1.0, v34, 1.0
	v_mul_f32_e32 v147, v146, v145
	v_fma_f32 v148, -v144, v147, v146
	v_fmac_f32_e32 v147, v148, v145
	v_fma_f32 v144, -v144, v147, v146
	v_div_fmas_f32 v144, v144, v145, v147
	v_div_fixup_f32 v203, v144, v34, 1.0
	v_or_b32_e32 v144, 32, v140
	v_ashrrev_i32_e32 v145, 31, v144
	v_lshlrev_b64 v[146:147], 6, v[144:145]
	v_lshl_add_u64 v[154:155], s[30:31], 0, v[146:147]
	global_load_dwordx4 v[146:149], v[154:155], off offset:32
	global_load_dwordx4 v[150:153], v[154:155], off offset:48
	global_load_dwordx4 v[186:189], v[154:155], off
	global_load_dwordx4 v[190:193], v[154:155], off offset:16
	v_mul_f32_e32 v180, 0x3f553b94, v203
	v_lshlrev_b64 v[178:179], 7, v[144:145]
	s_waitcnt vmcnt(2)
	v_add_f32_e32 v148, v148, v152
	v_add_f32_e32 v149, v149, v153
	v_add_f32_e32 v146, v146, v150
	v_add_f32_e32 v147, v147, v151
	s_waitcnt vmcnt(0)
	v_add_f32_e32 v154, v188, v192
	v_add_f32_e32 v155, v189, v193
	v_add_f32_e32 v158, v186, v190
	v_add_f32_e32 v159, v187, v191
	v_add_f32_e32 v148, v154, v148
	v_add_f32_e32 v149, v155, v149
	v_add_f32_e32 v146, v158, v146
	v_add_f32_e32 v147, v159, v147
	s_nop 0
	v_add_f32_e32 v34, v146, v147
	v_add_f32_e32 v146, v148, v149
	v_add_f32_e32 v34, v34, v146
	v_fmamk_f32 v34, v34, 0x3b000000, v169
	v_cmp_gt_f32_e32 vcc, s96, v34
	v_mul_f32_e32 v146, 0x4f800000, v34
	s_nop 0
	v_cndmask_b32_e32 v34, v34, v146, vcc
	v_sqrt_f32_e32 v146, v34
	s_nop 0
	v_add_u32_e32 v147, -1, v146
	v_fma_f32 v148, -v147, v146, v34
	v_cmp_ge_f32_e64 s[6:7], 0, v148
	v_add_u32_e32 v148, 1, v146
	s_nop 0
	v_cndmask_b32_e64 v147, v146, v147, s[6:7]
	v_fma_f32 v146, -v148, v146, v34
	v_cmp_lt_f32_e64 s[6:7], 0, v146
	s_nop 1
	v_cndmask_b32_e64 v146, v147, v148, s[6:7]
	v_mul_f32_e32 v147, 0x37800000, v146
	v_cndmask_b32_e32 v146, v146, v147, vcc
	v_cmp_class_f32_e32 vcc, v34, v173
	s_nop 1
	v_cndmask_b32_e32 v34, v146, v34, vcc
	v_div_scale_f32 v146, s[6:7], v34, v34, 1.0
	v_rcp_f32_e32 v147, v146
	s_nop 0
	v_fma_f32 v148, -v146, v147, 1.0
	v_fmac_f32_e32 v147, v148, v147
	v_div_scale_f32 v148, vcc, 1.0, v34, 1.0
	v_mul_f32_e32 v149, v148, v147
	v_fma_f32 v150, -v146, v149, v148
	v_fmac_f32_e32 v149, v150, v147
	v_fma_f32 v146, -v146, v149, v148
	v_div_fmas_f32 v146, v146, v147, v149
	v_div_fixup_f32 v205, v146, v34, 1.0
	v_or_b32_e32 v146, 48, v140
	v_ashrrev_i32_e32 v147, 31, v146
	v_lshlrev_b64 v[148:149], 6, v[146:147]
	v_lshl_add_u64 v[158:159], s[30:31], 0, v[148:149]
	global_load_dwordx4 v[148:151], v[158:159], off offset:32
	global_load_dwordx4 v[152:155], v[158:159], off offset:48
	global_load_dwordx4 v[186:189], v[158:159], off
	global_load_dwordx4 v[190:193], v[158:159], off offset:16
	v_mul_f32_e32 v176, 0x3f553b94, v205
	v_lshlrev_b64 v[174:175], 7, v[146:147]
	s_waitcnt vmcnt(2)
	v_add_f32_e32 v150, v150, v154
	v_add_f32_e32 v151, v151, v155
	v_add_f32_e32 v148, v148, v152
	v_add_f32_e32 v149, v149, v153
	s_waitcnt vmcnt(0)
	v_add_f32_e32 v158, v188, v192
	v_add_f32_e32 v159, v189, v193
	v_add_f32_e32 v162, v186, v190
	v_add_f32_e32 v163, v187, v191
	v_add_f32_e32 v150, v158, v150
	v_add_f32_e32 v151, v159, v151
	v_add_f32_e32 v148, v162, v148
	v_add_f32_e32 v149, v163, v149
	s_nop 0
	v_add_f32_e32 v34, v148, v149
	v_add_f32_e32 v148, v150, v151
	v_add_f32_e32 v34, v34, v148
	v_fmamk_f32 v34, v34, 0x3b000000, v169
	v_cmp_gt_f32_e32 vcc, s96, v34
	v_mul_f32_e32 v148, 0x4f800000, v34
	s_nop 0
	v_cndmask_b32_e32 v34, v34, v148, vcc
	v_sqrt_f32_e32 v148, v34
	s_nop 0
	v_add_u32_e32 v149, -1, v148
	v_fma_f32 v150, -v149, v148, v34
	v_cmp_ge_f32_e64 s[6:7], 0, v150
	v_add_u32_e32 v150, 1, v148
	s_nop 0
	v_cndmask_b32_e64 v149, v148, v149, s[6:7]
	v_fma_f32 v148, -v150, v148, v34
	v_cmp_lt_f32_e64 s[6:7], 0, v148
	s_nop 1
	v_cndmask_b32_e64 v148, v149, v150, s[6:7]
	v_mul_f32_e32 v149, 0x37800000, v148
	v_cndmask_b32_e32 v148, v148, v149, vcc
	v_cmp_class_f32_e32 vcc, v34, v173
	s_nop 1
	v_cndmask_b32_e32 v34, v148, v34, vcc
	v_div_scale_f32 v148, s[6:7], v34, v34, 1.0
	v_rcp_f32_e32 v149, v148
	s_nop 0
	v_fma_f32 v150, -v148, v149, 1.0
	v_fmac_f32_e32 v149, v150, v149
	v_div_scale_f32 v150, vcc, 1.0, v34, 1.0
	v_mul_f32_e32 v151, v150, v149
	v_fma_f32 v152, -v148, v151, v150
	v_fmac_f32_e32 v151, v152, v149
	v_fma_f32 v148, -v148, v151, v150
	v_div_fmas_f32 v148, v148, v149, v151
	v_div_fixup_f32 v206, v148, v34, 1.0
	v_add_u32_e32 v148, 0x80, v140
	v_ashrrev_i32_e32 v149, 31, v148
	v_lshlrev_b64 v[150:151], 6, v[148:149]
	v_lshl_add_u64 v[154:155], s[30:31], 0, v[150:151]
	global_load_dwordx4 v[150:153], v[154:155], off offset:32
	global_load_dwordx4 v[186:189], v[154:155], off offset:48
	global_load_dwordx4 v[190:193], v[154:155], off
	global_load_dwordx4 v[208:211], v[154:155], off offset:16
	v_mul_f32_e32 v172, 0x3f553b94, v206
	s_waitcnt vmcnt(2)
	v_add_f32_e32 v152, v152, v188
	v_add_f32_e32 v153, v153, v189
	v_add_f32_e32 v150, v150, v186
	v_add_f32_e32 v151, v151, v187
	s_waitcnt vmcnt(0)
	v_add_f32_e32 v154, v192, v210
	v_add_f32_e32 v155, v193, v211
	v_add_f32_e32 v158, v190, v208
	v_add_f32_e32 v159, v191, v209
	v_add_f32_e32 v152, v154, v152
	v_add_f32_e32 v153, v155, v153
	v_add_f32_e32 v150, v158, v150
	v_add_f32_e32 v151, v159, v151
	s_nop 0
	v_add_f32_e32 v34, v150, v151
	v_add_f32_e32 v150, v152, v153
	v_add_f32_e32 v34, v34, v150
	v_fmamk_f32 v34, v34, 0x3b000000, v169
	v_cmp_gt_f32_e32 vcc, s96, v34
	v_mul_f32_e32 v150, 0x4f800000, v34
	s_nop 0
	v_cndmask_b32_e32 v34, v34, v150, vcc
	v_sqrt_f32_e32 v150, v34
	s_nop 0
	v_add_u32_e32 v151, -1, v150
	v_fma_f32 v152, -v151, v150, v34
	v_cmp_ge_f32_e64 s[6:7], 0, v152
	v_add_u32_e32 v152, 1, v150
	s_nop 0
	v_cndmask_b32_e64 v151, v150, v151, s[6:7]
	v_fma_f32 v150, -v152, v150, v34
	v_cmp_lt_f32_e64 s[6:7], 0, v150
	s_nop 1
	v_cndmask_b32_e64 v150, v151, v152, s[6:7]
	v_mul_f32_e32 v151, 0x37800000, v150
	v_cndmask_b32_e32 v150, v150, v151, vcc
	v_cmp_class_f32_e32 vcc, v34, v173
	s_nop 1
	v_cndmask_b32_e32 v34, v150, v34, vcc
	v_div_scale_f32 v150, s[6:7], v34, v34, 1.0
	v_rcp_f32_e32 v151, v150
	s_nop 0
	v_fma_f32 v152, -v150, v151, 1.0
	v_fmac_f32_e32 v151, v152, v151
	v_div_scale_f32 v152, vcc, 1.0, v34, 1.0
	v_mul_f32_e32 v153, v152, v151
	v_fma_f32 v154, -v150, v153, v152
	v_fmac_f32_e32 v153, v154, v151
	v_fma_f32 v150, -v150, v153, v152
	v_div_fmas_f32 v150, v150, v151, v153
	v_div_fixup_f32 v200, v150, v34, 1.0
	v_add_u32_e32 v150, 0x90, v140
	v_ashrrev_i32_e32 v151, 31, v150
	v_lshlrev_b64 v[152:153], 6, v[150:151]
	v_lshl_add_u64 v[158:159], s[30:31], 0, v[152:153]
	global_load_dwordx4 v[152:155], v[158:159], off offset:32
	global_load_dwordx4 v[186:189], v[158:159], off offset:48
	global_load_dwordx4 v[190:193], v[158:159], off
	global_load_dwordx4 v[208:211], v[158:159], off offset:16
	v_mul_f32_e32 v168, 0x3f553b94, v200
	s_waitcnt vmcnt(2)
	v_add_f32_e32 v154, v154, v188
	v_add_f32_e32 v155, v155, v189
	v_add_f32_e32 v152, v152, v186
	v_add_f32_e32 v153, v153, v187
	s_waitcnt vmcnt(0)
	v_add_f32_e32 v158, v192, v210
	v_add_f32_e32 v159, v193, v211
	v_add_f32_e32 v162, v190, v208
	v_add_f32_e32 v163, v191, v209
	v_add_f32_e32 v154, v158, v154
	v_add_f32_e32 v155, v159, v155
	v_add_f32_e32 v152, v162, v152
	v_add_f32_e32 v153, v163, v153
	s_nop 0
	v_add_f32_e32 v34, v152, v153
	v_add_f32_e32 v152, v154, v155
	v_add_f32_e32 v34, v34, v152
	v_fmamk_f32 v34, v34, 0x3b000000, v169
	v_cmp_gt_f32_e32 vcc, s96, v34
	v_mul_f32_e32 v152, 0x4f800000, v34
	s_nop 0
	v_cndmask_b32_e32 v34, v34, v152, vcc
	v_sqrt_f32_e32 v152, v34
	s_nop 0
	v_add_u32_e32 v153, -1, v152
	v_fma_f32 v154, -v153, v152, v34
	v_cmp_ge_f32_e64 s[6:7], 0, v154
	v_add_u32_e32 v154, 1, v152
	s_nop 0
	v_cndmask_b32_e64 v153, v152, v153, s[6:7]
	v_fma_f32 v152, -v154, v152, v34
	v_cmp_lt_f32_e64 s[6:7], 0, v152
	s_nop 1
	v_cndmask_b32_e64 v152, v153, v154, s[6:7]
	v_mul_f32_e32 v153, 0x37800000, v152
	v_cndmask_b32_e32 v152, v152, v153, vcc
	v_cmp_class_f32_e32 vcc, v34, v173
	s_nop 1
	v_cndmask_b32_e32 v34, v152, v34, vcc
	v_div_scale_f32 v152, s[6:7], v34, v34, 1.0
	v_rcp_f32_e32 v153, v152
	s_nop 0
	v_fma_f32 v154, -v152, v153, 1.0
	v_fmac_f32_e32 v153, v154, v153
	v_div_scale_f32 v154, vcc, 1.0, v34, 1.0
	v_mul_f32_e32 v155, v154, v153
	v_fma_f32 v156, -v152, v155, v154
	v_fmac_f32_e32 v155, v156, v153
	v_fma_f32 v152, -v152, v155, v154
	v_div_fmas_f32 v152, v152, v153, v155
	v_div_fixup_f32 v201, v152, v34, 1.0
	v_add_u32_e32 v152, 0xa0, v140
	v_ashrrev_i32_e32 v153, 31, v152
	v_lshlrev_b64 v[154:155], 6, v[152:153]
	v_lshl_add_u64 v[154:155], s[30:31], 0, v[154:155]
	global_load_dwordx4 v[186:189], v[154:155], off offset:32
	global_load_dwordx4 v[190:193], v[154:155], off offset:48
	global_load_dwordx4 v[208:211], v[154:155], off
	global_load_dwordx4 v[212:215], v[154:155], off offset:16
	v_mul_f32_e32 v164, 0x3f553b94, v201
	s_waitcnt vmcnt(2)
	v_add_f32_e32 v162, v188, v192
	v_add_f32_e32 v163, v189, v193
	v_add_f32_e32 v166, v186, v190
	v_add_f32_e32 v167, v187, v191
	s_waitcnt vmcnt(0)
	v_add_f32_e32 v154, v210, v214
	v_add_f32_e32 v155, v211, v215
	v_add_f32_e32 v158, v208, v212
	v_add_f32_e32 v159, v209, v213
	v_add_f32_e32 v154, v154, v162
	v_add_f32_e32 v155, v155, v163
	v_add_f32_e32 v158, v158, v166
	v_add_f32_e32 v159, v159, v167
	v_add_f32_e32 v154, v154, v155
	v_add_f32_e32 v34, v158, v159
	v_add_f32_e32 v34, v34, v154
	v_fmamk_f32 v34, v34, 0x3b000000, v169
	v_cmp_gt_f32_e32 vcc, s96, v34
	v_mul_f32_e32 v154, 0x4f800000, v34
	s_nop 0
	v_cndmask_b32_e32 v34, v34, v154, vcc
	v_sqrt_f32_e32 v154, v34
	s_nop 0
	v_add_u32_e32 v155, -1, v154
	v_fma_f32 v156, -v155, v154, v34
	v_cmp_ge_f32_e64 s[6:7], 0, v156
	v_add_u32_e32 v156, 1, v154
	s_nop 0
	v_cndmask_b32_e64 v155, v154, v155, s[6:7]
	v_fma_f32 v154, -v156, v154, v34
	v_cmp_lt_f32_e64 s[6:7], 0, v154
	s_nop 1
	v_cndmask_b32_e64 v154, v155, v156, s[6:7]
	v_mul_f32_e32 v155, 0x37800000, v154
	v_cndmask_b32_e32 v154, v154, v155, vcc
	v_cmp_class_f32_e32 vcc, v34, v173
	s_nop 1
	v_cndmask_b32_e32 v34, v154, v34, vcc
	v_div_scale_f32 v154, s[6:7], v34, v34, 1.0
	v_rcp_f32_e32 v155, v154
	s_nop 0
	v_fma_f32 v156, -v154, v155, 1.0
	v_fmac_f32_e32 v155, v156, v155
	v_div_scale_f32 v156, vcc, 1.0, v34, 1.0
	v_mul_f32_e32 v158, v156, v155
	v_fma_f32 v159, -v154, v158, v156
	v_fmac_f32_e32 v158, v159, v155
	v_fma_f32 v154, -v154, v158, v156
	v_div_fmas_f32 v154, v154, v155, v158
	v_div_fixup_f32 v204, v154, v34, 1.0
	v_add_u32_e32 v154, 0xb0, v140
	v_ashrrev_i32_e32 v155, 31, v154
	v_lshlrev_b64 v[158:159], 6, v[154:155]
	v_lshl_add_u64 v[158:159], s[30:31], 0, v[158:159]
	global_load_dwordx4 v[186:189], v[158:159], off offset:32
	global_load_dwordx4 v[190:193], v[158:159], off offset:48
	global_load_dwordx4 v[208:211], v[158:159], off
	global_load_dwordx4 v[212:215], v[158:159], off offset:16
	s_waitcnt vmcnt(2)
	v_add_f32_e32 v166, v188, v192
	v_add_f32_e32 v167, v189, v193
	v_add_f32_e32 v170, v186, v190
	v_add_f32_e32 v171, v187, v191
	s_waitcnt vmcnt(0)
	v_add_f32_e32 v158, v210, v214
	v_add_f32_e32 v159, v211, v215
	v_add_f32_e32 v162, v208, v212
	v_add_f32_e32 v163, v209, v213
	v_add_f32_e32 v158, v158, v166
	v_add_f32_e32 v159, v159, v167
	v_add_f32_e32 v162, v162, v170
	v_add_f32_e32 v163, v163, v171
	v_add_f32_e32 v156, v158, v159
	v_add_f32_e32 v34, v162, v163
	v_add_f32_e32 v34, v34, v156
	v_fmamk_f32 v34, v34, 0x3b000000, v169
	v_cmp_gt_f32_e32 vcc, s96, v34
	v_mul_f32_e32 v156, 0x4f800000, v34
	v_lshlrev_b64 v[186:187], 7, v[140:141]
	v_cndmask_b32_e32 v34, v34, v156, vcc
	v_sqrt_f32_e32 v156, v34
	v_lshlrev_b64 v[170:171], 7, v[148:149]
	v_lshlrev_b64 v[166:167], 7, v[150:151]
	v_add_u32_e32 v158, -1, v156
	v_fma_f32 v159, -v158, v156, v34
	v_cmp_ge_f32_e64 s[6:7], 0, v159
	v_add_u32_e32 v159, 1, v156
	s_nop 0
	v_cndmask_b32_e64 v158, v156, v158, s[6:7]
	v_fma_f32 v156, -v159, v156, v34
	v_cmp_lt_f32_e64 s[6:7], 0, v156
	s_nop 1
	v_cndmask_b32_e64 v156, v158, v159, s[6:7]
	v_mul_f32_e32 v158, 0x37800000, v156
	v_cndmask_b32_e32 v156, v156, v158, vcc
	v_cmp_class_f32_e32 vcc, v34, v173
	s_nop 1
	v_cndmask_b32_e32 v34, v156, v34, vcc
	v_div_scale_f32 v156, s[6:7], v34, v34, 1.0
	v_rcp_f32_e32 v158, v156
	s_nop 0
	v_fma_f32 v159, -v156, v158, 1.0
	v_fmac_f32_e32 v158, v159, v158
	v_div_scale_f32 v159, vcc, 1.0, v34, 1.0
	v_mul_f32_e32 v160, v159, v158
	v_fma_f32 v162, -v156, v160, v159
	v_fmac_f32_e32 v160, v162, v158
	v_fma_f32 v156, -v156, v160, v159
	v_div_fmas_f32 v156, v156, v158, v160
	v_div_fixup_f32 v207, v156, v34, 1.0
	v_lshl_or_b32 v34, v199, 3, s2
	v_or_b32_e32 v208, s92, v34
	v_mul_hi_i32 v34, v208, s97
	v_lshrrev_b32_e32 v156, 31, v34
	v_lshrrev_b32_e32 v34, 5, v34
	v_add_u32_e32 v34, v34, v156
	v_mul_lo_u32 v192, v34, s28
	v_sub_u32_e32 v188, v208, v192
	v_cmp_lt_i32_e32 vcc, s29, v188
	v_ashrrev_i32_e32 v193, 31, v192
	v_mul_f32_e32 v160, 0x3f553b94, v204
	v_lshlrev_b64 v[162:163], 7, v[152:153]
	v_mul_f32_e32 v156, 0x3f553b94, v207
	v_lshlrev_b64 v[158:159], 7, v[154:155]
	s_and_saveexec_b64 s[6:7], vcc
	s_xor_b64 s[6:7], exec, s[6:7]
	s_cbranch_execz .LBB0_575
	v_add_u32_e32 v34, 0xffffff80, v188
	v_lshrrev_b32_e32 v34, 1, v34
	v_lshlrev_b64 v[188:189], 2, v[34:35]
	v_lshl_add_u64 v[190:191], s[16:17], 0, v[188:189]
	v_lshl_add_u64 v[194:195], v[190:191], 0, v[186:187]
	global_load_dwordx4 v[210:213], v[194:195], off
	v_lshl_add_u64 v[194:195], s[14:15], 0, v[188:189]
	v_lshl_add_u64 v[188:189], v[194:195], 0, v[186:187]
	global_load_dwordx4 v[214:217], v[188:189], off
	v_mul_f32_e32 v222, v22, v184
	v_mul_f32_e32 v223, v23, v184
	v_mul_f32_e32 v218, v18, v184
	v_mul_f32_e32 v219, v19, v184
	v_mov_b32_e32 v141, v35
	v_mov_b32_e32 v143, v35
	v_mul_f32_e32 v220, v24, v184
	v_mul_f32_e32 v221, v25, v184
	v_lshl_add_u64 v[188:189], v[192:193], 1, s[26:27]
	v_mul_f32_e32 v192, v20, v184
	v_mul_f32_e32 v193, v21, v184
	v_mad_i64_i32 v[224:225], s[12:13], v140, s10, v[188:189]
	s_waitcnt vmcnt(1)
	v_mul_f32_e32 v228, v222, v210
	v_mul_f32_e32 v229, v223, v211
	v_mul_f32_e32 v210, v218, v210
	v_mul_f32_e32 v211, v219, v211
	v_mul_f32_e32 v226, v220, v212
	v_mul_f32_e32 v227, v221, v213
	s_waitcnt vmcnt(0)
	v_fma_f32 v218, v218, v214, -v228
	v_fma_f32 v219, v219, v215, -v229
	v_fmac_f32_e32 v210, v222, v214
	v_fmac_f32_e32 v211, v223, v215
	v_cvt_pk_fp8_f32 v141, v218, v219
	v_cvt_pk_fp8_f32 v143, v210, v211
	v_mul_f32_e32 v212, v192, v212
	v_mul_f32_e32 v213, v193, v213
	v_fma_f32 v192, v192, v216, -v226
	v_fma_f32 v193, v193, v217, -v227
	v_fma_f32 v210, v220, v216, v212
	v_fma_f32 v211, v221, v217, v213
	v_cvt_pk_fp8_f32 v141, v192, v193 op_sel:[0,0,1]
	v_cvt_pk_fp8_f32 v143, v210, v211 op_sel:[0,0,1]
	v_lshl_add_u64 v[192:193], v[224:225], 0, v[34:35]
	v_lshl_add_u64 v[210:211], v[190:191], 0, v[182:183]
	global_store_dword v[192:193], v141, off offset:256
	global_store_dword v[192:193], v143, off offset:288
	global_load_dwordx4 v[210:213], v[210:211], off
	v_lshl_add_u64 v[192:193], v[194:195], 0, v[182:183]
	global_load_dwordx4 v[214:217], v[192:193], off
	v_mul_f32_e32 v222, v30, v180
	v_mul_f32_e32 v223, v31, v180
	v_mul_f32_e32 v218, v26, v180
	v_mul_f32_e32 v219, v27, v180
	v_mov_b32_e32 v141, v35
	v_mov_b32_e32 v143, v35
	v_mul_f32_e32 v220, v32, v180
	v_mul_f32_e32 v221, v33, v180
	v_mul_f32_e32 v192, v28, v180
	v_mul_f32_e32 v193, v29, v180
	v_mad_i64_i32 v[224:225], s[12:13], v142, s10, v[188:189]
	s_waitcnt vmcnt(1)
	v_mul_f32_e32 v228, v222, v210
	v_mul_f32_e32 v229, v223, v211
	v_mul_f32_e32 v210, v218, v210
	v_mul_f32_e32 v211, v219, v211
	s_waitcnt vmcnt(0)
	v_fma_f32 v218, v218, v214, -v228
	v_fma_f32 v219, v219, v215, -v229
	v_fmac_f32_e32 v210, v222, v214
	v_fmac_f32_e32 v211, v223, v215
	v_cvt_pk_fp8_f32 v141, v218, v219
	v_cvt_pk_fp8_f32 v143, v210, v211
	v_mul_f32_e32 v226, v220, v212
	v_mul_f32_e32 v227, v221, v213
	v_mul_f32_e32 v212, v192, v212
	v_mul_f32_e32 v213, v193, v213
	v_fma_f32 v192, v192, v216, -v226
	v_fma_f32 v193, v193, v217, -v227
	v_fma_f32 v210, v220, v216, v212
	v_fma_f32 v211, v221, v217, v213
	v_cvt_pk_fp8_f32 v141, v192, v193 op_sel:[0,0,1]
	v_cvt_pk_fp8_f32 v143, v210, v211 op_sel:[0,0,1]
	v_lshl_add_u64 v[192:193], v[224:225], 0, v[34:35]
	v_lshl_add_u64 v[210:211], v[190:191], 0, v[178:179]
	global_store_dword v[192:193], v141, off offset:256
	global_store_dword v[192:193], v143, off offset:288
	global_load_dwordx4 v[210:213], v[210:211], off
	v_lshl_add_u64 v[192:193], v[194:195], 0, v[178:179]
	global_load_dwordx4 v[214:217], v[192:193], off
	v_mul_f32_e32 v222, v6, v176
	v_mul_f32_e32 v223, v7, v176
	v_mul_f32_e32 v218, v2, v176
	v_mul_f32_e32 v219, v3, v176
	v_mov_b32_e32 v141, v35
	v_mov_b32_e32 v143, v35
	v_mul_f32_e32 v220, v8, v176
	v_mul_f32_e32 v221, v9, v176
	v_mul_f32_e32 v192, v4, v176
	v_mul_f32_e32 v193, v5, v176
	v_mad_i64_i32 v[224:225], s[12:13], v144, s10, v[188:189]
	s_waitcnt vmcnt(1)
	v_mul_f32_e32 v228, v222, v210
	v_mul_f32_e32 v229, v223, v211
	v_mul_f32_e32 v210, v218, v210
	v_mul_f32_e32 v211, v219, v211
	s_waitcnt vmcnt(0)
	v_fma_f32 v218, v218, v214, -v228
	v_fma_f32 v219, v219, v215, -v229
	v_fmac_f32_e32 v210, v222, v214
	v_fmac_f32_e32 v211, v223, v215
	v_cvt_pk_fp8_f32 v141, v218, v219
	v_cvt_pk_fp8_f32 v143, v210, v211
	v_mul_f32_e32 v226, v220, v212
	v_mul_f32_e32 v227, v221, v213
	v_mul_f32_e32 v212, v192, v212
	v_mul_f32_e32 v213, v193, v213
	v_fma_f32 v192, v192, v216, -v226
	v_fma_f32 v193, v193, v217, -v227
	v_fma_f32 v210, v220, v216, v212
	v_fma_f32 v211, v221, v217, v213
	v_cvt_pk_fp8_f32 v141, v192, v193 op_sel:[0,0,1]
	v_cvt_pk_fp8_f32 v143, v210, v211 op_sel:[0,0,1]
	v_lshl_add_u64 v[192:193], v[224:225], 0, v[34:35]
	v_lshl_add_u64 v[210:211], v[190:191], 0, v[174:175]
	global_store_dword v[192:193], v141, off offset:256
	global_store_dword v[192:193], v143, off offset:288
	global_load_dwordx4 v[210:213], v[210:211], off
	v_lshl_add_u64 v[192:193], v[194:195], 0, v[174:175]
	global_load_dwordx4 v[214:217], v[192:193], off
	v_mul_f32_e32 v222, v14, v172
	v_mul_f32_e32 v223, v15, v172
	v_mul_f32_e32 v218, v10, v172
	v_mul_f32_e32 v219, v11, v172
	v_mov_b32_e32 v141, v35
	v_mov_b32_e32 v143, v35
	v_mul_f32_e32 v220, v16, v172
	v_mul_f32_e32 v221, v17, v172
	v_mul_f32_e32 v192, v12, v172
	v_mul_f32_e32 v193, v13, v172
	v_mad_i64_i32 v[224:225], s[12:13], v146, s10, v[188:189]
	s_waitcnt vmcnt(1)
	v_mul_f32_e32 v228, v222, v210
	v_mul_f32_e32 v229, v223, v211
	v_mul_f32_e32 v210, v218, v210
	v_mul_f32_e32 v211, v219, v211
	s_waitcnt vmcnt(0)
	v_fma_f32 v218, v218, v214, -v228
	v_fma_f32 v219, v219, v215, -v229
	v_fmac_f32_e32 v210, v222, v214
	v_fmac_f32_e32 v211, v223, v215
	v_cvt_pk_fp8_f32 v141, v218, v219
	v_cvt_pk_fp8_f32 v143, v210, v211
	v_mul_f32_e32 v226, v220, v212
	v_mul_f32_e32 v227, v221, v213
	v_mul_f32_e32 v212, v192, v212
	v_mul_f32_e32 v213, v193, v213
	v_fma_f32 v192, v192, v216, -v226
	v_fma_f32 v193, v193, v217, -v227
	v_fma_f32 v210, v220, v216, v212
	v_fma_f32 v211, v221, v217, v213
	v_cvt_pk_fp8_f32 v141, v192, v193 op_sel:[0,0,1]
	v_cvt_pk_fp8_f32 v143, v210, v211 op_sel:[0,0,1]
	v_lshl_add_u64 v[192:193], v[224:225], 0, v[34:35]
	v_lshl_add_u64 v[210:211], v[190:191], 0, v[170:171]
	global_store_dword v[192:193], v141, off offset:256
	global_store_dword v[192:193], v143, off offset:288
	global_load_dwordx4 v[210:213], v[210:211], off
	v_lshl_add_u64 v[192:193], v[194:195], 0, v[170:171]
	global_load_dwordx4 v[214:217], v[192:193], off
	v_mul_f32_e32 v222, v120, v168
	v_mul_f32_e32 v223, v121, v168
	v_mul_f32_e32 v218, v116, v168
	v_mul_f32_e32 v219, v117, v168
	v_mov_b32_e32 v141, v35
	v_mov_b32_e32 v143, v35
	v_mul_f32_e32 v220, v122, v168
	v_mul_f32_e32 v221, v123, v168
	v_mul_f32_e32 v192, v118, v168
	v_mul_f32_e32 v193, v119, v168
	v_mad_i64_i32 v[224:225], s[12:13], v148, s10, v[188:189]
	s_waitcnt vmcnt(1)
	v_mul_f32_e32 v228, v222, v210
	v_mul_f32_e32 v229, v223, v211
	v_mul_f32_e32 v210, v218, v210
	v_mul_f32_e32 v211, v219, v211
	s_waitcnt vmcnt(0)
	v_fma_f32 v218, v218, v214, -v228
	v_fma_f32 v219, v219, v215, -v229
	v_fmac_f32_e32 v210, v222, v214
	v_fmac_f32_e32 v211, v223, v215
	v_cvt_pk_fp8_f32 v141, v218, v219
	v_cvt_pk_fp8_f32 v143, v210, v211
	v_mul_f32_e32 v226, v220, v212
	v_mul_f32_e32 v227, v221, v213
	v_mul_f32_e32 v212, v192, v212
	v_mul_f32_e32 v213, v193, v213
	v_fma_f32 v192, v192, v216, -v226
	v_fma_f32 v193, v193, v217, -v227
	v_fma_f32 v210, v220, v216, v212
	v_fma_f32 v211, v221, v217, v213
	v_cvt_pk_fp8_f32 v141, v192, v193 op_sel:[0,0,1]
	v_cvt_pk_fp8_f32 v143, v210, v211 op_sel:[0,0,1]
	v_lshl_add_u64 v[192:193], v[224:225], 0, v[34:35]
	v_lshl_add_u64 v[210:211], v[190:191], 0, v[166:167]
	global_store_dword v[192:193], v141, off offset:256
	global_store_dword v[192:193], v143, off offset:288
	global_load_dwordx4 v[210:213], v[210:211], off
	v_lshl_add_u64 v[192:193], v[194:195], 0, v[166:167]
	global_load_dwordx4 v[214:217], v[192:193], off
	v_mul_f32_e32 v222, v128, v164
	v_mul_f32_e32 v223, v129, v164
	v_mul_f32_e32 v218, v124, v164
	v_mul_f32_e32 v219, v125, v164
	v_mov_b32_e32 v141, v35
	v_mov_b32_e32 v143, v35
	v_mul_f32_e32 v220, v130, v164
	v_mul_f32_e32 v221, v131, v164
	v_mul_f32_e32 v192, v126, v164
	v_mul_f32_e32 v193, v127, v164
	v_mad_i64_i32 v[224:225], s[12:13], v150, s10, v[188:189]
	s_waitcnt vmcnt(1)
	v_mul_f32_e32 v228, v222, v210
	v_mul_f32_e32 v229, v223, v211
	v_mul_f32_e32 v210, v218, v210
	v_mul_f32_e32 v211, v219, v211
	s_waitcnt vmcnt(0)
	v_fma_f32 v218, v218, v214, -v228
	v_fma_f32 v219, v219, v215, -v229
	v_fmac_f32_e32 v210, v222, v214
	v_fmac_f32_e32 v211, v223, v215
	v_cvt_pk_fp8_f32 v141, v218, v219
	v_cvt_pk_fp8_f32 v143, v210, v211
	v_mul_f32_e32 v226, v220, v212
	v_mul_f32_e32 v227, v221, v213
	v_mul_f32_e32 v212, v192, v212
	v_mul_f32_e32 v213, v193, v213
	v_fma_f32 v192, v192, v216, -v226
	v_fma_f32 v193, v193, v217, -v227
	v_fma_f32 v210, v220, v216, v212
	v_fma_f32 v211, v221, v217, v213
	v_cvt_pk_fp8_f32 v141, v192, v193 op_sel:[0,0,1]
	v_cvt_pk_fp8_f32 v143, v210, v211 op_sel:[0,0,1]
	v_lshl_add_u64 v[192:193], v[224:225], 0, v[34:35]
	v_lshl_add_u64 v[210:211], v[190:191], 0, v[162:163]
	global_store_dword v[192:193], v141, off offset:256
	global_store_dword v[192:193], v143, off offset:288
	global_load_dwordx4 v[210:213], v[210:211], off
	v_lshl_add_u64 v[192:193], v[194:195], 0, v[162:163]
	global_load_dwordx4 v[214:217], v[192:193], off
	v_mul_f32_e32 v222, v104, v160
	v_mul_f32_e32 v223, v105, v160
	v_mul_f32_e32 v218, v100, v160
	v_mul_f32_e32 v219, v101, v160
	v_mov_b32_e32 v141, v35
	v_mov_b32_e32 v143, v35
	v_mul_f32_e32 v220, v106, v160
	v_mul_f32_e32 v221, v107, v160
	v_mul_f32_e32 v192, v102, v160
	v_mul_f32_e32 v193, v103, v160
	v_mad_i64_i32 v[224:225], s[12:13], v152, s10, v[188:189]
	v_lshl_add_u64 v[190:191], v[190:191], 0, v[158:159]
	v_lshl_add_u64 v[194:195], v[194:195], 0, v[158:159]
	v_mad_i64_i32 v[188:189], s[12:13], v154, s10, v[188:189]
	v_lshl_add_u64 v[188:189], v[188:189], 0, v[34:35]
	s_waitcnt vmcnt(1)
	v_mul_f32_e32 v228, v222, v210
	v_mul_f32_e32 v229, v223, v211
	v_mul_f32_e32 v210, v218, v210
	v_mul_f32_e32 v211, v219, v211
	s_waitcnt vmcnt(0)
	v_fma_f32 v218, v218, v214, -v228
	v_fma_f32 v219, v219, v215, -v229
	v_fmac_f32_e32 v210, v222, v214
	v_fmac_f32_e32 v211, v223, v215
	v_cvt_pk_fp8_f32 v141, v218, v219
	v_cvt_pk_fp8_f32 v143, v210, v211
	v_mul_f32_e32 v226, v220, v212
	v_mul_f32_e32 v227, v221, v213
	v_mul_f32_e32 v212, v192, v212
	v_mul_f32_e32 v213, v193, v213
	v_fma_f32 v192, v192, v216, -v226
	v_fma_f32 v193, v193, v217, -v227
	v_fma_f32 v210, v220, v216, v212
	v_fma_f32 v211, v221, v217, v213
	v_cvt_pk_fp8_f32 v141, v192, v193 op_sel:[0,0,1]
	v_cvt_pk_fp8_f32 v143, v210, v211 op_sel:[0,0,1]
	v_lshl_add_u64 v[192:193], v[224:225], 0, v[34:35]
	global_store_dword v[192:193], v141, off offset:256
	global_store_dword v[192:193], v143, off offset:288
	global_load_dwordx4 v[190:193], v[190:191], off
	v_mul_f32_e32 v218, v112, v156
	v_mul_f32_e32 v219, v113, v156
	global_load_dwordx4 v[210:213], v[194:195], off
	v_mul_f32_e32 v214, v108, v156
	v_mul_f32_e32 v215, v109, v156
	v_mov_b32_e32 v141, v35
	v_mov_b32_e32 v143, v35
	v_mul_f32_e32 v216, v114, v156
	v_mul_f32_e32 v217, v115, v156
	v_mul_f32_e32 v194, v110, v156
	v_mul_f32_e32 v195, v111, v156
	s_waitcnt vmcnt(1)
	v_mul_f32_e32 v222, v218, v190
	v_mul_f32_e32 v223, v219, v191
	v_mul_f32_e32 v190, v214, v190
	v_mul_f32_e32 v191, v215, v191
	s_waitcnt vmcnt(0)
	v_fma_f32 v214, v214, v210, -v222
	v_fma_f32 v215, v215, v211, -v223
	v_fmac_f32_e32 v190, v218, v210
	v_fmac_f32_e32 v191, v219, v211
	v_cvt_pk_fp8_f32 v141, v214, v215
	v_cvt_pk_fp8_f32 v143, v190, v191
	v_mul_f32_e32 v220, v216, v192
	v_mul_f32_e32 v221, v217, v193
	v_mul_f32_e32 v192, v194, v192
	v_mul_f32_e32 v193, v195, v193
	v_fma_f32 v190, v194, v212, -v220
	v_fma_f32 v191, v195, v213, -v221
	v_fmac_f32_e32 v192, v216, v212
	v_fmac_f32_e32 v193, v217, v213
	v_cvt_pk_fp8_f32 v141, v190, v191 op_sel:[0,0,1]
	v_cvt_pk_fp8_f32 v143, v192, v193 op_sel:[0,0,1]
	global_store_dword v[188:189], v141, off offset:256
	global_store_dword v[188:189], v143, off offset:288

.LBB0_584:
	s_or_b64 exec, exec, s[4:5]
	v_mul_f32_e32 v194, 0x3dd53b94, v139
	v_mul_f32_e32 v18, v194, v18
	v_mul_f32_e32 v19, v194, v19
	v_mul_f32_e32 v2, v194, v2
	v_mul_f32_e32 v3, v194, v3
	v_mul_f32_e32 v20, v194, v20
	v_mul_f32_e32 v21, v194, v21
	v_mul_f32_e32 v4, v194, v4
	v_mul_f32_e32 v5, v194, v5
	v_max_f32_e64 v139, |v18|, |v2|
	v_max_f32_e64 v143, |v19|, |v3|
	v_mul_f32_e32 v22, v194, v22
	v_mul_f32_e32 v23, v194, v23
	v_mul_f32_e32 v6, v194, v6
	v_mul_f32_e32 v7, v194, v7
	v_max3_f32 v139, v139, 0, v143
	v_max_f32_e64 v143, |v20|, |v4|
	v_max_f32_e64 v145, |v21|, |v5|
	v_mul_f32_e32 v24, v194, v24
	v_mul_f32_e32 v25, v194, v25
	v_mul_f32_e32 v8, v194, v8
	v_mul_f32_e32 v9, v194, v9
	v_max3_f32 v139, v139, v143, v145
	v_max_f32_e64 v143, |v22|, |v6|
	v_max_f32_e64 v145, |v23|, |v7|
	v_mul_f32_e32 v26, v194, v26
	v_mul_f32_e32 v27, v194, v27
	v_mul_f32_e32 v10, v194, v10
	v_mul_f32_e32 v11, v194, v11
	v_max3_f32 v139, v139, v143, v145
	v_max_f32_e64 v143, |v24|, |v8|
	v_max_f32_e64 v145, |v25|, |v9|
	v_mul_f32_e32 v28, v194, v28
	v_mul_f32_e32 v29, v194, v29
	v_mul_f32_e32 v12, v194, v12
	v_mul_f32_e32 v13, v194, v13
	v_max3_f32 v139, v139, v143, v145
	v_max_f32_e64 v143, |v26|, |v10|
	v_max_f32_e64 v145, |v27|, |v11|
	v_mul_f32_e32 v30, v194, v30
	v_mul_f32_e32 v31, v194, v31
	v_mul_f32_e32 v14, v194, v14
	v_mul_f32_e32 v15, v194, v15
	v_max3_f32 v139, v139, v143, v145
	v_max_f32_e64 v143, |v28|, |v12|
	v_max_f32_e64 v145, |v29|, |v13|
	v_mul_f32_e32 v32, v194, v32
	v_mul_f32_e32 v33, v194, v33
	v_mul_f32_e32 v16, v194, v16
	v_mul_f32_e32 v17, v194, v17
	v_max3_f32 v139, v139, v143, v145
	v_max_f32_e64 v143, |v30|, |v14|
	v_max_f32_e64 v145, |v31|, |v15|
	v_max3_f32 v139, v139, v143, v145
	v_max_f32_e64 v143, |v32|, |v16|
	v_max_f32_e64 v145, |v33|, |v17|
	v_max3_f32 v139, v139, v143, v145
	v_cmp_gt_u32_e32 vcc, 64, v188
	v_bfe_u32 v143, v139, 23, 8
	v_and_b32_e32 v139, 0x7fffff, v139
	v_cndmask_b32_e32 v34, v177, v181, vcc
	v_cndmask_b32_e64 v190, 64, 0, vcc
	v_cmp_gt_u32_e32 vcc, s11, v139
	v_mov_b64_e32 v[194:195], s[26:27]
	v_mad_i64_i32 v[194:195], s[4:5], v141, s10, v[194:195]
	v_cndmask_b32_e64 v139, -2, -3, vcc
	v_add3_u32 v139, v143, v139, s0
	v_max_i32_e32 v139, 0xffffff88, v139
	v_add_u32_e32 v139, 0x7f, v139
	v_lshl_add_u64 v[194:195], v[192:193], 1, v[194:195]
	v_and_b32_e32 v188, 32, v188
	v_mov_b32_e32 v189, v35
	v_lshlrev_b32_e32 v196, 23, v139
	v_lshl_add_u64 v[218:219], v[194:195], 0, v[34:35]
	v_cvt_scalef32_2xpk16_fp6_f32 v[210:215], v[18:33], v[2:17], v196
	v_sub_u32_e32 v198, 0x7f000000, v196
	v_lshl_add_u64 v[218:219], v[218:219], 0, v[188:189]
	global_store_dwordx4 v[218:219], v[210:213], off
	v_mul_lo_u32 v216, v139, s1
	v_mov_b32_e32 v217, v35
	v_mul_f32_e32 v210, v18, v198
	v_mul_f32_e32 v211, v19, v198
	v_mul_f32_e32 v212, v2, v198
	v_mul_f32_e32 v213, v3, v198
	v_cmp_lt_f32_e64 vcc, |v210|, 4.0
	v_and_b32_e32 v139, 0x7fffffff, v210
	global_store_dwordx4 v[218:219], v[214:217], off offset:16
	v_cndmask_b32_e32 v143, 0.5, v185, vcc
	v_cmp_nlt_f32_e64 vcc, |v210|, 2.0
	v_mul_f32_e32 v214, v20, v198
	v_mul_f32_e32 v215, v21, v198
	v_mov_b32_e32 v191, v35
	v_cndmask_b32_e32 v143, v197, v143, vcc
	v_permlane32_swap_b32_e32 v116, v100
	v_cmp_lt_f32_e64 vcc, |v211|, 4.0
	v_and_b32_e32 v145, 0x7fffffff, v211
	v_sub_u32_e32 v147, 0x7f000000, v143
	v_mul_f32_e64 v139, |v210|, v147
	v_cndmask_b32_e32 v147, 0.5, v185, vcc
	v_cmp_nlt_f32_e64 vcc, |v211|, 2.0
	v_rndne_f32_e32 v139, v139
	v_mul_f32_e32 v139, v143, v139
	v_cndmask_b32_e32 v147, v197, v147, vcc
	v_min_f32_e32 v139, 0x40f00000, v139
	v_bfi_b32 v210, s22, v139, v210
	v_permlane32_swap_b32_e32 v117, v101
	v_sub_u32_e32 v145, 0x7f000000, v147
	v_mul_f32_e64 v143, |v211|, v145
	v_rndne_f32_e32 v143, v143
	v_mul_f32_e32 v143, v147, v143
	v_cmp_lt_f32_e64 vcc, |v212|, 4.0
	v_min_f32_e32 v143, 0x40f00000, v143
	v_bfi_b32 v211, s22, v143, v211
	v_cndmask_b32_e32 v145, 0.5, v185, vcc
	v_cmp_nlt_f32_e64 vcc, |v212|, 2.0
	v_and_b32_e32 v143, 0x7fffffff, v212
	v_mul_f32_e32 v210, v210, v196
	v_mul_f32_e32 v211, v211, v196
	v_cndmask_b32_e32 v145, v197, v145, vcc
	v_fma_f32 v18, v18, 2.0, -v210
	v_fma_f32 v19, v19, 2.0, -v211
	v_permlane32_swap_b32_e32 v118, v102
	v_cmp_lt_f32_e64 vcc, |v213|, 4.0
	v_and_b32_e32 v143, 0x7fffffff, v213
	v_sub_u32_e32 v147, 0x7f000000, v145
	v_mul_f32_e64 v139, |v212|, v147
	v_cndmask_b32_e32 v147, 0.5, v185, vcc
	v_cmp_nlt_f32_e64 vcc, |v213|, 2.0
	v_rndne_f32_e32 v139, v139
	v_mul_f32_e32 v139, v145, v139
	v_cndmask_b32_e32 v147, v197, v147, vcc
	v_min_f32_e32 v139, 0x40f00000, v139
	v_sub_u32_e32 v145, 0x7f000000, v147
	v_mul_f32_e64 v143, |v213|, v145
	v_rndne_f32_e32 v143, v143
	v_mul_f32_e32 v143, v147, v143
	v_cmp_lt_f32_e64 vcc, |v214|, 4.0
	v_min_f32_e32 v143, 0x40f00000, v143
	v_bfi_b32 v211, s22, v143, v213
	v_cndmask_b32_e32 v145, 0.5, v185, vcc
	v_cmp_nlt_f32_e64 vcc, |v214|, 2.0
	v_and_b32_e32 v143, 0x7fffffff, v214
	v_bfi_b32 v210, s22, v139, v212
	v_cndmask_b32_e32 v145, v197, v145, vcc
	v_mul_f32_e32 v212, v4, v198
	v_mul_f32_e32 v213, v5, v198
	v_mul_f32_e32 v210, v210, v196
	v_mul_f32_e32 v211, v211, v196
	v_permlane32_swap_b32_e32 v119, v103
	v_cmp_lt_f32_e64 vcc, |v215|, 4.0
	v_and_b32_e32 v143, 0x7fffffff, v215
	v_sub_u32_e32 v147, 0x7f000000, v145
	v_mul_f32_e64 v139, |v214|, v147
	v_cndmask_b32_e32 v147, 0.5, v185, vcc
	v_cmp_nlt_f32_e64 vcc, |v215|, 2.0
	v_rndne_f32_e32 v139, v139
	v_mul_f32_e32 v139, v145, v139
	v_cndmask_b32_e32 v147, v197, v147, vcc
	v_fma_f32 v2, v2, 2.0, -v210
	v_fma_f32 v3, v3, 2.0, -v211
	v_sub_u32_e32 v145, 0x7f000000, v147
	v_mul_f32_e64 v143, |v215|, v145
	v_rndne_f32_e32 v143, v143
	v_mul_f32_e32 v143, v147, v143
	v_cmp_lt_f32_e64 vcc, |v212|, 4.0
	v_min_f32_e32 v143, 0x40f00000, v143
	v_bfi_b32 v211, s22, v143, v215
	v_cndmask_b32_e32 v145, 0.5, v185, vcc
	v_cmp_nlt_f32_e64 vcc, |v212|, 2.0
	v_and_b32_e32 v143, 0x7fffffff, v212
	v_min_f32_e32 v139, 0x40f00000, v139
	v_cndmask_b32_e32 v145, v197, v145, vcc
	v_bfi_b32 v210, s22, v139, v214
	v_mul_f32_e32 v214, v22, v198
	v_mul_f32_e32 v215, v23, v198
	v_mul_f32_e32 v210, v210, v196
	v_mul_f32_e32 v211, v211, v196
	v_cmp_lt_f32_e64 vcc, |v213|, 4.0
	v_and_b32_e32 v143, 0x7fffffff, v213
	v_sub_u32_e32 v147, 0x7f000000, v145
	v_mul_f32_e64 v139, |v212|, v147
	v_cndmask_b32_e32 v147, 0.5, v185, vcc
	v_cmp_nlt_f32_e64 vcc, |v213|, 2.0
	v_rndne_f32_e32 v139, v139
	v_mul_f32_e32 v139, v145, v139
	v_cndmask_b32_e32 v147, v197, v147, vcc
	v_fma_f32 v20, v20, 2.0, -v210
	v_fma_f32 v21, v21, 2.0, -v211
	v_sub_u32_e32 v145, 0x7f000000, v147
	v_mul_f32_e64 v143, |v213|, v145
	v_rndne_f32_e32 v143, v143
	v_mul_f32_e32 v143, v147, v143
	v_cmp_lt_f32_e64 vcc, |v214|, 4.0
	v_min_f32_e32 v143, 0x40f00000, v143
	v_bfi_b32 v211, s22, v143, v213
	v_cndmask_b32_e32 v145, 0.5, v185, vcc
	v_cmp_nlt_f32_e64 vcc, |v214|, 2.0
	v_and_b32_e32 v143, 0x7fffffff, v214
	v_min_f32_e32 v139, 0x40f00000, v139
	v_cndmask_b32_e32 v145, v197, v145, vcc
	v_bfi_b32 v210, s22, v139, v212
	v_mul_f32_e32 v212, v6, v198
	v_mul_f32_e32 v213, v7, v198
	v_mul_f32_e32 v210, v210, v196
	v_mul_f32_e32 v211, v211, v196
	v_cmp_lt_f32_e64 vcc, |v215|, 4.0
	v_and_b32_e32 v143, 0x7fffffff, v215
	v_sub_u32_e32 v147, 0x7f000000, v145
	v_mul_f32_e64 v139, |v214|, v147
	v_cndmask_b32_e32 v147, 0.5, v185, vcc
	v_cmp_nlt_f32_e64 vcc, |v215|, 2.0
	v_rndne_f32_e32 v139, v139
	v_mul_f32_e32 v139, v145, v139
	v_cndmask_b32_e32 v147, v197, v147, vcc
	v_fma_f32 v4, v4, 2.0, -v210
	v_fma_f32 v5, v5, 2.0, -v211
	v_sub_u32_e32 v145, 0x7f000000, v147
	v_mul_f32_e64 v143, |v215|, v145
	v_rndne_f32_e32 v143, v143
	v_mul_f32_e32 v143, v147, v143
	v_cmp_lt_f32_e64 vcc, |v212|, 4.0
	v_min_f32_e32 v143, 0x40f00000, v143
	v_bfi_b32 v211, s22, v143, v215
	v_cndmask_b32_e32 v145, 0.5, v185, vcc
	v_cmp_nlt_f32_e64 vcc, |v212|, 2.0
	v_and_b32_e32 v143, 0x7fffffff, v212
	v_min_f32_e32 v139, 0x40f00000, v139
	v_cndmask_b32_e32 v145, v197, v145, vcc
	v_bfi_b32 v210, s22, v139, v214
	v_mul_f32_e32 v214, v24, v198
	v_mul_f32_e32 v215, v25, v198
	v_mul_f32_e32 v210, v210, v196
	v_mul_f32_e32 v211, v211, v196
	v_cmp_lt_f32_e64 vcc, |v213|, 4.0
	v_and_b32_e32 v143, 0x7fffffff, v213
	v_sub_u32_e32 v147, 0x7f000000, v145
	v_mul_f32_e64 v139, |v212|, v147
	v_cndmask_b32_e32 v147, 0.5, v185, vcc
	v_cmp_nlt_f32_e64 vcc, |v213|, 2.0
	v_rndne_f32_e32 v139, v139
	v_mul_f32_e32 v139, v145, v139
	v_cndmask_b32_e32 v147, v197, v147, vcc
	v_fma_f32 v22, v22, 2.0, -v210
	v_fma_f32 v23, v23, 2.0, -v211
	v_sub_u32_e32 v145, 0x7f000000, v147
	v_mul_f32_e64 v143, |v213|, v145
	v_rndne_f32_e32 v143, v143
	v_mul_f32_e32 v143, v147, v143
	v_cmp_lt_f32_e64 vcc, |v214|, 4.0
	v_min_f32_e32 v143, 0x40f00000, v143
	v_bfi_b32 v211, s22, v143, v213
	v_cndmask_b32_e32 v145, 0.5, v185, vcc
	v_cmp_nlt_f32_e64 vcc, |v214|, 2.0
	v_and_b32_e32 v143, 0x7fffffff, v214
	v_min_f32_e32 v139, 0x40f00000, v139
	v_cndmask_b32_e32 v145, v197, v145, vcc
	v_bfi_b32 v210, s22, v139, v212
	v_mul_f32_e32 v212, v8, v198
	v_mul_f32_e32 v213, v9, v198
	v_mul_f32_e32 v210, v210, v196
	v_mul_f32_e32 v211, v211, v196
	v_cmp_lt_f32_e64 vcc, |v215|, 4.0
	v_and_b32_e32 v143, 0x7fffffff, v215
	v_sub_u32_e32 v147, 0x7f000000, v145
	v_mul_f32_e64 v139, |v214|, v147
	v_cndmask_b32_e32 v147, 0.5, v185, vcc
	v_cmp_nlt_f32_e64 vcc, |v215|, 2.0
	v_rndne_f32_e32 v139, v139
	v_mul_f32_e32 v139, v145, v139
	v_cndmask_b32_e32 v147, v197, v147, vcc
	v_fma_f32 v6, v6, 2.0, -v210
	v_fma_f32 v7, v7, 2.0, -v211
	v_sub_u32_e32 v145, 0x7f000000, v147
	v_mul_f32_e64 v143, |v215|, v145
	v_rndne_f32_e32 v143, v143
	v_mul_f32_e32 v143, v147, v143
	v_cmp_lt_f32_e64 vcc, |v212|, 4.0
	v_min_f32_e32 v143, 0x40f00000, v143
	v_bfi_b32 v211, s22, v143, v215
	v_cndmask_b32_e32 v145, 0.5, v185, vcc
	v_cmp_nlt_f32_e64 vcc, |v212|, 2.0
	v_and_b32_e32 v143, 0x7fffffff, v212
	v_min_f32_e32 v139, 0x40f00000, v139
	v_cndmask_b32_e32 v145, v197, v145, vcc
	v_bfi_b32 v210, s22, v139, v214
	v_mul_f32_e32 v214, v26, v198
	v_mul_f32_e32 v215, v27, v198
	v_mul_f32_e32 v210, v210, v196
	v_mul_f32_e32 v211, v211, v196
	v_cmp_lt_f32_e64 vcc, |v213|, 4.0
	v_and_b32_e32 v143, 0x7fffffff, v213
	v_sub_u32_e32 v147, 0x7f000000, v145
	v_mul_f32_e64 v139, |v212|, v147
	v_cndmask_b32_e32 v147, 0.5, v185, vcc
	v_cmp_nlt_f32_e64 vcc, |v213|, 2.0
	v_rndne_f32_e32 v139, v139
	v_mul_f32_e32 v139, v145, v139
	v_cndmask_b32_e32 v147, v197, v147, vcc
	v_fma_f32 v24, v24, 2.0, -v210
	v_fma_f32 v25, v25, 2.0, -v211
	v_sub_u32_e32 v145, 0x7f000000, v147
	v_mul_f32_e64 v143, |v213|, v145
	v_rndne_f32_e32 v143, v143
	v_mul_f32_e32 v143, v147, v143
	v_cmp_lt_f32_e64 vcc, |v214|, 4.0
	v_min_f32_e32 v143, 0x40f00000, v143
	v_bfi_b32 v211, s22, v143, v213
	v_cndmask_b32_e32 v145, 0.5, v185, vcc
	v_cmp_nlt_f32_e64 vcc, |v214|, 2.0
	v_and_b32_e32 v143, 0x7fffffff, v214
	v_min_f32_e32 v139, 0x40f00000, v139
	v_cndmask_b32_e32 v145, v197, v145, vcc
	v_bfi_b32 v210, s22, v139, v212
	v_mul_f32_e32 v212, v10, v198
	v_mul_f32_e32 v213, v11, v198
	v_mul_f32_e32 v210, v210, v196
	v_mul_f32_e32 v211, v211, v196
	v_cmp_lt_f32_e64 vcc, |v215|, 4.0
	v_and_b32_e32 v143, 0x7fffffff, v215
	v_sub_u32_e32 v147, 0x7f000000, v145
	v_mul_f32_e64 v139, |v214|, v147
	v_cndmask_b32_e32 v147, 0.5, v185, vcc
	v_cmp_nlt_f32_e64 vcc, |v215|, 2.0
	v_rndne_f32_e32 v139, v139
	v_mul_f32_e32 v139, v145, v139
	v_cndmask_b32_e32 v147, v197, v147, vcc
	v_fma_f32 v8, v8, 2.0, -v210
	v_fma_f32 v9, v9, 2.0, -v211
	v_sub_u32_e32 v145, 0x7f000000, v147
	v_mul_f32_e64 v143, |v215|, v145
	v_rndne_f32_e32 v143, v143
	v_mul_f32_e32 v143, v147, v143
	v_cmp_lt_f32_e64 vcc, |v212|, 4.0
	v_min_f32_e32 v143, 0x40f00000, v143
	v_bfi_b32 v211, s22, v143, v215
	v_cndmask_b32_e32 v145, 0.5, v185, vcc
	v_cmp_nlt_f32_e64 vcc, |v212|, 2.0
	v_and_b32_e32 v143, 0x7fffffff, v212
	v_min_f32_e32 v139, 0x40f00000, v139
	v_cndmask_b32_e32 v145, v197, v145, vcc
	v_bfi_b32 v210, s22, v139, v214
	v_mul_f32_e32 v214, v28, v198
	v_mul_f32_e32 v215, v29, v198
	v_mul_f32_e32 v210, v210, v196
	v_mul_f32_e32 v211, v211, v196
	v_cmp_lt_f32_e64 vcc, |v213|, 4.0
	v_and_b32_e32 v143, 0x7fffffff, v213
	v_sub_u32_e32 v147, 0x7f000000, v145
	v_mul_f32_e64 v139, |v212|, v147
	v_cndmask_b32_e32 v147, 0.5, v185, vcc
	v_cmp_nlt_f32_e64 vcc, |v213|, 2.0
	v_rndne_f32_e32 v139, v139
	v_mul_f32_e32 v139, v145, v139
	v_cndmask_b32_e32 v147, v197, v147, vcc
	v_fma_f32 v26, v26, 2.0, -v210
	v_fma_f32 v27, v27, 2.0, -v211
	v_sub_u32_e32 v145, 0x7f000000, v147
	v_mul_f32_e64 v143, |v213|, v145
	v_rndne_f32_e32 v143, v143
	v_mul_f32_e32 v143, v147, v143
	v_cmp_lt_f32_e64 vcc, |v214|, 4.0
	v_min_f32_e32 v143, 0x40f00000, v143
	v_bfi_b32 v211, s22, v143, v213
	v_cndmask_b32_e32 v145, 0.5, v185, vcc
	v_cmp_nlt_f32_e64 vcc, |v214|, 2.0
	v_and_b32_e32 v143, 0x7fffffff, v214
	v_min_f32_e32 v139, 0x40f00000, v139
	v_cndmask_b32_e32 v145, v197, v145, vcc
	v_bfi_b32 v210, s22, v139, v212
	v_mul_f32_e32 v212, v12, v198
	v_mul_f32_e32 v213, v13, v198
	v_mul_f32_e32 v210, v210, v196
	v_mul_f32_e32 v211, v211, v196
	v_cmp_lt_f32_e64 vcc, |v215|, 4.0
	v_and_b32_e32 v143, 0x7fffffff, v215
	v_sub_u32_e32 v147, 0x7f000000, v145
	v_mul_f32_e64 v139, |v214|, v147
	v_cndmask_b32_e32 v147, 0.5, v185, vcc
	v_cmp_nlt_f32_e64 vcc, |v215|, 2.0
	v_rndne_f32_e32 v139, v139
	v_mul_f32_e32 v139, v145, v139
	v_cndmask_b32_e32 v147, v197, v147, vcc
	v_fma_f32 v10, v10, 2.0, -v210
	v_fma_f32 v11, v11, 2.0, -v211
	v_sub_u32_e32 v145, 0x7f000000, v147
	v_mul_f32_e64 v143, |v215|, v145
	v_rndne_f32_e32 v143, v143
	v_mul_f32_e32 v143, v147, v143
	v_cmp_lt_f32_e64 vcc, |v212|, 4.0
	v_min_f32_e32 v143, 0x40f00000, v143
	v_bfi_b32 v211, s22, v143, v215
	v_cndmask_b32_e32 v145, 0.5, v185, vcc
	v_cmp_nlt_f32_e64 vcc, |v212|, 2.0
	v_and_b32_e32 v143, 0x7fffffff, v212
	v_min_f32_e32 v139, 0x40f00000, v139
	v_cndmask_b32_e32 v145, v197, v145, vcc
	v_bfi_b32 v210, s22, v139, v214
	v_mul_f32_e32 v214, v30, v198
	v_mul_f32_e32 v215, v31, v198
	v_mul_f32_e32 v210, v210, v196
	v_mul_f32_e32 v211, v211, v196
	v_cmp_lt_f32_e64 vcc, |v213|, 4.0
	v_and_b32_e32 v143, 0x7fffffff, v213
	v_sub_u32_e32 v147, 0x7f000000, v145
	v_mul_f32_e64 v139, |v212|, v147
	v_cndmask_b32_e32 v147, 0.5, v185, vcc
	v_cmp_nlt_f32_e64 vcc, |v213|, 2.0
	v_rndne_f32_e32 v139, v139
	v_mul_f32_e32 v139, v145, v139
	v_cndmask_b32_e32 v147, v197, v147, vcc
	v_fma_f32 v28, v28, 2.0, -v210
	v_fma_f32 v29, v29, 2.0, -v211
	v_sub_u32_e32 v145, 0x7f000000, v147
	v_mul_f32_e64 v143, |v213|, v145
	v_rndne_f32_e32 v143, v143
	v_mul_f32_e32 v143, v147, v143
	v_cmp_lt_f32_e64 vcc, |v214|, 4.0
	v_min_f32_e32 v143, 0x40f00000, v143
	v_bfi_b32 v211, s22, v143, v213
	v_cndmask_b32_e32 v145, 0.5, v185, vcc
	v_cmp_nlt_f32_e64 vcc, |v214|, 2.0
	v_and_b32_e32 v143, 0x7fffffff, v214
	v_min_f32_e32 v139, 0x40f00000, v139
	v_cndmask_b32_e32 v145, v197, v145, vcc
	v_bfi_b32 v210, s22, v139, v212
	v_mul_f32_e32 v212, v14, v198
	v_mul_f32_e32 v213, v15, v198
	v_mul_f32_e32 v210, v210, v196
	v_mul_f32_e32 v211, v211, v196
	v_cmp_lt_f32_e64 vcc, |v215|, 4.0
	v_and_b32_e32 v143, 0x7fffffff, v215
	v_sub_u32_e32 v147, 0x7f000000, v145
	v_mul_f32_e64 v139, |v214|, v147
	v_cndmask_b32_e32 v147, 0.5, v185, vcc
	v_cmp_nlt_f32_e64 vcc, |v215|, 2.0
	v_rndne_f32_e32 v139, v139
	v_mul_f32_e32 v139, v145, v139
	v_cndmask_b32_e32 v147, v197, v147, vcc
	v_fma_f32 v12, v12, 2.0, -v210
	v_fma_f32 v13, v13, 2.0, -v211
	v_sub_u32_e32 v145, 0x7f000000, v147
	v_mul_f32_e64 v143, |v215|, v145
	v_rndne_f32_e32 v143, v143
	v_mul_f32_e32 v143, v147, v143
	v_cmp_lt_f32_e64 vcc, |v212|, 4.0
	v_min_f32_e32 v143, 0x40f00000, v143
	v_bfi_b32 v211, s22, v143, v215
	v_cndmask_b32_e32 v145, 0.5, v185, vcc
	v_cmp_nlt_f32_e64 vcc, |v212|, 2.0
	v_and_b32_e32 v143, 0x7fffffff, v212
	v_min_f32_e32 v139, 0x40f00000, v139
	v_cndmask_b32_e32 v145, v197, v145, vcc
	v_bfi_b32 v210, s22, v139, v214
	v_mul_f32_e32 v214, v32, v198
	v_mul_f32_e32 v215, v33, v198
	v_mul_f32_e32 v210, v210, v196
	v_mul_f32_e32 v211, v211, v196
	v_cmp_lt_f32_e64 vcc, |v213|, 4.0
	v_and_b32_e32 v143, 0x7fffffff, v213
	v_sub_u32_e32 v147, 0x7f000000, v145
	v_mul_f32_e64 v139, |v212|, v147
	v_cndmask_b32_e32 v147, 0.5, v185, vcc
	v_cmp_nlt_f32_e64 vcc, |v213|, 2.0
	v_rndne_f32_e32 v139, v139
	v_mul_f32_e32 v139, v145, v139
	v_cndmask_b32_e32 v147, v197, v147, vcc
	v_fma_f32 v30, v30, 2.0, -v210
	v_fma_f32 v31, v31, 2.0, -v211
	v_sub_u32_e32 v145, 0x7f000000, v147
	v_mul_f32_e64 v143, |v213|, v145
	v_rndne_f32_e32 v143, v143
	v_mul_f32_e32 v143, v147, v143
	v_cmp_lt_f32_e64 vcc, |v214|, 4.0
	v_min_f32_e32 v143, 0x40f00000, v143
	v_bfi_b32 v211, s22, v143, v213
	v_cndmask_b32_e32 v145, 0.5, v185, vcc
	v_cmp_nlt_f32_e64 vcc, |v214|, 2.0
	v_and_b32_e32 v143, 0x7fffffff, v214
	v_min_f32_e32 v139, 0x40f00000, v139
	v_cndmask_b32_e32 v145, v197, v145, vcc
	v_bfi_b32 v210, s22, v139, v212
	v_mul_f32_e32 v212, v16, v198
	v_mul_f32_e32 v213, v17, v198
	v_mul_f32_e32 v210, v210, v196
	v_mul_f32_e32 v211, v211, v196
	v_cmp_lt_f32_e64 vcc, |v215|, 4.0
	v_and_b32_e32 v143, 0x7fffffff, v215
	v_sub_u32_e32 v147, 0x7f000000, v145
	v_mul_f32_e64 v139, |v214|, v147
	v_cndmask_b32_e32 v147, 0.5, v185, vcc
	v_cmp_nlt_f32_e64 vcc, |v215|, 2.0
	v_rndne_f32_e32 v139, v139
	v_mul_f32_e32 v139, v145, v139
	v_cndmask_b32_e32 v147, v197, v147, vcc
	v_fma_f32 v14, v14, 2.0, -v210
	v_fma_f32 v15, v15, 2.0, -v211
	v_sub_u32_e32 v145, 0x7f000000, v147
	v_mul_f32_e64 v143, |v215|, v145
	v_rndne_f32_e32 v143, v143
	v_mul_f32_e32 v143, v147, v143
	v_cmp_lt_f32_e64 vcc, |v212|, 4.0
	v_min_f32_e32 v143, 0x40f00000, v143
	v_bfi_b32 v211, s22, v143, v215
	v_cndmask_b32_e32 v145, 0.5, v185, vcc
	v_cmp_nlt_f32_e64 vcc, |v212|, 2.0
	v_and_b32_e32 v143, 0x7fffffff, v212
	v_min_f32_e32 v139, 0x40f00000, v139
	v_cndmask_b32_e32 v145, v197, v145, vcc
	v_bfi_b32 v210, s22, v139, v214
	v_mul_f32_e32 v210, v210, v196
	v_mul_f32_e32 v211, v211, v196
	v_permlane32_swap_b32_e32 v120, v104
	v_cmp_lt_f32_e64 vcc, |v213|, 4.0
	v_and_b32_e32 v143, 0x7fffffff, v213
	v_sub_u32_e32 v147, 0x7f000000, v145
	v_mul_f32_e64 v139, |v212|, v147
	v_cndmask_b32_e32 v147, 0.5, v185, vcc
	v_cmp_nlt_f32_e64 vcc, |v213|, 2.0
	v_rndne_f32_e32 v139, v139
	v_mul_f32_e32 v139, v145, v139
	v_cndmask_b32_e32 v147, v197, v147, vcc
	v_min_f32_e32 v139, 0x40f00000, v139
	v_sub_u32_e32 v145, 0x7f000000, v147
	v_mul_f32_e64 v143, |v213|, v145
	v_rndne_f32_e32 v143, v143
	v_mul_f32_e32 v143, v147, v143
	v_min_f32_e32 v143, 0x40f00000, v143
	v_fma_f32 v32, v32, 2.0, -v210
	v_fma_f32 v33, v33, 2.0, -v211
	v_bfi_b32 v211, s22, v143, v213
	v_bfi_b32 v210, s22, v139, v212
	v_max_f32_e64 v139, |v18|, |v2|
	v_max_f32_e64 v143, |v19|, |v3|
	v_max3_f32 v139, v139, 0, v143
	v_max_f32_e64 v143, |v20|, |v4|
	v_max_f32_e64 v145, |v21|, |v5|
	v_max3_f32 v139, v139, v143, v145
	v_max_f32_e64 v143, |v22|, |v6|
	v_max_f32_e64 v145, |v23|, |v7|
	v_max3_f32 v139, v139, v143, v145
	v_max_f32_e64 v143, |v24|, |v8|
	v_max_f32_e64 v145, |v25|, |v9|
	v_max3_f32 v139, v139, v143, v145
	v_max_f32_e64 v143, |v26|, |v10|
	v_max_f32_e64 v145, |v27|, |v11|
	v_mul_f32_e32 v210, v210, v196
	v_mul_f32_e32 v211, v211, v196
	v_max3_f32 v139, v139, v143, v145
	v_max_f32_e64 v143, |v28|, |v12|
	v_max_f32_e64 v145, |v29|, |v13|
	v_fma_f32 v16, v16, 2.0, -v210
	v_fma_f32 v17, v17, 2.0, -v211
	v_max3_f32 v139, v139, v143, v145
	v_max_f32_e64 v143, |v30|, |v14|
	v_max_f32_e64 v145, |v31|, |v15|
	v_max3_f32 v139, v139, v143, v145
	v_max_f32_e64 v143, |v32|, |v16|
	v_max_f32_e64 v145, |v33|, |v17|
	v_max3_f32 v139, v139, v143, v145
	v_bfe_u32 v143, v139, 23, 8
	v_and_b32_e32 v139, 0x7fffff, v139
	v_cmp_gt_u32_e32 vcc, s11, v139
	v_permlane32_swap_b32_e32 v121, v105
	s_nop 0
	v_cndmask_b32_e64 v139, -2, -3, vcc
	v_add3_u32 v139, v143, v139, s0
	v_max_i32_e32 v139, 0xffffff88, v139
	v_add_u32_e32 v139, 0x7f, v139
	v_lshlrev_b32_e32 v143, 23, v139
	v_cvt_scalef32_2xpk16_fp6_f32 v[210:215], v[18:33], v[2:17], v143
	v_lshl_add_u64 v[2:3], v[194:195], 0, v[190:191]
	v_permlane32_swap_b32_e32 v122, v106
	v_permlane32_swap_b32_e32 v123, v107
	v_permlane32_swap_b32_e32 v124, v108
	v_permlane32_swap_b32_e32 v125, v109
	v_permlane32_swap_b32_e32 v126, v110
	v_permlane32_swap_b32_e32 v127, v111
	v_permlane32_swap_b32_e32 v128, v112
	v_permlane32_swap_b32_e32 v129, v113
	v_permlane32_swap_b32_e32 v130, v114
	v_permlane32_swap_b32_e32 v131, v115
	v_lshl_add_u64 v[2:3], v[2:3], 0, v[188:189]
	v_permlane16_swap_b32_e32 v116, v124
	v_permlane16_swap_b32_e32 v117, v125
	v_permlane16_swap_b32_e32 v118, v126
	v_permlane16_swap_b32_e32 v119, v127
	v_permlane16_swap_b32_e32 v120, v128
	v_permlane16_swap_b32_e32 v121, v129
	v_permlane16_swap_b32_e32 v122, v130
	v_permlane16_swap_b32_e32 v123, v131
	v_permlane16_swap_b32_e32 v100, v108
	v_permlane16_swap_b32_e32 v101, v109
	v_permlane16_swap_b32_e32 v102, v110
	v_permlane16_swap_b32_e32 v103, v111
	v_permlane16_swap_b32_e32 v104, v112
	v_permlane16_swap_b32_e32 v105, v113
	v_permlane16_swap_b32_e32 v106, v114
	v_permlane16_swap_b32_e32 v107, v115
	v_cmp_lt_i32_e32 vcc, 1, v199
	v_mul_lo_u32 v216, v139, s1
	global_store_dwordx4 v[2:3], v[210:213], off
	global_store_dwordx4 v[2:3], v[214:217], off offset:16
	s_and_saveexec_b64 s[4:5], vcc
	s_xor_b64 s[4:5], exec, s[4:5]
	s_cbranch_execz .LBB0_588
	v_cmp_gt_i32_e32 vcc, 3, v199
	v_mov_b32_e32 v2, v207
	s_and_saveexec_b64 s[58:59], vcc
	v_mov_b32_e32 v2, v204
	s_or_b64 exec, exec, s[58:59]

.LBB0_592:
	s_or_b64 exec, exec, s[58:59]
	v_mul_f32_e32 v2, 0x3dd53b94, v2
	v_mul_f32_e32 v32, v2, v130
	v_mul_f32_e32 v33, v2, v131
	v_mul_f32_e32 v30, v2, v128
	v_mul_f32_e32 v31, v2, v129
	v_mul_f32_e32 v28, v2, v126
	v_mul_f32_e32 v29, v2, v127
	v_mul_f32_e32 v26, v2, v124
	v_mul_f32_e32 v27, v2, v125
	v_mul_f32_e32 v24, v2, v122
	v_mul_f32_e32 v25, v2, v123
	v_mul_f32_e32 v22, v2, v120
	v_mul_f32_e32 v23, v2, v121
	v_mul_f32_e32 v20, v2, v118
	v_mul_f32_e32 v21, v2, v119
	v_mul_f32_e32 v18, v2, v116
	v_mul_f32_e32 v19, v2, v117
	v_mul_f32_e32 v16, v2, v114
	v_mul_f32_e32 v17, v2, v115
	v_mul_f32_e32 v14, v2, v112
	v_mul_f32_e32 v15, v2, v113
	v_mul_f32_e32 v12, v2, v110
	v_mul_f32_e32 v13, v2, v111
	v_mul_f32_e32 v10, v2, v108
	v_mul_f32_e32 v11, v2, v109
	v_mul_f32_e32 v8, v2, v106
	v_mul_f32_e32 v9, v2, v107
	v_mul_f32_e32 v6, v2, v104
	v_mul_f32_e32 v7, v2, v105
	v_mul_f32_e32 v4, v2, v102
	v_mul_f32_e32 v5, v2, v103
	v_mul_f32_e32 v3, v2, v101
	v_mul_f32_e32 v2, v2, v100
	v_max_f32_e64 v100, |v18|, |v2|
	v_max_f32_e64 v101, |v19|, |v3|
	v_max3_f32 v100, v100, 0, v101
	v_max_f32_e64 v101, |v20|, |v4|
	v_max_f32_e64 v102, |v21|, |v5|
	v_max3_f32 v100, v100, v101, v102
	v_max_f32_e64 v101, |v22|, |v6|
	v_max_f32_e64 v102, |v23|, |v7|
	v_max3_f32 v100, v100, v101, v102
	v_max_f32_e64 v101, |v24|, |v8|
	v_max_f32_e64 v102, |v25|, |v9|
	v_max3_f32 v100, v100, v101, v102
	v_max_f32_e64 v101, |v26|, |v10|
	v_max_f32_e64 v102, |v27|, |v11|
	v_max3_f32 v100, v100, v101, v102
	v_max_f32_e64 v101, |v28|, |v12|
	v_max_f32_e64 v102, |v29|, |v13|
	v_max3_f32 v100, v100, v101, v102
	v_max_f32_e64 v101, |v30|, |v14|
	v_max_f32_e64 v102, |v31|, |v15|
	v_max3_f32 v100, v100, v101, v102
	v_max_f32_e64 v101, |v32|, |v16|
	v_max_f32_e64 v102, |v33|, |v17|
	v_max3_f32 v100, v100, v101, v102
	v_bfe_u32 v101, v100, 23, 8
	v_and_b32_e32 v100, 0x7fffff, v100
	v_cmp_gt_u32_e32 vcc, s11, v100
	v_add_u32_e32 v103, 0x80, v141
	v_mov_b32_e32 v113, v35
	v_cndmask_b32_e64 v100, -2, -3, vcc
	v_add3_u32 v100, v101, v100, s0
	v_max_i32_e32 v100, 0xffffff88, v100
	v_add_u32_e32 v100, 0x7f, v100
	v_lshlrev_b32_e32 v102, 23, v100
	v_mul_lo_u32 v112, v100, s1
	v_mov_b64_e32 v[100:101], s[26:27]
	v_mad_i64_i32 v[100:101], s[4:5], v103, s10, v[100:101]
	v_lshl_add_u64 v[100:101], v[192:193], 1, v[100:101]
	v_lshl_add_u64 v[114:115], v[100:101], 0, v[34:35]
	v_cvt_scalef32_2xpk16_fp6_f32 v[106:111], v[18:33], v[2:17], v102
	v_sub_u32_e32 v104, 0x7f000000, v102
	v_lshl_add_u64 v[114:115], v[114:115], 0, v[188:189]
	global_store_dwordx4 v[114:115], v[106:109], off
	global_store_dwordx4 v[114:115], v[110:113], off offset:16
	v_mov_b32_e32 v139, v102
	v_mul_f32_e32 v106, v18, v104
	v_mul_f32_e32 v107, v19, v104
	s_nop 0
	v_cmp_lt_f32_e64 vcc, |v106|, 4.0
	v_and_b32_e32 v34, 0x7fffffff, v106
	s_nop 0
	v_cndmask_b32_e32 v103, 0.5, v185, vcc
	v_cmp_nlt_f32_e64 vcc, |v106|, 2.0
	s_nop 1
	v_cndmask_b32_e32 v103, v197, v103, vcc
	v_cmp_lt_f32_e64 vcc, |v107|, 4.0
	v_and_b32_e32 v105, 0x7fffffff, v107
	v_sub_u32_e32 v108, 0x7f000000, v103
	v_mul_f32_e64 v34, |v106|, v108
	v_cndmask_b32_e32 v108, 0.5, v185, vcc
	v_cmp_nlt_f32_e64 vcc, |v107|, 2.0
	v_rndne_f32_e32 v34, v34
	v_mul_f32_e32 v34, v103, v34
	v_cndmask_b32_e32 v108, v197, v108, vcc
	v_min_f32_e32 v34, 0x40f00000, v34
	v_bfi_b32 v106, s22, v34, v106
	v_sub_u32_e32 v105, 0x7f000000, v108
	v_mul_f32_e64 v103, |v107|, v105
	v_rndne_f32_e32 v103, v103
	v_mul_f32_e32 v103, v108, v103
	v_mul_f32_e32 v108, v2, v104
	v_mul_f32_e32 v109, v3, v104
	v_min_f32_e32 v103, 0x40f00000, v103
	v_cmp_lt_f32_e64 vcc, |v108|, 4.0
	v_bfi_b32 v107, s22, v103, v107
	v_and_b32_e32 v103, 0x7fffffff, v108
	v_cndmask_b32_e32 v105, 0.5, v185, vcc
	v_cmp_nlt_f32_e64 vcc, |v108|, 2.0
	v_mul_f32_e32 v106, v106, v102
	v_mul_f32_e32 v107, v107, v102
	s_nop 0
	v_cndmask_b32_e32 v105, v197, v105, vcc
	v_fma_f32 v18, v18, 2.0, -v106
	v_fma_f32 v19, v19, 2.0, -v107
	v_cmp_lt_f32_e64 vcc, |v109|, 4.0
	v_and_b32_e32 v103, 0x7fffffff, v109
	v_sub_u32_e32 v106, 0x7f000000, v105
	v_mul_f32_e64 v34, |v108|, v106
	v_cndmask_b32_e32 v106, 0.5, v185, vcc
	v_cmp_nlt_f32_e64 vcc, |v109|, 2.0
	v_rndne_f32_e32 v34, v34
	v_mul_f32_e32 v34, v105, v34
	v_cndmask_b32_e32 v106, v197, v106, vcc
	v_min_f32_e32 v34, 0x40f00000, v34
	v_sub_u32_e32 v105, 0x7f000000, v106
	v_mul_f32_e64 v103, |v109|, v105
	v_rndne_f32_e32 v103, v103
	v_mul_f32_e32 v110, v20, v104
	v_mul_f32_e32 v111, v21, v104
	v_mul_f32_e32 v103, v106, v103
	v_cmp_lt_f32_e64 vcc, |v110|, 4.0
	v_min_f32_e32 v103, 0x40f00000, v103
	v_bfi_b32 v107, s22, v103, v109
	v_cndmask_b32_e32 v105, 0.5, v185, vcc
	v_cmp_nlt_f32_e64 vcc, |v110|, 2.0
	v_and_b32_e32 v103, 0x7fffffff, v110
	v_bfi_b32 v106, s22, v34, v108
	v_cndmask_b32_e32 v105, v197, v105, vcc
	v_mul_f32_e32 v106, v106, v102
	v_mul_f32_e32 v107, v107, v102
	v_fma_f32 v2, v2, 2.0, -v106
	v_fma_f32 v3, v3, 2.0, -v107
	v_cmp_lt_f32_e64 vcc, |v111|, 4.0
	v_and_b32_e32 v103, 0x7fffffff, v111
	v_sub_u32_e32 v106, 0x7f000000, v105
	v_mul_f32_e64 v34, |v110|, v106
	v_cndmask_b32_e32 v106, 0.5, v185, vcc
	v_cmp_nlt_f32_e64 vcc, |v111|, 2.0
	v_rndne_f32_e32 v34, v34
	v_mul_f32_e32 v34, v105, v34
	v_cndmask_b32_e32 v106, v197, v106, vcc
	v_min_f32_e32 v34, 0x40f00000, v34
	v_sub_u32_e32 v105, 0x7f000000, v106
	v_mul_f32_e64 v103, |v111|, v105
	v_rndne_f32_e32 v103, v103
	v_mul_f32_e32 v108, v4, v104
	v_mul_f32_e32 v109, v5, v104
	v_mul_f32_e32 v103, v106, v103
	v_cmp_lt_f32_e64 vcc, |v108|, 4.0
	v_min_f32_e32 v103, 0x40f00000, v103
	v_bfi_b32 v107, s22, v103, v111
	v_cndmask_b32_e32 v105, 0.5, v185, vcc
	v_cmp_nlt_f32_e64 vcc, |v108|, 2.0
	v_and_b32_e32 v103, 0x7fffffff, v108
	v_bfi_b32 v106, s22, v34, v110
	v_cndmask_b32_e32 v105, v197, v105, vcc
	v_mul_f32_e32 v106, v106, v102
	v_mul_f32_e32 v107, v107, v102
	v_fma_f32 v20, v20, 2.0, -v106
	v_fma_f32 v21, v21, 2.0, -v107
	v_cmp_lt_f32_e64 vcc, |v109|, 4.0
	v_and_b32_e32 v103, 0x7fffffff, v109
	v_sub_u32_e32 v106, 0x7f000000, v105
	v_mul_f32_e64 v34, |v108|, v106
	v_cndmask_b32_e32 v106, 0.5, v185, vcc
	v_cmp_nlt_f32_e64 vcc, |v109|, 2.0
	v_rndne_f32_e32 v34, v34
	v_mul_f32_e32 v34, v105, v34
	v_cndmask_b32_e32 v106, v197, v106, vcc
	v_min_f32_e32 v34, 0x40f00000, v34
	v_sub_u32_e32 v105, 0x7f000000, v106
	v_mul_f32_e64 v103, |v109|, v105
	v_rndne_f32_e32 v103, v103
	v_mul_f32_e32 v110, v22, v104
	v_mul_f32_e32 v111, v23, v104
	v_mul_f32_e32 v103, v106, v103
	v_cmp_lt_f32_e64 vcc, |v110|, 4.0
	v_min_f32_e32 v103, 0x40f00000, v103
	v_bfi_b32 v107, s22, v103, v109
	v_cndmask_b32_e32 v105, 0.5, v185, vcc
	v_cmp_nlt_f32_e64 vcc, |v110|, 2.0
	v_and_b32_e32 v103, 0x7fffffff, v110
	v_bfi_b32 v106, s22, v34, v108
	v_cndmask_b32_e32 v105, v197, v105, vcc
	v_mul_f32_e32 v106, v106, v102
	v_mul_f32_e32 v107, v107, v102
	v_fma_f32 v4, v4, 2.0, -v106
	v_fma_f32 v5, v5, 2.0, -v107
	v_cmp_lt_f32_e64 vcc, |v111|, 4.0
	v_and_b32_e32 v103, 0x7fffffff, v111
	v_sub_u32_e32 v106, 0x7f000000, v105
	v_mul_f32_e64 v34, |v110|, v106
	v_cndmask_b32_e32 v106, 0.5, v185, vcc
	v_cmp_nlt_f32_e64 vcc, |v111|, 2.0
	v_rndne_f32_e32 v34, v34
	v_mul_f32_e32 v34, v105, v34
	v_cndmask_b32_e32 v106, v197, v106, vcc
	v_min_f32_e32 v34, 0x40f00000, v34
	v_sub_u32_e32 v105, 0x7f000000, v106
	v_mul_f32_e64 v103, |v111|, v105
	v_rndne_f32_e32 v103, v103
	v_mul_f32_e32 v108, v6, v104
	v_mul_f32_e32 v109, v7, v104
	v_mul_f32_e32 v103, v106, v103
	v_cmp_lt_f32_e64 vcc, |v108|, 4.0
	v_min_f32_e32 v103, 0x40f00000, v103
	v_bfi_b32 v107, s22, v103, v111
	v_cndmask_b32_e32 v105, 0.5, v185, vcc
	v_cmp_nlt_f32_e64 vcc, |v108|, 2.0
	v_and_b32_e32 v103, 0x7fffffff, v108
	v_bfi_b32 v106, s22, v34, v110
	v_cndmask_b32_e32 v105, v197, v105, vcc
	v_mul_f32_e32 v106, v106, v102
	v_mul_f32_e32 v107, v107, v102
	v_fma_f32 v22, v22, 2.0, -v106
	v_fma_f32 v23, v23, 2.0, -v107
	v_cmp_lt_f32_e64 vcc, |v109|, 4.0
	v_and_b32_e32 v103, 0x7fffffff, v109
	v_sub_u32_e32 v106, 0x7f000000, v105
	v_mul_f32_e64 v34, |v108|, v106
	v_cndmask_b32_e32 v106, 0.5, v185, vcc
	v_cmp_nlt_f32_e64 vcc, |v109|, 2.0
	v_rndne_f32_e32 v34, v34
	v_mul_f32_e32 v34, v105, v34
	v_cndmask_b32_e32 v106, v197, v106, vcc
	v_min_f32_e32 v34, 0x40f00000, v34
	v_sub_u32_e32 v105, 0x7f000000, v106
	v_mul_f32_e64 v103, |v109|, v105
	v_rndne_f32_e32 v103, v103
	v_mul_f32_e32 v110, v24, v104
	v_mul_f32_e32 v111, v25, v104
	v_mul_f32_e32 v103, v106, v103
	v_cmp_lt_f32_e64 vcc, |v110|, 4.0
	v_min_f32_e32 v103, 0x40f00000, v103
	v_bfi_b32 v107, s22, v103, v109
	v_cndmask_b32_e32 v105, 0.5, v185, vcc
	v_cmp_nlt_f32_e64 vcc, |v110|, 2.0
	v_and_b32_e32 v103, 0x7fffffff, v110
	v_bfi_b32 v106, s22, v34, v108
	v_cndmask_b32_e32 v105, v197, v105, vcc
	v_mul_f32_e32 v106, v106, v102
	v_mul_f32_e32 v107, v107, v102
	v_fma_f32 v6, v6, 2.0, -v106
	v_fma_f32 v7, v7, 2.0, -v107
	v_cmp_lt_f32_e64 vcc, |v111|, 4.0
	v_and_b32_e32 v103, 0x7fffffff, v111
	v_sub_u32_e32 v106, 0x7f000000, v105
	v_mul_f32_e64 v34, |v110|, v106
	v_cndmask_b32_e32 v106, 0.5, v185, vcc
	v_cmp_nlt_f32_e64 vcc, |v111|, 2.0
	v_rndne_f32_e32 v34, v34
	v_mul_f32_e32 v34, v105, v34
	v_cndmask_b32_e32 v106, v197, v106, vcc
	v_min_f32_e32 v34, 0x40f00000, v34
	v_sub_u32_e32 v105, 0x7f000000, v106
	v_mul_f32_e64 v103, |v111|, v105
	v_rndne_f32_e32 v103, v103
	v_mul_f32_e32 v108, v8, v104
	v_mul_f32_e32 v109, v9, v104
	v_mul_f32_e32 v103, v106, v103
	v_cmp_lt_f32_e64 vcc, |v108|, 4.0
	v_min_f32_e32 v103, 0x40f00000, v103
	v_bfi_b32 v107, s22, v103, v111
	v_cndmask_b32_e32 v105, 0.5, v185, vcc
	v_cmp_nlt_f32_e64 vcc, |v108|, 2.0
	v_and_b32_e32 v103, 0x7fffffff, v108
	v_bfi_b32 v106, s22, v34, v110
	v_cndmask_b32_e32 v105, v197, v105, vcc
	v_mul_f32_e32 v106, v106, v102
	v_mul_f32_e32 v107, v107, v102
	v_fma_f32 v24, v24, 2.0, -v106
	v_fma_f32 v25, v25, 2.0, -v107
	v_cmp_lt_f32_e64 vcc, |v109|, 4.0
	v_and_b32_e32 v103, 0x7fffffff, v109
	v_sub_u32_e32 v106, 0x7f000000, v105
	v_mul_f32_e64 v34, |v108|, v106
	v_cndmask_b32_e32 v106, 0.5, v185, vcc
	v_cmp_nlt_f32_e64 vcc, |v109|, 2.0
	v_rndne_f32_e32 v34, v34
	v_mul_f32_e32 v34, v105, v34
	v_cndmask_b32_e32 v106, v197, v106, vcc
	v_min_f32_e32 v34, 0x40f00000, v34
	v_sub_u32_e32 v105, 0x7f000000, v106
	v_mul_f32_e64 v103, |v109|, v105
	v_rndne_f32_e32 v103, v103
	v_mul_f32_e32 v110, v26, v104
	v_mul_f32_e32 v111, v27, v104
	v_mul_f32_e32 v103, v106, v103
	v_cmp_lt_f32_e64 vcc, |v110|, 4.0
	v_min_f32_e32 v103, 0x40f00000, v103
	v_bfi_b32 v107, s22, v103, v109
	v_cndmask_b32_e32 v105, 0.5, v185, vcc
	v_cmp_nlt_f32_e64 vcc, |v110|, 2.0
	v_and_b32_e32 v103, 0x7fffffff, v110
	v_bfi_b32 v106, s22, v34, v108
	v_cndmask_b32_e32 v105, v197, v105, vcc
	v_mul_f32_e32 v106, v106, v102
	v_mul_f32_e32 v107, v107, v102
	v_fma_f32 v8, v8, 2.0, -v106
	v_fma_f32 v9, v9, 2.0, -v107
	v_cmp_lt_f32_e64 vcc, |v111|, 4.0
	v_and_b32_e32 v103, 0x7fffffff, v111
	v_sub_u32_e32 v106, 0x7f000000, v105
	v_mul_f32_e64 v34, |v110|, v106
	v_cndmask_b32_e32 v106, 0.5, v185, vcc
	v_cmp_nlt_f32_e64 vcc, |v111|, 2.0
	v_rndne_f32_e32 v34, v34
	v_mul_f32_e32 v34, v105, v34
	v_cndmask_b32_e32 v106, v197, v106, vcc
	v_min_f32_e32 v34, 0x40f00000, v34
	v_sub_u32_e32 v105, 0x7f000000, v106
	v_mul_f32_e64 v103, |v111|, v105
	v_rndne_f32_e32 v103, v103
	v_mul_f32_e32 v108, v10, v104
	v_mul_f32_e32 v109, v11, v104
	v_mul_f32_e32 v103, v106, v103
	v_cmp_lt_f32_e64 vcc, |v108|, 4.0
	v_min_f32_e32 v103, 0x40f00000, v103
	v_bfi_b32 v107, s22, v103, v111
	v_cndmask_b32_e32 v105, 0.5, v185, vcc
	v_cmp_nlt_f32_e64 vcc, |v108|, 2.0
	v_and_b32_e32 v103, 0x7fffffff, v108
	v_bfi_b32 v106, s22, v34, v110
	v_cndmask_b32_e32 v105, v197, v105, vcc
	v_mul_f32_e32 v106, v106, v102
	v_mul_f32_e32 v107, v107, v102
	v_fma_f32 v26, v26, 2.0, -v106
	v_fma_f32 v27, v27, 2.0, -v107
	v_cmp_lt_f32_e64 vcc, |v109|, 4.0
	v_and_b32_e32 v103, 0x7fffffff, v109
	v_sub_u32_e32 v106, 0x7f000000, v105
	v_mul_f32_e64 v34, |v108|, v106
	v_cndmask_b32_e32 v106, 0.5, v185, vcc
	v_cmp_nlt_f32_e64 vcc, |v109|, 2.0
	v_rndne_f32_e32 v34, v34
	v_mul_f32_e32 v34, v105, v34
	v_cndmask_b32_e32 v106, v197, v106, vcc
	v_min_f32_e32 v34, 0x40f00000, v34
	v_sub_u32_e32 v105, 0x7f000000, v106
	v_mul_f32_e64 v103, |v109|, v105
	v_rndne_f32_e32 v103, v103
	v_mul_f32_e32 v110, v28, v104
	v_mul_f32_e32 v111, v29, v104
	v_mul_f32_e32 v103, v106, v103
	v_cmp_lt_f32_e64 vcc, |v110|, 4.0
	v_min_f32_e32 v103, 0x40f00000, v103
	v_bfi_b32 v107, s22, v103, v109
	v_cndmask_b32_e32 v105, 0.5, v185, vcc
	v_cmp_nlt_f32_e64 vcc, |v110|, 2.0
	v_and_b32_e32 v103, 0x7fffffff, v110
	v_bfi_b32 v106, s22, v34, v108
	v_cndmask_b32_e32 v105, v197, v105, vcc
	v_mul_f32_e32 v106, v106, v102
	v_mul_f32_e32 v107, v107, v102
	v_fma_f32 v10, v10, 2.0, -v106
	v_fma_f32 v11, v11, 2.0, -v107
	v_cmp_lt_f32_e64 vcc, |v111|, 4.0
	v_and_b32_e32 v103, 0x7fffffff, v111
	v_sub_u32_e32 v106, 0x7f000000, v105
	v_mul_f32_e64 v34, |v110|, v106
	v_cndmask_b32_e32 v106, 0.5, v185, vcc
	v_cmp_nlt_f32_e64 vcc, |v111|, 2.0
	v_rndne_f32_e32 v34, v34
	v_mul_f32_e32 v34, v105, v34
	v_cndmask_b32_e32 v106, v197, v106, vcc
	v_min_f32_e32 v34, 0x40f00000, v34
	v_sub_u32_e32 v105, 0x7f000000, v106
	v_mul_f32_e64 v103, |v111|, v105
	v_rndne_f32_e32 v103, v103
	v_mul_f32_e32 v108, v12, v104
	v_mul_f32_e32 v109, v13, v104
	v_mul_f32_e32 v103, v106, v103
	v_cmp_lt_f32_e64 vcc, |v108|, 4.0
	v_min_f32_e32 v103, 0x40f00000, v103
	v_bfi_b32 v107, s22, v103, v111
	v_cndmask_b32_e32 v105, 0.5, v185, vcc
	v_cmp_nlt_f32_e64 vcc, |v108|, 2.0
	v_and_b32_e32 v103, 0x7fffffff, v108
	v_bfi_b32 v106, s22, v34, v110
	v_cndmask_b32_e32 v105, v197, v105, vcc
	v_mul_f32_e32 v106, v106, v102
	v_mul_f32_e32 v107, v107, v102
	v_fma_f32 v28, v28, 2.0, -v106
	v_fma_f32 v29, v29, 2.0, -v107
	v_cmp_lt_f32_e64 vcc, |v109|, 4.0
	v_and_b32_e32 v103, 0x7fffffff, v109
	v_sub_u32_e32 v106, 0x7f000000, v105
	v_mul_f32_e64 v34, |v108|, v106
	v_cndmask_b32_e32 v106, 0.5, v185, vcc
	v_cmp_nlt_f32_e64 vcc, |v109|, 2.0
	v_rndne_f32_e32 v34, v34
	v_mul_f32_e32 v34, v105, v34
	v_cndmask_b32_e32 v106, v197, v106, vcc
	v_min_f32_e32 v34, 0x40f00000, v34
	v_sub_u32_e32 v105, 0x7f000000, v106
	v_mul_f32_e64 v103, |v109|, v105
	v_rndne_f32_e32 v103, v103
	v_mul_f32_e32 v110, v30, v104
	v_mul_f32_e32 v111, v31, v104
	v_mul_f32_e32 v103, v106, v103
	v_cmp_lt_f32_e64 vcc, |v110|, 4.0
	v_min_f32_e32 v103, 0x40f00000, v103
	v_bfi_b32 v107, s22, v103, v109
	v_cndmask_b32_e32 v105, 0.5, v185, vcc
	v_cmp_nlt_f32_e64 vcc, |v110|, 2.0
	v_and_b32_e32 v103, 0x7fffffff, v110
	v_bfi_b32 v106, s22, v34, v108
	v_cndmask_b32_e32 v105, v197, v105, vcc
	v_mul_f32_e32 v106, v106, v102
	v_mul_f32_e32 v107, v107, v102
	v_fma_f32 v12, v12, 2.0, -v106
	v_fma_f32 v13, v13, 2.0, -v107
	v_cmp_lt_f32_e64 vcc, |v111|, 4.0
	v_and_b32_e32 v103, 0x7fffffff, v111
	v_sub_u32_e32 v106, 0x7f000000, v105
	v_mul_f32_e64 v34, |v110|, v106
	v_cndmask_b32_e32 v106, 0.5, v185, vcc
	v_cmp_nlt_f32_e64 vcc, |v111|, 2.0
	v_rndne_f32_e32 v34, v34
	v_mul_f32_e32 v34, v105, v34
	v_cndmask_b32_e32 v106, v197, v106, vcc
	v_min_f32_e32 v34, 0x40f00000, v34
	v_sub_u32_e32 v105, 0x7f000000, v106
	v_mul_f32_e64 v103, |v111|, v105
	v_rndne_f32_e32 v103, v103
	v_mul_f32_e32 v108, v14, v104
	v_mul_f32_e32 v109, v15, v104
	v_mul_f32_e32 v103, v106, v103
	v_cmp_lt_f32_e64 vcc, |v108|, 4.0
	v_min_f32_e32 v103, 0x40f00000, v103
	v_bfi_b32 v107, s22, v103, v111
	v_cndmask_b32_e32 v105, 0.5, v185, vcc
	v_cmp_nlt_f32_e64 vcc, |v108|, 2.0
	v_and_b32_e32 v103, 0x7fffffff, v108
	v_bfi_b32 v106, s22, v34, v110
	v_cndmask_b32_e32 v105, v197, v105, vcc
	v_mul_f32_e32 v106, v106, v102
	v_mul_f32_e32 v107, v107, v102
	v_fma_f32 v30, v30, 2.0, -v106
	v_fma_f32 v31, v31, 2.0, -v107
	v_cmp_lt_f32_e64 vcc, |v109|, 4.0
	v_and_b32_e32 v103, 0x7fffffff, v109
	v_sub_u32_e32 v106, 0x7f000000, v105
	v_mul_f32_e64 v34, |v108|, v106
	v_cndmask_b32_e32 v106, 0.5, v185, vcc
	v_cmp_nlt_f32_e64 vcc, |v109|, 2.0
	v_rndne_f32_e32 v34, v34
	v_mul_f32_e32 v34, v105, v34
	v_cndmask_b32_e32 v106, v197, v106, vcc
	v_min_f32_e32 v34, 0x40f00000, v34
	v_sub_u32_e32 v105, 0x7f000000, v106
	v_mul_f32_e64 v103, |v109|, v105
	v_rndne_f32_e32 v103, v103
	v_mul_f32_e32 v103, v106, v103
	v_bfi_b32 v106, s22, v34, v108
	v_mul_f32_e32 v34, v32, v104
	v_cmp_lt_f32_e64 vcc, |v34|, 4.0
	v_min_f32_e32 v103, 0x40f00000, v103
	v_bfi_b32 v107, s22, v103, v109
	v_cndmask_b32_e32 v105, 0.5, v185, vcc
	v_cmp_nlt_f32_e64 vcc, |v34|, 2.0
	v_and_b32_e32 v103, 0x7fffffff, v34
	v_mul_f32_e32 v106, v106, v102
	v_mul_f32_e32 v107, v107, v102
	v_cndmask_b32_e32 v105, v197, v105, vcc
	v_fma_f32 v14, v14, 2.0, -v106
	v_fma_f32 v15, v15, 2.0, -v107
	v_sub_u32_e32 v106, 0x7f000000, v105
	v_mul_f32_e64 v103, |v34|, v106
	v_rndne_f32_e32 v103, v103
	v_mul_f32_e32 v103, v105, v103
	v_mul_f32_e32 v105, v16, v104
	v_cmp_lt_f32_e64 vcc, |v105|, 4.0
	v_and_b32_e32 v107, 0x7fffffff, v105
	v_min_f32_e32 v103, 0x40f00000, v103
	v_cndmask_b32_e32 v106, 0.5, v185, vcc
	v_cmp_nlt_f32_e64 vcc, |v105|, 2.0
	v_bfi_b32 v34, s22, v103, v34
	v_add_f32_e32 v32, v32, v32
	v_cndmask_b32_e32 v108, v197, v106, vcc
	v_mul_f32_e32 v106, v34, v102
	v_add_f32_e32 v16, v16, v16
	v_sub_u32_e32 v103, 0x7f000000, v108
	v_mul_f32_e64 v34, |v105|, v103
	v_mul_f32_e32 v103, v33, v104
	v_rndne_f32_e32 v34, v34
	v_cmp_lt_f32_e64 vcc, |v103|, 4.0
	v_mul_f32_e32 v34, v108, v34
	v_and_b32_e32 v107, 0x7fffffff, v103
	v_cndmask_b32_e32 v108, 0.5, v185, vcc
	v_cmp_nlt_f32_e64 vcc, |v103|, 2.0
	v_min_f32_e32 v34, 0x40f00000, v34
	v_bfi_b32 v34, s22, v34, v105
	v_cndmask_b32_e32 v109, v197, v108, vcc
	v_mul_f32_e32 v108, v34, v102
	v_sub_u32_e32 v105, 0x7f000000, v109
	v_mul_f32_e64 v34, |v103|, v105
	v_rndne_f32_e32 v34, v34
	v_mul_f32_e32 v34, v109, v34
	v_min_f32_e32 v34, 0x40f00000, v34
	v_bfi_b32 v111, s22, v34, v103
	v_mul_f32_e32 v34, v17, v104
	v_cmp_lt_f32_e64 vcc, |v34|, 4.0
	v_mov_b32_e32 v110, v33
	v_and_b32_e32 v104, 0x7fffffff, v34
	v_cndmask_b32_e32 v33, 0.5, v185, vcc
	v_cmp_nlt_f32_e64 vcc, |v34|, 2.0
	v_mul_f32_e32 v102, v110, v138
	v_mul_f32_e32 v103, v111, v139
	s_nop 0
	v_cndmask_b32_e32 v105, v197, v33, vcc
	v_mov_b32_e32 v33, v102
	v_mov_b32_e32 v107, v103
	v_add_f32_e64 v32, v32, -v106
	v_add_f32_e64 v33, v33, -v107
	v_sub_u32_e32 v103, 0x7f000000, v105
	v_mul_f32_e64 v102, |v34|, v103
	v_rndne_f32_e32 v102, v102
	v_mul_f32_e32 v102, v105, v102
	v_min_f32_e32 v102, 0x40f00000, v102
	v_bfi_b32 v103, s22, v102, v34
	v_mov_b32_e32 v102, v17
	v_mul_f32_e32 v102, v102, v138
	v_mul_f32_e32 v103, v103, v139
	v_max_f32_e64 v34, |v18|, |v2|
	v_mov_b32_e32 v17, v102
	v_max_f32_e64 v102, |v19|, |v3|
	v_mov_b32_e32 v109, v103
	v_max3_f32 v34, v34, 0, v102
	v_max_f32_e64 v102, |v20|, |v4|
	v_max_f32_e64 v103, |v21|, |v5|
	v_max3_f32 v34, v34, v102, v103
	v_max_f32_e64 v102, |v22|, |v6|
	v_max_f32_e64 v103, |v23|, |v7|
	v_max3_f32 v34, v34, v102, v103
	v_max_f32_e64 v102, |v24|, |v8|
	v_max_f32_e64 v103, |v25|, |v9|
	v_max3_f32 v34, v34, v102, v103
	v_max_f32_e64 v102, |v26|, |v10|
	v_max_f32_e64 v103, |v27|, |v11|
	v_max3_f32 v34, v34, v102, v103
	v_max_f32_e64 v102, |v28|, |v12|
	v_max_f32_e64 v103, |v29|, |v13|
	v_add_f32_e64 v16, v16, -v108
	v_add_f32_e64 v17, v17, -v109
	v_max3_f32 v34, v34, v102, v103
	v_max_f32_e64 v102, |v30|, |v14|
	v_max_f32_e64 v103, |v31|, |v15|
	v_max3_f32 v34, v34, v102, v103
	v_max_f32_e64 v102, |v32|, |v16|
	v_max_f32_e64 v103, |v33|, |v17|
	v_max3_f32 v34, v34, v102, v103
	v_bfe_u32 v102, v34, 23, 8
	v_and_b32_e32 v34, 0x7fffff, v34
	v_cmp_gt_u32_e32 vcc, s11, v34
	s_nop 1
	v_cndmask_b32_e64 v34, -2, -3, vcc
	v_add3_u32 v34, v102, v34, s0
	v_max_i32_e32 v34, 0xffffff88, v34
	v_add_u32_e32 v34, 0x7f, v34
	v_lshlrev_b32_e32 v108, 23, v34
	v_cvt_scalef32_2xpk16_fp6_f32 v[102:107], v[18:33], v[2:17], v108
	v_lshl_add_u64 v[2:3], v[100:101], 0, v[190:191]
	v_mul_lo_u32 v34, v34, s1
	v_lshl_add_u64 v[2:3], v[2:3], 0, v[188:189]
	v_mov_b32_e32 v32, v106
	v_mov_b32_e32 v33, v107
	global_store_dwordx4 v[2:3], v[102:105], off
	global_store_dwordx4 v[2:3], v[32:35], off offset:16

.LBB0_596:
	v_add_u32_e32 v2, 0xffffff80, v104
	v_lshrrev_b32_e32 v34, 1, v2
	v_lshlrev_b64 v[6:7], 2, v[34:35]
	v_lshl_add_u64 v[2:3], s[16:17], 0, v[6:7]
	v_lshl_add_u64 v[8:9], v[2:3], 0, v[186:187]
	global_load_dwordx4 v[10:13], v[8:9], off
	v_lshl_add_u64 v[8:9], s[14:15], 0, v[6:7]
	v_lshl_add_u64 v[6:7], v[8:9], 0, v[186:187]
	global_load_dwordx4 v[14:17], v[6:7], off
	v_mul_f32_e32 v24, v88, v184
	v_mul_f32_e32 v25, v89, v184
	v_mul_f32_e32 v20, v84, v184
	v_mul_f32_e32 v21, v85, v184
	v_mov_b32_e32 v32, v35
	v_mov_b32_e32 v33, v35
	v_mul_f32_e32 v22, v90, v184
	v_mul_f32_e32 v23, v91, v184
	v_mul_f32_e32 v18, v86, v184
	v_mul_f32_e32 v19, v87, v184
	v_sub_u32_e32 v4, v4, v104
	v_mov_b64_e32 v[6:7], s[26:27]
	v_ashrrev_i32_e32 v5, 31, v4
	v_mad_i64_i32 v[26:27], s[4:5], v140, s10, v[6:7]
	v_lshlrev_b64 v[4:5], 1, v[4:5]
	v_lshl_add_u64 v[26:27], v[26:27], 0, v[4:5]
	s_waitcnt vmcnt(1)
	v_mul_f32_e32 v30, v24, v10
	v_mul_f32_e32 v31, v25, v11
	v_mul_f32_e32 v10, v20, v10
	v_mul_f32_e32 v11, v21, v11
	v_mul_f32_e32 v28, v22, v12
	v_mul_f32_e32 v29, v23, v13
	s_waitcnt vmcnt(0)
	v_fma_f32 v20, v20, v14, -v30
	v_fma_f32 v21, v21, v15, -v31
	v_fmac_f32_e32 v10, v24, v14
	v_fmac_f32_e32 v11, v25, v15
	v_cvt_pk_fp8_f32 v32, v20, v21
	v_cvt_pk_fp8_f32 v33, v10, v11
	v_mul_f32_e32 v12, v18, v12
	v_mul_f32_e32 v13, v19, v13
	v_fma_f32 v10, v18, v16, -v28
	v_fma_f32 v11, v19, v17, -v29
	v_fmac_f32_e32 v12, v22, v16
	v_fmac_f32_e32 v13, v23, v17
	v_cvt_pk_fp8_f32 v32, v10, v11 op_sel:[0,0,1]
	v_cvt_pk_fp8_f32 v33, v12, v13 op_sel:[0,0,1]
	v_lshl_add_u64 v[10:11], v[26:27], 0, v[34:35]
	v_lshl_add_u64 v[12:13], v[2:3], 0, v[182:183]
	global_store_dword v[10:11], v32, off offset:256
	global_store_dword v[10:11], v33, off offset:288
	global_load_dwordx4 v[10:13], v[12:13], off
	v_lshl_add_u64 v[14:15], v[8:9], 0, v[182:183]
	global_load_dwordx4 v[14:17], v[14:15], off
	v_mul_f32_e32 v24, v96, v180
	v_mul_f32_e32 v25, v97, v180
	v_mul_f32_e32 v20, v92, v180
	v_mul_f32_e32 v21, v93, v180
	v_mov_b32_e32 v32, v35
	v_mov_b32_e32 v33, v35
	v_mul_f32_e32 v22, v98, v180
	v_mul_f32_e32 v23, v99, v180
	v_mul_f32_e32 v18, v94, v180
	v_mul_f32_e32 v19, v95, v180
	v_mad_i64_i32 v[26:27], s[4:5], v142, s10, v[6:7]
	v_lshl_add_u64 v[26:27], v[26:27], 0, v[4:5]
	s_waitcnt vmcnt(1)
	v_mul_f32_e32 v30, v24, v10
	v_mul_f32_e32 v31, v25, v11
	v_mul_f32_e32 v10, v20, v10
	v_mul_f32_e32 v11, v21, v11
	s_waitcnt vmcnt(0)
	v_fma_f32 v20, v20, v14, -v30
	v_fma_f32 v21, v21, v15, -v31
	v_fmac_f32_e32 v10, v24, v14
	v_fmac_f32_e32 v11, v25, v15
	v_cvt_pk_fp8_f32 v32, v20, v21
	v_cvt_pk_fp8_f32 v33, v10, v11
	v_mul_f32_e32 v28, v22, v12
	v_mul_f32_e32 v29, v23, v13
	v_mul_f32_e32 v12, v18, v12
	v_mul_f32_e32 v13, v19, v13
	v_fma_f32 v10, v18, v16, -v28
	v_fma_f32 v11, v19, v17, -v29
	v_fmac_f32_e32 v12, v22, v16
	v_fmac_f32_e32 v13, v23, v17
	v_cvt_pk_fp8_f32 v32, v10, v11 op_sel:[0,0,1]
	v_cvt_pk_fp8_f32 v33, v12, v13 op_sel:[0,0,1]
	v_lshl_add_u64 v[10:11], v[26:27], 0, v[34:35]
	v_lshl_add_u64 v[12:13], v[2:3], 0, v[178:179]
	global_store_dword v[10:11], v32, off offset:256
	global_store_dword v[10:11], v33, off offset:288
	global_load_dwordx4 v[10:13], v[12:13], off
	v_lshl_add_u64 v[14:15], v[8:9], 0, v[178:179]
	global_load_dwordx4 v[14:17], v[14:15], off
	v_mul_f32_e32 v24, v72, v176
	v_mul_f32_e32 v25, v73, v176
	v_mul_f32_e32 v20, v68, v176
	v_mul_f32_e32 v21, v69, v176
	v_mov_b32_e32 v32, v35
	v_mov_b32_e32 v33, v35
	v_mul_f32_e32 v22, v74, v176
	v_mul_f32_e32 v23, v75, v176
	v_mul_f32_e32 v18, v70, v176
	v_mul_f32_e32 v19, v71, v176
	v_mad_i64_i32 v[26:27], s[4:5], v144, s10, v[6:7]
	v_lshl_add_u64 v[26:27], v[26:27], 0, v[4:5]
	s_waitcnt vmcnt(1)
	v_mul_f32_e32 v30, v24, v10
	v_mul_f32_e32 v31, v25, v11
	v_mul_f32_e32 v10, v20, v10
	v_mul_f32_e32 v11, v21, v11
	s_waitcnt vmcnt(0)
	v_fma_f32 v20, v20, v14, -v30
	v_fma_f32 v21, v21, v15, -v31
	v_fmac_f32_e32 v10, v24, v14
	v_fmac_f32_e32 v11, v25, v15
	v_cvt_pk_fp8_f32 v32, v20, v21
	v_cvt_pk_fp8_f32 v33, v10, v11
	v_mul_f32_e32 v28, v22, v12
	v_mul_f32_e32 v29, v23, v13
	v_mul_f32_e32 v12, v18, v12
	v_mul_f32_e32 v13, v19, v13
	v_fma_f32 v10, v18, v16, -v28
	v_fma_f32 v11, v19, v17, -v29
	v_fmac_f32_e32 v12, v22, v16
	v_fmac_f32_e32 v13, v23, v17
	v_cvt_pk_fp8_f32 v32, v10, v11 op_sel:[0,0,1]
	v_cvt_pk_fp8_f32 v33, v12, v13 op_sel:[0,0,1]
	v_lshl_add_u64 v[10:11], v[26:27], 0, v[34:35]
	v_lshl_add_u64 v[12:13], v[2:3], 0, v[174:175]
	global_store_dword v[10:11], v32, off offset:256
	global_store_dword v[10:11], v33, off offset:288
	global_load_dwordx4 v[10:13], v[12:13], off
	v_lshl_add_u64 v[14:15], v[8:9], 0, v[174:175]
	global_load_dwordx4 v[14:17], v[14:15], off
	v_mul_f32_e32 v24, v80, v172
	v_mul_f32_e32 v25, v81, v172
	v_mul_f32_e32 v20, v76, v172
	v_mul_f32_e32 v21, v77, v172
	v_mov_b32_e32 v32, v35
	v_mov_b32_e32 v33, v35
	v_mul_f32_e32 v22, v82, v172
	v_mul_f32_e32 v23, v83, v172
	v_mul_f32_e32 v18, v78, v172
	v_mul_f32_e32 v19, v79, v172
	v_mad_i64_i32 v[26:27], s[4:5], v146, s10, v[6:7]
	v_lshl_add_u64 v[26:27], v[26:27], 0, v[4:5]
	s_waitcnt vmcnt(1)
	v_mul_f32_e32 v30, v24, v10
	v_mul_f32_e32 v31, v25, v11
	v_mul_f32_e32 v10, v20, v10
	v_mul_f32_e32 v11, v21, v11
	s_waitcnt vmcnt(0)
	v_fma_f32 v20, v20, v14, -v30
	v_fma_f32 v21, v21, v15, -v31
	v_fmac_f32_e32 v10, v24, v14
	v_fmac_f32_e32 v11, v25, v15
	v_cvt_pk_fp8_f32 v32, v20, v21
	v_cvt_pk_fp8_f32 v33, v10, v11
	v_mul_f32_e32 v28, v22, v12
	v_mul_f32_e32 v29, v23, v13
	v_mul_f32_e32 v12, v18, v12
	v_mul_f32_e32 v13, v19, v13
	v_fma_f32 v10, v18, v16, -v28
	v_fma_f32 v11, v19, v17, -v29
	v_fmac_f32_e32 v12, v22, v16
	v_fmac_f32_e32 v13, v23, v17
	v_cvt_pk_fp8_f32 v32, v10, v11 op_sel:[0,0,1]
	v_cvt_pk_fp8_f32 v33, v12, v13 op_sel:[0,0,1]
	v_lshl_add_u64 v[10:11], v[26:27], 0, v[34:35]
	v_lshl_add_u64 v[12:13], v[2:3], 0, v[170:171]
	global_store_dword v[10:11], v32, off offset:256
	global_store_dword v[10:11], v33, off offset:288
	global_load_dwordx4 v[10:13], v[12:13], off
	v_lshl_add_u64 v[14:15], v[8:9], 0, v[170:171]
	global_load_dwordx4 v[14:17], v[14:15], off
	v_mul_f32_e32 v24, v56, v168
	v_mul_f32_e32 v25, v57, v168
	v_mul_f32_e32 v20, v52, v168
	v_mul_f32_e32 v21, v53, v168
	v_mov_b32_e32 v32, v35
	v_mov_b32_e32 v33, v35
	v_mul_f32_e32 v22, v58, v168
	v_mul_f32_e32 v23, v59, v168
	v_mul_f32_e32 v18, v54, v168
	v_mul_f32_e32 v19, v55, v168
	v_mad_i64_i32 v[26:27], s[4:5], v148, s10, v[6:7]
	v_lshl_add_u64 v[26:27], v[26:27], 0, v[4:5]
	s_waitcnt vmcnt(1)
	v_mul_f32_e32 v30, v24, v10
	v_mul_f32_e32 v31, v25, v11
	v_mul_f32_e32 v10, v20, v10
	v_mul_f32_e32 v11, v21, v11
	s_waitcnt vmcnt(0)
	v_fma_f32 v20, v20, v14, -v30
	v_fma_f32 v21, v21, v15, -v31
	v_fmac_f32_e32 v10, v24, v14
	v_fmac_f32_e32 v11, v25, v15
	v_cvt_pk_fp8_f32 v32, v20, v21
	v_cvt_pk_fp8_f32 v33, v10, v11
	v_mul_f32_e32 v28, v22, v12
	v_mul_f32_e32 v29, v23, v13
	v_mul_f32_e32 v12, v18, v12
	v_mul_f32_e32 v13, v19, v13
	v_fma_f32 v10, v18, v16, -v28
	v_fma_f32 v11, v19, v17, -v29
	v_fmac_f32_e32 v12, v22, v16
	v_fmac_f32_e32 v13, v23, v17
	v_cvt_pk_fp8_f32 v32, v10, v11 op_sel:[0,0,1]
	v_cvt_pk_fp8_f32 v33, v12, v13 op_sel:[0,0,1]
	v_lshl_add_u64 v[10:11], v[26:27], 0, v[34:35]
	v_lshl_add_u64 v[12:13], v[2:3], 0, v[166:167]
	global_store_dword v[10:11], v32, off offset:256
	global_store_dword v[10:11], v33, off offset:288
	global_load_dwordx4 v[10:13], v[12:13], off
	v_lshl_add_u64 v[14:15], v[8:9], 0, v[166:167]
	global_load_dwordx4 v[14:17], v[14:15], off
	v_mul_f32_e32 v24, v64, v164
	v_mul_f32_e32 v25, v65, v164
	v_mul_f32_e32 v20, v60, v164
	v_mul_f32_e32 v21, v61, v164
	v_mov_b32_e32 v32, v35
	v_mov_b32_e32 v33, v35
	v_mul_f32_e32 v22, v66, v164
	v_mul_f32_e32 v23, v67, v164
	v_mul_f32_e32 v18, v62, v164
	v_mul_f32_e32 v19, v63, v164
	v_mad_i64_i32 v[26:27], s[4:5], v150, s10, v[6:7]
	v_lshl_add_u64 v[26:27], v[26:27], 0, v[4:5]
	s_waitcnt vmcnt(1)
	v_mul_f32_e32 v30, v24, v10
	v_mul_f32_e32 v31, v25, v11
	v_mul_f32_e32 v10, v20, v10
	v_mul_f32_e32 v11, v21, v11
	s_waitcnt vmcnt(0)
	v_fma_f32 v20, v20, v14, -v30
	v_fma_f32 v21, v21, v15, -v31
	v_fmac_f32_e32 v10, v24, v14
	v_fmac_f32_e32 v11, v25, v15
	v_cvt_pk_fp8_f32 v32, v20, v21
	v_cvt_pk_fp8_f32 v33, v10, v11
	v_mul_f32_e32 v28, v22, v12
	v_mul_f32_e32 v29, v23, v13
	v_mul_f32_e32 v12, v18, v12
	v_mul_f32_e32 v13, v19, v13
	v_fma_f32 v10, v18, v16, -v28
	v_fma_f32 v11, v19, v17, -v29
	v_fmac_f32_e32 v12, v22, v16
	v_fmac_f32_e32 v13, v23, v17
	v_cvt_pk_fp8_f32 v32, v10, v11 op_sel:[0,0,1]
	v_cvt_pk_fp8_f32 v33, v12, v13 op_sel:[0,0,1]
	v_lshl_add_u64 v[10:11], v[26:27], 0, v[34:35]
	v_lshl_add_u64 v[12:13], v[2:3], 0, v[162:163]
	global_store_dword v[10:11], v32, off offset:256
	global_store_dword v[10:11], v33, off offset:288
	global_load_dwordx4 v[10:13], v[12:13], off
	v_lshl_add_u64 v[14:15], v[8:9], 0, v[162:163]
	global_load_dwordx4 v[14:17], v[14:15], off
	v_mul_f32_e32 v24, v44, v160
	v_mul_f32_e32 v25, v45, v160
	v_mul_f32_e32 v20, v36, v160
	v_mul_f32_e32 v21, v37, v160
	v_mov_b32_e32 v32, v35
	v_mov_b32_e32 v33, v35
	v_mul_f32_e32 v22, v46, v160
	v_mul_f32_e32 v23, v47, v160
	v_mul_f32_e32 v18, v38, v160
	v_mul_f32_e32 v19, v39, v160
	v_mad_i64_i32 v[26:27], s[4:5], v152, s10, v[6:7]
	v_lshl_add_u64 v[26:27], v[26:27], 0, v[4:5]
	v_lshl_add_u64 v[2:3], v[2:3], 0, v[158:159]
	v_mad_i64_i32 v[6:7], s[4:5], v154, s10, v[6:7]
	s_waitcnt vmcnt(1)
	v_mul_f32_e32 v30, v24, v10
	v_mul_f32_e32 v31, v25, v11
	v_mul_f32_e32 v10, v20, v10
	v_mul_f32_e32 v11, v21, v11
	s_waitcnt vmcnt(0)
	v_fma_f32 v20, v20, v14, -v30
	v_fma_f32 v21, v21, v15, -v31
	v_fmac_f32_e32 v10, v24, v14
	v_fmac_f32_e32 v11, v25, v15
	v_cvt_pk_fp8_f32 v32, v20, v21
	v_cvt_pk_fp8_f32 v33, v10, v11
	v_mul_f32_e32 v28, v22, v12
	v_mul_f32_e32 v29, v23, v13
	v_mul_f32_e32 v12, v18, v12
	v_mul_f32_e32 v13, v19, v13
	v_fma_f32 v10, v18, v16, -v28
	v_fma_f32 v11, v19, v17, -v29
	v_fmac_f32_e32 v12, v22, v16
	v_fmac_f32_e32 v13, v23, v17
	v_cvt_pk_fp8_f32 v32, v10, v11 op_sel:[0,0,1]
	v_cvt_pk_fp8_f32 v33, v12, v13 op_sel:[0,0,1]
	v_lshl_add_u64 v[10:11], v[26:27], 0, v[34:35]
	global_store_dword v[10:11], v32, off offset:256
	global_store_dword v[10:11], v33, off offset:288
	global_load_dwordx4 v[10:13], v[2:3], off
	v_lshl_add_u64 v[2:3], v[8:9], 0, v[158:159]
	global_load_dwordx4 v[14:17], v[2:3], off
	v_mul_f32_e32 v20, v40, v156
	v_mul_f32_e32 v21, v41, v156
	v_mul_f32_e32 v8, v48, v156
	v_mul_f32_e32 v9, v49, v156
	v_mov_b32_e32 v26, v35
	v_mov_b32_e32 v27, v35
	v_mul_f32_e32 v18, v42, v156
	v_mul_f32_e32 v19, v43, v156
	v_mul_f32_e32 v2, v50, v156
	v_mul_f32_e32 v3, v51, v156
	s_waitcnt vmcnt(1)
	v_mul_f32_e32 v24, v20, v10
	v_mul_f32_e32 v25, v21, v11
	v_mul_f32_e32 v10, v8, v10
	v_mul_f32_e32 v11, v9, v11
	s_waitcnt vmcnt(0)
	v_fma_f32 v8, v8, v14, -v24
	v_fma_f32 v9, v9, v15, -v25
	v_fmac_f32_e32 v10, v20, v14
	v_fmac_f32_e32 v11, v21, v15
	v_cvt_pk_fp8_f32 v26, v8, v9
	v_cvt_pk_fp8_f32 v27, v10, v11
	v_mul_f32_e32 v22, v18, v12
	v_mul_f32_e32 v23, v19, v13
	v_mul_f32_e32 v12, v2, v12
	v_mul_f32_e32 v13, v3, v13
	v_fma_f32 v2, v2, v16, -v22
	v_fma_f32 v3, v3, v17, -v23
	v_fma_f32 v8, v18, v16, v12
	v_fma_f32 v9, v19, v17, v13
	v_cvt_pk_fp8_f32 v26, v2, v3 op_sel:[0,0,1]
	v_cvt_pk_fp8_f32 v27, v8, v9 op_sel:[0,0,1]
	v_lshl_add_u64 v[2:3], v[6:7], 0, v[4:5]
	v_lshl_add_u64 v[2:3], v[2:3], 0, v[34:35]
	global_store_dword v[2:3], v26, off offset:256
	global_store_dword v[2:3], v27, off offset:288
	s_andn2_saveexec_b64 s[6:7], s[6:7]
	s_cbranch_execz .LBB0_595

.LBB0_607:
	s_or_b64 exec, exec, s[58:59]
	v_mul_f32_e32 v2, 0x3dd53b94, v206
	v_mul_f32_e32 v32, v2, v98
	v_mul_f32_e32 v33, v2, v99
	v_mul_f32_e32 v30, v2, v96
	v_mul_f32_e32 v31, v2, v97
	v_mul_f32_e32 v28, v2, v94
	v_mul_f32_e32 v29, v2, v95
	v_mul_f32_e32 v26, v2, v92
	v_mul_f32_e32 v27, v2, v93
	v_mul_f32_e32 v24, v2, v90
	v_mul_f32_e32 v25, v2, v91
	v_mul_f32_e32 v22, v2, v88
	v_mul_f32_e32 v23, v2, v89
	v_mul_f32_e32 v20, v2, v86
	v_mul_f32_e32 v21, v2, v87
	v_mul_f32_e32 v18, v2, v84
	v_mul_f32_e32 v19, v2, v85
	v_mul_f32_e32 v16, v2, v82
	v_mul_f32_e32 v17, v2, v83
	v_mul_f32_e32 v14, v2, v80
	v_mul_f32_e32 v15, v2, v81
	v_mul_f32_e32 v12, v2, v78
	v_mul_f32_e32 v13, v2, v79
	v_mul_f32_e32 v10, v2, v76
	v_mul_f32_e32 v11, v2, v77
	v_mul_f32_e32 v8, v2, v74
	v_mul_f32_e32 v9, v2, v75
	v_mul_f32_e32 v6, v2, v72
	v_mul_f32_e32 v7, v2, v73
	v_mul_f32_e32 v4, v2, v70
	v_mul_f32_e32 v5, v2, v71
	v_mul_f32_e32 v3, v2, v69
	v_mul_f32_e32 v2, v2, v68
	v_max_f32_e64 v68, |v18|, |v2|
	v_max_f32_e64 v69, |v19|, |v3|
	v_max3_f32 v68, v68, 0, v69
	v_max_f32_e64 v69, |v20|, |v4|
	v_max_f32_e64 v70, |v21|, |v5|
	v_max3_f32 v68, v68, v69, v70
	v_max_f32_e64 v69, |v22|, |v6|
	v_max_f32_e64 v70, |v23|, |v7|
	v_max3_f32 v68, v68, v69, v70
	v_max_f32_e64 v69, |v24|, |v8|
	v_max_f32_e64 v70, |v25|, |v9|
	v_max3_f32 v68, v68, v69, v70
	v_max_f32_e64 v69, |v26|, |v10|
	v_max_f32_e64 v70, |v27|, |v11|
	v_max3_f32 v68, v68, v69, v70
	v_max_f32_e64 v69, |v28|, |v12|
	v_max_f32_e64 v70, |v29|, |v13|
	v_max3_f32 v68, v68, v69, v70
	v_max_f32_e64 v69, |v30|, |v14|
	v_max_f32_e64 v70, |v31|, |v15|
	v_max3_f32 v68, v68, v69, v70
	v_max_f32_e64 v69, |v32|, |v16|
	v_max_f32_e64 v70, |v33|, |v17|
	v_max3_f32 v68, v68, v69, v70
	v_cmp_gt_u32_e32 vcc, 64, v104
	v_bfe_u32 v69, v68, 23, 8
	v_and_b32_e32 v68, 0x7fffff, v68
	v_cndmask_b32_e32 v34, v177, v181, vcc
	v_cndmask_b32_e64 v102, 64, 0, vcc
	v_cmp_gt_u32_e32 vcc, s11, v68
	v_ashrrev_i32_e32 v73, 31, v208
	v_and_b32_e32 v100, 32, v104
	v_cndmask_b32_e64 v68, -2, -3, vcc
	v_add3_u32 v68, v69, v68, s0
	v_max_i32_e32 v68, 0xffffff88, v68
	v_add_u32_e32 v68, 0x7f, v68
	v_lshlrev_b32_e32 v72, 23, v68
	v_mul_lo_u32 v82, v68, s1
	v_mov_b64_e32 v[68:69], s[26:27]
	v_mad_i64_i32 v[70:71], s[4:5], v141, s10, v[68:69]
	v_ashrrev_i32_e32 v69, 31, v104
	v_sub_co_u32_e32 v68, vcc, v208, v104
	v_mov_b32_e32 v101, v35
	s_nop 0
	v_subb_co_u32_e32 v69, vcc, v73, v69, vcc
	v_lshl_add_u64 v[70:71], v[68:69], 1, v[70:71]
	v_lshl_add_u64 v[84:85], v[70:71], 0, v[34:35]
	v_cvt_scalef32_2xpk16_fp6_f32 v[76:81], v[18:33], v[2:17], v72
	v_sub_u32_e32 v74, 0x7f000000, v72
	v_lshl_add_u64 v[84:85], v[84:85], 0, v[100:101]
	global_store_dwordx4 v[84:85], v[76:79], off offset:256
	v_mov_b32_e32 v83, v35
	global_store_dwordx4 v[84:85], v[80:83], off offset:272
	v_mul_f32_e32 v76, v18, v74
	v_mul_f32_e32 v77, v19, v74
	v_mov_b32_e32 v103, v35
	v_cmp_lt_f32_e64 vcc, |v76|, 4.0
	v_and_b32_e32 v73, 0x7fffffff, v76
	v_permlane32_swap_b32_e32 v52, v36
	v_cndmask_b32_e32 v75, 0.5, v185, vcc
	v_cmp_nlt_f32_e64 vcc, |v76|, 2.0
	v_permlane32_swap_b32_e32 v53, v37
	s_nop 0
	v_cndmask_b32_e32 v75, v197, v75, vcc
	v_permlane32_swap_b32_e32 v54, v38
	v_cmp_lt_f32_e64 vcc, |v77|, 4.0
	v_and_b32_e32 v78, 0x7fffffff, v77
	v_sub_u32_e32 v79, 0x7f000000, v75
	v_mul_f32_e64 v73, |v76|, v79
	v_cndmask_b32_e32 v79, 0.5, v185, vcc
	v_cmp_nlt_f32_e64 vcc, |v77|, 2.0
	v_rndne_f32_e32 v73, v73
	v_mul_f32_e32 v73, v75, v73
	v_cndmask_b32_e32 v79, v197, v79, vcc
	v_min_f32_e32 v73, 0x40f00000, v73
	v_bfi_b32 v76, s22, v73, v76
	v_permlane32_swap_b32_e32 v55, v39
	v_sub_u32_e32 v78, 0x7f000000, v79
	v_mul_f32_e64 v75, |v77|, v78
	v_rndne_f32_e32 v75, v75
	v_mul_f32_e32 v75, v79, v75
	v_min_f32_e32 v75, 0x40f00000, v75
	v_mul_f32_e32 v78, v2, v74
	v_mul_f32_e32 v79, v3, v74
	v_bfi_b32 v77, s22, v75, v77
	v_cmp_lt_f32_e64 vcc, |v78|, 4.0
	v_and_b32_e32 v75, 0x7fffffff, v78
	v_mul_f32_e32 v76, v76, v72
	v_mul_f32_e32 v77, v77, v72
	v_cndmask_b32_e32 v80, 0.5, v185, vcc
	v_cmp_nlt_f32_e64 vcc, |v78|, 2.0
	v_fma_f32 v18, v18, 2.0, -v76
	v_fma_f32 v19, v19, 2.0, -v77
	v_permlane32_swap_b32_e32 v56, v44
	v_cndmask_b32_e32 v80, v197, v80, vcc
	v_permlane32_swap_b32_e32 v57, v45
	v_permlane32_swap_b32_e32 v58, v46
	v_cmp_lt_f32_e64 vcc, |v79|, 4.0
	v_and_b32_e32 v75, 0x7fffffff, v79
	v_sub_u32_e32 v76, 0x7f000000, v80
	v_mul_f32_e64 v73, |v78|, v76
	v_cndmask_b32_e32 v76, 0.5, v185, vcc
	v_cmp_nlt_f32_e64 vcc, |v79|, 2.0
	v_rndne_f32_e32 v73, v73
	v_mul_f32_e32 v73, v80, v73
	v_cndmask_b32_e32 v76, v197, v76, vcc
	v_min_f32_e32 v73, 0x40f00000, v73
	v_sub_u32_e32 v77, 0x7f000000, v76
	v_mul_f32_e64 v75, |v79|, v77
	v_rndne_f32_e32 v75, v75
	v_mul_f32_e32 v75, v76, v75
	v_min_f32_e32 v75, 0x40f00000, v75
	v_mul_f32_e32 v80, v20, v74
	v_mul_f32_e32 v81, v21, v74
	v_bfi_b32 v77, s22, v75, v79
	v_cmp_lt_f32_e64 vcc, |v80|, 4.0
	v_and_b32_e32 v75, 0x7fffffff, v80
	v_permlane32_swap_b32_e32 v59, v47
	v_cndmask_b32_e32 v76, 0.5, v185, vcc
	v_cmp_nlt_f32_e64 vcc, |v80|, 2.0
	v_permlane32_swap_b32_e32 v60, v48
	s_nop 0
	v_cndmask_b32_e32 v79, v197, v76, vcc
	v_bfi_b32 v76, s22, v73, v78
	v_mul_f32_e32 v76, v76, v72
	v_mul_f32_e32 v77, v77, v72
	v_permlane32_swap_b32_e32 v61, v49
	v_fma_f32 v2, v2, 2.0, -v76
	v_fma_f32 v3, v3, 2.0, -v77
	v_cmp_lt_f32_e64 vcc, |v81|, 4.0
	v_and_b32_e32 v75, 0x7fffffff, v81
	v_sub_u32_e32 v76, 0x7f000000, v79
	v_mul_f32_e64 v73, |v80|, v76
	v_cndmask_b32_e32 v76, 0.5, v185, vcc
	v_cmp_nlt_f32_e64 vcc, |v81|, 2.0
	v_rndne_f32_e32 v73, v73
	v_mul_f32_e32 v73, v79, v73
	v_cndmask_b32_e32 v76, v197, v76, vcc
	v_min_f32_e32 v73, 0x40f00000, v73
	v_sub_u32_e32 v77, 0x7f000000, v76
	v_mul_f32_e64 v75, |v81|, v77
	v_rndne_f32_e32 v75, v75
	v_mul_f32_e32 v75, v76, v75
	v_min_f32_e32 v75, 0x40f00000, v75
	v_mul_f32_e32 v78, v4, v74
	v_mul_f32_e32 v79, v5, v74
	v_bfi_b32 v77, s22, v75, v81
	v_cmp_lt_f32_e64 vcc, |v78|, 4.0
	v_and_b32_e32 v75, 0x7fffffff, v78
	v_permlane32_swap_b32_e32 v62, v50
	v_cndmask_b32_e32 v76, 0.5, v185, vcc
	v_cmp_nlt_f32_e64 vcc, |v78|, 2.0
	v_permlane32_swap_b32_e32 v63, v51
	s_nop 0
	v_cndmask_b32_e32 v81, v197, v76, vcc
	v_bfi_b32 v76, s22, v73, v80
	v_mul_f32_e32 v76, v76, v72
	v_mul_f32_e32 v77, v77, v72
	v_permlane32_swap_b32_e32 v64, v40
	v_fma_f32 v20, v20, 2.0, -v76
	v_fma_f32 v21, v21, 2.0, -v77
	v_cmp_lt_f32_e64 vcc, |v79|, 4.0
	v_and_b32_e32 v75, 0x7fffffff, v79
	v_sub_u32_e32 v76, 0x7f000000, v81
	v_mul_f32_e64 v73, |v78|, v76
	v_cndmask_b32_e32 v76, 0.5, v185, vcc
	v_cmp_nlt_f32_e64 vcc, |v79|, 2.0
	v_rndne_f32_e32 v73, v73
	v_mul_f32_e32 v73, v81, v73
	v_cndmask_b32_e32 v76, v197, v76, vcc
	v_min_f32_e32 v73, 0x40f00000, v73
	v_sub_u32_e32 v77, 0x7f000000, v76
	v_mul_f32_e64 v75, |v79|, v77
	v_rndne_f32_e32 v75, v75
	v_mul_f32_e32 v75, v76, v75
	v_min_f32_e32 v75, 0x40f00000, v75
	v_mul_f32_e32 v80, v22, v74
	v_mul_f32_e32 v81, v23, v74
	v_bfi_b32 v77, s22, v75, v79
	v_cmp_lt_f32_e64 vcc, |v80|, 4.0
	v_and_b32_e32 v75, 0x7fffffff, v80
	v_permlane32_swap_b32_e32 v65, v41
	v_cndmask_b32_e32 v76, 0.5, v185, vcc
	v_cmp_nlt_f32_e64 vcc, |v80|, 2.0
	v_permlane32_swap_b32_e32 v66, v42
	s_nop 0
	v_cndmask_b32_e32 v79, v197, v76, vcc
	v_bfi_b32 v76, s22, v73, v78
	v_mul_f32_e32 v76, v76, v72
	v_mul_f32_e32 v77, v77, v72
	v_permlane32_swap_b32_e32 v67, v43
	v_fma_f32 v4, v4, 2.0, -v76
	v_fma_f32 v5, v5, 2.0, -v77
	v_cmp_lt_f32_e64 vcc, |v81|, 4.0
	v_and_b32_e32 v75, 0x7fffffff, v81
	v_sub_u32_e32 v76, 0x7f000000, v79
	v_mul_f32_e64 v73, |v80|, v76
	v_cndmask_b32_e32 v76, 0.5, v185, vcc
	v_cmp_nlt_f32_e64 vcc, |v81|, 2.0
	v_rndne_f32_e32 v73, v73
	v_mul_f32_e32 v73, v79, v73
	v_cndmask_b32_e32 v76, v197, v76, vcc
	v_min_f32_e32 v73, 0x40f00000, v73
	v_sub_u32_e32 v77, 0x7f000000, v76
	v_mul_f32_e64 v75, |v81|, v77
	v_rndne_f32_e32 v75, v75
	v_mul_f32_e32 v75, v76, v75
	v_min_f32_e32 v75, 0x40f00000, v75
	v_mul_f32_e32 v78, v6, v74
	v_mul_f32_e32 v79, v7, v74
	v_bfi_b32 v77, s22, v75, v81
	v_cmp_lt_f32_e64 vcc, |v78|, 4.0
	v_and_b32_e32 v75, 0x7fffffff, v78
	v_permlane16_swap_b32_e32 v52, v60
	v_cndmask_b32_e32 v76, 0.5, v185, vcc
	v_cmp_nlt_f32_e64 vcc, |v78|, 2.0
	v_permlane16_swap_b32_e32 v53, v61
	s_nop 0
	v_cndmask_b32_e32 v81, v197, v76, vcc
	v_bfi_b32 v76, s22, v73, v80
	v_mul_f32_e32 v76, v76, v72
	v_mul_f32_e32 v77, v77, v72
	v_permlane16_swap_b32_e32 v54, v62
	v_fma_f32 v22, v22, 2.0, -v76
	v_fma_f32 v23, v23, 2.0, -v77
	v_cmp_lt_f32_e64 vcc, |v79|, 4.0
	v_and_b32_e32 v75, 0x7fffffff, v79
	v_sub_u32_e32 v76, 0x7f000000, v81
	v_mul_f32_e64 v73, |v78|, v76
	v_cndmask_b32_e32 v76, 0.5, v185, vcc
	v_cmp_nlt_f32_e64 vcc, |v79|, 2.0
	v_rndne_f32_e32 v73, v73
	v_mul_f32_e32 v73, v81, v73
	v_cndmask_b32_e32 v76, v197, v76, vcc
	v_min_f32_e32 v73, 0x40f00000, v73
	v_sub_u32_e32 v77, 0x7f000000, v76
	v_mul_f32_e64 v75, |v79|, v77
	v_rndne_f32_e32 v75, v75
	v_mul_f32_e32 v75, v76, v75
	v_min_f32_e32 v75, 0x40f00000, v75
	v_mul_f32_e32 v80, v24, v74
	v_mul_f32_e32 v81, v25, v74
	v_bfi_b32 v77, s22, v75, v79
	v_cmp_lt_f32_e64 vcc, |v80|, 4.0
	v_and_b32_e32 v75, 0x7fffffff, v80
	v_permlane16_swap_b32_e32 v55, v63
	v_cndmask_b32_e32 v76, 0.5, v185, vcc
	v_cmp_nlt_f32_e64 vcc, |v80|, 2.0
	v_permlane16_swap_b32_e32 v56, v64
	s_nop 0
	v_cndmask_b32_e32 v79, v197, v76, vcc
	v_bfi_b32 v76, s22, v73, v78
	v_mul_f32_e32 v76, v76, v72
	v_mul_f32_e32 v77, v77, v72
	v_permlane16_swap_b32_e32 v57, v65
	v_fma_f32 v6, v6, 2.0, -v76
	v_fma_f32 v7, v7, 2.0, -v77
	v_cmp_lt_f32_e64 vcc, |v81|, 4.0
	v_and_b32_e32 v75, 0x7fffffff, v81
	v_sub_u32_e32 v76, 0x7f000000, v79
	v_mul_f32_e64 v73, |v80|, v76
	v_cndmask_b32_e32 v76, 0.5, v185, vcc
	v_cmp_nlt_f32_e64 vcc, |v81|, 2.0
	v_rndne_f32_e32 v73, v73
	v_mul_f32_e32 v73, v79, v73
	v_cndmask_b32_e32 v76, v197, v76, vcc
	v_min_f32_e32 v73, 0x40f00000, v73
	v_sub_u32_e32 v77, 0x7f000000, v76
	v_mul_f32_e64 v75, |v81|, v77
	v_rndne_f32_e32 v75, v75
	v_mul_f32_e32 v75, v76, v75
	v_min_f32_e32 v75, 0x40f00000, v75
	v_mul_f32_e32 v78, v8, v74
	v_mul_f32_e32 v79, v9, v74
	v_bfi_b32 v77, s22, v75, v81
	v_cmp_lt_f32_e64 vcc, |v78|, 4.0
	v_and_b32_e32 v75, 0x7fffffff, v78
	v_permlane16_swap_b32_e32 v58, v66
	v_cndmask_b32_e32 v76, 0.5, v185, vcc
	v_cmp_nlt_f32_e64 vcc, |v78|, 2.0
	v_permlane16_swap_b32_e32 v59, v67
	s_nop 0
	v_cndmask_b32_e32 v81, v197, v76, vcc
	v_bfi_b32 v76, s22, v73, v80
	v_mul_f32_e32 v76, v76, v72
	v_mul_f32_e32 v77, v77, v72
	v_permlane16_swap_b32_e32 v36, v48
	v_fma_f32 v24, v24, 2.0, -v76
	v_fma_f32 v25, v25, 2.0, -v77
	v_cmp_lt_f32_e64 vcc, |v79|, 4.0
	v_and_b32_e32 v75, 0x7fffffff, v79
	v_sub_u32_e32 v76, 0x7f000000, v81
	v_mul_f32_e64 v73, |v78|, v76
	v_cndmask_b32_e32 v76, 0.5, v185, vcc
	v_cmp_nlt_f32_e64 vcc, |v79|, 2.0
	v_rndne_f32_e32 v73, v73
	v_mul_f32_e32 v73, v81, v73
	v_cndmask_b32_e32 v76, v197, v76, vcc
	v_min_f32_e32 v73, 0x40f00000, v73
	v_sub_u32_e32 v77, 0x7f000000, v76
	v_mul_f32_e64 v75, |v79|, v77
	v_rndne_f32_e32 v75, v75
	v_mul_f32_e32 v75, v76, v75
	v_min_f32_e32 v75, 0x40f00000, v75
	v_mul_f32_e32 v80, v26, v74
	v_mul_f32_e32 v81, v27, v74
	v_bfi_b32 v77, s22, v75, v79
	v_cmp_lt_f32_e64 vcc, |v80|, 4.0
	v_and_b32_e32 v75, 0x7fffffff, v80
	v_permlane16_swap_b32_e32 v37, v49
	v_cndmask_b32_e32 v76, 0.5, v185, vcc
	v_cmp_nlt_f32_e64 vcc, |v80|, 2.0
	v_permlane16_swap_b32_e32 v38, v50
	s_nop 0
	v_cndmask_b32_e32 v79, v197, v76, vcc
	v_bfi_b32 v76, s22, v73, v78
	v_mul_f32_e32 v76, v76, v72
	v_mul_f32_e32 v77, v77, v72
	v_permlane16_swap_b32_e32 v39, v51
	v_fma_f32 v8, v8, 2.0, -v76
	v_fma_f32 v9, v9, 2.0, -v77
	v_cmp_lt_f32_e64 vcc, |v81|, 4.0
	v_and_b32_e32 v75, 0x7fffffff, v81
	v_sub_u32_e32 v76, 0x7f000000, v79
	v_mul_f32_e64 v73, |v80|, v76
	v_cndmask_b32_e32 v76, 0.5, v185, vcc
	v_cmp_nlt_f32_e64 vcc, |v81|, 2.0
	v_rndne_f32_e32 v73, v73
	v_mul_f32_e32 v73, v79, v73
	v_cndmask_b32_e32 v76, v197, v76, vcc
	v_min_f32_e32 v73, 0x40f00000, v73
	v_sub_u32_e32 v77, 0x7f000000, v76
	v_mul_f32_e64 v75, |v81|, v77
	v_rndne_f32_e32 v75, v75
	v_mul_f32_e32 v75, v76, v75
	v_min_f32_e32 v75, 0x40f00000, v75
	v_mul_f32_e32 v78, v10, v74
	v_mul_f32_e32 v79, v11, v74
	v_bfi_b32 v77, s22, v75, v81
	v_cmp_lt_f32_e64 vcc, |v78|, 4.0
	v_and_b32_e32 v75, 0x7fffffff, v78
	v_permlane16_swap_b32_e32 v44, v40
	v_cndmask_b32_e32 v76, 0.5, v185, vcc
	v_cmp_nlt_f32_e64 vcc, |v78|, 2.0
	v_permlane16_swap_b32_e32 v45, v41
	s_nop 0
	v_cndmask_b32_e32 v81, v197, v76, vcc
	v_bfi_b32 v76, s22, v73, v80
	v_mul_f32_e32 v76, v76, v72
	v_mul_f32_e32 v77, v77, v72
	v_permlane16_swap_b32_e32 v46, v42
	v_fma_f32 v26, v26, 2.0, -v76
	v_fma_f32 v27, v27, 2.0, -v77
	v_cmp_lt_f32_e64 vcc, |v79|, 4.0
	v_and_b32_e32 v75, 0x7fffffff, v79
	v_sub_u32_e32 v76, 0x7f000000, v81
	v_mul_f32_e64 v73, |v78|, v76
	v_cndmask_b32_e32 v76, 0.5, v185, vcc
	v_cmp_nlt_f32_e64 vcc, |v79|, 2.0
	v_rndne_f32_e32 v73, v73
	v_mul_f32_e32 v73, v81, v73
	v_cndmask_b32_e32 v76, v197, v76, vcc
	v_min_f32_e32 v73, 0x40f00000, v73
	v_sub_u32_e32 v77, 0x7f000000, v76
	v_mul_f32_e64 v75, |v79|, v77
	v_rndne_f32_e32 v75, v75
	v_mul_f32_e32 v75, v76, v75
	v_min_f32_e32 v75, 0x40f00000, v75
	v_mul_f32_e32 v80, v28, v74
	v_mul_f32_e32 v81, v29, v74
	v_bfi_b32 v77, s22, v75, v79
	v_cmp_lt_f32_e64 vcc, |v80|, 4.0
	v_and_b32_e32 v75, 0x7fffffff, v80
	v_permlane16_swap_b32_e32 v47, v43
	v_cndmask_b32_e32 v76, 0.5, v185, vcc
	v_cmp_nlt_f32_e64 vcc, |v80|, 2.0
	s_nop 1
	v_cndmask_b32_e32 v79, v197, v76, vcc
	v_bfi_b32 v76, s22, v73, v78
	v_mul_f32_e32 v76, v76, v72
	v_mul_f32_e32 v77, v77, v72
	v_fma_f32 v10, v10, 2.0, -v76
	v_fma_f32 v11, v11, 2.0, -v77
	v_cmp_lt_f32_e64 vcc, |v81|, 4.0
	v_and_b32_e32 v75, 0x7fffffff, v81
	v_sub_u32_e32 v76, 0x7f000000, v79
	v_mul_f32_e64 v73, |v80|, v76
	v_cndmask_b32_e32 v76, 0.5, v185, vcc
	v_cmp_nlt_f32_e64 vcc, |v81|, 2.0
	v_rndne_f32_e32 v73, v73
	v_mul_f32_e32 v73, v79, v73
	v_cndmask_b32_e32 v76, v197, v76, vcc
	v_min_f32_e32 v73, 0x40f00000, v73
	v_sub_u32_e32 v77, 0x7f000000, v76
	v_mul_f32_e64 v75, |v81|, v77
	v_rndne_f32_e32 v75, v75
	v_mul_f32_e32 v75, v76, v75
	v_min_f32_e32 v75, 0x40f00000, v75
	v_mul_f32_e32 v78, v12, v74
	v_mul_f32_e32 v79, v13, v74
	v_bfi_b32 v77, s22, v75, v81
	v_cmp_lt_f32_e64 vcc, |v78|, 4.0
	v_and_b32_e32 v75, 0x7fffffff, v78
	s_nop 0
	v_cndmask_b32_e32 v76, 0.5, v185, vcc
	v_cmp_nlt_f32_e64 vcc, |v78|, 2.0
	s_nop 1
	v_cndmask_b32_e32 v81, v197, v76, vcc
	v_bfi_b32 v76, s22, v73, v80
	v_mul_f32_e32 v76, v76, v72
	v_mul_f32_e32 v77, v77, v72
	v_fma_f32 v28, v28, 2.0, -v76
	v_fma_f32 v29, v29, 2.0, -v77
	v_cmp_lt_f32_e64 vcc, |v79|, 4.0
	v_and_b32_e32 v75, 0x7fffffff, v79
	v_sub_u32_e32 v76, 0x7f000000, v81
	v_mul_f32_e64 v73, |v78|, v76
	v_cndmask_b32_e32 v76, 0.5, v185, vcc
	v_cmp_nlt_f32_e64 vcc, |v79|, 2.0
	v_rndne_f32_e32 v73, v73
	v_mul_f32_e32 v73, v81, v73
	v_cndmask_b32_e32 v76, v197, v76, vcc
	v_min_f32_e32 v73, 0x40f00000, v73
	v_sub_u32_e32 v77, 0x7f000000, v76
	v_mul_f32_e64 v75, |v79|, v77
	v_rndne_f32_e32 v75, v75
	v_mul_f32_e32 v75, v76, v75
	v_min_f32_e32 v75, 0x40f00000, v75
	v_mul_f32_e32 v80, v30, v74
	v_mul_f32_e32 v81, v31, v74
	v_bfi_b32 v77, s22, v75, v79
	v_cmp_lt_f32_e64 vcc, |v80|, 4.0
	v_and_b32_e32 v75, 0x7fffffff, v80
	s_nop 0
	v_cndmask_b32_e32 v76, 0.5, v185, vcc
	v_cmp_nlt_f32_e64 vcc, |v80|, 2.0
	s_nop 1
	v_cndmask_b32_e32 v79, v197, v76, vcc
	v_bfi_b32 v76, s22, v73, v78
	v_mul_f32_e32 v76, v76, v72
	v_mul_f32_e32 v77, v77, v72
	v_fma_f32 v12, v12, 2.0, -v76
	v_fma_f32 v13, v13, 2.0, -v77
	v_cmp_lt_f32_e64 vcc, |v81|, 4.0
	v_and_b32_e32 v75, 0x7fffffff, v81
	v_sub_u32_e32 v76, 0x7f000000, v79
	v_mul_f32_e64 v73, |v80|, v76
	v_cndmask_b32_e32 v76, 0.5, v185, vcc
	v_cmp_nlt_f32_e64 vcc, |v81|, 2.0
	v_rndne_f32_e32 v73, v73
	v_mul_f32_e32 v73, v79, v73
	v_cndmask_b32_e32 v76, v197, v76, vcc
	v_min_f32_e32 v73, 0x40f00000, v73
	v_sub_u32_e32 v77, 0x7f000000, v76
	v_mul_f32_e64 v75, |v81|, v77
	v_rndne_f32_e32 v75, v75
	v_mul_f32_e32 v75, v76, v75
	v_min_f32_e32 v75, 0x40f00000, v75
	v_mul_f32_e32 v78, v14, v74
	v_mul_f32_e32 v79, v15, v74
	v_bfi_b32 v77, s22, v75, v81
	v_cmp_lt_f32_e64 vcc, |v78|, 4.0
	v_and_b32_e32 v75, 0x7fffffff, v78
	s_nop 0
	v_cndmask_b32_e32 v76, 0.5, v185, vcc
	v_cmp_nlt_f32_e64 vcc, |v78|, 2.0
	s_nop 1
	v_cndmask_b32_e32 v81, v197, v76, vcc
	v_bfi_b32 v76, s22, v73, v80
	v_mul_f32_e32 v76, v76, v72
	v_mul_f32_e32 v77, v77, v72
	v_fma_f32 v30, v30, 2.0, -v76
	v_fma_f32 v31, v31, 2.0, -v77
	v_cmp_lt_f32_e64 vcc, |v79|, 4.0
	v_and_b32_e32 v75, 0x7fffffff, v79
	v_sub_u32_e32 v76, 0x7f000000, v81
	v_mul_f32_e64 v73, |v78|, v76
	v_cndmask_b32_e32 v76, 0.5, v185, vcc
	v_cmp_nlt_f32_e64 vcc, |v79|, 2.0
	v_rndne_f32_e32 v73, v73
	v_mul_f32_e32 v73, v81, v73
	v_cndmask_b32_e32 v76, v197, v76, vcc
	v_min_f32_e32 v73, 0x40f00000, v73
	v_sub_u32_e32 v77, 0x7f000000, v76
	v_mul_f32_e64 v75, |v79|, v77
	v_rndne_f32_e32 v75, v75
	v_mul_f32_e32 v75, v76, v75
	v_min_f32_e32 v75, 0x40f00000, v75
	v_mul_f32_e32 v80, v32, v74
	v_mul_f32_e32 v81, v33, v74
	v_bfi_b32 v77, s22, v75, v79
	v_cmp_lt_f32_e64 vcc, |v80|, 4.0
	v_and_b32_e32 v75, 0x7fffffff, v80
	s_nop 0
	v_cndmask_b32_e32 v76, 0.5, v185, vcc
	v_cmp_nlt_f32_e64 vcc, |v80|, 2.0
	s_nop 1
	v_cndmask_b32_e32 v79, v197, v76, vcc
	v_bfi_b32 v76, s22, v73, v78
	v_mul_f32_e32 v76, v76, v72
	v_mul_f32_e32 v77, v77, v72
	v_fma_f32 v14, v14, 2.0, -v76
	v_fma_f32 v15, v15, 2.0, -v77
	v_cmp_lt_f32_e64 vcc, |v81|, 4.0
	v_and_b32_e32 v75, 0x7fffffff, v81
	v_sub_u32_e32 v76, 0x7f000000, v79
	v_mul_f32_e64 v73, |v80|, v76
	v_cndmask_b32_e32 v76, 0.5, v185, vcc
	v_cmp_nlt_f32_e64 vcc, |v81|, 2.0
	v_rndne_f32_e32 v73, v73
	v_mul_f32_e32 v73, v79, v73
	v_cndmask_b32_e32 v76, v197, v76, vcc
	v_min_f32_e32 v73, 0x40f00000, v73
	v_sub_u32_e32 v77, 0x7f000000, v76
	v_mul_f32_e64 v75, |v81|, v77
	v_rndne_f32_e32 v75, v75
	v_mul_f32_e32 v75, v76, v75
	v_min_f32_e32 v75, 0x40f00000, v75
	v_bfi_b32 v75, s22, v75, v81
	v_mul_f32_e32 v76, v16, v74
	v_mul_f32_e32 v77, v17, v74
	s_nop 0
	v_cmp_lt_f32_e64 vcc, |v76|, 4.0
	v_and_b32_e32 v78, 0x7fffffff, v76
	s_nop 0
	v_cndmask_b32_e32 v74, 0.5, v185, vcc
	v_cmp_nlt_f32_e64 vcc, |v76|, 2.0
	s_nop 1
	v_cndmask_b32_e32 v79, v197, v74, vcc
	v_bfi_b32 v74, s22, v73, v80
	v_mul_f32_e32 v74, v74, v72
	v_mul_f32_e32 v75, v75, v72
	v_fma_f32 v32, v32, 2.0, -v74
	v_fma_f32 v33, v33, 2.0, -v75
	v_cmp_lt_f32_e64 vcc, |v77|, 4.0
	v_and_b32_e32 v74, 0x7fffffff, v77
	v_sub_u32_e32 v75, 0x7f000000, v79
	v_mul_f32_e64 v73, |v76|, v75
	v_cndmask_b32_e32 v75, 0.5, v185, vcc
	v_cmp_nlt_f32_e64 vcc, |v77|, 2.0
	v_rndne_f32_e32 v73, v73
	v_mul_f32_e32 v73, v79, v73
	v_cndmask_b32_e32 v75, v197, v75, vcc
	v_min_f32_e32 v73, 0x40f00000, v73
	v_sub_u32_e32 v78, 0x7f000000, v75
	v_mul_f32_e64 v74, |v77|, v78
	v_rndne_f32_e32 v74, v74
	v_mul_f32_e32 v74, v75, v74
	v_min_f32_e32 v74, 0x40f00000, v74
	v_bfi_b32 v75, s22, v74, v77
	v_bfi_b32 v74, s22, v73, v76
	v_mul_f32_e32 v73, v75, v72
	v_mul_f32_e32 v72, v74, v72
	v_max_f32_e64 v74, |v21|, |v5|
	v_fma_f32 v16, v16, 2.0, -v72
	v_fma_f32 v17, v17, 2.0, -v73
	v_max_f32_e64 v72, |v18|, |v2|
	v_max_f32_e64 v73, |v19|, |v3|
	v_max3_f32 v72, v72, 0, v73
	v_max_f32_e64 v73, |v20|, |v4|
	v_max3_f32 v72, v72, v73, v74
	v_max_f32_e64 v73, |v22|, |v6|
	v_max_f32_e64 v74, |v23|, |v7|
	v_max3_f32 v72, v72, v73, v74
	v_max_f32_e64 v73, |v24|, |v8|
	v_max_f32_e64 v74, |v25|, |v9|
	v_max3_f32 v72, v72, v73, v74
	v_max_f32_e64 v73, |v26|, |v10|
	v_max_f32_e64 v74, |v27|, |v11|
	v_max3_f32 v72, v72, v73, v74
	v_max_f32_e64 v73, |v28|, |v12|
	v_max_f32_e64 v74, |v29|, |v13|
	v_max3_f32 v72, v72, v73, v74
	v_max_f32_e64 v73, |v30|, |v14|
	v_max_f32_e64 v74, |v31|, |v15|
	v_max3_f32 v72, v72, v73, v74
	v_max_f32_e64 v73, |v32|, |v16|
	v_max_f32_e64 v74, |v33|, |v17|
	v_max3_f32 v72, v72, v73, v74
	v_bfe_u32 v73, v72, 23, 8
	v_and_b32_e32 v72, 0x7fffff, v72
	v_cmp_gt_u32_e32 vcc, s11, v72
	s_nop 1
	v_cndmask_b32_e64 v72, -2, -3, vcc
	v_add3_u32 v72, v73, v72, s0
	v_max_i32_e32 v72, 0xffffff88, v72
	v_add_u32_e32 v72, 0x7f, v72
	v_lshlrev_b32_e32 v79, 23, v72
	v_mul_lo_u32 v78, v72, s1
	v_cvt_scalef32_2xpk16_fp6_f32 v[72:77], v[18:33], v[2:17], v79
	v_lshl_add_u64 v[2:3], v[70:71], 0, v[102:103]
	v_lshl_add_u64 v[2:3], v[2:3], 0, v[100:101]
	v_mov_b32_e32 v79, v35
	v_cmp_lt_i32_e32 vcc, 1, v199
	global_store_dwordx4 v[2:3], v[72:75], off offset:256
	global_store_dwordx4 v[2:3], v[76:79], off offset:272
	s_and_saveexec_b64 s[4:5], vcc
	s_xor_b64 s[4:5], exec, s[4:5]
	s_cbranch_execz .LBB0_611
	v_cmp_gt_i32_e32 vcc, 3, v199
	s_and_saveexec_b64 s[58:59], vcc
	v_mov_b32_e32 v207, v204
	s_or_b64 exec, exec, s[58:59]

.LBB0_617:
	s_or_b64 exec, exec, s[58:59]
	v_mul_f32_e32 v2, 0x3dd53b94, v207
	v_mul_f32_e32 v32, v2, v66
	v_mul_f32_e32 v33, v2, v67
	v_mul_f32_e32 v30, v2, v64
	v_mul_f32_e32 v31, v2, v65
	v_mul_f32_e32 v28, v2, v62
	v_mul_f32_e32 v29, v2, v63
	v_mul_f32_e32 v26, v2, v60
	v_mul_f32_e32 v27, v2, v61
	v_mul_f32_e32 v24, v2, v58
	v_mul_f32_e32 v25, v2, v59
	v_mul_f32_e32 v22, v2, v56
	v_mul_f32_e32 v23, v2, v57
	v_mul_f32_e32 v20, v2, v54
	v_mul_f32_e32 v21, v2, v55
	v_mul_f32_e32 v18, v2, v52
	v_mul_f32_e32 v19, v2, v53
	v_mul_f32_e32 v16, v2, v42
	v_mul_f32_e32 v17, v2, v43
	v_mul_f32_e32 v14, v2, v40
	v_mul_f32_e32 v15, v2, v41
	v_mul_f32_e32 v12, v2, v50
	v_mul_f32_e32 v13, v2, v51
	v_mul_f32_e32 v10, v2, v48
	v_mul_f32_e32 v11, v2, v49
	v_mul_f32_e32 v8, v2, v46
	v_mul_f32_e32 v9, v2, v47
	v_mul_f32_e32 v6, v2, v44
	v_mul_f32_e32 v7, v2, v45
	v_mul_f32_e32 v4, v2, v38
	v_mul_f32_e32 v5, v2, v39
	v_mul_f32_e32 v3, v2, v37
	v_mul_f32_e32 v2, v2, v36
	v_max_f32_e64 v36, |v18|, |v2|
	v_max_f32_e64 v37, |v19|, |v3|
	v_max3_f32 v36, v36, 0, v37
	v_max_f32_e64 v37, |v20|, |v4|
	v_max_f32_e64 v38, |v21|, |v5|
	v_max3_f32 v36, v36, v37, v38
	v_max_f32_e64 v37, |v22|, |v6|
	v_max_f32_e64 v38, |v23|, |v7|
	v_max3_f32 v36, v36, v37, v38
	v_max_f32_e64 v37, |v24|, |v8|
	v_max_f32_e64 v38, |v25|, |v9|
	v_max3_f32 v36, v36, v37, v38
	v_max_f32_e64 v37, |v26|, |v10|
	v_max_f32_e64 v38, |v27|, |v11|
	v_max3_f32 v36, v36, v37, v38
	v_max_f32_e64 v37, |v28|, |v12|
	v_max_f32_e64 v38, |v29|, |v13|
	v_max3_f32 v36, v36, v37, v38
	v_max_f32_e64 v37, |v30|, |v14|
	v_max_f32_e64 v38, |v31|, |v15|
	v_max3_f32 v36, v36, v37, v38
	v_max_f32_e64 v37, |v32|, |v16|
	v_max_f32_e64 v38, |v33|, |v17|
	v_max3_f32 v36, v36, v37, v38
	v_bfe_u32 v37, v36, 23, 8
	v_and_b32_e32 v36, 0x7fffff, v36
	v_cmp_gt_u32_e32 vcc, s11, v36
	v_add_u32_e32 v39, 0x80, v141
	v_mov_b32_e32 v49, v35
	v_cndmask_b32_e64 v36, -2, -3, vcc
	v_add3_u32 v36, v37, v36, s0
	v_max_i32_e32 v36, 0xffffff88, v36
	v_add_u32_e32 v36, 0x7f, v36
	v_lshlrev_b32_e32 v38, 23, v36
	v_mul_lo_u32 v48, v36, s1
	v_mov_b64_e32 v[36:37], s[26:27]
	v_mad_i64_i32 v[36:37], s[4:5], v39, s10, v[36:37]
	v_lshl_add_u64 v[36:37], v[68:69], 1, v[36:37]
	v_lshl_add_u64 v[50:51], v[36:37], 0, v[34:35]
	v_cvt_scalef32_2xpk16_fp6_f32 v[42:47], v[18:33], v[2:17], v38
	v_sub_u32_e32 v40, 0x7f000000, v38
	v_lshl_add_u64 v[50:51], v[50:51], 0, v[100:101]
	global_store_dwordx4 v[50:51], v[42:45], off offset:256
	global_store_dwordx4 v[50:51], v[46:49], off offset:272
	s_nop 0
	v_mul_f32_e32 v42, v18, v40
	v_mul_f32_e32 v43, v19, v40
	s_nop 0
	v_cmp_lt_f32_e64 vcc, |v42|, 4.0
	v_and_b32_e32 v34, 0x7fffffff, v42
	s_nop 0
	v_cndmask_b32_e32 v39, 0.5, v185, vcc
	v_cmp_nlt_f32_e64 vcc, |v42|, 2.0
	s_nop 1
	v_cndmask_b32_e32 v39, v197, v39, vcc
	v_cmp_lt_f32_e64 vcc, |v43|, 4.0
	v_and_b32_e32 v41, 0x7fffffff, v43
	v_sub_u32_e32 v44, 0x7f000000, v39
	v_mul_f32_e64 v34, |v42|, v44
	v_cndmask_b32_e32 v44, 0.5, v185, vcc
	v_cmp_nlt_f32_e64 vcc, |v43|, 2.0
	v_rndne_f32_e32 v34, v34
	v_mul_f32_e32 v34, v39, v34
	v_cndmask_b32_e32 v44, v197, v44, vcc
	v_min_f32_e32 v34, 0x40f00000, v34
	v_bfi_b32 v42, s22, v34, v42
	v_sub_u32_e32 v41, 0x7f000000, v44
	v_mul_f32_e64 v39, |v43|, v41
	v_rndne_f32_e32 v39, v39
	v_mul_f32_e32 v39, v44, v39
	v_mul_f32_e32 v44, v2, v40
	v_mul_f32_e32 v45, v3, v40
	v_min_f32_e32 v39, 0x40f00000, v39
	v_cmp_lt_f32_e64 vcc, |v44|, 4.0
	v_bfi_b32 v43, s22, v39, v43
	v_and_b32_e32 v39, 0x7fffffff, v44
	v_cndmask_b32_e32 v41, 0.5, v185, vcc
	v_cmp_nlt_f32_e64 vcc, |v44|, 2.0
	v_mul_f32_e32 v42, v42, v38
	v_mul_f32_e32 v43, v43, v38
	s_nop 0
	v_cndmask_b32_e32 v41, v197, v41, vcc
	v_fma_f32 v18, v18, 2.0, -v42
	v_fma_f32 v19, v19, 2.0, -v43
	v_cmp_lt_f32_e64 vcc, |v45|, 4.0
	v_and_b32_e32 v39, 0x7fffffff, v45
	v_sub_u32_e32 v42, 0x7f000000, v41
	v_mul_f32_e64 v34, |v44|, v42
	v_cndmask_b32_e32 v42, 0.5, v185, vcc
	v_cmp_nlt_f32_e64 vcc, |v45|, 2.0
	v_rndne_f32_e32 v34, v34
	v_mul_f32_e32 v34, v41, v34
	v_cndmask_b32_e32 v42, v197, v42, vcc
	v_min_f32_e32 v34, 0x40f00000, v34
	v_sub_u32_e32 v41, 0x7f000000, v42
	v_mul_f32_e64 v39, |v45|, v41
	v_rndne_f32_e32 v39, v39
	v_mul_f32_e32 v46, v20, v40
	v_mul_f32_e32 v47, v21, v40
	v_mul_f32_e32 v39, v42, v39
	v_cmp_lt_f32_e64 vcc, |v46|, 4.0
	v_min_f32_e32 v39, 0x40f00000, v39
	v_bfi_b32 v43, s22, v39, v45
	v_cndmask_b32_e32 v41, 0.5, v185, vcc
	v_cmp_nlt_f32_e64 vcc, |v46|, 2.0
	v_and_b32_e32 v39, 0x7fffffff, v46
	v_bfi_b32 v42, s22, v34, v44
	v_cndmask_b32_e32 v41, v197, v41, vcc
	v_mul_f32_e32 v42, v42, v38
	v_mul_f32_e32 v43, v43, v38
	v_fma_f32 v2, v2, 2.0, -v42
	v_fma_f32 v3, v3, 2.0, -v43
	v_cmp_lt_f32_e64 vcc, |v47|, 4.0
	v_and_b32_e32 v39, 0x7fffffff, v47
	v_sub_u32_e32 v42, 0x7f000000, v41
	v_mul_f32_e64 v34, |v46|, v42
	v_cndmask_b32_e32 v42, 0.5, v185, vcc
	v_cmp_nlt_f32_e64 vcc, |v47|, 2.0
	v_rndne_f32_e32 v34, v34
	v_mul_f32_e32 v34, v41, v34
	v_cndmask_b32_e32 v42, v197, v42, vcc
	v_min_f32_e32 v34, 0x40f00000, v34
	v_sub_u32_e32 v41, 0x7f000000, v42
	v_mul_f32_e64 v39, |v47|, v41
	v_rndne_f32_e32 v39, v39
	v_mul_f32_e32 v44, v4, v40
	v_mul_f32_e32 v45, v5, v40
	v_mul_f32_e32 v39, v42, v39
	v_cmp_lt_f32_e64 vcc, |v44|, 4.0
	v_min_f32_e32 v39, 0x40f00000, v39
	v_bfi_b32 v43, s22, v39, v47
	v_cndmask_b32_e32 v41, 0.5, v185, vcc
	v_cmp_nlt_f32_e64 vcc, |v44|, 2.0
	v_and_b32_e32 v39, 0x7fffffff, v44
	v_bfi_b32 v42, s22, v34, v46
	v_cndmask_b32_e32 v41, v197, v41, vcc
	v_mul_f32_e32 v42, v42, v38
	v_mul_f32_e32 v43, v43, v38
	v_fma_f32 v20, v20, 2.0, -v42
	v_fma_f32 v21, v21, 2.0, -v43
	v_cmp_lt_f32_e64 vcc, |v45|, 4.0
	v_and_b32_e32 v39, 0x7fffffff, v45
	v_sub_u32_e32 v42, 0x7f000000, v41
	v_mul_f32_e64 v34, |v44|, v42
	v_cndmask_b32_e32 v42, 0.5, v185, vcc
	v_cmp_nlt_f32_e64 vcc, |v45|, 2.0
	v_rndne_f32_e32 v34, v34
	v_mul_f32_e32 v34, v41, v34
	v_cndmask_b32_e32 v42, v197, v42, vcc
	v_min_f32_e32 v34, 0x40f00000, v34
	v_sub_u32_e32 v41, 0x7f000000, v42
	v_mul_f32_e64 v39, |v45|, v41
	v_rndne_f32_e32 v39, v39
	v_mul_f32_e32 v46, v22, v40
	v_mul_f32_e32 v47, v23, v40
	v_mul_f32_e32 v39, v42, v39
	v_cmp_lt_f32_e64 vcc, |v46|, 4.0
	v_min_f32_e32 v39, 0x40f00000, v39
	v_bfi_b32 v43, s22, v39, v45
	v_cndmask_b32_e32 v41, 0.5, v185, vcc
	v_cmp_nlt_f32_e64 vcc, |v46|, 2.0
	v_and_b32_e32 v39, 0x7fffffff, v46
	v_bfi_b32 v42, s22, v34, v44
	v_cndmask_b32_e32 v41, v197, v41, vcc
	v_mul_f32_e32 v42, v42, v38
	v_mul_f32_e32 v43, v43, v38
	v_fma_f32 v4, v4, 2.0, -v42
	v_fma_f32 v5, v5, 2.0, -v43
	v_cmp_lt_f32_e64 vcc, |v47|, 4.0
	v_and_b32_e32 v39, 0x7fffffff, v47
	v_sub_u32_e32 v42, 0x7f000000, v41
	v_mul_f32_e64 v34, |v46|, v42
	v_cndmask_b32_e32 v42, 0.5, v185, vcc
	v_cmp_nlt_f32_e64 vcc, |v47|, 2.0
	v_rndne_f32_e32 v34, v34
	v_mul_f32_e32 v34, v41, v34
	v_cndmask_b32_e32 v42, v197, v42, vcc
	v_min_f32_e32 v34, 0x40f00000, v34
	v_sub_u32_e32 v41, 0x7f000000, v42
	v_mul_f32_e64 v39, |v47|, v41
	v_rndne_f32_e32 v39, v39
	v_mul_f32_e32 v44, v6, v40
	v_mul_f32_e32 v45, v7, v40
	v_mul_f32_e32 v39, v42, v39
	v_cmp_lt_f32_e64 vcc, |v44|, 4.0
	v_min_f32_e32 v39, 0x40f00000, v39
	v_bfi_b32 v43, s22, v39, v47
	v_cndmask_b32_e32 v41, 0.5, v185, vcc
	v_cmp_nlt_f32_e64 vcc, |v44|, 2.0
	v_and_b32_e32 v39, 0x7fffffff, v44
	v_bfi_b32 v42, s22, v34, v46
	v_cndmask_b32_e32 v41, v197, v41, vcc
	v_mul_f32_e32 v42, v42, v38
	v_mul_f32_e32 v43, v43, v38
	v_fma_f32 v22, v22, 2.0, -v42
	v_fma_f32 v23, v23, 2.0, -v43
	v_cmp_lt_f32_e64 vcc, |v45|, 4.0
	v_and_b32_e32 v39, 0x7fffffff, v45
	v_sub_u32_e32 v42, 0x7f000000, v41
	v_mul_f32_e64 v34, |v44|, v42
	v_cndmask_b32_e32 v42, 0.5, v185, vcc
	v_cmp_nlt_f32_e64 vcc, |v45|, 2.0
	v_rndne_f32_e32 v34, v34
	v_mul_f32_e32 v34, v41, v34
	v_cndmask_b32_e32 v42, v197, v42, vcc
	v_min_f32_e32 v34, 0x40f00000, v34
	v_sub_u32_e32 v41, 0x7f000000, v42
	v_mul_f32_e64 v39, |v45|, v41
	v_rndne_f32_e32 v39, v39
	v_mul_f32_e32 v46, v24, v40
	v_mul_f32_e32 v47, v25, v40
	v_mul_f32_e32 v39, v42, v39
	v_cmp_lt_f32_e64 vcc, |v46|, 4.0
	v_min_f32_e32 v39, 0x40f00000, v39
	v_bfi_b32 v43, s22, v39, v45
	v_cndmask_b32_e32 v41, 0.5, v185, vcc
	v_cmp_nlt_f32_e64 vcc, |v46|, 2.0
	v_and_b32_e32 v39, 0x7fffffff, v46
	v_bfi_b32 v42, s22, v34, v44
	v_cndmask_b32_e32 v41, v197, v41, vcc
	v_mul_f32_e32 v42, v42, v38
	v_mul_f32_e32 v43, v43, v38
	v_fma_f32 v6, v6, 2.0, -v42
	v_fma_f32 v7, v7, 2.0, -v43
	v_cmp_lt_f32_e64 vcc, |v47|, 4.0
	v_and_b32_e32 v39, 0x7fffffff, v47
	v_sub_u32_e32 v42, 0x7f000000, v41
	v_mul_f32_e64 v34, |v46|, v42
	v_cndmask_b32_e32 v42, 0.5, v185, vcc
	v_cmp_nlt_f32_e64 vcc, |v47|, 2.0
	v_rndne_f32_e32 v34, v34
	v_mul_f32_e32 v34, v41, v34
	v_cndmask_b32_e32 v42, v197, v42, vcc
	v_min_f32_e32 v34, 0x40f00000, v34
	v_sub_u32_e32 v41, 0x7f000000, v42
	v_mul_f32_e64 v39, |v47|, v41
	v_rndne_f32_e32 v39, v39
	v_mul_f32_e32 v44, v8, v40
	v_mul_f32_e32 v45, v9, v40
	v_mul_f32_e32 v39, v42, v39
	v_cmp_lt_f32_e64 vcc, |v44|, 4.0
	v_min_f32_e32 v39, 0x40f00000, v39
	v_bfi_b32 v43, s22, v39, v47
	v_cndmask_b32_e32 v41, 0.5, v185, vcc
	v_cmp_nlt_f32_e64 vcc, |v44|, 2.0
	v_and_b32_e32 v39, 0x7fffffff, v44
	v_bfi_b32 v42, s22, v34, v46
	v_cndmask_b32_e32 v41, v197, v41, vcc
	v_mul_f32_e32 v42, v42, v38
	v_mul_f32_e32 v43, v43, v38
	v_fma_f32 v24, v24, 2.0, -v42
	v_fma_f32 v25, v25, 2.0, -v43
	v_cmp_lt_f32_e64 vcc, |v45|, 4.0
	v_and_b32_e32 v39, 0x7fffffff, v45
	v_sub_u32_e32 v42, 0x7f000000, v41
	v_mul_f32_e64 v34, |v44|, v42
	v_cndmask_b32_e32 v42, 0.5, v185, vcc
	v_cmp_nlt_f32_e64 vcc, |v45|, 2.0
	v_rndne_f32_e32 v34, v34
	v_mul_f32_e32 v34, v41, v34
	v_cndmask_b32_e32 v42, v197, v42, vcc
	v_min_f32_e32 v34, 0x40f00000, v34
	v_sub_u32_e32 v41, 0x7f000000, v42
	v_mul_f32_e64 v39, |v45|, v41
	v_rndne_f32_e32 v39, v39
	v_mul_f32_e32 v46, v26, v40
	v_mul_f32_e32 v47, v27, v40
	v_mul_f32_e32 v39, v42, v39
	v_cmp_lt_f32_e64 vcc, |v46|, 4.0
	v_min_f32_e32 v39, 0x40f00000, v39
	v_bfi_b32 v43, s22, v39, v45
	v_cndmask_b32_e32 v41, 0.5, v185, vcc
	v_cmp_nlt_f32_e64 vcc, |v46|, 2.0
	v_and_b32_e32 v39, 0x7fffffff, v46
	v_bfi_b32 v42, s22, v34, v44
	v_cndmask_b32_e32 v41, v197, v41, vcc
	v_mul_f32_e32 v42, v42, v38
	v_mul_f32_e32 v43, v43, v38
	v_fma_f32 v8, v8, 2.0, -v42
	v_fma_f32 v9, v9, 2.0, -v43
	v_cmp_lt_f32_e64 vcc, |v47|, 4.0
	v_and_b32_e32 v39, 0x7fffffff, v47
	v_sub_u32_e32 v42, 0x7f000000, v41
	v_mul_f32_e64 v34, |v46|, v42
	v_cndmask_b32_e32 v42, 0.5, v185, vcc
	v_cmp_nlt_f32_e64 vcc, |v47|, 2.0
	v_rndne_f32_e32 v34, v34
	v_mul_f32_e32 v34, v41, v34
	v_cndmask_b32_e32 v42, v197, v42, vcc
	v_min_f32_e32 v34, 0x40f00000, v34
	v_sub_u32_e32 v41, 0x7f000000, v42
	v_mul_f32_e64 v39, |v47|, v41
	v_rndne_f32_e32 v39, v39
	v_mul_f32_e32 v44, v10, v40
	v_mul_f32_e32 v45, v11, v40
	v_mul_f32_e32 v39, v42, v39
	v_cmp_lt_f32_e64 vcc, |v44|, 4.0
	v_min_f32_e32 v39, 0x40f00000, v39
	v_bfi_b32 v43, s22, v39, v47
	v_cndmask_b32_e32 v41, 0.5, v185, vcc
	v_cmp_nlt_f32_e64 vcc, |v44|, 2.0
	v_and_b32_e32 v39, 0x7fffffff, v44
	v_bfi_b32 v42, s22, v34, v46
	v_cndmask_b32_e32 v41, v197, v41, vcc
	v_mul_f32_e32 v42, v42, v38
	v_mul_f32_e32 v43, v43, v38
	v_fma_f32 v26, v26, 2.0, -v42
	v_fma_f32 v27, v27, 2.0, -v43
	v_cmp_lt_f32_e64 vcc, |v45|, 4.0
	v_and_b32_e32 v39, 0x7fffffff, v45
	v_sub_u32_e32 v42, 0x7f000000, v41
	v_mul_f32_e64 v34, |v44|, v42
	v_cndmask_b32_e32 v42, 0.5, v185, vcc
	v_cmp_nlt_f32_e64 vcc, |v45|, 2.0
	v_rndne_f32_e32 v34, v34
	v_mul_f32_e32 v34, v41, v34
	v_cndmask_b32_e32 v42, v197, v42, vcc
	v_min_f32_e32 v34, 0x40f00000, v34
	v_sub_u32_e32 v41, 0x7f000000, v42
	v_mul_f32_e64 v39, |v45|, v41
	v_rndne_f32_e32 v39, v39
	v_mul_f32_e32 v46, v28, v40
	v_mul_f32_e32 v47, v29, v40
	v_mul_f32_e32 v39, v42, v39
	v_cmp_lt_f32_e64 vcc, |v46|, 4.0
	v_min_f32_e32 v39, 0x40f00000, v39
	v_bfi_b32 v43, s22, v39, v45
	v_cndmask_b32_e32 v41, 0.5, v185, vcc
	v_cmp_nlt_f32_e64 vcc, |v46|, 2.0
	v_and_b32_e32 v39, 0x7fffffff, v46
	v_bfi_b32 v42, s22, v34, v44
	v_cndmask_b32_e32 v41, v197, v41, vcc
	v_mul_f32_e32 v42, v42, v38
	v_mul_f32_e32 v43, v43, v38
	v_fma_f32 v10, v10, 2.0, -v42
	v_fma_f32 v11, v11, 2.0, -v43
	v_cmp_lt_f32_e64 vcc, |v47|, 4.0
	v_and_b32_e32 v39, 0x7fffffff, v47
	v_sub_u32_e32 v42, 0x7f000000, v41
	v_mul_f32_e64 v34, |v46|, v42
	v_cndmask_b32_e32 v42, 0.5, v185, vcc
	v_cmp_nlt_f32_e64 vcc, |v47|, 2.0
	v_rndne_f32_e32 v34, v34
	v_mul_f32_e32 v34, v41, v34
	v_cndmask_b32_e32 v42, v197, v42, vcc
	v_min_f32_e32 v34, 0x40f00000, v34
	v_sub_u32_e32 v41, 0x7f000000, v42
	v_mul_f32_e64 v39, |v47|, v41
	v_rndne_f32_e32 v39, v39
	v_mul_f32_e32 v44, v12, v40
	v_mul_f32_e32 v45, v13, v40
	v_mul_f32_e32 v39, v42, v39
	v_cmp_lt_f32_e64 vcc, |v44|, 4.0
	v_min_f32_e32 v39, 0x40f00000, v39
	v_bfi_b32 v43, s22, v39, v47
	v_cndmask_b32_e32 v41, 0.5, v185, vcc
	v_cmp_nlt_f32_e64 vcc, |v44|, 2.0
	v_and_b32_e32 v39, 0x7fffffff, v44
	v_bfi_b32 v42, s22, v34, v46
	v_cndmask_b32_e32 v41, v197, v41, vcc
	v_mul_f32_e32 v42, v42, v38
	v_mul_f32_e32 v43, v43, v38
	v_fma_f32 v28, v28, 2.0, -v42
	v_fma_f32 v29, v29, 2.0, -v43
	v_cmp_lt_f32_e64 vcc, |v45|, 4.0
	v_and_b32_e32 v39, 0x7fffffff, v45
	v_sub_u32_e32 v42, 0x7f000000, v41
	v_mul_f32_e64 v34, |v44|, v42
	v_cndmask_b32_e32 v42, 0.5, v185, vcc
	v_cmp_nlt_f32_e64 vcc, |v45|, 2.0
	v_rndne_f32_e32 v34, v34
	v_mul_f32_e32 v34, v41, v34
	v_cndmask_b32_e32 v42, v197, v42, vcc
	v_min_f32_e32 v34, 0x40f00000, v34
	v_sub_u32_e32 v41, 0x7f000000, v42
	v_mul_f32_e64 v39, |v45|, v41
	v_rndne_f32_e32 v39, v39
	v_mul_f32_e32 v46, v30, v40
	v_mul_f32_e32 v47, v31, v40
	v_mul_f32_e32 v39, v42, v39
	v_cmp_lt_f32_e64 vcc, |v46|, 4.0
	v_min_f32_e32 v39, 0x40f00000, v39
	v_bfi_b32 v43, s22, v39, v45
	v_cndmask_b32_e32 v41, 0.5, v185, vcc
	v_cmp_nlt_f32_e64 vcc, |v46|, 2.0
	v_and_b32_e32 v39, 0x7fffffff, v46
	v_bfi_b32 v42, s22, v34, v44
	v_cndmask_b32_e32 v41, v197, v41, vcc
	v_mul_f32_e32 v42, v42, v38
	v_mul_f32_e32 v43, v43, v38
	v_fma_f32 v12, v12, 2.0, -v42
	v_fma_f32 v13, v13, 2.0, -v43
	v_cmp_lt_f32_e64 vcc, |v47|, 4.0
	v_and_b32_e32 v39, 0x7fffffff, v47
	v_sub_u32_e32 v42, 0x7f000000, v41
	v_mul_f32_e64 v34, |v46|, v42
	v_cndmask_b32_e32 v42, 0.5, v185, vcc
	v_cmp_nlt_f32_e64 vcc, |v47|, 2.0
	v_rndne_f32_e32 v34, v34
	v_mul_f32_e32 v34, v41, v34
	v_cndmask_b32_e32 v42, v197, v42, vcc
	v_min_f32_e32 v34, 0x40f00000, v34
	v_sub_u32_e32 v41, 0x7f000000, v42
	v_mul_f32_e64 v39, |v47|, v41
	v_rndne_f32_e32 v39, v39
	v_mul_f32_e32 v44, v14, v40
	v_mul_f32_e32 v45, v15, v40
	v_mul_f32_e32 v39, v42, v39
	v_cmp_lt_f32_e64 vcc, |v44|, 4.0
	v_min_f32_e32 v39, 0x40f00000, v39
	v_bfi_b32 v43, s22, v39, v47
	v_cndmask_b32_e32 v41, 0.5, v185, vcc
	v_cmp_nlt_f32_e64 vcc, |v44|, 2.0
	v_and_b32_e32 v39, 0x7fffffff, v44
	v_bfi_b32 v42, s22, v34, v46
	v_cndmask_b32_e32 v41, v197, v41, vcc
	v_mul_f32_e32 v42, v42, v38
	v_mul_f32_e32 v43, v43, v38
	v_fma_f32 v30, v30, 2.0, -v42
	v_fma_f32 v31, v31, 2.0, -v43
	v_cmp_lt_f32_e64 vcc, |v45|, 4.0
	v_and_b32_e32 v39, 0x7fffffff, v45
	v_sub_u32_e32 v42, 0x7f000000, v41
	v_mul_f32_e64 v34, |v44|, v42
	v_cndmask_b32_e32 v42, 0.5, v185, vcc
	v_cmp_nlt_f32_e64 vcc, |v45|, 2.0
	v_rndne_f32_e32 v34, v34
	v_mul_f32_e32 v34, v41, v34
	v_cndmask_b32_e32 v42, v197, v42, vcc
	v_min_f32_e32 v34, 0x40f00000, v34
	v_sub_u32_e32 v41, 0x7f000000, v42
	v_mul_f32_e64 v39, |v45|, v41
	v_rndne_f32_e32 v39, v39
	v_mul_f32_e32 v46, v32, v40
	v_mul_f32_e32 v47, v33, v40
	v_mul_f32_e32 v39, v42, v39
	v_cmp_lt_f32_e64 vcc, |v46|, 4.0
	v_min_f32_e32 v39, 0x40f00000, v39
	v_bfi_b32 v43, s22, v39, v45
	v_cndmask_b32_e32 v41, 0.5, v185, vcc
	v_cmp_nlt_f32_e64 vcc, |v46|, 2.0
	v_and_b32_e32 v39, 0x7fffffff, v46
	v_bfi_b32 v42, s22, v34, v44
	v_cndmask_b32_e32 v41, v197, v41, vcc
	v_mul_f32_e32 v42, v42, v38
	v_mul_f32_e32 v43, v43, v38
	v_fma_f32 v14, v14, 2.0, -v42
	v_fma_f32 v15, v15, 2.0, -v43
	v_cmp_lt_f32_e64 vcc, |v47|, 4.0
	v_and_b32_e32 v39, 0x7fffffff, v47
	v_sub_u32_e32 v42, 0x7f000000, v41
	v_mul_f32_e64 v34, |v46|, v42
	v_cndmask_b32_e32 v42, 0.5, v185, vcc
	v_cmp_nlt_f32_e64 vcc, |v47|, 2.0
	v_rndne_f32_e32 v34, v34
	v_mul_f32_e32 v34, v41, v34
	v_cndmask_b32_e32 v42, v197, v42, vcc
	v_min_f32_e32 v34, 0x40f00000, v34
	v_sub_u32_e32 v41, 0x7f000000, v42
	v_mul_f32_e64 v39, |v47|, v41
	v_rndne_f32_e32 v39, v39
	v_mul_f32_e32 v39, v42, v39
	v_min_f32_e32 v39, 0x40f00000, v39
	v_bfi_b32 v41, s22, v39, v47
	v_mul_f32_e32 v42, v16, v40
	v_mul_f32_e32 v43, v17, v40
	s_nop 0
	v_cmp_lt_f32_e64 vcc, |v42|, 4.0
	v_and_b32_e32 v39, 0x7fffffff, v42
	s_nop 0
	v_cndmask_b32_e32 v40, 0.5, v185, vcc
	v_cmp_nlt_f32_e64 vcc, |v42|, 2.0
	s_nop 1
	v_cndmask_b32_e32 v44, v197, v40, vcc
	v_bfi_b32 v40, s22, v34, v46
	v_mul_f32_e32 v40, v40, v38
	v_mul_f32_e32 v41, v41, v38
	v_fma_f32 v32, v32, 2.0, -v40
	v_fma_f32 v33, v33, 2.0, -v41
	v_cmp_lt_f32_e64 vcc, |v43|, 4.0
	v_and_b32_e32 v39, 0x7fffffff, v43
	v_sub_u32_e32 v40, 0x7f000000, v44
	v_mul_f32_e64 v34, |v42|, v40
	v_cndmask_b32_e32 v40, 0.5, v185, vcc
	v_cmp_nlt_f32_e64 vcc, |v43|, 2.0
	v_rndne_f32_e32 v34, v34
	v_mul_f32_e32 v34, v44, v34
	v_cndmask_b32_e32 v40, v197, v40, vcc
	v_min_f32_e32 v34, 0x40f00000, v34
	v_sub_u32_e32 v41, 0x7f000000, v40
	v_mul_f32_e64 v39, |v43|, v41
	v_rndne_f32_e32 v39, v39
	v_mul_f32_e32 v39, v40, v39
	v_min_f32_e32 v39, 0x40f00000, v39
	v_bfi_b32 v41, s22, v39, v43
	v_bfi_b32 v40, s22, v34, v42
	v_mul_f32_e32 v39, v41, v38
	v_mul_f32_e32 v38, v40, v38
	v_max_f32_e64 v34, |v18|, |v2|
	v_fma_f32 v16, v16, 2.0, -v38
	v_fma_f32 v17, v17, 2.0, -v39
	v_max_f32_e64 v38, |v19|, |v3|
	v_max3_f32 v34, v34, 0, v38
	v_max_f32_e64 v38, |v20|, |v4|
	v_max_f32_e64 v39, |v21|, |v5|
	v_max3_f32 v34, v34, v38, v39
	v_max_f32_e64 v38, |v22|, |v6|
	v_max_f32_e64 v39, |v23|, |v7|
	v_max3_f32 v34, v34, v38, v39
	v_max_f32_e64 v38, |v24|, |v8|
	v_max_f32_e64 v39, |v25|, |v9|
	v_max3_f32 v34, v34, v38, v39
	v_max_f32_e64 v38, |v26|, |v10|
	v_max_f32_e64 v39, |v27|, |v11|
	v_max3_f32 v34, v34, v38, v39
	v_max_f32_e64 v38, |v28|, |v12|
	v_max_f32_e64 v39, |v29|, |v13|
	v_max3_f32 v34, v34, v38, v39
	v_max_f32_e64 v38, |v30|, |v14|
	v_max_f32_e64 v39, |v31|, |v15|
	v_max3_f32 v34, v34, v38, v39
	v_max_f32_e64 v38, |v32|, |v16|
	v_max_f32_e64 v39, |v33|, |v17|
	v_max3_f32 v34, v34, v38, v39
	v_bfe_u32 v38, v34, 23, 8
	v_and_b32_e32 v34, 0x7fffff, v34
	v_cmp_gt_u32_e32 vcc, s11, v34
	s_nop 1
	v_cndmask_b32_e64 v34, -2, -3, vcc
	v_add3_u32 v34, v38, v34, s0
	v_max_i32_e32 v34, 0xffffff88, v34
	v_add_u32_e32 v34, 0x7f, v34
	v_lshlrev_b32_e32 v44, 23, v34
	v_cvt_scalef32_2xpk16_fp6_f32 v[38:43], v[18:33], v[2:17], v44
	v_lshl_add_u64 v[2:3], v[36:37], 0, v[102:103]
	v_mul_lo_u32 v34, v34, s1
	v_lshl_add_u64 v[2:3], v[2:3], 0, v[100:101]
	v_mov_b32_e32 v32, v42
	v_mov_b32_e32 v33, v43
	global_store_dwordx4 v[2:3], v[38:41], off offset:256
	global_store_dwordx4 v[2:3], v[32:35], off offset:272
	s_or_b64 exec, exec, s[6:7]
	s_cmp_eq_u32 s88, s93
	s_mov_b64 s[4:5], -1
	s_cbranch_scc1 .LBB0_566

.LBB0_631:
	v_mov_b32_e32 v136, v0
	s_lshl_b32 s9, s6, 8
	v_readlane_b32 s6, v254, 48
	s_add_i32 s9, s9, s6
	v_and_b32_e32 v34, 15, v136
	v_or_b32_e32 v146, s9, v34
	v_ashrrev_i32_e32 v147, 31, v146
	v_lshlrev_b64 v[138:139], 5, v[146:147]
	v_lshl_add_u64 v[144:145], s[20:21], 0, v[138:139]
	global_load_dwordx4 v[138:141], v[144:145], off
	global_load_dwordx4 v[156:159], v[144:145], off offset:16
	s_lshl_b32 s90, s7, 7
	v_bfe_u32 v155, v136, 4, 2
	v_lshl_or_b32 v136, v155, 3, s90
	v_or_b32_e32 v136, s30, v136
	v_ashrrev_i32_e32 v137, 31, v136
	v_lshlrev_b64 v[136:137], 14, v[136:137]
	v_or_b32_e32 v148, 16, v146
	v_ashrrev_i32_e32 v149, 31, v148
	v_lshlrev_b64 v[148:149], 5, v[148:149]
	v_lshl_add_u64 v[148:149], s[20:21], 0, v[148:149]
	v_permlane32_swap_b32_e32 v2, v18
	v_permlane32_swap_b32_e32 v3, v19
	v_permlane32_swap_b32_e32 v10, v26
	v_permlane32_swap_b32_e32 v11, v27
	v_permlane32_swap_b32_e32 v4, v20
	v_permlane32_swap_b32_e32 v5, v21
	v_permlane32_swap_b32_e32 v6, v22
	v_permlane32_swap_b32_e32 v7, v23
	v_permlane32_swap_b32_e32 v8, v24
	v_permlane32_swap_b32_e32 v9, v25
	v_permlane32_swap_b32_e32 v12, v28
	v_permlane32_swap_b32_e32 v13, v29
	v_permlane32_swap_b32_e32 v14, v30
	v_permlane32_swap_b32_e32 v15, v31
	v_permlane32_swap_b32_e32 v16, v32
	v_permlane32_swap_b32_e32 v17, v33
	v_permlane16_swap_b32_e32 v2, v10
	v_permlane16_swap_b32_e32 v3, v11
	v_permlane16_swap_b32_e32 v18, v26
	v_permlane16_swap_b32_e32 v19, v27
	v_permlane16_swap_b32_e32 v4, v12
	v_permlane16_swap_b32_e32 v5, v13
	v_permlane16_swap_b32_e32 v6, v14
	v_permlane16_swap_b32_e32 v7, v15
	v_permlane16_swap_b32_e32 v8, v16
	v_permlane16_swap_b32_e32 v9, v17
	v_permlane16_swap_b32_e32 v20, v28
	v_permlane16_swap_b32_e32 v21, v29
	v_permlane16_swap_b32_e32 v22, v30
	v_permlane16_swap_b32_e32 v23, v31
	v_permlane16_swap_b32_e32 v24, v32
	v_permlane16_swap_b32_e32 v25, v33
	s_ashr_i32 s91, s90, 31
	v_permlane32_swap_b32_e32 v36, v40
	v_permlane32_swap_b32_e32 v37, v41
	s_waitcnt vmcnt(0)
	v_add_f32_e32 v140, v140, v158
	v_add_f32_e32 v141, v141, v159
	v_add_f32_e32 v138, v138, v156
	v_add_f32_e32 v139, v139, v157
	v_permlane32_swap_b32_e32 v38, v42
	v_pk_mov_b32 v[142:143], v[138:139], v[140:141] op_sel:[1,0]
	v_mov_b32_e32 v139, v141
	v_add_f32_e32 v138, v142, v138
	v_add_f32_e32 v139, v143, v139
	v_permlane32_swap_b32_e32 v39, v43
	v_add_f32_e32 v138, v138, v139
	v_fmamk_f32 v138, v138, 0x3b800000, v153
	v_cmp_gt_f32_e32 vcc, s24, v138
	v_mul_f32_e32 v139, 0x4f800000, v138
	v_permlane32_swap_b32_e32 v44, v48
	v_cndmask_b32_e32 v138, v138, v139, vcc
	v_sqrt_f32_e32 v139, v138
	v_permlane32_swap_b32_e32 v45, v49
	v_permlane32_swap_b32_e32 v46, v50
	v_add_u32_e32 v140, -1, v139
	v_fma_f32 v141, -v140, v139, v138
	v_cmp_ge_f32_e64 s[6:7], 0, v141
	v_add_u32_e32 v141, 1, v139
	v_permlane32_swap_b32_e32 v47, v51
	v_cndmask_b32_e64 v140, v139, v140, s[6:7]
	v_fma_f32 v139, -v141, v139, v138
	v_cmp_lt_f32_e64 s[6:7], 0, v139
	v_permlane32_swap_b32_e32 v52, v56
	s_nop 0
	v_cndmask_b32_e64 v139, v140, v141, s[6:7]
	v_mul_f32_e32 v140, 0x37800000, v139
	v_cndmask_b32_e32 v139, v139, v140, vcc
	v_cmp_class_f32_e32 vcc, v138, v154
	v_permlane32_swap_b32_e32 v53, v57
	s_nop 0
	v_cndmask_b32_e32 v138, v139, v138, vcc
	v_div_scale_f32 v139, s[6:7], v138, v138, 1.0
	v_rcp_f32_e32 v140, v139
	s_mov_b32 s6, 0x10000
	v_permlane32_swap_b32_e32 v54, v58
	v_fma_f32 v141, -v139, v140, 1.0
	v_fmac_f32_e32 v140, v141, v140
	v_div_scale_f32 v141, vcc, 1.0, v138, 1.0
	v_mul_f32_e32 v142, v141, v140
	v_fma_f32 v143, -v139, v142, v141
	v_fmac_f32_e32 v142, v143, v140
	v_fma_f32 v139, -v139, v142, v141
	v_div_fmas_f32 v139, v139, v140, v142
	v_div_fixup_f32 v138, v139, v138, 1.0
	v_mul_f32_e32 v124, v124, v138
	v_mul_f32_e32 v125, v125, v138
	v_mov_b32_e32 v140, 0
	v_cvt_pk_fp8_f32 v140, v124, v125
	v_mul_f32_e32 v128, v128, v138
	v_mul_f32_e32 v129, v129, v138
	v_mov_b32_e32 v142, 0
	v_cvt_pk_fp8_f32 v142, v128, v129
	v_mul_f32_e32 v126, v126, v138
	v_mul_f32_e32 v127, v127, v138
	v_lshl_add_u64 v[124:125], s[22:23], 0, v[136:137]
	v_cvt_pk_fp8_f32 v140, v126, v127 op_sel:[0,0,1]
	v_lshl_add_u64 v[124:125], v[124:125], 0, v[146:147]
	v_mul_f32_e32 v130, v130, v138
	v_mul_f32_e32 v131, v131, v138
	v_add_co_u32_e32 v126, vcc, s6, v124
	v_cvt_pk_fp8_f32 v142, v130, v131 op_sel:[0,0,1]
	s_nop 0
	v_addc_co_u32_e32 v127, vcc, 0, v125, vcc
	s_movk_i32 s6, 0x4000
	v_add_co_u32_e32 v128, vcc, s6, v124
	v_lshrrev_b32_e32 v130, 8, v140
	s_nop 0
	v_addc_co_u32_e32 v129, vcc, 0, v125, vcc
	s_mov_b32 s6, 0x14000
	global_store_byte v[128:129], v130, off
	v_add_co_u32_e32 v130, vcc, s6, v124
	v_lshrrev_b32_e32 v136, 8, v142
	s_nop 0
	v_addc_co_u32_e32 v131, vcc, 0, v125, vcc
	s_mov_b32 s6, 0x8000
	global_store_byte v[130:131], v136, off
	v_add_co_u32_e32 v136, vcc, s6, v124
	s_mov_b32 s6, 0x18000
	s_nop 0
	v_addc_co_u32_e32 v137, vcc, 0, v125, vcc
	v_add_co_u32_e32 v138, vcc, s6, v124
	s_mov_b32 s6, 0xc000
	s_nop 0
	v_addc_co_u32_e32 v139, vcc, 0, v125, vcc
	global_store_byte v[124:125], v140, off
	global_store_byte_d16_hi v[136:137], v140, off
	v_lshrrev_b32_e32 v143, 24, v140
	v_add_co_u32_e32 v140, vcc, s6, v124
	s_mov_b32 s6, 0x1c000
	s_nop 0
	v_addc_co_u32_e32 v141, vcc, 0, v125, vcc
	global_store_byte v[126:127], v142, off
	global_store_byte_d16_hi v[138:139], v142, off
	v_lshrrev_b32_e32 v147, 24, v142
	v_add_co_u32_e32 v142, vcc, s6, v124
	global_store_byte v[140:141], v143, off
	s_nop 0
	v_addc_co_u32_e32 v143, vcc, 0, v125, vcc
	global_store_byte v[142:143], v147, off
	global_load_dwordx4 v[156:159], v[148:149], off
	global_load_dwordx4 v[160:163], v[148:149], off offset:16
	v_permlane32_swap_b32_e32 v55, v59
	v_permlane32_swap_b32_e32 v60, v64
	v_permlane32_swap_b32_e32 v61, v65
	v_permlane32_swap_b32_e32 v62, v66
	v_permlane32_swap_b32_e32 v63, v67
	v_permlane16_swap_b32_e32 v36, v52
	v_permlane16_swap_b32_e32 v37, v53
	v_permlane16_swap_b32_e32 v38, v54
	v_permlane16_swap_b32_e32 v39, v55
	v_permlane16_swap_b32_e32 v44, v60
	v_permlane16_swap_b32_e32 v45, v61
	v_permlane16_swap_b32_e32 v46, v62
	v_permlane16_swap_b32_e32 v47, v63
	v_permlane16_swap_b32_e32 v40, v56
	v_permlane16_swap_b32_e32 v41, v57
	v_permlane16_swap_b32_e32 v42, v58
	v_permlane16_swap_b32_e32 v43, v59
	v_permlane16_swap_b32_e32 v48, v64
	v_permlane16_swap_b32_e32 v49, v65
	v_permlane16_swap_b32_e32 v50, v66
	v_permlane16_swap_b32_e32 v51, v67
	s_cmp_eq_u32 s0, s50
	v_readlane_b32 s96, v254, 46
	v_readlane_b32 s97, v254, 47
	s_waitcnt vmcnt(0)
	v_add_f32_e32 v148, v158, v162
	v_add_f32_e32 v149, v159, v163
	v_add_f32_e32 v156, v156, v160
	v_add_f32_e32 v157, v157, v161
	s_nop 0
	v_pk_mov_b32 v[158:159], v[156:157], v[148:149] op_sel:[1,0]
	v_mov_b32_e32 v157, v149
	v_add_f32_e32 v148, v158, v156
	v_add_f32_e32 v149, v159, v157
	s_nop 0
	v_add_f32_e32 v147, v148, v149
	v_fmamk_f32 v147, v147, 0x3b800000, v153
	v_cmp_gt_f32_e32 vcc, s24, v147
	v_mul_f32_e32 v148, 0x4f800000, v147
	s_nop 0
	v_cndmask_b32_e32 v147, v147, v148, vcc
	v_sqrt_f32_e32 v148, v147
	s_nop 0
	v_add_u32_e32 v149, -1, v148
	v_fma_f32 v156, -v149, v148, v147
	v_cmp_ge_f32_e64 s[6:7], 0, v156
	v_add_u32_e32 v156, 1, v148
	s_nop 0
	v_cndmask_b32_e64 v149, v148, v149, s[6:7]
	v_fma_f32 v148, -v156, v148, v147
	v_cmp_lt_f32_e64 s[6:7], 0, v148
	s_nop 1
	v_cndmask_b32_e64 v148, v149, v156, s[6:7]
	v_mul_f32_e32 v149, 0x37800000, v148
	v_cndmask_b32_e32 v148, v148, v149, vcc
	v_cmp_class_f32_e32 vcc, v147, v154
	s_nop 1
	v_cndmask_b32_e32 v147, v148, v147, vcc
	v_div_scale_f32 v148, s[6:7], v147, v147, 1.0
	v_rcp_f32_e32 v149, v148
	s_nop 0
	v_fma_f32 v156, -v148, v149, 1.0
	v_fmac_f32_e32 v149, v156, v149
	v_div_scale_f32 v156, vcc, 1.0, v147, 1.0
	v_mul_f32_e32 v157, v156, v149
	v_fma_f32 v158, -v148, v157, v156
	v_fmac_f32_e32 v157, v158, v149
	v_fma_f32 v148, -v148, v157, v156
	v_div_fmas_f32 v148, v148, v149, v157
	v_div_fixup_f32 v148, v148, v147, 1.0
	v_mul_f32_e32 v116, v116, v148
	v_mul_f32_e32 v117, v117, v148
	v_mov_b32_e32 v147, 0
	v_mul_f32_e32 v120, v120, v148
	v_mul_f32_e32 v121, v121, v148
	v_cvt_pk_fp8_f32 v147, v116, v117
	v_mov_b32_e32 v116, 0
	v_cvt_pk_fp8_f32 v116, v120, v121
	v_mul_f32_e32 v118, v118, v148
	v_mul_f32_e32 v119, v119, v148
	v_mul_f32_e32 v122, v122, v148
	v_mul_f32_e32 v123, v123, v148
	v_cvt_pk_fp8_f32 v147, v118, v119 op_sel:[0,0,1]
	v_cvt_pk_fp8_f32 v116, v122, v123 op_sel:[0,0,1]
	global_store_byte v[124:125], v147, off offset:16
	global_store_byte v[126:127], v116, off offset:16
	v_lshrrev_b32_e32 v117, 8, v147
	global_store_byte v[128:129], v117, off offset:16
	v_lshrrev_b32_e32 v117, 8, v116
	global_store_byte v[130:131], v117, off offset:16
	global_store_byte_d16_hi v[136:137], v147, off offset:16
	global_store_byte_d16_hi v[138:139], v116, off offset:16
	v_lshrrev_b32_e32 v116, 24, v116
	v_lshrrev_b32_e32 v117, 24, v147
	global_store_byte v[142:143], v116, off offset:16
	v_or_b32_e32 v116, 32, v146
	global_store_byte v[140:141], v117, off offset:16
	v_ashrrev_i32_e32 v117, 31, v116
	v_lshlrev_b64 v[116:117], 5, v[116:117]
	v_lshl_add_u64 v[120:121], s[20:21], 0, v[116:117]
	global_load_dwordx4 v[116:119], v[120:121], off
	s_nop 0
	global_load_dwordx4 v[120:123], v[120:121], off offset:16
	s_waitcnt vmcnt(0)
	v_add_f32_e32 v118, v118, v122
	v_add_f32_e32 v119, v119, v123
	v_add_f32_e32 v116, v116, v120
	v_add_f32_e32 v117, v117, v121
	s_nop 0
	v_pk_mov_b32 v[120:121], v[116:117], v[118:119] op_sel:[1,0]
	v_mov_b32_e32 v117, v119
	v_add_f32_e32 v116, v120, v116
	v_add_f32_e32 v117, v121, v117
	s_nop 0
	v_add_f32_e32 v116, v116, v117
	v_fmamk_f32 v116, v116, 0x3b800000, v153
	v_cmp_gt_f32_e32 vcc, s24, v116
	v_mul_f32_e32 v117, 0x4f800000, v116
	s_nop 0
	v_cndmask_b32_e32 v116, v116, v117, vcc
	v_sqrt_f32_e32 v117, v116
	s_nop 0
	v_add_u32_e32 v118, -1, v117
	v_fma_f32 v119, -v118, v117, v116
	v_cmp_ge_f32_e64 s[6:7], 0, v119
	v_add_u32_e32 v119, 1, v117
	s_nop 0
	v_cndmask_b32_e64 v118, v117, v118, s[6:7]
	v_fma_f32 v117, -v119, v117, v116
	v_cmp_lt_f32_e64 s[6:7], 0, v117
	s_nop 1
	v_cndmask_b32_e64 v117, v118, v119, s[6:7]
	v_mul_f32_e32 v118, 0x37800000, v117
	v_cndmask_b32_e32 v117, v117, v118, vcc
	v_cmp_class_f32_e32 vcc, v116, v154
	s_nop 1
	v_cndmask_b32_e32 v116, v117, v116, vcc
	v_div_scale_f32 v117, s[6:7], v116, v116, 1.0
	v_rcp_f32_e32 v118, v117
	s_nop 0
	v_fma_f32 v119, -v117, v118, 1.0
	v_fmac_f32_e32 v118, v119, v118
	v_div_scale_f32 v119, vcc, 1.0, v116, 1.0
	v_mul_f32_e32 v120, v119, v118
	v_fma_f32 v121, -v117, v120, v119
	v_fmac_f32_e32 v120, v121, v118
	v_fma_f32 v117, -v117, v120, v119
	v_div_fmas_f32 v117, v117, v118, v120
	v_div_fixup_f32 v116, v117, v116, 1.0
	v_mul_f32_e32 v110, v110, v116
	v_mul_f32_e32 v111, v111, v116
	v_mul_f32_e32 v108, v108, v116
	v_mul_f32_e32 v109, v109, v116
	v_mul_f32_e32 v114, v114, v116
	v_mul_f32_e32 v115, v115, v116
	v_mul_f32_e32 v112, v112, v116
	v_mul_f32_e32 v113, v113, v116
	v_mov_b32_e32 v116, 0
	v_cvt_pk_fp8_f32 v116, v108, v109
	v_mov_b32_e32 v108, 0
	v_cvt_pk_fp8_f32 v108, v112, v113
	v_cvt_pk_fp8_f32 v116, v110, v111 op_sel:[0,0,1]
	v_cvt_pk_fp8_f32 v108, v114, v115 op_sel:[0,0,1]
	global_store_byte v[124:125], v116, off offset:32
	global_store_byte v[126:127], v108, off offset:32
	v_lshrrev_b32_e32 v109, 8, v116
	global_store_byte v[128:129], v109, off offset:32
	v_lshrrev_b32_e32 v109, 8, v108
	global_store_byte v[130:131], v109, off offset:32
	global_store_byte_d16_hi v[136:137], v116, off offset:32
	global_store_byte_d16_hi v[138:139], v108, off offset:32
	v_lshrrev_b32_e32 v108, 24, v108
	v_lshrrev_b32_e32 v109, 24, v116
	global_store_byte v[142:143], v108, off offset:32
	v_or_b32_e32 v108, 48, v146
	global_store_byte v[140:141], v109, off offset:32
	v_ashrrev_i32_e32 v109, 31, v108
	v_lshlrev_b64 v[108:109], 5, v[108:109]
	v_lshl_add_u64 v[112:113], s[20:21], 0, v[108:109]
	global_load_dwordx4 v[108:111], v[112:113], off
	s_nop 0
	global_load_dwordx4 v[112:115], v[112:113], off offset:16
	s_waitcnt vmcnt(0)
	v_add_f32_e32 v110, v110, v114
	v_add_f32_e32 v111, v111, v115
	v_add_f32_e32 v108, v108, v112
	v_add_f32_e32 v109, v109, v113
	s_nop 0
	v_pk_mov_b32 v[112:113], v[108:109], v[110:111] op_sel:[1,0]
	v_mov_b32_e32 v109, v111
	v_add_f32_e32 v108, v112, v108
	v_add_f32_e32 v109, v113, v109
	s_nop 0
	v_add_f32_e32 v108, v108, v109
	v_fmamk_f32 v108, v108, 0x3b800000, v153
	v_cmp_gt_f32_e32 vcc, s24, v108
	v_mul_f32_e32 v109, 0x4f800000, v108
	s_nop 0
	v_cndmask_b32_e32 v108, v108, v109, vcc
	v_sqrt_f32_e32 v109, v108
	s_nop 0
	v_add_u32_e32 v110, -1, v109
	v_fma_f32 v111, -v110, v109, v108
	v_cmp_ge_f32_e64 s[6:7], 0, v111
	v_add_u32_e32 v111, 1, v109
	s_nop 0
	v_cndmask_b32_e64 v110, v109, v110, s[6:7]
	v_fma_f32 v109, -v111, v109, v108
	v_cmp_lt_f32_e64 s[6:7], 0, v109
	s_nop 1
	v_cndmask_b32_e64 v109, v110, v111, s[6:7]
	v_mul_f32_e32 v110, 0x37800000, v109
	v_cndmask_b32_e32 v109, v109, v110, vcc
	v_cmp_class_f32_e32 vcc, v108, v154
	s_nop 1
	v_cndmask_b32_e32 v108, v109, v108, vcc
	v_div_scale_f32 v109, s[6:7], v108, v108, 1.0
	v_rcp_f32_e32 v110, v109
	s_mov_b64 s[6:7], 0x1000
	v_fma_f32 v111, -v109, v110, 1.0
	v_fmac_f32_e32 v110, v111, v110
	v_div_scale_f32 v111, vcc, 1.0, v108, 1.0
	v_mul_f32_e32 v112, v111, v110
	v_fma_f32 v113, -v109, v112, v111
	v_fmac_f32_e32 v112, v113, v110
	v_fma_f32 v109, -v109, v112, v111
	v_div_fmas_f32 v109, v109, v110, v112
	v_div_fixup_f32 v108, v109, v108, 1.0
	v_mul_f32_e32 v102, v102, v108
	v_mul_f32_e32 v103, v103, v108
	v_mul_f32_e32 v100, v100, v108
	v_mul_f32_e32 v101, v101, v108
	v_mul_f32_e32 v106, v106, v108
	v_mul_f32_e32 v107, v107, v108
	v_mul_f32_e32 v104, v104, v108
	v_mul_f32_e32 v105, v105, v108
	v_mov_b32_e32 v108, 0
	v_cvt_pk_fp8_f32 v108, v100, v101
	v_mov_b32_e32 v100, 0
	v_cvt_pk_fp8_f32 v100, v104, v105
	v_cvt_pk_fp8_f32 v108, v102, v103 op_sel:[0,0,1]
	v_cvt_pk_fp8_f32 v100, v106, v107 op_sel:[0,0,1]
	global_store_byte v[124:125], v108, off offset:48
	global_store_byte v[126:127], v100, off offset:48
	v_lshrrev_b32_e32 v101, 8, v108
	global_store_byte v[128:129], v101, off offset:48
	v_lshrrev_b32_e32 v101, 8, v100
	global_store_byte v[130:131], v101, off offset:48
	global_store_byte_d16_hi v[136:137], v108, off offset:48
	global_store_byte_d16_hi v[138:139], v100, off offset:48
	v_lshrrev_b32_e32 v100, 24, v100
	v_lshl_add_u64 v[106:107], v[144:145], 0, s[6:7]
	s_movk_i32 s6, 0x1000
	v_lshrrev_b32_e32 v101, 24, v108
	global_store_byte v[142:143], v100, off offset:48
	v_add_co_u32_e32 v100, vcc, s6, v144
	global_store_byte v[140:141], v101, off offset:48
	s_nop 0
	v_addc_co_u32_e32 v101, vcc, 0, v145, vcc
	global_load_dwordx4 v[102:105], v[100:101], off
	s_nop 0
	global_load_dwordx4 v[106:109], v[106:107], off offset:16
	s_waitcnt vmcnt(0)
	v_add_f32_e32 v104, v104, v108
	v_add_f32_e32 v105, v105, v109
	v_add_f32_e32 v102, v102, v106
	v_add_f32_e32 v103, v103, v107
	s_nop 0
	v_pk_mov_b32 v[106:107], v[102:103], v[104:105] op_sel:[1,0]
	v_mov_b32_e32 v103, v105
	v_add_f32_e32 v102, v106, v102
	v_add_f32_e32 v103, v107, v103
	s_nop 0
	v_add_f32_e32 v102, v102, v103
	v_fmamk_f32 v102, v102, 0x3b800000, v153
	v_cmp_gt_f32_e32 vcc, s24, v102
	v_mul_f32_e32 v103, 0x4f800000, v102
	s_nop 0
	v_cndmask_b32_e32 v102, v102, v103, vcc
	v_sqrt_f32_e32 v103, v102
	s_nop 0
	v_add_u32_e32 v104, -1, v103
	v_fma_f32 v105, -v104, v103, v102
	v_cmp_ge_f32_e64 s[6:7], 0, v105
	v_add_u32_e32 v105, 1, v103
	s_nop 0
	v_cndmask_b32_e64 v104, v103, v104, s[6:7]
	v_fma_f32 v103, -v105, v103, v102
	v_cmp_lt_f32_e64 s[6:7], 0, v103
	s_nop 1
	v_cndmask_b32_e64 v103, v104, v105, s[6:7]
	v_mul_f32_e32 v104, 0x37800000, v103
	v_cndmask_b32_e32 v103, v103, v104, vcc
	v_cmp_class_f32_e32 vcc, v102, v154
	s_nop 1
	v_cndmask_b32_e32 v102, v103, v102, vcc
	v_div_scale_f32 v103, s[6:7], v102, v102, 1.0
	v_rcp_f32_e32 v104, v103
	s_mov_b64 s[6:7], 0x1200
	v_fma_f32 v105, -v103, v104, 1.0
	v_fmac_f32_e32 v104, v105, v104
	v_div_scale_f32 v105, vcc, 1.0, v102, 1.0
	v_mul_f32_e32 v106, v105, v104
	v_fma_f32 v107, -v103, v106, v105
	v_fmac_f32_e32 v106, v107, v104
	v_fma_f32 v103, -v103, v106, v105
	v_div_fmas_f32 v103, v103, v104, v106
	v_div_fixup_f32 v102, v103, v102, 1.0
	v_mul_f32_e32 v104, v92, v102
	v_mul_f32_e32 v105, v93, v102
	v_mul_f32_e32 v92, v98, v102
	v_mul_f32_e32 v93, v99, v102
	v_mov_b32_e32 v98, 0
	v_cvt_pk_fp8_f32 v98, v104, v105
	v_mul_f32_e32 v94, v94, v102
	v_mul_f32_e32 v95, v95, v102
	v_mul_f32_e32 v96, v96, v102
	v_mul_f32_e32 v97, v97, v102
	v_cvt_pk_fp8_f32 v98, v94, v95 op_sel:[0,0,1]
	v_mov_b32_e32 v94, 0
	v_cvt_pk_fp8_f32 v94, v96, v97
	v_lshl_add_u64 v[96:97], v[144:145], 0, s[6:7]
	v_cvt_pk_fp8_f32 v94, v92, v93 op_sel:[0,0,1]
	v_lshrrev_b32_e32 v92, 8, v98
	global_store_byte v[124:125], v98, off offset:128
	global_store_byte v[126:127], v94, off offset:128
	global_store_byte v[128:129], v92, off offset:128
	v_lshrrev_b32_e32 v92, 8, v94
	global_store_byte v[130:131], v92, off offset:128
	global_store_byte_d16_hi v[136:137], v98, off offset:128
	global_store_byte_d16_hi v[138:139], v94, off offset:128
	v_lshrrev_b32_e32 v92, 24, v98
	global_store_byte v[140:141], v92, off offset:128
	v_lshrrev_b32_e32 v92, 24, v94
	global_store_byte v[142:143], v92, off offset:128
	global_load_dwordx4 v[92:95], v[100:101], off offset:512
	s_nop 0
	global_load_dwordx4 v[96:99], v[96:97], off offset:16
	s_waitcnt vmcnt(0)
	v_add_f32_e32 v94, v94, v98
	v_add_f32_e32 v95, v95, v99
	v_add_f32_e32 v92, v92, v96
	v_add_f32_e32 v93, v93, v97
	s_nop 0
	v_pk_mov_b32 v[96:97], v[92:93], v[94:95] op_sel:[1,0]
	v_mov_b32_e32 v93, v95
	v_add_f32_e32 v92, v96, v92
	v_add_f32_e32 v93, v97, v93
	s_nop 0
	v_add_f32_e32 v92, v92, v93
	v_fmamk_f32 v92, v92, 0x3b800000, v153
	v_cmp_gt_f32_e32 vcc, s24, v92
	v_mul_f32_e32 v93, 0x4f800000, v92
	s_nop 0
	v_cndmask_b32_e32 v92, v92, v93, vcc
	v_sqrt_f32_e32 v93, v92
	s_nop 0
	v_add_u32_e32 v94, -1, v93
	v_fma_f32 v95, -v94, v93, v92
	v_cmp_ge_f32_e64 s[6:7], 0, v95
	v_add_u32_e32 v95, 1, v93
	s_nop 0
	v_cndmask_b32_e64 v94, v93, v94, s[6:7]
	v_fma_f32 v93, -v95, v93, v92
	v_cmp_lt_f32_e64 s[6:7], 0, v93
	s_nop 1
	v_cndmask_b32_e64 v93, v94, v95, s[6:7]
	v_mul_f32_e32 v94, 0x37800000, v93
	v_cndmask_b32_e32 v93, v93, v94, vcc
	v_cmp_class_f32_e32 vcc, v92, v154
	s_nop 1
	v_cndmask_b32_e32 v92, v93, v92, vcc
	v_div_scale_f32 v93, s[6:7], v92, v92, 1.0
	v_rcp_f32_e32 v94, v93
	s_mov_b64 s[6:7], 0x1400
	v_fma_f32 v95, -v93, v94, 1.0
	v_fmac_f32_e32 v94, v95, v94
	v_div_scale_f32 v95, vcc, 1.0, v92, 1.0
	v_mul_f32_e32 v96, v95, v94
	v_fma_f32 v97, -v93, v96, v95
	v_fmac_f32_e32 v96, v97, v94
	v_fma_f32 v93, -v93, v96, v95
	v_div_fmas_f32 v93, v93, v94, v96
	v_div_fixup_f32 v92, v93, v92, 1.0
	v_mul_f32_e32 v94, v84, v92
	v_mul_f32_e32 v95, v85, v92
	v_mul_f32_e32 v84, v90, v92
	v_mul_f32_e32 v85, v91, v92
	v_mov_b32_e32 v90, 0
	v_cvt_pk_fp8_f32 v90, v94, v95
	v_mul_f32_e32 v86, v86, v92
	v_mul_f32_e32 v87, v87, v92
	v_mul_f32_e32 v88, v88, v92
	v_mul_f32_e32 v89, v89, v92
	v_cvt_pk_fp8_f32 v90, v86, v87 op_sel:[0,0,1]
	v_mov_b32_e32 v86, 0
	v_cvt_pk_fp8_f32 v86, v88, v89
	v_lshl_add_u64 v[88:89], v[144:145], 0, s[6:7]
	v_cvt_pk_fp8_f32 v86, v84, v85 op_sel:[0,0,1]
	v_lshrrev_b32_e32 v84, 8, v90
	global_store_byte v[124:125], v90, off offset:144
	global_store_byte v[126:127], v86, off offset:144
	global_store_byte v[128:129], v84, off offset:144
	v_lshrrev_b32_e32 v84, 8, v86
	global_store_byte v[130:131], v84, off offset:144
	global_store_byte_d16_hi v[136:137], v90, off offset:144
	global_store_byte_d16_hi v[138:139], v86, off offset:144
	v_lshrrev_b32_e32 v84, 24, v90
	global_store_byte v[140:141], v84, off offset:144
	v_lshrrev_b32_e32 v84, 24, v86
	global_store_byte v[142:143], v84, off offset:144
	global_load_dwordx4 v[84:87], v[100:101], off offset:1024
	s_nop 0
	global_load_dwordx4 v[88:91], v[88:89], off offset:16
	s_waitcnt vmcnt(0)
	v_add_f32_e32 v86, v86, v90
	v_add_f32_e32 v87, v87, v91
	v_add_f32_e32 v84, v84, v88
	v_add_f32_e32 v85, v85, v89
	s_nop 0
	v_pk_mov_b32 v[88:89], v[84:85], v[86:87] op_sel:[1,0]
	v_mov_b32_e32 v85, v87
	v_add_f32_e32 v84, v88, v84
	v_add_f32_e32 v85, v89, v85
	s_nop 0
	v_add_f32_e32 v84, v84, v85
	v_fmamk_f32 v84, v84, 0x3b800000, v153
	v_cmp_gt_f32_e32 vcc, s24, v84
	v_mul_f32_e32 v85, 0x4f800000, v84
	s_nop 0
	v_cndmask_b32_e32 v84, v84, v85, vcc
	v_sqrt_f32_e32 v85, v84
	s_nop 0
	v_add_u32_e32 v86, -1, v85
	v_fma_f32 v87, -v86, v85, v84
	v_cmp_ge_f32_e64 s[6:7], 0, v87
	v_add_u32_e32 v87, 1, v85
	s_nop 0
	v_cndmask_b32_e64 v86, v85, v86, s[6:7]
	v_fma_f32 v85, -v87, v85, v84
	v_cmp_lt_f32_e64 s[6:7], 0, v85
	s_nop 1
	v_cndmask_b32_e64 v85, v86, v87, s[6:7]
	v_mul_f32_e32 v86, 0x37800000, v85
	v_cndmask_b32_e32 v85, v85, v86, vcc
	v_cmp_class_f32_e32 vcc, v84, v154
	s_nop 1
	v_cndmask_b32_e32 v84, v85, v84, vcc
	v_div_scale_f32 v85, s[6:7], v84, v84, 1.0
	v_rcp_f32_e32 v86, v85
	s_mov_b64 s[6:7], 0x1600
	v_fma_f32 v87, -v85, v86, 1.0
	v_fmac_f32_e32 v86, v87, v86
	v_div_scale_f32 v87, vcc, 1.0, v84, 1.0
	v_mul_f32_e32 v88, v87, v86
	v_fma_f32 v89, -v85, v88, v87
	v_fmac_f32_e32 v88, v89, v86
	v_fma_f32 v85, -v85, v88, v87
	v_div_fmas_f32 v85, v85, v86, v88
	v_div_fixup_f32 v84, v85, v84, 1.0
	v_mul_f32_e32 v86, v76, v84
	v_mul_f32_e32 v87, v77, v84
	v_mul_f32_e32 v76, v82, v84
	v_mul_f32_e32 v77, v83, v84
	v_mov_b32_e32 v82, 0
	v_cvt_pk_fp8_f32 v82, v86, v87
	v_mul_f32_e32 v78, v78, v84
	v_mul_f32_e32 v79, v79, v84
	v_mul_f32_e32 v80, v80, v84
	v_mul_f32_e32 v81, v81, v84
	v_cvt_pk_fp8_f32 v82, v78, v79 op_sel:[0,0,1]
	v_mov_b32_e32 v78, 0
	v_cvt_pk_fp8_f32 v78, v80, v81
	v_lshl_add_u64 v[80:81], v[144:145], 0, s[6:7]
	v_cvt_pk_fp8_f32 v78, v76, v77 op_sel:[0,0,1]
	v_lshrrev_b32_e32 v76, 8, v82
	global_store_byte v[124:125], v82, off offset:160
	global_store_byte v[126:127], v78, off offset:160
	global_store_byte v[128:129], v76, off offset:160
	v_lshrrev_b32_e32 v76, 8, v78
	global_store_byte v[130:131], v76, off offset:160
	global_store_byte_d16_hi v[136:137], v82, off offset:160
	global_store_byte_d16_hi v[138:139], v78, off offset:160
	v_lshrrev_b32_e32 v76, 24, v82
	global_store_byte v[140:141], v76, off offset:160
	v_lshrrev_b32_e32 v76, 24, v78
	global_store_byte v[142:143], v76, off offset:160
	global_load_dwordx4 v[76:79], v[100:101], off offset:1536
	s_nop 0
	global_load_dwordx4 v[80:83], v[80:81], off offset:16
	s_waitcnt vmcnt(0)
	v_add_f32_e32 v78, v78, v82
	v_add_f32_e32 v79, v79, v83
	v_add_f32_e32 v76, v76, v80
	v_add_f32_e32 v77, v77, v81
	s_nop 0
	v_pk_mov_b32 v[80:81], v[76:77], v[78:79] op_sel:[1,0]
	v_mov_b32_e32 v77, v79
	v_add_f32_e32 v76, v80, v76
	v_add_f32_e32 v77, v81, v77
	s_nop 0
	v_add_f32_e32 v76, v76, v77
	v_fmamk_f32 v76, v76, 0x3b800000, v153
	v_cmp_gt_f32_e32 vcc, s24, v76
	v_mul_f32_e32 v77, 0x4f800000, v76
	s_nop 0
	v_cndmask_b32_e32 v76, v76, v77, vcc
	v_sqrt_f32_e32 v77, v76
	s_nop 0
	v_add_u32_e32 v78, -1, v77
	v_fma_f32 v79, -v78, v77, v76
	v_cmp_ge_f32_e64 s[6:7], 0, v79
	v_add_u32_e32 v79, 1, v77
	s_nop 0
	v_cndmask_b32_e64 v78, v77, v78, s[6:7]
	v_fma_f32 v77, -v79, v77, v76
	v_cmp_lt_f32_e64 s[6:7], 0, v77
	s_nop 1
	v_cndmask_b32_e64 v77, v78, v79, s[6:7]
	v_mul_f32_e32 v78, 0x37800000, v77
	v_cndmask_b32_e32 v77, v77, v78, vcc
	v_cmp_class_f32_e32 vcc, v76, v154
	s_nop 1
	v_cndmask_b32_e32 v76, v77, v76, vcc
	v_div_scale_f32 v77, s[6:7], v76, v76, 1.0
	v_rcp_f32_e32 v78, v77
	s_nop 0
	v_fma_f32 v79, -v77, v78, 1.0
	v_fmac_f32_e32 v78, v79, v78
	v_div_scale_f32 v79, vcc, 1.0, v76, 1.0
	v_mul_f32_e32 v80, v79, v78
	v_fma_f32 v81, -v77, v80, v79
	v_fmac_f32_e32 v80, v81, v78
	v_fma_f32 v77, -v77, v80, v79
	v_div_fmas_f32 v77, v77, v78, v80
	v_div_fixup_f32 v76, v77, v76, 1.0
	v_mul_f32_e32 v70, v70, v76
	v_mul_f32_e32 v71, v71, v76
	v_mul_f32_e32 v68, v68, v76
	v_mul_f32_e32 v69, v69, v76
	v_mul_f32_e32 v74, v74, v76
	v_mul_f32_e32 v75, v75, v76
	v_mul_f32_e32 v72, v72, v76
	v_mul_f32_e32 v73, v73, v76
	v_mov_b32_e32 v76, 0
	v_cvt_pk_fp8_f32 v76, v68, v69
	v_mov_b32_e32 v68, 0
	v_cvt_pk_fp8_f32 v68, v72, v73
	v_cvt_pk_fp8_f32 v76, v70, v71 op_sel:[0,0,1]
	v_cvt_pk_fp8_f32 v68, v74, v75 op_sel:[0,0,1]
	global_store_byte v[124:125], v76, off offset:176
	global_store_byte v[126:127], v68, off offset:176
	v_lshrrev_b32_e32 v69, 8, v76
	global_store_byte v[128:129], v69, off offset:176
	v_lshrrev_b32_e32 v69, 8, v68
	global_store_byte v[130:131], v69, off offset:176
	global_store_byte_d16_hi v[136:137], v76, off offset:176
	global_store_byte_d16_hi v[138:139], v68, off offset:176
	v_lshrrev_b32_e32 v68, 24, v68
	global_store_byte v[142:143], v68, off offset:176
	v_lshlrev_b32_e32 v68, 4, v155
	v_lshrrev_b32_e32 v69, 24, v76
	v_or3_b32 v68, v68, s9, v34
	global_store_byte v[140:141], v69, off offset:176
	v_ashrrev_i32_e32 v69, 31, v68
	v_lshlrev_b64 v[70:71], 5, v[68:69]
	v_lshl_add_u64 v[74:75], s[20:21], 0, v[70:71]
	global_load_dwordx4 v[70:73], v[74:75], off
	s_nop 0
	global_load_dwordx4 v[74:77], v[74:75], off offset:16
	s_waitcnt vmcnt(0)
	v_add_f32_e32 v72, v72, v76
	v_add_f32_e32 v73, v73, v77
	v_add_f32_e32 v70, v70, v74
	v_add_f32_e32 v71, v71, v75
	s_nop 0
	v_pk_mov_b32 v[74:75], v[70:71], v[72:73] op_sel:[1,0]
	v_mov_b32_e32 v71, v73
	v_add_f32_e32 v70, v74, v70
	v_add_f32_e32 v71, v75, v71
	s_nop 0
	v_add_f32_e32 v34, v70, v71
	v_fmamk_f32 v34, v34, 0x3b800000, v153
	v_cmp_gt_f32_e32 vcc, s24, v34
	v_mul_f32_e32 v70, 0x4f800000, v34
	s_nop 0
	v_cndmask_b32_e32 v34, v34, v70, vcc
	v_sqrt_f32_e32 v70, v34
	s_nop 0
	v_add_u32_e32 v71, -1, v70
	v_fma_f32 v72, -v71, v70, v34
	v_cmp_ge_f32_e64 s[6:7], 0, v72
	v_add_u32_e32 v72, 1, v70
	s_nop 0
	v_cndmask_b32_e64 v71, v70, v71, s[6:7]
	v_fma_f32 v70, -v72, v70, v34
	v_cmp_lt_f32_e64 s[6:7], 0, v70
	s_nop 1
	v_cndmask_b32_e64 v70, v71, v72, s[6:7]
	v_mul_f32_e32 v71, 0x37800000, v70
	v_cndmask_b32_e32 v70, v70, v71, vcc
	v_cmp_class_f32_e32 vcc, v34, v154
	s_nop 1
	v_cndmask_b32_e32 v34, v70, v34, vcc
	v_div_scale_f32 v70, s[6:7], v34, v34, 1.0
	v_rcp_f32_e32 v71, v70
	s_nop 0
	v_fma_f32 v72, -v70, v71, 1.0
	v_fmac_f32_e32 v71, v72, v71
	v_div_scale_f32 v72, vcc, 1.0, v34, 1.0
	v_mul_f32_e32 v73, v72, v71
	v_fma_f32 v74, -v70, v73, v72
	v_fmac_f32_e32 v73, v74, v71
	v_fma_f32 v70, -v70, v73, v72
	v_div_fmas_f32 v70, v70, v71, v73
	v_div_fixup_f32 v34, v70, v34, 1.0
	v_mul_f32_e32 v2, v34, v2
	v_mul_f32_e32 v3, v34, v3
	v_mul_f32_e32 v18, v34, v18
	v_mul_f32_e32 v19, v34, v19
	v_mul_f32_e32 v16, v34, v16
	v_mul_f32_e32 v17, v34, v17
	v_mul_f32_e32 v14, v34, v14
	v_mul_f32_e32 v15, v34, v15
	v_mul_f32_e32 v12, v34, v12
	v_mul_f32_e32 v13, v34, v13
	v_mul_f32_e32 v10, v34, v10
	v_mul_f32_e32 v11, v34, v11
	v_mul_f32_e32 v8, v34, v8
	v_mul_f32_e32 v9, v34, v9
	v_mul_f32_e32 v6, v34, v6
	v_mul_f32_e32 v7, v34, v7
	v_mul_f32_e32 v4, v34, v4
	v_mul_f32_e32 v5, v34, v5
	v_mul_f32_e32 v32, v34, v32
	v_mul_f32_e32 v33, v34, v33
	v_mul_f32_e32 v30, v34, v30
	v_mul_f32_e32 v31, v34, v31
	v_mul_f32_e32 v28, v34, v28
	v_mul_f32_e32 v29, v34, v29
	v_mul_f32_e32 v26, v34, v26
	v_mul_f32_e32 v27, v34, v27
	v_mul_f32_e32 v24, v34, v24
	v_mul_f32_e32 v25, v34, v25
	v_mul_f32_e32 v22, v34, v22
	v_mul_f32_e32 v23, v34, v23
	v_mul_f32_e32 v20, v34, v20
	v_mul_f32_e32 v21, v34, v21
	v_max_f32_e64 v34, |v2|, |v18|
	v_max_f32_e64 v70, |v3|, |v19|
	v_max3_f32 v34, v34, 0, v70
	v_max_f32_e64 v70, |v4|, |v20|
	v_max_f32_e64 v71, |v5|, |v21|
	v_max3_f32 v34, v34, v70, v71
	v_max_f32_e64 v70, |v6|, |v22|
	v_max_f32_e64 v71, |v7|, |v23|
	v_max3_f32 v34, v34, v70, v71
	v_max_f32_e64 v70, |v8|, |v24|
	v_max_f32_e64 v71, |v9|, |v25|
	v_max3_f32 v34, v34, v70, v71
	v_max_f32_e64 v70, |v10|, |v26|
	v_max_f32_e64 v71, |v11|, |v27|
	v_max3_f32 v34, v34, v70, v71
	v_max_f32_e64 v70, |v12|, |v28|
	v_max_f32_e64 v71, |v13|, |v29|
	v_max3_f32 v34, v34, v70, v71
	v_max_f32_e64 v70, |v14|, |v30|
	v_max_f32_e64 v71, |v15|, |v31|
	v_max3_f32 v34, v34, v70, v71
	v_max_f32_e64 v70, |v16|, |v32|
	v_max_f32_e64 v71, |v17|, |v33|
	v_max3_f32 v34, v34, v70, v71
	v_bfe_u32 v70, v34, 23, 8
	v_and_b32_e32 v34, 0x7fffff, v34
	v_cmp_gt_u32_e32 vcc, s25, v34
	s_nop 1
	v_cndmask_b32_e64 v34, -2, -3, vcc
	v_add3_u32 v34, v70, v34, s40
	v_max_i32_e32 v34, 0xffffff88, v34
	v_add_u32_e32 v34, 0x7f, v34
	v_lshlrev_b32_e32 v76, 23, v34
	v_cvt_scalef32_2xpk16_fp6_f32 v[70:75], v[2:17], v[18:33], v76
	v_lshlrev_b64 v[2:3], 10, v[68:69]
	v_lshl_add_u64 v[2:3], s[26:27], 0, v[2:3]
	v_lshl_add_u64 v[2:3], v[2:3], 0, s[90:91]
	v_add_u32_e32 v68, 0x80, v68
	v_mul_lo_u32 v34, v34, s2
	v_lshl_add_u64 v[2:3], v[2:3], 0, s[30:31]
	v_mov_b32_e32 v32, v74
	v_mov_b32_e32 v33, v75
	v_ashrrev_i32_e32 v69, 31, v68
	global_store_dwordx4 v[2:3], v[70:73], off
	global_store_dwordx4 v[2:3], v[32:35], off offset:16
	v_lshlrev_b64 v[2:3], 5, v[68:69]
	v_lshl_add_u64 v[2:3], s[20:21], 0, v[2:3]
	global_load_dwordx4 v[4:7], v[2:3], off
	global_load_dwordx4 v[8:11], v[2:3], off offset:16
	s_waitcnt vmcnt(0)
	v_add_f32_e32 v2, v6, v10
	v_add_f32_e32 v3, v7, v11
	v_add_f32_e32 v4, v4, v8
	v_add_f32_e32 v5, v5, v9
	s_nop 0
	v_pk_mov_b32 v[6:7], v[4:5], v[2:3] op_sel:[1,0]
	v_mov_b32_e32 v5, v3
	v_add_f32_e32 v2, v6, v4
	v_add_f32_e32 v3, v7, v5
	s_nop 0
	v_add_f32_e32 v2, v2, v3
	v_fmamk_f32 v2, v2, 0x3b800000, v153
	v_cmp_gt_f32_e32 vcc, s24, v2
	v_mul_f32_e32 v3, 0x4f800000, v2
	s_nop 0
	v_cndmask_b32_e32 v2, v2, v3, vcc
	v_sqrt_f32_e32 v3, v2
	s_nop 0
	v_add_u32_e32 v4, -1, v3
	v_fma_f32 v5, -v4, v3, v2
	v_cmp_ge_f32_e64 s[6:7], 0, v5
	v_add_u32_e32 v5, 1, v3
	s_nop 0
	v_cndmask_b32_e64 v4, v3, v4, s[6:7]
	v_fma_f32 v3, -v5, v3, v2
	v_cmp_lt_f32_e64 s[6:7], 0, v3
	s_nop 1
	v_cndmask_b32_e64 v3, v4, v5, s[6:7]
	v_mul_f32_e32 v4, 0x37800000, v3
	v_cndmask_b32_e32 v3, v3, v4, vcc
	v_cmp_class_f32_e32 vcc, v2, v154
	s_nop 1
	v_cndmask_b32_e32 v2, v3, v2, vcc
	v_div_scale_f32 v3, s[6:7], v2, v2, 1.0
	v_rcp_f32_e32 v4, v3
	s_mov_b64 s[6:7], -1
	v_fma_f32 v5, -v3, v4, 1.0
	v_fmac_f32_e32 v4, v5, v4
	v_div_scale_f32 v5, vcc, 1.0, v2, 1.0
	v_mul_f32_e32 v6, v5, v4
	v_fma_f32 v7, -v3, v6, v5
	v_fmac_f32_e32 v6, v7, v4
	v_fma_f32 v3, -v3, v6, v5
	v_div_fmas_f32 v3, v3, v4, v6
	v_div_fixup_f32 v18, v3, v2, 1.0
	v_mul_f32_e32 v16, v18, v62
	v_mul_f32_e32 v17, v18, v63
	v_mul_f32_e32 v14, v18, v60
	v_mul_f32_e32 v15, v18, v61
	v_mul_f32_e32 v12, v18, v54
	v_mul_f32_e32 v13, v18, v55
	v_mul_f32_e32 v10, v18, v52
	v_mul_f32_e32 v11, v18, v53
	v_mul_f32_e32 v8, v18, v46
	v_mul_f32_e32 v9, v18, v47
	v_mul_f32_e32 v6, v18, v44
	v_mul_f32_e32 v7, v18, v45
	v_mul_f32_e32 v4, v18, v38
	v_mul_f32_e32 v5, v18, v39
	v_mul_f32_e32 v2, v18, v36
	v_mul_f32_e32 v3, v18, v37
	v_mul_f32_e32 v32, v18, v66
	v_mul_f32_e32 v33, v18, v67
	v_mul_f32_e32 v30, v18, v64
	v_mul_f32_e32 v31, v18, v65
	v_mul_f32_e32 v28, v18, v58
	v_mul_f32_e32 v29, v18, v59
	v_mul_f32_e32 v26, v18, v56
	v_mul_f32_e32 v27, v18, v57
	v_mul_f32_e32 v24, v18, v50
	v_mul_f32_e32 v25, v18, v51
	v_mul_f32_e32 v22, v18, v48
	v_mul_f32_e32 v23, v18, v49
	v_mul_f32_e32 v20, v18, v42
	v_mul_f32_e32 v21, v18, v43
	v_mul_f32_e32 v19, v18, v41
	v_mul_f32_e32 v18, v18, v40
	v_max_f32_e64 v34, |v2|, |v18|
	v_max_f32_e64 v36, |v3|, |v19|
	v_max3_f32 v34, v34, 0, v36
	v_max_f32_e64 v36, |v4|, |v20|
	v_max_f32_e64 v37, |v5|, |v21|
	v_max3_f32 v34, v34, v36, v37
	v_max_f32_e64 v36, |v6|, |v22|
	v_max_f32_e64 v37, |v7|, |v23|
	v_max3_f32 v34, v34, v36, v37
	v_max_f32_e64 v36, |v8|, |v24|
	v_max_f32_e64 v37, |v9|, |v25|
	v_max3_f32 v34, v34, v36, v37
	v_max_f32_e64 v36, |v10|, |v26|
	v_max_f32_e64 v37, |v11|, |v27|
	v_max3_f32 v34, v34, v36, v37
	v_max_f32_e64 v36, |v12|, |v28|
	v_max_f32_e64 v37, |v13|, |v29|
	v_max3_f32 v34, v34, v36, v37
	v_max_f32_e64 v36, |v14|, |v30|
	v_max_f32_e64 v37, |v15|, |v31|
	v_max3_f32 v34, v34, v36, v37
	v_max_f32_e64 v36, |v16|, |v32|
	v_max_f32_e64 v37, |v17|, |v33|
	v_max3_f32 v34, v34, v36, v37
	v_bfe_u32 v36, v34, 23, 8
	v_and_b32_e32 v34, 0x7fffff, v34
	v_cmp_gt_u32_e32 vcc, s25, v34
	s_nop 1
	v_cndmask_b32_e64 v34, -2, -3, vcc
	v_add3_u32 v34, v36, v34, s40
	v_max_i32_e32 v34, 0xffffff88, v34
	v_add_u32_e32 v34, 0x7f, v34
	v_lshlrev_b32_e32 v42, 23, v34
	v_cvt_scalef32_2xpk16_fp6_f32 v[36:41], v[2:17], v[18:33], v42
	v_lshlrev_b64 v[2:3], 10, v[68:69]
	v_lshl_add_u64 v[2:3], s[26:27], 0, v[2:3]
	v_lshl_add_u64 v[2:3], v[2:3], 0, s[90:91]
	v_mul_lo_u32 v34, v34, s2
	v_lshl_add_u64 v[2:3], v[2:3], 0, s[30:31]
	v_mov_b32_e32 v32, v40
	v_mov_b32_e32 v33, v41
	global_store_dwordx4 v[2:3], v[36:39], off
	global_store_dwordx4 v[2:3], v[32:35], off offset:16
	s_cbranch_scc1 .LBB0_626
	v_readlane_b32 s6, v254, 50
	v_readlane_b32 s7, v254, 51
	s_andn2_b64 vcc, exec, s[6:7]
	s_cbranch_vccnz .LBB0_625
	s_barrier
	s_branch .LBB0_625

.LBB0_722:
	s_waitcnt lgkmcnt(2)
	v_mfma_scale_f32_32x32x64_f8f6f4 v[66:81], v[90:97], v[130:137], v[66:81], v220, v220 op_sel_hi:[0,0,0]
	s_waitcnt lgkmcnt(0)
	v_mfma_scale_f32_32x32x64_f8f6f4 v[34:49], v[82:89], v[130:137], v[34:49], v220, v220 op_sel_hi:[0,0,0]
	ds_read_b128 v[82:85], v101 offset:5120
	ds_read_b128 v[86:89], v101 offset:5136
	v_exp_f32_e32 v114, v114
	v_exp_f32_e32 v115, v115
	s_nop 0
	v_exp_f32_e32 v116, v116
	v_exp_f32_e32 v117, v117
	v_exp_f32_e32 v118, v118
	s_nop 0
	v_exp_f32_e32 v119, v119
	v_exp_f32_e32 v120, v120
	v_exp_f32_e32 v121, v121
	s_waitcnt lgkmcnt(0)
	v_mfma_scale_f32_32x32x64_f8f6f4 v[18:33], v[82:89], v[130:137], v[18:33], v220, v220 op_sel_hi:[0,0,0]
	v_exp_f32_e32 v122, v122
	v_exp_f32_e32 v123, v123
	v_exp_f32_e32 v124, v124
	ds_read_b128 v[82:85], v101 offset:7680
	ds_read_b128 v[86:89], v101 offset:7696
	v_exp_f32_e32 v125, v125
	v_exp_f32_e32 v126, v126
	v_exp_f32_e32 v127, v127
	s_nop 0
	v_exp_f32_e32 v128, v128
	v_exp_f32_e32 v129, v129
	v_exp_f32_e32 v50, v50
	s_nop 0
	v_exp_f32_e32 v51, v51
	v_exp_f32_e32 v52, v52
	v_exp_f32_e32 v53, v53
	s_waitcnt lgkmcnt(0)
	v_mfma_scale_f32_32x32x64_f8f6f4 v[2:17], v[82:89], v[130:137], v[2:17], v220, v220 op_sel_hi:[0,0,0]
	v_exp_f32_e32 v54, v54
	v_exp_f32_e32 v55, v55
	v_exp_f32_e32 v56, v56
	s_nop 0
	v_exp_f32_e32 v57, v57
	v_exp_f32_e32 v58, v58
	v_exp_f32_e32 v59, v59
	s_nop 0
	v_exp_f32_e32 v60, v60
	v_exp_f32_e32 v61, v61
	v_exp_f32_e32 v62, v62
	s_nop 0
	v_exp_f32_e32 v63, v63
	v_exp_f32_e32 v64, v64
	v_exp_f32_e32 v65, v65
	v_cmp_gt_f32_e32 vcc, 1.0, v98
	s_cbranch_vccz .LBB0_724
	v_mul_f32_e32 v80, v80, v98
	v_mul_f32_e32 v81, v81, v98
	v_mul_f32_e32 v78, v78, v98
	v_mul_f32_e32 v79, v79, v98
	v_mul_f32_e32 v76, v76, v98
	v_mul_f32_e32 v77, v77, v98
	v_mul_f32_e32 v74, v74, v98
	v_mul_f32_e32 v75, v75, v98
	v_mul_f32_e32 v72, v72, v98
	v_mul_f32_e32 v73, v73, v98
	v_mul_f32_e32 v70, v70, v98
	v_mul_f32_e32 v71, v71, v98
	v_mul_f32_e32 v68, v68, v98
	v_mul_f32_e32 v69, v69, v98
	v_mul_f32_e32 v66, v66, v98
	v_mul_f32_e32 v67, v67, v98
	v_mul_f32_e32 v48, v48, v98
	v_mul_f32_e32 v49, v49, v98
	v_mul_f32_e32 v46, v46, v98
	v_mul_f32_e32 v47, v47, v98
	v_mul_f32_e32 v44, v44, v98
	v_mul_f32_e32 v45, v45, v98
	v_mul_f32_e32 v42, v42, v98
	v_mul_f32_e32 v43, v43, v98
	v_mul_f32_e32 v40, v40, v98
	v_mul_f32_e32 v41, v41, v98
	v_mul_f32_e32 v38, v38, v98
	v_mul_f32_e32 v39, v39, v98
	v_mul_f32_e32 v36, v36, v98
	v_mul_f32_e32 v37, v37, v98
	v_mul_f32_e32 v34, v34, v98
	v_mul_f32_e32 v35, v35, v98
	v_mul_f32_e32 v32, v98, v32
	v_mul_f32_e32 v33, v98, v33
	v_mul_f32_e32 v30, v98, v30
	v_mul_f32_e32 v31, v98, v31
	v_mul_f32_e32 v28, v98, v28
	v_mul_f32_e32 v29, v98, v29
	v_mul_f32_e32 v26, v98, v26
	v_mul_f32_e32 v27, v98, v27
	v_mul_f32_e32 v24, v98, v24
	v_mul_f32_e32 v25, v98, v25
	v_mul_f32_e32 v22, v98, v22
	v_mul_f32_e32 v23, v98, v23
	v_mul_f32_e32 v20, v98, v20
	v_mul_f32_e32 v21, v98, v21
	v_mul_f32_e32 v18, v98, v18
	v_mul_f32_e32 v19, v98, v19
	v_mul_f32_e32 v16, v98, v16
	v_mul_f32_e32 v17, v98, v17
	v_mul_f32_e32 v14, v98, v14
	v_mul_f32_e32 v15, v98, v15
	v_mul_f32_e32 v12, v98, v12
	v_mul_f32_e32 v13, v98, v13
	v_mul_f32_e32 v10, v98, v10
	v_mul_f32_e32 v11, v98, v11
	v_mul_f32_e32 v8, v98, v8
	v_mul_f32_e32 v9, v98, v9
	v_mul_f32_e32 v6, v98, v6
	v_mul_f32_e32 v7, v98, v7
	v_mul_f32_e32 v4, v98, v4
	v_mul_f32_e32 v5, v98, v5
	v_mul_f32_e32 v2, v98, v2
	v_mul_f32_e32 v3, v98, v3
.LBB0_724:
	v_add_f32_e32 v82, 0, v114
	v_add_f32_e32 v84, 0, v115
	v_add_f32_e32 v85, 0, v116
	v_add_f32_e32 v86, 0, v117
	v_add_f32_e32 v87, v118, v82
	s_lshl_b64 s[34:35], s[26:27], 20
	v_cvt_pk_fp8_f32 v82, v114, v115
	v_cvt_pk_fp8_f32 v83, v50, v51
	s_add_u32 s5, s29, s34
	s_addc_u32 s34, s39, s35
	v_cvt_pk_fp8_f32 v82, v116, v117 op_sel:[0,0,1]
	v_cvt_pk_fp8_f32 v83, v52, v53 op_sel:[0,0,1]
	s_lshl_b64 s[30:31], s[30:31], 1
	s_add_u32 s30, s5, s30
	v_add_f32_e32 v90, v99, v100
	v_permlane32_swap_b32_e32 v82, v83
	s_addc_u32 s31, s34, s31
	v_fmac_f32_e32 v90, v195, v138
	v_add_f32_e32 v84, v119, v84
	v_add_f32_e32 v85, v120, v85
	v_add_f32_e32 v86, v121, v86
	v_add_f32_e32 v87, v122, v87
	v_add_f32_e32 v84, v123, v84
	s_nop 0
	v_add_f32_e32 v85, v124, v85
	v_add_f32_e32 v86, v125, v86
	v_add_f32_e32 v87, v126, v87
	v_add_f32_e32 v88, v127, v84
	v_add_f32_e32 v89, v128, v85
	v_add_f32_e32 v86, v129, v86
	s_nop 0
	v_cvt_pk_fp8_f32 v84, v118, v119
	v_cvt_pk_fp8_f32 v85, v54, v55
	v_cvt_pk_fp8_f32 v84, v120, v121 op_sel:[0,0,1]
	v_cvt_pk_fp8_f32 v85, v56, v57 op_sel:[0,0,1]
	s_nop 1
	v_permlane32_swap_b32_e32 v84, v85
	v_add_f32_e32 v50, v50, v87
	v_add_f32_e32 v51, v51, v88
	v_add_f32_e32 v52, v52, v89
	v_add_f32_e32 v53, v53, v86
	v_add_f32_e32 v50, v54, v50
	s_nop 0
	v_cvt_pk_fp8_f32 v86, v122, v123
	v_cvt_pk_fp8_f32 v87, v58, v59
	v_cvt_pk_fp8_f32 v86, v124, v125 op_sel:[0,0,1]
	v_cvt_pk_fp8_f32 v87, v60, v61 op_sel:[0,0,1]
	s_nop 1
	v_permlane32_swap_b32_e32 v86, v87
	v_add_f32_e32 v51, v55, v51
	v_add_f32_e32 v52, v56, v52
	v_add_f32_e32 v53, v57, v53
	v_add_f32_e32 v50, v58, v50
	v_add_f32_e32 v51, v59, v51
	s_nop 0
	v_add_f32_e32 v52, v60, v52
	v_add_f32_e32 v53, v61, v53
	v_add_f32_e32 v58, v62, v50
	v_add_f32_e32 v60, v63, v51
	v_add_f32_e32 v59, v64, v52
	v_add_f32_e32 v61, v65, v53
	s_nop 0
	v_cvt_pk_fp8_f32 v88, v126, v127
	v_cvt_pk_fp8_f32 v89, v62, v63
	v_cvt_pk_fp8_f32 v88, v128, v129 op_sel:[0,0,1]
	v_cvt_pk_fp8_f32 v89, v64, v65 op_sel:[0,0,1]
	s_nop 1
	v_permlane32_swap_b32_e32 v88, v89
	v_add_u32_e32 v62, s4, v191
	ds_read_b128 v[50:53], v62
	ds_read_b128 v[54:57], v62 offset:16
	v_add_f32_e32 v58, v58, v60
	v_add_f32_e32 v59, v59, v61
	s_waitcnt lgkmcnt(0)
	v_mfma_scale_f32_32x32x64_f8f6f4 v[66:81], v[50:57], v[82:89], v[66:81], v220, v220 op_sel_hi:[0,0,0]
	v_pk_add_f32 v[58:59], v[58:59], v[58:59] op_sel:[0,1] op_sel_hi:[1,0]
	s_nop 0
	v_mov_b32_e32 v59, v58
	s_nop 1
	v_permlane32_swap_b32_e32 v58, v59
	v_add_f32_e32 v58, v58, v59
	v_fmac_f32_e32 v58, v90, v98
	ds_read_b128 v[50:53], v62 offset:2560
	ds_read_b128 v[54:57], v62 offset:2576
	s_waitcnt lgkmcnt(0)
	v_mfma_scale_f32_32x32x64_f8f6f4 v[34:49], v[50:57], v[82:89], v[34:49], v220, v220 op_sel_hi:[0,0,0]
	ds_read_b128 v[50:53], v62 offset:5120
	ds_read_b128 v[54:57], v62 offset:5136
	s_waitcnt lgkmcnt(0)
	v_mfma_scale_f32_32x32x64_f8f6f4 v[18:33], v[50:57], v[82:89], v[18:33], v220, v220 op_sel_hi:[0,0,0]
	ds_read_b128 v[50:53], v62 offset:7680
	ds_read_b128 v[54:57], v62 offset:7696
	s_waitcnt lgkmcnt(0)
	v_mfma_scale_f32_32x32x64_f8f6f4 v[2:17], v[50:57], v[82:89], v[2:17], v220, v220 op_sel_hi:[0,0,0]
	v_rcp_f32_e32 v54, v58
	v_lshlrev_b64 v[50:51], 12, v[212:213]
	v_lshl_add_u64 v[50:51], s[30:31], 0, v[50:51]
	v_lshlrev_b32_e32 v186, 3, v221
	v_mul_f32_e32 v53, v67, v54
	v_mul_f32_e32 v52, v66, v54
	v_mul_f32_e32 v56, v69, v54
	v_mul_f32_e32 v57, v53, v53
	v_lshl_add_u64 v[50:51], v[50:51], 0, v[186:187]
	v_mul_f32_e32 v55, v68, v54
	v_fmac_f32_e32 v57, v52, v52
	v_mul_f32_e32 v58, v56, v56
	v_cvt_pk_bf16_f32 v52, v52, v53
	v_cvt_pk_bf16_f32 v53, v55, v56
	v_fmac_f32_e32 v58, v55, v55
	global_store_dwordx2 v[50:51], v[52:53], off
	v_mul_f32_e32 v53, v71, v54
	v_mul_f32_e32 v56, v73, v54
	v_add_f32_e32 v57, v57, v58
	v_mul_f32_e32 v52, v70, v54
	v_mul_f32_e32 v55, v72, v54
	v_mul_f32_e32 v58, v53, v53
	v_mul_f32_e32 v59, v56, v56
	v_fmac_f32_e32 v58, v52, v52
	v_fmac_f32_e32 v59, v55, v55
	v_cvt_pk_bf16_f32 v52, v52, v53
	v_cvt_pk_bf16_f32 v53, v55, v56
	v_add_f32_e32 v58, v58, v59
	global_store_dwordx2 v[50:51], v[52:53], off offset:16
	v_mul_f32_e32 v53, v75, v54
	v_mul_f32_e32 v56, v77, v54
	v_add_f32_e32 v57, v57, v58
	v_mul_f32_e32 v52, v74, v54
	v_mul_f32_e32 v55, v76, v54
	v_mul_f32_e32 v58, v53, v53
	v_mul_f32_e32 v59, v56, v56
	v_fmac_f32_e32 v58, v52, v52
	v_fmac_f32_e32 v59, v55, v55
	v_cvt_pk_bf16_f32 v52, v52, v53
	v_cvt_pk_bf16_f32 v53, v55, v56
	v_add_f32_e32 v58, v58, v59
	global_store_dwordx2 v[50:51], v[52:53], off offset:32
	v_mul_f32_e32 v53, v79, v54
	v_add_f32_e32 v57, v58, v57
	v_mul_f32_e32 v52, v78, v54
	v_mul_f32_e32 v58, v53, v53
	v_fmac_f32_e32 v58, v52, v52
	v_cvt_pk_bf16_f32 v52, v52, v53
	v_mul_f32_e32 v35, v54, v35
	v_mul_f32_e32 v55, v80, v54
	v_mul_f32_e32 v56, v81, v54
	v_cvt_pk_bf16_f32 v53, v55, v56
	global_store_dwordx2 v[50:51], v[52:53], off offset:48
	v_mul_f32_e32 v34, v54, v34
	v_mul_f32_e32 v52, v35, v35
	v_mul_f32_e32 v36, v54, v36
	v_mul_f32_e32 v37, v54, v37
	v_fmac_f32_e32 v52, v34, v34
	v_cvt_pk_bf16_f32 v34, v34, v35
	v_cvt_pk_bf16_f32 v35, v36, v37
	global_store_dwordx2 v[50:51], v[34:35], off offset:64
	v_mul_f32_e32 v35, v54, v39
	v_mul_f32_e32 v59, v56, v56
	v_mul_f32_e32 v53, v37, v37
	v_mul_f32_e32 v34, v54, v38
	v_mul_f32_e32 v37, v54, v41
	v_mul_f32_e32 v38, v35, v35
	v_fmac_f32_e32 v59, v55, v55
	v_fmac_f32_e32 v53, v36, v36
	v_mul_f32_e32 v36, v54, v40
	v_fmac_f32_e32 v38, v34, v34
	v_mul_f32_e32 v39, v37, v37
	v_cvt_pk_bf16_f32 v34, v34, v35
	v_cvt_pk_bf16_f32 v35, v36, v37
	v_add_f32_e32 v58, v58, v59
	v_fmac_f32_e32 v39, v36, v36
	global_store_dwordx2 v[50:51], v[34:35], off offset:80
	v_mul_f32_e32 v35, v54, v43
	v_mul_f32_e32 v37, v54, v45
	v_add_f32_e32 v57, v58, v57
	v_add_f32_e32 v52, v52, v53
	v_add_f32_e32 v38, v38, v39
	v_mul_f32_e32 v34, v54, v42
	v_mul_f32_e32 v36, v54, v44
	v_mul_f32_e32 v39, v35, v35
	v_mul_f32_e32 v40, v37, v37
	v_add_f32_e32 v52, v57, v52
	v_fmac_f32_e32 v39, v34, v34
	v_fmac_f32_e32 v40, v36, v36
	v_cvt_pk_bf16_f32 v34, v34, v35
	v_cvt_pk_bf16_f32 v35, v36, v37
	v_add_f32_e32 v38, v38, v52
	v_add_f32_e32 v39, v39, v40
	global_store_dwordx2 v[50:51], v[34:35], off offset:96
	v_mul_f32_e32 v35, v54, v47
	v_add_f32_e32 v38, v39, v38
	v_mul_f32_e32 v34, v54, v46
	v_mul_f32_e32 v39, v35, v35
	v_fmac_f32_e32 v39, v34, v34
	v_cvt_pk_bf16_f32 v34, v34, v35
	v_mul_f32_e32 v19, v54, v19
	v_mul_f32_e32 v36, v54, v48
	v_mul_f32_e32 v37, v54, v49
	v_cvt_pk_bf16_f32 v35, v36, v37
	global_store_dwordx2 v[50:51], v[34:35], off offset:112
	v_mul_f32_e32 v18, v54, v18
	v_mul_f32_e32 v34, v19, v19
	v_mul_f32_e32 v20, v54, v20
	v_mul_f32_e32 v21, v54, v21
	v_fmac_f32_e32 v34, v18, v18
	v_cvt_pk_bf16_f32 v18, v18, v19
	v_cvt_pk_bf16_f32 v19, v20, v21
	global_store_dwordx2 v[50:51], v[18:19], off offset:128
	v_mul_f32_e32 v19, v54, v23
	v_mul_f32_e32 v40, v37, v37
	v_mul_f32_e32 v35, v21, v21
	v_mul_f32_e32 v18, v54, v22
	v_mul_f32_e32 v21, v54, v25
	v_mul_f32_e32 v22, v19, v19
	v_fmac_f32_e32 v40, v36, v36
	v_fmac_f32_e32 v35, v20, v20
	v_mul_f32_e32 v20, v54, v24
	v_fmac_f32_e32 v22, v18, v18
	v_mul_f32_e32 v23, v21, v21
	v_cvt_pk_bf16_f32 v18, v18, v19
	v_cvt_pk_bf16_f32 v19, v20, v21
	v_add_f32_e32 v39, v39, v40
	v_fmac_f32_e32 v23, v20, v20
	global_store_dwordx2 v[50:51], v[18:19], off offset:144
	v_mul_f32_e32 v19, v54, v27
	v_mul_f32_e32 v21, v54, v29
	v_add_f32_e32 v38, v39, v38
	v_add_f32_e32 v34, v34, v35
	v_add_f32_e32 v22, v22, v23
	v_mul_f32_e32 v18, v54, v26
	v_mul_f32_e32 v20, v54, v28
	v_mul_f32_e32 v23, v19, v19
	v_mul_f32_e32 v24, v21, v21
	v_add_f32_e32 v34, v38, v34
	v_fmac_f32_e32 v23, v18, v18
	v_fmac_f32_e32 v24, v20, v20
	v_cvt_pk_bf16_f32 v18, v18, v19
	v_cvt_pk_bf16_f32 v19, v20, v21
	v_add_f32_e32 v22, v22, v34
	v_add_f32_e32 v23, v23, v24
	global_store_dwordx2 v[50:51], v[18:19], off offset:160
	v_mul_f32_e32 v19, v54, v31
	v_add_f32_e32 v22, v23, v22
	v_mul_f32_e32 v18, v54, v30
	v_mul_f32_e32 v23, v19, v19
	v_fmac_f32_e32 v23, v18, v18
	v_cvt_pk_bf16_f32 v18, v18, v19
	v_mul_f32_e32 v3, v54, v3
	v_mul_f32_e32 v20, v54, v32
	v_mul_f32_e32 v21, v54, v33
	v_cvt_pk_bf16_f32 v19, v20, v21
	global_store_dwordx2 v[50:51], v[18:19], off offset:176
	v_mul_f32_e32 v2, v54, v2
	v_mul_f32_e32 v18, v3, v3
	v_mul_f32_e32 v4, v54, v4
	v_mul_f32_e32 v5, v54, v5
	v_fmac_f32_e32 v18, v2, v2
	v_cvt_pk_bf16_f32 v2, v2, v3
	v_cvt_pk_bf16_f32 v3, v4, v5
	global_store_dwordx2 v[50:51], v[2:3], off offset:192
	v_mul_f32_e32 v3, v54, v7
	v_mul_f32_e32 v24, v21, v21
	v_mul_f32_e32 v19, v5, v5
	v_mul_f32_e32 v2, v54, v6
	v_mul_f32_e32 v5, v54, v9
	v_mul_f32_e32 v6, v3, v3
	v_fmac_f32_e32 v24, v20, v20
	v_fmac_f32_e32 v19, v4, v4
	v_mul_f32_e32 v4, v54, v8
	v_fmac_f32_e32 v6, v2, v2
	v_mul_f32_e32 v7, v5, v5
	v_cvt_pk_bf16_f32 v2, v2, v3
	v_cvt_pk_bf16_f32 v3, v4, v5
	v_add_f32_e32 v23, v23, v24
	v_fmac_f32_e32 v7, v4, v4
	global_store_dwordx2 v[50:51], v[2:3], off offset:208
	v_mul_f32_e32 v3, v54, v11
	v_mul_f32_e32 v5, v54, v13
	v_add_f32_e32 v22, v23, v22
	v_add_f32_e32 v18, v18, v19
	v_add_f32_e32 v6, v6, v7
	v_mul_f32_e32 v2, v54, v10
	v_mul_f32_e32 v4, v54, v12
	v_mul_f32_e32 v7, v3, v3
	v_mul_f32_e32 v8, v5, v5
	v_add_f32_e32 v18, v22, v18
	v_fmac_f32_e32 v7, v2, v2
	v_fmac_f32_e32 v8, v4, v4
	v_add_f32_e32 v6, v6, v18
	v_add_f32_e32 v7, v7, v8
	v_add_f32_e32 v6, v7, v6
	v_cvt_pk_bf16_f32 v2, v2, v3
	v_cvt_pk_bf16_f32 v3, v4, v5
	v_mul_f32_e32 v4, v54, v15
	v_mul_f32_e32 v7, v54, v17
	global_store_dwordx2 v[50:51], v[2:3], off offset:224
	v_mul_f32_e32 v3, v54, v14
	v_mul_f32_e32 v5, v54, v16
	v_mul_f32_e32 v2, v4, v4
	v_mul_f32_e32 v8, v7, v7
	v_fmac_f32_e32 v2, v3, v3
	v_fmac_f32_e32 v8, v5, v5
	v_add_f32_e32 v2, v2, v8
	v_add_f32_e32 v2, v2, v6
	v_cvt_pk_bf16_f32 v4, v3, v4
	v_mov_b32_e32 v3, v2
	s_nop 1
	v_permlane32_swap_b32_e32 v2, v3
	v_cmp_eq_u32_e32 vcc, 0, v221
	v_cvt_pk_bf16_f32 v5, v5, v7
	global_store_dwordx2 v[50:51], v[4:5], off offset:240
	s_and_saveexec_b64 s[4:5], vcc
	s_cbranch_execz .LBB0_691
	s_lshl_b64 s[26:27], s[26:27], 14
	s_add_u32 s26, s40, s26
	s_addc_u32 s27, s41, s27
	s_lshl_b64 s[22:23], s[22:23], 2
	s_add_u32 s22, s26, s22
	s_addc_u32 s23, s27, s23
	v_lshlrev_b64 v[4:5], 6, v[212:213]
	v_lshl_add_u64 v[4:5], s[22:23], 0, v[4:5]
	v_add_f32_e32 v2, v2, v3
	global_store_dword v[4:5], v2, off
	s_branch .LBB0_691

.LBB0_731:
	s_mov_b32 s47, s10
	s_mov_b32 s10, s4
	v_lshl_add_u64 v[98:99], v[198:199], 0, s[22:23]
	v_add_co_u32_e32 v100, vcc, s37, v98
	s_nop 1
	v_addc_co_u32_e32 v101, vcc, 0, v99, vcc
	global_load_dwordx4 v[162:165], v[100:101], off
	v_lshl_add_u64 v[100:101], v[200:201], 0, s[22:23]
	v_add_co_u32_e32 v102, vcc, s37, v100
	s_nop 1
	v_addc_co_u32_e32 v103, vcc, 0, v101, vcc
	v_add_co_u32_e32 v98, vcc, s39, v98
	global_load_dwordx4 v[166:169], v[102:103], off
	s_nop 0
	v_addc_co_u32_e32 v99, vcc, 0, v99, vcc
	global_load_dwordx4 v[170:173], v[98:99], off
	v_add_co_u32_e32 v98, vcc, s39, v100
	s_nop 1
	v_addc_co_u32_e32 v99, vcc, 0, v101, vcc
	global_load_dwordx4 v[174:177], v[98:99], off
	ds_read_b128 v[98:101], v216 offset:17408
	ds_read_b128 v[102:105], v216 offset:26112
	ds_read_b128 v[178:181], v216 offset:17440
	v_add_f32_e32 v190, 0, v82
	v_add_f32_e32 v191, 0, v83
	s_waitcnt lgkmcnt(2)
	v_mfma_f32_32x32x16_bf16 v[114:129], v[98:101], v[158:161], 0
	v_mov_b32_e32 v98, 0
	v_mov_b32_e32 v99, 0
	ds_read_b128 v[182:185], v216 offset:26144
	v_add_f32_e32 v226, v84, v98
	v_add_f32_e32 v227, v85, v99
	s_waitcnt lgkmcnt(2)
	v_mfma_f32_32x32x16_bf16 v[98:113], v[102:105], v[158:161], 0
	ds_read_b128 v[186:189], v216 offset:17472
	v_add_f32_e32 v228, v86, v190
	v_add_f32_e32 v229, v87, v191
	v_cvt_pk_bf16_f32 v190, v82, v83
	v_cvt_pk_bf16_f32 v191, v84, v85
	v_cvt_pk_bf16_f32 v192, v86, v87
	v_cvt_pk_bf16_f32 v193, v88, v89
	s_waitcnt lgkmcnt(2)
	v_mfma_f32_32x32x16_bf16 v[114:129], v[178:181], v[154:157], v[114:129]
	v_permlane32_swap_b32_e32 v190, v192
	v_permlane32_swap_b32_e32 v191, v193
	ds_read_b128 v[82:85], v216 offset:26176
	v_add_f32_e32 v226, v88, v226
	v_add_f32_e32 v227, v89, v227
	s_waitcnt lgkmcnt(2)
	v_mfma_f32_32x32x16_bf16 v[98:113], v[182:185], v[154:157], v[98:113]
	ds_read_b128 v[86:89], v216 offset:17504
	v_add_f32_e32 v182, v90, v228
	v_add_f32_e32 v183, v91, v229
	s_waitcnt lgkmcnt(2)
	v_mfma_f32_32x32x16_bf16 v[114:129], v[186:189], v[150:153], v[114:129]
	ds_read_b128 v[178:181], v216 offset:26208
	v_add_f32_e32 v184, v92, v226
	v_add_f32_e32 v185, v93, v227
	s_waitcnt lgkmcnt(2)
	v_mfma_f32_32x32x16_bf16 v[98:113], v[82:85], v[150:153], v[98:113]
	ds_read_b128 v[82:85], v216 offset:17536
	v_add_f32_e32 v182, v94, v182
	v_add_f32_e32 v183, v95, v183
	v_cvt_pk_bf16_f32 v186, v90, v91
	v_cvt_pk_bf16_f32 v187, v92, v93
	v_cvt_pk_bf16_f32 v188, v94, v95
	v_cvt_pk_bf16_f32 v189, v96, v97
	s_waitcnt lgkmcnt(2)
	v_mfma_f32_32x32x16_bf16 v[114:129], v[86:89], v[146:149], v[114:129]
	v_permlane32_swap_b32_e32 v186, v188
	v_permlane32_swap_b32_e32 v187, v189
	ds_read_b128 v[86:89], v216 offset:26240
	v_add_f32_e32 v94, v96, v184
	v_add_f32_e32 v95, v97, v185
	s_waitcnt lgkmcnt(2)
	v_mfma_f32_32x32x16_bf16 v[98:113], v[178:181], v[146:149], v[98:113]
	ds_read_b128 v[90:93], v216 offset:17568
	v_add_f32_e32 v96, v66, v182
	v_add_f32_e32 v97, v67, v183
	s_waitcnt lgkmcnt(2)
	v_mfma_f32_32x32x16_bf16 v[114:129], v[82:85], v[142:145], v[114:129]
	ds_read_b128 v[82:85], v216 offset:26272
	v_add_f32_e32 v94, v68, v94
	v_add_f32_e32 v95, v69, v95
	s_waitcnt lgkmcnt(2)
	v_mfma_f32_32x32x16_bf16 v[98:113], v[86:89], v[142:145], v[98:113]
	ds_read_b128 v[86:89], v216 offset:17600
	v_add_f32_e32 v96, v70, v96
	v_add_f32_e32 v97, v71, v97
	v_cvt_pk_bf16_f32 v182, v66, v67
	v_cvt_pk_bf16_f32 v183, v68, v69
	v_cvt_pk_bf16_f32 v184, v70, v71
	v_cvt_pk_bf16_f32 v185, v72, v73
	s_waitcnt lgkmcnt(2)
	v_mfma_f32_32x32x16_bf16 v[114:129], v[90:93], v[138:141], v[114:129]
	v_permlane32_swap_b32_e32 v182, v184
	v_permlane32_swap_b32_e32 v183, v185
	ds_read_b128 v[66:69], v216 offset:26304
	v_add_f32_e32 v90, v72, v94
	v_add_f32_e32 v91, v73, v95
	s_waitcnt lgkmcnt(2)
	v_mfma_f32_32x32x16_bf16 v[98:113], v[82:85], v[138:141], v[98:113]
	ds_read_b128 v[70:73], v216 offset:17632
	v_add_f32_e32 v92, v74, v96
	v_add_f32_e32 v93, v75, v97
	s_waitcnt lgkmcnt(2)
	v_mfma_f32_32x32x16_bf16 v[114:129], v[86:89], v[134:137], v[114:129]
	ds_read_b128 v[82:85], v216 offset:26336
	v_add_f32_e32 v86, v76, v90
	v_add_f32_e32 v87, v77, v91
	s_waitcnt lgkmcnt(2)
	v_mfma_f32_32x32x16_bf16 v[98:113], v[66:69], v[134:137], v[98:113]
	v_add_f32_e32 v66, v78, v92
	v_add_f32_e32 v67, v79, v93
	v_cvt_pk_bf16_f32 v178, v74, v75
	v_cvt_pk_bf16_f32 v179, v76, v77
	v_cvt_pk_bf16_f32 v180, v78, v79
	v_cvt_pk_bf16_f32 v181, v80, v81
	s_waitcnt lgkmcnt(1)
	v_mfma_f32_32x32x16_bf16 v[114:129], v[70:73], v[130:133], v[114:129]
	v_permlane32_swap_b32_e32 v178, v180
	v_permlane32_swap_b32_e32 v179, v181
	v_add_f32_e32 v68, v80, v86
	v_add_f32_e32 v69, v81, v87
	s_waitcnt lgkmcnt(0)
	v_mfma_f32_32x32x16_bf16 v[98:113], v[82:85], v[130:133], v[98:113]
	v_add_f32_e32 v66, v66, v67
	v_add_f32_e32 v67, v68, v69
	s_add_i32 s4, s45, 0
	v_add_f32_e32 v226, v66, v67
	v_add_u32_e32 v66, s4, v219
	s_waitcnt vmcnt(0)
	s_waitcnt vmcnt(3)
	ds_write_b128 v66, v[162:165]
	v_add_u32_e32 v66, s4, v220
	s_waitcnt vmcnt(2)
	ds_write_b128 v66, v[166:169]
	s_waitcnt vmcnt(1)
	ds_write_b128 v218, v[170:173] offset:49152
	s_waitcnt vmcnt(0)
	ds_write_b128 v218, v[174:177] offset:57856
	v_add_u32_e32 v230, s10, v211
	ds_read_b64_tr_b16 v[66:67], v230
	ds_read_b64_tr_b16 v[68:69], v230 offset:2048
	ds_read_b64_tr_b16 v[70:71], v230 offset:512
	ds_read_b64_tr_b16 v[74:75], v230 offset:1024
	ds_read_b64_tr_b16 v[72:73], v230 offset:2560
	ds_read_b64_tr_b16 v[76:77], v230 offset:3072
	s_waitcnt lgkmcnt(4)
	v_mfma_f32_32x32x16_bf16 v[2:17], v[190:193], v[66:69], v[2:17]
	v_add_u32_e32 v66, 0x7b, v224
	v_cmp_lt_u32_e32 vcc, s30, v66
	v_add_u32_e32 v67, 0xffffffa0, v223
	v_add_u32_e32 v68, 0x79, v224
	v_cndmask_b32_e32 v66, v1, v114, vcc
	v_cmp_gt_u32_e32 vcc, s31, v67
	v_mov_b32_e32 v227, v226
	s_nop 1
	v_permlane32_swap_b32_e32 v226, v227
	v_cndmask_b32_e32 v83, v1, v115, vcc
	v_cmp_lt_u32_e32 vcc, s30, v68
	v_add_u32_e32 v68, 0x78, v224
	v_max3_f32 v67, v66, s34, v83
	v_cndmask_b32_e32 v84, v1, v116, vcc
	v_cmp_lt_u32_e32 vcc, s30, v68
	v_add_u32_e32 v68, 0x73, v224
	s_nop 0
	v_cndmask_b32_e32 v85, v1, v117, vcc
	v_cmp_lt_u32_e32 vcc, s30, v68
	v_add_u32_e32 v68, 0x72, v224
	v_max3_f32 v67, v67, v84, v85
	v_cndmask_b32_e32 v86, v1, v118, vcc
	v_cmp_lt_u32_e32 vcc, s30, v68
	v_add_u32_e32 v68, 0x71, v224
	s_nop 0
	v_cndmask_b32_e32 v87, v1, v119, vcc
	v_cmp_lt_u32_e32 vcc, s30, v68
	v_add_u32_e32 v68, 0x70, v224
	v_max3_f32 v67, v67, v86, v87
	v_cndmask_b32_e32 v88, v1, v120, vcc
	v_cmp_lt_u32_e32 vcc, s30, v68
	s_nop 1
	v_cndmask_b32_e32 v89, v1, v121, vcc
	v_max3_f32 v67, v67, v88, v89
	v_add_u32_e32 v68, 0x6b, v224
	v_cmp_lt_u32_e32 vcc, s30, v68
	v_add_u32_e32 v68, 0x6a, v224
	s_waitcnt lgkmcnt(1)
	v_mfma_f32_32x32x16_bf16 v[50:65], v[190:193], v[70:73], v[50:65]
	v_cndmask_b32_e32 v90, v1, v122, vcc
	v_cmp_lt_u32_e32 vcc, s30, v68
	v_add_u32_e32 v68, 0x69, v224
	ds_read_b64_tr_b16 v[78:79], v230 offset:1536
	ds_read_b64_tr_b16 v[80:81], v230 offset:3584
	v_cndmask_b32_e32 v91, v1, v123, vcc
	v_cmp_lt_u32_e32 vcc, s30, v68
	v_add_u32_e32 v68, 0x68, v224
	v_max3_f32 v67, v67, v90, v91
	v_cndmask_b32_e32 v92, v1, v124, vcc
	v_cmp_lt_u32_e32 vcc, s30, v68
	v_add_u32_e32 v68, 0x63, v224
	s_nop 0
	v_cndmask_b32_e32 v93, v1, v125, vcc
	v_cmp_lt_u32_e32 vcc, s30, v68
	v_add_u32_e32 v68, 0x62, v224
	v_max3_f32 v67, v67, v92, v93
	v_cndmask_b32_e32 v94, v1, v126, vcc
	v_cmp_lt_u32_e32 vcc, s30, v68
	v_add_u32_e32 v68, 0x61, v224
	s_nop 0
	v_cndmask_b32_e32 v95, v1, v127, vcc
	v_cmp_lt_u32_e32 vcc, s30, v68
	v_add_u32_e32 v68, 0x60, v224
	v_max3_f32 v67, v67, v94, v95
	v_cndmask_b32_e32 v96, v1, v128, vcc
	v_cmp_lt_u32_e32 vcc, s30, v68
	s_nop 1
	v_cndmask_b32_e32 v97, v1, v129, vcc
	v_max3_f32 v68, v67, v96, v97
	v_add_u32_e32 v67, 0x5b, v224
	v_cmp_lt_u32_e32 vcc, s30, v67
	v_subrev_u32_e32 v67, 64, v223
	v_add_u32_e32 v69, 0x58, v224
	v_cndmask_b32_e32 v118, v1, v98, vcc
	v_cmp_gt_u32_e32 vcc, s31, v67
	s_waitcnt lgkmcnt(2)
	v_mfma_f32_32x32x16_bf16 v[34:49], v[190:193], v[74:77], v[34:49]
	v_add_u32_e32 v71, 0x52, v224
	v_cndmask_b32_e32 v67, v1, v99, vcc
	v_max3_f32 v70, v68, v118, v67
	v_add_u32_e32 v68, 0x59, v224
	v_cmp_lt_u32_e32 vcc, s30, v68
	ds_read_b64_tr_b16 v[114:115], v230 offset:4096
	ds_read_b64_tr_b16 v[116:117], v230 offset:6144
	v_cndmask_b32_e32 v68, v1, v100, vcc
	v_cmp_lt_u32_e32 vcc, s30, v69
	v_add_u32_e32 v73, 0x50, v224
	s_nop 0
	v_cndmask_b32_e32 v69, v1, v101, vcc
	v_max3_f32 v72, v70, v68, v69
	v_add_u32_e32 v70, 0x53, v224
	v_cmp_lt_u32_e32 vcc, s30, v70
	s_nop 1
	v_cndmask_b32_e32 v70, v1, v102, vcc
	v_cmp_lt_u32_e32 vcc, s30, v71
	s_nop 1
	v_cndmask_b32_e32 v71, v1, v103, vcc
	v_max3_f32 v74, v72, v70, v71
	v_add_u32_e32 v72, 0x51, v224
	v_cmp_lt_u32_e32 vcc, s30, v72
	s_nop 1
	v_cndmask_b32_e32 v72, v1, v104, vcc
	v_cmp_lt_u32_e32 vcc, s30, v73
	s_nop 1
	v_cndmask_b32_e32 v73, v1, v105, vcc
	v_max3_f32 v82, v74, v72, v73
	v_add_u32_e32 v74, 0x4b, v224
	v_cmp_lt_u32_e32 vcc, s30, v74
	v_add_u32_e32 v75, 0x4a, v224
	v_add_u32_e32 v76, 0x49, v224
	v_cndmask_b32_e32 v74, v1, v106, vcc
	v_cmp_lt_u32_e32 vcc, s30, v75
	s_waitcnt lgkmcnt(2)
	v_mfma_f32_32x32x16_bf16 v[18:33], v[190:193], v[78:81], v[18:33]
	v_add_u32_e32 v77, 0x48, v224
	v_cndmask_b32_e32 v75, v1, v107, vcc
	v_cmp_lt_u32_e32 vcc, s30, v76
	v_add_u32_e32 v78, 0x43, v224
	v_add_u32_e32 v79, 0x42, v224
	v_cndmask_b32_e32 v76, v1, v108, vcc
	v_cmp_lt_u32_e32 vcc, s30, v77
	ds_read_b64_tr_b16 v[98:99], v230 offset:4608
	ds_read_b64_tr_b16 v[100:101], v230 offset:6656
	v_cndmask_b32_e32 v77, v1, v109, vcc
	v_cmp_lt_u32_e32 vcc, s30, v78
	v_add_u32_e32 v80, 0x41, v224
	v_add_u32_e32 v81, 64, v224
	v_cndmask_b32_e32 v78, v1, v110, vcc
	v_cmp_lt_u32_e32 vcc, s30, v79
	v_max3_f32 v82, v82, v74, v75
	v_max3_f32 v82, v82, v76, v77
	v_cndmask_b32_e32 v79, v1, v111, vcc
	v_cmp_lt_u32_e32 vcc, s30, v80
	v_max3_f32 v82, v82, v78, v79
	s_nop 0
	v_cndmask_b32_e32 v80, v1, v112, vcc
	v_cmp_lt_u32_e32 vcc, s30, v81
	s_nop 1
	v_cndmask_b32_e32 v81, v1, v113, vcc
	v_max3_f32 v82, v82, v80, v81
	s_nop 0
	v_mov_b32_e32 v106, v82
	s_nop 1
	v_permlane32_swap_b32_e32 v82, v106
	v_max_f32_e32 v106, v106, v106
	v_max_f32_e32 v82, v82, v82
	v_max_f32_e32 v82, v82, v106
	v_sub_f32_e32 v106, v82, v225
	s_waitcnt lgkmcnt(2)
	v_mfma_f32_32x32x16_bf16 v[2:17], v[186:189], v[114:117], v[2:17]
	v_cmp_ge_f32_e32 vcc, s35, v106
	s_cmp_eq_u64 vcc, exec
	v_max_f32_e32 v106, v225, v225
	ds_read_b64_tr_b16 v[102:103], v230 offset:5120
	ds_read_b64_tr_b16 v[104:105], v230 offset:7168
	v_max_f32_e32 v82, v106, v82
	s_cselect_b64 vcc, -1, 0
	v_cndmask_b32_e32 v229, v82, v225, vcc
	v_sub_f32_e32 v82, v225, v229
	v_mul_f32_e32 v82, 0x3e0293ee, v82
	v_exp_f32_e32 v228, v82
	v_fma_f32 v110, v229, s36, 0
	s_waitcnt lgkmcnt(2)
	v_mfma_f32_32x32x16_bf16 v[50:65], v[186:189], v[98:101], v[50:65]
	ds_read_b64_tr_b16 v[106:107], v230 offset:5632
	ds_read_b64_tr_b16 v[108:109], v230 offset:7680
	v_fmamk_f32 v66, v66, 0x3e0293ee, v110
	v_exp_f32_e32 v82, v66
	v_fmamk_f32 v66, v83, 0x3e0293ee, v110
	v_exp_f32_e32 v83, v66
	s_waitcnt lgkmcnt(2)
	v_mfma_f32_32x32x16_bf16 v[34:49], v[186:189], v[102:105], v[34:49]
	ds_read_b64_tr_b16 v[98:99], v230 offset:8192
	ds_read_b64_tr_b16 v[100:101], v230 offset:10240
	v_fmamk_f32 v66, v84, 0x3e0293ee, v110
	v_exp_f32_e32 v84, v66
	v_fmamk_f32 v66, v85, 0x3e0293ee, v110
	v_exp_f32_e32 v85, v66
	v_fmamk_f32 v66, v86, 0x3e0293ee, v110
	v_exp_f32_e32 v86, v66
	s_waitcnt lgkmcnt(2)
	v_mfma_f32_32x32x16_bf16 v[18:33], v[186:189], v[106:109], v[18:33]
	ds_read_b64_tr_b16 v[102:103], v230 offset:8704
	ds_read_b64_tr_b16 v[104:105], v230 offset:10752
	v_fmamk_f32 v66, v87, 0x3e0293ee, v110
	v_exp_f32_e32 v87, v66
	v_fmamk_f32 v66, v88, 0x3e0293ee, v110
	v_exp_f32_e32 v88, v66
	v_fmamk_f32 v66, v89, 0x3e0293ee, v110
	v_exp_f32_e32 v89, v66
	s_waitcnt lgkmcnt(2)
	v_mfma_f32_32x32x16_bf16 v[2:17], v[182:185], v[98:101], v[2:17]
	ds_read_b64_tr_b16 v[106:107], v230 offset:9216
	ds_read_b64_tr_b16 v[108:109], v230 offset:11264
	v_fmamk_f32 v66, v90, 0x3e0293ee, v110
	v_exp_f32_e32 v90, v66
	v_fmamk_f32 v66, v91, 0x3e0293ee, v110
	v_exp_f32_e32 v91, v66
	v_fmamk_f32 v66, v92, 0x3e0293ee, v110
	v_exp_f32_e32 v92, v66
	s_waitcnt lgkmcnt(2)
	v_mfma_f32_32x32x16_bf16 v[50:65], v[182:185], v[102:105], v[50:65]
	ds_read_b64_tr_b16 v[98:99], v230 offset:9728
	ds_read_b64_tr_b16 v[100:101], v230 offset:11776
	v_fmamk_f32 v66, v93, 0x3e0293ee, v110
	v_exp_f32_e32 v93, v66
	v_fmamk_f32 v66, v94, 0x3e0293ee, v110
	v_exp_f32_e32 v94, v66
	v_fmamk_f32 v66, v95, 0x3e0293ee, v110
	v_exp_f32_e32 v95, v66
	s_waitcnt lgkmcnt(2)
	v_mfma_f32_32x32x16_bf16 v[34:49], v[182:185], v[106:109], v[34:49]
	ds_read_b64_tr_b16 v[102:103], v230 offset:12288
	ds_read_b64_tr_b16 v[104:105], v230 offset:14336
	v_fmamk_f32 v66, v96, 0x3e0293ee, v110
	v_exp_f32_e32 v96, v66
	v_fmamk_f32 v66, v97, 0x3e0293ee, v110
	v_exp_f32_e32 v97, v66
	v_fmamk_f32 v66, v118, 0x3e0293ee, v110
	v_exp_f32_e32 v66, v66
	s_waitcnt lgkmcnt(2)
	v_mfma_f32_32x32x16_bf16 v[18:33], v[182:185], v[98:101], v[18:33]
	ds_read_b64_tr_b16 v[106:107], v230 offset:12800
	ds_read_b64_tr_b16 v[108:109], v230 offset:14848
	v_fmamk_f32 v67, v67, 0x3e0293ee, v110
	v_fmamk_f32 v68, v68, 0x3e0293ee, v110
	v_fmamk_f32 v69, v69, 0x3e0293ee, v110
	v_exp_f32_e32 v67, v67
	v_exp_f32_e32 v68, v68
	v_exp_f32_e32 v69, v69
	s_waitcnt lgkmcnt(2)
	v_mfma_f32_32x32x16_bf16 v[2:17], v[178:181], v[102:105], v[2:17]
	ds_read_b64_tr_b16 v[98:99], v230 offset:13312
	ds_read_b64_tr_b16 v[100:101], v230 offset:15360
	v_fmamk_f32 v70, v70, 0x3e0293ee, v110
	v_fmamk_f32 v71, v71, 0x3e0293ee, v110
	v_fmamk_f32 v72, v72, 0x3e0293ee, v110
	v_exp_f32_e32 v70, v70
	v_exp_f32_e32 v71, v71
	v_exp_f32_e32 v72, v72
	s_waitcnt lgkmcnt(2)
	v_mfma_f32_32x32x16_bf16 v[50:65], v[178:181], v[106:109], v[50:65]
	ds_read_b64_tr_b16 v[102:103], v230 offset:13824
	ds_read_b64_tr_b16 v[104:105], v230 offset:15872
	v_fmamk_f32 v73, v73, 0x3e0293ee, v110
	v_fmamk_f32 v74, v74, 0x3e0293ee, v110
	v_fmamk_f32 v75, v75, 0x3e0293ee, v110
	v_exp_f32_e32 v73, v73
	v_exp_f32_e32 v74, v74
	v_exp_f32_e32 v75, v75
	s_waitcnt lgkmcnt(2)
	v_mfma_f32_32x32x16_bf16 v[34:49], v[178:181], v[98:101], v[34:49]
	v_fmamk_f32 v76, v76, 0x3e0293ee, v110
	v_fmamk_f32 v77, v77, 0x3e0293ee, v110
	v_fmamk_f32 v78, v78, 0x3e0293ee, v110
	v_exp_f32_e32 v76, v76
	v_exp_f32_e32 v77, v77
	v_exp_f32_e32 v78, v78
	s_waitcnt lgkmcnt(0)
	v_mfma_f32_32x32x16_bf16 v[18:33], v[178:181], v[102:105], v[18:33]
	v_fmamk_f32 v79, v79, 0x3e0293ee, v110
	v_fmamk_f32 v80, v80, 0x3e0293ee, v110
	v_fmac_f32_e32 v110, 0x3e0293ee, v81
	v_exp_f32_e32 v79, v79
	v_exp_f32_e32 v80, v80
	v_exp_f32_e32 v81, v110
	v_cmp_gt_f32_e32 vcc, 1.0, v228
	s_cbranch_vccz .LBB0_735
	s_and_saveexec_b64 s[4:5], s[6:7]
	ds_write_b32 v213, v228 offset:128
	s_or_b64 exec, exec, s[4:5]
	s_waitcnt lgkmcnt(0)
	ds_read_b128 v[98:101], v208 offset:224
	ds_read_b128 v[102:105], v208 offset:192
	ds_read_b128 v[106:109], v208 offset:160
	ds_read_b128 v[110:113], v208 offset:128
	s_waitcnt lgkmcnt(3)
	v_mul_f32_e32 v16, v16, v100
	v_mul_f32_e32 v17, v17, v101
	s_waitcnt lgkmcnt(2)
	v_mul_f32_e32 v12, v12, v104
	v_mul_f32_e32 v13, v13, v105
	s_waitcnt lgkmcnt(1)
	v_mul_f32_e32 v8, v8, v108
	v_mul_f32_e32 v9, v9, v109
	s_waitcnt lgkmcnt(0)
	v_mul_f32_e32 v4, v4, v112
	v_mul_f32_e32 v5, v5, v113
	v_mul_f32_e32 v14, v14, v98
	v_mul_f32_e32 v15, v15, v99
	v_mul_f32_e32 v10, v10, v102
	v_mul_f32_e32 v11, v11, v103
	v_mul_f32_e32 v6, v6, v106
	v_mul_f32_e32 v7, v7, v107
	v_mul_f32_e32 v2, v2, v110
	v_mul_f32_e32 v3, v3, v111
	v_mul_f32_e32 v64, v64, v100
	v_mul_f32_e32 v65, v65, v101
	v_mul_f32_e32 v60, v60, v104
	v_mul_f32_e32 v61, v61, v105
	v_mul_f32_e32 v56, v56, v108
	v_mul_f32_e32 v57, v57, v109
	v_mul_f32_e32 v52, v52, v112
	v_mul_f32_e32 v53, v53, v113
	v_mul_f32_e32 v62, v62, v98
	v_mul_f32_e32 v63, v63, v99
	v_mul_f32_e32 v58, v58, v102
	v_mul_f32_e32 v59, v59, v103
	v_mul_f32_e32 v54, v54, v106
	v_mul_f32_e32 v55, v55, v107
	v_mul_f32_e32 v50, v50, v110
	v_mul_f32_e32 v51, v51, v111
	v_mul_f32_e32 v48, v48, v100
	v_mul_f32_e32 v49, v49, v101
	v_mul_f32_e32 v44, v44, v104
	v_mul_f32_e32 v45, v45, v105
	v_mul_f32_e32 v40, v40, v108
	v_mul_f32_e32 v41, v41, v109
	v_mul_f32_e32 v36, v36, v112
	v_mul_f32_e32 v37, v37, v113
	v_mul_f32_e32 v46, v46, v98
	v_mul_f32_e32 v47, v47, v99
	v_mul_f32_e32 v42, v42, v102
	v_mul_f32_e32 v43, v43, v103
	v_mul_f32_e32 v38, v38, v106
	v_mul_f32_e32 v39, v39, v107
	v_mul_f32_e32 v34, v34, v110
	v_mul_f32_e32 v35, v35, v111
	v_mul_f32_e32 v32, v32, v100
	v_mul_f32_e32 v33, v33, v101
	v_mul_f32_e32 v28, v28, v104
	v_mul_f32_e32 v29, v29, v105
	v_mul_f32_e32 v24, v24, v108
	v_mul_f32_e32 v25, v25, v109
	v_mul_f32_e32 v20, v20, v112
	v_mul_f32_e32 v21, v21, v113
	v_mul_f32_e32 v30, v30, v98
	v_mul_f32_e32 v31, v31, v99
	v_mul_f32_e32 v26, v26, v102
	v_mul_f32_e32 v27, v27, v103
	v_mul_f32_e32 v22, v22, v106
	v_mul_f32_e32 v23, v23, v107
	v_mul_f32_e32 v18, v18, v110
	v_mul_f32_e32 v19, v19, v111

.LBB0_739:
	s_waitcnt vmcnt(3)
	v_add_u32_e32 v162, s47, v211
	ds_read_b64_tr_b16 v[66:67], v162
	ds_read_b64_tr_b16 v[68:69], v162 offset:2048
	ds_read_b64_tr_b16 v[70:71], v162 offset:512
	ds_read_b64_tr_b16 v[74:75], v162 offset:1024
	ds_read_b64_tr_b16 v[72:73], v162 offset:2560
	ds_read_b64_tr_b16 v[76:77], v162 offset:3072
	s_waitcnt lgkmcnt(4)
	v_mfma_f32_32x32x16_bf16 v[2:17], v[190:193], v[66:69], v[2:17]
	v_add_u32_e32 v66, 59, v224
	v_cmp_lt_u32_e32 vcc, s30, v66
	v_subrev_u32_e32 v67, 32, v223
	v_add_u32_e32 v68, 57, v224
	v_cndmask_b32_e32 v66, v1, v114, vcc
	v_cmp_gt_u32_e32 vcc, s31, v67
	s_nop 1
	v_cndmask_b32_e32 v83, v1, v115, vcc
	v_cmp_lt_u32_e32 vcc, s30, v68
	v_add_u32_e32 v68, 56, v224
	v_max3_f32 v67, v66, s34, v83
	v_cndmask_b32_e32 v84, v1, v116, vcc
	v_cmp_lt_u32_e32 vcc, s30, v68
	v_add_u32_e32 v68, 51, v224
	s_nop 0
	v_cndmask_b32_e32 v85, v1, v117, vcc
	v_cmp_lt_u32_e32 vcc, s30, v68
	v_add_u32_e32 v68, 50, v224
	v_max3_f32 v67, v67, v84, v85
	v_cndmask_b32_e32 v86, v1, v118, vcc
	v_cmp_lt_u32_e32 vcc, s30, v68
	v_add_u32_e32 v68, 49, v224
	s_nop 0
	v_cndmask_b32_e32 v87, v1, v119, vcc
	v_cmp_lt_u32_e32 vcc, s30, v68
	v_add_u32_e32 v68, 48, v224
	v_max3_f32 v67, v67, v86, v87
	v_cndmask_b32_e32 v88, v1, v120, vcc
	v_cmp_lt_u32_e32 vcc, s30, v68
	s_nop 1
	v_cndmask_b32_e32 v89, v1, v121, vcc
	v_max3_f32 v67, v67, v88, v89
	v_add_u32_e32 v68, 43, v224
	v_cmp_lt_u32_e32 vcc, s30, v68
	v_add_u32_e32 v68, 42, v224
	s_waitcnt lgkmcnt(1)
	v_mfma_f32_32x32x16_bf16 v[50:65], v[190:193], v[70:73], v[50:65]
	v_cndmask_b32_e32 v90, v1, v122, vcc
	v_cmp_lt_u32_e32 vcc, s30, v68
	v_add_u32_e32 v68, 41, v224
	ds_read_b64_tr_b16 v[78:79], v162 offset:1536
	ds_read_b64_tr_b16 v[80:81], v162 offset:3584
	v_cndmask_b32_e32 v91, v1, v123, vcc
	v_cmp_lt_u32_e32 vcc, s30, v68
	v_add_u32_e32 v68, 40, v224
	v_max3_f32 v67, v67, v90, v91
	v_cndmask_b32_e32 v92, v1, v124, vcc
	v_cmp_lt_u32_e32 vcc, s30, v68
	v_add_u32_e32 v68, 35, v224
	s_nop 0
	v_cndmask_b32_e32 v93, v1, v125, vcc
	v_cmp_lt_u32_e32 vcc, s30, v68
	v_add_u32_e32 v68, 34, v224
	v_max3_f32 v67, v67, v92, v93
	v_cndmask_b32_e32 v94, v1, v126, vcc
	v_cmp_lt_u32_e32 vcc, s30, v68
	v_add_u32_e32 v68, 33, v224
	s_nop 0
	v_cndmask_b32_e32 v95, v1, v127, vcc
	v_cmp_lt_u32_e32 vcc, s30, v68
	v_add_u32_e32 v68, 32, v224
	v_max3_f32 v67, v67, v94, v95
	v_cndmask_b32_e32 v96, v1, v128, vcc
	v_cmp_lt_u32_e32 vcc, s30, v68
	s_nop 1
	v_cndmask_b32_e32 v97, v1, v129, vcc
	v_max3_f32 v68, v67, v96, v97
	v_add_u32_e32 v67, 27, v224
	v_cmp_lt_u32_e32 vcc, s30, v67
	v_add_u32_e32 v69, 24, v224
	s_waitcnt lgkmcnt(2)
	v_mfma_f32_32x32x16_bf16 v[34:49], v[190:193], v[74:77], v[34:49]
	v_cndmask_b32_e32 v118, v1, v98, vcc
	v_cmp_gt_u32_e32 vcc, s31, v223
	v_add_u32_e32 v71, 18, v224
	ds_read_b64_tr_b16 v[114:115], v162 offset:4096
	ds_read_b64_tr_b16 v[116:117], v162 offset:6144
	v_cndmask_b32_e32 v67, v1, v99, vcc
	v_max3_f32 v70, v68, v118, v67
	v_add_u32_e32 v68, 25, v224
	v_cmp_lt_u32_e32 vcc, s30, v68
	v_add_u32_e32 v73, 16, v224
	s_nop 0
	v_cndmask_b32_e32 v68, v1, v100, vcc
	v_cmp_lt_u32_e32 vcc, s30, v69
	s_nop 1
	v_cndmask_b32_e32 v69, v1, v101, vcc
	v_max3_f32 v72, v70, v68, v69
	v_add_u32_e32 v70, 19, v224
	v_cmp_lt_u32_e32 vcc, s30, v70
	s_nop 1
	v_cndmask_b32_e32 v70, v1, v102, vcc
	v_cmp_lt_u32_e32 vcc, s30, v71
	s_nop 1
	v_cndmask_b32_e32 v71, v1, v103, vcc
	v_max3_f32 v74, v72, v70, v71
	v_add_u32_e32 v72, 17, v224
	v_cmp_lt_u32_e32 vcc, s30, v72
	s_nop 1
	v_cndmask_b32_e32 v72, v1, v104, vcc
	v_cmp_lt_u32_e32 vcc, s30, v73
	s_nop 1
	v_cndmask_b32_e32 v73, v1, v105, vcc
	v_max3_f32 v82, v74, v72, v73
	v_add_u32_e32 v74, 11, v224
	v_cmp_lt_u32_e32 vcc, s30, v74
	v_add_u32_e32 v75, 10, v224
	v_add_u32_e32 v76, 9, v224
	v_cndmask_b32_e32 v74, v1, v106, vcc
	v_cmp_lt_u32_e32 vcc, s30, v75
	s_waitcnt lgkmcnt(2)
	v_mfma_f32_32x32x16_bf16 v[18:33], v[190:193], v[78:81], v[18:33]
	v_add_u32_e32 v77, 8, v224
	v_cndmask_b32_e32 v75, v1, v107, vcc
	v_cmp_lt_u32_e32 vcc, s30, v76
	v_add_u32_e32 v78, 3, v224
	v_add_u32_e32 v79, 2, v224
	v_cndmask_b32_e32 v76, v1, v108, vcc
	v_cmp_lt_u32_e32 vcc, s30, v77
	ds_read_b64_tr_b16 v[100:101], v162 offset:4608
	ds_read_b64_tr_b16 v[102:103], v162 offset:6656
	v_cndmask_b32_e32 v77, v1, v109, vcc
	v_cmp_lt_u32_e32 vcc, s30, v78
	v_add_u32_e32 v80, 1, v224
	v_max3_f32 v82, v82, v74, v75
	v_cndmask_b32_e32 v78, v1, v110, vcc
	v_cmp_lt_u32_e32 vcc, s30, v79
	v_max3_f32 v82, v82, v76, v77
	s_nop 0
	v_cndmask_b32_e32 v79, v1, v111, vcc
	v_cmp_lt_u32_e32 vcc, s30, v80
	v_max3_f32 v82, v82, v78, v79
	s_nop 0
	v_cndmask_b32_e32 v80, v1, v112, vcc
	v_cmp_lt_u32_e32 vcc, s30, v224
	s_nop 1
	v_cndmask_b32_e32 v81, v1, v113, vcc
	v_max3_f32 v82, v82, v80, v81
	s_nop 0
	v_mov_b32_e32 v98, v82
	s_nop 1
	v_permlane32_swap_b32_e32 v82, v98
	v_max_f32_e32 v98, v98, v98
	v_max_f32_e32 v82, v82, v82
	v_max_f32_e32 v82, v82, v98
	v_sub_f32_e32 v98, v82, v229
	s_waitcnt lgkmcnt(2)
	v_mfma_f32_32x32x16_bf16 v[2:17], v[186:189], v[114:117], v[2:17]
	v_cmp_ge_f32_e32 vcc, s35, v98
	s_cmp_eq_u64 vcc, exec
	v_max_f32_e32 v98, v229, v229
	ds_read_b64_tr_b16 v[104:105], v162 offset:5120
	ds_read_b64_tr_b16 v[106:107], v162 offset:7168
	v_max_f32_e32 v82, v98, v82
	s_cselect_b64 vcc, -1, 0
	v_cndmask_b32_e32 v225, v82, v229, vcc
	v_sub_f32_e32 v82, v229, v225
	v_mul_f32_e32 v82, 0x3e0293ee, v82
	v_exp_f32_e32 v98, v82
	v_fma_f32 v99, v225, s36, 0
	s_waitcnt lgkmcnt(2)
	v_mfma_f32_32x32x16_bf16 v[50:65], v[186:189], v[100:103], v[50:65]
	ds_read_b64_tr_b16 v[108:109], v162 offset:5632
	ds_read_b64_tr_b16 v[110:111], v162 offset:7680
	v_fmamk_f32 v66, v66, 0x3e0293ee, v99
	v_exp_f32_e32 v82, v66
	v_fmamk_f32 v66, v83, 0x3e0293ee, v99
	v_exp_f32_e32 v83, v66
	s_waitcnt lgkmcnt(2)
	v_mfma_f32_32x32x16_bf16 v[34:49], v[186:189], v[104:107], v[34:49]
	ds_read_b64_tr_b16 v[100:101], v162 offset:8192
	ds_read_b64_tr_b16 v[102:103], v162 offset:10240
	v_fmamk_f32 v66, v84, 0x3e0293ee, v99
	v_exp_f32_e32 v84, v66
	v_fmamk_f32 v66, v85, 0x3e0293ee, v99
	v_exp_f32_e32 v85, v66
	v_fmamk_f32 v66, v86, 0x3e0293ee, v99
	v_exp_f32_e32 v86, v66
	s_waitcnt lgkmcnt(2)
	v_mfma_f32_32x32x16_bf16 v[18:33], v[186:189], v[108:111], v[18:33]
	ds_read_b64_tr_b16 v[104:105], v162 offset:8704
	ds_read_b64_tr_b16 v[106:107], v162 offset:10752
	v_fmamk_f32 v66, v87, 0x3e0293ee, v99
	v_exp_f32_e32 v87, v66
	v_fmamk_f32 v66, v88, 0x3e0293ee, v99
	v_exp_f32_e32 v88, v66
	v_fmamk_f32 v66, v89, 0x3e0293ee, v99
	v_exp_f32_e32 v89, v66
	s_waitcnt lgkmcnt(2)
	v_mfma_f32_32x32x16_bf16 v[2:17], v[182:185], v[100:103], v[2:17]
	ds_read_b64_tr_b16 v[108:109], v162 offset:9216
	ds_read_b64_tr_b16 v[110:111], v162 offset:11264
	v_fmamk_f32 v66, v90, 0x3e0293ee, v99
	v_exp_f32_e32 v90, v66
	v_fmamk_f32 v66, v91, 0x3e0293ee, v99
	v_exp_f32_e32 v91, v66
	v_fmamk_f32 v66, v92, 0x3e0293ee, v99
	v_exp_f32_e32 v92, v66
	s_waitcnt lgkmcnt(2)
	v_mfma_f32_32x32x16_bf16 v[50:65], v[182:185], v[104:107], v[50:65]
	ds_read_b64_tr_b16 v[100:101], v162 offset:9728
	ds_read_b64_tr_b16 v[102:103], v162 offset:11776
	v_fmamk_f32 v66, v93, 0x3e0293ee, v99
	v_exp_f32_e32 v93, v66
	v_fmamk_f32 v66, v94, 0x3e0293ee, v99
	v_exp_f32_e32 v94, v66
	v_fmamk_f32 v66, v95, 0x3e0293ee, v99
	v_exp_f32_e32 v95, v66
	s_waitcnt lgkmcnt(2)
	v_mfma_f32_32x32x16_bf16 v[34:49], v[182:185], v[108:111], v[34:49]
	ds_read_b64_tr_b16 v[104:105], v162 offset:12288
	ds_read_b64_tr_b16 v[106:107], v162 offset:14336
	v_fmamk_f32 v66, v96, 0x3e0293ee, v99
	v_exp_f32_e32 v96, v66
	v_fmamk_f32 v66, v97, 0x3e0293ee, v99
	v_exp_f32_e32 v97, v66
	v_fmamk_f32 v66, v118, 0x3e0293ee, v99
	v_exp_f32_e32 v66, v66
	s_waitcnt lgkmcnt(2)
	v_mfma_f32_32x32x16_bf16 v[18:33], v[182:185], v[100:103], v[18:33]
	ds_read_b64_tr_b16 v[108:109], v162 offset:12800
	ds_read_b64_tr_b16 v[110:111], v162 offset:14848
	v_fmamk_f32 v67, v67, 0x3e0293ee, v99
	v_fmamk_f32 v68, v68, 0x3e0293ee, v99
	v_fmamk_f32 v69, v69, 0x3e0293ee, v99
	v_exp_f32_e32 v67, v67
	v_exp_f32_e32 v68, v68
	v_exp_f32_e32 v69, v69
	s_waitcnt lgkmcnt(2)
	v_mfma_f32_32x32x16_bf16 v[2:17], v[178:181], v[104:107], v[2:17]
	ds_read_b64_tr_b16 v[100:101], v162 offset:13312
	ds_read_b64_tr_b16 v[102:103], v162 offset:15360
	v_fmamk_f32 v70, v70, 0x3e0293ee, v99
	v_fmamk_f32 v71, v71, 0x3e0293ee, v99
	v_fmamk_f32 v72, v72, 0x3e0293ee, v99
	v_exp_f32_e32 v70, v70
	v_exp_f32_e32 v71, v71
	v_exp_f32_e32 v72, v72
	s_waitcnt lgkmcnt(2)
	v_mfma_f32_32x32x16_bf16 v[50:65], v[178:181], v[108:111], v[50:65]
	ds_read_b64_tr_b16 v[104:105], v162 offset:13824
	ds_read_b64_tr_b16 v[106:107], v162 offset:15872
	v_fmamk_f32 v73, v73, 0x3e0293ee, v99
	v_fmamk_f32 v74, v74, 0x3e0293ee, v99
	v_fmamk_f32 v75, v75, 0x3e0293ee, v99
	v_exp_f32_e32 v73, v73
	v_exp_f32_e32 v74, v74
	v_exp_f32_e32 v75, v75
	s_waitcnt lgkmcnt(2)
	v_mfma_f32_32x32x16_bf16 v[34:49], v[178:181], v[100:103], v[34:49]
	v_fmamk_f32 v76, v76, 0x3e0293ee, v99
	v_fmamk_f32 v77, v77, 0x3e0293ee, v99
	v_fmamk_f32 v78, v78, 0x3e0293ee, v99
	v_exp_f32_e32 v76, v76
	v_exp_f32_e32 v77, v77
	v_exp_f32_e32 v78, v78
	s_waitcnt lgkmcnt(0)
	v_mfma_f32_32x32x16_bf16 v[18:33], v[178:181], v[104:107], v[18:33]
	v_fmamk_f32 v79, v79, 0x3e0293ee, v99
	v_fmamk_f32 v80, v80, 0x3e0293ee, v99
	v_fmac_f32_e32 v99, 0x3e0293ee, v81
	v_exp_f32_e32 v79, v79
	v_exp_f32_e32 v80, v80
	v_exp_f32_e32 v81, v99
	v_cmp_gt_f32_e32 vcc, 1.0, v98
	s_cbranch_vccz .LBB0_743
	s_and_saveexec_b64 s[4:5], s[6:7]
	ds_write_b32 v213, v98 offset:128
	s_or_b64 exec, exec, s[4:5]
	s_waitcnt lgkmcnt(0)
	ds_read_b128 v[100:103], v208 offset:224
	ds_read_b128 v[104:107], v208 offset:192
	ds_read_b128 v[108:111], v208 offset:160
	ds_read_b128 v[112:115], v208 offset:128
	s_waitcnt lgkmcnt(3)
	v_mul_f32_e32 v16, v16, v102
	v_mul_f32_e32 v17, v17, v103
	s_waitcnt lgkmcnt(2)
	v_mul_f32_e32 v12, v12, v106
	v_mul_f32_e32 v13, v13, v107
	s_waitcnt lgkmcnt(1)
	v_mul_f32_e32 v8, v8, v110
	v_mul_f32_e32 v9, v9, v111
	s_waitcnt lgkmcnt(0)
	v_mul_f32_e32 v4, v4, v114
	v_mul_f32_e32 v5, v5, v115
	v_mul_f32_e32 v14, v14, v100
	v_mul_f32_e32 v15, v15, v101
	v_mul_f32_e32 v10, v10, v104
	v_mul_f32_e32 v11, v11, v105
	v_mul_f32_e32 v6, v6, v108
	v_mul_f32_e32 v7, v7, v109
	v_mul_f32_e32 v2, v2, v112
	v_mul_f32_e32 v3, v3, v113
	v_mul_f32_e32 v64, v64, v102
	v_mul_f32_e32 v65, v65, v103
	v_mul_f32_e32 v60, v60, v106
	v_mul_f32_e32 v61, v61, v107
	v_mul_f32_e32 v56, v56, v110
	v_mul_f32_e32 v57, v57, v111
	v_mul_f32_e32 v52, v52, v114
	v_mul_f32_e32 v53, v53, v115
	v_mul_f32_e32 v62, v62, v100
	v_mul_f32_e32 v63, v63, v101
	v_mul_f32_e32 v58, v58, v104
	v_mul_f32_e32 v59, v59, v105
	v_mul_f32_e32 v54, v54, v108
	v_mul_f32_e32 v55, v55, v109
	v_mul_f32_e32 v50, v50, v112
	v_mul_f32_e32 v51, v51, v113
	v_mul_f32_e32 v48, v48, v102
	v_mul_f32_e32 v49, v49, v103
	v_mul_f32_e32 v44, v44, v106
	v_mul_f32_e32 v45, v45, v107
	v_mul_f32_e32 v40, v40, v110
	v_mul_f32_e32 v41, v41, v111
	v_mul_f32_e32 v36, v36, v114
	v_mul_f32_e32 v37, v37, v115
	v_mul_f32_e32 v46, v46, v100
	v_mul_f32_e32 v47, v47, v101
	v_mul_f32_e32 v42, v42, v104
	v_mul_f32_e32 v43, v43, v105
	v_mul_f32_e32 v38, v38, v108
	v_mul_f32_e32 v39, v39, v109
	v_mul_f32_e32 v34, v34, v112
	v_mul_f32_e32 v35, v35, v113
	v_mul_f32_e32 v32, v32, v102
	v_mul_f32_e32 v33, v33, v103
	v_mul_f32_e32 v28, v28, v106
	v_mul_f32_e32 v29, v29, v107
	v_mul_f32_e32 v24, v24, v110
	v_mul_f32_e32 v25, v25, v111
	v_mul_f32_e32 v20, v20, v114
	v_mul_f32_e32 v21, v21, v115
	v_mul_f32_e32 v30, v30, v100
	v_mul_f32_e32 v31, v31, v101
	v_mul_f32_e32 v26, v26, v104
	v_mul_f32_e32 v27, v27, v105
	v_mul_f32_e32 v22, v22, v108
	v_mul_f32_e32 v23, v23, v109
	v_mul_f32_e32 v18, v18, v112
	v_mul_f32_e32 v19, v19, v113

.LBB0_747:
	ds_read_b128 v[98:101], v216 offset:17408
	ds_read_b128 v[102:105], v216 offset:26112
	ds_read_b128 v[162:165], v216 offset:17440
	s_waitcnt vmcnt(0)
	v_add_f32_e32 v174, 0, v82
	v_add_f32_e32 v175, 0, v83
	s_waitcnt lgkmcnt(2)
	v_mfma_f32_32x32x16_bf16 v[114:129], v[98:101], v[158:161], 0
	v_mov_b32_e32 v98, v195
	v_mov_b32_e32 v99, v195
	s_nop 0
	v_add_f32_e32 v176, v84, v98
	v_add_f32_e32 v177, v85, v99
	s_waitcnt lgkmcnt(1)
	v_mfma_f32_32x32x16_bf16 v[98:113], v[102:105], v[158:161], 0
	ds_read_b128 v[166:169], v216 offset:26144
	ds_read_b128 v[170:173], v216 offset:17472
	v_add_f32_e32 v174, v86, v174
	v_add_f32_e32 v175, v87, v175
	v_cvt_pk_bf16_f32 v158, v82, v83
	v_cvt_pk_bf16_f32 v159, v84, v85
	v_cvt_pk_bf16_f32 v160, v86, v87
	v_cvt_pk_bf16_f32 v161, v88, v89
	s_waitcnt lgkmcnt(2)
	v_mfma_f32_32x32x16_bf16 v[114:129], v[162:165], v[154:157], v[114:129]
	v_permlane32_swap_b32_e32 v158, v160
	v_permlane32_swap_b32_e32 v159, v161
	s_waitcnt lgkmcnt(1)
	v_mfma_f32_32x32x16_bf16 v[98:113], v[166:169], v[154:157], v[98:113]
	ds_read_b128 v[82:85], v216 offset:26176
	v_add_f32_e32 v162, v88, v176
	v_add_f32_e32 v163, v89, v177
	ds_read_b128 v[86:89], v216 offset:17504
	v_add_f32_e32 v164, v90, v174
	v_add_f32_e32 v165, v91, v175
	s_waitcnt lgkmcnt(2)
	v_mfma_f32_32x32x16_bf16 v[114:129], v[170:173], v[150:153], v[114:129]
	s_waitcnt lgkmcnt(1)
	v_mfma_f32_32x32x16_bf16 v[98:113], v[82:85], v[150:153], v[98:113]
	ds_read_b128 v[154:157], v216 offset:26208
	v_add_f32_e32 v162, v92, v162
	v_add_f32_e32 v163, v93, v163
	ds_read_b128 v[82:85], v216 offset:17536
	v_add_f32_e32 v164, v94, v164
	v_add_f32_e32 v165, v95, v165
	v_cvt_pk_bf16_f32 v150, v90, v91
	v_cvt_pk_bf16_f32 v151, v92, v93
	v_cvt_pk_bf16_f32 v152, v94, v95
	v_cvt_pk_bf16_f32 v153, v96, v97
	s_waitcnt lgkmcnt(2)
	v_mfma_f32_32x32x16_bf16 v[114:129], v[86:89], v[146:149], v[114:129]
	v_permlane32_swap_b32_e32 v150, v152
	v_permlane32_swap_b32_e32 v151, v153
	s_waitcnt lgkmcnt(1)
	v_mfma_f32_32x32x16_bf16 v[98:113], v[154:157], v[146:149], v[98:113]
	ds_read_b128 v[86:89], v216 offset:26240
	v_add_f32_e32 v94, v96, v162
	v_add_f32_e32 v95, v97, v163
	ds_read_b128 v[90:93], v216 offset:17568
	v_add_f32_e32 v96, v66, v164
	v_add_f32_e32 v97, v67, v165
	s_waitcnt lgkmcnt(2)
	v_mfma_f32_32x32x16_bf16 v[114:129], v[82:85], v[142:145], v[114:129]
	s_waitcnt lgkmcnt(1)
	v_mfma_f32_32x32x16_bf16 v[98:113], v[86:89], v[142:145], v[98:113]
	ds_read_b128 v[82:85], v216 offset:26272
	v_add_f32_e32 v94, v68, v94
	v_add_f32_e32 v95, v69, v95
	ds_read_b128 v[86:89], v216 offset:17600
	v_add_f32_e32 v96, v70, v96
	v_add_f32_e32 v97, v71, v97
	v_cvt_pk_bf16_f32 v142, v66, v67
	v_cvt_pk_bf16_f32 v143, v68, v69
	v_cvt_pk_bf16_f32 v144, v70, v71
	v_cvt_pk_bf16_f32 v145, v72, v73
	s_waitcnt lgkmcnt(2)
	v_mfma_f32_32x32x16_bf16 v[114:129], v[90:93], v[138:141], v[114:129]
	v_permlane32_swap_b32_e32 v142, v144
	v_permlane32_swap_b32_e32 v143, v145
	s_waitcnt lgkmcnt(1)
	v_mfma_f32_32x32x16_bf16 v[98:113], v[82:85], v[138:141], v[98:113]
	ds_read_b128 v[66:69], v216 offset:26304
	v_add_f32_e32 v90, v72, v94
	v_add_f32_e32 v91, v73, v95
	ds_read_b128 v[70:73], v216 offset:17632
	v_add_f32_e32 v92, v74, v96
	v_add_f32_e32 v93, v75, v97
	s_waitcnt lgkmcnt(2)
	v_mfma_f32_32x32x16_bf16 v[114:129], v[86:89], v[134:137], v[114:129]
	s_waitcnt lgkmcnt(1)
	v_mfma_f32_32x32x16_bf16 v[98:113], v[66:69], v[134:137], v[98:113]
	ds_read_b128 v[82:85], v216 offset:26336
	v_add_f32_e32 v86, v76, v90
	v_add_f32_e32 v87, v77, v91
	s_nop 0
	v_add_f32_e32 v66, v78, v92
	v_add_f32_e32 v67, v79, v93
	v_cvt_pk_bf16_f32 v134, v74, v75
	v_cvt_pk_bf16_f32 v135, v76, v77
	v_cvt_pk_bf16_f32 v136, v78, v79
	v_cvt_pk_bf16_f32 v137, v80, v81
	s_waitcnt lgkmcnt(1)
	v_mfma_f32_32x32x16_bf16 v[114:129], v[70:73], v[130:133], v[114:129]
	v_permlane32_swap_b32_e32 v134, v136
	v_permlane32_swap_b32_e32 v135, v137
	s_waitcnt lgkmcnt(0)
	v_mfma_f32_32x32x16_bf16 v[98:113], v[82:85], v[130:133], v[98:113]
	v_add_f32_e32 v68, v80, v86
	v_add_f32_e32 v69, v81, v87
	s_nop 0
	v_add_f32_e32 v66, v66, v67
	v_add_f32_e32 v67, v68, v69
	v_add_u32_e32 v132, s45, v211
	v_add_f32_e32 v130, v66, v67
	v_lshl_or_b32 v82, s43, 6, v207
	ds_read_b64_tr_b16 v[66:67], v132
	ds_read_b64_tr_b16 v[68:69], v132 offset:2048
	ds_read_b64_tr_b16 v[70:71], v132 offset:512
	ds_read_b64_tr_b16 v[74:75], v132 offset:1024
	ds_read_b64_tr_b16 v[72:73], v132 offset:2560
	ds_read_b64_tr_b16 v[76:77], v132 offset:3072
	s_waitcnt lgkmcnt(4)
	v_mfma_f32_32x32x16_bf16 v[2:17], v[158:161], v[66:69], v[2:17]
	v_sub_u32_e32 v66, v214, v82
	v_cmp_lt_u32_e32 vcc, s30, v66
	v_sub_u32_e32 v67, v82, v214
	v_or_b32_e32 v68, 2, v82
	v_cndmask_b32_e32 v66, v1, v114, vcc
	v_cmp_gt_u32_e32 vcc, s31, v67
	v_sub_u32_e32 v69, v214, v68
	v_or_b32_e32 v133, 8, v82
	v_cndmask_b32_e32 v83, v1, v115, vcc
	v_cmp_lt_u32_e32 vcc, s30, v69
	v_or_b32_e32 v69, 3, v82
	v_sub_u32_e32 v78, v214, v69
	v_cndmask_b32_e32 v84, v1, v116, vcc
	v_cmp_lt_u32_e32 vcc, s30, v78
	v_sub_u32_e32 v78, v214, v133
	v_max3_f32 v67, v66, s34, v83
	v_cndmask_b32_e32 v85, v1, v117, vcc
	v_cmp_lt_u32_e32 vcc, s30, v78
	v_max3_f32 v67, v67, v84, v85
	v_mov_b32_e32 v131, v130
	v_cndmask_b32_e32 v86, v1, v118, vcc
	v_or_b32_e32 v118, 9, v82
	v_sub_u32_e32 v78, v214, v118
	v_cmp_lt_u32_e32 vcc, s30, v78
	v_permlane32_swap_b32_e32 v130, v131
	s_nop 0
	v_cndmask_b32_e32 v87, v1, v119, vcc
	v_or_b32_e32 v119, 10, v82
	v_sub_u32_e32 v78, v214, v119
	v_cmp_lt_u32_e32 vcc, s30, v78
	v_max3_f32 v67, v67, v86, v87
	s_nop 0
	v_cndmask_b32_e32 v88, v1, v120, vcc
	v_or_b32_e32 v120, 11, v82
	v_sub_u32_e32 v78, v214, v120
	v_cmp_lt_u32_e32 vcc, s30, v78
	s_nop 1
	v_cndmask_b32_e32 v89, v1, v121, vcc
	v_max3_f32 v67, v67, v88, v89
	v_or_b32_e32 v121, 16, v82
	v_sub_u32_e32 v90, v214, v121
	v_cmp_lt_u32_e32 vcc, s30, v90
	s_waitcnt lgkmcnt(1)
	v_mfma_f32_32x32x16_bf16 v[50:65], v[158:161], v[70:73], v[50:65]
	ds_read_b64_tr_b16 v[78:79], v132 offset:1536
	ds_read_b64_tr_b16 v[80:81], v132 offset:3584
	v_cndmask_b32_e32 v90, v1, v122, vcc
	v_or_b32_e32 v122, 17, v82
	v_sub_u32_e32 v70, v214, v122
	v_cmp_lt_u32_e32 vcc, s30, v70
	s_nop 1
	v_cndmask_b32_e32 v91, v1, v123, vcc
	v_or_b32_e32 v123, 18, v82
	v_sub_u32_e32 v70, v214, v123
	v_cmp_lt_u32_e32 vcc, s30, v70
	v_max3_f32 v67, v67, v90, v91
	s_nop 0
	v_cndmask_b32_e32 v92, v1, v124, vcc
	v_or_b32_e32 v124, 19, v82
	v_sub_u32_e32 v70, v214, v124
	v_cmp_lt_u32_e32 vcc, s30, v70
	s_nop 1
	v_cndmask_b32_e32 v93, v1, v125, vcc
	v_or_b32_e32 v125, 24, v82
	v_sub_u32_e32 v70, v214, v125
	v_cmp_lt_u32_e32 vcc, s30, v70
	v_max3_f32 v67, v67, v92, v93
	s_nop 0
	v_cndmask_b32_e32 v94, v1, v126, vcc
	v_or_b32_e32 v126, 25, v82
	v_sub_u32_e32 v70, v214, v126
	v_cmp_lt_u32_e32 vcc, s30, v70
	s_nop 1
	v_cndmask_b32_e32 v95, v1, v127, vcc
	v_or_b32_e32 v127, 26, v82
	v_sub_u32_e32 v70, v214, v127
	v_cmp_lt_u32_e32 vcc, s30, v70
	v_max3_f32 v67, v67, v94, v95
	s_nop 0
	v_cndmask_b32_e32 v96, v1, v128, vcc
	v_or_b32_e32 v128, 27, v82
	v_sub_u32_e32 v70, v214, v128
	v_cmp_lt_u32_e32 vcc, s30, v70
	s_nop 1
	v_cndmask_b32_e32 v97, v1, v129, vcc
	v_max3_f32 v70, v67, v96, v97
	v_sub_u32_e32 v67, v215, v82
	v_cmp_lt_u32_e32 vcc, s30, v67
	v_sub_u32_e32 v67, v82, v215
	v_sub_u32_e32 v68, v215, v68
	v_cndmask_b32_e32 v129, v1, v98, vcc
	v_cmp_gt_u32_e32 vcc, s31, v67
	v_sub_u32_e32 v69, v215, v69
	s_waitcnt lgkmcnt(2)
	v_mfma_f32_32x32x16_bf16 v[34:49], v[158:161], v[74:77], v[34:49]
	v_cndmask_b32_e32 v67, v1, v99, vcc
	v_cmp_lt_u32_e32 vcc, s30, v68
	v_max3_f32 v70, v70, v129, v67
	v_sub_u32_e32 v71, v215, v118
	v_cndmask_b32_e32 v68, v1, v100, vcc
	v_cmp_lt_u32_e32 vcc, s30, v69
	ds_read_b64_tr_b16 v[114:115], v132 offset:4096
	ds_read_b64_tr_b16 v[116:117], v132 offset:6144
	v_cndmask_b32_e32 v69, v1, v101, vcc
	v_max3_f32 v72, v70, v68, v69
	v_sub_u32_e32 v70, v215, v133
	v_cmp_lt_u32_e32 vcc, s30, v70
	v_sub_u32_e32 v73, v215, v120
	s_nop 0
	v_cndmask_b32_e32 v70, v1, v102, vcc
	v_cmp_lt_u32_e32 vcc, s30, v71
	s_nop 1
	v_cndmask_b32_e32 v71, v1, v103, vcc
	v_max3_f32 v74, v72, v70, v71
	v_sub_u32_e32 v72, v215, v119
	v_cmp_lt_u32_e32 vcc, s30, v72
	s_nop 1
	v_cndmask_b32_e32 v72, v1, v104, vcc
	v_cmp_lt_u32_e32 vcc, s30, v73
	s_nop 1
	v_cndmask_b32_e32 v73, v1, v105, vcc
	v_max3_f32 v82, v74, v72, v73
	v_sub_u32_e32 v74, v215, v121
	v_cmp_lt_u32_e32 vcc, s30, v74
	v_sub_u32_e32 v75, v215, v122
	v_sub_u32_e32 v76, v215, v123
	v_cndmask_b32_e32 v74, v1, v106, vcc
	v_cmp_lt_u32_e32 vcc, s30, v75
	s_waitcnt lgkmcnt(2)
	v_mfma_f32_32x32x16_bf16 v[18:33], v[158:161], v[78:81], v[18:33]
	v_sub_u32_e32 v77, v215, v124
	v_cndmask_b32_e32 v75, v1, v107, vcc
	v_cmp_lt_u32_e32 vcc, s30, v76
	v_sub_u32_e32 v78, v215, v125
	v_sub_u32_e32 v79, v215, v126
	v_cndmask_b32_e32 v76, v1, v108, vcc
	v_cmp_lt_u32_e32 vcc, s30, v77
	ds_read_b64_tr_b16 v[100:101], v132 offset:4608
	ds_read_b64_tr_b16 v[102:103], v132 offset:6656
	v_cndmask_b32_e32 v77, v1, v109, vcc
	v_cmp_lt_u32_e32 vcc, s30, v78
	v_sub_u32_e32 v80, v215, v127
	v_sub_u32_e32 v81, v215, v128
	v_cndmask_b32_e32 v78, v1, v110, vcc
	v_cmp_lt_u32_e32 vcc, s30, v79
	v_max3_f32 v82, v82, v74, v75
	v_max3_f32 v82, v82, v76, v77
	v_cndmask_b32_e32 v79, v1, v111, vcc
	v_cmp_lt_u32_e32 vcc, s30, v80
	v_max3_f32 v82, v82, v78, v79
	s_nop 0
	v_cndmask_b32_e32 v80, v1, v112, vcc
	v_cmp_lt_u32_e32 vcc, s30, v81
	s_nop 1
	v_cndmask_b32_e32 v81, v1, v113, vcc
	v_max3_f32 v82, v82, v80, v81
	s_nop 0
	v_mov_b32_e32 v98, v82
	s_nop 1
	v_permlane32_swap_b32_e32 v82, v98
	v_max_f32_e32 v98, v98, v98
	v_max_f32_e32 v82, v82, v82
	v_max_f32_e32 v82, v82, v98
	v_sub_f32_e32 v98, v82, v225
	s_waitcnt lgkmcnt(2)
	v_mfma_f32_32x32x16_bf16 v[2:17], v[150:153], v[114:117], v[2:17]
	v_cmp_ge_f32_e32 vcc, s35, v98
	s_cmp_eq_u64 vcc, exec
	v_max_f32_e32 v98, v225, v225
	ds_read_b64_tr_b16 v[104:105], v132 offset:5120
	ds_read_b64_tr_b16 v[106:107], v132 offset:7168
	v_max_f32_e32 v82, v98, v82
	s_cselect_b64 vcc, -1, 0
	v_cndmask_b32_e32 v82, v82, v225, vcc
	v_sub_f32_e32 v98, v225, v82
	v_mul_f32_e32 v98, 0x3e0293ee, v98
	v_exp_f32_e32 v98, v98
	v_fma_f32 v99, v82, s36, 0
	s_waitcnt lgkmcnt(2)
	v_mfma_f32_32x32x16_bf16 v[50:65], v[150:153], v[100:103], v[50:65]
	ds_read_b64_tr_b16 v[108:109], v132 offset:5632
	ds_read_b64_tr_b16 v[110:111], v132 offset:7680
	v_fmamk_f32 v66, v66, 0x3e0293ee, v99
	v_exp_f32_e32 v82, v66
	v_fmamk_f32 v66, v83, 0x3e0293ee, v99
	v_exp_f32_e32 v83, v66
	s_waitcnt lgkmcnt(2)
	v_mfma_f32_32x32x16_bf16 v[34:49], v[150:153], v[104:107], v[34:49]
	ds_read_b64_tr_b16 v[100:101], v132 offset:8192
	ds_read_b64_tr_b16 v[102:103], v132 offset:10240
	v_fmamk_f32 v66, v84, 0x3e0293ee, v99
	v_exp_f32_e32 v84, v66
	v_fmamk_f32 v66, v85, 0x3e0293ee, v99
	v_exp_f32_e32 v85, v66
	v_fmamk_f32 v66, v86, 0x3e0293ee, v99
	v_exp_f32_e32 v86, v66
	s_waitcnt lgkmcnt(2)
	v_mfma_f32_32x32x16_bf16 v[18:33], v[150:153], v[108:111], v[18:33]
	ds_read_b64_tr_b16 v[104:105], v132 offset:8704
	ds_read_b64_tr_b16 v[106:107], v132 offset:10752
	v_fmamk_f32 v66, v87, 0x3e0293ee, v99
	v_exp_f32_e32 v87, v66
	v_fmamk_f32 v66, v88, 0x3e0293ee, v99
	v_exp_f32_e32 v88, v66
	v_fmamk_f32 v66, v89, 0x3e0293ee, v99
	v_exp_f32_e32 v89, v66
	s_waitcnt lgkmcnt(2)
	v_mfma_f32_32x32x16_bf16 v[2:17], v[142:145], v[100:103], v[2:17]
	ds_read_b64_tr_b16 v[108:109], v132 offset:9216
	ds_read_b64_tr_b16 v[110:111], v132 offset:11264
	v_fmamk_f32 v66, v90, 0x3e0293ee, v99
	v_exp_f32_e32 v90, v66
	v_fmamk_f32 v66, v91, 0x3e0293ee, v99
	v_exp_f32_e32 v91, v66
	v_fmamk_f32 v66, v92, 0x3e0293ee, v99
	v_exp_f32_e32 v92, v66
	s_waitcnt lgkmcnt(2)
	v_mfma_f32_32x32x16_bf16 v[50:65], v[142:145], v[104:107], v[50:65]
	ds_read_b64_tr_b16 v[100:101], v132 offset:9728
	ds_read_b64_tr_b16 v[102:103], v132 offset:11776
	v_fmamk_f32 v66, v93, 0x3e0293ee, v99
	v_exp_f32_e32 v93, v66
	v_fmamk_f32 v66, v94, 0x3e0293ee, v99
	v_exp_f32_e32 v94, v66
	v_fmamk_f32 v66, v95, 0x3e0293ee, v99
	v_exp_f32_e32 v95, v66
	s_waitcnt lgkmcnt(2)
	v_mfma_f32_32x32x16_bf16 v[34:49], v[142:145], v[108:111], v[34:49]
	ds_read_b64_tr_b16 v[104:105], v132 offset:12288
	ds_read_b64_tr_b16 v[106:107], v132 offset:14336
	v_fmamk_f32 v66, v96, 0x3e0293ee, v99
	v_exp_f32_e32 v96, v66
	v_fmamk_f32 v66, v97, 0x3e0293ee, v99
	v_exp_f32_e32 v97, v66
	v_fmamk_f32 v66, v129, 0x3e0293ee, v99
	v_exp_f32_e32 v66, v66
	s_waitcnt lgkmcnt(2)
	v_mfma_f32_32x32x16_bf16 v[18:33], v[142:145], v[100:103], v[18:33]
	ds_read_b64_tr_b16 v[108:109], v132 offset:12800
	ds_read_b64_tr_b16 v[110:111], v132 offset:14848
	v_fmamk_f32 v67, v67, 0x3e0293ee, v99
	v_fmamk_f32 v68, v68, 0x3e0293ee, v99
	v_fmamk_f32 v69, v69, 0x3e0293ee, v99
	v_exp_f32_e32 v67, v67
	v_exp_f32_e32 v68, v68
	v_exp_f32_e32 v69, v69
	s_waitcnt lgkmcnt(2)
	v_mfma_f32_32x32x16_bf16 v[2:17], v[134:137], v[104:107], v[2:17]
	ds_read_b64_tr_b16 v[100:101], v132 offset:13312
	ds_read_b64_tr_b16 v[102:103], v132 offset:15360
	v_fmamk_f32 v70, v70, 0x3e0293ee, v99
	v_fmamk_f32 v71, v71, 0x3e0293ee, v99
	v_fmamk_f32 v72, v72, 0x3e0293ee, v99
	v_exp_f32_e32 v70, v70
	v_exp_f32_e32 v71, v71
	v_exp_f32_e32 v72, v72
	s_waitcnt lgkmcnt(2)
	v_mfma_f32_32x32x16_bf16 v[50:65], v[134:137], v[108:111], v[50:65]
	ds_read_b64_tr_b16 v[104:105], v132 offset:13824
	ds_read_b64_tr_b16 v[106:107], v132 offset:15872
	v_fmamk_f32 v73, v73, 0x3e0293ee, v99
	v_fmamk_f32 v74, v74, 0x3e0293ee, v99
	v_fmamk_f32 v75, v75, 0x3e0293ee, v99
	v_exp_f32_e32 v73, v73
	v_exp_f32_e32 v74, v74
	v_exp_f32_e32 v75, v75
	s_waitcnt lgkmcnt(2)
	v_mfma_f32_32x32x16_bf16 v[34:49], v[134:137], v[100:103], v[34:49]
	v_fmamk_f32 v76, v76, 0x3e0293ee, v99
	v_fmamk_f32 v77, v77, 0x3e0293ee, v99
	v_fmamk_f32 v78, v78, 0x3e0293ee, v99
	v_exp_f32_e32 v76, v76
	v_exp_f32_e32 v77, v77
	v_exp_f32_e32 v78, v78
	s_waitcnt lgkmcnt(0)
	v_mfma_f32_32x32x16_bf16 v[18:33], v[134:137], v[104:107], v[18:33]
	v_fmamk_f32 v79, v79, 0x3e0293ee, v99
	v_fmamk_f32 v80, v80, 0x3e0293ee, v99
	v_fmac_f32_e32 v99, 0x3e0293ee, v81
	v_exp_f32_e32 v79, v79
	v_exp_f32_e32 v80, v80
	v_exp_f32_e32 v81, v99
	v_cmp_gt_f32_e32 vcc, 1.0, v98
	s_cbranch_vccz .LBB0_751
	v_cmp_gt_u32_e32 vcc, 32, v194
	s_and_saveexec_b64 s[4:5], vcc
	ds_write_b32 v213, v98 offset:128
	s_or_b64 exec, exec, s[4:5]
	s_waitcnt lgkmcnt(0)
	ds_read_b128 v[100:103], v208 offset:224
	ds_read_b128 v[104:107], v208 offset:192
	ds_read_b128 v[108:111], v208 offset:160
	ds_read_b128 v[112:115], v208 offset:128
	s_waitcnt lgkmcnt(3)
	v_mul_f32_e32 v16, v16, v102
	v_mul_f32_e32 v17, v17, v103
	s_waitcnt lgkmcnt(2)
	v_mul_f32_e32 v12, v12, v106
	v_mul_f32_e32 v13, v13, v107
	s_waitcnt lgkmcnt(1)
	v_mul_f32_e32 v8, v8, v110
	v_mul_f32_e32 v9, v9, v111
	s_waitcnt lgkmcnt(0)
	v_mul_f32_e32 v4, v4, v114
	v_mul_f32_e32 v5, v5, v115
	v_mul_f32_e32 v14, v14, v100
	v_mul_f32_e32 v15, v15, v101
	v_mul_f32_e32 v10, v10, v104
	v_mul_f32_e32 v11, v11, v105
	v_mul_f32_e32 v6, v6, v108
	v_mul_f32_e32 v7, v7, v109
	v_mul_f32_e32 v2, v2, v112
	v_mul_f32_e32 v3, v3, v113
	v_mul_f32_e32 v64, v64, v102
	v_mul_f32_e32 v65, v65, v103
	v_mul_f32_e32 v60, v60, v106
	v_mul_f32_e32 v61, v61, v107
	v_mul_f32_e32 v56, v56, v110
	v_mul_f32_e32 v57, v57, v111
	v_mul_f32_e32 v52, v52, v114
	v_mul_f32_e32 v53, v53, v115
	v_mul_f32_e32 v62, v62, v100
	v_mul_f32_e32 v63, v63, v101
	v_mul_f32_e32 v58, v58, v104
	v_mul_f32_e32 v59, v59, v105
	v_mul_f32_e32 v54, v54, v108
	v_mul_f32_e32 v55, v55, v109
	v_mul_f32_e32 v50, v50, v112
	v_mul_f32_e32 v51, v51, v113
	v_mul_f32_e32 v48, v48, v102
	v_mul_f32_e32 v49, v49, v103
	v_mul_f32_e32 v44, v44, v106
	v_mul_f32_e32 v45, v45, v107
	v_mul_f32_e32 v40, v40, v110
	v_mul_f32_e32 v41, v41, v111
	v_mul_f32_e32 v36, v36, v114
	v_mul_f32_e32 v37, v37, v115
	v_mul_f32_e32 v46, v46, v100
	v_mul_f32_e32 v47, v47, v101
	v_mul_f32_e32 v42, v42, v104
	v_mul_f32_e32 v43, v43, v105
	v_mul_f32_e32 v38, v38, v108
	v_mul_f32_e32 v39, v39, v109
	v_mul_f32_e32 v34, v34, v112
	v_mul_f32_e32 v35, v35, v113
	v_mul_f32_e32 v32, v32, v102
	v_mul_f32_e32 v33, v33, v103
	v_mul_f32_e32 v28, v28, v106
	v_mul_f32_e32 v29, v29, v107
	v_mul_f32_e32 v24, v24, v110
	v_mul_f32_e32 v25, v25, v111
	v_mul_f32_e32 v20, v20, v114
	v_mul_f32_e32 v21, v21, v115
	v_mul_f32_e32 v30, v30, v100
	v_mul_f32_e32 v31, v31, v101
	v_mul_f32_e32 v26, v26, v104
	v_mul_f32_e32 v27, v27, v105
	v_mul_f32_e32 v22, v22, v108
	v_mul_f32_e32 v23, v23, v109
	v_mul_f32_e32 v18, v18, v112
	v_mul_f32_e32 v19, v19, v113

.LBB0_858:
	s_cmpk_lg_i32 s62, 0x800
	s_cbranch_scc1 .LBB0_857
	v_mov_b32_e32 v3, v0
	s_mov_b32 s8, 0x358637bd
	v_and_or_b32 v136, v3, 15, s53
	v_ashrrev_i32_e32 v137, 31, v136
	v_lshlrev_b64 v[4:5], 6, v[136:137]
	v_lshl_add_u64 v[134:135], s[26:27], 0, v[4:5]
	global_load_dwordx4 v[138:141], v[134:135], off offset:32
	global_load_dwordx4 v[142:145], v[134:135], off offset:48
	global_load_dwordx4 v[146:149], v[134:135], off
	global_load_dwordx4 v[166:169], v[134:135], off offset:16
	s_waitcnt vmcnt(0)
	v_add_f32_e32 v138, v138, v142
	v_add_f32_e32 v139, v139, v143
	v_add_f32_e32 v140, v140, v144
	v_add_f32_e32 v141, v141, v145
	v_add_f32_e32 v146, v146, v166
	v_add_f32_e32 v147, v147, v167
	v_add_f32_e32 v4, v148, v168
	v_add_f32_e32 v5, v149, v169
	v_mov_b32_e32 v142, v138
	v_mov_b32_e32 v143, v146
	v_mov_b32_e32 v146, v139
	v_add_f32_e32 v138, v142, v146
	v_add_f32_e32 v139, v143, v147
	v_mov_b32_e32 v142, v140
	v_mov_b32_e32 v143, v4
	v_mov_b32_e32 v4, v141
	v_add_f32_e32 v4, v142, v4
	v_add_f32_e32 v5, v143, v5
	s_nop 0
	v_add_f32_e32 v138, v138, v4
	v_add_f32_e32 v139, v139, v5
	v_mov_b64_e32 v[4:5], s[8:9]
	v_fma_f32 v138, v138, s46, v4
	v_fma_f32 v139, v139, s46, v4
	s_nop 0
	v_div_scale_f32 v3, s[8:9], v139, v139, v138
	v_rcp_f32_e32 v137, v3
	s_nop 0
	v_fma_f32 v140, -v3, v137, 1.0
	v_fmac_f32_e32 v137, v140, v137
	v_div_scale_f32 v140, vcc, v138, v139, v138
	v_mul_f32_e32 v141, v140, v137
	v_fma_f32 v142, -v3, v141, v140
	v_fmac_f32_e32 v141, v142, v137
	v_fma_f32 v3, -v3, v141, v140
	v_div_fmas_f32 v3, v3, v137, v141
	v_div_fixup_f32 v3, v3, v139, v138
	v_cmp_gt_f32_e32 vcc, s50, v3
	v_mul_f32_e32 v137, 0x4f800000, v3
	s_nop 0
	v_cndmask_b32_e32 v3, v3, v137, vcc
	v_sqrt_f32_e32 v137, v3
	s_nop 0
	v_add_u32_e32 v138, -1, v137
	v_fma_f32 v139, -v138, v137, v3
	v_cmp_ge_f32_e64 s[8:9], 0, v139
	v_add_u32_e32 v139, 1, v137
	s_nop 0
	v_cndmask_b32_e64 v138, v137, v138, s[8:9]
	v_fma_f32 v137, -v139, v137, v3
	v_cmp_lt_f32_e64 s[8:9], 0, v137
	s_nop 1
	v_cndmask_b32_e64 v137, v138, v139, s[8:9]
	v_mul_f32_e32 v138, 0x37800000, v137
	v_cndmask_b32_e32 v137, v137, v138, vcc
	v_cmp_class_f32_e32 vcc, v3, v162
	s_nop 1
	v_cndmask_b32_e32 v138, v137, v3, vcc
	v_mul_f32_e32 v132, v132, v138
	v_mul_f32_e32 v133, v133, v138
	v_mul_f32_e32 v130, v130, v138
	v_mul_f32_e32 v131, v131, v138
	v_mul_f32_e32 v128, v128, v138
	v_mul_f32_e32 v129, v129, v138
	v_mul_f32_e32 v126, v126, v138
	v_mul_f32_e32 v127, v127, v138
	v_mul_f32_e32 v124, v124, v138
	v_mul_f32_e32 v125, v125, v138
	v_mul_f32_e32 v122, v122, v138
	v_mul_f32_e32 v123, v123, v138
	v_mul_f32_e32 v120, v120, v138
	v_mul_f32_e32 v121, v121, v138
	v_mul_f32_e32 v118, v118, v138
	v_mul_f32_e32 v119, v119, v138
	v_or_b32_e32 v138, 16, v136
	v_ashrrev_i32_e32 v139, 31, v138
	v_lshlrev_b64 v[138:139], 6, v[138:139]
	v_lshl_add_u64 v[166:167], s[26:27], 0, v[138:139]
	global_load_dwordx4 v[138:141], v[166:167], off offset:32
	global_load_dwordx4 v[142:145], v[166:167], off offset:48
	global_load_dwordx4 v[146:149], v[166:167], off
	s_nop 0
	global_load_dwordx4 v[166:169], v[166:167], off offset:16
	s_waitcnt vmcnt(2)
	v_add_f32_e32 v138, v138, v142
	v_add_f32_e32 v139, v139, v143
	v_add_f32_e32 v140, v140, v144
	v_add_f32_e32 v141, v141, v145
	s_waitcnt vmcnt(0)
	v_add_f32_e32 v146, v146, v166
	v_add_f32_e32 v147, v147, v167
	v_add_f32_e32 v148, v148, v168
	v_add_f32_e32 v149, v149, v169
	v_mov_b32_e32 v142, v138
	v_mov_b32_e32 v143, v146
	v_mov_b32_e32 v146, v139
	v_add_f32_e32 v138, v142, v146
	v_add_f32_e32 v139, v143, v147
	v_mov_b32_e32 v142, v140
	v_mov_b32_e32 v143, v148
	v_mov_b32_e32 v148, v141
	v_add_f32_e32 v140, v142, v148
	v_add_f32_e32 v141, v143, v149
	s_nop 0
	v_add_f32_e32 v138, v138, v140
	v_add_f32_e32 v139, v139, v141
	s_nop 0
	v_fma_f32 v138, v138, s46, v4
	v_fma_f32 v139, v139, s46, v4
	s_nop 0
	v_div_scale_f32 v3, s[8:9], v139, v139, v138
	v_rcp_f32_e32 v137, v3
	s_nop 0
	v_fma_f32 v140, -v3, v137, 1.0
	v_fmac_f32_e32 v137, v140, v137
	v_div_scale_f32 v140, vcc, v138, v139, v138
	v_mul_f32_e32 v141, v140, v137
	v_fma_f32 v142, -v3, v141, v140
	v_fmac_f32_e32 v141, v142, v137
	v_fma_f32 v3, -v3, v141, v140
	v_div_fmas_f32 v3, v3, v137, v141
	v_div_fixup_f32 v3, v3, v139, v138
	v_cmp_gt_f32_e32 vcc, s50, v3
	v_mul_f32_e32 v137, 0x4f800000, v3
	s_nop 0
	v_cndmask_b32_e32 v3, v3, v137, vcc
	v_sqrt_f32_e32 v137, v3
	s_nop 0
	v_add_u32_e32 v138, -1, v137
	v_fma_f32 v139, -v138, v137, v3
	v_cmp_ge_f32_e64 s[8:9], 0, v139
	v_add_u32_e32 v139, 1, v137
	s_nop 0
	v_cndmask_b32_e64 v138, v137, v138, s[8:9]
	v_fma_f32 v137, -v139, v137, v3
	v_cmp_lt_f32_e64 s[8:9], 0, v137
	s_nop 1
	v_cndmask_b32_e64 v137, v138, v139, s[8:9]
	v_mul_f32_e32 v138, 0x37800000, v137
	v_cndmask_b32_e32 v137, v137, v138, vcc
	v_cmp_class_f32_e32 vcc, v3, v162
	s_nop 1
	v_cndmask_b32_e32 v138, v137, v3, vcc
	v_mul_f32_e32 v116, v116, v138
	v_mul_f32_e32 v117, v117, v138
	v_mul_f32_e32 v114, v114, v138
	v_mul_f32_e32 v115, v115, v138
	v_mul_f32_e32 v112, v112, v138
	v_mul_f32_e32 v113, v113, v138
	v_mul_f32_e32 v110, v110, v138
	v_mul_f32_e32 v111, v111, v138
	v_mul_f32_e32 v108, v108, v138
	v_mul_f32_e32 v109, v109, v138
	v_mul_f32_e32 v106, v106, v138
	v_mul_f32_e32 v107, v107, v138
	v_mul_f32_e32 v104, v104, v138
	v_mul_f32_e32 v105, v105, v138
	v_mul_f32_e32 v102, v102, v138
	v_mul_f32_e32 v103, v103, v138
	v_or_b32_e32 v138, 32, v136
	v_ashrrev_i32_e32 v139, 31, v138
	v_lshlrev_b64 v[138:139], 6, v[138:139]
	v_lshl_add_u64 v[166:167], s[26:27], 0, v[138:139]
	global_load_dwordx4 v[138:141], v[166:167], off offset:32
	global_load_dwordx4 v[142:145], v[166:167], off offset:48
	global_load_dwordx4 v[146:149], v[166:167], off
	s_nop 0
	global_load_dwordx4 v[166:169], v[166:167], off offset:16
	v_or_b32_e32 v136, 48, v136
	s_waitcnt vmcnt(2)
	v_add_f32_e32 v138, v138, v142
	v_add_f32_e32 v139, v139, v143
	v_add_f32_e32 v140, v140, v144
	v_add_f32_e32 v141, v141, v145
	s_waitcnt vmcnt(0)
	v_add_f32_e32 v146, v146, v166
	v_add_f32_e32 v147, v147, v167
	v_add_f32_e32 v148, v148, v168
	v_add_f32_e32 v149, v149, v169
	v_mov_b32_e32 v142, v138
	v_mov_b32_e32 v143, v146
	v_mov_b32_e32 v146, v139
	v_add_f32_e32 v138, v142, v146
	v_add_f32_e32 v139, v143, v147
	v_mov_b32_e32 v142, v140
	v_mov_b32_e32 v143, v148
	v_mov_b32_e32 v148, v141
	v_add_f32_e32 v140, v142, v148
	v_add_f32_e32 v141, v143, v149
	s_nop 0
	v_add_f32_e32 v138, v138, v140
	v_add_f32_e32 v139, v139, v141
	s_nop 0
	v_fma_f32 v138, v138, s46, v4
	v_fma_f32 v139, v139, s46, v4
	s_nop 0
	v_div_scale_f32 v3, s[8:9], v139, v139, v138
	v_rcp_f32_e32 v137, v3
	s_nop 0
	v_fma_f32 v140, -v3, v137, 1.0
	v_fmac_f32_e32 v137, v140, v137
	v_div_scale_f32 v140, vcc, v138, v139, v138
	v_mul_f32_e32 v141, v140, v137
	v_fma_f32 v142, -v3, v141, v140
	v_fmac_f32_e32 v141, v142, v137
	v_fma_f32 v3, -v3, v141, v140
	v_div_fmas_f32 v3, v3, v137, v141
	v_div_fixup_f32 v3, v3, v139, v138
	v_cmp_gt_f32_e32 vcc, s50, v3
	v_mul_f32_e32 v137, 0x4f800000, v3
	s_nop 0
	v_cndmask_b32_e32 v3, v3, v137, vcc
	v_sqrt_f32_e32 v137, v3
	s_nop 0
	v_add_u32_e32 v138, -1, v137
	v_fma_f32 v139, -v138, v137, v3
	v_cmp_ge_f32_e64 s[8:9], 0, v139
	v_add_u32_e32 v139, 1, v137
	s_nop 0
	v_cndmask_b32_e64 v138, v137, v138, s[8:9]
	v_fma_f32 v137, -v139, v137, v3
	v_cmp_lt_f32_e64 s[8:9], 0, v137
	s_nop 1
	v_cndmask_b32_e64 v137, v138, v139, s[8:9]
	v_mul_f32_e32 v138, 0x37800000, v137
	v_cndmask_b32_e32 v137, v137, v138, vcc
	v_cmp_class_f32_e32 vcc, v3, v162
	s_nop 1
	v_cndmask_b32_e32 v138, v137, v3, vcc
	v_ashrrev_i32_e32 v137, 31, v136
	v_lshlrev_b64 v[136:137], 6, v[136:137]
	v_lshl_add_u64 v[148:149], s[26:27], 0, v[136:137]
	v_mul_f32_e32 v100, v100, v138
	v_mul_f32_e32 v101, v101, v138
	v_mul_f32_e32 v98, v98, v138
	v_mul_f32_e32 v99, v99, v138
	v_mul_f32_e32 v96, v96, v138
	v_mul_f32_e32 v97, v97, v138
	v_mul_f32_e32 v94, v94, v138
	v_mul_f32_e32 v95, v95, v138
	v_mul_f32_e32 v92, v92, v138
	v_mul_f32_e32 v93, v93, v138
	v_mul_f32_e32 v90, v90, v138
	v_mul_f32_e32 v91, v91, v138
	v_mul_f32_e32 v88, v88, v138
	v_mul_f32_e32 v89, v89, v138
	v_mul_f32_e32 v86, v86, v138
	v_mul_f32_e32 v87, v87, v138
	global_load_dwordx4 v[136:139], v[148:149], off offset:32
	global_load_dwordx4 v[140:143], v[148:149], off offset:48
	global_load_dwordx4 v[144:147], v[148:149], off
	global_load_dwordx4 v[166:169], v[148:149], off offset:16
	s_waitcnt vmcnt(2)
	v_add_f32_e32 v136, v136, v140
	v_add_f32_e32 v137, v137, v141
	v_add_f32_e32 v138, v138, v142
	v_add_f32_e32 v139, v139, v143
	s_waitcnt vmcnt(0)
	v_add_f32_e32 v144, v144, v166
	v_add_f32_e32 v145, v145, v167
	v_add_f32_e32 v146, v146, v168
	v_add_f32_e32 v147, v147, v169
	v_mov_b32_e32 v140, v136
	v_mov_b32_e32 v141, v144
	v_mov_b32_e32 v144, v137
	v_add_f32_e32 v136, v140, v144
	v_add_f32_e32 v137, v141, v145
	v_mov_b32_e32 v140, v138
	v_mov_b32_e32 v141, v146
	v_mov_b32_e32 v146, v139
	v_add_f32_e32 v138, v140, v146
	v_add_f32_e32 v139, v141, v147
	s_nop 0
	v_add_f32_e32 v136, v136, v138
	v_add_f32_e32 v137, v137, v139
	s_nop 0
	v_fma_f32 v136, v136, s46, v4
	v_fma_f32 v137, v137, s46, v4
	s_nop 0
	v_div_scale_f32 v3, s[8:9], v137, v137, v136
	v_rcp_f32_e32 v138, v3
	s_nop 0
	v_fma_f32 v139, -v3, v138, 1.0
	v_fmac_f32_e32 v138, v139, v138
	v_div_scale_f32 v139, vcc, v136, v137, v136
	v_mul_f32_e32 v140, v139, v138
	v_fma_f32 v141, -v3, v140, v139
	v_fmac_f32_e32 v140, v141, v138
	v_fma_f32 v3, -v3, v140, v139
	v_div_fmas_f32 v3, v3, v138, v140
	v_div_fixup_f32 v3, v3, v137, v136
	v_cmp_gt_f32_e32 vcc, s50, v3
	v_mul_f32_e32 v136, 0x4f800000, v3
	s_nop 0
	v_cndmask_b32_e32 v3, v3, v136, vcc
	v_sqrt_f32_e32 v136, v3
	s_nop 0
	v_add_u32_e32 v137, -1, v136
	v_fma_f32 v138, -v137, v136, v3
	v_cmp_ge_f32_e64 s[8:9], 0, v138
	v_add_u32_e32 v138, 1, v136
	s_nop 0
	v_cndmask_b32_e64 v137, v136, v137, s[8:9]
	v_fma_f32 v136, -v138, v136, v3
	v_cmp_lt_f32_e64 s[8:9], 0, v136
	s_nop 1
	v_cndmask_b32_e64 v136, v137, v138, s[8:9]
	v_mul_f32_e32 v137, 0x37800000, v136
	v_cndmask_b32_e32 v136, v136, v137, vcc
	v_cmp_class_f32_e32 vcc, v3, v162
	s_mov_b64 s[8:9], 0x2000
	v_lshl_add_u64 v[166:167], v[134:135], 0, s[8:9]
	v_cndmask_b32_e32 v136, v136, v3, vcc
	s_movk_i32 s8, 0x2000
	v_mul_f32_e32 v84, v84, v136
	v_mul_f32_e32 v85, v85, v136
	v_mul_f32_e32 v82, v82, v136
	v_mul_f32_e32 v83, v83, v136
	v_mul_f32_e32 v80, v80, v136
	v_mul_f32_e32 v81, v81, v136
	v_mul_f32_e32 v78, v78, v136
	v_mul_f32_e32 v79, v79, v136
	v_mul_f32_e32 v76, v76, v136
	v_mul_f32_e32 v77, v77, v136
	v_mul_f32_e32 v74, v74, v136
	v_mul_f32_e32 v75, v75, v136
	v_mul_f32_e32 v72, v72, v136
	v_mul_f32_e32 v73, v73, v136
	v_mul_f32_e32 v70, v70, v136
	v_mul_f32_e32 v71, v71, v136
	v_add_co_u32_e32 v136, vcc, s8, v134
	s_nop 1
	v_addc_co_u32_e32 v137, vcc, 0, v135, vcc
	global_load_dwordx4 v[138:141], v[136:137], off
	global_load_dwordx4 v[142:145], v[166:167], off offset:32
	global_load_dwordx4 v[146:149], v[166:167], off offset:48
	s_nop 0
	global_load_dwordx4 v[166:169], v[166:167], off offset:16
	s_waitcnt vmcnt(1)
	v_add_f32_e32 v144, v144, v148
	v_add_f32_e32 v145, v145, v149
	s_waitcnt vmcnt(0)
	v_add_f32_e32 v140, v140, v168
	v_add_f32_e32 v141, v141, v169
	v_add_f32_e32 v138, v138, v166
	v_add_f32_e32 v139, v139, v167
	v_add_f32_e32 v142, v142, v146
	v_add_f32_e32 v143, v143, v147
	v_mov_b32_e32 v147, v138
	v_mov_b32_e32 v146, v142
	v_mov_b32_e32 v138, v143
	v_mov_b32_e32 v142, v144
	v_mov_b32_e32 v143, v140
	v_mov_b32_e32 v140, v145
	v_add_f32_e32 v138, v146, v138
	v_add_f32_e32 v139, v147, v139
	v_add_f32_e32 v140, v142, v140
	v_add_f32_e32 v141, v143, v141
	s_nop 0
	v_add_f32_e32 v138, v138, v140
	v_add_f32_e32 v139, v139, v141
	s_nop 0
	v_fma_f32 v138, v138, s46, v4
	v_fma_f32 v139, v139, s46, v4
	s_nop 0
	v_div_scale_f32 v3, s[8:9], v139, v139, v138
	v_rcp_f32_e32 v140, v3
	s_nop 0
	v_fma_f32 v141, -v3, v140, 1.0
	v_fmac_f32_e32 v140, v141, v140
	v_div_scale_f32 v141, vcc, v138, v139, v138
	v_mul_f32_e32 v142, v141, v140
	v_fma_f32 v143, -v3, v142, v141
	v_fmac_f32_e32 v142, v143, v140
	v_fma_f32 v3, -v3, v142, v141
	v_div_fmas_f32 v3, v3, v140, v142
	v_div_fixup_f32 v3, v3, v139, v138
	v_cmp_gt_f32_e32 vcc, s50, v3
	v_mul_f32_e32 v138, 0x4f800000, v3
	s_nop 0
	v_cndmask_b32_e32 v3, v3, v138, vcc
	v_sqrt_f32_e32 v138, v3
	s_nop 0
	v_add_u32_e32 v139, -1, v138
	v_fma_f32 v140, -v139, v138, v3
	v_cmp_ge_f32_e64 s[8:9], 0, v140
	v_add_u32_e32 v140, 1, v138
	s_nop 0
	v_cndmask_b32_e64 v139, v138, v139, s[8:9]
	v_fma_f32 v138, -v140, v138, v3
	v_cmp_lt_f32_e64 s[8:9], 0, v138
	s_nop 1
	v_cndmask_b32_e64 v138, v139, v140, s[8:9]
	v_mul_f32_e32 v139, 0x37800000, v138
	v_cndmask_b32_e32 v138, v138, v139, vcc
	v_cmp_class_f32_e32 vcc, v3, v162
	s_mov_b64 s[8:9], 0x2400
	v_lshl_add_u64 v[166:167], v[134:135], 0, s[8:9]
	v_cndmask_b32_e32 v138, v138, v3, vcc
	v_mul_f32_e32 v68, v68, v138
	v_mul_f32_e32 v69, v69, v138
	v_mul_f32_e32 v66, v66, v138
	v_mul_f32_e32 v67, v67, v138
	v_mul_f32_e32 v64, v64, v138
	v_mul_f32_e32 v65, v65, v138
	v_mul_f32_e32 v62, v62, v138
	v_mul_f32_e32 v63, v63, v138
	v_mul_f32_e32 v60, v60, v138
	v_mul_f32_e32 v61, v61, v138
	v_mul_f32_e32 v58, v58, v138
	v_mul_f32_e32 v59, v59, v138
	v_mul_f32_e32 v56, v56, v138
	v_mul_f32_e32 v57, v57, v138
	v_mul_f32_e32 v54, v54, v138
	v_mul_f32_e32 v55, v55, v138
	global_load_dwordx4 v[138:141], v[136:137], off offset:1024
	global_load_dwordx4 v[142:145], v[166:167], off offset:32
	global_load_dwordx4 v[146:149], v[166:167], off offset:48
	s_nop 0
	global_load_dwordx4 v[166:169], v[166:167], off offset:16
	s_waitcnt vmcnt(1)
	v_add_f32_e32 v144, v144, v148
	v_add_f32_e32 v145, v145, v149
	s_waitcnt vmcnt(0)
	v_add_f32_e32 v140, v140, v168
	v_add_f32_e32 v141, v141, v169
	v_add_f32_e32 v138, v138, v166
	v_add_f32_e32 v139, v139, v167
	v_add_f32_e32 v142, v142, v146
	v_add_f32_e32 v143, v143, v147
	v_mov_b32_e32 v147, v138
	v_mov_b32_e32 v146, v142
	v_mov_b32_e32 v138, v143
	v_mov_b32_e32 v142, v144
	v_mov_b32_e32 v143, v140
	v_mov_b32_e32 v140, v145
	v_add_f32_e32 v138, v146, v138
	v_add_f32_e32 v139, v147, v139
	v_add_f32_e32 v140, v142, v140
	v_add_f32_e32 v141, v143, v141
	s_nop 0
	v_add_f32_e32 v138, v138, v140
	v_add_f32_e32 v139, v139, v141
	s_nop 0
	v_fma_f32 v138, v138, s46, v4
	v_fma_f32 v139, v139, s46, v4
	s_nop 0
	v_div_scale_f32 v3, s[8:9], v139, v139, v138
	v_rcp_f32_e32 v140, v3
	s_nop 0
	v_fma_f32 v141, -v3, v140, 1.0
	v_fmac_f32_e32 v140, v141, v140
	v_div_scale_f32 v141, vcc, v138, v139, v138
	v_mul_f32_e32 v142, v141, v140
	v_fma_f32 v143, -v3, v142, v141
	v_fmac_f32_e32 v142, v143, v140
	v_fma_f32 v3, -v3, v142, v141
	v_div_fmas_f32 v3, v3, v140, v142
	v_div_fixup_f32 v3, v3, v139, v138
	v_cmp_gt_f32_e32 vcc, s50, v3
	v_mul_f32_e32 v138, 0x4f800000, v3
	s_nop 0
	v_cndmask_b32_e32 v3, v3, v138, vcc
	v_sqrt_f32_e32 v138, v3
	s_nop 0
	v_add_u32_e32 v139, -1, v138
	v_fma_f32 v140, -v139, v138, v3
	v_cmp_ge_f32_e64 s[8:9], 0, v140
	v_add_u32_e32 v140, 1, v138
	s_nop 0
	v_cndmask_b32_e64 v139, v138, v139, s[8:9]
	v_fma_f32 v138, -v140, v138, v3
	v_cmp_lt_f32_e64 s[8:9], 0, v138
	s_nop 1
	v_cndmask_b32_e64 v138, v139, v140, s[8:9]
	v_mul_f32_e32 v139, 0x37800000, v138
	v_cndmask_b32_e32 v138, v138, v139, vcc
	v_cmp_class_f32_e32 vcc, v3, v162
	s_mov_b64 s[8:9], 0x2800
	v_lshl_add_u64 v[166:167], v[134:135], 0, s[8:9]
	v_cndmask_b32_e32 v138, v138, v3, vcc
	v_mul_f32_e32 v52, v52, v138
	v_mul_f32_e32 v53, v53, v138
	v_mul_f32_e32 v50, v50, v138
	v_mul_f32_e32 v51, v51, v138
	v_mul_f32_e32 v48, v48, v138
	v_mul_f32_e32 v49, v49, v138
	v_mul_f32_e32 v46, v46, v138
	v_mul_f32_e32 v47, v47, v138
	v_mul_f32_e32 v44, v44, v138
	v_mul_f32_e32 v45, v45, v138
	v_mul_f32_e32 v42, v42, v138
	v_mul_f32_e32 v43, v43, v138
	v_mul_f32_e32 v40, v40, v138
	v_mul_f32_e32 v41, v41, v138
	v_mul_f32_e32 v38, v38, v138
	v_mul_f32_e32 v39, v39, v138
	global_load_dwordx4 v[138:141], v[136:137], off offset:2048
	global_load_dwordx4 v[142:145], v[166:167], off offset:32
	global_load_dwordx4 v[146:149], v[166:167], off offset:48
	s_nop 0
	global_load_dwordx4 v[166:169], v[166:167], off offset:16
	s_waitcnt vmcnt(1)
	v_add_f32_e32 v144, v144, v148
	v_add_f32_e32 v145, v145, v149
	s_waitcnt vmcnt(0)
	v_add_f32_e32 v140, v140, v168
	v_add_f32_e32 v141, v141, v169
	v_add_f32_e32 v138, v138, v166
	v_add_f32_e32 v139, v139, v167
	v_add_f32_e32 v142, v142, v146
	v_add_f32_e32 v143, v143, v147
	v_mov_b32_e32 v147, v138
	v_mov_b32_e32 v146, v142
	v_mov_b32_e32 v138, v143
	v_mov_b32_e32 v142, v144
	v_mov_b32_e32 v143, v140
	v_mov_b32_e32 v140, v145
	v_add_f32_e32 v138, v146, v138
	v_add_f32_e32 v139, v147, v139
	v_add_f32_e32 v140, v142, v140
	v_add_f32_e32 v141, v143, v141
	s_nop 0
	v_add_f32_e32 v138, v138, v140
	v_add_f32_e32 v139, v139, v141
	s_nop 0
	v_fma_f32 v138, v138, s46, v4
	v_fma_f32 v139, v139, s46, v4
	s_nop 0
	v_div_scale_f32 v3, s[8:9], v139, v139, v138
	v_rcp_f32_e32 v140, v3
	s_nop 0
	v_fma_f32 v141, -v3, v140, 1.0
	v_fmac_f32_e32 v140, v141, v140
	v_div_scale_f32 v141, vcc, v138, v139, v138
	v_mul_f32_e32 v142, v141, v140
	v_fma_f32 v143, -v3, v142, v141
	v_fmac_f32_e32 v142, v143, v140
	v_fma_f32 v3, -v3, v142, v141
	v_div_fmas_f32 v3, v3, v140, v142
	v_div_fixup_f32 v3, v3, v139, v138
	v_cmp_gt_f32_e32 vcc, s50, v3
	v_mul_f32_e32 v138, 0x4f800000, v3
	s_nop 0
	v_cndmask_b32_e32 v3, v3, v138, vcc
	v_sqrt_f32_e32 v138, v3
	s_nop 0
	v_add_u32_e32 v139, -1, v138
	v_fma_f32 v140, -v139, v138, v3
	v_cmp_ge_f32_e64 s[8:9], 0, v140
	v_add_u32_e32 v140, 1, v138
	s_nop 0
	v_cndmask_b32_e64 v139, v138, v139, s[8:9]
	v_fma_f32 v138, -v140, v138, v3
	v_cmp_lt_f32_e64 s[8:9], 0, v138
	s_nop 1
	v_cndmask_b32_e64 v138, v139, v140, s[8:9]
	v_mul_f32_e32 v139, 0x37800000, v138
	v_cndmask_b32_e32 v138, v138, v139, vcc
	v_cmp_class_f32_e32 vcc, v3, v162
	s_mov_b64 s[8:9], 0x2c00
	v_lshl_add_u64 v[146:147], v[134:135], 0, s[8:9]
	v_cndmask_b32_e32 v138, v138, v3, vcc
	v_mul_f32_e32 v36, v36, v138
	v_mul_f32_e32 v37, v37, v138
	v_mul_f32_e32 v34, v34, v138
	v_mul_f32_e32 v35, v35, v138
	v_mul_f32_e32 v32, v32, v138
	v_mul_f32_e32 v33, v33, v138
	v_mul_f32_e32 v30, v30, v138
	v_mul_f32_e32 v31, v31, v138
	v_mul_f32_e32 v28, v28, v138
	v_mul_f32_e32 v29, v29, v138
	v_mul_f32_e32 v26, v26, v138
	v_mul_f32_e32 v27, v27, v138
	v_mul_f32_e32 v24, v24, v138
	v_mul_f32_e32 v25, v25, v138
	v_mul_f32_e32 v22, v22, v138
	v_mul_f32_e32 v23, v23, v138
	global_load_dwordx4 v[142:145], v[136:137], off offset:3072
	s_nop 0
	global_load_dwordx4 v[134:137], v[146:147], off offset:32
	global_load_dwordx4 v[138:141], v[146:147], off offset:48
	s_nop 0
	global_load_dwordx4 v[146:149], v[146:147], off offset:16
	s_waitcnt vmcnt(1)
	v_add_f32_e32 v134, v134, v138
	v_add_f32_e32 v135, v135, v139
	s_waitcnt vmcnt(0)
	v_add_f32_e32 v142, v142, v146
	v_add_f32_e32 v143, v143, v147
	v_add_f32_e32 v144, v144, v148
	v_add_f32_e32 v145, v145, v149
	v_add_f32_e32 v136, v136, v140
	v_add_f32_e32 v137, v137, v141
	v_mov_b32_e32 v138, v134
	v_mov_b32_e32 v139, v142
	v_mov_b32_e32 v142, v135
	v_add_f32_e32 v134, v138, v142
	v_add_f32_e32 v135, v139, v143
	v_mov_b32_e32 v138, v136
	v_mov_b32_e32 v139, v144
	v_mov_b32_e32 v144, v137
	v_add_f32_e32 v136, v138, v144
	v_add_f32_e32 v137, v139, v145
	s_nop 0
	v_add_f32_e32 v134, v134, v136
	v_add_f32_e32 v135, v135, v137
	s_nop 0
	v_fma_f32 v5, v135, s46, v4
	v_fmac_f32_e32 v4, s46, v134
	s_nop 0
	v_div_scale_f32 v3, s[8:9], v5, v5, v4
	v_rcp_f32_e32 v134, v3
	s_nop 0
	v_fma_f32 v135, -v3, v134, 1.0
	v_fmac_f32_e32 v134, v135, v134
	v_div_scale_f32 v135, vcc, v4, v5, v4
	v_mul_f32_e32 v136, v135, v134
	v_fma_f32 v137, -v3, v136, v135
	v_fmac_f32_e32 v136, v137, v134
	v_fma_f32 v3, -v3, v136, v135
	v_div_fmas_f32 v3, v3, v134, v136
	v_div_fixup_f32 v3, v3, v5, v4
	v_cmp_gt_f32_e32 vcc, s50, v3
	v_mul_f32_e32 v4, 0x4f800000, v3
	s_nop 0
	v_cndmask_b32_e32 v3, v3, v4, vcc
	v_sqrt_f32_e32 v4, v3
	s_nop 0
	v_add_u32_e32 v5, -1, v4
	v_fma_f32 v134, -v5, v4, v3
	v_cmp_ge_f32_e64 s[8:9], 0, v134
	v_add_u32_e32 v134, 1, v4
	s_nop 0
	v_cndmask_b32_e64 v5, v4, v5, s[8:9]
	v_fma_f32 v4, -v134, v4, v3
	v_cmp_lt_f32_e64 s[8:9], 0, v4
	s_nop 1
	v_cndmask_b32_e64 v4, v5, v134, s[8:9]
	v_mul_f32_e32 v5, 0x37800000, v4
	v_cndmask_b32_e32 v4, v4, v5, vcc
	v_cmp_class_f32_e32 vcc, v3, v162
	s_nop 1
	v_cndmask_b32_e32 v4, v4, v3, vcc
	v_mul_f32_e32 v20, v20, v4
	v_mul_f32_e32 v21, v21, v4
	v_mul_f32_e32 v18, v18, v4
	v_mul_f32_e32 v19, v19, v4
	v_mul_f32_e32 v16, v16, v4
	v_mul_f32_e32 v17, v17, v4
	v_mul_f32_e32 v14, v14, v4
	v_mul_f32_e32 v15, v15, v4
	v_mul_f32_e32 v12, v12, v4
	v_mul_f32_e32 v13, v13, v4
	v_mul_f32_e32 v10, v10, v4
	v_mul_f32_e32 v11, v11, v4
	v_mul_f32_e32 v8, v8, v4
	v_mul_f32_e32 v9, v9, v4
	v_mul_f32_e32 v6, v6, v4
	v_mul_f32_e32 v7, v7, v4
	s_branch .LBB0_857

.LBB0_862:
	v_mov_b32_e32 v3, v0
	s_lshl_b32 s4, s65, 8
	v_and_or_b32 v134, v3, 15, s53
	v_ashrrev_i32_e32 v135, 31, v134
	v_lshlrev_b64 v[4:5], 6, v[134:135]
	v_lshl_add_u64 v[4:5], s[26:27], 0, v[4:5]
	global_load_dwordx4 v[136:139], v[4:5], off offset:32
	global_load_dwordx4 v[140:143], v[4:5], off offset:48
	v_lshrrev_b32_e32 v3, 1, v3
	v_and_or_b32 v3, v3, 24, s4
	v_or_b32_e32 v4, s47, v3
	v_lshlrev_b64 v[144:145], 11, v[134:135]
	v_ashrrev_i32_e32 v5, 31, v4
	v_lshl_add_u64 v[144:145], v[144:145], 0, v[4:5]
	v_readlane_b32 s76, v254, 14
	v_lshlrev_b64 v[148:149], 2, v[144:145]
	v_readlane_b32 s77, v254, 15
	v_readlane_b32 s78, v254, 16
	v_readlane_b32 s79, v254, 17
	v_lshl_add_u64 v[160:161], s[76:77], 0, v[148:149]
	global_load_dwordx4 v[144:147], v[160:161], off
	global_load_dwordx4 v[166:169], v[160:161], off offset:16
	v_readlane_b32 s80, v254, 18
	v_readlane_b32 s81, v254, 19
	v_readlane_b32 s82, v254, 20
	v_readlane_b32 s83, v254, 21
	v_readlane_b32 s84, v254, 22
	v_readlane_b32 s85, v254, 23
	v_readlane_b32 s86, v254, 24
	v_readlane_b32 s87, v254, 25
	v_readlane_b32 s88, v254, 26
	v_readlane_b32 s89, v254, 27
	v_readlane_b32 s90, v254, 28
	v_readlane_b32 s91, v254, 29
	s_waitcnt vmcnt(0)
	v_add_f32_e32 v138, v138, v142
	v_add_f32_e32 v139, v139, v143
	v_add_f32_e32 v136, v136, v140
	v_add_f32_e32 v137, v137, v141
	s_nop 0
	v_pk_mov_b32 v[140:141], v[136:137], v[138:139] op_sel:[1,0]
	v_mov_b32_e32 v137, v139
	v_add_f32_e32 v136, v140, v136
	v_add_f32_e32 v137, v141, v137
	s_nop 0
	v_add_f32_e32 v3, v136, v137
	v_fmamk_f32 v3, v3, 0x3a800000, v164
	v_mul_f32_e32 v135, 0x4f800000, v3
	v_cmp_gt_f32_e32 vcc, s50, v3
	s_nop 1
	v_cndmask_b32_e32 v3, v3, v135, vcc
	v_sqrt_f32_e32 v135, v3
	s_nop 0
	v_add_u32_e32 v136, -1, v135
	v_add_u32_e32 v137, 1, v135
	v_fma_f32 v138, -v136, v135, v3
	v_fma_f32 v139, -v137, v135, v3
	v_cmp_ge_f32_e64 s[8:9], 0, v138
	s_nop 1
	v_cndmask_b32_e64 v135, v135, v136, s[8:9]
	v_cmp_lt_f32_e64 s[8:9], 0, v139
	s_nop 1
	v_cndmask_b32_e64 v135, v135, v137, s[8:9]
	v_mul_f32_e32 v136, 0x37800000, v135
	v_cndmask_b32_e32 v135, v135, v136, vcc
	v_cmp_class_f32_e32 vcc, v3, v162
	v_lshl_add_u64 v[136:137], s[22:23], 0, v[148:149]
	v_or_b32_e32 v148, 0x200, v148
	v_cndmask_b32_e32 v3, v135, v3, vcc
	v_div_scale_f32 v135, s[4:5], v3, v3, 1.0
	v_rcp_f32_e32 v138, v135
	v_div_scale_f32 v139, vcc, 1.0, v3, 1.0
	v_fma_f32 v140, -v135, v138, 1.0
	v_fmac_f32_e32 v138, v140, v138
	v_mul_f32_e32 v140, v139, v138
	v_fma_f32 v141, -v135, v140, v139
	v_fmac_f32_e32 v140, v141, v138
	v_fma_f32 v135, -v135, v140, v139
	v_div_fmas_f32 v135, v135, v138, v140
	v_div_fixup_f32 v138, v135, v3, 1.0
	v_mul_f32_e32 v130, v130, v138
	v_mul_f32_e32 v131, v131, v138
	v_mul_f32_e32 v132, v132, v138
	v_mul_f32_e32 v133, v133, v138
	v_mul_f32_e32 v140, v126, v138
	v_mul_f32_e32 v141, v127, v138
	v_mul_f32_e32 v142, v128, v138
	v_mul_f32_e32 v143, v129, v138
	v_fma_f32 v128, v146, s48, v132
	v_fma_f32 v129, v147, s48, v133
	v_fma_f32 v126, v144, s48, v130
	v_fma_f32 v127, v145, s48, v131
	v_fma_f32 v132, v168, s48, v142
	v_fma_f32 v133, v169, s48, v143
	v_fma_f32 v130, v166, s48, v140
	v_fma_f32 v131, v167, s48, v141
	global_store_dwordx4 v[136:137], v[126:129], off
	global_store_dwordx4 v[136:137], v[130:133], off offset:16
	global_load_dwordx4 v[126:129], v[160:161], off offset:512
	s_nop 0
	global_load_dwordx4 v[130:133], v[160:161], off offset:528
	v_or_b32_e32 v136, 16, v134
	v_mul_f32_e32 v124, v124, v138
	v_mul_f32_e32 v125, v125, v138
	v_mul_f32_e32 v122, v122, v138
	v_mul_f32_e32 v123, v123, v138
	v_ashrrev_i32_e32 v137, 31, v136
	v_lshl_add_u64 v[142:143], s[22:23], 0, v[148:149]
	v_mul_f32_e32 v144, v120, v138
	v_mul_f32_e32 v145, v121, v138
	v_mul_f32_e32 v139, v119, v138
	v_mul_f32_e32 v138, v118, v138
	v_lshlrev_b64 v[140:141], 6, v[136:137]
	v_lshl_add_u64 v[140:141], s[26:27], 0, v[140:141]
	s_waitcnt vmcnt(1)
	v_fma_f32 v118, v126, s48, v122
	v_fma_f32 v119, v127, s48, v123
	v_fma_f32 v120, v128, s48, v124
	v_fma_f32 v121, v129, s48, v125
	s_waitcnt vmcnt(0)
	v_fma_f32 v122, v130, s48, v138
	v_fma_f32 v123, v131, s48, v139
	v_fma_f32 v124, v132, s48, v144
	v_fma_f32 v125, v133, s48, v145
	global_store_dwordx4 v[142:143], v[118:121], off
	global_store_dwordx4 v[142:143], v[122:125], off offset:16
	global_load_dwordx4 v[118:121], v[140:141], off offset:32
	global_load_dwordx4 v[122:125], v[140:141], off offset:48
	v_lshlrev_b64 v[126:127], 11, v[136:137]
	v_lshl_add_u64 v[126:127], v[126:127], 0, v[4:5]
	v_lshlrev_b64 v[136:137], 2, v[126:127]
	v_lshl_add_u64 v[138:139], s[76:77], 0, v[136:137]
	global_load_dwordx4 v[126:129], v[138:139], off
	global_load_dwordx4 v[130:133], v[138:139], off offset:16
	s_waitcnt vmcnt(2)
	v_add_f32_e32 v120, v120, v124
	v_add_f32_e32 v121, v121, v125
	v_add_f32_e32 v118, v118, v122
	v_add_f32_e32 v119, v119, v123
	s_nop 0
	v_pk_mov_b32 v[122:123], v[118:119], v[120:121] op_sel:[1,0]
	v_mov_b32_e32 v119, v121
	v_add_f32_e32 v118, v122, v118
	v_add_f32_e32 v119, v123, v119
	s_nop 0
	v_add_f32_e32 v3, v118, v119
	v_fmamk_f32 v3, v3, 0x3a800000, v164
	v_mul_f32_e32 v118, 0x4f800000, v3
	v_cmp_gt_f32_e32 vcc, s50, v3
	s_nop 1
	v_cndmask_b32_e32 v3, v3, v118, vcc
	v_sqrt_f32_e32 v118, v3
	s_nop 0
	v_add_u32_e32 v119, -1, v118
	v_add_u32_e32 v120, 1, v118
	v_fma_f32 v121, -v119, v118, v3
	v_fma_f32 v122, -v120, v118, v3
	v_cmp_ge_f32_e64 s[8:9], 0, v121
	s_nop 1
	v_cndmask_b32_e64 v118, v118, v119, s[8:9]
	v_cmp_lt_f32_e64 s[8:9], 0, v122
	s_nop 1
	v_cndmask_b32_e64 v118, v118, v120, s[8:9]
	v_mul_f32_e32 v119, 0x37800000, v118
	v_cndmask_b32_e32 v118, v118, v119, vcc
	v_cmp_class_f32_e32 vcc, v3, v162
	s_nop 1
	v_cndmask_b32_e32 v3, v118, v3, vcc
	v_div_scale_f32 v120, s[4:5], v3, v3, 1.0
	v_rcp_f32_e32 v121, v120
	v_div_scale_f32 v122, vcc, 1.0, v3, 1.0
	v_lshl_add_u64 v[118:119], s[22:23], 0, v[136:137]
	v_fma_f32 v123, -v120, v121, 1.0
	v_fmac_f32_e32 v121, v123, v121
	v_mul_f32_e32 v123, v122, v121
	v_fma_f32 v124, -v120, v123, v122
	v_fmac_f32_e32 v123, v124, v121
	v_fma_f32 v120, -v120, v123, v122
	v_div_fmas_f32 v120, v120, v121, v123
	v_div_fixup_f32 v120, v120, v3, 1.0
	v_mul_f32_e32 v114, v114, v120
	v_mul_f32_e32 v115, v115, v120
	v_mul_f32_e32 v116, v116, v120
	v_mul_f32_e32 v117, v117, v120
	v_mul_f32_e32 v122, v110, v120
	v_mul_f32_e32 v123, v111, v120
	v_mul_f32_e32 v124, v112, v120
	v_mul_f32_e32 v125, v113, v120
	s_waitcnt vmcnt(1)
	v_fma_f32 v112, v128, s48, v116
	v_fma_f32 v113, v129, s48, v117
	v_fma_f32 v110, v126, s48, v114
	v_fma_f32 v111, v127, s48, v115
	s_waitcnt vmcnt(0)
	v_fma_f32 v116, v132, s48, v124
	v_fma_f32 v117, v133, s48, v125
	v_fma_f32 v114, v130, s48, v122
	v_fma_f32 v115, v131, s48, v123
	global_store_dwordx4 v[118:119], v[110:113], off
	global_store_dwordx4 v[118:119], v[114:117], off offset:16
	global_load_dwordx4 v[110:113], v[138:139], off offset:512
	s_nop 0
	global_load_dwordx4 v[114:117], v[138:139], off offset:528
	v_or_b32_e32 v118, 32, v134
	v_or_b32_e32 v136, 0x200, v136
	v_mul_f32_e32 v108, v108, v120
	v_mul_f32_e32 v109, v109, v120
	v_mul_f32_e32 v106, v106, v120
	v_mul_f32_e32 v107, v107, v120
	v_ashrrev_i32_e32 v119, 31, v118
	v_lshl_add_u64 v[124:125], s[22:23], 0, v[136:137]
	v_mul_f32_e32 v126, v104, v120
	v_mul_f32_e32 v127, v105, v120
	v_mul_f32_e32 v121, v103, v120
	v_mul_f32_e32 v120, v102, v120
	v_lshlrev_b64 v[122:123], 6, v[118:119]
	v_lshl_add_u64 v[122:123], s[26:27], 0, v[122:123]
	s_waitcnt vmcnt(1)
	v_fma_f32 v102, v110, s48, v106
	v_fma_f32 v103, v111, s48, v107
	v_fma_f32 v104, v112, s48, v108
	v_fma_f32 v105, v113, s48, v109
	s_waitcnt vmcnt(0)
	v_fma_f32 v106, v114, s48, v120
	v_fma_f32 v107, v115, s48, v121
	v_fma_f32 v108, v116, s48, v126
	v_fma_f32 v109, v117, s48, v127
	global_store_dwordx4 v[124:125], v[102:105], off
	global_store_dwordx4 v[124:125], v[106:109], off offset:16
	global_load_dwordx4 v[102:105], v[122:123], off offset:32
	global_load_dwordx4 v[106:109], v[122:123], off offset:48
	v_lshlrev_b64 v[110:111], 11, v[118:119]
	v_lshl_add_u64 v[110:111], v[110:111], 0, v[4:5]
	v_lshlrev_b64 v[118:119], 2, v[110:111]
	v_lshl_add_u64 v[120:121], s[76:77], 0, v[118:119]
	global_load_dwordx4 v[110:113], v[120:121], off
	global_load_dwordx4 v[114:117], v[120:121], off offset:16
	s_waitcnt vmcnt(2)
	v_add_f32_e32 v104, v104, v108
	v_add_f32_e32 v105, v105, v109
	v_add_f32_e32 v102, v102, v106
	v_add_f32_e32 v103, v103, v107
	s_nop 0
	v_pk_mov_b32 v[106:107], v[102:103], v[104:105] op_sel:[1,0]
	v_mov_b32_e32 v103, v105
	v_add_f32_e32 v102, v106, v102
	v_add_f32_e32 v103, v107, v103
	s_nop 0
	v_add_f32_e32 v3, v102, v103
	v_fmamk_f32 v3, v3, 0x3a800000, v164
	v_mul_f32_e32 v102, 0x4f800000, v3
	v_cmp_gt_f32_e32 vcc, s50, v3
	s_nop 1
	v_cndmask_b32_e32 v3, v3, v102, vcc
	v_sqrt_f32_e32 v102, v3
	s_nop 0
	v_add_u32_e32 v103, -1, v102
	v_add_u32_e32 v104, 1, v102
	v_fma_f32 v105, -v103, v102, v3
	v_fma_f32 v106, -v104, v102, v3
	v_cmp_ge_f32_e64 s[8:9], 0, v105
	s_nop 1
	v_cndmask_b32_e64 v102, v102, v103, s[8:9]
	v_cmp_lt_f32_e64 s[8:9], 0, v106
	s_nop 1
	v_cndmask_b32_e64 v102, v102, v104, s[8:9]
	v_mul_f32_e32 v103, 0x37800000, v102
	v_cndmask_b32_e32 v102, v102, v103, vcc
	v_cmp_class_f32_e32 vcc, v3, v162
	s_nop 1
	v_cndmask_b32_e32 v3, v102, v3, vcc
	v_div_scale_f32 v104, s[4:5], v3, v3, 1.0
	v_rcp_f32_e32 v105, v104
	v_div_scale_f32 v106, vcc, 1.0, v3, 1.0
	v_lshl_add_u64 v[102:103], s[22:23], 0, v[118:119]
	v_fma_f32 v107, -v104, v105, 1.0
	v_fmac_f32_e32 v105, v107, v105
	v_mul_f32_e32 v107, v106, v105
	v_fma_f32 v108, -v104, v107, v106
	v_fmac_f32_e32 v107, v108, v105
	v_fma_f32 v104, -v104, v107, v106
	v_div_fmas_f32 v104, v104, v105, v107
	v_div_fixup_f32 v104, v104, v3, 1.0
	v_mul_f32_e32 v98, v98, v104
	v_mul_f32_e32 v99, v99, v104
	v_mul_f32_e32 v100, v100, v104
	v_mul_f32_e32 v101, v101, v104
	v_mul_f32_e32 v106, v94, v104
	v_mul_f32_e32 v107, v95, v104
	v_mul_f32_e32 v108, v96, v104
	v_mul_f32_e32 v109, v97, v104
	s_waitcnt vmcnt(1)
	v_fma_f32 v96, v112, s48, v100
	v_fma_f32 v97, v113, s48, v101
	v_fma_f32 v94, v110, s48, v98
	v_fma_f32 v95, v111, s48, v99
	s_waitcnt vmcnt(0)
	v_fma_f32 v100, v116, s48, v108
	v_fma_f32 v101, v117, s48, v109
	v_fma_f32 v98, v114, s48, v106
	v_fma_f32 v99, v115, s48, v107
	global_store_dwordx4 v[102:103], v[94:97], off
	global_store_dwordx4 v[102:103], v[98:101], off offset:16
	global_load_dwordx4 v[94:97], v[120:121], off offset:512
	s_nop 0
	global_load_dwordx4 v[98:101], v[120:121], off offset:528
	v_or_b32_e32 v102, 48, v134
	v_or_b32_e32 v118, 0x200, v118
	v_mul_f32_e32 v92, v92, v104
	v_mul_f32_e32 v93, v93, v104
	v_mul_f32_e32 v90, v90, v104
	v_mul_f32_e32 v91, v91, v104
	v_ashrrev_i32_e32 v103, 31, v102
	v_lshl_add_u64 v[108:109], s[22:23], 0, v[118:119]
	v_mul_f32_e32 v110, v88, v104
	v_mul_f32_e32 v111, v89, v104
	v_mul_f32_e32 v105, v87, v104
	v_mul_f32_e32 v104, v86, v104
	v_lshlrev_b64 v[106:107], 6, v[102:103]
	v_lshl_add_u64 v[106:107], s[26:27], 0, v[106:107]
	s_waitcnt vmcnt(1)
	v_fma_f32 v86, v94, s48, v90
	v_fma_f32 v87, v95, s48, v91
	v_fma_f32 v88, v96, s48, v92
	v_fma_f32 v89, v97, s48, v93
	s_waitcnt vmcnt(0)
	v_fma_f32 v90, v98, s48, v104
	v_fma_f32 v91, v99, s48, v105
	v_fma_f32 v92, v100, s48, v110
	v_fma_f32 v93, v101, s48, v111
	global_store_dwordx4 v[108:109], v[86:89], off
	global_store_dwordx4 v[108:109], v[90:93], off offset:16
	global_load_dwordx4 v[86:89], v[106:107], off offset:32
	global_load_dwordx4 v[90:93], v[106:107], off offset:48
	v_lshlrev_b64 v[94:95], 11, v[102:103]
	v_lshl_add_u64 v[94:95], v[94:95], 0, v[4:5]
	v_lshlrev_b64 v[102:103], 2, v[94:95]
	v_lshl_add_u64 v[104:105], s[76:77], 0, v[102:103]
	global_load_dwordx4 v[94:97], v[104:105], off
	global_load_dwordx4 v[98:101], v[104:105], off offset:16
	s_waitcnt vmcnt(2)
	v_add_f32_e32 v88, v88, v92
	v_add_f32_e32 v89, v89, v93
	v_add_f32_e32 v86, v86, v90
	v_add_f32_e32 v87, v87, v91
	s_nop 0
	v_pk_mov_b32 v[90:91], v[86:87], v[88:89] op_sel:[1,0]
	v_mov_b32_e32 v87, v89
	v_add_f32_e32 v86, v90, v86
	v_add_f32_e32 v87, v91, v87
	s_nop 0
	v_add_f32_e32 v3, v86, v87
	v_fmamk_f32 v3, v3, 0x3a800000, v164
	v_mul_f32_e32 v86, 0x4f800000, v3
	v_cmp_gt_f32_e32 vcc, s50, v3
	s_nop 1
	v_cndmask_b32_e32 v3, v3, v86, vcc
	v_sqrt_f32_e32 v86, v3
	s_nop 0
	v_add_u32_e32 v87, -1, v86
	v_add_u32_e32 v88, 1, v86
	v_fma_f32 v89, -v87, v86, v3
	v_fma_f32 v90, -v88, v86, v3
	v_cmp_ge_f32_e64 s[8:9], 0, v89
	s_nop 1
	v_cndmask_b32_e64 v86, v86, v87, s[8:9]
	v_cmp_lt_f32_e64 s[8:9], 0, v90
	s_nop 1
	v_cndmask_b32_e64 v86, v86, v88, s[8:9]
	v_mul_f32_e32 v87, 0x37800000, v86
	v_cndmask_b32_e32 v86, v86, v87, vcc
	v_cmp_class_f32_e32 vcc, v3, v162
	s_nop 1
	v_cndmask_b32_e32 v3, v86, v3, vcc
	v_div_scale_f32 v88, s[4:5], v3, v3, 1.0
	v_rcp_f32_e32 v89, v88
	v_div_scale_f32 v90, vcc, 1.0, v3, 1.0
	v_lshl_add_u64 v[86:87], s[22:23], 0, v[102:103]
	v_fma_f32 v91, -v88, v89, 1.0
	v_fmac_f32_e32 v89, v91, v89
	v_mul_f32_e32 v91, v90, v89
	v_fma_f32 v92, -v88, v91, v90
	v_fmac_f32_e32 v91, v92, v89
	v_fma_f32 v88, -v88, v91, v90
	v_div_fmas_f32 v88, v88, v89, v91
	v_div_fixup_f32 v88, v88, v3, 1.0
	v_mul_f32_e32 v82, v82, v88
	v_mul_f32_e32 v83, v83, v88
	v_mul_f32_e32 v84, v84, v88
	v_mul_f32_e32 v85, v85, v88
	v_mul_f32_e32 v90, v78, v88
	v_mul_f32_e32 v91, v79, v88
	v_mul_f32_e32 v92, v80, v88
	v_mul_f32_e32 v93, v81, v88
	s_waitcnt vmcnt(1)
	v_fma_f32 v80, v96, s48, v84
	v_fma_f32 v81, v97, s48, v85
	v_fma_f32 v78, v94, s48, v82
	v_fma_f32 v79, v95, s48, v83
	s_waitcnt vmcnt(0)
	v_fma_f32 v84, v100, s48, v92
	v_fma_f32 v85, v101, s48, v93
	v_fma_f32 v82, v98, s48, v90
	v_fma_f32 v83, v99, s48, v91
	global_store_dwordx4 v[86:87], v[78:81], off
	global_store_dwordx4 v[86:87], v[82:85], off offset:16
	global_load_dwordx4 v[78:81], v[104:105], off offset:512
	s_nop 0
	global_load_dwordx4 v[82:85], v[104:105], off offset:528
	v_add_u32_e32 v86, 0x80, v134
	v_or_b32_e32 v102, 0x200, v102
	v_mul_f32_e32 v76, v76, v88
	v_mul_f32_e32 v77, v77, v88
	v_mul_f32_e32 v74, v74, v88
	v_mul_f32_e32 v75, v75, v88
	v_ashrrev_i32_e32 v87, 31, v86
	v_lshl_add_u64 v[92:93], s[22:23], 0, v[102:103]
	v_mul_f32_e32 v94, v72, v88
	v_mul_f32_e32 v95, v73, v88
	v_mul_f32_e32 v89, v71, v88
	v_mul_f32_e32 v88, v70, v88
	v_lshlrev_b64 v[90:91], 6, v[86:87]
	v_lshl_add_u64 v[90:91], s[26:27], 0, v[90:91]
	s_waitcnt vmcnt(1)
	v_fma_f32 v70, v78, s48, v74
	v_fma_f32 v71, v79, s48, v75
	v_fma_f32 v72, v80, s48, v76
	v_fma_f32 v73, v81, s48, v77
	s_waitcnt vmcnt(0)
	v_fma_f32 v74, v82, s48, v88
	v_fma_f32 v75, v83, s48, v89
	v_fma_f32 v76, v84, s48, v94
	v_fma_f32 v77, v85, s48, v95
	global_store_dwordx4 v[92:93], v[70:73], off
	global_store_dwordx4 v[92:93], v[74:77], off offset:16
	global_load_dwordx4 v[70:73], v[90:91], off offset:32
	global_load_dwordx4 v[74:77], v[90:91], off offset:48
	v_lshlrev_b64 v[78:79], 11, v[86:87]
	v_lshl_add_u64 v[78:79], v[78:79], 0, v[4:5]
	v_lshlrev_b64 v[86:87], 2, v[78:79]
	v_lshl_add_u64 v[88:89], s[76:77], 0, v[86:87]
	global_load_dwordx4 v[78:81], v[88:89], off
	global_load_dwordx4 v[82:85], v[88:89], off offset:16
	s_waitcnt vmcnt(2)
	v_add_f32_e32 v72, v72, v76
	v_add_f32_e32 v73, v73, v77
	v_add_f32_e32 v70, v70, v74
	v_add_f32_e32 v71, v71, v75
	s_nop 0
	v_pk_mov_b32 v[74:75], v[70:71], v[72:73] op_sel:[1,0]
	v_mov_b32_e32 v71, v73
	v_add_f32_e32 v70, v74, v70
	v_add_f32_e32 v71, v75, v71
	s_nop 0
	v_add_f32_e32 v3, v70, v71
	v_fmamk_f32 v3, v3, 0x3a800000, v164
	v_mul_f32_e32 v70, 0x4f800000, v3
	v_cmp_gt_f32_e32 vcc, s50, v3
	s_nop 1
	v_cndmask_b32_e32 v3, v3, v70, vcc
	v_sqrt_f32_e32 v70, v3
	s_nop 0
	v_add_u32_e32 v71, -1, v70
	v_add_u32_e32 v72, 1, v70
	v_fma_f32 v73, -v71, v70, v3
	v_fma_f32 v74, -v72, v70, v3
	v_cmp_ge_f32_e64 s[8:9], 0, v73
	s_nop 1
	v_cndmask_b32_e64 v70, v70, v71, s[8:9]
	v_cmp_lt_f32_e64 s[8:9], 0, v74
	s_nop 1
	v_cndmask_b32_e64 v70, v70, v72, s[8:9]
	v_mul_f32_e32 v71, 0x37800000, v70
	v_cndmask_b32_e32 v70, v70, v71, vcc
	v_cmp_class_f32_e32 vcc, v3, v162
	s_nop 1
	v_cndmask_b32_e32 v3, v70, v3, vcc
	v_div_scale_f32 v72, s[4:5], v3, v3, 1.0
	v_rcp_f32_e32 v73, v72
	v_div_scale_f32 v74, vcc, 1.0, v3, 1.0
	v_lshl_add_u64 v[70:71], s[22:23], 0, v[86:87]
	v_fma_f32 v75, -v72, v73, 1.0
	v_fmac_f32_e32 v73, v75, v73
	v_mul_f32_e32 v75, v74, v73
	v_fma_f32 v76, -v72, v75, v74
	v_fmac_f32_e32 v75, v76, v73
	v_fma_f32 v72, -v72, v75, v74
	v_div_fmas_f32 v72, v72, v73, v75
	v_div_fixup_f32 v72, v72, v3, 1.0
	v_mul_f32_e32 v66, v66, v72
	v_mul_f32_e32 v67, v67, v72
	v_mul_f32_e32 v68, v68, v72
	v_mul_f32_e32 v69, v69, v72
	v_mul_f32_e32 v74, v62, v72
	v_mul_f32_e32 v75, v63, v72
	v_mul_f32_e32 v76, v64, v72
	v_mul_f32_e32 v77, v65, v72
	s_waitcnt vmcnt(1)
	v_fma_f32 v64, v80, s48, v68
	v_fma_f32 v65, v81, s48, v69
	v_fma_f32 v62, v78, s48, v66
	v_fma_f32 v63, v79, s48, v67
	s_waitcnt vmcnt(0)
	v_fma_f32 v68, v84, s48, v76
	v_fma_f32 v69, v85, s48, v77
	v_fma_f32 v66, v82, s48, v74
	v_fma_f32 v67, v83, s48, v75
	global_store_dwordx4 v[70:71], v[62:65], off
	global_store_dwordx4 v[70:71], v[66:69], off offset:16
	global_load_dwordx4 v[62:65], v[88:89], off offset:512
	s_nop 0
	global_load_dwordx4 v[66:69], v[88:89], off offset:528
	v_add_u32_e32 v70, 0x90, v134
	v_or_b32_e32 v86, 0x200, v86
	v_mul_f32_e32 v60, v60, v72
	v_mul_f32_e32 v61, v61, v72
	v_mul_f32_e32 v58, v58, v72
	v_mul_f32_e32 v59, v59, v72
	v_ashrrev_i32_e32 v71, 31, v70
	v_lshl_add_u64 v[76:77], s[22:23], 0, v[86:87]
	v_mul_f32_e32 v78, v56, v72
	v_mul_f32_e32 v79, v57, v72
	v_mul_f32_e32 v73, v55, v72
	v_mul_f32_e32 v72, v54, v72
	v_lshlrev_b64 v[74:75], 6, v[70:71]
	v_lshl_add_u64 v[74:75], s[26:27], 0, v[74:75]
	s_waitcnt vmcnt(1)
	v_fma_f32 v54, v62, s48, v58
	v_fma_f32 v55, v63, s48, v59
	v_fma_f32 v56, v64, s48, v60
	v_fma_f32 v57, v65, s48, v61
	s_waitcnt vmcnt(0)
	v_fma_f32 v58, v66, s48, v72
	v_fma_f32 v59, v67, s48, v73
	v_fma_f32 v60, v68, s48, v78
	v_fma_f32 v61, v69, s48, v79
	global_store_dwordx4 v[76:77], v[54:57], off
	global_store_dwordx4 v[76:77], v[58:61], off offset:16
	global_load_dwordx4 v[54:57], v[74:75], off offset:32
	global_load_dwordx4 v[58:61], v[74:75], off offset:48
	v_lshlrev_b64 v[62:63], 11, v[70:71]
	v_lshl_add_u64 v[62:63], v[62:63], 0, v[4:5]
	v_lshlrev_b64 v[70:71], 2, v[62:63]
	v_lshl_add_u64 v[72:73], s[76:77], 0, v[70:71]
	global_load_dwordx4 v[62:65], v[72:73], off
	global_load_dwordx4 v[66:69], v[72:73], off offset:16
	s_waitcnt vmcnt(2)
	v_add_f32_e32 v56, v56, v60
	v_add_f32_e32 v57, v57, v61
	v_add_f32_e32 v54, v54, v58
	v_add_f32_e32 v55, v55, v59
	s_nop 0
	v_pk_mov_b32 v[58:59], v[54:55], v[56:57] op_sel:[1,0]
	v_mov_b32_e32 v55, v57
	v_add_f32_e32 v54, v58, v54
	v_add_f32_e32 v55, v59, v55
	s_nop 0
	v_add_f32_e32 v3, v54, v55
	v_fmamk_f32 v3, v3, 0x3a800000, v164
	v_mul_f32_e32 v54, 0x4f800000, v3
	v_cmp_gt_f32_e32 vcc, s50, v3
	s_nop 1
	v_cndmask_b32_e32 v3, v3, v54, vcc
	v_sqrt_f32_e32 v54, v3
	s_nop 0
	v_add_u32_e32 v55, -1, v54
	v_add_u32_e32 v56, 1, v54
	v_fma_f32 v57, -v55, v54, v3
	v_fma_f32 v58, -v56, v54, v3
	v_cmp_ge_f32_e64 s[8:9], 0, v57
	s_nop 1
	v_cndmask_b32_e64 v54, v54, v55, s[8:9]
	v_cmp_lt_f32_e64 s[8:9], 0, v58
	s_nop 1
	v_cndmask_b32_e64 v54, v54, v56, s[8:9]
	v_mul_f32_e32 v55, 0x37800000, v54
	v_cndmask_b32_e32 v54, v54, v55, vcc
	v_cmp_class_f32_e32 vcc, v3, v162
	s_nop 1
	v_cndmask_b32_e32 v3, v54, v3, vcc
	v_div_scale_f32 v56, s[4:5], v3, v3, 1.0
	v_rcp_f32_e32 v57, v56
	v_div_scale_f32 v58, vcc, 1.0, v3, 1.0
	v_lshl_add_u64 v[54:55], s[22:23], 0, v[70:71]
	v_fma_f32 v59, -v56, v57, 1.0
	v_fmac_f32_e32 v57, v59, v57
	v_mul_f32_e32 v59, v58, v57
	v_fma_f32 v60, -v56, v59, v58
	v_fmac_f32_e32 v59, v60, v57
	v_fma_f32 v56, -v56, v59, v58
	v_div_fmas_f32 v56, v56, v57, v59
	v_div_fixup_f32 v56, v56, v3, 1.0
	v_mul_f32_e32 v50, v50, v56
	v_mul_f32_e32 v51, v51, v56
	v_mul_f32_e32 v52, v52, v56
	v_mul_f32_e32 v53, v53, v56
	v_mul_f32_e32 v58, v46, v56
	v_mul_f32_e32 v59, v47, v56
	v_mul_f32_e32 v60, v48, v56
	v_mul_f32_e32 v61, v49, v56
	s_waitcnt vmcnt(1)
	v_fma_f32 v48, v64, s48, v52
	v_fma_f32 v49, v65, s48, v53
	v_fma_f32 v46, v62, s48, v50
	v_fma_f32 v47, v63, s48, v51
	s_waitcnt vmcnt(0)
	v_fma_f32 v52, v68, s48, v60
	v_fma_f32 v53, v69, s48, v61
	v_fma_f32 v50, v66, s48, v58
	v_fma_f32 v51, v67, s48, v59
	global_store_dwordx4 v[54:55], v[46:49], off
	global_store_dwordx4 v[54:55], v[50:53], off offset:16
	global_load_dwordx4 v[46:49], v[72:73], off offset:512
	s_nop 0
	global_load_dwordx4 v[50:53], v[72:73], off offset:528
	v_add_u32_e32 v54, 0xa0, v134
	v_or_b32_e32 v70, 0x200, v70
	v_mul_f32_e32 v44, v44, v56
	v_mul_f32_e32 v45, v45, v56
	v_mul_f32_e32 v42, v42, v56
	v_mul_f32_e32 v43, v43, v56
	v_ashrrev_i32_e32 v55, 31, v54
	v_lshl_add_u64 v[60:61], s[22:23], 0, v[70:71]
	v_mul_f32_e32 v62, v40, v56
	v_mul_f32_e32 v63, v41, v56
	v_mul_f32_e32 v57, v39, v56
	v_mul_f32_e32 v56, v38, v56
	v_lshlrev_b64 v[58:59], 6, v[54:55]
	v_lshl_add_u64 v[58:59], s[26:27], 0, v[58:59]
	s_waitcnt vmcnt(1)
	v_fma_f32 v38, v46, s48, v42
	v_fma_f32 v39, v47, s48, v43
	v_fma_f32 v40, v48, s48, v44
	v_fma_f32 v41, v49, s48, v45
	s_waitcnt vmcnt(0)
	v_fma_f32 v42, v50, s48, v56
	v_fma_f32 v43, v51, s48, v57
	v_fma_f32 v44, v52, s48, v62
	v_fma_f32 v45, v53, s48, v63
	global_store_dwordx4 v[60:61], v[38:41], off
	global_store_dwordx4 v[60:61], v[42:45], off offset:16
	global_load_dwordx4 v[38:41], v[58:59], off offset:32
	global_load_dwordx4 v[42:45], v[58:59], off offset:48
	v_lshlrev_b64 v[46:47], 11, v[54:55]
	v_lshl_add_u64 v[46:47], v[46:47], 0, v[4:5]
	v_lshlrev_b64 v[54:55], 2, v[46:47]
	v_lshl_add_u64 v[56:57], s[76:77], 0, v[54:55]
	global_load_dwordx4 v[46:49], v[56:57], off
	global_load_dwordx4 v[50:53], v[56:57], off offset:16
	s_waitcnt vmcnt(2)
	v_add_f32_e32 v40, v40, v44
	v_add_f32_e32 v41, v41, v45
	v_add_f32_e32 v38, v38, v42
	v_add_f32_e32 v39, v39, v43
	s_nop 0
	v_pk_mov_b32 v[42:43], v[38:39], v[40:41] op_sel:[1,0]
	v_mov_b32_e32 v39, v41
	v_add_f32_e32 v38, v42, v38
	v_add_f32_e32 v39, v43, v39
	s_nop 0
	v_add_f32_e32 v3, v38, v39
	v_fmamk_f32 v3, v3, 0x3a800000, v164
	v_mul_f32_e32 v38, 0x4f800000, v3
	v_cmp_gt_f32_e32 vcc, s50, v3
	s_nop 1
	v_cndmask_b32_e32 v3, v3, v38, vcc
	v_sqrt_f32_e32 v38, v3
	s_nop 0
	v_add_u32_e32 v39, -1, v38
	v_add_u32_e32 v40, 1, v38
	v_fma_f32 v41, -v39, v38, v3
	v_fma_f32 v42, -v40, v38, v3
	v_cmp_ge_f32_e64 s[8:9], 0, v41
	s_nop 1
	v_cndmask_b32_e64 v38, v38, v39, s[8:9]
	v_cmp_lt_f32_e64 s[8:9], 0, v42
	s_nop 1
	v_cndmask_b32_e64 v38, v38, v40, s[8:9]
	v_mul_f32_e32 v39, 0x37800000, v38
	v_cndmask_b32_e32 v38, v38, v39, vcc
	v_cmp_class_f32_e32 vcc, v3, v162
	s_nop 1
	v_cndmask_b32_e32 v3, v38, v3, vcc
	v_div_scale_f32 v40, s[4:5], v3, v3, 1.0
	v_rcp_f32_e32 v41, v40
	v_div_scale_f32 v42, vcc, 1.0, v3, 1.0
	v_lshl_add_u64 v[38:39], s[22:23], 0, v[54:55]
	v_fma_f32 v43, -v40, v41, 1.0
	v_fmac_f32_e32 v41, v43, v41
	v_mul_f32_e32 v43, v42, v41
	v_fma_f32 v44, -v40, v43, v42
	v_fmac_f32_e32 v43, v44, v41
	v_fma_f32 v40, -v40, v43, v42
	v_div_fmas_f32 v40, v40, v41, v43
	v_div_fixup_f32 v40, v40, v3, 1.0
	v_mul_f32_e32 v34, v34, v40
	v_mul_f32_e32 v35, v35, v40
	v_mul_f32_e32 v36, v36, v40
	v_mul_f32_e32 v37, v37, v40
	v_mul_f32_e32 v42, v30, v40
	v_mul_f32_e32 v43, v31, v40
	v_mul_f32_e32 v44, v32, v40
	v_mul_f32_e32 v45, v33, v40
	s_waitcnt vmcnt(1)
	v_fma_f32 v32, v48, s48, v36
	v_fma_f32 v33, v49, s48, v37
	v_fma_f32 v30, v46, s48, v34
	v_fma_f32 v31, v47, s48, v35
	s_waitcnt vmcnt(0)
	v_fma_f32 v36, v52, s48, v44
	v_fma_f32 v37, v53, s48, v45
	v_fma_f32 v34, v50, s48, v42
	v_fma_f32 v35, v51, s48, v43
	global_store_dwordx4 v[38:39], v[30:33], off
	global_store_dwordx4 v[38:39], v[34:37], off offset:16
	global_load_dwordx4 v[30:33], v[56:57], off offset:512
	s_nop 0
	global_load_dwordx4 v[34:37], v[56:57], off offset:528
	v_add_u32_e32 v38, 0xb0, v134
	v_or_b32_e32 v54, 0x200, v54
	v_mul_f32_e32 v28, v28, v40
	v_mul_f32_e32 v29, v29, v40
	v_mul_f32_e32 v26, v26, v40
	v_mul_f32_e32 v27, v27, v40
	v_ashrrev_i32_e32 v39, 31, v38
	v_lshl_add_u64 v[44:45], s[22:23], 0, v[54:55]
	v_mul_f32_e32 v46, v24, v40
	v_mul_f32_e32 v47, v25, v40
	v_mul_f32_e32 v41, v23, v40
	v_mul_f32_e32 v40, v22, v40
	v_lshlrev_b64 v[42:43], 6, v[38:39]
	v_lshl_add_u64 v[42:43], s[26:27], 0, v[42:43]
	s_waitcnt vmcnt(1)
	v_fma_f32 v22, v30, s48, v26
	v_fma_f32 v23, v31, s48, v27
	v_fma_f32 v24, v32, s48, v28
	v_fma_f32 v25, v33, s48, v29
	s_waitcnt vmcnt(0)
	v_fma_f32 v26, v34, s48, v40
	v_fma_f32 v27, v35, s48, v41
	v_fma_f32 v28, v36, s48, v46
	v_fma_f32 v29, v37, s48, v47
	global_store_dwordx4 v[44:45], v[22:25], off
	global_store_dwordx4 v[44:45], v[26:29], off offset:16
	global_load_dwordx4 v[22:25], v[42:43], off offset:32
	global_load_dwordx4 v[26:29], v[42:43], off offset:48
	v_lshlrev_b64 v[30:31], 11, v[38:39]
	v_lshl_add_u64 v[4:5], v[30:31], 0, v[4:5]
	v_lshlrev_b64 v[4:5], 2, v[4:5]
	v_lshl_add_u64 v[38:39], s[76:77], 0, v[4:5]
	global_load_dwordx4 v[30:33], v[38:39], off
	global_load_dwordx4 v[34:37], v[38:39], off offset:16
	s_waitcnt vmcnt(2)
	v_add_f32_e32 v24, v24, v28
	v_add_f32_e32 v25, v25, v29
	v_add_f32_e32 v22, v22, v26
	v_add_f32_e32 v23, v23, v27
	s_nop 0
	v_pk_mov_b32 v[26:27], v[22:23], v[24:25] op_sel:[1,0]
	v_mov_b32_e32 v23, v25
	v_add_f32_e32 v22, v26, v22
	v_add_f32_e32 v23, v27, v23
	s_nop 0
	v_add_f32_e32 v3, v22, v23
	v_fmamk_f32 v3, v3, 0x3a800000, v164
	v_mul_f32_e32 v22, 0x4f800000, v3
	v_cmp_gt_f32_e32 vcc, s50, v3
	s_nop 1
	v_cndmask_b32_e32 v3, v3, v22, vcc
	v_sqrt_f32_e32 v22, v3
	s_nop 0
	v_add_u32_e32 v23, -1, v22
	v_add_u32_e32 v24, 1, v22
	v_fma_f32 v25, -v23, v22, v3
	v_fma_f32 v26, -v24, v22, v3
	v_cmp_ge_f32_e64 s[8:9], 0, v25
	s_nop 1
	v_cndmask_b32_e64 v22, v22, v23, s[8:9]
	v_cmp_lt_f32_e64 s[8:9], 0, v26
	s_nop 1
	v_cndmask_b32_e64 v22, v22, v24, s[8:9]
	v_mul_f32_e32 v23, 0x37800000, v22
	v_cndmask_b32_e32 v22, v22, v23, vcc
	v_cmp_class_f32_e32 vcc, v3, v162
	s_nop 1
	v_cndmask_b32_e32 v3, v22, v3, vcc
	v_div_scale_f32 v24, s[4:5], v3, v3, 1.0
	v_rcp_f32_e32 v25, v24
	v_div_scale_f32 v26, vcc, 1.0, v3, 1.0
	v_lshl_add_u64 v[22:23], s[22:23], 0, v[4:5]
	v_fma_f32 v27, -v24, v25, 1.0
	v_fmac_f32_e32 v25, v27, v25
	v_mul_f32_e32 v27, v26, v25
	v_fma_f32 v28, -v24, v27, v26
	v_fmac_f32_e32 v27, v28, v25
	v_fma_f32 v24, -v24, v27, v26
	v_div_fmas_f32 v24, v24, v25, v27
	v_div_fixup_f32 v24, v24, v3, 1.0
	v_mul_f32_e32 v18, v18, v24
	v_mul_f32_e32 v19, v19, v24
	v_mul_f32_e32 v20, v20, v24
	v_mul_f32_e32 v21, v21, v24
	v_mul_f32_e32 v26, v14, v24
	v_mul_f32_e32 v27, v15, v24
	v_mul_f32_e32 v28, v16, v24
	v_mul_f32_e32 v29, v17, v24
	s_waitcnt vmcnt(1)
	v_fma_f32 v16, v32, s48, v20
	v_fma_f32 v17, v33, s48, v21
	v_fma_f32 v14, v30, s48, v18
	v_fma_f32 v15, v31, s48, v19
	s_waitcnt vmcnt(0)
	v_fma_f32 v20, v36, s48, v28
	v_fma_f32 v21, v37, s48, v29
	v_fma_f32 v18, v34, s48, v26
	v_fma_f32 v19, v35, s48, v27
	global_store_dwordx4 v[22:23], v[14:17], off
	global_store_dwordx4 v[22:23], v[18:21], off offset:16
	global_load_dwordx4 v[14:17], v[38:39], off offset:512
	s_nop 0
	global_load_dwordx4 v[18:21], v[38:39], off offset:528
	v_or_b32_e32 v4, 0x200, v4
	v_lshl_add_u64 v[22:23], s[22:23], 0, v[4:5]
	v_mul_f32_e32 v12, v12, v24
	v_mul_f32_e32 v13, v13, v24
	v_mul_f32_e32 v4, v10, v24
	v_mul_f32_e32 v5, v11, v24
	v_mul_f32_e32 v10, v8, v24
	v_mul_f32_e32 v11, v9, v24
	v_mul_f32_e32 v8, v6, v24
	v_mul_f32_e32 v9, v7, v24
	s_andn2_b64 vcc, exec, s[6:7]
	s_mov_b64 s[4:5], -1
	s_waitcnt vmcnt(1)
	v_fmac_f32_e32 v4, s48, v14
	v_fmac_f32_e32 v5, s48, v15
	v_fma_f32 v6, v16, s48, v12
	v_fma_f32 v7, v17, s48, v13
	s_waitcnt vmcnt(0)
	v_fmac_f32_e32 v8, s48, v18
	v_fmac_f32_e32 v9, s48, v19
	v_fmac_f32_e32 v10, s48, v20
	v_fmac_f32_e32 v11, s48, v21
	global_store_dwordx4 v[22:23], v[4:7], off
	global_store_dwordx4 v[22:23], v[8:11], off offset:16
	s_cbranch_vccnz .LBB0_849
	s_andn2_b64 vcc, exec, s[20:21]
	s_cbranch_vccnz .LBB0_848
	s_barrier
	s_branch .LBB0_848

.LBB0_923:
	s_or_b64 exec, exec, s[4:5]
	v_mov_b32_e32 v3, v4
	v_mov_b32_e32 v7, v5
	v_mov_b32_e32 v4, v128
	v_mov_b32_e32 v5, v126
	v_mul_f32_e32 v2, v2, v34
	v_mul_f32_e32 v3, v3, v34
	v_mul_f32_e32 v18, v18, v34
	v_mul_f32_e32 v19, v19, v34
	v_mul_f32_e32 v4, v4, v34
	v_mul_f32_e32 v5, v5, v34
	s_waitcnt vmcnt(13)
	v_fma_f32 v2, v92, v2, v96
	v_fma_f32 v3, v93, v3, v97
	v_mov_b32_e32 v126, v129
	v_mul_f32_e32 v20, v20, v34
	v_mul_f32_e32 v21, v21, v34
	s_waitcnt vmcnt(6)
	v_fma_f32 v18, v60, v18, v64
	v_fma_f32 v19, v61, v19, v65
	v_mul_f32_e32 v30, v30, v34
	v_mul_f32_e32 v31, v31, v34
	v_fma_f32 v4, v94, v4, v98
	v_fma_f32 v5, v95, v5, v99
	v_mul_f32_e32 v8, v126, v34
	v_mul_f32_e32 v9, v127, v34
	v_mul_f32_e32 v6, v6, v34
	v_mul_f32_e32 v7, v7, v34
	v_mul_f32_e32 v12, v12, v34
	v_mul_f32_e32 v13, v13, v34
	v_mul_f32_e32 v10, v10, v34
	v_mul_f32_e32 v11, v11, v34
	v_mul_f32_e32 v16, v16, v34
	v_mul_f32_e32 v17, v17, v34
	v_mul_f32_e32 v14, v14, v34
	v_mul_f32_e32 v15, v15, v34
	v_fma_f32 v20, v62, v20, v66
	v_fma_f32 v21, v63, v21, v67
	v_mul_f32_e32 v24, v24, v34
	v_mul_f32_e32 v25, v25, v34
	v_mul_f32_e32 v22, v22, v34
	v_mul_f32_e32 v23, v23, v34
	v_mul_f32_e32 v28, v28, v34
	v_mul_f32_e32 v29, v29, v34
	v_mul_f32_e32 v26, v26, v34
	v_mul_f32_e32 v27, v27, v34
	v_mul_f32_e32 v32, v32, v34
	v_mul_f32_e32 v33, v33, v34
	s_waitcnt vmcnt(0)
	v_fma_f32 v30, v36, v30, v40
	v_fma_f32 v31, v37, v31, v41
	v_max_f32_e64 v34, |v2|, |v18|
	v_max_f32_e64 v36, |v3|, |v19|
	v_fma_f32 v6, v84, v6, v88
	v_fma_f32 v7, v85, v7, v89
	v_fma_f32 v22, v52, v22, v56
	v_fma_f32 v23, v53, v23, v57
	v_max3_f32 v34, v34, 0, v36
	v_max_f32_e64 v36, |v4|, |v20|
	v_max_f32_e64 v37, |v5|, |v21|
	v_fma_f32 v8, v86, v8, v90
	v_fma_f32 v9, v87, v9, v91
	v_fma_f32 v24, v54, v24, v58
	v_fma_f32 v25, v55, v25, v59
	v_max3_f32 v34, v34, v36, v37
	v_max_f32_e64 v36, |v6|, |v22|
	v_max_f32_e64 v37, |v7|, |v23|
	v_fma_f32 v10, v76, v10, v80
	v_fma_f32 v11, v77, v11, v81
	v_fma_f32 v26, v44, v26, v48
	v_fma_f32 v27, v45, v27, v49
	v_max3_f32 v34, v34, v36, v37
	v_max_f32_e64 v36, |v8|, |v24|
	v_max_f32_e64 v37, |v9|, |v25|
	v_fma_f32 v12, v78, v12, v82
	v_fma_f32 v13, v79, v13, v83
	v_fma_f32 v28, v46, v28, v50
	v_fma_f32 v29, v47, v29, v51
	v_max3_f32 v34, v34, v36, v37
	v_max_f32_e64 v36, |v10|, |v26|
	v_max_f32_e64 v37, |v11|, |v27|
	v_fma_f32 v14, v68, v14, v72
	v_fma_f32 v15, v69, v15, v73
	v_max3_f32 v34, v34, v36, v37
	v_max_f32_e64 v36, |v12|, |v28|
	v_max_f32_e64 v37, |v13|, |v29|
	v_fma_f32 v16, v70, v16, v74
	v_fma_f32 v17, v71, v17, v75
	v_fma_f32 v32, v38, v32, v42
	v_fma_f32 v33, v39, v33, v43
	v_max3_f32 v34, v34, v36, v37
	v_max_f32_e64 v36, |v14|, |v30|
	v_max_f32_e64 v37, |v15|, |v31|
	v_max3_f32 v34, v34, v36, v37
	v_max_f32_e64 v36, |v16|, |v32|
	v_max_f32_e64 v37, |v17|, |v33|
	v_max3_f32 v34, v34, v36, v37
	v_bfe_u32 v36, v34, 23, 8
	v_and_b32_e32 v34, 0x7fffff, v34
	v_cmp_gt_u32_e32 vcc, s2, v34
	v_add_u32_e32 v1, 8, v1
	v_add_u32_e32 v120, 16, v120
	v_cndmask_b32_e64 v34, -2, -3, vcc
	v_add3_u32 v34, v36, v34, s3
	v_max_i32_e32 v34, 0xffffff88, v34
	v_add_u32_e32 v34, 0x7f, v34
	v_lshlrev_b32_e32 v42, 23, v34
	v_cvt_scalef32_2xpk16_fp6_f32 v[36:41], v[2:17], v[18:33], v42
	v_lshl_add_u64 v[2:3], s[72:73], 0, v[124:125]
	v_add_co_u32_e32 v2, vcc, s23, v2
	v_mul_lo_u32 v34, v34, s22
	s_nop 0
	v_addc_co_u32_e32 v3, vcc, 0, v3, vcc
	v_cmp_le_i32_e32 vcc, s0, v1
	v_mov_b32_e32 v32, v40
	v_mov_b32_e32 v33, v41
	v_lshl_add_u64 v[122:123], v[122:123], 0, s[18:19]
	s_or_b64 s[16:17], vcc, s[16:17]
	v_lshl_add_u64 v[124:125], v[124:125], 0, s[20:21]
	global_store_dwordx4 v[2:3], v[36:39], off
	global_store_dwordx4 v[2:3], v[32:35], off offset:64
	s_andn2_b64 exec, exec, s[16:17]
	s_cbranch_execz .LBB0_926
.LBB0_924:
	v_lshl_add_u64 v[18:19], s[72:73], 0, v[122:123]
	v_add_co_u32_e32 v14, vcc, 0x1ab00000, v18
	s_nop 1
	v_addc_co_u32_e32 v15, vcc, 0, v19, vcc
	global_load_dwordx4 v[6:9], v[14:15], off offset:1024
	global_load_dwordx4 v[2:5], v[14:15], off
	global_load_dwordx4 v[10:13], v[14:15], off offset:2048
	s_nop 0
	global_load_dwordx4 v[14:17], v[14:15], off offset:3072
	v_add_co_u32_e32 v30, vcc, 0x1ab01000, v18
	s_nop 1
	v_addc_co_u32_e32 v31, vcc, 0, v19, vcc
	global_load_dwordx4 v[18:21], v[30:31], off
	global_load_dwordx4 v[22:25], v[30:31], off offset:1024
	global_load_dwordx4 v[26:29], v[30:31], off offset:2048
	s_nop 0
	global_load_dwordx4 v[30:33], v[30:31], off offset:3072
	s_waitcnt vmcnt(4)
	v_mov_b32_e32 v36, v6
	v_mov_b32_e32 v37, v2
	v_mov_b32_e32 v38, v7
	v_mov_b32_e32 v39, v3
	v_mov_b32_e32 v40, v8
	v_mov_b32_e32 v41, v4
	v_mov_b32_e32 v42, v9
	v_mov_b32_e32 v43, v5
	v_mov_b32_e32 v44, v11
	v_mov_b32_e32 v45, v12
	v_mov_b32_e32 v46, v10
	v_mov_b32_e32 v47, v13
	v_add_f32_e32 v36, v36, v38
	v_add_f32_e32 v37, v37, v39
	v_add_f32_e32 v38, v40, v42
	v_add_f32_e32 v39, v41, v43
	v_add_f32_e32 v40, v44, v46
	v_add_f32_e32 v41, v45, v47
	v_add_f32_e32 v36, v36, v38
	v_add_f32_e32 v37, v37, v39
	v_add_f32_e32 v38, v40, v40
	v_add_f32_e32 v39, v40, v41
	v_add_f32_e32 v34, 0, v37
	v_add_f32_e32 v49, v14, v15
	v_add_f32_e32 v51, v16, v17
	v_add_f32_e32 v43, v36, v34
	s_waitcnt vmcnt(3)
	v_mov_b32_e32 v48, v18
	v_mov_b32_e32 v50, v19
	v_mov_b32_e32 v42, v21
	v_mov_b32_e32 v38, v20
	s_waitcnt vmcnt(2)
	v_mov_b32_e32 v44, v23
	v_mov_b32_e32 v45, v24
	v_mov_b32_e32 v46, v22
	v_mov_b32_e32 v47, v25
	v_add_f32_e32 v40, v48, v50
	v_add_f32_e32 v41, v49, v51
	v_add_f32_e32 v36, v38, v42
	v_add_f32_e32 v37, v39, v43
	v_add_f32_e32 v44, v44, v46
	v_add_f32_e32 v45, v45, v47
	v_add_f32_e32 v36, v40, v36
	v_add_f32_e32 v37, v41, v37
	v_add_f32_e32 v45, v44, v45
	v_add_f32_e32 v44, v44, v44
	v_add_f32_e32 v37, v36, v37
	v_add_f32_e32 v36, v36, v36
	s_waitcnt vmcnt(1)
	v_add_f32_e32 v53, v26, v27
	v_add_f32_e32 v55, v28, v29
	s_waitcnt vmcnt(0)
	v_mov_b32_e32 v52, v30
	v_mov_b32_e32 v54, v31
	v_mov_b32_e32 v44, v32
	v_mov_b32_e32 v36, v33
	v_add_f32_e32 v46, v52, v54
	v_add_f32_e32 v47, v53, v55
	v_add_f32_e32 v36, v44, v36
	v_add_f32_e32 v37, v45, v37
	s_nop 0
	v_add_f32_e32 v36, v46, v36
	v_add_f32_e32 v37, v47, v37
	s_nop 0
	v_add_f32_e32 v34, v36, v37
	ds_bpermute_b32 v36, v130, v34
	s_waitcnt lgkmcnt(0)
	v_add_f32_e32 v34, v34, v36
	ds_bpermute_b32 v36, v131, v34
	s_waitcnt lgkmcnt(0)
	v_add_f32_e32 v34, v34, v36
	ds_bpermute_b32 v36, v132, v34
	s_waitcnt lgkmcnt(0)
	v_add_f32_e32 v34, v34, v36
	ds_bpermute_b32 v36, v133, v34
	s_waitcnt lgkmcnt(0)
	v_add_f32_e32 v34, v34, v36
	ds_bpermute_b32 v36, v134, v34
	s_waitcnt lgkmcnt(0)
	v_add_f32_e32 v34, v34, v36
	ds_bpermute_b32 v36, v135, v34
	s_waitcnt lgkmcnt(0)
	v_add_f32_e32 v121, v34, v36
	v_fmamk_f32 v126, v121, 0xba000000, v5
	v_fmamk_f32 v128, v121, 0xba000000, v4
	v_fmamk_f32 v4, v121, 0xba000000, v3
	v_fmamk_f32 v127, v121, 0xba000000, v9
	v_fmamk_f32 v5, v121, 0xba000000, v7
	v_fmac_f32_e32 v6, 0xba000000, v121
	v_fmamk_f32 v13, v121, 0xba000000, v13
	v_fmamk_f32 v12, v121, 0xba000000, v12
	v_fmamk_f32 v11, v121, 0xba000000, v11
	v_fmac_f32_e32 v10, 0xba000000, v121
	v_fmac_f32_e32 v2, 0xba000000, v121
	v_fmamk_f32 v129, v121, 0xba000000, v8
	v_mov_b32_e32 v3, v6
	v_mul_f32_e32 v8, v4, v4
	v_mul_f32_e32 v9, v5, v5
	v_mul_f32_e32 v36, v126, v126
	v_mul_f32_e32 v37, v127, v127
	v_mul_f32_e32 v38, v12, v12
	v_mul_f32_e32 v39, v13, v13
	v_mul_f32_e32 v40, v10, v10
	v_mul_f32_e32 v41, v11, v11
	v_fmamk_f32 v16, v121, 0xba000000, v16
	v_fmac_f32_e32 v14, 0xba000000, v121
	v_fmac_f32_e32 v8, v2, v2
	v_fmac_f32_e32 v9, v3, v3
	v_fmac_f32_e32 v36, v128, v128
	v_fmac_f32_e32 v37, v129, v129
	v_pk_mov_b32 v[52:53], v[40:41], v[38:39] op_sel:[1,0]
	v_mov_b32_e32 v41, v39
	v_fmamk_f32 v17, v121, 0xba000000, v17
	v_fmamk_f32 v15, v121, 0xba000000, v15
	v_fmamk_f32 v25, v121, 0xba000000, v25
	v_fmamk_f32 v24, v121, 0xba000000, v24
	v_fmamk_f32 v23, v121, 0xba000000, v23
	v_fmac_f32_e32 v22, 0xba000000, v121
	v_mul_f32_e32 v34, v14, v14
	v_mul_f32_e32 v42, v16, v16
	v_add_f32_e32 v8, v8, v36
	v_add_f32_e32 v9, v9, v37
	v_add_f32_e32 v36, v52, v40
	v_add_f32_e32 v37, v53, v41
	v_fmamk_f32 v21, v121, 0xba000000, v21
	v_fmamk_f32 v20, v121, 0xba000000, v20
	v_fmamk_f32 v19, v121, 0xba000000, v19
	v_fmac_f32_e32 v18, 0xba000000, v121
	v_mul_f32_e32 v44, v24, v24
	v_mul_f32_e32 v45, v25, v25
	v_mul_f32_e32 v46, v22, v22
	v_mul_f32_e32 v47, v23, v23
	v_fma_f32 v38, v14, v14, v34
	v_fma_f32 v39, v15, v15, v34
	v_fma_f32 v43, v17, v17, v42
	v_fmac_f32_e32 v42, v16, v16
	v_add_f32_e32 v9, v8, v9
	v_add_f32_e32 v8, v8, v8
	v_add_f32_e32 v37, v36, v37
	v_add_f32_e32 v36, v36, v36
	v_fmamk_f32 v28, v121, 0xba000000, v28
	v_fmac_f32_e32 v26, 0xba000000, v121
	v_pk_mov_b32 v[54:55], v[46:47], v[44:45] op_sel:[1,0]
	v_mov_b32_e32 v47, v45
	v_mul_f32_e32 v38, v18, v18
	v_mul_f32_e32 v42, v19, v19
	v_mul_f32_e32 v36, v20, v20
	v_mul_f32_e32 v8, v21, v21
	v_fmamk_f32 v29, v121, 0xba000000, v29
	v_fmamk_f32 v27, v121, 0xba000000, v27
	v_mul_f32_e32 v48, v26, v26
	v_mul_f32_e32 v50, v28, v28
	v_add_f32_e32 v40, v54, v46
	v_add_f32_e32 v41, v55, v47
	v_add_f32_e32 v38, v38, v42
	v_add_f32_e32 v39, v39, v43
	v_add_f32_e32 v8, v36, v8
	v_add_f32_e32 v9, v37, v9
	v_fma_f32 v138, v26, v26, v48
	v_fma_f32 v139, v27, v27, v48
	v_fma_f32 v140, v28, v28, v50
	v_fma_f32 v141, v29, v29, v50
	v_add_f32_e32 v142, v40, v40
	v_add_f32_e32 v143, v40, v41
	v_add_f32_e32 v8, v38, v8
	v_add_f32_e32 v9, v39, v9
	global_load_dwordx4 v[92:95], v[100:101], off
	global_load_dwordx4 v[84:87], v[100:101], off offset:1024
	global_load_dwordx4 v[96:99], v[102:103], off
	global_load_dwordx4 v[88:91], v[102:103], off offset:1024
	global_load_dwordx4 v[76:79], v[100:101], off offset:2048
	global_load_dwordx4 v[68:71], v[100:101], off offset:3072
	global_load_dwordx4 v[80:83], v[102:103], off offset:2048
	global_load_dwordx4 v[72:75], v[102:103], off offset:3072
	global_load_dwordx4 v[60:63], v[104:105], off
	global_load_dwordx4 v[64:67], v[106:107], off
	global_load_dwordx4 v[52:55], v[108:109], off
	global_load_dwordx4 v[56:59], v[110:111], off
	global_load_dwordx4 v[44:47], v[112:113], off
	global_load_dwordx4 v[48:51], v[114:115], off
	global_load_dwordx4 v[36:39], v[116:117], off
	global_load_dwordx4 v[40:43], v[118:119], off
	v_fmamk_f32 v33, v121, 0xba000000, v33
	v_add_f32_e32 v9, v8, v9
	v_add_f32_e32 v8, v8, v8
	v_fmamk_f32 v32, v121, 0xba000000, v32
	v_fmamk_f32 v31, v121, 0xba000000, v31
	v_fmac_f32_e32 v30, 0xba000000, v121
	v_mul_f32_e32 v138, v30, v30
	v_mul_f32_e32 v140, v31, v31
	v_mul_f32_e32 v142, v32, v32
	v_mul_f32_e32 v8, v33, v33
	v_add_f32_e32 v138, v138, v140
	v_add_f32_e32 v139, v139, v141
	v_add_f32_e32 v8, v142, v8
	v_add_f32_e32 v9, v143, v9
	s_nop 0
	v_add_f32_e32 v8, v138, v8
	v_add_f32_e32 v9, v139, v9
	s_nop 0
	v_add_f32_e32 v3, v8, v9
	ds_bpermute_b32 v7, v130, v3
	s_waitcnt lgkmcnt(0)
	v_add_f32_e32 v3, v3, v7
	ds_bpermute_b32 v7, v131, v3
	s_waitcnt lgkmcnt(0)
	v_add_f32_e32 v3, v3, v7
	ds_bpermute_b32 v7, v132, v3
	s_waitcnt lgkmcnt(0)
	v_add_f32_e32 v3, v3, v7
	ds_bpermute_b32 v7, v133, v3
	s_waitcnt lgkmcnt(0)
	v_add_f32_e32 v3, v3, v7
	ds_bpermute_b32 v7, v134, v3
	s_waitcnt lgkmcnt(0)
	v_add_f32_e32 v3, v3, v7
	ds_bpermute_b32 v7, v135, v3
	s_waitcnt lgkmcnt(0)
	v_add_f32_e32 v3, v3, v7
	v_fmamk_f32 v3, v3, 0x3a000000, v136
	v_mul_f32_e32 v7, 0x4f800000, v3
	v_cmp_gt_f32_e32 vcc, s1, v3
	s_nop 1
	v_cndmask_b32_e32 v3, v3, v7, vcc
	v_sqrt_f32_e32 v7, v3
	s_nop 0
	v_add_u32_e32 v8, -1, v7
	v_add_u32_e32 v9, 1, v7
	v_fma_f32 v34, -v8, v7, v3
	v_fma_f32 v138, -v9, v7, v3
	v_cmp_ge_f32_e64 s[8:9], 0, v34
	s_nop 1
	v_cndmask_b32_e64 v7, v7, v8, s[8:9]
	v_cmp_lt_f32_e64 s[8:9], 0, v138
	s_nop 1
	v_cndmask_b32_e64 v7, v7, v9, s[8:9]
	v_mul_f32_e32 v8, 0x37800000, v7
	v_cndmask_b32_e32 v7, v7, v8, vcc
	v_cmp_class_f32_e32 vcc, v3, v137
	s_nop 1
	v_cndmask_b32_e32 v3, v7, v3, vcc
	v_div_scale_f32 v7, s[4:5], v3, v3, 1.0
	v_rcp_f32_e32 v8, v7
	s_nop 0
	v_fma_f32 v9, -v7, v8, 1.0
	v_fmac_f32_e32 v8, v9, v8
	v_div_scale_f32 v9, vcc, 1.0, v3, 1.0
	v_mul_f32_e32 v34, v9, v8
	v_fma_f32 v138, -v7, v34, v9
	v_fmac_f32_e32 v34, v138, v8
	v_fma_f32 v7, -v7, v34, v9
	v_div_fmas_f32 v7, v7, v8, v34
	v_div_fixup_f32 v34, v7, v3, 1.0
	s_and_saveexec_b64 s[4:5], s[6:7]
	s_cbranch_execz .LBB0_923
	v_mul_f32_e32 v8, 0x3a000000, v121
	v_ashrrev_i32_e32 v121, 31, v120
	v_lshl_add_u64 v[138:139], v[120:121], 2, s[14:15]
	v_mov_b32_e32 v9, v34
	global_store_dwordx2 v[138:139], v[8:9], off
	s_branch .LBB0_923

.LBB0_1077:
	v_mov_b32_e32 v116, v0
	s_lshl_b32 s5, s62, 8
	v_lshrrev_b32_e32 v114, 1, v116
	s_lshl_b32 s4, s61, 8
	v_and_or_b32 v114, v114, 24, s5
	s_add_i32 s4, s4, s84
	v_or_b32_e32 v114, s85, v114
	v_ashrrev_i32_e32 v115, 31, v114
	v_and_or_b32 v174, v116, 15, s4
	v_lshlrev_b64 v[172:173], 2, v[114:115]
	v_ashrrev_i32_e32 v175, 31, v174
	v_lshlrev_b32_e32 v114, 1, v174
	v_ashrrev_i32_e32 v115, 31, v114
	v_lshlrev_b64 v[116:117], 13, v[174:175]
	v_lshl_add_u64 v[114:115], v[114:115], 2, s[22:23]
	v_lshl_add_u64 v[116:117], s[20:21], 0, v[116:117]
	v_readlane_b32 s48, v254, 30
	v_lshl_add_u64 v[196:197], v[116:117], 0, v[172:173]
	global_load_dwordx2 v[198:199], v[114:115], off
	global_load_dwordx4 v[180:183], v[196:197], off
	global_load_dwordx4 v[184:187], v[196:197], off offset:16
	global_load_dwordx4 v[188:191], v[196:197], off offset:512
	global_load_dwordx4 v[192:195], v[196:197], off offset:528
	v_readlane_b32 s52, v254, 34
	v_readlane_b32 s53, v254, 35
	v_readlane_b32 s54, v254, 36
	v_readlane_b32 s55, v254, 37
	v_lshl_add_u64 v[122:123], s[52:53], 0, v[172:173]
	v_or_b32_e32 v200, 16, v174
	v_lshl_add_u64 v[142:143], s[54:55], 0, v[172:173]
	global_load_dwordx4 v[118:121], v[142:143], off
	global_load_dwordx4 v[130:133], v[122:123], off
	global_load_dwordx4 v[114:117], v[122:123], off offset:16
	global_load_dwordx4 v[134:137], v[142:143], off offset:16
	global_load_dwordx4 v[126:129], v[142:143], off offset:512
	global_load_dwordx4 v[138:141], v[122:123], off offset:512
	s_nop 0
	global_load_dwordx4 v[122:125], v[122:123], off offset:528
	s_nop 0
	global_load_dwordx4 v[142:145], v[142:143], off offset:528
	v_ashrrev_i32_e32 v201, 31, v200
	v_lshlrev_b32_e32 v202, 1, v200
	v_ashrrev_i32_e32 v203, 31, v202
	v_lshlrev_b64 v[200:201], 13, v[200:201]
	v_lshl_add_u64 v[202:203], v[202:203], 2, s[22:23]
	v_lshl_add_u64 v[200:201], s[20:21], 0, v[200:201]
	v_lshl_add_u64 v[200:201], v[200:201], 0, v[172:173]
	s_and_b64 vcc, exec, s[6:7]
	s_mov_b64 s[4:5], -1
	v_readlane_b32 s49, v254, 31
	v_readlane_b32 s50, v254, 32
	v_readlane_b32 s51, v254, 33
	v_readlane_b32 s56, v254, 38
	v_readlane_b32 s57, v254, 39
	v_readlane_b32 s58, v254, 40
	v_readlane_b32 s59, v254, 41
	v_readlane_b32 s60, v254, 42
	v_readlane_b32 s61, v254, 43
	v_readlane_b32 s62, v254, 44
	v_readlane_b32 s63, v254, 45
	s_waitcnt vmcnt(0)
	v_sub_f32_e32 v183, v183, v198
	v_sub_f32_e32 v182, v182, v198
	v_sub_f32_e32 v181, v181, v198
	v_sub_f32_e32 v180, v180, v198
	v_sub_f32_e32 v187, v187, v198
	v_sub_f32_e32 v186, v186, v198
	v_sub_f32_e32 v185, v185, v198
	v_sub_f32_e32 v184, v184, v198
	v_sub_f32_e32 v191, v191, v198
	v_sub_f32_e32 v190, v190, v198
	v_sub_f32_e32 v189, v189, v198
	v_sub_f32_e32 v188, v188, v198
	v_sub_f32_e32 v195, v195, v198
	v_sub_f32_e32 v194, v194, v198
	v_sub_f32_e32 v193, v193, v198
	v_sub_f32_e32 v192, v192, v198
	v_mul_f32_e32 v180, v199, v180
	v_mul_f32_e32 v181, v199, v181
	v_mul_f32_e32 v182, v199, v182
	v_mul_f32_e32 v183, v199, v183
	v_mul_f32_e32 v184, v199, v184
	v_mul_f32_e32 v185, v199, v185
	v_mul_f32_e32 v186, v199, v186
	v_mul_f32_e32 v187, v199, v187
	v_mul_f32_e32 v188, v199, v188
	v_mul_f32_e32 v189, v199, v189
	v_mul_f32_e32 v190, v199, v190
	v_mul_f32_e32 v191, v199, v191
	v_mul_f32_e32 v192, v199, v192
	v_mul_f32_e32 v193, v199, v193
	v_mul_f32_e32 v194, v199, v194
	v_mul_f32_e32 v195, v199, v195
	v_fma_f32 v182, v132, v182, v120
	v_fma_f32 v183, v133, v183, v121
	v_fma_f32 v180, v130, v180, v118
	v_fma_f32 v181, v131, v181, v119
	v_fma_f32 v186, v116, v186, v136
	v_fma_f32 v187, v117, v187, v137
	v_fma_f32 v184, v114, v184, v134
	v_fma_f32 v185, v115, v185, v135
	v_fma_f32 v190, v140, v190, v128
	v_fma_f32 v191, v141, v191, v129
	v_fma_f32 v188, v138, v188, v126
	v_fma_f32 v189, v139, v189, v127
	v_fma_f32 v194, v124, v194, v144
	v_fma_f32 v195, v125, v195, v145
	v_fma_f32 v192, v122, v192, v142
	v_fma_f32 v193, v123, v193, v143
	v_fmac_f32_e32 v160, s44, v182
	v_fmac_f32_e32 v161, s44, v183
	v_fmac_f32_e32 v158, s44, v180
	v_fmac_f32_e32 v159, s44, v181
	v_fmac_f32_e32 v156, s44, v186
	v_fmac_f32_e32 v157, s44, v187
	v_fmac_f32_e32 v154, s44, v184
	v_fmac_f32_e32 v155, s44, v185
	v_fmac_f32_e32 v152, s44, v190
	v_fmac_f32_e32 v153, s44, v191
	v_fmac_f32_e32 v150, s44, v188
	v_fmac_f32_e32 v151, s44, v189
	v_fmac_f32_e32 v148, s44, v194
	v_fmac_f32_e32 v149, s44, v195
	v_fmac_f32_e32 v146, s44, v192
	v_fmac_f32_e32 v147, s44, v193
	global_store_dwordx4 v[196:197], v[158:161], off
	global_store_dwordx4 v[196:197], v[154:157], off offset:16
	global_store_dwordx4 v[196:197], v[150:153], off offset:512
	global_store_dwordx4 v[196:197], v[146:149], off offset:528
	global_load_dwordx2 v[180:181], v[202:203], off
	global_load_dwordx4 v[146:149], v[200:201], off
	global_load_dwordx4 v[150:153], v[200:201], off offset:16
	global_load_dwordx4 v[154:157], v[200:201], off offset:512
	global_load_dwordx4 v[158:161], v[200:201], off offset:528
	v_or_b32_e32 v182, 32, v174
	v_ashrrev_i32_e32 v183, 31, v182
	v_lshlrev_b32_e32 v184, 1, v182
	v_ashrrev_i32_e32 v185, 31, v184
	v_lshlrev_b64 v[182:183], 13, v[182:183]
	v_lshl_add_u64 v[184:185], v[184:185], 2, s[22:23]
	v_lshl_add_u64 v[182:183], s[20:21], 0, v[182:183]
	v_lshl_add_u64 v[182:183], v[182:183], 0, v[172:173]
	s_waitcnt vmcnt(3)
	v_sub_f32_e32 v149, v149, v180
	v_sub_f32_e32 v148, v148, v180
	v_sub_f32_e32 v147, v147, v180
	v_sub_f32_e32 v146, v146, v180
	s_waitcnt vmcnt(2)
	v_sub_f32_e32 v153, v153, v180
	v_sub_f32_e32 v152, v152, v180
	v_sub_f32_e32 v151, v151, v180
	v_sub_f32_e32 v150, v150, v180
	s_waitcnt vmcnt(1)
	v_sub_f32_e32 v157, v157, v180
	v_sub_f32_e32 v156, v156, v180
	v_sub_f32_e32 v155, v155, v180
	v_sub_f32_e32 v154, v154, v180
	s_waitcnt vmcnt(0)
	v_sub_f32_e32 v161, v161, v180
	v_sub_f32_e32 v160, v160, v180
	v_sub_f32_e32 v159, v159, v180
	v_sub_f32_e32 v158, v158, v180
	v_mul_f32_e32 v146, v181, v146
	v_mul_f32_e32 v147, v181, v147
	v_mul_f32_e32 v148, v181, v148
	v_mul_f32_e32 v149, v181, v149
	v_mul_f32_e32 v150, v181, v150
	v_mul_f32_e32 v151, v181, v151
	v_mul_f32_e32 v152, v181, v152
	v_mul_f32_e32 v153, v181, v153
	v_mul_f32_e32 v154, v181, v154
	v_mul_f32_e32 v155, v181, v155
	v_mul_f32_e32 v156, v181, v156
	v_mul_f32_e32 v157, v181, v157
	v_mul_f32_e32 v158, v181, v158
	v_mul_f32_e32 v159, v181, v159
	v_mul_f32_e32 v160, v181, v160
	v_mul_f32_e32 v161, v181, v161
	v_fma_f32 v148, v132, v148, v120
	v_fma_f32 v149, v133, v149, v121
	v_fma_f32 v146, v130, v146, v118
	v_fma_f32 v147, v131, v147, v119
	v_fma_f32 v152, v116, v152, v136
	v_fma_f32 v153, v117, v153, v137
	v_fma_f32 v150, v114, v150, v134
	v_fma_f32 v151, v115, v151, v135
	v_fma_f32 v156, v140, v156, v128
	v_fma_f32 v157, v141, v157, v129
	v_fma_f32 v154, v138, v154, v126
	v_fma_f32 v155, v139, v155, v127
	v_fma_f32 v160, v124, v160, v144
	v_fma_f32 v161, v125, v161, v145
	v_fma_f32 v158, v122, v158, v142
	v_fma_f32 v159, v123, v159, v143
	v_fmac_f32_e32 v112, s44, v148
	v_fmac_f32_e32 v113, s44, v149
	v_fmac_f32_e32 v110, s44, v146
	v_fmac_f32_e32 v111, s44, v147
	v_fmac_f32_e32 v108, s44, v152
	v_fmac_f32_e32 v109, s44, v153
	v_fmac_f32_e32 v106, s44, v150
	v_fmac_f32_e32 v107, s44, v151
	v_fmac_f32_e32 v104, s44, v156
	v_fmac_f32_e32 v105, s44, v157
	v_fmac_f32_e32 v102, s44, v154
	v_fmac_f32_e32 v103, s44, v155
	v_fmac_f32_e32 v100, s44, v160
	v_fmac_f32_e32 v101, s44, v161
	v_fmac_f32_e32 v98, s44, v158
	v_fmac_f32_e32 v99, s44, v159
	global_store_dwordx4 v[200:201], v[110:113], off
	global_store_dwordx4 v[200:201], v[106:109], off offset:16
	global_store_dwordx4 v[200:201], v[102:105], off offset:512
	global_store_dwordx4 v[200:201], v[98:101], off offset:528
	global_load_dwordx2 v[146:147], v[184:185], off
	global_load_dwordx4 v[98:101], v[182:183], off
	global_load_dwordx4 v[102:105], v[182:183], off offset:16
	global_load_dwordx4 v[106:109], v[182:183], off offset:512
	global_load_dwordx4 v[110:113], v[182:183], off offset:528
	v_or_b32_e32 v148, 48, v174
	v_ashrrev_i32_e32 v149, 31, v148
	v_lshlrev_b32_e32 v150, 1, v148
	v_ashrrev_i32_e32 v151, 31, v150
	v_lshlrev_b64 v[148:149], 13, v[148:149]
	v_lshl_add_u64 v[150:151], v[150:151], 2, s[22:23]
	v_lshl_add_u64 v[148:149], s[20:21], 0, v[148:149]
	v_lshl_add_u64 v[148:149], v[148:149], 0, v[172:173]
	s_waitcnt vmcnt(3)
	v_sub_f32_e32 v101, v101, v146
	v_sub_f32_e32 v100, v100, v146
	v_sub_f32_e32 v99, v99, v146
	v_sub_f32_e32 v98, v98, v146
	s_waitcnt vmcnt(2)
	v_sub_f32_e32 v105, v105, v146
	v_sub_f32_e32 v104, v104, v146
	v_sub_f32_e32 v103, v103, v146
	v_sub_f32_e32 v102, v102, v146
	s_waitcnt vmcnt(1)
	v_sub_f32_e32 v109, v109, v146
	v_sub_f32_e32 v108, v108, v146
	v_sub_f32_e32 v107, v107, v146
	v_sub_f32_e32 v106, v106, v146
	s_waitcnt vmcnt(0)
	v_sub_f32_e32 v113, v113, v146
	v_sub_f32_e32 v112, v112, v146
	v_sub_f32_e32 v111, v111, v146
	v_sub_f32_e32 v110, v110, v146
	v_mul_f32_e32 v98, v147, v98
	v_mul_f32_e32 v99, v147, v99
	v_mul_f32_e32 v100, v147, v100
	v_mul_f32_e32 v101, v147, v101
	v_mul_f32_e32 v102, v147, v102
	v_mul_f32_e32 v103, v147, v103
	v_mul_f32_e32 v104, v147, v104
	v_mul_f32_e32 v105, v147, v105
	v_mul_f32_e32 v106, v147, v106
	v_mul_f32_e32 v107, v147, v107
	v_mul_f32_e32 v108, v147, v108
	v_mul_f32_e32 v109, v147, v109
	v_mul_f32_e32 v110, v147, v110
	v_mul_f32_e32 v111, v147, v111
	v_mul_f32_e32 v112, v147, v112
	v_mul_f32_e32 v113, v147, v113
	v_fma_f32 v100, v132, v100, v120
	v_fma_f32 v101, v133, v101, v121
	v_fma_f32 v98, v130, v98, v118
	v_fma_f32 v99, v131, v99, v119
	v_fma_f32 v104, v116, v104, v136
	v_fma_f32 v105, v117, v105, v137
	v_fma_f32 v102, v114, v102, v134
	v_fma_f32 v103, v115, v103, v135
	v_fma_f32 v108, v140, v108, v128
	v_fma_f32 v109, v141, v109, v129
	v_fma_f32 v106, v138, v106, v126
	v_fma_f32 v107, v139, v107, v127
	v_fma_f32 v112, v124, v112, v144
	v_fma_f32 v113, v125, v113, v145
	v_fma_f32 v110, v122, v110, v142
	v_fma_f32 v111, v123, v111, v143
	v_fmac_f32_e32 v96, s44, v100
	v_fmac_f32_e32 v97, s44, v101
	v_fmac_f32_e32 v94, s44, v98
	v_fmac_f32_e32 v95, s44, v99
	v_fmac_f32_e32 v92, s44, v104
	v_fmac_f32_e32 v93, s44, v105
	v_fmac_f32_e32 v90, s44, v102
	v_fmac_f32_e32 v91, s44, v103
	v_fmac_f32_e32 v88, s44, v108
	v_fmac_f32_e32 v89, s44, v109
	v_fmac_f32_e32 v86, s44, v106
	v_fmac_f32_e32 v87, s44, v107
	v_fmac_f32_e32 v84, s44, v112
	v_fmac_f32_e32 v85, s44, v113
	v_fmac_f32_e32 v82, s44, v110
	v_fmac_f32_e32 v83, s44, v111
	global_store_dwordx4 v[182:183], v[94:97], off
	global_store_dwordx4 v[182:183], v[90:93], off offset:16
	global_store_dwordx4 v[182:183], v[86:89], off offset:512
	global_store_dwordx4 v[182:183], v[82:85], off offset:528
	global_load_dwordx2 v[98:99], v[150:151], off
	global_load_dwordx4 v[82:85], v[148:149], off
	global_load_dwordx4 v[86:89], v[148:149], off offset:16
	global_load_dwordx4 v[90:93], v[148:149], off offset:512
	global_load_dwordx4 v[94:97], v[148:149], off offset:528
	v_add_u32_e32 v100, 0x80, v174
	v_ashrrev_i32_e32 v101, 31, v100
	v_lshlrev_b32_e32 v102, 1, v100
	v_ashrrev_i32_e32 v103, 31, v102
	v_lshlrev_b64 v[100:101], 13, v[100:101]
	v_lshl_add_u64 v[102:103], v[102:103], 2, s[22:23]
	v_lshl_add_u64 v[100:101], s[20:21], 0, v[100:101]
	v_lshl_add_u64 v[100:101], v[100:101], 0, v[172:173]
	s_waitcnt vmcnt(3)
	v_sub_f32_e32 v85, v85, v98
	v_sub_f32_e32 v84, v84, v98
	v_sub_f32_e32 v83, v83, v98
	v_sub_f32_e32 v82, v82, v98
	s_waitcnt vmcnt(2)
	v_sub_f32_e32 v89, v89, v98
	v_sub_f32_e32 v88, v88, v98
	v_sub_f32_e32 v87, v87, v98
	v_sub_f32_e32 v86, v86, v98
	s_waitcnt vmcnt(1)
	v_sub_f32_e32 v93, v93, v98
	v_sub_f32_e32 v92, v92, v98
	v_sub_f32_e32 v91, v91, v98
	v_sub_f32_e32 v90, v90, v98
	s_waitcnt vmcnt(0)
	v_sub_f32_e32 v97, v97, v98
	v_sub_f32_e32 v96, v96, v98
	v_sub_f32_e32 v95, v95, v98
	v_sub_f32_e32 v94, v94, v98
	v_mul_f32_e32 v82, v99, v82
	v_mul_f32_e32 v83, v99, v83
	v_mul_f32_e32 v84, v99, v84
	v_mul_f32_e32 v85, v99, v85
	v_mul_f32_e32 v86, v99, v86
	v_mul_f32_e32 v87, v99, v87
	v_mul_f32_e32 v88, v99, v88
	v_mul_f32_e32 v89, v99, v89
	v_mul_f32_e32 v90, v99, v90
	v_mul_f32_e32 v91, v99, v91
	v_mul_f32_e32 v92, v99, v92
	v_mul_f32_e32 v93, v99, v93
	v_mul_f32_e32 v94, v99, v94
	v_mul_f32_e32 v95, v99, v95
	v_mul_f32_e32 v96, v99, v96
	v_mul_f32_e32 v97, v99, v97
	v_fma_f32 v84, v132, v84, v120
	v_fma_f32 v85, v133, v85, v121
	v_fma_f32 v82, v130, v82, v118
	v_fma_f32 v83, v131, v83, v119
	v_fma_f32 v88, v116, v88, v136
	v_fma_f32 v89, v117, v89, v137
	v_fma_f32 v86, v114, v86, v134
	v_fma_f32 v87, v115, v87, v135
	v_fma_f32 v92, v140, v92, v128
	v_fma_f32 v93, v141, v93, v129
	v_fma_f32 v90, v138, v90, v126
	v_fma_f32 v91, v139, v91, v127
	v_fma_f32 v96, v124, v96, v144
	v_fma_f32 v97, v125, v97, v145
	v_fma_f32 v94, v122, v94, v142
	v_fma_f32 v95, v123, v95, v143
	v_fmac_f32_e32 v80, s44, v84
	v_fmac_f32_e32 v81, s44, v85
	v_fmac_f32_e32 v78, s44, v82
	v_fmac_f32_e32 v79, s44, v83
	v_fmac_f32_e32 v76, s44, v88
	v_fmac_f32_e32 v77, s44, v89
	v_fmac_f32_e32 v74, s44, v86
	v_fmac_f32_e32 v75, s44, v87
	v_fmac_f32_e32 v72, s44, v92
	v_fmac_f32_e32 v73, s44, v93
	v_fmac_f32_e32 v70, s44, v90
	v_fmac_f32_e32 v71, s44, v91
	v_fmac_f32_e32 v68, s44, v96
	v_fmac_f32_e32 v69, s44, v97
	v_fmac_f32_e32 v66, s44, v94
	v_fmac_f32_e32 v67, s44, v95
	global_store_dwordx4 v[148:149], v[78:81], off
	global_store_dwordx4 v[148:149], v[74:77], off offset:16
	global_store_dwordx4 v[148:149], v[70:73], off offset:512
	global_store_dwordx4 v[148:149], v[66:69], off offset:528
	global_load_dwordx2 v[82:83], v[102:103], off
	global_load_dwordx4 v[66:69], v[100:101], off
	global_load_dwordx4 v[70:73], v[100:101], off offset:16
	global_load_dwordx4 v[74:77], v[100:101], off offset:512
	global_load_dwordx4 v[78:81], v[100:101], off offset:528
	v_add_u32_e32 v84, 0x90, v174
	v_ashrrev_i32_e32 v85, 31, v84
	v_lshlrev_b32_e32 v86, 1, v84
	v_ashrrev_i32_e32 v87, 31, v86
	v_lshlrev_b64 v[84:85], 13, v[84:85]
	v_lshl_add_u64 v[86:87], v[86:87], 2, s[22:23]
	v_lshl_add_u64 v[84:85], s[20:21], 0, v[84:85]
	v_lshl_add_u64 v[84:85], v[84:85], 0, v[172:173]
	s_waitcnt vmcnt(3)
	v_sub_f32_e32 v69, v69, v82
	v_sub_f32_e32 v68, v68, v82
	v_sub_f32_e32 v67, v67, v82
	v_sub_f32_e32 v66, v66, v82
	s_waitcnt vmcnt(2)
	v_sub_f32_e32 v73, v73, v82
	v_sub_f32_e32 v72, v72, v82
	v_sub_f32_e32 v71, v71, v82
	v_sub_f32_e32 v70, v70, v82
	s_waitcnt vmcnt(1)
	v_sub_f32_e32 v77, v77, v82
	v_sub_f32_e32 v76, v76, v82
	v_sub_f32_e32 v75, v75, v82
	v_sub_f32_e32 v74, v74, v82
	s_waitcnt vmcnt(0)
	v_sub_f32_e32 v81, v81, v82
	v_sub_f32_e32 v80, v80, v82
	v_sub_f32_e32 v79, v79, v82
	v_sub_f32_e32 v78, v78, v82
	v_mul_f32_e32 v66, v83, v66
	v_mul_f32_e32 v67, v83, v67
	v_mul_f32_e32 v68, v83, v68
	v_mul_f32_e32 v69, v83, v69
	v_mul_f32_e32 v70, v83, v70
	v_mul_f32_e32 v71, v83, v71
	v_mul_f32_e32 v72, v83, v72
	v_mul_f32_e32 v73, v83, v73
	v_mul_f32_e32 v74, v83, v74
	v_mul_f32_e32 v75, v83, v75
	v_mul_f32_e32 v76, v83, v76
	v_mul_f32_e32 v77, v83, v77
	v_mul_f32_e32 v78, v83, v78
	v_mul_f32_e32 v79, v83, v79
	v_mul_f32_e32 v80, v83, v80
	v_mul_f32_e32 v81, v83, v81
	v_fma_f32 v68, v132, v68, v120
	v_fma_f32 v69, v133, v69, v121
	v_fma_f32 v66, v130, v66, v118
	v_fma_f32 v67, v131, v67, v119
	v_fma_f32 v72, v116, v72, v136
	v_fma_f32 v73, v117, v73, v137
	v_fma_f32 v70, v114, v70, v134
	v_fma_f32 v71, v115, v71, v135
	v_fma_f32 v76, v140, v76, v128
	v_fma_f32 v77, v141, v77, v129
	v_fma_f32 v74, v138, v74, v126
	v_fma_f32 v75, v139, v75, v127
	v_fma_f32 v80, v124, v80, v144
	v_fma_f32 v81, v125, v81, v145
	v_fma_f32 v78, v122, v78, v142
	v_fma_f32 v79, v123, v79, v143
	v_fmac_f32_e32 v64, s44, v68
	v_fmac_f32_e32 v65, s44, v69
	v_fmac_f32_e32 v62, s44, v66
	v_fmac_f32_e32 v63, s44, v67
	v_fmac_f32_e32 v60, s44, v72
	v_fmac_f32_e32 v61, s44, v73
	v_fmac_f32_e32 v58, s44, v70
	v_fmac_f32_e32 v59, s44, v71
	v_fmac_f32_e32 v56, s44, v76
	v_fmac_f32_e32 v57, s44, v77
	v_fmac_f32_e32 v54, s44, v74
	v_fmac_f32_e32 v55, s44, v75
	v_fmac_f32_e32 v52, s44, v80
	v_fmac_f32_e32 v53, s44, v81
	v_fmac_f32_e32 v50, s44, v78
	v_fmac_f32_e32 v51, s44, v79
	global_store_dwordx4 v[100:101], v[62:65], off
	global_store_dwordx4 v[100:101], v[58:61], off offset:16
	global_store_dwordx4 v[100:101], v[54:57], off offset:512
	global_store_dwordx4 v[100:101], v[50:53], off offset:528
	global_load_dwordx2 v[66:67], v[86:87], off
	global_load_dwordx4 v[50:53], v[84:85], off
	global_load_dwordx4 v[54:57], v[84:85], off offset:16
	global_load_dwordx4 v[58:61], v[84:85], off offset:512
	global_load_dwordx4 v[62:65], v[84:85], off offset:528
	v_add_u32_e32 v68, 0xa0, v174
	v_ashrrev_i32_e32 v69, 31, v68
	v_lshlrev_b32_e32 v70, 1, v68
	v_ashrrev_i32_e32 v71, 31, v70
	v_lshlrev_b64 v[68:69], 13, v[68:69]
	v_lshl_add_u64 v[70:71], v[70:71], 2, s[22:23]
	v_lshl_add_u64 v[68:69], s[20:21], 0, v[68:69]
	v_lshl_add_u64 v[68:69], v[68:69], 0, v[172:173]
	s_waitcnt vmcnt(3)
	v_sub_f32_e32 v53, v53, v66
	v_sub_f32_e32 v52, v52, v66
	v_sub_f32_e32 v51, v51, v66
	v_sub_f32_e32 v50, v50, v66
	s_waitcnt vmcnt(2)
	v_sub_f32_e32 v57, v57, v66
	v_sub_f32_e32 v56, v56, v66
	v_sub_f32_e32 v55, v55, v66
	v_sub_f32_e32 v54, v54, v66
	s_waitcnt vmcnt(1)
	v_sub_f32_e32 v61, v61, v66
	v_sub_f32_e32 v60, v60, v66
	v_sub_f32_e32 v59, v59, v66
	v_sub_f32_e32 v58, v58, v66
	s_waitcnt vmcnt(0)
	v_sub_f32_e32 v65, v65, v66
	v_sub_f32_e32 v64, v64, v66
	v_sub_f32_e32 v63, v63, v66
	v_sub_f32_e32 v62, v62, v66
	v_mul_f32_e32 v50, v67, v50
	v_mul_f32_e32 v51, v67, v51
	v_mul_f32_e32 v52, v67, v52
	v_mul_f32_e32 v53, v67, v53
	v_mul_f32_e32 v54, v67, v54
	v_mul_f32_e32 v55, v67, v55
	v_mul_f32_e32 v56, v67, v56
	v_mul_f32_e32 v57, v67, v57
	v_mul_f32_e32 v58, v67, v58
	v_mul_f32_e32 v59, v67, v59
	v_mul_f32_e32 v60, v67, v60
	v_mul_f32_e32 v61, v67, v61
	v_mul_f32_e32 v62, v67, v62
	v_mul_f32_e32 v63, v67, v63
	v_mul_f32_e32 v64, v67, v64
	v_mul_f32_e32 v65, v67, v65
	v_fma_f32 v52, v132, v52, v120
	v_fma_f32 v53, v133, v53, v121
	v_fma_f32 v50, v130, v50, v118
	v_fma_f32 v51, v131, v51, v119
	v_fma_f32 v56, v116, v56, v136
	v_fma_f32 v57, v117, v57, v137
	v_fma_f32 v54, v114, v54, v134
	v_fma_f32 v55, v115, v55, v135
	v_fma_f32 v60, v140, v60, v128
	v_fma_f32 v61, v141, v61, v129
	v_fma_f32 v58, v138, v58, v126
	v_fma_f32 v59, v139, v59, v127
	v_fma_f32 v64, v124, v64, v144
	v_fma_f32 v65, v125, v65, v145
	v_fma_f32 v62, v122, v62, v142
	v_fma_f32 v63, v123, v63, v143
	v_fmac_f32_e32 v48, s44, v52
	v_fmac_f32_e32 v49, s44, v53
	v_fmac_f32_e32 v46, s44, v50
	v_fmac_f32_e32 v47, s44, v51
	v_fmac_f32_e32 v44, s44, v56
	v_fmac_f32_e32 v45, s44, v57
	v_fmac_f32_e32 v42, s44, v54
	v_fmac_f32_e32 v43, s44, v55
	v_fmac_f32_e32 v40, s44, v60
	v_fmac_f32_e32 v41, s44, v61
	v_fmac_f32_e32 v38, s44, v58
	v_fmac_f32_e32 v39, s44, v59
	v_fmac_f32_e32 v36, s44, v64
	v_fmac_f32_e32 v37, s44, v65
	v_fmac_f32_e32 v34, s44, v62
	v_fmac_f32_e32 v35, s44, v63
	global_store_dwordx4 v[84:85], v[46:49], off
	global_store_dwordx4 v[84:85], v[42:45], off offset:16
	global_store_dwordx4 v[84:85], v[38:41], off offset:512
	global_store_dwordx4 v[84:85], v[34:37], off offset:528
	global_load_dwordx2 v[50:51], v[70:71], off
	global_load_dwordx4 v[34:37], v[68:69], off
	global_load_dwordx4 v[38:41], v[68:69], off offset:16
	global_load_dwordx4 v[42:45], v[68:69], off offset:512
	global_load_dwordx4 v[46:49], v[68:69], off offset:528
	v_add_u32_e32 v52, 0xb0, v174
	v_ashrrev_i32_e32 v53, 31, v52
	v_lshlrev_b32_e32 v54, 1, v52
	v_ashrrev_i32_e32 v55, 31, v54
	v_lshlrev_b64 v[52:53], 13, v[52:53]
	v_lshl_add_u64 v[54:55], v[54:55], 2, s[22:23]
	v_lshl_add_u64 v[52:53], s[20:21], 0, v[52:53]
	v_lshl_add_u64 v[52:53], v[52:53], 0, v[172:173]
	s_waitcnt vmcnt(3)
	v_sub_f32_e32 v37, v37, v50
	v_sub_f32_e32 v36, v36, v50
	v_sub_f32_e32 v35, v35, v50
	v_sub_f32_e32 v34, v34, v50
	s_waitcnt vmcnt(2)
	v_sub_f32_e32 v41, v41, v50
	v_sub_f32_e32 v40, v40, v50
	v_sub_f32_e32 v39, v39, v50
	v_sub_f32_e32 v38, v38, v50
	s_waitcnt vmcnt(1)
	v_sub_f32_e32 v45, v45, v50
	v_sub_f32_e32 v44, v44, v50
	v_sub_f32_e32 v43, v43, v50
	v_sub_f32_e32 v42, v42, v50
	s_waitcnt vmcnt(0)
	v_sub_f32_e32 v49, v49, v50
	v_sub_f32_e32 v48, v48, v50
	v_sub_f32_e32 v47, v47, v50
	v_sub_f32_e32 v46, v46, v50
	v_mul_f32_e32 v34, v51, v34
	v_mul_f32_e32 v35, v51, v35
	v_mul_f32_e32 v36, v51, v36
	v_mul_f32_e32 v37, v51, v37
	v_mul_f32_e32 v38, v51, v38
	v_mul_f32_e32 v39, v51, v39
	v_mul_f32_e32 v40, v51, v40
	v_mul_f32_e32 v41, v51, v41
	v_mul_f32_e32 v42, v51, v42
	v_mul_f32_e32 v43, v51, v43
	v_mul_f32_e32 v44, v51, v44
	v_mul_f32_e32 v45, v51, v45
	v_mul_f32_e32 v46, v51, v46
	v_mul_f32_e32 v47, v51, v47
	v_mul_f32_e32 v48, v51, v48
	v_mul_f32_e32 v49, v51, v49
	v_fma_f32 v36, v132, v36, v120
	v_fma_f32 v37, v133, v37, v121
	v_fma_f32 v34, v130, v34, v118
	v_fma_f32 v35, v131, v35, v119
	v_fma_f32 v40, v116, v40, v136
	v_fma_f32 v41, v117, v41, v137
	v_fma_f32 v38, v114, v38, v134
	v_fma_f32 v39, v115, v39, v135
	v_fma_f32 v44, v140, v44, v128
	v_fma_f32 v45, v141, v45, v129
	v_fma_f32 v42, v138, v42, v126
	v_fma_f32 v43, v139, v43, v127
	v_fma_f32 v48, v124, v48, v144
	v_fma_f32 v49, v125, v49, v145
	v_fma_f32 v46, v122, v46, v142
	v_fma_f32 v47, v123, v47, v143
	v_fmac_f32_e32 v32, s44, v36
	v_fmac_f32_e32 v33, s44, v37
	v_fmac_f32_e32 v30, s44, v34
	v_fmac_f32_e32 v31, s44, v35
	v_fmac_f32_e32 v28, s44, v40
	v_fmac_f32_e32 v29, s44, v41
	v_fmac_f32_e32 v26, s44, v38
	v_fmac_f32_e32 v27, s44, v39
	v_fmac_f32_e32 v24, s44, v44
	v_fmac_f32_e32 v25, s44, v45
	v_fmac_f32_e32 v22, s44, v42
	v_fmac_f32_e32 v23, s44, v43
	v_fmac_f32_e32 v20, s44, v48
	v_fmac_f32_e32 v21, s44, v49
	v_fmac_f32_e32 v18, s44, v46
	v_fmac_f32_e32 v19, s44, v47
	global_store_dwordx4 v[68:69], v[30:33], off
	global_store_dwordx4 v[68:69], v[26:29], off offset:16
	global_store_dwordx4 v[68:69], v[22:25], off offset:512
	global_store_dwordx4 v[68:69], v[18:21], off offset:528
	global_load_dwordx2 v[34:35], v[54:55], off
	global_load_dwordx4 v[18:21], v[52:53], off
	global_load_dwordx4 v[22:25], v[52:53], off offset:16
	global_load_dwordx4 v[26:29], v[52:53], off offset:512
	global_load_dwordx4 v[30:33], v[52:53], off offset:528
	s_waitcnt vmcnt(3)
	v_sub_f32_e32 v21, v21, v34
	v_sub_f32_e32 v20, v20, v34
	v_sub_f32_e32 v19, v19, v34
	v_sub_f32_e32 v18, v18, v34
	s_waitcnt vmcnt(2)
	v_sub_f32_e32 v25, v25, v34
	v_sub_f32_e32 v24, v24, v34
	v_sub_f32_e32 v23, v23, v34
	v_sub_f32_e32 v22, v22, v34
	s_waitcnt vmcnt(1)
	v_sub_f32_e32 v29, v29, v34
	v_sub_f32_e32 v28, v28, v34
	v_sub_f32_e32 v27, v27, v34
	v_sub_f32_e32 v26, v26, v34
	s_waitcnt vmcnt(0)
	v_sub_f32_e32 v33, v33, v34
	v_sub_f32_e32 v32, v32, v34
	v_sub_f32_e32 v31, v31, v34
	v_sub_f32_e32 v30, v30, v34
	v_mul_f32_e32 v18, v35, v18
	v_mul_f32_e32 v19, v35, v19
	v_mul_f32_e32 v20, v35, v20
	v_mul_f32_e32 v21, v35, v21
	v_mul_f32_e32 v22, v35, v22
	v_mul_f32_e32 v23, v35, v23
	v_mul_f32_e32 v24, v35, v24
	v_mul_f32_e32 v25, v35, v25
	v_mul_f32_e32 v26, v35, v26
	v_mul_f32_e32 v27, v35, v27
	v_mul_f32_e32 v28, v35, v28
	v_mul_f32_e32 v29, v35, v29
	v_mul_f32_e32 v30, v35, v30
	v_mul_f32_e32 v31, v35, v31
	v_mul_f32_e32 v32, v35, v32
	v_mul_f32_e32 v33, v35, v33
	v_fma_f32 v20, v132, v20, v120
	v_fma_f32 v21, v133, v21, v121
	v_fma_f32 v18, v130, v18, v118
	v_fma_f32 v19, v131, v19, v119
	v_fma_f32 v24, v116, v24, v136
	v_fma_f32 v25, v117, v25, v137
	v_fma_f32 v22, v114, v22, v134
	v_fma_f32 v23, v115, v23, v135
	v_fma_f32 v28, v140, v28, v128
	v_fma_f32 v29, v141, v29, v129
	v_fma_f32 v26, v138, v26, v126
	v_fma_f32 v27, v139, v27, v127
	v_fma_f32 v32, v124, v32, v144
	v_fma_f32 v33, v125, v33, v145
	v_fma_f32 v30, v122, v30, v142
	v_fma_f32 v31, v123, v31, v143
	v_fmac_f32_e32 v16, s44, v20
	v_fmac_f32_e32 v17, s44, v21
	v_fmac_f32_e32 v14, s44, v18
	v_fmac_f32_e32 v15, s44, v19
	v_fmac_f32_e32 v12, s44, v24
	v_fmac_f32_e32 v13, s44, v25
	v_fmac_f32_e32 v10, s44, v22
	v_fmac_f32_e32 v11, s44, v23
	v_fmac_f32_e32 v8, s44, v28
	v_fmac_f32_e32 v9, s44, v29
	v_fmac_f32_e32 v6, s44, v26
	v_fmac_f32_e32 v7, s44, v27
	v_fmac_f32_e32 v4, s44, v32
	v_fmac_f32_e32 v5, s44, v33
	v_fmac_f32_e32 v2, s44, v30
	v_fmac_f32_e32 v3, s44, v31
	global_store_dwordx4 v[52:53], v[14:17], off
	global_store_dwordx4 v[52:53], v[10:13], off offset:16
	global_store_dwordx4 v[52:53], v[6:9], off offset:512
	global_store_dwordx4 v[52:53], v[2:5], off offset:528
	s_cbranch_vccnz .LBB0_1062
	s_andn2_b64 vcc, exec, s[18:19]
	s_cbranch_vccnz .LBB0_1061
	s_barrier
	s_branch .LBB0_1061

.LBB0_1138:
	s_or_b64 exec, exec, s[4:5]
	v_mov_b32_e32 v31, v128
	v_mov_b32_e32 v27, v129
	v_mov_b32_e32 v128, v126
	v_mov_b32_e32 v129, v124
	v_mul_f32_e32 v30, v30, v28
	v_mul_f32_e32 v31, v31, v28
	v_mov_b32_e32 v124, v127
	v_mul_f32_e32 v128, v128, v28
	v_mul_f32_e32 v129, v129, v28
	s_waitcnt vmcnt(13)
	v_fma_f32 v30, v88, v30, v92
	v_fma_f32 v31, v89, v31, v93
	v_mul_f32_e32 v88, v124, v28
	v_mul_f32_e32 v89, v125, v28
	v_mul_f32_e32 v26, v26, v28
	v_mul_f32_e32 v27, v27, v28
	v_mul_f32_e32 v24, v24, v28
	v_mul_f32_e32 v25, v25, v28
	v_mul_f32_e32 v22, v22, v28
	v_mul_f32_e32 v23, v23, v28
	v_mul_f32_e32 v20, v20, v28
	v_mul_f32_e32 v21, v21, v28
	v_mul_f32_e32 v18, v18, v28
	v_mul_f32_e32 v19, v19, v28
	v_mul_f32_e32 v16, v16, v28
	v_mul_f32_e32 v17, v17, v28
	v_mul_f32_e32 v14, v14, v28
	v_mul_f32_e32 v15, v15, v28
	v_mul_f32_e32 v12, v12, v28
	v_mul_f32_e32 v13, v13, v28
	v_mul_f32_e32 v10, v10, v28
	v_mul_f32_e32 v11, v11, v28
	v_mul_f32_e32 v8, v8, v28
	v_mul_f32_e32 v9, v9, v28
	v_mul_f32_e32 v6, v6, v28
	v_mul_f32_e32 v7, v7, v28
	v_mul_f32_e32 v4, v4, v28
	v_mul_f32_e32 v5, v5, v28
	v_mul_f32_e32 v2, v2, v28
	v_mul_f32_e32 v3, v3, v28
	v_lshl_add_u64 v[28:29], s[72:73], 0, v[122:123]
	v_add_co_u32_e32 v28, vcc, s2, v28
	v_add_u32_e32 v96, s14, v96
	s_nop 0
	v_addc_co_u32_e32 v29, vcc, 0, v29, vcc
	v_cmp_lt_i32_e32 vcc, s3, v96
	s_waitcnt vmcnt(12)
	v_fma_f32 v26, v80, v26, v84
	v_fma_f32 v27, v81, v27, v85
	s_waitcnt vmcnt(9)
	v_fma_f32 v22, v72, v22, v76
	v_fma_f32 v23, v73, v23, v77
	s_waitcnt vmcnt(8)
	v_fma_f32 v18, v64, v18, v68
	v_fma_f32 v19, v65, v19, v69
	s_waitcnt vmcnt(6)
	v_fma_f32 v14, v56, v14, v60
	v_fma_f32 v15, v57, v15, v61
	s_waitcnt vmcnt(4)
	v_fma_f32 v10, v48, v10, v52
	v_fma_f32 v11, v49, v11, v53
	s_waitcnt vmcnt(2)
	v_fma_f32 v6, v40, v6, v44
	v_fma_f32 v7, v41, v7, v45
	s_waitcnt vmcnt(0)
	v_fma_f32 v2, v32, v2, v36
	v_fma_f32 v3, v33, v3, v37
	v_add_u32_e32 v118, s0, v118
	v_lshl_add_u64 v[120:121], v[120:121], 0, s[18:19]
	s_or_b64 s[22:23], vcc, s[22:23]
	v_lshl_add_u64 v[122:123], v[122:123], 0, s[20:21]
	v_fma_f32 v90, v90, v128, v94
	v_fma_f32 v91, v91, v129, v95
	v_fma_f32 v82, v82, v88, v86
	v_fma_f32 v83, v83, v89, v87
	v_fma_f32 v24, v74, v24, v78
	v_fma_f32 v25, v75, v25, v79
	v_fma_f32 v20, v66, v20, v70
	v_fma_f32 v21, v67, v21, v71
	v_fma_f32 v16, v58, v16, v62
	v_fma_f32 v17, v59, v17, v63
	v_fma_f32 v12, v50, v12, v54
	v_fma_f32 v13, v51, v13, v55
	v_fma_f32 v8, v42, v8, v46
	v_fma_f32 v9, v43, v9, v47
	v_fma_f32 v4, v34, v4, v38
	v_fma_f32 v5, v35, v5, v39
	v_cvt_pk_bf16_f32 v30, v30, v31
	v_cvt_pk_bf16_f32 v31, v90, v91
	global_store_dwordx2 v[28:29], v[30:31], off
	v_cvt_pk_bf16_f32 v26, v26, v27
	v_cvt_pk_bf16_f32 v27, v82, v83
	global_store_dwordx2 v[28:29], v[26:27], off offset:512
	v_cvt_pk_bf16_f32 v22, v22, v23
	v_cvt_pk_bf16_f32 v23, v24, v25
	global_store_dwordx2 v[28:29], v[22:23], off offset:1024
	v_cvt_pk_bf16_f32 v18, v18, v19
	v_cvt_pk_bf16_f32 v19, v20, v21
	global_store_dwordx2 v[28:29], v[18:19], off offset:1536
	v_cvt_pk_bf16_f32 v14, v14, v15
	v_cvt_pk_bf16_f32 v15, v16, v17
	global_store_dwordx2 v[28:29], v[14:15], off offset:2048
	v_cvt_pk_bf16_f32 v10, v10, v11
	v_cvt_pk_bf16_f32 v11, v12, v13
	global_store_dwordx2 v[28:29], v[10:11], off offset:2560
	v_cvt_pk_bf16_f32 v6, v6, v7
	v_cvt_pk_bf16_f32 v7, v8, v9
	global_store_dwordx2 v[28:29], v[6:7], off offset:3072
	v_cvt_pk_bf16_f32 v2, v2, v3
	v_cvt_pk_bf16_f32 v3, v4, v5
	global_store_dwordx2 v[28:29], v[2:3], off offset:3584
	s_andn2_b64 exec, exec, s[22:23]
	s_cbranch_execz .LBB0_1141
.LBB0_1139:
	v_lshl_add_u64 v[2:3], s[72:73], 0, v[120:121]
	v_add_co_u32_e32 v4, vcc, 0x1ab00000, v2
	s_nop 1
	v_addc_co_u32_e32 v5, vcc, 0, v3, vcc
	global_load_dwordx4 v[30:33], v[4:5], off
	global_load_dwordx4 v[26:29], v[4:5], off offset:1024
	global_load_dwordx4 v[22:25], v[4:5], off offset:2048
	global_load_dwordx4 v[18:21], v[4:5], off offset:3072
	v_add_co_u32_e32 v2, vcc, 0x1ab01000, v2
	s_nop 1
	v_addc_co_u32_e32 v3, vcc, 0, v3, vcc
	global_load_dwordx4 v[14:17], v[2:3], off
	global_load_dwordx4 v[10:13], v[2:3], off offset:1024
	global_load_dwordx4 v[6:9], v[2:3], off offset:2048
	s_nop 0
	global_load_dwordx4 v[2:5], v[2:3], off offset:3072
	s_waitcnt vmcnt(4)
	v_mov_b32_e32 v34, v30
	v_mov_b32_e32 v35, v26
	v_mov_b32_e32 v36, v31
	v_mov_b32_e32 v37, v27
	v_mov_b32_e32 v38, v32
	v_mov_b32_e32 v39, v28
	v_mov_b32_e32 v40, v33
	v_mov_b32_e32 v41, v29
	v_mov_b32_e32 v42, v23
	v_mov_b32_e32 v43, v24
	v_mov_b32_e32 v44, v22
	v_mov_b32_e32 v45, v25
	v_add_f32_e32 v34, v34, v36
	v_add_f32_e32 v35, v35, v37
	v_add_f32_e32 v36, v38, v40
	v_add_f32_e32 v37, v39, v41
	v_add_f32_e32 v38, v42, v44
	v_add_f32_e32 v39, v43, v45
	v_add_f32_e32 v34, v34, v36
	v_add_f32_e32 v35, v35, v37
	v_add_f32_e32 v36, v38, v39
	v_add_f32_e32 v37, v39, v38
	v_add_f32_e32 v34, 0, v34
	v_add_f32_e32 v46, v18, v19
	v_add_f32_e32 v48, v20, v21
	v_add_f32_e32 v40, v34, v35
	s_waitcnt vmcnt(3)
	v_mov_b32_e32 v41, v14
	v_mov_b32_e32 v47, v16
	v_mov_b32_e32 v49, v17
	v_mov_b32_e32 v37, v15
	s_waitcnt vmcnt(2)
	v_mov_b32_e32 v42, v11
	v_mov_b32_e32 v43, v12
	v_mov_b32_e32 v44, v10
	v_mov_b32_e32 v45, v13
	v_add_f32_e32 v38, v46, v48
	v_add_f32_e32 v39, v47, v49
	v_add_f32_e32 v34, v40, v36
	v_add_f32_e32 v35, v41, v37
	v_add_f32_e32 v42, v42, v44
	v_add_f32_e32 v43, v43, v45
	v_add_f32_e32 v34, v34, v38
	v_add_f32_e32 v35, v35, v39
	v_pk_add_f32 v[42:43], v[42:43], v[42:43] op_sel:[0,1] op_sel_hi:[1,0]
	v_pk_add_f32 v[34:35], v[34:35], v[34:35] op_sel:[0,1] op_sel_hi:[1,0]
	s_waitcnt vmcnt(1)
	v_add_f32_e32 v50, v6, v7
	v_add_f32_e32 v52, v8, v9
	s_waitcnt vmcnt(0)
	v_mov_b32_e32 v51, v4
	v_mov_b32_e32 v53, v5
	v_mov_b32_e32 v43, v3
	v_mov_b32_e32 v35, v2
	v_add_f32_e32 v44, v50, v52
	v_add_f32_e32 v45, v51, v53
	v_add_f32_e32 v34, v34, v42
	v_add_f32_e32 v35, v35, v43
	s_nop 0
	v_add_f32_e32 v34, v34, v44
	v_add_f32_e32 v35, v35, v45
	s_nop 0
	v_add_f32_e32 v34, v34, v35
	ds_bpermute_b32 v35, v1, v34
	s_waitcnt lgkmcnt(0)
	v_add_f32_e32 v34, v34, v35
	ds_bpermute_b32 v35, v130, v34
	s_waitcnt lgkmcnt(0)
	v_add_f32_e32 v34, v34, v35
	ds_bpermute_b32 v35, v131, v34
	s_waitcnt lgkmcnt(0)
	v_add_f32_e32 v34, v34, v35
	ds_bpermute_b32 v35, v132, v34
	s_waitcnt lgkmcnt(0)
	v_add_f32_e32 v34, v34, v35
	ds_bpermute_b32 v35, v133, v34
	s_waitcnt lgkmcnt(0)
	v_add_f32_e32 v34, v34, v35
	ds_bpermute_b32 v35, v134, v34
	s_waitcnt lgkmcnt(0)
	v_add_f32_e32 v119, v34, v35
	v_fmamk_f32 v124, v119, 0xba000000, v33
	v_fmamk_f32 v128, v119, 0xba000000, v31
	v_fmamk_f32 v125, v119, 0xba000000, v29
	v_fmamk_f32 v129, v119, 0xba000000, v27
	v_fmac_f32_e32 v26, 0xba000000, v119
	v_fmamk_f32 v25, v119, 0xba000000, v25
	v_fmamk_f32 v24, v119, 0xba000000, v24
	v_fmamk_f32 v23, v119, 0xba000000, v23
	v_fmac_f32_e32 v22, 0xba000000, v119
	v_fmamk_f32 v126, v119, 0xba000000, v32
	v_fmac_f32_e32 v30, 0xba000000, v119
	v_fmamk_f32 v127, v119, 0xba000000, v28
	v_mov_b32_e32 v31, v26
	v_mul_f32_e32 v28, v128, v128
	v_mul_f32_e32 v29, v129, v129
	v_mul_f32_e32 v32, v124, v124
	v_mul_f32_e32 v33, v125, v125
	v_mul_f32_e32 v34, v24, v24
	v_mul_f32_e32 v35, v25, v25
	v_mul_f32_e32 v36, v22, v22
	v_mul_f32_e32 v37, v23, v23
	v_fmamk_f32 v20, v119, 0xba000000, v20
	v_fmac_f32_e32 v18, 0xba000000, v119
	v_fmac_f32_e32 v28, v30, v30
	v_fmac_f32_e32 v29, v31, v31
	v_fmac_f32_e32 v32, v126, v126
	v_fmac_f32_e32 v33, v127, v127
	v_pk_mov_b32 v[50:51], v[36:37], v[34:35] op_sel:[1,0]
	v_mov_b32_e32 v37, v35
	v_fmamk_f32 v21, v119, 0xba000000, v21
	v_fmamk_f32 v19, v119, 0xba000000, v19
	v_fmamk_f32 v13, v119, 0xba000000, v13
	v_fmamk_f32 v12, v119, 0xba000000, v12
	v_fmamk_f32 v11, v119, 0xba000000, v11
	v_fmac_f32_e32 v10, 0xba000000, v119
	v_mul_f32_e32 v38, v18, v18
	v_mul_f32_e32 v40, v20, v20
	v_add_f32_e32 v28, v28, v32
	v_add_f32_e32 v29, v29, v33
	v_add_f32_e32 v32, v50, v36
	v_add_f32_e32 v33, v51, v37
	v_fmamk_f32 v17, v119, 0xba000000, v17
	v_fmamk_f32 v16, v119, 0xba000000, v16
	v_fmamk_f32 v15, v119, 0xba000000, v15
	v_fmac_f32_e32 v14, 0xba000000, v119
	v_mul_f32_e32 v42, v12, v12
	v_mul_f32_e32 v43, v13, v13
	v_mul_f32_e32 v44, v10, v10
	v_mul_f32_e32 v45, v11, v11
	v_fma_f32 v34, v18, v18, v38
	v_fma_f32 v35, v19, v19, v38
	v_fma_f32 v38, v20, v20, v40
	v_fma_f32 v39, v21, v21, v40
	v_add_f32_e32 v29, v28, v29
	v_add_f32_e32 v28, v28, v28
	v_add_f32_e32 v33, v32, v33
	v_add_f32_e32 v32, v32, v32
	v_fmamk_f32 v8, v119, 0xba000000, v8
	v_fmac_f32_e32 v6, 0xba000000, v119
	v_pk_mov_b32 v[40:41], v[44:45], v[42:43] op_sel:[1,0]
	v_mov_b32_e32 v45, v43
	v_mul_f32_e32 v34, v14, v14
	v_mul_f32_e32 v38, v15, v15
	v_mul_f32_e32 v32, v16, v16
	v_mul_f32_e32 v28, v17, v17
	v_fmamk_f32 v9, v119, 0xba000000, v9
	v_fmamk_f32 v7, v119, 0xba000000, v7
	v_mul_f32_e32 v46, v6, v6
	v_mul_f32_e32 v48, v8, v8
	v_add_f32_e32 v36, v40, v44
	v_add_f32_e32 v37, v41, v45
	v_add_f32_e32 v34, v34, v38
	v_add_f32_e32 v35, v35, v39
	v_add_f32_e32 v28, v32, v28
	v_add_f32_e32 v29, v33, v29
	v_fma_f32 v136, v6, v6, v46
	v_fma_f32 v137, v7, v7, v46
	v_fma_f32 v138, v8, v8, v48
	v_fma_f32 v139, v9, v9, v48
	v_add_f32_e32 v140, v36, v36
	v_add_f32_e32 v141, v36, v37
	v_add_f32_e32 v28, v34, v28
	v_add_f32_e32 v29, v35, v29
	global_load_dwordx4 v[88:91], v[98:99], off
	global_load_dwordx4 v[80:83], v[98:99], off offset:1024
	global_load_dwordx4 v[92:95], v[100:101], off
	global_load_dwordx4 v[84:87], v[100:101], off offset:1024
	global_load_dwordx4 v[72:75], v[98:99], off offset:2048
	global_load_dwordx4 v[64:67], v[98:99], off offset:3072
	global_load_dwordx4 v[76:79], v[100:101], off offset:2048
	global_load_dwordx4 v[68:71], v[100:101], off offset:3072
	global_load_dwordx4 v[56:59], v[102:103], off
	global_load_dwordx4 v[60:63], v[104:105], off
	global_load_dwordx4 v[48:51], v[106:107], off
	global_load_dwordx4 v[52:55], v[108:109], off
	global_load_dwordx4 v[40:43], v[110:111], off
	global_load_dwordx4 v[44:47], v[112:113], off
	global_load_dwordx4 v[32:35], v[114:115], off
	global_load_dwordx4 v[36:39], v[116:117], off
	v_fmamk_f32 v5, v119, 0xba000000, v5
	v_add_f32_e32 v29, v28, v29
	v_add_f32_e32 v28, v28, v28
	v_fmamk_f32 v4, v119, 0xba000000, v4
	v_fmamk_f32 v3, v119, 0xba000000, v3
	v_fmac_f32_e32 v2, 0xba000000, v119
	v_mul_f32_e32 v136, v2, v2
	v_mul_f32_e32 v138, v3, v3
	v_mul_f32_e32 v140, v4, v4
	v_mul_f32_e32 v28, v5, v5
	v_add_f32_e32 v136, v136, v138
	v_add_f32_e32 v137, v137, v139
	v_add_f32_e32 v28, v140, v28
	v_add_f32_e32 v29, v141, v29
	s_nop 0
	v_add_f32_e32 v28, v136, v28
	v_add_f32_e32 v29, v137, v29
	s_nop 0
	v_add_f32_e32 v27, v28, v29
	ds_bpermute_b32 v28, v1, v27
	s_waitcnt lgkmcnt(0)
	v_add_f32_e32 v27, v27, v28
	ds_bpermute_b32 v28, v130, v27
	s_waitcnt lgkmcnt(0)
	v_add_f32_e32 v27, v27, v28
	ds_bpermute_b32 v28, v131, v27
	s_waitcnt lgkmcnt(0)
	v_add_f32_e32 v27, v27, v28
	ds_bpermute_b32 v28, v132, v27
	s_waitcnt lgkmcnt(0)
	v_add_f32_e32 v27, v27, v28
	ds_bpermute_b32 v28, v133, v27
	s_waitcnt lgkmcnt(0)
	v_add_f32_e32 v27, v27, v28
	ds_bpermute_b32 v28, v134, v27
	s_waitcnt lgkmcnt(0)
	v_add_f32_e32 v27, v27, v28
	v_fmamk_f32 v27, v27, 0x3a000000, v97
	v_mul_f32_e32 v28, 0x4f800000, v27
	v_cmp_gt_f32_e32 vcc, s1, v27
	s_nop 1
	v_cndmask_b32_e32 v27, v27, v28, vcc
	v_sqrt_f32_e32 v28, v27
	s_nop 0
	v_add_u32_e32 v29, -1, v28
	v_add_u32_e32 v31, 1, v28
	v_fma_f32 v136, -v29, v28, v27
	v_fma_f32 v137, -v31, v28, v27
	v_cmp_ge_f32_e64 s[8:9], 0, v136
	s_nop 1
	v_cndmask_b32_e64 v28, v28, v29, s[8:9]
	v_cmp_lt_f32_e64 s[8:9], 0, v137
	s_nop 1
	v_cndmask_b32_e64 v28, v28, v31, s[8:9]
	v_mul_f32_e32 v29, 0x37800000, v28
	v_cndmask_b32_e32 v28, v28, v29, vcc
	v_cmp_class_f32_e32 vcc, v27, v135
	s_nop 1
	v_cndmask_b32_e32 v27, v28, v27, vcc
	v_div_scale_f32 v28, s[4:5], v27, v27, 1.0
	v_rcp_f32_e32 v29, v28
	s_nop 0
	v_fma_f32 v31, -v28, v29, 1.0
	v_fmac_f32_e32 v29, v31, v29
	v_div_scale_f32 v31, vcc, 1.0, v27, 1.0
	v_mul_f32_e32 v136, v31, v29
	v_fma_f32 v137, -v28, v136, v31
	v_fmac_f32_e32 v136, v137, v29
	v_fma_f32 v28, -v28, v136, v31
	v_div_fmas_f32 v28, v28, v29, v136
	v_div_fixup_f32 v28, v28, v27, 1.0
	s_and_saveexec_b64 s[4:5], s[6:7]
	s_cbranch_execz .LBB0_1138
	v_mul_f32_e32 v136, 0x3a000000, v119
	v_ashrrev_i32_e32 v119, 31, v118
	v_lshl_add_u64 v[138:139], v[118:119], 2, s[16:17]
	v_mov_b32_e32 v137, v28
	global_store_dwordx2 v[138:139], v[136:137], off
	s_branch .LBB0_1138

.LBB0_1234:
	s_add_u32 s4, s72, s4
	s_addc_u32 s5, s73, s5
	v_lshlrev_b64 v[144:145], 2, v[134:135]
	v_lshl_add_u64 v[146:147], s[4:5], 0, v[144:145]
	v_mad_i64_i32 v[148:149], s[4:5], s90, v142, 0
	s_add_u32 s94, s72, s94
	v_lshlrev_b64 v[154:155], 2, v[148:149]
	v_lshl_add_u64 v[148:149], v[146:147], 0, v[154:155]
	s_addc_u32 s95, s73, s95
	global_load_dwordx4 v[150:153], v[148:149], off
	v_lshl_add_u64 v[148:149], s[94:95], 0, v[144:145]
	v_lshl_add_u64 v[144:145], v[148:149], 0, v[154:155]
	global_load_dwordx4 v[166:169], v[144:145], off
	v_mov_b32_e32 v134, v143
	v_ashrrev_i32_e32 v143, 31, v142
	s_mov_b64 s[4:5], -1
	v_lshl_add_u64 v[144:145], v[134:135], 1, s[10:11]
	s_and_b64 vcc, exec, s[92:93]
	s_waitcnt vmcnt(0)
	v_mul_f32_e32 v154, v124, v152
	v_mul_f32_e32 v155, v125, v153
	v_mul_f32_e32 v156, v122, v150
	v_mul_f32_e32 v157, v123, v151
	v_mul_f32_e32 v152, v128, v152
	v_mul_f32_e32 v153, v129, v153
	v_mul_f32_e32 v158, v126, v150
	v_mul_f32_e32 v159, v127, v151
	v_fma_f32 v150, v128, v168, -v154
	v_fma_f32 v151, v129, v169, -v155
	v_fma_f32 v156, v126, v166, -v156
	v_fma_f32 v157, v127, v167, -v157
	v_fmac_f32_e32 v152, v124, v168
	v_fmac_f32_e32 v153, v125, v169
	v_fma_f32 v154, v122, v166, v158
	v_fma_f32 v155, v123, v167, v159
	s_cbranch_vccz .LBB0_1236
	v_mul_lo_u32 v165, s89, v142
	v_mul_lo_u32 v168, s88, v143
	v_mad_u64_u32 v[166:167], s[4:5], s88, v142, 0
	v_add3_u32 v167, v167, v168, v165
	v_lshl_add_u64 v[166:167], v[166:167], 1, v[144:145]
	s_lshl_b32 s22, s90, 1
	v_cvt_pk_bf16_f32 v158, v156, v157
	v_cvt_pk_bf16_f32 v159, v150, v151
	global_store_dwordx2 v[166:167], v[158:159], off
	v_lshl_add_u64 v[166:167], v[166:167], 0, s[22:23]
	v_cvt_pk_bf16_f32 v158, v154, v155
	v_cvt_pk_bf16_f32 v159, v152, v153
	global_store_dwordx2 v[166:167], v[158:159], off
	s_mov_b64 s[4:5], 0

.LBB0_1238:
	v_or_b32_e32 v150, 16, v142
	v_mad_i64_i32 v[152:153], s[4:5], s90, v150, 0
	v_lshlrev_b64 v[156:157], 2, v[152:153]
	v_lshl_add_u64 v[152:153], v[146:147], 0, v[156:157]
	global_load_dwordx4 v[152:155], v[152:153], off
	v_lshl_add_u64 v[156:157], v[148:149], 0, v[156:157]
	global_load_dwordx4 v[166:169], v[156:157], off
	v_cndmask_b32_e64 v143, 0, 1, s[92:93]
	v_ashrrev_i32_e32 v151, 31, v150
	v_cmp_ne_u32_e64 s[10:11], 1, v143
	s_andn2_b64 vcc, exec, s[92:93]
	s_mov_b64 s[4:5], -1
	s_waitcnt vmcnt(1)
	v_mul_f32_e32 v156, v116, v154
	v_mul_f32_e32 v157, v117, v155
	v_mul_f32_e32 v158, v114, v152
	v_mul_f32_e32 v159, v115, v153
	v_mul_f32_e32 v154, v120, v154
	v_mul_f32_e32 v155, v121, v155
	v_mul_f32_e32 v170, v118, v152
	v_mul_f32_e32 v171, v119, v153
	s_waitcnt vmcnt(0)
	v_fma_f32 v152, v120, v168, -v156
	v_fma_f32 v153, v121, v169, -v157
	v_fma_f32 v158, v118, v166, -v158
	v_fma_f32 v159, v119, v167, -v159
	v_fmac_f32_e32 v154, v116, v168
	v_fmac_f32_e32 v155, v117, v169
	v_fma_f32 v156, v114, v166, v170
	v_fma_f32 v157, v115, v167, v171
	s_cbranch_vccnz .LBB0_1240
	v_mul_lo_u32 v143, s89, v150
	v_mul_lo_u32 v165, s88, v151
	v_mad_u64_u32 v[168:169], s[4:5], s88, v150, 0
	v_add3_u32 v169, v169, v165, v143
	v_lshl_add_u64 v[168:169], v[168:169], 1, v[144:145]
	s_lshl_b32 s22, s90, 1
	v_cvt_pk_bf16_f32 v166, v158, v159
	v_cvt_pk_bf16_f32 v167, v152, v153
	global_store_dwordx2 v[168:169], v[166:167], off
	v_lshl_add_u64 v[168:169], v[168:169], 0, s[22:23]
	s_mov_b64 s[4:5], 0
	v_cvt_pk_bf16_f32 v166, v156, v157
	v_cvt_pk_bf16_f32 v167, v154, v155
	global_store_dwordx2 v[168:169], v[166:167], off

.LBB0_1242:
	v_or_b32_e32 v150, 32, v142
	v_mad_i64_i32 v[152:153], s[4:5], s90, v150, 0
	v_lshlrev_b64 v[156:157], 2, v[152:153]
	v_lshl_add_u64 v[152:153], v[146:147], 0, v[156:157]
	global_load_dwordx4 v[152:155], v[152:153], off
	v_lshl_add_u64 v[156:157], v[148:149], 0, v[156:157]
	global_load_dwordx4 v[166:169], v[156:157], off
	s_and_b64 vcc, exec, s[10:11]
	v_ashrrev_i32_e32 v151, 31, v150
	s_mov_b64 s[4:5], -1
	s_waitcnt vmcnt(1)
	v_mul_f32_e32 v156, v108, v154
	v_mul_f32_e32 v157, v109, v155
	v_mul_f32_e32 v158, v106, v152
	v_mul_f32_e32 v159, v107, v153
	v_mul_f32_e32 v154, v112, v154
	v_mul_f32_e32 v155, v113, v155
	v_mul_f32_e32 v170, v110, v152
	v_mul_f32_e32 v171, v111, v153
	s_waitcnt vmcnt(0)
	v_fma_f32 v152, v112, v168, -v156
	v_fma_f32 v153, v113, v169, -v157
	v_fma_f32 v158, v110, v166, -v158
	v_fma_f32 v159, v111, v167, -v159
	v_fmac_f32_e32 v154, v108, v168
	v_fmac_f32_e32 v155, v109, v169
	v_fma_f32 v156, v106, v166, v170
	v_fma_f32 v157, v107, v167, v171
	s_cbranch_vccnz .LBB0_1244
	v_mul_lo_u32 v143, s89, v150
	v_mul_lo_u32 v165, s88, v151
	v_mad_u64_u32 v[168:169], s[4:5], s88, v150, 0
	v_add3_u32 v169, v169, v165, v143
	v_lshl_add_u64 v[168:169], v[168:169], 1, v[144:145]
	s_lshl_b32 s22, s90, 1
	v_cvt_pk_bf16_f32 v166, v158, v159
	v_cvt_pk_bf16_f32 v167, v152, v153
	global_store_dwordx2 v[168:169], v[166:167], off
	v_lshl_add_u64 v[168:169], v[168:169], 0, s[22:23]
	s_mov_b64 s[4:5], 0
	v_cvt_pk_bf16_f32 v166, v156, v157
	v_cvt_pk_bf16_f32 v167, v154, v155
	global_store_dwordx2 v[168:169], v[166:167], off

.LBB0_1246:
	v_or_b32_e32 v150, 48, v142
	v_mad_i64_i32 v[152:153], s[4:5], s90, v150, 0
	v_lshlrev_b64 v[156:157], 2, v[152:153]
	v_lshl_add_u64 v[152:153], v[146:147], 0, v[156:157]
	global_load_dwordx4 v[152:155], v[152:153], off
	v_lshl_add_u64 v[156:157], v[148:149], 0, v[156:157]
	global_load_dwordx4 v[166:169], v[156:157], off
	s_and_b64 vcc, exec, s[10:11]
	v_ashrrev_i32_e32 v151, 31, v150
	s_mov_b64 s[4:5], -1
	s_waitcnt vmcnt(1)
	v_mul_f32_e32 v156, v100, v154
	v_mul_f32_e32 v157, v101, v155
	v_mul_f32_e32 v158, v98, v152
	v_mul_f32_e32 v159, v99, v153
	v_mul_f32_e32 v154, v104, v154
	v_mul_f32_e32 v155, v105, v155
	v_mul_f32_e32 v170, v102, v152
	v_mul_f32_e32 v171, v103, v153
	s_waitcnt vmcnt(0)
	v_fma_f32 v152, v104, v168, -v156
	v_fma_f32 v153, v105, v169, -v157
	v_fma_f32 v158, v102, v166, -v158
	v_fma_f32 v159, v103, v167, -v159
	v_fmac_f32_e32 v154, v100, v168
	v_fmac_f32_e32 v155, v101, v169
	v_fma_f32 v156, v98, v166, v170
	v_fma_f32 v157, v99, v167, v171
	s_cbranch_vccnz .LBB0_1248
	v_mul_lo_u32 v143, s89, v150
	v_mul_lo_u32 v165, s88, v151
	v_mad_u64_u32 v[168:169], s[4:5], s88, v150, 0
	v_add3_u32 v169, v169, v165, v143
	v_lshl_add_u64 v[168:169], v[168:169], 1, v[144:145]
	s_lshl_b32 s22, s90, 1
	v_cvt_pk_bf16_f32 v166, v158, v159
	v_cvt_pk_bf16_f32 v167, v152, v153
	global_store_dwordx2 v[168:169], v[166:167], off
	v_lshl_add_u64 v[168:169], v[168:169], 0, s[22:23]
	s_mov_b64 s[4:5], 0
	v_cvt_pk_bf16_f32 v166, v156, v157
	v_cvt_pk_bf16_f32 v167, v154, v155
	global_store_dwordx2 v[168:169], v[166:167], off

.LBB0_1250:
	v_add_u32_e32 v150, 0x80, v142
	v_mad_i64_i32 v[152:153], s[4:5], s90, v150, 0
	v_lshlrev_b64 v[156:157], 2, v[152:153]
	v_lshl_add_u64 v[152:153], v[146:147], 0, v[156:157]
	global_load_dwordx4 v[152:155], v[152:153], off
	v_lshl_add_u64 v[156:157], v[148:149], 0, v[156:157]
	global_load_dwordx4 v[166:169], v[156:157], off
	s_and_b64 vcc, exec, s[10:11]
	v_ashrrev_i32_e32 v151, 31, v150
	s_mov_b64 s[4:5], -1
	s_waitcnt vmcnt(1)
	v_mul_f32_e32 v156, v92, v154
	v_mul_f32_e32 v157, v93, v155
	v_mul_f32_e32 v158, v90, v152
	v_mul_f32_e32 v159, v91, v153
	v_mul_f32_e32 v154, v96, v154
	v_mul_f32_e32 v155, v97, v155
	v_mul_f32_e32 v170, v94, v152
	v_mul_f32_e32 v171, v95, v153
	s_waitcnt vmcnt(0)
	v_fma_f32 v152, v96, v168, -v156
	v_fma_f32 v153, v97, v169, -v157
	v_fma_f32 v158, v94, v166, -v158
	v_fma_f32 v159, v95, v167, -v159
	v_fmac_f32_e32 v154, v92, v168
	v_fmac_f32_e32 v155, v93, v169
	v_fma_f32 v156, v90, v166, v170
	v_fma_f32 v157, v91, v167, v171
	s_cbranch_vccnz .LBB0_1252
	v_mul_lo_u32 v143, s89, v150
	v_mul_lo_u32 v165, s88, v151
	v_mad_u64_u32 v[168:169], s[4:5], s88, v150, 0
	v_add3_u32 v169, v169, v165, v143
	v_lshl_add_u64 v[168:169], v[168:169], 1, v[144:145]
	s_lshl_b32 s22, s90, 1
	v_cvt_pk_bf16_f32 v166, v158, v159
	v_cvt_pk_bf16_f32 v167, v152, v153
	global_store_dwordx2 v[168:169], v[166:167], off
	v_lshl_add_u64 v[168:169], v[168:169], 0, s[22:23]
	s_mov_b64 s[4:5], 0
	v_cvt_pk_bf16_f32 v166, v156, v157
	v_cvt_pk_bf16_f32 v167, v154, v155
	global_store_dwordx2 v[168:169], v[166:167], off

.LBB0_1254:
	v_add_u32_e32 v150, 0x90, v142
	v_mad_i64_i32 v[152:153], s[4:5], s90, v150, 0
	v_lshlrev_b64 v[156:157], 2, v[152:153]
	v_lshl_add_u64 v[152:153], v[146:147], 0, v[156:157]
	global_load_dwordx4 v[152:155], v[152:153], off
	v_lshl_add_u64 v[156:157], v[148:149], 0, v[156:157]
	global_load_dwordx4 v[166:169], v[156:157], off
	s_and_b64 vcc, exec, s[10:11]
	v_ashrrev_i32_e32 v151, 31, v150
	s_mov_b64 s[4:5], -1
	s_waitcnt vmcnt(1)
	v_mul_f32_e32 v156, v84, v154
	v_mul_f32_e32 v157, v85, v155
	v_mul_f32_e32 v158, v82, v152
	v_mul_f32_e32 v159, v83, v153
	v_mul_f32_e32 v154, v88, v154
	v_mul_f32_e32 v155, v89, v155
	v_mul_f32_e32 v170, v86, v152
	v_mul_f32_e32 v171, v87, v153
	s_waitcnt vmcnt(0)
	v_fma_f32 v152, v88, v168, -v156
	v_fma_f32 v153, v89, v169, -v157
	v_fma_f32 v158, v86, v166, -v158
	v_fma_f32 v159, v87, v167, -v159
	v_fmac_f32_e32 v154, v84, v168
	v_fmac_f32_e32 v155, v85, v169
	v_fma_f32 v156, v82, v166, v170
	v_fma_f32 v157, v83, v167, v171
	s_cbranch_vccnz .LBB0_1256
	v_mul_lo_u32 v143, s89, v150
	v_mul_lo_u32 v165, s88, v151
	v_mad_u64_u32 v[168:169], s[4:5], s88, v150, 0
	v_add3_u32 v169, v169, v165, v143
	v_lshl_add_u64 v[168:169], v[168:169], 1, v[144:145]
	s_lshl_b32 s22, s90, 1
	v_cvt_pk_bf16_f32 v166, v158, v159
	v_cvt_pk_bf16_f32 v167, v152, v153
	global_store_dwordx2 v[168:169], v[166:167], off
	v_lshl_add_u64 v[168:169], v[168:169], 0, s[22:23]
	s_mov_b64 s[4:5], 0
	v_cvt_pk_bf16_f32 v166, v156, v157
	v_cvt_pk_bf16_f32 v167, v154, v155
	global_store_dwordx2 v[168:169], v[166:167], off

.LBB0_1258:
	v_add_u32_e32 v150, 0xa0, v142
	v_mad_i64_i32 v[152:153], s[4:5], s90, v150, 0
	v_lshlrev_b64 v[156:157], 2, v[152:153]
	v_lshl_add_u64 v[152:153], v[146:147], 0, v[156:157]
	global_load_dwordx4 v[152:155], v[152:153], off
	v_lshl_add_u64 v[156:157], v[148:149], 0, v[156:157]
	global_load_dwordx4 v[166:169], v[156:157], off
	s_and_b64 vcc, exec, s[10:11]
	v_ashrrev_i32_e32 v151, 31, v150
	s_mov_b64 s[4:5], -1
	s_waitcnt vmcnt(1)
	v_mul_f32_e32 v156, v76, v154
	v_mul_f32_e32 v157, v77, v155
	v_mul_f32_e32 v158, v74, v152
	v_mul_f32_e32 v159, v75, v153
	v_mul_f32_e32 v154, v80, v154
	v_mul_f32_e32 v155, v81, v155
	v_mul_f32_e32 v170, v78, v152
	v_mul_f32_e32 v171, v79, v153
	s_waitcnt vmcnt(0)
	v_fma_f32 v152, v80, v168, -v156
	v_fma_f32 v153, v81, v169, -v157
	v_fma_f32 v158, v78, v166, -v158
	v_fma_f32 v159, v79, v167, -v159
	v_fmac_f32_e32 v154, v76, v168
	v_fmac_f32_e32 v155, v77, v169
	v_fma_f32 v156, v74, v166, v170
	v_fma_f32 v157, v75, v167, v171
	s_cbranch_vccnz .LBB0_1260
	v_mul_lo_u32 v143, s89, v150
	v_mul_lo_u32 v165, s88, v151
	v_mad_u64_u32 v[168:169], s[4:5], s88, v150, 0
	v_add3_u32 v169, v169, v165, v143
	v_lshl_add_u64 v[168:169], v[168:169], 1, v[144:145]
	s_lshl_b32 s22, s90, 1
	v_cvt_pk_bf16_f32 v166, v158, v159
	v_cvt_pk_bf16_f32 v167, v152, v153
	global_store_dwordx2 v[168:169], v[166:167], off
	v_lshl_add_u64 v[168:169], v[168:169], 0, s[22:23]
	s_mov_b64 s[4:5], 0
	v_cvt_pk_bf16_f32 v166, v156, v157
	v_cvt_pk_bf16_f32 v167, v154, v155
	global_store_dwordx2 v[168:169], v[166:167], off

.LBB0_1262:
	v_add_u32_e32 v150, 0xb0, v142
	v_mad_i64_i32 v[152:153], s[4:5], s90, v150, 0
	v_lshlrev_b64 v[156:157], 2, v[152:153]
	v_lshl_add_u64 v[146:147], v[146:147], 0, v[156:157]
	global_load_dwordx4 v[152:155], v[146:147], off
	v_lshl_add_u64 v[146:147], v[148:149], 0, v[156:157]
	global_load_dwordx4 v[166:169], v[146:147], off
	s_and_b64 vcc, exec, s[10:11]
	v_ashrrev_i32_e32 v151, 31, v150
	s_mov_b64 s[4:5], -1
	s_waitcnt vmcnt(1)
	v_mul_f32_e32 v146, v68, v154
	v_mul_f32_e32 v147, v69, v155
	v_mul_f32_e32 v148, v66, v152
	v_mul_f32_e32 v149, v67, v153
	v_mul_f32_e32 v154, v72, v154
	v_mul_f32_e32 v155, v73, v155
	v_mul_f32_e32 v158, v70, v152
	v_mul_f32_e32 v159, v71, v153
	s_waitcnt vmcnt(0)
	v_fma_f32 v146, v72, v168, -v146
	v_fma_f32 v147, v73, v169, -v147
	v_fma_f32 v156, v70, v166, -v148
	v_fma_f32 v157, v71, v167, -v149
	v_fma_f32 v152, v68, v168, v154
	v_fma_f32 v153, v69, v169, v155
	v_fma_f32 v154, v66, v166, v158
	v_fma_f32 v155, v67, v167, v159
	s_cbranch_vccnz .LBB0_1264
	v_mul_lo_u32 v143, s89, v150
	v_mul_lo_u32 v165, s88, v151
	v_mad_u64_u32 v[158:159], s[4:5], s88, v150, 0
	v_add3_u32 v159, v159, v165, v143
	v_lshl_add_u64 v[144:145], v[158:159], 1, v[144:145]
	s_lshl_b32 s22, s90, 1
	v_cvt_pk_bf16_f32 v148, v156, v157
	v_cvt_pk_bf16_f32 v149, v146, v147
	global_store_dwordx2 v[144:145], v[148:149], off
	v_lshl_add_u64 v[144:145], v[144:145], 0, s[22:23]
	s_mov_b64 s[4:5], 0
	v_cvt_pk_bf16_f32 v148, v154, v155
	v_cvt_pk_bf16_f32 v149, v152, v153
	global_store_dwordx2 v[144:145], v[148:149], off

.LBB0_1300:
	v_lshlrev_b64 v[70:71], 2, v[134:135]
	v_lshl_add_u64 v[68:69], s[4:5], 0, v[70:71]
	v_mad_i64_i32 v[72:73], s[4:5], s90, v142, 0
	v_lshlrev_b64 v[76:77], 2, v[72:73]
	v_lshl_add_u64 v[72:73], v[68:69], 0, v[76:77]
	v_lshl_add_u64 v[70:71], s[94:95], 0, v[70:71]
	global_load_dwordx4 v[72:75], v[72:73], off
	v_lshl_add_u64 v[76:77], v[70:71], 0, v[76:77]
	global_load_dwordx4 v[80:83], v[76:77], off
	v_mov_b32_e32 v134, v66
	v_cndmask_b32_e64 v76, 0, 1, s[92:93]
	s_waitcnt lgkmcnt(0)
	v_lshl_add_u64 v[66:67], v[134:135], 1, s[10:11]
	v_cmp_ne_u32_e64 s[10:11], 1, v76
	v_ashrrev_i32_e32 v143, 31, v142
	s_andn2_b64 vcc, exec, s[92:93]
	s_mov_b64 s[4:5], -1
	s_waitcnt vmcnt(0)
	v_mul_f32_e32 v76, v60, v74
	v_mul_f32_e32 v77, v61, v75
	v_mul_f32_e32 v78, v58, v72
	v_mul_f32_e32 v79, v59, v73
	v_mul_f32_e32 v74, v64, v74
	v_mul_f32_e32 v75, v65, v75
	v_mul_f32_e32 v84, v62, v72
	v_mul_f32_e32 v85, v63, v73
	v_fma_f32 v72, v64, v82, -v76
	v_fma_f32 v73, v65, v83, -v77
	v_fma_f32 v78, v62, v80, -v78
	v_fma_f32 v79, v63, v81, -v79
	v_fmac_f32_e32 v74, v60, v82
	v_fmac_f32_e32 v75, v61, v83
	v_fma_f32 v76, v58, v80, v84
	v_fma_f32 v77, v59, v81, v85
	s_cbranch_vccnz .LBB0_1302
	v_mul_lo_u32 v84, s89, v142
	v_mul_lo_u32 v85, s88, v143
	v_mad_u64_u32 v[82:83], s[4:5], s88, v142, 0
	v_add3_u32 v83, v83, v85, v84
	v_lshl_add_u64 v[82:83], v[82:83], 1, v[66:67]
	s_lshl_b32 s22, s90, 1
	v_cvt_pk_bf16_f32 v80, v78, v79
	v_cvt_pk_bf16_f32 v81, v72, v73
	global_store_dwordx2 v[82:83], v[80:81], off
	v_lshl_add_u64 v[82:83], v[82:83], 0, s[22:23]
	s_mov_b64 s[4:5], 0
	v_cvt_pk_bf16_f32 v80, v76, v77
	v_cvt_pk_bf16_f32 v81, v74, v75
	global_store_dwordx2 v[82:83], v[80:81], off

.LBB0_1304:
	v_or_b32_e32 v72, 16, v142
	v_mad_i64_i32 v[74:75], s[4:5], s90, v72, 0
	v_lshlrev_b64 v[78:79], 2, v[74:75]
	v_lshl_add_u64 v[74:75], v[68:69], 0, v[78:79]
	global_load_dwordx4 v[74:77], v[74:75], off
	v_lshl_add_u64 v[78:79], v[70:71], 0, v[78:79]
	global_load_dwordx4 v[82:85], v[78:79], off
	s_and_b64 vcc, exec, s[10:11]
	v_ashrrev_i32_e32 v73, 31, v72
	s_mov_b64 s[4:5], -1
	s_waitcnt vmcnt(1)
	v_mul_f32_e32 v78, v52, v76
	v_mul_f32_e32 v79, v53, v77
	v_mul_f32_e32 v80, v50, v74
	v_mul_f32_e32 v81, v51, v75
	v_mul_f32_e32 v76, v56, v76
	v_mul_f32_e32 v77, v57, v77
	v_mul_f32_e32 v86, v54, v74
	v_mul_f32_e32 v87, v55, v75
	s_waitcnt vmcnt(0)
	v_fma_f32 v74, v56, v84, -v78
	v_fma_f32 v75, v57, v85, -v79
	v_fma_f32 v80, v54, v82, -v80
	v_fma_f32 v81, v55, v83, -v81
	v_fmac_f32_e32 v76, v52, v84
	v_fmac_f32_e32 v77, v53, v85
	v_fma_f32 v78, v50, v82, v86
	v_fma_f32 v79, v51, v83, v87
	s_cbranch_vccnz .LBB0_1306
	v_mul_lo_u32 v86, s89, v72
	v_mul_lo_u32 v87, s88, v73
	v_mad_u64_u32 v[84:85], s[4:5], s88, v72, 0
	v_add3_u32 v85, v85, v87, v86
	v_lshl_add_u64 v[84:85], v[84:85], 1, v[66:67]
	s_lshl_b32 s22, s90, 1
	v_cvt_pk_bf16_f32 v82, v80, v81
	v_cvt_pk_bf16_f32 v83, v74, v75
	global_store_dwordx2 v[84:85], v[82:83], off
	v_lshl_add_u64 v[84:85], v[84:85], 0, s[22:23]
	s_mov_b64 s[4:5], 0
	v_cvt_pk_bf16_f32 v82, v78, v79
	v_cvt_pk_bf16_f32 v83, v76, v77
	global_store_dwordx2 v[84:85], v[82:83], off

.LBB0_1308:
	v_or_b32_e32 v72, 32, v142
	v_mad_i64_i32 v[74:75], s[4:5], s90, v72, 0
	v_lshlrev_b64 v[78:79], 2, v[74:75]
	v_lshl_add_u64 v[74:75], v[68:69], 0, v[78:79]
	global_load_dwordx4 v[74:77], v[74:75], off
	v_lshl_add_u64 v[78:79], v[70:71], 0, v[78:79]
	global_load_dwordx4 v[82:85], v[78:79], off
	s_and_b64 vcc, exec, s[10:11]
	v_ashrrev_i32_e32 v73, 31, v72
	s_mov_b64 s[4:5], -1
	s_waitcnt vmcnt(1)
	v_mul_f32_e32 v78, v44, v76
	v_mul_f32_e32 v79, v45, v77
	v_mul_f32_e32 v80, v42, v74
	v_mul_f32_e32 v81, v43, v75
	v_mul_f32_e32 v76, v48, v76
	v_mul_f32_e32 v77, v49, v77
	v_mul_f32_e32 v86, v46, v74
	v_mul_f32_e32 v87, v47, v75
	s_waitcnt vmcnt(0)
	v_fma_f32 v74, v48, v84, -v78
	v_fma_f32 v75, v49, v85, -v79
	v_fma_f32 v80, v46, v82, -v80
	v_fma_f32 v81, v47, v83, -v81
	v_fmac_f32_e32 v76, v44, v84
	v_fmac_f32_e32 v77, v45, v85
	v_fma_f32 v78, v42, v82, v86
	v_fma_f32 v79, v43, v83, v87
	s_cbranch_vccnz .LBB0_1310
	v_mul_lo_u32 v86, s89, v72
	v_mul_lo_u32 v87, s88, v73
	v_mad_u64_u32 v[84:85], s[4:5], s88, v72, 0
	v_add3_u32 v85, v85, v87, v86
	v_lshl_add_u64 v[84:85], v[84:85], 1, v[66:67]
	s_lshl_b32 s22, s90, 1
	v_cvt_pk_bf16_f32 v82, v80, v81
	v_cvt_pk_bf16_f32 v83, v74, v75
	global_store_dwordx2 v[84:85], v[82:83], off
	v_lshl_add_u64 v[84:85], v[84:85], 0, s[22:23]
	s_mov_b64 s[4:5], 0
	v_cvt_pk_bf16_f32 v82, v78, v79
	v_cvt_pk_bf16_f32 v83, v76, v77
	global_store_dwordx2 v[84:85], v[82:83], off

.LBB0_1312:
	v_or_b32_e32 v72, 48, v142
	v_mad_i64_i32 v[74:75], s[4:5], s90, v72, 0
	v_lshlrev_b64 v[78:79], 2, v[74:75]
	v_lshl_add_u64 v[74:75], v[68:69], 0, v[78:79]
	global_load_dwordx4 v[74:77], v[74:75], off
	v_lshl_add_u64 v[78:79], v[70:71], 0, v[78:79]
	global_load_dwordx4 v[82:85], v[78:79], off
	s_and_b64 vcc, exec, s[10:11]
	v_ashrrev_i32_e32 v73, 31, v72
	s_mov_b64 s[4:5], -1
	s_waitcnt vmcnt(1)
	v_mul_f32_e32 v78, v36, v76
	v_mul_f32_e32 v79, v37, v77
	v_mul_f32_e32 v80, v34, v74
	v_mul_f32_e32 v81, v35, v75
	v_mul_f32_e32 v76, v40, v76
	v_mul_f32_e32 v77, v41, v77
	v_mul_f32_e32 v86, v38, v74
	v_mul_f32_e32 v87, v39, v75
	s_waitcnt vmcnt(0)
	v_fma_f32 v74, v40, v84, -v78
	v_fma_f32 v75, v41, v85, -v79
	v_fma_f32 v80, v38, v82, -v80
	v_fma_f32 v81, v39, v83, -v81
	v_fmac_f32_e32 v76, v36, v84
	v_fmac_f32_e32 v77, v37, v85
	v_fma_f32 v78, v34, v82, v86
	v_fma_f32 v79, v35, v83, v87
	s_cbranch_vccnz .LBB0_1314
	v_mul_lo_u32 v86, s89, v72
	v_mul_lo_u32 v87, s88, v73
	v_mad_u64_u32 v[84:85], s[4:5], s88, v72, 0
	v_add3_u32 v85, v85, v87, v86
	v_lshl_add_u64 v[84:85], v[84:85], 1, v[66:67]
	s_lshl_b32 s22, s90, 1
	v_cvt_pk_bf16_f32 v82, v80, v81
	v_cvt_pk_bf16_f32 v83, v74, v75
	global_store_dwordx2 v[84:85], v[82:83], off
	v_lshl_add_u64 v[84:85], v[84:85], 0, s[22:23]
	s_mov_b64 s[4:5], 0
	v_cvt_pk_bf16_f32 v82, v78, v79
	v_cvt_pk_bf16_f32 v83, v76, v77
	global_store_dwordx2 v[84:85], v[82:83], off

.LBB0_1316:
	v_add_u32_e32 v72, 0x80, v142
	v_mad_i64_i32 v[74:75], s[4:5], s90, v72, 0
	v_lshlrev_b64 v[78:79], 2, v[74:75]
	v_lshl_add_u64 v[74:75], v[68:69], 0, v[78:79]
	global_load_dwordx4 v[74:77], v[74:75], off
	v_lshl_add_u64 v[78:79], v[70:71], 0, v[78:79]
	global_load_dwordx4 v[82:85], v[78:79], off
	s_and_b64 vcc, exec, s[10:11]
	v_ashrrev_i32_e32 v73, 31, v72
	s_mov_b64 s[4:5], -1
	s_waitcnt vmcnt(1)
	v_mul_f32_e32 v78, v28, v76
	v_mul_f32_e32 v79, v29, v77
	v_mul_f32_e32 v80, v26, v74
	v_mul_f32_e32 v81, v27, v75
	v_mul_f32_e32 v76, v32, v76
	v_mul_f32_e32 v77, v33, v77
	v_mul_f32_e32 v86, v30, v74
	v_mul_f32_e32 v87, v31, v75
	s_waitcnt vmcnt(0)
	v_fma_f32 v74, v32, v84, -v78
	v_fma_f32 v75, v33, v85, -v79
	v_fma_f32 v80, v30, v82, -v80
	v_fma_f32 v81, v31, v83, -v81
	v_fmac_f32_e32 v76, v28, v84
	v_fmac_f32_e32 v77, v29, v85
	v_fma_f32 v78, v26, v82, v86
	v_fma_f32 v79, v27, v83, v87
	s_cbranch_vccnz .LBB0_1318
	v_mul_lo_u32 v86, s89, v72
	v_mul_lo_u32 v87, s88, v73
	v_mad_u64_u32 v[84:85], s[4:5], s88, v72, 0
	v_add3_u32 v85, v85, v87, v86
	v_lshl_add_u64 v[84:85], v[84:85], 1, v[66:67]
	s_lshl_b32 s22, s90, 1
	v_cvt_pk_bf16_f32 v82, v80, v81
	v_cvt_pk_bf16_f32 v83, v74, v75
	global_store_dwordx2 v[84:85], v[82:83], off
	v_lshl_add_u64 v[84:85], v[84:85], 0, s[22:23]
	s_mov_b64 s[4:5], 0
	v_cvt_pk_bf16_f32 v82, v78, v79
	v_cvt_pk_bf16_f32 v83, v76, v77
	global_store_dwordx2 v[84:85], v[82:83], off

.LBB0_1320:
	v_add_u32_e32 v72, 0x90, v142
	v_mad_i64_i32 v[74:75], s[4:5], s90, v72, 0
	v_lshlrev_b64 v[78:79], 2, v[74:75]
	v_lshl_add_u64 v[74:75], v[68:69], 0, v[78:79]
	global_load_dwordx4 v[74:77], v[74:75], off
	v_lshl_add_u64 v[78:79], v[70:71], 0, v[78:79]
	global_load_dwordx4 v[82:85], v[78:79], off
	s_and_b64 vcc, exec, s[10:11]
	v_ashrrev_i32_e32 v73, 31, v72
	s_mov_b64 s[4:5], -1
	s_waitcnt vmcnt(1)
	v_mul_f32_e32 v78, v20, v76
	v_mul_f32_e32 v79, v21, v77
	v_mul_f32_e32 v80, v18, v74
	v_mul_f32_e32 v81, v19, v75
	v_mul_f32_e32 v76, v24, v76
	v_mul_f32_e32 v77, v25, v77
	v_mul_f32_e32 v86, v22, v74
	v_mul_f32_e32 v87, v23, v75
	s_waitcnt vmcnt(0)
	v_fma_f32 v74, v24, v84, -v78
	v_fma_f32 v75, v25, v85, -v79
	v_fma_f32 v80, v22, v82, -v80
	v_fma_f32 v81, v23, v83, -v81
	v_fmac_f32_e32 v76, v20, v84
	v_fmac_f32_e32 v77, v21, v85
	v_fma_f32 v78, v18, v82, v86
	v_fma_f32 v79, v19, v83, v87
	s_cbranch_vccnz .LBB0_1322
	v_mul_lo_u32 v86, s89, v72
	v_mul_lo_u32 v87, s88, v73
	v_mad_u64_u32 v[84:85], s[4:5], s88, v72, 0
	v_add3_u32 v85, v85, v87, v86
	v_lshl_add_u64 v[84:85], v[84:85], 1, v[66:67]
	s_lshl_b32 s22, s90, 1
	v_cvt_pk_bf16_f32 v82, v80, v81
	v_cvt_pk_bf16_f32 v83, v74, v75
	global_store_dwordx2 v[84:85], v[82:83], off
	v_lshl_add_u64 v[84:85], v[84:85], 0, s[22:23]
	s_mov_b64 s[4:5], 0
	v_cvt_pk_bf16_f32 v82, v78, v79
	v_cvt_pk_bf16_f32 v83, v76, v77
	global_store_dwordx2 v[84:85], v[82:83], off

.LBB0_1324:
	v_add_u32_e32 v72, 0xa0, v142
	v_mad_i64_i32 v[74:75], s[4:5], s90, v72, 0
	v_lshlrev_b64 v[78:79], 2, v[74:75]
	v_lshl_add_u64 v[74:75], v[68:69], 0, v[78:79]
	global_load_dwordx4 v[74:77], v[74:75], off
	v_lshl_add_u64 v[78:79], v[70:71], 0, v[78:79]
	global_load_dwordx4 v[82:85], v[78:79], off
	s_and_b64 vcc, exec, s[10:11]
	v_ashrrev_i32_e32 v73, 31, v72
	s_mov_b64 s[4:5], -1
	s_waitcnt vmcnt(1)
	v_mul_f32_e32 v78, v12, v76
	v_mul_f32_e32 v79, v13, v77
	v_mul_f32_e32 v80, v10, v74
	v_mul_f32_e32 v81, v11, v75
	v_mul_f32_e32 v76, v16, v76
	v_mul_f32_e32 v77, v17, v77
	v_mul_f32_e32 v86, v14, v74
	v_mul_f32_e32 v87, v15, v75
	s_waitcnt vmcnt(0)
	v_fma_f32 v74, v16, v84, -v78
	v_fma_f32 v75, v17, v85, -v79
	v_fma_f32 v80, v14, v82, -v80
	v_fma_f32 v81, v15, v83, -v81
	v_fmac_f32_e32 v76, v12, v84
	v_fmac_f32_e32 v77, v13, v85
	v_fma_f32 v78, v10, v82, v86
	v_fma_f32 v79, v11, v83, v87
	s_cbranch_vccnz .LBB0_1326
	v_mul_lo_u32 v86, s89, v72
	v_mul_lo_u32 v87, s88, v73
	v_mad_u64_u32 v[84:85], s[4:5], s88, v72, 0
	v_add3_u32 v85, v85, v87, v86
	v_lshl_add_u64 v[84:85], v[84:85], 1, v[66:67]
	s_lshl_b32 s22, s90, 1
	v_cvt_pk_bf16_f32 v82, v80, v81
	v_cvt_pk_bf16_f32 v83, v74, v75
	global_store_dwordx2 v[84:85], v[82:83], off
	v_lshl_add_u64 v[84:85], v[84:85], 0, s[22:23]
	s_mov_b64 s[4:5], 0
	v_cvt_pk_bf16_f32 v82, v78, v79
	v_cvt_pk_bf16_f32 v83, v76, v77
	global_store_dwordx2 v[84:85], v[82:83], off

.LBB0_1328:
	v_add_u32_e32 v72, 0xb0, v142
	v_mad_i64_i32 v[74:75], s[4:5], s90, v72, 0
	v_lshlrev_b64 v[78:79], 2, v[74:75]
	v_lshl_add_u64 v[68:69], v[68:69], 0, v[78:79]
	global_load_dwordx4 v[74:77], v[68:69], off
	v_lshl_add_u64 v[68:69], v[70:71], 0, v[78:79]
	global_load_dwordx4 v[80:83], v[68:69], off
	s_and_b64 vcc, exec, s[10:11]
	v_ashrrev_i32_e32 v73, 31, v72
	s_mov_b64 s[4:5], -1
	s_waitcnt vmcnt(1)
	v_mul_f32_e32 v68, v4, v76
	v_mul_f32_e32 v69, v5, v77
	v_mul_f32_e32 v70, v2, v74
	v_mul_f32_e32 v71, v3, v75
	v_mul_f32_e32 v76, v8, v76
	v_mul_f32_e32 v77, v9, v77
	v_mul_f32_e32 v84, v6, v74
	v_mul_f32_e32 v85, v7, v75
	s_waitcnt vmcnt(0)
	v_fma_f32 v68, v8, v82, -v68
	v_fma_f32 v69, v9, v83, -v69
	v_fma_f32 v78, v6, v80, -v70
	v_fma_f32 v79, v7, v81, -v71
	v_fma_f32 v74, v4, v82, v76
	v_fma_f32 v75, v5, v83, v77
	v_fma_f32 v76, v2, v80, v84
	v_fma_f32 v77, v3, v81, v85
	s_cbranch_vccnz .LBB0_1330
	v_mul_lo_u32 v82, s89, v72
	v_mul_lo_u32 v83, s88, v73
	v_mad_u64_u32 v[80:81], s[4:5], s88, v72, 0
	v_add3_u32 v81, v81, v83, v82
	v_lshl_add_u64 v[66:67], v[80:81], 1, v[66:67]
	s_lshl_b32 s22, s90, 1
	v_cvt_pk_bf16_f32 v70, v78, v79
	v_cvt_pk_bf16_f32 v71, v68, v69
	global_store_dwordx2 v[66:67], v[70:71], off
	v_lshl_add_u64 v[66:67], v[66:67], 0, s[22:23]
	s_mov_b64 s[4:5], 0
	v_cvt_pk_bf16_f32 v70, v76, v77
	v_cvt_pk_bf16_f32 v71, v74, v75
	global_store_dwordx2 v[66:67], v[70:71], off

.LBB0_1460:
	s_add_u32 s4, s72, s4
	s_addc_u32 s5, s73, s5
	v_lshlrev_b64 v[140:141], 2, v[134:135]
	v_lshl_add_u64 v[142:143], s[4:5], 0, v[140:141]
	v_mad_i64_i32 v[144:145], s[4:5], s88, v138, 0
	s_add_u32 s92, s72, s92
	v_lshlrev_b64 v[150:151], 2, v[144:145]
	v_lshl_add_u64 v[144:145], v[142:143], 0, v[150:151]
	s_addc_u32 s93, s73, s93
	global_load_dwordx4 v[146:149], v[144:145], off
	v_lshl_add_u64 v[144:145], s[92:93], 0, v[140:141]
	v_lshl_add_u64 v[140:141], v[144:145], 0, v[150:151]
	global_load_dwordx4 v[162:165], v[140:141], off
	v_mov_b32_e32 v134, v139
	v_ashrrev_i32_e32 v139, 31, v138
	s_mov_b64 s[4:5], -1
	v_lshl_add_u64 v[140:141], v[134:135], 1, s[8:9]
	s_and_b64 vcc, exec, s[90:91]
	s_waitcnt vmcnt(0)
	v_mul_f32_e32 v150, v124, v148
	v_mul_f32_e32 v151, v125, v149
	v_mul_f32_e32 v152, v122, v146
	v_mul_f32_e32 v153, v123, v147
	v_mul_f32_e32 v148, v128, v148
	v_mul_f32_e32 v149, v129, v149
	v_mul_f32_e32 v154, v126, v146
	v_mul_f32_e32 v155, v127, v147
	v_fma_f32 v146, v128, v164, -v150
	v_fma_f32 v147, v129, v165, -v151
	v_fma_f32 v152, v126, v162, -v152
	v_fma_f32 v153, v127, v163, -v153
	v_fmac_f32_e32 v148, v124, v164
	v_fmac_f32_e32 v149, v125, v165
	v_fma_f32 v150, v122, v162, v154
	v_fma_f32 v151, v123, v163, v155
	s_cbranch_vccz .LBB0_1462
	v_mul_lo_u32 v161, s87, v138
	v_mul_lo_u32 v164, s86, v139
	v_mad_u64_u32 v[162:163], s[4:5], s86, v138, 0
	v_add3_u32 v163, v163, v164, v161
	v_lshl_add_u64 v[162:163], v[162:163], 1, v[140:141]
	s_lshl_b32 s26, s88, 1
	v_cvt_pk_bf16_f32 v154, v152, v153
	v_cvt_pk_bf16_f32 v155, v146, v147
	global_store_dwordx2 v[162:163], v[154:155], off
	v_lshl_add_u64 v[162:163], v[162:163], 0, s[26:27]
	v_cvt_pk_bf16_f32 v154, v150, v151
	v_cvt_pk_bf16_f32 v155, v148, v149
	global_store_dwordx2 v[162:163], v[154:155], off
	s_mov_b64 s[4:5], 0

.LBB0_1464:
	v_or_b32_e32 v146, 16, v138
	v_mad_i64_i32 v[148:149], s[4:5], s88, v146, 0
	v_lshlrev_b64 v[152:153], 2, v[148:149]
	v_lshl_add_u64 v[148:149], v[142:143], 0, v[152:153]
	global_load_dwordx4 v[148:151], v[148:149], off
	v_lshl_add_u64 v[152:153], v[144:145], 0, v[152:153]
	global_load_dwordx4 v[162:165], v[152:153], off
	v_cndmask_b32_e64 v139, 0, 1, s[90:91]
	v_ashrrev_i32_e32 v147, 31, v146
	v_cmp_ne_u32_e64 s[8:9], 1, v139
	s_andn2_b64 vcc, exec, s[90:91]
	s_mov_b64 s[4:5], -1
	s_waitcnt vmcnt(1)
	v_mul_f32_e32 v152, v116, v150
	v_mul_f32_e32 v153, v117, v151
	v_mul_f32_e32 v154, v114, v148
	v_mul_f32_e32 v155, v115, v149
	v_mul_f32_e32 v150, v120, v150
	v_mul_f32_e32 v151, v121, v151
	v_mul_f32_e32 v166, v118, v148
	v_mul_f32_e32 v167, v119, v149
	s_waitcnt vmcnt(0)
	v_fma_f32 v148, v120, v164, -v152
	v_fma_f32 v149, v121, v165, -v153
	v_fma_f32 v154, v118, v162, -v154
	v_fma_f32 v155, v119, v163, -v155
	v_fmac_f32_e32 v150, v116, v164
	v_fmac_f32_e32 v151, v117, v165
	v_fma_f32 v152, v114, v162, v166
	v_fma_f32 v153, v115, v163, v167
	s_cbranch_vccnz .LBB0_1466
	v_mul_lo_u32 v139, s87, v146
	v_mul_lo_u32 v161, s86, v147
	v_mad_u64_u32 v[164:165], s[4:5], s86, v146, 0
	v_add3_u32 v165, v165, v161, v139
	v_lshl_add_u64 v[164:165], v[164:165], 1, v[140:141]
	s_lshl_b32 s26, s88, 1
	v_cvt_pk_bf16_f32 v162, v154, v155
	v_cvt_pk_bf16_f32 v163, v148, v149
	global_store_dwordx2 v[164:165], v[162:163], off
	v_lshl_add_u64 v[164:165], v[164:165], 0, s[26:27]
	s_mov_b64 s[4:5], 0
	v_cvt_pk_bf16_f32 v162, v152, v153
	v_cvt_pk_bf16_f32 v163, v150, v151
	global_store_dwordx2 v[164:165], v[162:163], off

.LBB0_1468:
	v_or_b32_e32 v146, 32, v138
	v_mad_i64_i32 v[148:149], s[4:5], s88, v146, 0
	v_lshlrev_b64 v[152:153], 2, v[148:149]
	v_lshl_add_u64 v[148:149], v[142:143], 0, v[152:153]
	global_load_dwordx4 v[148:151], v[148:149], off
	v_lshl_add_u64 v[152:153], v[144:145], 0, v[152:153]
	global_load_dwordx4 v[162:165], v[152:153], off
	s_and_b64 vcc, exec, s[8:9]
	v_ashrrev_i32_e32 v147, 31, v146
	s_mov_b64 s[4:5], -1
	s_waitcnt vmcnt(1)
	v_mul_f32_e32 v152, v108, v150
	v_mul_f32_e32 v153, v109, v151
	v_mul_f32_e32 v154, v106, v148
	v_mul_f32_e32 v155, v107, v149
	v_mul_f32_e32 v150, v112, v150
	v_mul_f32_e32 v151, v113, v151
	v_mul_f32_e32 v166, v110, v148
	v_mul_f32_e32 v167, v111, v149
	s_waitcnt vmcnt(0)
	v_fma_f32 v148, v112, v164, -v152
	v_fma_f32 v149, v113, v165, -v153
	v_fma_f32 v154, v110, v162, -v154
	v_fma_f32 v155, v111, v163, -v155
	v_fmac_f32_e32 v150, v108, v164
	v_fmac_f32_e32 v151, v109, v165
	v_fma_f32 v152, v106, v162, v166
	v_fma_f32 v153, v107, v163, v167
	s_cbranch_vccnz .LBB0_1470
	v_mul_lo_u32 v139, s87, v146
	v_mul_lo_u32 v161, s86, v147
	v_mad_u64_u32 v[164:165], s[4:5], s86, v146, 0
	v_add3_u32 v165, v165, v161, v139
	v_lshl_add_u64 v[164:165], v[164:165], 1, v[140:141]
	s_lshl_b32 s26, s88, 1
	v_cvt_pk_bf16_f32 v162, v154, v155
	v_cvt_pk_bf16_f32 v163, v148, v149
	global_store_dwordx2 v[164:165], v[162:163], off
	v_lshl_add_u64 v[164:165], v[164:165], 0, s[26:27]
	s_mov_b64 s[4:5], 0
	v_cvt_pk_bf16_f32 v162, v152, v153
	v_cvt_pk_bf16_f32 v163, v150, v151
	global_store_dwordx2 v[164:165], v[162:163], off

.LBB0_1472:
	v_or_b32_e32 v146, 48, v138
	v_mad_i64_i32 v[148:149], s[4:5], s88, v146, 0
	v_lshlrev_b64 v[152:153], 2, v[148:149]
	v_lshl_add_u64 v[148:149], v[142:143], 0, v[152:153]
	global_load_dwordx4 v[148:151], v[148:149], off
	v_lshl_add_u64 v[152:153], v[144:145], 0, v[152:153]
	global_load_dwordx4 v[162:165], v[152:153], off
	s_and_b64 vcc, exec, s[8:9]
	v_ashrrev_i32_e32 v147, 31, v146
	s_mov_b64 s[4:5], -1
	s_waitcnt vmcnt(1)
	v_mul_f32_e32 v152, v100, v150
	v_mul_f32_e32 v153, v101, v151
	v_mul_f32_e32 v154, v98, v148
	v_mul_f32_e32 v155, v99, v149
	v_mul_f32_e32 v150, v104, v150
	v_mul_f32_e32 v151, v105, v151
	v_mul_f32_e32 v166, v102, v148
	v_mul_f32_e32 v167, v103, v149
	s_waitcnt vmcnt(0)
	v_fma_f32 v148, v104, v164, -v152
	v_fma_f32 v149, v105, v165, -v153
	v_fma_f32 v154, v102, v162, -v154
	v_fma_f32 v155, v103, v163, -v155
	v_fmac_f32_e32 v150, v100, v164
	v_fmac_f32_e32 v151, v101, v165
	v_fma_f32 v152, v98, v162, v166
	v_fma_f32 v153, v99, v163, v167
	s_cbranch_vccnz .LBB0_1474
	v_mul_lo_u32 v139, s87, v146
	v_mul_lo_u32 v161, s86, v147
	v_mad_u64_u32 v[164:165], s[4:5], s86, v146, 0
	v_add3_u32 v165, v165, v161, v139
	v_lshl_add_u64 v[164:165], v[164:165], 1, v[140:141]
	s_lshl_b32 s26, s88, 1
	v_cvt_pk_bf16_f32 v162, v154, v155
	v_cvt_pk_bf16_f32 v163, v148, v149
	global_store_dwordx2 v[164:165], v[162:163], off
	v_lshl_add_u64 v[164:165], v[164:165], 0, s[26:27]
	s_mov_b64 s[4:5], 0
	v_cvt_pk_bf16_f32 v162, v152, v153
	v_cvt_pk_bf16_f32 v163, v150, v151
	global_store_dwordx2 v[164:165], v[162:163], off

.LBB0_1476:
	v_add_u32_e32 v146, 0x80, v138
	v_mad_i64_i32 v[148:149], s[4:5], s88, v146, 0
	v_lshlrev_b64 v[152:153], 2, v[148:149]
	v_lshl_add_u64 v[148:149], v[142:143], 0, v[152:153]
	global_load_dwordx4 v[148:151], v[148:149], off
	v_lshl_add_u64 v[152:153], v[144:145], 0, v[152:153]
	global_load_dwordx4 v[162:165], v[152:153], off
	s_and_b64 vcc, exec, s[8:9]
	v_ashrrev_i32_e32 v147, 31, v146
	s_mov_b64 s[4:5], -1
	s_waitcnt vmcnt(1)
	v_mul_f32_e32 v152, v92, v150
	v_mul_f32_e32 v153, v93, v151
	v_mul_f32_e32 v154, v90, v148
	v_mul_f32_e32 v155, v91, v149
	v_mul_f32_e32 v150, v96, v150
	v_mul_f32_e32 v151, v97, v151
	v_mul_f32_e32 v166, v94, v148
	v_mul_f32_e32 v167, v95, v149
	s_waitcnt vmcnt(0)
	v_fma_f32 v148, v96, v164, -v152
	v_fma_f32 v149, v97, v165, -v153
	v_fma_f32 v154, v94, v162, -v154
	v_fma_f32 v155, v95, v163, -v155
	v_fmac_f32_e32 v150, v92, v164
	v_fmac_f32_e32 v151, v93, v165
	v_fma_f32 v152, v90, v162, v166
	v_fma_f32 v153, v91, v163, v167
	s_cbranch_vccnz .LBB0_1478
	v_mul_lo_u32 v139, s87, v146
	v_mul_lo_u32 v161, s86, v147
	v_mad_u64_u32 v[164:165], s[4:5], s86, v146, 0
	v_add3_u32 v165, v165, v161, v139
	v_lshl_add_u64 v[164:165], v[164:165], 1, v[140:141]
	s_lshl_b32 s26, s88, 1
	v_cvt_pk_bf16_f32 v162, v154, v155
	v_cvt_pk_bf16_f32 v163, v148, v149
	global_store_dwordx2 v[164:165], v[162:163], off
	v_lshl_add_u64 v[164:165], v[164:165], 0, s[26:27]
	s_mov_b64 s[4:5], 0
	v_cvt_pk_bf16_f32 v162, v152, v153
	v_cvt_pk_bf16_f32 v163, v150, v151
	global_store_dwordx2 v[164:165], v[162:163], off

.LBB0_1480:
	v_add_u32_e32 v146, 0x90, v138
	v_mad_i64_i32 v[148:149], s[4:5], s88, v146, 0
	v_lshlrev_b64 v[152:153], 2, v[148:149]
	v_lshl_add_u64 v[148:149], v[142:143], 0, v[152:153]
	global_load_dwordx4 v[148:151], v[148:149], off
	v_lshl_add_u64 v[152:153], v[144:145], 0, v[152:153]
	global_load_dwordx4 v[162:165], v[152:153], off
	s_and_b64 vcc, exec, s[8:9]
	v_ashrrev_i32_e32 v147, 31, v146
	s_mov_b64 s[4:5], -1
	s_waitcnt vmcnt(1)
	v_mul_f32_e32 v152, v84, v150
	v_mul_f32_e32 v153, v85, v151
	v_mul_f32_e32 v154, v82, v148
	v_mul_f32_e32 v155, v83, v149
	v_mul_f32_e32 v150, v88, v150
	v_mul_f32_e32 v151, v89, v151
	v_mul_f32_e32 v166, v86, v148
	v_mul_f32_e32 v167, v87, v149
	s_waitcnt vmcnt(0)
	v_fma_f32 v148, v88, v164, -v152
	v_fma_f32 v149, v89, v165, -v153
	v_fma_f32 v154, v86, v162, -v154
	v_fma_f32 v155, v87, v163, -v155
	v_fmac_f32_e32 v150, v84, v164
	v_fmac_f32_e32 v151, v85, v165
	v_fma_f32 v152, v82, v162, v166
	v_fma_f32 v153, v83, v163, v167
	s_cbranch_vccnz .LBB0_1482
	v_mul_lo_u32 v139, s87, v146
	v_mul_lo_u32 v161, s86, v147
	v_mad_u64_u32 v[164:165], s[4:5], s86, v146, 0
	v_add3_u32 v165, v165, v161, v139
	v_lshl_add_u64 v[164:165], v[164:165], 1, v[140:141]
	s_lshl_b32 s26, s88, 1
	v_cvt_pk_bf16_f32 v162, v154, v155
	v_cvt_pk_bf16_f32 v163, v148, v149
	global_store_dwordx2 v[164:165], v[162:163], off
	v_lshl_add_u64 v[164:165], v[164:165], 0, s[26:27]
	s_mov_b64 s[4:5], 0
	v_cvt_pk_bf16_f32 v162, v152, v153
	v_cvt_pk_bf16_f32 v163, v150, v151
	global_store_dwordx2 v[164:165], v[162:163], off

.LBB0_1484:
	v_add_u32_e32 v146, 0xa0, v138
	v_mad_i64_i32 v[148:149], s[4:5], s88, v146, 0
	v_lshlrev_b64 v[152:153], 2, v[148:149]
	v_lshl_add_u64 v[148:149], v[142:143], 0, v[152:153]
	global_load_dwordx4 v[148:151], v[148:149], off
	v_lshl_add_u64 v[152:153], v[144:145], 0, v[152:153]
	global_load_dwordx4 v[162:165], v[152:153], off
	s_and_b64 vcc, exec, s[8:9]
	v_ashrrev_i32_e32 v147, 31, v146
	s_mov_b64 s[4:5], -1
	s_waitcnt vmcnt(1)
	v_mul_f32_e32 v152, v76, v150
	v_mul_f32_e32 v153, v77, v151
	v_mul_f32_e32 v154, v74, v148
	v_mul_f32_e32 v155, v75, v149
	v_mul_f32_e32 v150, v80, v150
	v_mul_f32_e32 v151, v81, v151
	v_mul_f32_e32 v166, v78, v148
	v_mul_f32_e32 v167, v79, v149
	s_waitcnt vmcnt(0)
	v_fma_f32 v148, v80, v164, -v152
	v_fma_f32 v149, v81, v165, -v153
	v_fma_f32 v154, v78, v162, -v154
	v_fma_f32 v155, v79, v163, -v155
	v_fmac_f32_e32 v150, v76, v164
	v_fmac_f32_e32 v151, v77, v165
	v_fma_f32 v152, v74, v162, v166
	v_fma_f32 v153, v75, v163, v167
	s_cbranch_vccnz .LBB0_1486
	v_mul_lo_u32 v139, s87, v146
	v_mul_lo_u32 v161, s86, v147
	v_mad_u64_u32 v[164:165], s[4:5], s86, v146, 0
	v_add3_u32 v165, v165, v161, v139
	v_lshl_add_u64 v[164:165], v[164:165], 1, v[140:141]
	s_lshl_b32 s26, s88, 1
	v_cvt_pk_bf16_f32 v162, v154, v155
	v_cvt_pk_bf16_f32 v163, v148, v149
	global_store_dwordx2 v[164:165], v[162:163], off
	v_lshl_add_u64 v[164:165], v[164:165], 0, s[26:27]
	s_mov_b64 s[4:5], 0
	v_cvt_pk_bf16_f32 v162, v152, v153
	v_cvt_pk_bf16_f32 v163, v150, v151
	global_store_dwordx2 v[164:165], v[162:163], off

.LBB0_1488:
	v_add_u32_e32 v146, 0xb0, v138
	v_mad_i64_i32 v[148:149], s[4:5], s88, v146, 0
	v_lshlrev_b64 v[152:153], 2, v[148:149]
	v_lshl_add_u64 v[142:143], v[142:143], 0, v[152:153]
	global_load_dwordx4 v[148:151], v[142:143], off
	v_lshl_add_u64 v[142:143], v[144:145], 0, v[152:153]
	global_load_dwordx4 v[162:165], v[142:143], off
	s_and_b64 vcc, exec, s[8:9]
	v_ashrrev_i32_e32 v147, 31, v146
	s_mov_b64 s[4:5], -1
	s_waitcnt vmcnt(1)
	v_mul_f32_e32 v142, v68, v150
	v_mul_f32_e32 v143, v69, v151
	v_mul_f32_e32 v144, v66, v148
	v_mul_f32_e32 v145, v67, v149
	v_mul_f32_e32 v150, v72, v150
	v_mul_f32_e32 v151, v73, v151
	v_mul_f32_e32 v154, v70, v148
	v_mul_f32_e32 v155, v71, v149
	s_waitcnt vmcnt(0)
	v_fma_f32 v142, v72, v164, -v142
	v_fma_f32 v143, v73, v165, -v143
	v_fma_f32 v152, v70, v162, -v144
	v_fma_f32 v153, v71, v163, -v145
	v_fma_f32 v148, v68, v164, v150
	v_fma_f32 v149, v69, v165, v151
	v_fma_f32 v150, v66, v162, v154
	v_fma_f32 v151, v67, v163, v155
	s_cbranch_vccnz .LBB0_1490
	v_mul_lo_u32 v139, s87, v146
	v_mul_lo_u32 v161, s86, v147
	v_mad_u64_u32 v[154:155], s[4:5], s86, v146, 0
	v_add3_u32 v155, v155, v161, v139
	v_lshl_add_u64 v[140:141], v[154:155], 1, v[140:141]
	s_lshl_b32 s26, s88, 1
	v_cvt_pk_bf16_f32 v144, v152, v153
	v_cvt_pk_bf16_f32 v145, v142, v143
	global_store_dwordx2 v[140:141], v[144:145], off
	v_lshl_add_u64 v[140:141], v[140:141], 0, s[26:27]
	s_mov_b64 s[4:5], 0
	v_cvt_pk_bf16_f32 v144, v150, v151
	v_cvt_pk_bf16_f32 v145, v148, v149
	global_store_dwordx2 v[140:141], v[144:145], off

.LBB0_1526:
	v_lshlrev_b64 v[70:71], 2, v[134:135]
	v_lshl_add_u64 v[68:69], s[4:5], 0, v[70:71]
	v_mad_i64_i32 v[72:73], s[4:5], s88, v138, 0
	v_lshlrev_b64 v[76:77], 2, v[72:73]
	v_lshl_add_u64 v[72:73], v[68:69], 0, v[76:77]
	v_lshl_add_u64 v[70:71], s[92:93], 0, v[70:71]
	global_load_dwordx4 v[72:75], v[72:73], off
	v_lshl_add_u64 v[76:77], v[70:71], 0, v[76:77]
	global_load_dwordx4 v[80:83], v[76:77], off
	v_mov_b32_e32 v134, v66
	v_cndmask_b32_e64 v76, 0, 1, s[90:91]
	s_waitcnt lgkmcnt(0)
	v_lshl_add_u64 v[66:67], v[134:135], 1, s[8:9]
	v_cmp_ne_u32_e64 s[8:9], 1, v76
	v_ashrrev_i32_e32 v139, 31, v138
	s_andn2_b64 vcc, exec, s[90:91]
	s_mov_b64 s[4:5], -1
	s_waitcnt vmcnt(0)
	v_mul_f32_e32 v76, v60, v74
	v_mul_f32_e32 v77, v61, v75
	v_mul_f32_e32 v78, v58, v72
	v_mul_f32_e32 v79, v59, v73
	v_mul_f32_e32 v74, v64, v74
	v_mul_f32_e32 v75, v65, v75
	v_mul_f32_e32 v84, v62, v72
	v_mul_f32_e32 v85, v63, v73
	v_fma_f32 v72, v64, v82, -v76
	v_fma_f32 v73, v65, v83, -v77
	v_fma_f32 v78, v62, v80, -v78
	v_fma_f32 v79, v63, v81, -v79
	v_fmac_f32_e32 v74, v60, v82
	v_fmac_f32_e32 v75, v61, v83
	v_fma_f32 v76, v58, v80, v84
	v_fma_f32 v77, v59, v81, v85
	s_cbranch_vccnz .LBB0_1528
	v_mul_lo_u32 v84, s87, v138
	v_mul_lo_u32 v85, s86, v139
	v_mad_u64_u32 v[82:83], s[4:5], s86, v138, 0
	v_add3_u32 v83, v83, v85, v84
	v_lshl_add_u64 v[82:83], v[82:83], 1, v[66:67]
	s_lshl_b32 s26, s88, 1
	v_cvt_pk_bf16_f32 v80, v78, v79
	v_cvt_pk_bf16_f32 v81, v72, v73
	global_store_dwordx2 v[82:83], v[80:81], off
	v_lshl_add_u64 v[82:83], v[82:83], 0, s[26:27]
	s_mov_b64 s[4:5], 0
	v_cvt_pk_bf16_f32 v80, v76, v77
	v_cvt_pk_bf16_f32 v81, v74, v75
	global_store_dwordx2 v[82:83], v[80:81], off

.LBB0_1530:
	v_or_b32_e32 v72, 16, v138
	v_mad_i64_i32 v[74:75], s[4:5], s88, v72, 0
	v_lshlrev_b64 v[78:79], 2, v[74:75]
	v_lshl_add_u64 v[74:75], v[68:69], 0, v[78:79]
	global_load_dwordx4 v[74:77], v[74:75], off
	v_lshl_add_u64 v[78:79], v[70:71], 0, v[78:79]
	global_load_dwordx4 v[82:85], v[78:79], off
	s_and_b64 vcc, exec, s[8:9]
	v_ashrrev_i32_e32 v73, 31, v72
	s_mov_b64 s[4:5], -1
	s_waitcnt vmcnt(1)
	v_mul_f32_e32 v78, v52, v76
	v_mul_f32_e32 v79, v53, v77
	v_mul_f32_e32 v80, v50, v74
	v_mul_f32_e32 v81, v51, v75
	v_mul_f32_e32 v76, v56, v76
	v_mul_f32_e32 v77, v57, v77
	v_mul_f32_e32 v86, v54, v74
	v_mul_f32_e32 v87, v55, v75
	s_waitcnt vmcnt(0)
	v_fma_f32 v74, v56, v84, -v78
	v_fma_f32 v75, v57, v85, -v79
	v_fma_f32 v80, v54, v82, -v80
	v_fma_f32 v81, v55, v83, -v81
	v_fmac_f32_e32 v76, v52, v84
	v_fmac_f32_e32 v77, v53, v85
	v_fma_f32 v78, v50, v82, v86
	v_fma_f32 v79, v51, v83, v87
	s_cbranch_vccnz .LBB0_1532
	v_mul_lo_u32 v86, s87, v72
	v_mul_lo_u32 v87, s86, v73
	v_mad_u64_u32 v[84:85], s[4:5], s86, v72, 0
	v_add3_u32 v85, v85, v87, v86
	v_lshl_add_u64 v[84:85], v[84:85], 1, v[66:67]
	s_lshl_b32 s26, s88, 1
	v_cvt_pk_bf16_f32 v82, v80, v81
	v_cvt_pk_bf16_f32 v83, v74, v75
	global_store_dwordx2 v[84:85], v[82:83], off
	v_lshl_add_u64 v[84:85], v[84:85], 0, s[26:27]
	s_mov_b64 s[4:5], 0
	v_cvt_pk_bf16_f32 v82, v78, v79
	v_cvt_pk_bf16_f32 v83, v76, v77
	global_store_dwordx2 v[84:85], v[82:83], off

.LBB0_1534:
	v_or_b32_e32 v72, 32, v138
	v_mad_i64_i32 v[74:75], s[4:5], s88, v72, 0
	v_lshlrev_b64 v[78:79], 2, v[74:75]
	v_lshl_add_u64 v[74:75], v[68:69], 0, v[78:79]
	global_load_dwordx4 v[74:77], v[74:75], off
	v_lshl_add_u64 v[78:79], v[70:71], 0, v[78:79]
	global_load_dwordx4 v[82:85], v[78:79], off
	s_and_b64 vcc, exec, s[8:9]
	v_ashrrev_i32_e32 v73, 31, v72
	s_mov_b64 s[4:5], -1
	s_waitcnt vmcnt(1)
	v_mul_f32_e32 v78, v44, v76
	v_mul_f32_e32 v79, v45, v77
	v_mul_f32_e32 v80, v42, v74
	v_mul_f32_e32 v81, v43, v75
	v_mul_f32_e32 v76, v48, v76
	v_mul_f32_e32 v77, v49, v77
	v_mul_f32_e32 v86, v46, v74
	v_mul_f32_e32 v87, v47, v75
	s_waitcnt vmcnt(0)
	v_fma_f32 v74, v48, v84, -v78
	v_fma_f32 v75, v49, v85, -v79
	v_fma_f32 v80, v46, v82, -v80
	v_fma_f32 v81, v47, v83, -v81
	v_fmac_f32_e32 v76, v44, v84
	v_fmac_f32_e32 v77, v45, v85
	v_fma_f32 v78, v42, v82, v86
	v_fma_f32 v79, v43, v83, v87
	s_cbranch_vccnz .LBB0_1536
	v_mul_lo_u32 v86, s87, v72
	v_mul_lo_u32 v87, s86, v73
	v_mad_u64_u32 v[84:85], s[4:5], s86, v72, 0
	v_add3_u32 v85, v85, v87, v86
	v_lshl_add_u64 v[84:85], v[84:85], 1, v[66:67]
	s_lshl_b32 s26, s88, 1
	v_cvt_pk_bf16_f32 v82, v80, v81
	v_cvt_pk_bf16_f32 v83, v74, v75
	global_store_dwordx2 v[84:85], v[82:83], off
	v_lshl_add_u64 v[84:85], v[84:85], 0, s[26:27]
	s_mov_b64 s[4:5], 0
	v_cvt_pk_bf16_f32 v82, v78, v79
	v_cvt_pk_bf16_f32 v83, v76, v77
	global_store_dwordx2 v[84:85], v[82:83], off

.LBB0_1538:
	v_or_b32_e32 v72, 48, v138
	v_mad_i64_i32 v[74:75], s[4:5], s88, v72, 0
	v_lshlrev_b64 v[78:79], 2, v[74:75]
	v_lshl_add_u64 v[74:75], v[68:69], 0, v[78:79]
	global_load_dwordx4 v[74:77], v[74:75], off
	v_lshl_add_u64 v[78:79], v[70:71], 0, v[78:79]
	global_load_dwordx4 v[82:85], v[78:79], off
	s_and_b64 vcc, exec, s[8:9]
	v_ashrrev_i32_e32 v73, 31, v72
	s_mov_b64 s[4:5], -1
	s_waitcnt vmcnt(1)
	v_mul_f32_e32 v78, v36, v76
	v_mul_f32_e32 v79, v37, v77
	v_mul_f32_e32 v80, v34, v74
	v_mul_f32_e32 v81, v35, v75
	v_mul_f32_e32 v76, v40, v76
	v_mul_f32_e32 v77, v41, v77
	v_mul_f32_e32 v86, v38, v74
	v_mul_f32_e32 v87, v39, v75
	s_waitcnt vmcnt(0)
	v_fma_f32 v74, v40, v84, -v78
	v_fma_f32 v75, v41, v85, -v79
	v_fma_f32 v80, v38, v82, -v80
	v_fma_f32 v81, v39, v83, -v81
	v_fmac_f32_e32 v76, v36, v84
	v_fmac_f32_e32 v77, v37, v85
	v_fma_f32 v78, v34, v82, v86
	v_fma_f32 v79, v35, v83, v87
	s_cbranch_vccnz .LBB0_1540
	v_mul_lo_u32 v86, s87, v72
	v_mul_lo_u32 v87, s86, v73
	v_mad_u64_u32 v[84:85], s[4:5], s86, v72, 0
	v_add3_u32 v85, v85, v87, v86
	v_lshl_add_u64 v[84:85], v[84:85], 1, v[66:67]
	s_lshl_b32 s26, s88, 1
	v_cvt_pk_bf16_f32 v82, v80, v81
	v_cvt_pk_bf16_f32 v83, v74, v75
	global_store_dwordx2 v[84:85], v[82:83], off
	v_lshl_add_u64 v[84:85], v[84:85], 0, s[26:27]
	s_mov_b64 s[4:5], 0
	v_cvt_pk_bf16_f32 v82, v78, v79
	v_cvt_pk_bf16_f32 v83, v76, v77
	global_store_dwordx2 v[84:85], v[82:83], off

.LBB0_1542:
	v_add_u32_e32 v72, 0x80, v138
	v_mad_i64_i32 v[74:75], s[4:5], s88, v72, 0
	v_lshlrev_b64 v[78:79], 2, v[74:75]
	v_lshl_add_u64 v[74:75], v[68:69], 0, v[78:79]
	global_load_dwordx4 v[74:77], v[74:75], off
	v_lshl_add_u64 v[78:79], v[70:71], 0, v[78:79]
	global_load_dwordx4 v[82:85], v[78:79], off
	s_and_b64 vcc, exec, s[8:9]
	v_ashrrev_i32_e32 v73, 31, v72
	s_mov_b64 s[4:5], -1
	s_waitcnt vmcnt(1)
	v_mul_f32_e32 v78, v28, v76
	v_mul_f32_e32 v79, v29, v77
	v_mul_f32_e32 v80, v26, v74
	v_mul_f32_e32 v81, v27, v75
	v_mul_f32_e32 v76, v32, v76
	v_mul_f32_e32 v77, v33, v77
	v_mul_f32_e32 v86, v30, v74
	v_mul_f32_e32 v87, v31, v75
	s_waitcnt vmcnt(0)
	v_fma_f32 v74, v32, v84, -v78
	v_fma_f32 v75, v33, v85, -v79
	v_fma_f32 v80, v30, v82, -v80
	v_fma_f32 v81, v31, v83, -v81
	v_fmac_f32_e32 v76, v28, v84
	v_fmac_f32_e32 v77, v29, v85
	v_fma_f32 v78, v26, v82, v86
	v_fma_f32 v79, v27, v83, v87
	s_cbranch_vccnz .LBB0_1544
	v_mul_lo_u32 v86, s87, v72
	v_mul_lo_u32 v87, s86, v73
	v_mad_u64_u32 v[84:85], s[4:5], s86, v72, 0
	v_add3_u32 v85, v85, v87, v86
	v_lshl_add_u64 v[84:85], v[84:85], 1, v[66:67]
	s_lshl_b32 s26, s88, 1
	v_cvt_pk_bf16_f32 v82, v80, v81
	v_cvt_pk_bf16_f32 v83, v74, v75
	global_store_dwordx2 v[84:85], v[82:83], off
	v_lshl_add_u64 v[84:85], v[84:85], 0, s[26:27]
	s_mov_b64 s[4:5], 0
	v_cvt_pk_bf16_f32 v82, v78, v79
	v_cvt_pk_bf16_f32 v83, v76, v77
	global_store_dwordx2 v[84:85], v[82:83], off

.LBB0_1546:
	v_add_u32_e32 v72, 0x90, v138
	v_mad_i64_i32 v[74:75], s[4:5], s88, v72, 0
	v_lshlrev_b64 v[78:79], 2, v[74:75]
	v_lshl_add_u64 v[74:75], v[68:69], 0, v[78:79]
	global_load_dwordx4 v[74:77], v[74:75], off
	v_lshl_add_u64 v[78:79], v[70:71], 0, v[78:79]
	global_load_dwordx4 v[82:85], v[78:79], off
	s_and_b64 vcc, exec, s[8:9]
	v_ashrrev_i32_e32 v73, 31, v72
	s_mov_b64 s[4:5], -1
	s_waitcnt vmcnt(1)
	v_mul_f32_e32 v78, v20, v76
	v_mul_f32_e32 v79, v21, v77
	v_mul_f32_e32 v80, v18, v74
	v_mul_f32_e32 v81, v19, v75
	v_mul_f32_e32 v76, v24, v76
	v_mul_f32_e32 v77, v25, v77
	v_mul_f32_e32 v86, v22, v74
	v_mul_f32_e32 v87, v23, v75
	s_waitcnt vmcnt(0)
	v_fma_f32 v74, v24, v84, -v78
	v_fma_f32 v75, v25, v85, -v79
	v_fma_f32 v80, v22, v82, -v80
	v_fma_f32 v81, v23, v83, -v81
	v_fmac_f32_e32 v76, v20, v84
	v_fmac_f32_e32 v77, v21, v85
	v_fma_f32 v78, v18, v82, v86
	v_fma_f32 v79, v19, v83, v87
	s_cbranch_vccnz .LBB0_1548
	v_mul_lo_u32 v86, s87, v72
	v_mul_lo_u32 v87, s86, v73
	v_mad_u64_u32 v[84:85], s[4:5], s86, v72, 0
	v_add3_u32 v85, v85, v87, v86
	v_lshl_add_u64 v[84:85], v[84:85], 1, v[66:67]
	s_lshl_b32 s26, s88, 1
	v_cvt_pk_bf16_f32 v82, v80, v81
	v_cvt_pk_bf16_f32 v83, v74, v75
	global_store_dwordx2 v[84:85], v[82:83], off
	v_lshl_add_u64 v[84:85], v[84:85], 0, s[26:27]
	s_mov_b64 s[4:5], 0
	v_cvt_pk_bf16_f32 v82, v78, v79
	v_cvt_pk_bf16_f32 v83, v76, v77
	global_store_dwordx2 v[84:85], v[82:83], off

.LBB0_1550:
	v_add_u32_e32 v72, 0xa0, v138
	v_mad_i64_i32 v[74:75], s[4:5], s88, v72, 0
	v_lshlrev_b64 v[78:79], 2, v[74:75]
	v_lshl_add_u64 v[74:75], v[68:69], 0, v[78:79]
	global_load_dwordx4 v[74:77], v[74:75], off
	v_lshl_add_u64 v[78:79], v[70:71], 0, v[78:79]
	global_load_dwordx4 v[82:85], v[78:79], off
	s_and_b64 vcc, exec, s[8:9]
	v_ashrrev_i32_e32 v73, 31, v72
	s_mov_b64 s[4:5], -1
	s_waitcnt vmcnt(1)
	v_mul_f32_e32 v78, v12, v76
	v_mul_f32_e32 v79, v13, v77
	v_mul_f32_e32 v80, v10, v74
	v_mul_f32_e32 v81, v11, v75
	v_mul_f32_e32 v76, v16, v76
	v_mul_f32_e32 v77, v17, v77
	v_mul_f32_e32 v86, v14, v74
	v_mul_f32_e32 v87, v15, v75
	s_waitcnt vmcnt(0)
	v_fma_f32 v74, v16, v84, -v78
	v_fma_f32 v75, v17, v85, -v79
	v_fma_f32 v80, v14, v82, -v80
	v_fma_f32 v81, v15, v83, -v81
	v_fmac_f32_e32 v76, v12, v84
	v_fmac_f32_e32 v77, v13, v85
	v_fma_f32 v78, v10, v82, v86
	v_fma_f32 v79, v11, v83, v87
	s_cbranch_vccnz .LBB0_1552
	v_mul_lo_u32 v86, s87, v72
	v_mul_lo_u32 v87, s86, v73
	v_mad_u64_u32 v[84:85], s[4:5], s86, v72, 0
	v_add3_u32 v85, v85, v87, v86
	v_lshl_add_u64 v[84:85], v[84:85], 1, v[66:67]
	s_lshl_b32 s26, s88, 1
	v_cvt_pk_bf16_f32 v82, v80, v81
	v_cvt_pk_bf16_f32 v83, v74, v75
	global_store_dwordx2 v[84:85], v[82:83], off
	v_lshl_add_u64 v[84:85], v[84:85], 0, s[26:27]
	s_mov_b64 s[4:5], 0
	v_cvt_pk_bf16_f32 v82, v78, v79
	v_cvt_pk_bf16_f32 v83, v76, v77
	global_store_dwordx2 v[84:85], v[82:83], off

.LBB0_1554:
	v_add_u32_e32 v72, 0xb0, v138
	v_mad_i64_i32 v[74:75], s[4:5], s88, v72, 0
	v_lshlrev_b64 v[78:79], 2, v[74:75]
	v_lshl_add_u64 v[68:69], v[68:69], 0, v[78:79]
	global_load_dwordx4 v[74:77], v[68:69], off
	v_lshl_add_u64 v[68:69], v[70:71], 0, v[78:79]
	global_load_dwordx4 v[80:83], v[68:69], off
	s_and_b64 vcc, exec, s[8:9]
	v_ashrrev_i32_e32 v73, 31, v72
	s_mov_b64 s[4:5], -1
	s_waitcnt vmcnt(1)
	v_mul_f32_e32 v68, v4, v76
	v_mul_f32_e32 v69, v5, v77
	v_mul_f32_e32 v70, v2, v74
	v_mul_f32_e32 v71, v3, v75
	v_mul_f32_e32 v76, v8, v76
	v_mul_f32_e32 v77, v9, v77
	v_mul_f32_e32 v84, v6, v74
	v_mul_f32_e32 v85, v7, v75
	s_waitcnt vmcnt(0)
	v_fma_f32 v68, v8, v82, -v68
	v_fma_f32 v69, v9, v83, -v69
	v_fma_f32 v78, v6, v80, -v70
	v_fma_f32 v79, v7, v81, -v71
	v_fma_f32 v74, v4, v82, v76
	v_fma_f32 v75, v5, v83, v77
	v_fma_f32 v76, v2, v80, v84
	v_fma_f32 v77, v3, v81, v85
	s_cbranch_vccnz .LBB0_1556
	v_mul_lo_u32 v82, s87, v72
	v_mul_lo_u32 v83, s86, v73
	v_mad_u64_u32 v[80:81], s[4:5], s86, v72, 0
	v_add3_u32 v81, v81, v83, v82
	v_lshl_add_u64 v[66:67], v[80:81], 1, v[66:67]
	s_lshl_b32 s26, s88, 1
	v_cvt_pk_bf16_f32 v70, v78, v79
	v_cvt_pk_bf16_f32 v71, v68, v69
	global_store_dwordx2 v[66:67], v[70:71], off
	v_lshl_add_u64 v[66:67], v[66:67], 0, s[26:27]
	s_mov_b64 s[4:5], 0
	v_cvt_pk_bf16_f32 v70, v76, v77
	v_cvt_pk_bf16_f32 v71, v74, v75
	global_store_dwordx2 v[66:67], v[70:71], off

.LBB0_1596:
	v_mov_b32_e32 v34, v0
	s_lshl_b32 s4, s6, 8
	s_add_i32 s4, s4, s90
	v_and_b32_e32 v139, 15, v34
	v_or_b32_e32 v140, s4, v139
	v_ashrrev_i32_e32 v141, 31, v140
	v_lshlrev_b64 v[142:143], 6, v[140:141]
	v_lshl_add_u64 v[154:155], s[26:27], 0, v[142:143]
	global_load_dwordx4 v[142:145], v[154:155], off offset:32
	global_load_dwordx4 v[146:149], v[154:155], off offset:48
	global_load_dwordx4 v[150:153], v[154:155], off
	global_load_dwordx4 v[186:189], v[154:155], off offset:16
	v_bfe_u32 v199, v34, 4, 2
	s_lshl_b32 s2, s2, 8
	s_waitcnt vmcnt(0)
	v_add_f32_e32 v144, v144, v148
	v_add_f32_e32 v145, v145, v149
	v_add_f32_e32 v142, v142, v146
	v_add_f32_e32 v143, v143, v147
	v_add_f32_e32 v152, v152, v188
	v_add_f32_e32 v153, v153, v189
	v_add_f32_e32 v150, v150, v186
	v_add_f32_e32 v151, v151, v187
	v_add_f32_e32 v144, v152, v144
	v_add_f32_e32 v145, v153, v145
	v_add_f32_e32 v142, v150, v142
	v_add_f32_e32 v143, v151, v143
	s_nop 0
	v_add_f32_e32 v34, v142, v143
	v_add_f32_e32 v142, v144, v145
	v_add_f32_e32 v34, v34, v142
	v_fmamk_f32 v34, v34, 0x3b000000, v169
	v_cmp_gt_f32_e32 vcc, s95, v34
	v_mul_f32_e32 v142, 0x4f800000, v34
	s_nop 0
	v_cndmask_b32_e32 v34, v34, v142, vcc
	v_sqrt_f32_e32 v142, v34
	s_nop 0
	v_add_u32_e32 v143, -1, v142
	v_fma_f32 v144, -v143, v142, v34
	v_cmp_ge_f32_e64 s[6:7], 0, v144
	v_add_u32_e32 v144, 1, v142
	s_nop 0
	v_cndmask_b32_e64 v143, v142, v143, s[6:7]
	v_fma_f32 v142, -v144, v142, v34
	v_cmp_lt_f32_e64 s[6:7], 0, v142
	s_nop 1
	v_cndmask_b32_e64 v142, v143, v144, s[6:7]
	v_mul_f32_e32 v143, 0x37800000, v142
	v_cndmask_b32_e32 v142, v142, v143, vcc
	v_cmp_class_f32_e32 vcc, v34, v173
	s_nop 1
	v_cndmask_b32_e32 v34, v142, v34, vcc
	v_div_scale_f32 v142, s[6:7], v34, v34, 1.0
	v_rcp_f32_e32 v143, v142
	s_nop 0
	v_fma_f32 v144, -v142, v143, 1.0
	v_fmac_f32_e32 v143, v144, v143
	v_div_scale_f32 v144, vcc, 1.0, v34, 1.0
	v_mul_f32_e32 v145, v144, v143
	v_fma_f32 v146, -v142, v145, v144
	v_fmac_f32_e32 v145, v146, v143
	v_fma_f32 v142, -v142, v145, v144
	v_div_fmas_f32 v142, v142, v143, v145
	v_div_fixup_f32 v202, v142, v34, 1.0
	v_or_b32_e32 v142, 16, v140
	v_ashrrev_i32_e32 v143, 31, v142
	v_lshlrev_b64 v[144:145], 6, v[142:143]
	v_lshl_add_u64 v[158:159], s[26:27], 0, v[144:145]
	global_load_dwordx4 v[144:147], v[158:159], off offset:32
	global_load_dwordx4 v[148:151], v[158:159], off offset:48
	global_load_dwordx4 v[152:155], v[158:159], off
	global_load_dwordx4 v[186:189], v[158:159], off offset:16
	v_mul_f32_e32 v184, 0x3f553b94, v202
	v_lshlrev_b64 v[182:183], 7, v[142:143]
	s_waitcnt vmcnt(2)
	v_add_f32_e32 v146, v146, v150
	v_add_f32_e32 v147, v147, v151
	v_add_f32_e32 v144, v144, v148
	v_add_f32_e32 v145, v145, v149
	s_waitcnt vmcnt(0)
	v_add_f32_e32 v154, v154, v188
	v_add_f32_e32 v155, v155, v189
	v_add_f32_e32 v152, v152, v186
	v_add_f32_e32 v153, v153, v187
	v_add_f32_e32 v146, v154, v146
	v_add_f32_e32 v147, v155, v147
	v_add_f32_e32 v144, v152, v144
	v_add_f32_e32 v145, v153, v145
	s_nop 0
	v_add_f32_e32 v34, v144, v145
	v_add_f32_e32 v144, v146, v147
	v_add_f32_e32 v34, v34, v144
	v_fmamk_f32 v34, v34, 0x3b000000, v169
	v_cmp_gt_f32_e32 vcc, s95, v34
	v_mul_f32_e32 v144, 0x4f800000, v34
	s_nop 0
	v_cndmask_b32_e32 v34, v34, v144, vcc
	v_sqrt_f32_e32 v144, v34
	s_nop 0
	v_add_u32_e32 v145, -1, v144
	v_fma_f32 v146, -v145, v144, v34
	v_cmp_ge_f32_e64 s[6:7], 0, v146
	v_add_u32_e32 v146, 1, v144
	s_nop 0
	v_cndmask_b32_e64 v145, v144, v145, s[6:7]
	v_fma_f32 v144, -v146, v144, v34
	v_cmp_lt_f32_e64 s[6:7], 0, v144
	s_nop 1
	v_cndmask_b32_e64 v144, v145, v146, s[6:7]
	v_mul_f32_e32 v145, 0x37800000, v144
	v_cndmask_b32_e32 v144, v144, v145, vcc
	v_cmp_class_f32_e32 vcc, v34, v173
	s_nop 1
	v_cndmask_b32_e32 v34, v144, v34, vcc
	v_div_scale_f32 v144, s[6:7], v34, v34, 1.0
	v_rcp_f32_e32 v145, v144
	s_nop 0
	v_fma_f32 v146, -v144, v145, 1.0
	v_fmac_f32_e32 v145, v146, v145
	v_div_scale_f32 v146, vcc, 1.0, v34, 1.0
	v_mul_f32_e32 v147, v146, v145
	v_fma_f32 v148, -v144, v147, v146
	v_fmac_f32_e32 v147, v148, v145
	v_fma_f32 v144, -v144, v147, v146
	v_div_fmas_f32 v144, v144, v145, v147
	v_div_fixup_f32 v203, v144, v34, 1.0
	v_or_b32_e32 v144, 32, v140
	v_ashrrev_i32_e32 v145, 31, v144
	v_lshlrev_b64 v[146:147], 6, v[144:145]
	v_lshl_add_u64 v[154:155], s[26:27], 0, v[146:147]
	global_load_dwordx4 v[146:149], v[154:155], off offset:32
	global_load_dwordx4 v[150:153], v[154:155], off offset:48
	global_load_dwordx4 v[186:189], v[154:155], off
	global_load_dwordx4 v[190:193], v[154:155], off offset:16
	v_mul_f32_e32 v180, 0x3f553b94, v203
	v_lshlrev_b64 v[178:179], 7, v[144:145]
	s_waitcnt vmcnt(2)
	v_add_f32_e32 v148, v148, v152
	v_add_f32_e32 v149, v149, v153
	v_add_f32_e32 v146, v146, v150
	v_add_f32_e32 v147, v147, v151
	s_waitcnt vmcnt(0)
	v_add_f32_e32 v154, v188, v192
	v_add_f32_e32 v155, v189, v193
	v_add_f32_e32 v158, v186, v190
	v_add_f32_e32 v159, v187, v191
	v_add_f32_e32 v148, v154, v148
	v_add_f32_e32 v149, v155, v149
	v_add_f32_e32 v146, v158, v146
	v_add_f32_e32 v147, v159, v147
	s_nop 0
	v_add_f32_e32 v34, v146, v147
	v_add_f32_e32 v146, v148, v149
	v_add_f32_e32 v34, v34, v146
	v_fmamk_f32 v34, v34, 0x3b000000, v169
	v_cmp_gt_f32_e32 vcc, s95, v34
	v_mul_f32_e32 v146, 0x4f800000, v34
	s_nop 0
	v_cndmask_b32_e32 v34, v34, v146, vcc
	v_sqrt_f32_e32 v146, v34
	s_nop 0
	v_add_u32_e32 v147, -1, v146
	v_fma_f32 v148, -v147, v146, v34
	v_cmp_ge_f32_e64 s[6:7], 0, v148
	v_add_u32_e32 v148, 1, v146
	s_nop 0
	v_cndmask_b32_e64 v147, v146, v147, s[6:7]
	v_fma_f32 v146, -v148, v146, v34
	v_cmp_lt_f32_e64 s[6:7], 0, v146
	s_nop 1
	v_cndmask_b32_e64 v146, v147, v148, s[6:7]
	v_mul_f32_e32 v147, 0x37800000, v146
	v_cndmask_b32_e32 v146, v146, v147, vcc
	v_cmp_class_f32_e32 vcc, v34, v173
	s_nop 1
	v_cndmask_b32_e32 v34, v146, v34, vcc
	v_div_scale_f32 v146, s[6:7], v34, v34, 1.0
	v_rcp_f32_e32 v147, v146
	s_nop 0
	v_fma_f32 v148, -v146, v147, 1.0
	v_fmac_f32_e32 v147, v148, v147
	v_div_scale_f32 v148, vcc, 1.0, v34, 1.0
	v_mul_f32_e32 v149, v148, v147
	v_fma_f32 v150, -v146, v149, v148
	v_fmac_f32_e32 v149, v150, v147
	v_fma_f32 v146, -v146, v149, v148
	v_div_fmas_f32 v146, v146, v147, v149
	v_div_fixup_f32 v205, v146, v34, 1.0
	v_or_b32_e32 v146, 48, v140
	v_ashrrev_i32_e32 v147, 31, v146
	v_lshlrev_b64 v[148:149], 6, v[146:147]
	v_lshl_add_u64 v[158:159], s[26:27], 0, v[148:149]
	global_load_dwordx4 v[148:151], v[158:159], off offset:32
	global_load_dwordx4 v[152:155], v[158:159], off offset:48
	global_load_dwordx4 v[186:189], v[158:159], off
	global_load_dwordx4 v[190:193], v[158:159], off offset:16
	v_mul_f32_e32 v176, 0x3f553b94, v205
	v_lshlrev_b64 v[174:175], 7, v[146:147]
	s_waitcnt vmcnt(2)
	v_add_f32_e32 v150, v150, v154
	v_add_f32_e32 v151, v151, v155
	v_add_f32_e32 v148, v148, v152
	v_add_f32_e32 v149, v149, v153
	s_waitcnt vmcnt(0)
	v_add_f32_e32 v158, v188, v192
	v_add_f32_e32 v159, v189, v193
	v_add_f32_e32 v162, v186, v190
	v_add_f32_e32 v163, v187, v191
	v_add_f32_e32 v150, v158, v150
	v_add_f32_e32 v151, v159, v151
	v_add_f32_e32 v148, v162, v148
	v_add_f32_e32 v149, v163, v149
	s_nop 0
	v_add_f32_e32 v34, v148, v149
	v_add_f32_e32 v148, v150, v151
	v_add_f32_e32 v34, v34, v148
	v_fmamk_f32 v34, v34, 0x3b000000, v169
	v_cmp_gt_f32_e32 vcc, s95, v34
	v_mul_f32_e32 v148, 0x4f800000, v34
	s_nop 0
	v_cndmask_b32_e32 v34, v34, v148, vcc
	v_sqrt_f32_e32 v148, v34
	s_nop 0
	v_add_u32_e32 v149, -1, v148
	v_fma_f32 v150, -v149, v148, v34
	v_cmp_ge_f32_e64 s[6:7], 0, v150
	v_add_u32_e32 v150, 1, v148
	s_nop 0
	v_cndmask_b32_e64 v149, v148, v149, s[6:7]
	v_fma_f32 v148, -v150, v148, v34
	v_cmp_lt_f32_e64 s[6:7], 0, v148
	s_nop 1
	v_cndmask_b32_e64 v148, v149, v150, s[6:7]
	v_mul_f32_e32 v149, 0x37800000, v148
	v_cndmask_b32_e32 v148, v148, v149, vcc
	v_cmp_class_f32_e32 vcc, v34, v173
	s_nop 1
	v_cndmask_b32_e32 v34, v148, v34, vcc
	v_div_scale_f32 v148, s[6:7], v34, v34, 1.0
	v_rcp_f32_e32 v149, v148
	s_nop 0
	v_fma_f32 v150, -v148, v149, 1.0
	v_fmac_f32_e32 v149, v150, v149
	v_div_scale_f32 v150, vcc, 1.0, v34, 1.0
	v_mul_f32_e32 v151, v150, v149
	v_fma_f32 v152, -v148, v151, v150
	v_fmac_f32_e32 v151, v152, v149
	v_fma_f32 v148, -v148, v151, v150
	v_div_fmas_f32 v148, v148, v149, v151
	v_div_fixup_f32 v206, v148, v34, 1.0
	v_add_u32_e32 v148, 0x80, v140
	v_ashrrev_i32_e32 v149, 31, v148
	v_lshlrev_b64 v[150:151], 6, v[148:149]
	v_lshl_add_u64 v[154:155], s[26:27], 0, v[150:151]
	global_load_dwordx4 v[150:153], v[154:155], off offset:32
	global_load_dwordx4 v[186:189], v[154:155], off offset:48
	global_load_dwordx4 v[190:193], v[154:155], off
	global_load_dwordx4 v[208:211], v[154:155], off offset:16
	v_mul_f32_e32 v172, 0x3f553b94, v206
	s_waitcnt vmcnt(2)
	v_add_f32_e32 v152, v152, v188
	v_add_f32_e32 v153, v153, v189
	v_add_f32_e32 v150, v150, v186
	v_add_f32_e32 v151, v151, v187
	s_waitcnt vmcnt(0)
	v_add_f32_e32 v154, v192, v210
	v_add_f32_e32 v155, v193, v211
	v_add_f32_e32 v158, v190, v208
	v_add_f32_e32 v159, v191, v209
	v_add_f32_e32 v152, v154, v152
	v_add_f32_e32 v153, v155, v153
	v_add_f32_e32 v150, v158, v150
	v_add_f32_e32 v151, v159, v151
	s_nop 0
	v_add_f32_e32 v34, v150, v151
	v_add_f32_e32 v150, v152, v153
	v_add_f32_e32 v34, v34, v150
	v_fmamk_f32 v34, v34, 0x3b000000, v169
	v_cmp_gt_f32_e32 vcc, s95, v34
	v_mul_f32_e32 v150, 0x4f800000, v34
	s_nop 0
	v_cndmask_b32_e32 v34, v34, v150, vcc
	v_sqrt_f32_e32 v150, v34
	s_nop 0
	v_add_u32_e32 v151, -1, v150
	v_fma_f32 v152, -v151, v150, v34
	v_cmp_ge_f32_e64 s[6:7], 0, v152
	v_add_u32_e32 v152, 1, v150
	s_nop 0
	v_cndmask_b32_e64 v151, v150, v151, s[6:7]
	v_fma_f32 v150, -v152, v150, v34
	v_cmp_lt_f32_e64 s[6:7], 0, v150
	s_nop 1
	v_cndmask_b32_e64 v150, v151, v152, s[6:7]
	v_mul_f32_e32 v151, 0x37800000, v150
	v_cndmask_b32_e32 v150, v150, v151, vcc
	v_cmp_class_f32_e32 vcc, v34, v173
	s_nop 1
	v_cndmask_b32_e32 v34, v150, v34, vcc
	v_div_scale_f32 v150, s[6:7], v34, v34, 1.0
	v_rcp_f32_e32 v151, v150
	s_nop 0
	v_fma_f32 v152, -v150, v151, 1.0
	v_fmac_f32_e32 v151, v152, v151
	v_div_scale_f32 v152, vcc, 1.0, v34, 1.0
	v_mul_f32_e32 v153, v152, v151
	v_fma_f32 v154, -v150, v153, v152
	v_fmac_f32_e32 v153, v154, v151
	v_fma_f32 v150, -v150, v153, v152
	v_div_fmas_f32 v150, v150, v151, v153
	v_div_fixup_f32 v200, v150, v34, 1.0
	v_add_u32_e32 v150, 0x90, v140
	v_ashrrev_i32_e32 v151, 31, v150
	v_lshlrev_b64 v[152:153], 6, v[150:151]
	v_lshl_add_u64 v[158:159], s[26:27], 0, v[152:153]
	global_load_dwordx4 v[152:155], v[158:159], off offset:32
	global_load_dwordx4 v[186:189], v[158:159], off offset:48
	global_load_dwordx4 v[190:193], v[158:159], off
	global_load_dwordx4 v[208:211], v[158:159], off offset:16
	v_mul_f32_e32 v168, 0x3f553b94, v200
	s_waitcnt vmcnt(2)
	v_add_f32_e32 v154, v154, v188
	v_add_f32_e32 v155, v155, v189
	v_add_f32_e32 v152, v152, v186
	v_add_f32_e32 v153, v153, v187
	s_waitcnt vmcnt(0)
	v_add_f32_e32 v158, v192, v210
	v_add_f32_e32 v159, v193, v211
	v_add_f32_e32 v162, v190, v208
	v_add_f32_e32 v163, v191, v209
	v_add_f32_e32 v154, v158, v154
	v_add_f32_e32 v155, v159, v155
	v_add_f32_e32 v152, v162, v152
	v_add_f32_e32 v153, v163, v153
	s_nop 0
	v_add_f32_e32 v34, v152, v153
	v_add_f32_e32 v152, v154, v155
	v_add_f32_e32 v34, v34, v152
	v_fmamk_f32 v34, v34, 0x3b000000, v169
	v_cmp_gt_f32_e32 vcc, s95, v34
	v_mul_f32_e32 v152, 0x4f800000, v34
	s_nop 0
	v_cndmask_b32_e32 v34, v34, v152, vcc
	v_sqrt_f32_e32 v152, v34
	s_nop 0
	v_add_u32_e32 v153, -1, v152
	v_fma_f32 v154, -v153, v152, v34
	v_cmp_ge_f32_e64 s[6:7], 0, v154
	v_add_u32_e32 v154, 1, v152
	s_nop 0
	v_cndmask_b32_e64 v153, v152, v153, s[6:7]
	v_fma_f32 v152, -v154, v152, v34
	v_cmp_lt_f32_e64 s[6:7], 0, v152
	s_nop 1
	v_cndmask_b32_e64 v152, v153, v154, s[6:7]
	v_mul_f32_e32 v153, 0x37800000, v152
	v_cndmask_b32_e32 v152, v152, v153, vcc
	v_cmp_class_f32_e32 vcc, v34, v173
	s_nop 1
	v_cndmask_b32_e32 v34, v152, v34, vcc
	v_div_scale_f32 v152, s[6:7], v34, v34, 1.0
	v_rcp_f32_e32 v153, v152
	s_nop 0
	v_fma_f32 v154, -v152, v153, 1.0
	v_fmac_f32_e32 v153, v154, v153
	v_div_scale_f32 v154, vcc, 1.0, v34, 1.0
	v_mul_f32_e32 v155, v154, v153
	v_fma_f32 v156, -v152, v155, v154
	v_fmac_f32_e32 v155, v156, v153
	v_fma_f32 v152, -v152, v155, v154
	v_div_fmas_f32 v152, v152, v153, v155
	v_div_fixup_f32 v201, v152, v34, 1.0
	v_add_u32_e32 v152, 0xa0, v140
	v_ashrrev_i32_e32 v153, 31, v152
	v_lshlrev_b64 v[154:155], 6, v[152:153]
	v_lshl_add_u64 v[154:155], s[26:27], 0, v[154:155]
	global_load_dwordx4 v[186:189], v[154:155], off offset:32
	global_load_dwordx4 v[190:193], v[154:155], off offset:48
	global_load_dwordx4 v[208:211], v[154:155], off
	global_load_dwordx4 v[212:215], v[154:155], off offset:16
	v_mul_f32_e32 v164, 0x3f553b94, v201
	s_waitcnt vmcnt(2)
	v_add_f32_e32 v162, v188, v192
	v_add_f32_e32 v163, v189, v193
	v_add_f32_e32 v166, v186, v190
	v_add_f32_e32 v167, v187, v191
	s_waitcnt vmcnt(0)
	v_add_f32_e32 v154, v210, v214
	v_add_f32_e32 v155, v211, v215
	v_add_f32_e32 v158, v208, v212
	v_add_f32_e32 v159, v209, v213
	v_add_f32_e32 v154, v154, v162
	v_add_f32_e32 v155, v155, v163
	v_add_f32_e32 v158, v158, v166
	v_add_f32_e32 v159, v159, v167
	v_add_f32_e32 v154, v154, v155
	v_add_f32_e32 v34, v158, v159
	v_add_f32_e32 v34, v34, v154
	v_fmamk_f32 v34, v34, 0x3b000000, v169
	v_cmp_gt_f32_e32 vcc, s95, v34
	v_mul_f32_e32 v154, 0x4f800000, v34
	s_nop 0
	v_cndmask_b32_e32 v34, v34, v154, vcc
	v_sqrt_f32_e32 v154, v34
	s_nop 0
	v_add_u32_e32 v155, -1, v154
	v_fma_f32 v156, -v155, v154, v34
	v_cmp_ge_f32_e64 s[6:7], 0, v156
	v_add_u32_e32 v156, 1, v154
	s_nop 0
	v_cndmask_b32_e64 v155, v154, v155, s[6:7]
	v_fma_f32 v154, -v156, v154, v34
	v_cmp_lt_f32_e64 s[6:7], 0, v154
	s_nop 1
	v_cndmask_b32_e64 v154, v155, v156, s[6:7]
	v_mul_f32_e32 v155, 0x37800000, v154
	v_cndmask_b32_e32 v154, v154, v155, vcc
	v_cmp_class_f32_e32 vcc, v34, v173
	s_nop 1
	v_cndmask_b32_e32 v34, v154, v34, vcc
	v_div_scale_f32 v154, s[6:7], v34, v34, 1.0
	v_rcp_f32_e32 v155, v154
	s_nop 0
	v_fma_f32 v156, -v154, v155, 1.0
	v_fmac_f32_e32 v155, v156, v155
	v_div_scale_f32 v156, vcc, 1.0, v34, 1.0
	v_mul_f32_e32 v158, v156, v155
	v_fma_f32 v159, -v154, v158, v156
	v_fmac_f32_e32 v158, v159, v155
	v_fma_f32 v154, -v154, v158, v156
	v_div_fmas_f32 v154, v154, v155, v158
	v_div_fixup_f32 v204, v154, v34, 1.0
	v_add_u32_e32 v154, 0xb0, v140
	v_ashrrev_i32_e32 v155, 31, v154
	v_lshlrev_b64 v[158:159], 6, v[154:155]
	v_lshl_add_u64 v[158:159], s[26:27], 0, v[158:159]
	global_load_dwordx4 v[186:189], v[158:159], off offset:32
	global_load_dwordx4 v[190:193], v[158:159], off offset:48
	global_load_dwordx4 v[208:211], v[158:159], off
	global_load_dwordx4 v[212:215], v[158:159], off offset:16
	s_waitcnt vmcnt(2)
	v_add_f32_e32 v166, v188, v192
	v_add_f32_e32 v167, v189, v193
	v_add_f32_e32 v170, v186, v190
	v_add_f32_e32 v171, v187, v191
	s_waitcnt vmcnt(0)
	v_add_f32_e32 v158, v210, v214
	v_add_f32_e32 v159, v211, v215
	v_add_f32_e32 v162, v208, v212
	v_add_f32_e32 v163, v209, v213
	v_add_f32_e32 v158, v158, v166
	v_add_f32_e32 v159, v159, v167
	v_add_f32_e32 v162, v162, v170
	v_add_f32_e32 v163, v163, v171
	v_add_f32_e32 v156, v158, v159
	v_add_f32_e32 v34, v162, v163
	v_add_f32_e32 v34, v34, v156
	v_fmamk_f32 v34, v34, 0x3b000000, v169
	v_cmp_gt_f32_e32 vcc, s95, v34
	v_mul_f32_e32 v156, 0x4f800000, v34
	v_lshlrev_b64 v[186:187], 7, v[140:141]
	v_cndmask_b32_e32 v34, v34, v156, vcc
	v_sqrt_f32_e32 v156, v34
	v_lshlrev_b64 v[170:171], 7, v[148:149]
	v_lshlrev_b64 v[166:167], 7, v[150:151]
	v_add_u32_e32 v158, -1, v156
	v_fma_f32 v159, -v158, v156, v34
	v_cmp_ge_f32_e64 s[6:7], 0, v159
	v_add_u32_e32 v159, 1, v156
	s_nop 0
	v_cndmask_b32_e64 v158, v156, v158, s[6:7]
	v_fma_f32 v156, -v159, v156, v34
	v_cmp_lt_f32_e64 s[6:7], 0, v156
	s_nop 1
	v_cndmask_b32_e64 v156, v158, v159, s[6:7]
	v_mul_f32_e32 v158, 0x37800000, v156
	v_cndmask_b32_e32 v156, v156, v158, vcc
	v_cmp_class_f32_e32 vcc, v34, v173
	s_nop 1
	v_cndmask_b32_e32 v34, v156, v34, vcc
	v_div_scale_f32 v156, s[6:7], v34, v34, 1.0
	v_rcp_f32_e32 v158, v156
	s_nop 0
	v_fma_f32 v159, -v156, v158, 1.0
	v_fmac_f32_e32 v158, v159, v158
	v_div_scale_f32 v159, vcc, 1.0, v34, 1.0
	v_mul_f32_e32 v160, v159, v158
	v_fma_f32 v162, -v156, v160, v159
	v_fmac_f32_e32 v160, v162, v158
	v_fma_f32 v156, -v156, v160, v159
	v_div_fmas_f32 v156, v156, v158, v160
	v_div_fixup_f32 v207, v156, v34, 1.0
	v_lshl_or_b32 v34, v199, 3, s2
	v_or_b32_e32 v208, s91, v34
	v_mul_hi_i32 v34, v208, s96
	v_lshrrev_b32_e32 v156, 31, v34
	v_lshrrev_b32_e32 v34, 5, v34
	v_add_u32_e32 v34, v34, v156
	v_mul_lo_u32 v192, v34, s28
	v_sub_u32_e32 v188, v208, v192
	v_cmp_lt_i32_e32 vcc, s29, v188
	v_ashrrev_i32_e32 v193, 31, v192
	v_mul_f32_e32 v160, 0x3f553b94, v204
	v_lshlrev_b64 v[162:163], 7, v[152:153]
	v_mul_f32_e32 v156, 0x3f553b94, v207
	v_lshlrev_b64 v[158:159], 7, v[154:155]
	s_and_saveexec_b64 s[6:7], vcc
	s_xor_b64 s[6:7], exec, s[6:7]
	s_cbranch_execz .LBB0_1598
	v_add_u32_e32 v34, 0xffffff80, v188
	v_lshrrev_b32_e32 v34, 1, v34
	v_lshlrev_b64 v[188:189], 2, v[34:35]
	v_lshl_add_u64 v[190:191], s[14:15], 0, v[188:189]
	v_lshl_add_u64 v[194:195], v[190:191], 0, v[186:187]
	global_load_dwordx4 v[210:213], v[194:195], off
	v_lshl_add_u64 v[194:195], s[12:13], 0, v[188:189]
	v_lshl_add_u64 v[188:189], v[194:195], 0, v[186:187]
	global_load_dwordx4 v[214:217], v[188:189], off
	v_mul_f32_e32 v222, v22, v184
	v_mul_f32_e32 v223, v23, v184
	v_mul_f32_e32 v218, v18, v184
	v_mul_f32_e32 v219, v19, v184
	v_mov_b32_e32 v141, v35
	v_mov_b32_e32 v143, v35
	v_mul_f32_e32 v220, v24, v184
	v_mul_f32_e32 v221, v25, v184
	v_lshl_add_u64 v[188:189], v[192:193], 1, s[22:23]
	v_mul_f32_e32 v192, v20, v184
	v_mul_f32_e32 v193, v21, v184
	v_mad_i64_i32 v[224:225], s[24:25], v140, s0, v[188:189]
	s_waitcnt vmcnt(1)
	v_mul_f32_e32 v228, v222, v210
	v_mul_f32_e32 v229, v223, v211
	v_mul_f32_e32 v210, v218, v210
	v_mul_f32_e32 v211, v219, v211
	v_mul_f32_e32 v226, v220, v212
	v_mul_f32_e32 v227, v221, v213
	s_waitcnt vmcnt(0)
	v_fma_f32 v218, v218, v214, -v228
	v_fma_f32 v219, v219, v215, -v229
	v_fmac_f32_e32 v210, v222, v214
	v_fmac_f32_e32 v211, v223, v215
	v_cvt_pk_fp8_f32 v141, v218, v219
	v_cvt_pk_fp8_f32 v143, v210, v211
	v_mul_f32_e32 v212, v192, v212
	v_mul_f32_e32 v213, v193, v213
	v_fma_f32 v192, v192, v216, -v226
	v_fma_f32 v193, v193, v217, -v227
	v_fma_f32 v210, v220, v216, v212
	v_fma_f32 v211, v221, v217, v213
	v_cvt_pk_fp8_f32 v141, v192, v193 op_sel:[0,0,1]
	v_cvt_pk_fp8_f32 v143, v210, v211 op_sel:[0,0,1]
	v_lshl_add_u64 v[192:193], v[224:225], 0, v[34:35]
	v_lshl_add_u64 v[210:211], v[190:191], 0, v[182:183]
	global_store_dword v[192:193], v141, off offset:256
	global_store_dword v[192:193], v143, off offset:288
	global_load_dwordx4 v[210:213], v[210:211], off
	v_lshl_add_u64 v[192:193], v[194:195], 0, v[182:183]
	global_load_dwordx4 v[214:217], v[192:193], off
	v_mul_f32_e32 v222, v30, v180
	v_mul_f32_e32 v223, v31, v180
	v_mul_f32_e32 v218, v26, v180
	v_mul_f32_e32 v219, v27, v180
	v_mov_b32_e32 v141, v35
	v_mov_b32_e32 v143, v35
	v_mul_f32_e32 v220, v32, v180
	v_mul_f32_e32 v221, v33, v180
	v_mul_f32_e32 v192, v28, v180
	v_mul_f32_e32 v193, v29, v180
	v_mad_i64_i32 v[224:225], s[24:25], v142, s0, v[188:189]
	s_waitcnt vmcnt(1)
	v_mul_f32_e32 v228, v222, v210
	v_mul_f32_e32 v229, v223, v211
	v_mul_f32_e32 v210, v218, v210
	v_mul_f32_e32 v211, v219, v211
	s_waitcnt vmcnt(0)
	v_fma_f32 v218, v218, v214, -v228
	v_fma_f32 v219, v219, v215, -v229
	v_fmac_f32_e32 v210, v222, v214
	v_fmac_f32_e32 v211, v223, v215
	v_cvt_pk_fp8_f32 v141, v218, v219
	v_cvt_pk_fp8_f32 v143, v210, v211
	v_mul_f32_e32 v226, v220, v212
	v_mul_f32_e32 v227, v221, v213
	v_mul_f32_e32 v212, v192, v212
	v_mul_f32_e32 v213, v193, v213
	v_fma_f32 v192, v192, v216, -v226
	v_fma_f32 v193, v193, v217, -v227
	v_fma_f32 v210, v220, v216, v212
	v_fma_f32 v211, v221, v217, v213
	v_cvt_pk_fp8_f32 v141, v192, v193 op_sel:[0,0,1]
	v_cvt_pk_fp8_f32 v143, v210, v211 op_sel:[0,0,1]
	v_lshl_add_u64 v[192:193], v[224:225], 0, v[34:35]
	v_lshl_add_u64 v[210:211], v[190:191], 0, v[178:179]
	global_store_dword v[192:193], v141, off offset:256
	global_store_dword v[192:193], v143, off offset:288
	global_load_dwordx4 v[210:213], v[210:211], off
	v_lshl_add_u64 v[192:193], v[194:195], 0, v[178:179]
	global_load_dwordx4 v[214:217], v[192:193], off
	v_mul_f32_e32 v222, v6, v176
	v_mul_f32_e32 v223, v7, v176
	v_mul_f32_e32 v218, v2, v176
	v_mul_f32_e32 v219, v3, v176
	v_mov_b32_e32 v141, v35
	v_mov_b32_e32 v143, v35
	v_mul_f32_e32 v220, v8, v176
	v_mul_f32_e32 v221, v9, v176
	v_mul_f32_e32 v192, v4, v176
	v_mul_f32_e32 v193, v5, v176
	v_mad_i64_i32 v[224:225], s[24:25], v144, s0, v[188:189]
	s_waitcnt vmcnt(1)
	v_mul_f32_e32 v228, v222, v210
	v_mul_f32_e32 v229, v223, v211
	v_mul_f32_e32 v210, v218, v210
	v_mul_f32_e32 v211, v219, v211
	s_waitcnt vmcnt(0)
	v_fma_f32 v218, v218, v214, -v228
	v_fma_f32 v219, v219, v215, -v229
	v_fmac_f32_e32 v210, v222, v214
	v_fmac_f32_e32 v211, v223, v215
	v_cvt_pk_fp8_f32 v141, v218, v219
	v_cvt_pk_fp8_f32 v143, v210, v211
	v_mul_f32_e32 v226, v220, v212
	v_mul_f32_e32 v227, v221, v213
	v_mul_f32_e32 v212, v192, v212
	v_mul_f32_e32 v213, v193, v213
	v_fma_f32 v192, v192, v216, -v226
	v_fma_f32 v193, v193, v217, -v227
	v_fma_f32 v210, v220, v216, v212
	v_fma_f32 v211, v221, v217, v213
	v_cvt_pk_fp8_f32 v141, v192, v193 op_sel:[0,0,1]
	v_cvt_pk_fp8_f32 v143, v210, v211 op_sel:[0,0,1]
	v_lshl_add_u64 v[192:193], v[224:225], 0, v[34:35]
	v_lshl_add_u64 v[210:211], v[190:191], 0, v[174:175]
	global_store_dword v[192:193], v141, off offset:256
	global_store_dword v[192:193], v143, off offset:288
	global_load_dwordx4 v[210:213], v[210:211], off
	v_lshl_add_u64 v[192:193], v[194:195], 0, v[174:175]
	global_load_dwordx4 v[214:217], v[192:193], off
	v_mul_f32_e32 v222, v14, v172
	v_mul_f32_e32 v223, v15, v172
	v_mul_f32_e32 v218, v10, v172
	v_mul_f32_e32 v219, v11, v172
	v_mov_b32_e32 v141, v35
	v_mov_b32_e32 v143, v35
	v_mul_f32_e32 v220, v16, v172
	v_mul_f32_e32 v221, v17, v172
	v_mul_f32_e32 v192, v12, v172
	v_mul_f32_e32 v193, v13, v172
	v_mad_i64_i32 v[224:225], s[24:25], v146, s0, v[188:189]
	s_waitcnt vmcnt(1)
	v_mul_f32_e32 v228, v222, v210
	v_mul_f32_e32 v229, v223, v211
	v_mul_f32_e32 v210, v218, v210
	v_mul_f32_e32 v211, v219, v211
	s_waitcnt vmcnt(0)
	v_fma_f32 v218, v218, v214, -v228
	v_fma_f32 v219, v219, v215, -v229
	v_fmac_f32_e32 v210, v222, v214
	v_fmac_f32_e32 v211, v223, v215
	v_cvt_pk_fp8_f32 v141, v218, v219
	v_cvt_pk_fp8_f32 v143, v210, v211
	v_mul_f32_e32 v226, v220, v212
	v_mul_f32_e32 v227, v221, v213
	v_mul_f32_e32 v212, v192, v212
	v_mul_f32_e32 v213, v193, v213
	v_fma_f32 v192, v192, v216, -v226
	v_fma_f32 v193, v193, v217, -v227
	v_fma_f32 v210, v220, v216, v212
	v_fma_f32 v211, v221, v217, v213
	v_cvt_pk_fp8_f32 v141, v192, v193 op_sel:[0,0,1]
	v_cvt_pk_fp8_f32 v143, v210, v211 op_sel:[0,0,1]
	v_lshl_add_u64 v[192:193], v[224:225], 0, v[34:35]
	v_lshl_add_u64 v[210:211], v[190:191], 0, v[170:171]
	global_store_dword v[192:193], v141, off offset:256
	global_store_dword v[192:193], v143, off offset:288
	global_load_dwordx4 v[210:213], v[210:211], off
	v_lshl_add_u64 v[192:193], v[194:195], 0, v[170:171]
	global_load_dwordx4 v[214:217], v[192:193], off
	v_mul_f32_e32 v222, v120, v168
	v_mul_f32_e32 v223, v121, v168
	v_mul_f32_e32 v218, v116, v168
	v_mul_f32_e32 v219, v117, v168
	v_mov_b32_e32 v141, v35
	v_mov_b32_e32 v143, v35
	v_mul_f32_e32 v220, v122, v168
	v_mul_f32_e32 v221, v123, v168
	v_mul_f32_e32 v192, v118, v168
	v_mul_f32_e32 v193, v119, v168
	v_mad_i64_i32 v[224:225], s[24:25], v148, s0, v[188:189]
	s_waitcnt vmcnt(1)
	v_mul_f32_e32 v228, v222, v210
	v_mul_f32_e32 v229, v223, v211
	v_mul_f32_e32 v210, v218, v210
	v_mul_f32_e32 v211, v219, v211
	s_waitcnt vmcnt(0)
	v_fma_f32 v218, v218, v214, -v228
	v_fma_f32 v219, v219, v215, -v229
	v_fmac_f32_e32 v210, v222, v214
	v_fmac_f32_e32 v211, v223, v215
	v_cvt_pk_fp8_f32 v141, v218, v219
	v_cvt_pk_fp8_f32 v143, v210, v211
	v_mul_f32_e32 v226, v220, v212
	v_mul_f32_e32 v227, v221, v213
	v_mul_f32_e32 v212, v192, v212
	v_mul_f32_e32 v213, v193, v213
	v_fma_f32 v192, v192, v216, -v226
	v_fma_f32 v193, v193, v217, -v227
	v_fma_f32 v210, v220, v216, v212
	v_fma_f32 v211, v221, v217, v213
	v_cvt_pk_fp8_f32 v141, v192, v193 op_sel:[0,0,1]
	v_cvt_pk_fp8_f32 v143, v210, v211 op_sel:[0,0,1]
	v_lshl_add_u64 v[192:193], v[224:225], 0, v[34:35]
	v_lshl_add_u64 v[210:211], v[190:191], 0, v[166:167]
	global_store_dword v[192:193], v141, off offset:256
	global_store_dword v[192:193], v143, off offset:288
	global_load_dwordx4 v[210:213], v[210:211], off
	v_lshl_add_u64 v[192:193], v[194:195], 0, v[166:167]
	global_load_dwordx4 v[214:217], v[192:193], off
	v_mul_f32_e32 v222, v128, v164
	v_mul_f32_e32 v223, v129, v164
	v_mul_f32_e32 v218, v124, v164
	v_mul_f32_e32 v219, v125, v164
	v_mov_b32_e32 v141, v35
	v_mov_b32_e32 v143, v35
	v_mul_f32_e32 v220, v130, v164
	v_mul_f32_e32 v221, v131, v164
	v_mul_f32_e32 v192, v126, v164
	v_mul_f32_e32 v193, v127, v164
	v_mad_i64_i32 v[224:225], s[24:25], v150, s0, v[188:189]
	s_waitcnt vmcnt(1)
	v_mul_f32_e32 v228, v222, v210
	v_mul_f32_e32 v229, v223, v211
	v_mul_f32_e32 v210, v218, v210
	v_mul_f32_e32 v211, v219, v211
	s_waitcnt vmcnt(0)
	v_fma_f32 v218, v218, v214, -v228
	v_fma_f32 v219, v219, v215, -v229
	v_fmac_f32_e32 v210, v222, v214
	v_fmac_f32_e32 v211, v223, v215
	v_cvt_pk_fp8_f32 v141, v218, v219
	v_cvt_pk_fp8_f32 v143, v210, v211
	v_mul_f32_e32 v226, v220, v212
	v_mul_f32_e32 v227, v221, v213
	v_mul_f32_e32 v212, v192, v212
	v_mul_f32_e32 v213, v193, v213
	v_fma_f32 v192, v192, v216, -v226
	v_fma_f32 v193, v193, v217, -v227
	v_fma_f32 v210, v220, v216, v212
	v_fma_f32 v211, v221, v217, v213
	v_cvt_pk_fp8_f32 v141, v192, v193 op_sel:[0,0,1]
	v_cvt_pk_fp8_f32 v143, v210, v211 op_sel:[0,0,1]
	v_lshl_add_u64 v[192:193], v[224:225], 0, v[34:35]
	v_lshl_add_u64 v[210:211], v[190:191], 0, v[162:163]
	global_store_dword v[192:193], v141, off offset:256
	global_store_dword v[192:193], v143, off offset:288
	global_load_dwordx4 v[210:213], v[210:211], off
	v_lshl_add_u64 v[192:193], v[194:195], 0, v[162:163]
	global_load_dwordx4 v[214:217], v[192:193], off
	v_mul_f32_e32 v222, v104, v160
	v_mul_f32_e32 v223, v105, v160
	v_mul_f32_e32 v218, v100, v160
	v_mul_f32_e32 v219, v101, v160
	v_mov_b32_e32 v141, v35
	v_mov_b32_e32 v143, v35
	v_mul_f32_e32 v220, v106, v160
	v_mul_f32_e32 v221, v107, v160
	v_mul_f32_e32 v192, v102, v160
	v_mul_f32_e32 v193, v103, v160
	v_mad_i64_i32 v[224:225], s[24:25], v152, s0, v[188:189]
	v_lshl_add_u64 v[190:191], v[190:191], 0, v[158:159]
	v_lshl_add_u64 v[194:195], v[194:195], 0, v[158:159]
	v_mad_i64_i32 v[188:189], s[24:25], v154, s0, v[188:189]
	v_lshl_add_u64 v[188:189], v[188:189], 0, v[34:35]
	s_waitcnt vmcnt(1)
	v_mul_f32_e32 v228, v222, v210
	v_mul_f32_e32 v229, v223, v211
	v_mul_f32_e32 v210, v218, v210
	v_mul_f32_e32 v211, v219, v211
	s_waitcnt vmcnt(0)
	v_fma_f32 v218, v218, v214, -v228
	v_fma_f32 v219, v219, v215, -v229
	v_fmac_f32_e32 v210, v222, v214
	v_fmac_f32_e32 v211, v223, v215
	v_cvt_pk_fp8_f32 v141, v218, v219
	v_cvt_pk_fp8_f32 v143, v210, v211
	v_mul_f32_e32 v226, v220, v212
	v_mul_f32_e32 v227, v221, v213
	v_mul_f32_e32 v212, v192, v212
	v_mul_f32_e32 v213, v193, v213
	v_fma_f32 v192, v192, v216, -v226
	v_fma_f32 v193, v193, v217, -v227
	v_fma_f32 v210, v220, v216, v212
	v_fma_f32 v211, v221, v217, v213
	v_cvt_pk_fp8_f32 v141, v192, v193 op_sel:[0,0,1]
	v_cvt_pk_fp8_f32 v143, v210, v211 op_sel:[0,0,1]
	v_lshl_add_u64 v[192:193], v[224:225], 0, v[34:35]
	global_store_dword v[192:193], v141, off offset:256
	global_store_dword v[192:193], v143, off offset:288
	global_load_dwordx4 v[190:193], v[190:191], off
	v_mul_f32_e32 v218, v112, v156
	v_mul_f32_e32 v219, v113, v156
	global_load_dwordx4 v[210:213], v[194:195], off
	v_mul_f32_e32 v214, v108, v156
	v_mul_f32_e32 v215, v109, v156
	v_mov_b32_e32 v141, v35
	v_mov_b32_e32 v143, v35
	v_mul_f32_e32 v216, v114, v156
	v_mul_f32_e32 v217, v115, v156
	v_mul_f32_e32 v194, v110, v156
	v_mul_f32_e32 v195, v111, v156
	s_waitcnt vmcnt(1)
	v_mul_f32_e32 v222, v218, v190
	v_mul_f32_e32 v223, v219, v191
	v_mul_f32_e32 v190, v214, v190
	v_mul_f32_e32 v191, v215, v191
	s_waitcnt vmcnt(0)
	v_fma_f32 v214, v214, v210, -v222
	v_fma_f32 v215, v215, v211, -v223
	v_fmac_f32_e32 v190, v218, v210
	v_fmac_f32_e32 v191, v219, v211
	v_cvt_pk_fp8_f32 v141, v214, v215
	v_cvt_pk_fp8_f32 v143, v190, v191
	v_mul_f32_e32 v220, v216, v192
	v_mul_f32_e32 v221, v217, v193
	v_mul_f32_e32 v192, v194, v192
	v_mul_f32_e32 v193, v195, v193
	v_fma_f32 v190, v194, v212, -v220
	v_fma_f32 v191, v195, v213, -v221
	v_fmac_f32_e32 v192, v216, v212
	v_fmac_f32_e32 v193, v217, v213
	v_cvt_pk_fp8_f32 v141, v190, v191 op_sel:[0,0,1]
	v_cvt_pk_fp8_f32 v143, v192, v193 op_sel:[0,0,1]
	global_store_dword v[188:189], v141, off offset:256
	global_store_dword v[188:189], v143, off offset:288

.LBB0_1607:
	s_or_b64 exec, exec, s[4:5]
	v_mul_f32_e32 v194, 0x3dd53b94, v139
	v_mul_f32_e32 v18, v194, v18
	v_mul_f32_e32 v19, v194, v19
	v_mul_f32_e32 v2, v194, v2
	v_mul_f32_e32 v3, v194, v3
	v_mul_f32_e32 v20, v194, v20
	v_mul_f32_e32 v21, v194, v21
	v_mul_f32_e32 v4, v194, v4
	v_mul_f32_e32 v5, v194, v5
	v_max_f32_e64 v139, |v18|, |v2|
	v_max_f32_e64 v143, |v19|, |v3|
	v_mul_f32_e32 v22, v194, v22
	v_mul_f32_e32 v23, v194, v23
	v_mul_f32_e32 v6, v194, v6
	v_mul_f32_e32 v7, v194, v7
	v_max3_f32 v139, v139, 0, v143
	v_max_f32_e64 v143, |v20|, |v4|
	v_max_f32_e64 v145, |v21|, |v5|
	v_mul_f32_e32 v24, v194, v24
	v_mul_f32_e32 v25, v194, v25
	v_mul_f32_e32 v8, v194, v8
	v_mul_f32_e32 v9, v194, v9
	v_max3_f32 v139, v139, v143, v145
	v_max_f32_e64 v143, |v22|, |v6|
	v_max_f32_e64 v145, |v23|, |v7|
	v_mul_f32_e32 v26, v194, v26
	v_mul_f32_e32 v27, v194, v27
	v_mul_f32_e32 v10, v194, v10
	v_mul_f32_e32 v11, v194, v11
	v_max3_f32 v139, v139, v143, v145
	v_max_f32_e64 v143, |v24|, |v8|
	v_max_f32_e64 v145, |v25|, |v9|
	v_mul_f32_e32 v28, v194, v28
	v_mul_f32_e32 v29, v194, v29
	v_mul_f32_e32 v12, v194, v12
	v_mul_f32_e32 v13, v194, v13
	v_max3_f32 v139, v139, v143, v145
	v_max_f32_e64 v143, |v26|, |v10|
	v_max_f32_e64 v145, |v27|, |v11|
	v_mul_f32_e32 v30, v194, v30
	v_mul_f32_e32 v31, v194, v31
	v_mul_f32_e32 v14, v194, v14
	v_mul_f32_e32 v15, v194, v15
	v_max3_f32 v139, v139, v143, v145
	v_max_f32_e64 v143, |v28|, |v12|
	v_max_f32_e64 v145, |v29|, |v13|
	v_mul_f32_e32 v32, v194, v32
	v_mul_f32_e32 v33, v194, v33
	v_mul_f32_e32 v16, v194, v16
	v_mul_f32_e32 v17, v194, v17
	v_max3_f32 v139, v139, v143, v145
	v_max_f32_e64 v143, |v30|, |v14|
	v_max_f32_e64 v145, |v31|, |v15|
	v_max3_f32 v139, v139, v143, v145
	v_max_f32_e64 v143, |v32|, |v16|
	v_max_f32_e64 v145, |v33|, |v17|
	v_max3_f32 v139, v139, v143, v145
	v_cmp_gt_u32_e32 vcc, 64, v188
	v_bfe_u32 v143, v139, 23, 8
	v_and_b32_e32 v139, 0x7fffff, v139
	v_cndmask_b32_e32 v34, v177, v181, vcc
	v_cndmask_b32_e64 v190, 64, 0, vcc
	v_cmp_gt_u32_e32 vcc, s1, v139
	v_mov_b64_e32 v[194:195], s[22:23]
	v_mad_i64_i32 v[194:195], s[4:5], v141, s0, v[194:195]
	v_cndmask_b32_e64 v139, -2, -3, vcc
	v_add3_u32 v139, v143, v139, s97
	v_max_i32_e32 v139, 0xffffff88, v139
	v_add_u32_e32 v139, 0x7f, v139
	v_lshl_add_u64 v[194:195], v[192:193], 1, v[194:195]
	v_and_b32_e32 v188, 32, v188
	v_mov_b32_e32 v189, v35
	v_lshlrev_b32_e32 v196, 23, v139
	v_lshl_add_u64 v[218:219], v[194:195], 0, v[34:35]
	v_cvt_scalef32_2xpk16_fp6_f32 v[210:215], v[18:33], v[2:17], v196
	v_sub_u32_e32 v198, 0x7f000000, v196
	v_lshl_add_u64 v[218:219], v[218:219], 0, v[188:189]
	global_store_dwordx4 v[218:219], v[210:213], off
	v_mul_lo_u32 v216, v139, s3
	v_mov_b32_e32 v217, v35
	v_mul_f32_e32 v210, v18, v198
	v_mul_f32_e32 v211, v19, v198
	v_mul_f32_e32 v212, v2, v198
	v_mul_f32_e32 v213, v3, v198
	v_cmp_lt_f32_e64 vcc, |v210|, 4.0
	v_and_b32_e32 v139, 0x7fffffff, v210
	global_store_dwordx4 v[218:219], v[214:217], off offset:16
	v_cndmask_b32_e32 v143, 0.5, v185, vcc
	v_cmp_nlt_f32_e64 vcc, |v210|, 2.0
	v_mul_f32_e32 v214, v20, v198
	v_mul_f32_e32 v215, v21, v198
	v_mov_b32_e32 v191, v35
	v_cndmask_b32_e32 v143, v197, v143, vcc
	v_permlane32_swap_b32_e32 v116, v100
	v_cmp_lt_f32_e64 vcc, |v211|, 4.0
	v_and_b32_e32 v145, 0x7fffffff, v211
	v_sub_u32_e32 v147, 0x7f000000, v143
	v_mul_f32_e64 v139, |v210|, v147
	v_cndmask_b32_e32 v147, 0.5, v185, vcc
	v_cmp_nlt_f32_e64 vcc, |v211|, 2.0
	v_rndne_f32_e32 v139, v139
	v_mul_f32_e32 v139, v143, v139
	v_cndmask_b32_e32 v147, v197, v147, vcc
	v_min_f32_e32 v139, 0x40f00000, v139
	v_bfi_b32 v210, s10, v139, v210
	v_permlane32_swap_b32_e32 v117, v101
	v_sub_u32_e32 v145, 0x7f000000, v147
	v_mul_f32_e64 v143, |v211|, v145
	v_rndne_f32_e32 v143, v143
	v_mul_f32_e32 v143, v147, v143
	v_cmp_lt_f32_e64 vcc, |v212|, 4.0
	v_min_f32_e32 v143, 0x40f00000, v143
	v_bfi_b32 v211, s10, v143, v211
	v_cndmask_b32_e32 v145, 0.5, v185, vcc
	v_cmp_nlt_f32_e64 vcc, |v212|, 2.0
	v_and_b32_e32 v143, 0x7fffffff, v212
	v_mul_f32_e32 v210, v210, v196
	v_mul_f32_e32 v211, v211, v196
	v_cndmask_b32_e32 v145, v197, v145, vcc
	v_fma_f32 v18, v18, 2.0, -v210
	v_fma_f32 v19, v19, 2.0, -v211
	v_permlane32_swap_b32_e32 v118, v102
	v_cmp_lt_f32_e64 vcc, |v213|, 4.0
	v_and_b32_e32 v143, 0x7fffffff, v213
	v_sub_u32_e32 v147, 0x7f000000, v145
	v_mul_f32_e64 v139, |v212|, v147
	v_cndmask_b32_e32 v147, 0.5, v185, vcc
	v_cmp_nlt_f32_e64 vcc, |v213|, 2.0
	v_rndne_f32_e32 v139, v139
	v_mul_f32_e32 v139, v145, v139
	v_cndmask_b32_e32 v147, v197, v147, vcc
	v_min_f32_e32 v139, 0x40f00000, v139
	v_sub_u32_e32 v145, 0x7f000000, v147
	v_mul_f32_e64 v143, |v213|, v145
	v_rndne_f32_e32 v143, v143
	v_mul_f32_e32 v143, v147, v143
	v_cmp_lt_f32_e64 vcc, |v214|, 4.0
	v_min_f32_e32 v143, 0x40f00000, v143
	v_bfi_b32 v211, s10, v143, v213
	v_cndmask_b32_e32 v145, 0.5, v185, vcc
	v_cmp_nlt_f32_e64 vcc, |v214|, 2.0
	v_and_b32_e32 v143, 0x7fffffff, v214
	v_bfi_b32 v210, s10, v139, v212
	v_cndmask_b32_e32 v145, v197, v145, vcc
	v_mul_f32_e32 v212, v4, v198
	v_mul_f32_e32 v213, v5, v198
	v_mul_f32_e32 v210, v210, v196
	v_mul_f32_e32 v211, v211, v196
	v_permlane32_swap_b32_e32 v119, v103
	v_cmp_lt_f32_e64 vcc, |v215|, 4.0
	v_and_b32_e32 v143, 0x7fffffff, v215
	v_sub_u32_e32 v147, 0x7f000000, v145
	v_mul_f32_e64 v139, |v214|, v147
	v_cndmask_b32_e32 v147, 0.5, v185, vcc
	v_cmp_nlt_f32_e64 vcc, |v215|, 2.0
	v_rndne_f32_e32 v139, v139
	v_mul_f32_e32 v139, v145, v139
	v_cndmask_b32_e32 v147, v197, v147, vcc
	v_fma_f32 v2, v2, 2.0, -v210
	v_fma_f32 v3, v3, 2.0, -v211
	v_sub_u32_e32 v145, 0x7f000000, v147
	v_mul_f32_e64 v143, |v215|, v145
	v_rndne_f32_e32 v143, v143
	v_mul_f32_e32 v143, v147, v143
	v_cmp_lt_f32_e64 vcc, |v212|, 4.0
	v_min_f32_e32 v143, 0x40f00000, v143
	v_bfi_b32 v211, s10, v143, v215
	v_cndmask_b32_e32 v145, 0.5, v185, vcc
	v_cmp_nlt_f32_e64 vcc, |v212|, 2.0
	v_and_b32_e32 v143, 0x7fffffff, v212
	v_min_f32_e32 v139, 0x40f00000, v139
	v_cndmask_b32_e32 v145, v197, v145, vcc
	v_bfi_b32 v210, s10, v139, v214
	v_mul_f32_e32 v214, v22, v198
	v_mul_f32_e32 v215, v23, v198
	v_mul_f32_e32 v210, v210, v196
	v_mul_f32_e32 v211, v211, v196
	v_cmp_lt_f32_e64 vcc, |v213|, 4.0
	v_and_b32_e32 v143, 0x7fffffff, v213
	v_sub_u32_e32 v147, 0x7f000000, v145
	v_mul_f32_e64 v139, |v212|, v147
	v_cndmask_b32_e32 v147, 0.5, v185, vcc
	v_cmp_nlt_f32_e64 vcc, |v213|, 2.0
	v_rndne_f32_e32 v139, v139
	v_mul_f32_e32 v139, v145, v139
	v_cndmask_b32_e32 v147, v197, v147, vcc
	v_fma_f32 v20, v20, 2.0, -v210
	v_fma_f32 v21, v21, 2.0, -v211
	v_sub_u32_e32 v145, 0x7f000000, v147
	v_mul_f32_e64 v143, |v213|, v145
	v_rndne_f32_e32 v143, v143
	v_mul_f32_e32 v143, v147, v143
	v_cmp_lt_f32_e64 vcc, |v214|, 4.0
	v_min_f32_e32 v143, 0x40f00000, v143
	v_bfi_b32 v211, s10, v143, v213
	v_cndmask_b32_e32 v145, 0.5, v185, vcc
	v_cmp_nlt_f32_e64 vcc, |v214|, 2.0
	v_and_b32_e32 v143, 0x7fffffff, v214
	v_min_f32_e32 v139, 0x40f00000, v139
	v_cndmask_b32_e32 v145, v197, v145, vcc
	v_bfi_b32 v210, s10, v139, v212
	v_mul_f32_e32 v212, v6, v198
	v_mul_f32_e32 v213, v7, v198
	v_mul_f32_e32 v210, v210, v196
	v_mul_f32_e32 v211, v211, v196
	v_cmp_lt_f32_e64 vcc, |v215|, 4.0
	v_and_b32_e32 v143, 0x7fffffff, v215
	v_sub_u32_e32 v147, 0x7f000000, v145
	v_mul_f32_e64 v139, |v214|, v147
	v_cndmask_b32_e32 v147, 0.5, v185, vcc
	v_cmp_nlt_f32_e64 vcc, |v215|, 2.0
	v_rndne_f32_e32 v139, v139
	v_mul_f32_e32 v139, v145, v139
	v_cndmask_b32_e32 v147, v197, v147, vcc
	v_fma_f32 v4, v4, 2.0, -v210
	v_fma_f32 v5, v5, 2.0, -v211
	v_sub_u32_e32 v145, 0x7f000000, v147
	v_mul_f32_e64 v143, |v215|, v145
	v_rndne_f32_e32 v143, v143
	v_mul_f32_e32 v143, v147, v143
	v_cmp_lt_f32_e64 vcc, |v212|, 4.0
	v_min_f32_e32 v143, 0x40f00000, v143
	v_bfi_b32 v211, s10, v143, v215
	v_cndmask_b32_e32 v145, 0.5, v185, vcc
	v_cmp_nlt_f32_e64 vcc, |v212|, 2.0
	v_and_b32_e32 v143, 0x7fffffff, v212
	v_min_f32_e32 v139, 0x40f00000, v139
	v_cndmask_b32_e32 v145, v197, v145, vcc
	v_bfi_b32 v210, s10, v139, v214
	v_mul_f32_e32 v214, v24, v198
	v_mul_f32_e32 v215, v25, v198
	v_mul_f32_e32 v210, v210, v196
	v_mul_f32_e32 v211, v211, v196
	v_cmp_lt_f32_e64 vcc, |v213|, 4.0
	v_and_b32_e32 v143, 0x7fffffff, v213
	v_sub_u32_e32 v147, 0x7f000000, v145
	v_mul_f32_e64 v139, |v212|, v147
	v_cndmask_b32_e32 v147, 0.5, v185, vcc
	v_cmp_nlt_f32_e64 vcc, |v213|, 2.0
	v_rndne_f32_e32 v139, v139
	v_mul_f32_e32 v139, v145, v139
	v_cndmask_b32_e32 v147, v197, v147, vcc
	v_fma_f32 v22, v22, 2.0, -v210
	v_fma_f32 v23, v23, 2.0, -v211
	v_sub_u32_e32 v145, 0x7f000000, v147
	v_mul_f32_e64 v143, |v213|, v145
	v_rndne_f32_e32 v143, v143
	v_mul_f32_e32 v143, v147, v143
	v_cmp_lt_f32_e64 vcc, |v214|, 4.0
	v_min_f32_e32 v143, 0x40f00000, v143
	v_bfi_b32 v211, s10, v143, v213
	v_cndmask_b32_e32 v145, 0.5, v185, vcc
	v_cmp_nlt_f32_e64 vcc, |v214|, 2.0
	v_and_b32_e32 v143, 0x7fffffff, v214
	v_min_f32_e32 v139, 0x40f00000, v139
	v_cndmask_b32_e32 v145, v197, v145, vcc
	v_bfi_b32 v210, s10, v139, v212
	v_mul_f32_e32 v212, v8, v198
	v_mul_f32_e32 v213, v9, v198
	v_mul_f32_e32 v210, v210, v196
	v_mul_f32_e32 v211, v211, v196
	v_cmp_lt_f32_e64 vcc, |v215|, 4.0
	v_and_b32_e32 v143, 0x7fffffff, v215
	v_sub_u32_e32 v147, 0x7f000000, v145
	v_mul_f32_e64 v139, |v214|, v147
	v_cndmask_b32_e32 v147, 0.5, v185, vcc
	v_cmp_nlt_f32_e64 vcc, |v215|, 2.0
	v_rndne_f32_e32 v139, v139
	v_mul_f32_e32 v139, v145, v139
	v_cndmask_b32_e32 v147, v197, v147, vcc
	v_fma_f32 v6, v6, 2.0, -v210
	v_fma_f32 v7, v7, 2.0, -v211
	v_sub_u32_e32 v145, 0x7f000000, v147
	v_mul_f32_e64 v143, |v215|, v145
	v_rndne_f32_e32 v143, v143
	v_mul_f32_e32 v143, v147, v143
	v_cmp_lt_f32_e64 vcc, |v212|, 4.0
	v_min_f32_e32 v143, 0x40f00000, v143
	v_bfi_b32 v211, s10, v143, v215
	v_cndmask_b32_e32 v145, 0.5, v185, vcc
	v_cmp_nlt_f32_e64 vcc, |v212|, 2.0
	v_and_b32_e32 v143, 0x7fffffff, v212
	v_min_f32_e32 v139, 0x40f00000, v139
	v_cndmask_b32_e32 v145, v197, v145, vcc
	v_bfi_b32 v210, s10, v139, v214
	v_mul_f32_e32 v214, v26, v198
	v_mul_f32_e32 v215, v27, v198
	v_mul_f32_e32 v210, v210, v196
	v_mul_f32_e32 v211, v211, v196
	v_cmp_lt_f32_e64 vcc, |v213|, 4.0
	v_and_b32_e32 v143, 0x7fffffff, v213
	v_sub_u32_e32 v147, 0x7f000000, v145
	v_mul_f32_e64 v139, |v212|, v147
	v_cndmask_b32_e32 v147, 0.5, v185, vcc
	v_cmp_nlt_f32_e64 vcc, |v213|, 2.0
	v_rndne_f32_e32 v139, v139
	v_mul_f32_e32 v139, v145, v139
	v_cndmask_b32_e32 v147, v197, v147, vcc
	v_fma_f32 v24, v24, 2.0, -v210
	v_fma_f32 v25, v25, 2.0, -v211
	v_sub_u32_e32 v145, 0x7f000000, v147
	v_mul_f32_e64 v143, |v213|, v145
	v_rndne_f32_e32 v143, v143
	v_mul_f32_e32 v143, v147, v143
	v_cmp_lt_f32_e64 vcc, |v214|, 4.0
	v_min_f32_e32 v143, 0x40f00000, v143
	v_bfi_b32 v211, s10, v143, v213
	v_cndmask_b32_e32 v145, 0.5, v185, vcc
	v_cmp_nlt_f32_e64 vcc, |v214|, 2.0
	v_and_b32_e32 v143, 0x7fffffff, v214
	v_min_f32_e32 v139, 0x40f00000, v139
	v_cndmask_b32_e32 v145, v197, v145, vcc
	v_bfi_b32 v210, s10, v139, v212
	v_mul_f32_e32 v212, v10, v198
	v_mul_f32_e32 v213, v11, v198
	v_mul_f32_e32 v210, v210, v196
	v_mul_f32_e32 v211, v211, v196
	v_cmp_lt_f32_e64 vcc, |v215|, 4.0
	v_and_b32_e32 v143, 0x7fffffff, v215
	v_sub_u32_e32 v147, 0x7f000000, v145
	v_mul_f32_e64 v139, |v214|, v147
	v_cndmask_b32_e32 v147, 0.5, v185, vcc
	v_cmp_nlt_f32_e64 vcc, |v215|, 2.0
	v_rndne_f32_e32 v139, v139
	v_mul_f32_e32 v139, v145, v139
	v_cndmask_b32_e32 v147, v197, v147, vcc
	v_fma_f32 v8, v8, 2.0, -v210
	v_fma_f32 v9, v9, 2.0, -v211
	v_sub_u32_e32 v145, 0x7f000000, v147
	v_mul_f32_e64 v143, |v215|, v145
	v_rndne_f32_e32 v143, v143
	v_mul_f32_e32 v143, v147, v143
	v_cmp_lt_f32_e64 vcc, |v212|, 4.0
	v_min_f32_e32 v143, 0x40f00000, v143
	v_bfi_b32 v211, s10, v143, v215
	v_cndmask_b32_e32 v145, 0.5, v185, vcc
	v_cmp_nlt_f32_e64 vcc, |v212|, 2.0
	v_and_b32_e32 v143, 0x7fffffff, v212
	v_min_f32_e32 v139, 0x40f00000, v139
	v_cndmask_b32_e32 v145, v197, v145, vcc
	v_bfi_b32 v210, s10, v139, v214
	v_mul_f32_e32 v214, v28, v198
	v_mul_f32_e32 v215, v29, v198
	v_mul_f32_e32 v210, v210, v196
	v_mul_f32_e32 v211, v211, v196
	v_cmp_lt_f32_e64 vcc, |v213|, 4.0
	v_and_b32_e32 v143, 0x7fffffff, v213
	v_sub_u32_e32 v147, 0x7f000000, v145
	v_mul_f32_e64 v139, |v212|, v147
	v_cndmask_b32_e32 v147, 0.5, v185, vcc
	v_cmp_nlt_f32_e64 vcc, |v213|, 2.0
	v_rndne_f32_e32 v139, v139
	v_mul_f32_e32 v139, v145, v139
	v_cndmask_b32_e32 v147, v197, v147, vcc
	v_fma_f32 v26, v26, 2.0, -v210
	v_fma_f32 v27, v27, 2.0, -v211
	v_sub_u32_e32 v145, 0x7f000000, v147
	v_mul_f32_e64 v143, |v213|, v145
	v_rndne_f32_e32 v143, v143
	v_mul_f32_e32 v143, v147, v143
	v_cmp_lt_f32_e64 vcc, |v214|, 4.0
	v_min_f32_e32 v143, 0x40f00000, v143
	v_bfi_b32 v211, s10, v143, v213
	v_cndmask_b32_e32 v145, 0.5, v185, vcc
	v_cmp_nlt_f32_e64 vcc, |v214|, 2.0
	v_and_b32_e32 v143, 0x7fffffff, v214
	v_min_f32_e32 v139, 0x40f00000, v139
	v_cndmask_b32_e32 v145, v197, v145, vcc
	v_bfi_b32 v210, s10, v139, v212
	v_mul_f32_e32 v212, v12, v198
	v_mul_f32_e32 v213, v13, v198
	v_mul_f32_e32 v210, v210, v196
	v_mul_f32_e32 v211, v211, v196
	v_cmp_lt_f32_e64 vcc, |v215|, 4.0
	v_and_b32_e32 v143, 0x7fffffff, v215
	v_sub_u32_e32 v147, 0x7f000000, v145
	v_mul_f32_e64 v139, |v214|, v147
	v_cndmask_b32_e32 v147, 0.5, v185, vcc
	v_cmp_nlt_f32_e64 vcc, |v215|, 2.0
	v_rndne_f32_e32 v139, v139
	v_mul_f32_e32 v139, v145, v139
	v_cndmask_b32_e32 v147, v197, v147, vcc
	v_fma_f32 v10, v10, 2.0, -v210
	v_fma_f32 v11, v11, 2.0, -v211
	v_sub_u32_e32 v145, 0x7f000000, v147
	v_mul_f32_e64 v143, |v215|, v145
	v_rndne_f32_e32 v143, v143
	v_mul_f32_e32 v143, v147, v143
	v_cmp_lt_f32_e64 vcc, |v212|, 4.0
	v_min_f32_e32 v143, 0x40f00000, v143
	v_bfi_b32 v211, s10, v143, v215
	v_cndmask_b32_e32 v145, 0.5, v185, vcc
	v_cmp_nlt_f32_e64 vcc, |v212|, 2.0
	v_and_b32_e32 v143, 0x7fffffff, v212
	v_min_f32_e32 v139, 0x40f00000, v139
	v_cndmask_b32_e32 v145, v197, v145, vcc
	v_bfi_b32 v210, s10, v139, v214
	v_mul_f32_e32 v214, v30, v198
	v_mul_f32_e32 v215, v31, v198
	v_mul_f32_e32 v210, v210, v196
	v_mul_f32_e32 v211, v211, v196
	v_cmp_lt_f32_e64 vcc, |v213|, 4.0
	v_and_b32_e32 v143, 0x7fffffff, v213
	v_sub_u32_e32 v147, 0x7f000000, v145
	v_mul_f32_e64 v139, |v212|, v147
	v_cndmask_b32_e32 v147, 0.5, v185, vcc
	v_cmp_nlt_f32_e64 vcc, |v213|, 2.0
	v_rndne_f32_e32 v139, v139
	v_mul_f32_e32 v139, v145, v139
	v_cndmask_b32_e32 v147, v197, v147, vcc
	v_fma_f32 v28, v28, 2.0, -v210
	v_fma_f32 v29, v29, 2.0, -v211
	v_sub_u32_e32 v145, 0x7f000000, v147
	v_mul_f32_e64 v143, |v213|, v145
	v_rndne_f32_e32 v143, v143
	v_mul_f32_e32 v143, v147, v143
	v_cmp_lt_f32_e64 vcc, |v214|, 4.0
	v_min_f32_e32 v143, 0x40f00000, v143
	v_bfi_b32 v211, s10, v143, v213
	v_cndmask_b32_e32 v145, 0.5, v185, vcc
	v_cmp_nlt_f32_e64 vcc, |v214|, 2.0
	v_and_b32_e32 v143, 0x7fffffff, v214
	v_min_f32_e32 v139, 0x40f00000, v139
	v_cndmask_b32_e32 v145, v197, v145, vcc
	v_bfi_b32 v210, s10, v139, v212
	v_mul_f32_e32 v212, v14, v198
	v_mul_f32_e32 v213, v15, v198
	v_mul_f32_e32 v210, v210, v196
	v_mul_f32_e32 v211, v211, v196
	v_cmp_lt_f32_e64 vcc, |v215|, 4.0
	v_and_b32_e32 v143, 0x7fffffff, v215
	v_sub_u32_e32 v147, 0x7f000000, v145
	v_mul_f32_e64 v139, |v214|, v147
	v_cndmask_b32_e32 v147, 0.5, v185, vcc
	v_cmp_nlt_f32_e64 vcc, |v215|, 2.0
	v_rndne_f32_e32 v139, v139
	v_mul_f32_e32 v139, v145, v139
	v_cndmask_b32_e32 v147, v197, v147, vcc
	v_fma_f32 v12, v12, 2.0, -v210
	v_fma_f32 v13, v13, 2.0, -v211
	v_sub_u32_e32 v145, 0x7f000000, v147
	v_mul_f32_e64 v143, |v215|, v145
	v_rndne_f32_e32 v143, v143
	v_mul_f32_e32 v143, v147, v143
	v_cmp_lt_f32_e64 vcc, |v212|, 4.0
	v_min_f32_e32 v143, 0x40f00000, v143
	v_bfi_b32 v211, s10, v143, v215
	v_cndmask_b32_e32 v145, 0.5, v185, vcc
	v_cmp_nlt_f32_e64 vcc, |v212|, 2.0
	v_and_b32_e32 v143, 0x7fffffff, v212
	v_min_f32_e32 v139, 0x40f00000, v139
	v_cndmask_b32_e32 v145, v197, v145, vcc
	v_bfi_b32 v210, s10, v139, v214
	v_mul_f32_e32 v214, v32, v198
	v_mul_f32_e32 v215, v33, v198
	v_mul_f32_e32 v210, v210, v196
	v_mul_f32_e32 v211, v211, v196
	v_cmp_lt_f32_e64 vcc, |v213|, 4.0
	v_and_b32_e32 v143, 0x7fffffff, v213
	v_sub_u32_e32 v147, 0x7f000000, v145
	v_mul_f32_e64 v139, |v212|, v147
	v_cndmask_b32_e32 v147, 0.5, v185, vcc
	v_cmp_nlt_f32_e64 vcc, |v213|, 2.0
	v_rndne_f32_e32 v139, v139
	v_mul_f32_e32 v139, v145, v139
	v_cndmask_b32_e32 v147, v197, v147, vcc
	v_fma_f32 v30, v30, 2.0, -v210
	v_fma_f32 v31, v31, 2.0, -v211
	v_sub_u32_e32 v145, 0x7f000000, v147
	v_mul_f32_e64 v143, |v213|, v145
	v_rndne_f32_e32 v143, v143
	v_mul_f32_e32 v143, v147, v143
	v_cmp_lt_f32_e64 vcc, |v214|, 4.0
	v_min_f32_e32 v143, 0x40f00000, v143
	v_bfi_b32 v211, s10, v143, v213
	v_cndmask_b32_e32 v145, 0.5, v185, vcc
	v_cmp_nlt_f32_e64 vcc, |v214|, 2.0
	v_and_b32_e32 v143, 0x7fffffff, v214
	v_min_f32_e32 v139, 0x40f00000, v139
	v_cndmask_b32_e32 v145, v197, v145, vcc
	v_bfi_b32 v210, s10, v139, v212
	v_mul_f32_e32 v212, v16, v198
	v_mul_f32_e32 v213, v17, v198
	v_mul_f32_e32 v210, v210, v196
	v_mul_f32_e32 v211, v211, v196
	v_cmp_lt_f32_e64 vcc, |v215|, 4.0
	v_and_b32_e32 v143, 0x7fffffff, v215
	v_sub_u32_e32 v147, 0x7f000000, v145
	v_mul_f32_e64 v139, |v214|, v147
	v_cndmask_b32_e32 v147, 0.5, v185, vcc
	v_cmp_nlt_f32_e64 vcc, |v215|, 2.0
	v_rndne_f32_e32 v139, v139
	v_mul_f32_e32 v139, v145, v139
	v_cndmask_b32_e32 v147, v197, v147, vcc
	v_fma_f32 v14, v14, 2.0, -v210
	v_fma_f32 v15, v15, 2.0, -v211
	v_sub_u32_e32 v145, 0x7f000000, v147
	v_mul_f32_e64 v143, |v215|, v145
	v_rndne_f32_e32 v143, v143
	v_mul_f32_e32 v143, v147, v143
	v_cmp_lt_f32_e64 vcc, |v212|, 4.0
	v_min_f32_e32 v143, 0x40f00000, v143
	v_bfi_b32 v211, s10, v143, v215
	v_cndmask_b32_e32 v145, 0.5, v185, vcc
	v_cmp_nlt_f32_e64 vcc, |v212|, 2.0
	v_and_b32_e32 v143, 0x7fffffff, v212
	v_min_f32_e32 v139, 0x40f00000, v139
	v_cndmask_b32_e32 v145, v197, v145, vcc
	v_bfi_b32 v210, s10, v139, v214
	v_mul_f32_e32 v210, v210, v196
	v_mul_f32_e32 v211, v211, v196
	v_permlane32_swap_b32_e32 v120, v104
	v_cmp_lt_f32_e64 vcc, |v213|, 4.0
	v_and_b32_e32 v143, 0x7fffffff, v213
	v_sub_u32_e32 v147, 0x7f000000, v145
	v_mul_f32_e64 v139, |v212|, v147
	v_cndmask_b32_e32 v147, 0.5, v185, vcc
	v_cmp_nlt_f32_e64 vcc, |v213|, 2.0
	v_rndne_f32_e32 v139, v139
	v_mul_f32_e32 v139, v145, v139
	v_cndmask_b32_e32 v147, v197, v147, vcc
	v_min_f32_e32 v139, 0x40f00000, v139
	v_sub_u32_e32 v145, 0x7f000000, v147
	v_mul_f32_e64 v143, |v213|, v145
	v_rndne_f32_e32 v143, v143
	v_mul_f32_e32 v143, v147, v143
	v_min_f32_e32 v143, 0x40f00000, v143
	v_fma_f32 v32, v32, 2.0, -v210
	v_fma_f32 v33, v33, 2.0, -v211
	v_bfi_b32 v211, s10, v143, v213
	v_bfi_b32 v210, s10, v139, v212
	v_max_f32_e64 v139, |v18|, |v2|
	v_max_f32_e64 v143, |v19|, |v3|
	v_max3_f32 v139, v139, 0, v143
	v_max_f32_e64 v143, |v20|, |v4|
	v_max_f32_e64 v145, |v21|, |v5|
	v_max3_f32 v139, v139, v143, v145
	v_max_f32_e64 v143, |v22|, |v6|
	v_max_f32_e64 v145, |v23|, |v7|
	v_max3_f32 v139, v139, v143, v145
	v_max_f32_e64 v143, |v24|, |v8|
	v_max_f32_e64 v145, |v25|, |v9|
	v_max3_f32 v139, v139, v143, v145
	v_max_f32_e64 v143, |v26|, |v10|
	v_max_f32_e64 v145, |v27|, |v11|
	v_mul_f32_e32 v210, v210, v196
	v_mul_f32_e32 v211, v211, v196
	v_max3_f32 v139, v139, v143, v145
	v_max_f32_e64 v143, |v28|, |v12|
	v_max_f32_e64 v145, |v29|, |v13|
	v_fma_f32 v16, v16, 2.0, -v210
	v_fma_f32 v17, v17, 2.0, -v211
	v_max3_f32 v139, v139, v143, v145
	v_max_f32_e64 v143, |v30|, |v14|
	v_max_f32_e64 v145, |v31|, |v15|
	v_max3_f32 v139, v139, v143, v145
	v_max_f32_e64 v143, |v32|, |v16|
	v_max_f32_e64 v145, |v33|, |v17|
	v_max3_f32 v139, v139, v143, v145
	v_bfe_u32 v143, v139, 23, 8
	v_and_b32_e32 v139, 0x7fffff, v139
	v_cmp_gt_u32_e32 vcc, s1, v139
	v_permlane32_swap_b32_e32 v121, v105
	s_nop 0
	v_cndmask_b32_e64 v139, -2, -3, vcc
	v_add3_u32 v139, v143, v139, s97
	v_max_i32_e32 v139, 0xffffff88, v139
	v_add_u32_e32 v139, 0x7f, v139
	v_lshlrev_b32_e32 v143, 23, v139
	v_cvt_scalef32_2xpk16_fp6_f32 v[210:215], v[18:33], v[2:17], v143
	v_lshl_add_u64 v[2:3], v[194:195], 0, v[190:191]
	v_permlane32_swap_b32_e32 v122, v106
	v_permlane32_swap_b32_e32 v123, v107
	v_permlane32_swap_b32_e32 v124, v108
	v_permlane32_swap_b32_e32 v125, v109
	v_permlane32_swap_b32_e32 v126, v110
	v_permlane32_swap_b32_e32 v127, v111
	v_permlane32_swap_b32_e32 v128, v112
	v_permlane32_swap_b32_e32 v129, v113
	v_permlane32_swap_b32_e32 v130, v114
	v_permlane32_swap_b32_e32 v131, v115
	v_lshl_add_u64 v[2:3], v[2:3], 0, v[188:189]
	v_permlane16_swap_b32_e32 v116, v124
	v_permlane16_swap_b32_e32 v117, v125
	v_permlane16_swap_b32_e32 v118, v126
	v_permlane16_swap_b32_e32 v119, v127
	v_permlane16_swap_b32_e32 v120, v128
	v_permlane16_swap_b32_e32 v121, v129
	v_permlane16_swap_b32_e32 v122, v130
	v_permlane16_swap_b32_e32 v123, v131
	v_permlane16_swap_b32_e32 v100, v108
	v_permlane16_swap_b32_e32 v101, v109
	v_permlane16_swap_b32_e32 v102, v110
	v_permlane16_swap_b32_e32 v103, v111
	v_permlane16_swap_b32_e32 v104, v112
	v_permlane16_swap_b32_e32 v105, v113
	v_permlane16_swap_b32_e32 v106, v114
	v_permlane16_swap_b32_e32 v107, v115
	v_cmp_lt_i32_e32 vcc, 1, v199
	v_mul_lo_u32 v216, v139, s3
	global_store_dwordx4 v[2:3], v[210:213], off
	global_store_dwordx4 v[2:3], v[214:217], off offset:16
	s_and_saveexec_b64 s[4:5], vcc
	s_xor_b64 s[4:5], exec, s[4:5]
	s_cbranch_execz .LBB0_1611
	v_cmp_gt_i32_e32 vcc, 3, v199
	v_mov_b32_e32 v2, v207
	s_and_saveexec_b64 s[56:57], vcc
	v_mov_b32_e32 v2, v204
	s_or_b64 exec, exec, s[56:57]

.LBB0_1615:
	s_or_b64 exec, exec, s[56:57]
	v_mul_f32_e32 v2, 0x3dd53b94, v2
	v_mul_f32_e32 v32, v2, v130
	v_mul_f32_e32 v33, v2, v131
	v_mul_f32_e32 v30, v2, v128
	v_mul_f32_e32 v31, v2, v129
	v_mul_f32_e32 v28, v2, v126
	v_mul_f32_e32 v29, v2, v127
	v_mul_f32_e32 v26, v2, v124
	v_mul_f32_e32 v27, v2, v125
	v_mul_f32_e32 v24, v2, v122
	v_mul_f32_e32 v25, v2, v123
	v_mul_f32_e32 v22, v2, v120
	v_mul_f32_e32 v23, v2, v121
	v_mul_f32_e32 v20, v2, v118
	v_mul_f32_e32 v21, v2, v119
	v_mul_f32_e32 v18, v2, v116
	v_mul_f32_e32 v19, v2, v117
	v_mul_f32_e32 v16, v2, v114
	v_mul_f32_e32 v17, v2, v115
	v_mul_f32_e32 v14, v2, v112
	v_mul_f32_e32 v15, v2, v113
	v_mul_f32_e32 v12, v2, v110
	v_mul_f32_e32 v13, v2, v111
	v_mul_f32_e32 v10, v2, v108
	v_mul_f32_e32 v11, v2, v109
	v_mul_f32_e32 v8, v2, v106
	v_mul_f32_e32 v9, v2, v107
	v_mul_f32_e32 v6, v2, v104
	v_mul_f32_e32 v7, v2, v105
	v_mul_f32_e32 v4, v2, v102
	v_mul_f32_e32 v5, v2, v103
	v_mul_f32_e32 v3, v2, v101
	v_mul_f32_e32 v2, v2, v100
	v_max_f32_e64 v100, |v18|, |v2|
	v_max_f32_e64 v101, |v19|, |v3|
	v_max3_f32 v100, v100, 0, v101
	v_max_f32_e64 v101, |v20|, |v4|
	v_max_f32_e64 v102, |v21|, |v5|
	v_max3_f32 v100, v100, v101, v102
	v_max_f32_e64 v101, |v22|, |v6|
	v_max_f32_e64 v102, |v23|, |v7|
	v_max3_f32 v100, v100, v101, v102
	v_max_f32_e64 v101, |v24|, |v8|
	v_max_f32_e64 v102, |v25|, |v9|
	v_max3_f32 v100, v100, v101, v102
	v_max_f32_e64 v101, |v26|, |v10|
	v_max_f32_e64 v102, |v27|, |v11|
	v_max3_f32 v100, v100, v101, v102
	v_max_f32_e64 v101, |v28|, |v12|
	v_max_f32_e64 v102, |v29|, |v13|
	v_max3_f32 v100, v100, v101, v102
	v_max_f32_e64 v101, |v30|, |v14|
	v_max_f32_e64 v102, |v31|, |v15|
	v_max3_f32 v100, v100, v101, v102
	v_max_f32_e64 v101, |v32|, |v16|
	v_max_f32_e64 v102, |v33|, |v17|
	v_max3_f32 v100, v100, v101, v102
	v_bfe_u32 v101, v100, 23, 8
	v_and_b32_e32 v100, 0x7fffff, v100
	v_cmp_gt_u32_e32 vcc, s1, v100
	v_add_u32_e32 v103, 0x80, v141
	v_mov_b32_e32 v113, v35
	v_cndmask_b32_e64 v100, -2, -3, vcc
	v_add3_u32 v100, v101, v100, s97
	v_max_i32_e32 v100, 0xffffff88, v100
	v_add_u32_e32 v100, 0x7f, v100
	v_lshlrev_b32_e32 v102, 23, v100
	v_mul_lo_u32 v112, v100, s3
	v_mov_b64_e32 v[100:101], s[22:23]
	v_mad_i64_i32 v[100:101], s[4:5], v103, s0, v[100:101]
	v_lshl_add_u64 v[100:101], v[192:193], 1, v[100:101]
	v_lshl_add_u64 v[114:115], v[100:101], 0, v[34:35]
	v_cvt_scalef32_2xpk16_fp6_f32 v[106:111], v[18:33], v[2:17], v102
	v_sub_u32_e32 v104, 0x7f000000, v102
	v_lshl_add_u64 v[114:115], v[114:115], 0, v[188:189]
	global_store_dwordx4 v[114:115], v[106:109], off
	global_store_dwordx4 v[114:115], v[110:113], off offset:16
	v_mov_b32_e32 v139, v102
	v_mul_f32_e32 v106, v18, v104
	v_mul_f32_e32 v107, v19, v104
	s_nop 0
	v_cmp_lt_f32_e64 vcc, |v106|, 4.0
	v_and_b32_e32 v34, 0x7fffffff, v106
	s_nop 0
	v_cndmask_b32_e32 v103, 0.5, v185, vcc
	v_cmp_nlt_f32_e64 vcc, |v106|, 2.0
	s_nop 1
	v_cndmask_b32_e32 v103, v197, v103, vcc
	v_cmp_lt_f32_e64 vcc, |v107|, 4.0
	v_and_b32_e32 v105, 0x7fffffff, v107
	v_sub_u32_e32 v108, 0x7f000000, v103
	v_mul_f32_e64 v34, |v106|, v108
	v_cndmask_b32_e32 v108, 0.5, v185, vcc
	v_cmp_nlt_f32_e64 vcc, |v107|, 2.0
	v_rndne_f32_e32 v34, v34
	v_mul_f32_e32 v34, v103, v34
	v_cndmask_b32_e32 v108, v197, v108, vcc
	v_min_f32_e32 v34, 0x40f00000, v34
	v_bfi_b32 v106, s10, v34, v106
	v_sub_u32_e32 v105, 0x7f000000, v108
	v_mul_f32_e64 v103, |v107|, v105
	v_rndne_f32_e32 v103, v103
	v_mul_f32_e32 v103, v108, v103
	v_mul_f32_e32 v108, v2, v104
	v_mul_f32_e32 v109, v3, v104
	v_min_f32_e32 v103, 0x40f00000, v103
	v_cmp_lt_f32_e64 vcc, |v108|, 4.0
	v_bfi_b32 v107, s10, v103, v107
	v_and_b32_e32 v103, 0x7fffffff, v108
	v_cndmask_b32_e32 v105, 0.5, v185, vcc
	v_cmp_nlt_f32_e64 vcc, |v108|, 2.0
	v_mul_f32_e32 v106, v106, v102
	v_mul_f32_e32 v107, v107, v102
	s_nop 0
	v_cndmask_b32_e32 v105, v197, v105, vcc
	v_fma_f32 v18, v18, 2.0, -v106
	v_fma_f32 v19, v19, 2.0, -v107
	v_cmp_lt_f32_e64 vcc, |v109|, 4.0
	v_and_b32_e32 v103, 0x7fffffff, v109
	v_sub_u32_e32 v106, 0x7f000000, v105
	v_mul_f32_e64 v34, |v108|, v106
	v_cndmask_b32_e32 v106, 0.5, v185, vcc
	v_cmp_nlt_f32_e64 vcc, |v109|, 2.0
	v_rndne_f32_e32 v34, v34
	v_mul_f32_e32 v34, v105, v34
	v_cndmask_b32_e32 v106, v197, v106, vcc
	v_min_f32_e32 v34, 0x40f00000, v34
	v_sub_u32_e32 v105, 0x7f000000, v106
	v_mul_f32_e64 v103, |v109|, v105
	v_rndne_f32_e32 v103, v103
	v_mul_f32_e32 v110, v20, v104
	v_mul_f32_e32 v111, v21, v104
	v_mul_f32_e32 v103, v106, v103
	v_cmp_lt_f32_e64 vcc, |v110|, 4.0
	v_min_f32_e32 v103, 0x40f00000, v103
	v_bfi_b32 v107, s10, v103, v109
	v_cndmask_b32_e32 v105, 0.5, v185, vcc
	v_cmp_nlt_f32_e64 vcc, |v110|, 2.0
	v_and_b32_e32 v103, 0x7fffffff, v110
	v_bfi_b32 v106, s10, v34, v108
	v_cndmask_b32_e32 v105, v197, v105, vcc
	v_mul_f32_e32 v106, v106, v102
	v_mul_f32_e32 v107, v107, v102
	v_fma_f32 v2, v2, 2.0, -v106
	v_fma_f32 v3, v3, 2.0, -v107
	v_cmp_lt_f32_e64 vcc, |v111|, 4.0
	v_and_b32_e32 v103, 0x7fffffff, v111
	v_sub_u32_e32 v106, 0x7f000000, v105
	v_mul_f32_e64 v34, |v110|, v106
	v_cndmask_b32_e32 v106, 0.5, v185, vcc
	v_cmp_nlt_f32_e64 vcc, |v111|, 2.0
	v_rndne_f32_e32 v34, v34
	v_mul_f32_e32 v34, v105, v34
	v_cndmask_b32_e32 v106, v197, v106, vcc
	v_min_f32_e32 v34, 0x40f00000, v34
	v_sub_u32_e32 v105, 0x7f000000, v106
	v_mul_f32_e64 v103, |v111|, v105
	v_rndne_f32_e32 v103, v103
	v_mul_f32_e32 v108, v4, v104
	v_mul_f32_e32 v109, v5, v104
	v_mul_f32_e32 v103, v106, v103
	v_cmp_lt_f32_e64 vcc, |v108|, 4.0
	v_min_f32_e32 v103, 0x40f00000, v103
	v_bfi_b32 v107, s10, v103, v111
	v_cndmask_b32_e32 v105, 0.5, v185, vcc
	v_cmp_nlt_f32_e64 vcc, |v108|, 2.0
	v_and_b32_e32 v103, 0x7fffffff, v108
	v_bfi_b32 v106, s10, v34, v110
	v_cndmask_b32_e32 v105, v197, v105, vcc
	v_mul_f32_e32 v106, v106, v102
	v_mul_f32_e32 v107, v107, v102
	v_fma_f32 v20, v20, 2.0, -v106
	v_fma_f32 v21, v21, 2.0, -v107
	v_cmp_lt_f32_e64 vcc, |v109|, 4.0
	v_and_b32_e32 v103, 0x7fffffff, v109
	v_sub_u32_e32 v106, 0x7f000000, v105
	v_mul_f32_e64 v34, |v108|, v106
	v_cndmask_b32_e32 v106, 0.5, v185, vcc
	v_cmp_nlt_f32_e64 vcc, |v109|, 2.0
	v_rndne_f32_e32 v34, v34
	v_mul_f32_e32 v34, v105, v34
	v_cndmask_b32_e32 v106, v197, v106, vcc
	v_min_f32_e32 v34, 0x40f00000, v34
	v_sub_u32_e32 v105, 0x7f000000, v106
	v_mul_f32_e64 v103, |v109|, v105
	v_rndne_f32_e32 v103, v103
	v_mul_f32_e32 v110, v22, v104
	v_mul_f32_e32 v111, v23, v104
	v_mul_f32_e32 v103, v106, v103
	v_cmp_lt_f32_e64 vcc, |v110|, 4.0
	v_min_f32_e32 v103, 0x40f00000, v103
	v_bfi_b32 v107, s10, v103, v109
	v_cndmask_b32_e32 v105, 0.5, v185, vcc
	v_cmp_nlt_f32_e64 vcc, |v110|, 2.0
	v_and_b32_e32 v103, 0x7fffffff, v110
	v_bfi_b32 v106, s10, v34, v108
	v_cndmask_b32_e32 v105, v197, v105, vcc
	v_mul_f32_e32 v106, v106, v102
	v_mul_f32_e32 v107, v107, v102
	v_fma_f32 v4, v4, 2.0, -v106
	v_fma_f32 v5, v5, 2.0, -v107
	v_cmp_lt_f32_e64 vcc, |v111|, 4.0
	v_and_b32_e32 v103, 0x7fffffff, v111
	v_sub_u32_e32 v106, 0x7f000000, v105
	v_mul_f32_e64 v34, |v110|, v106
	v_cndmask_b32_e32 v106, 0.5, v185, vcc
	v_cmp_nlt_f32_e64 vcc, |v111|, 2.0
	v_rndne_f32_e32 v34, v34
	v_mul_f32_e32 v34, v105, v34
	v_cndmask_b32_e32 v106, v197, v106, vcc
	v_min_f32_e32 v34, 0x40f00000, v34
	v_sub_u32_e32 v105, 0x7f000000, v106
	v_mul_f32_e64 v103, |v111|, v105
	v_rndne_f32_e32 v103, v103
	v_mul_f32_e32 v108, v6, v104
	v_mul_f32_e32 v109, v7, v104
	v_mul_f32_e32 v103, v106, v103
	v_cmp_lt_f32_e64 vcc, |v108|, 4.0
	v_min_f32_e32 v103, 0x40f00000, v103
	v_bfi_b32 v107, s10, v103, v111
	v_cndmask_b32_e32 v105, 0.5, v185, vcc
	v_cmp_nlt_f32_e64 vcc, |v108|, 2.0
	v_and_b32_e32 v103, 0x7fffffff, v108
	v_bfi_b32 v106, s10, v34, v110
	v_cndmask_b32_e32 v105, v197, v105, vcc
	v_mul_f32_e32 v106, v106, v102
	v_mul_f32_e32 v107, v107, v102
	v_fma_f32 v22, v22, 2.0, -v106
	v_fma_f32 v23, v23, 2.0, -v107
	v_cmp_lt_f32_e64 vcc, |v109|, 4.0
	v_and_b32_e32 v103, 0x7fffffff, v109
	v_sub_u32_e32 v106, 0x7f000000, v105
	v_mul_f32_e64 v34, |v108|, v106
	v_cndmask_b32_e32 v106, 0.5, v185, vcc
	v_cmp_nlt_f32_e64 vcc, |v109|, 2.0
	v_rndne_f32_e32 v34, v34
	v_mul_f32_e32 v34, v105, v34
	v_cndmask_b32_e32 v106, v197, v106, vcc
	v_min_f32_e32 v34, 0x40f00000, v34
	v_sub_u32_e32 v105, 0x7f000000, v106
	v_mul_f32_e64 v103, |v109|, v105
	v_rndne_f32_e32 v103, v103
	v_mul_f32_e32 v110, v24, v104
	v_mul_f32_e32 v111, v25, v104
	v_mul_f32_e32 v103, v106, v103
	v_cmp_lt_f32_e64 vcc, |v110|, 4.0
	v_min_f32_e32 v103, 0x40f00000, v103
	v_bfi_b32 v107, s10, v103, v109
	v_cndmask_b32_e32 v105, 0.5, v185, vcc
	v_cmp_nlt_f32_e64 vcc, |v110|, 2.0
	v_and_b32_e32 v103, 0x7fffffff, v110
	v_bfi_b32 v106, s10, v34, v108
	v_cndmask_b32_e32 v105, v197, v105, vcc
	v_mul_f32_e32 v106, v106, v102
	v_mul_f32_e32 v107, v107, v102
	v_fma_f32 v6, v6, 2.0, -v106
	v_fma_f32 v7, v7, 2.0, -v107
	v_cmp_lt_f32_e64 vcc, |v111|, 4.0
	v_and_b32_e32 v103, 0x7fffffff, v111
	v_sub_u32_e32 v106, 0x7f000000, v105
	v_mul_f32_e64 v34, |v110|, v106
	v_cndmask_b32_e32 v106, 0.5, v185, vcc
	v_cmp_nlt_f32_e64 vcc, |v111|, 2.0
	v_rndne_f32_e32 v34, v34
	v_mul_f32_e32 v34, v105, v34
	v_cndmask_b32_e32 v106, v197, v106, vcc
	v_min_f32_e32 v34, 0x40f00000, v34
	v_sub_u32_e32 v105, 0x7f000000, v106
	v_mul_f32_e64 v103, |v111|, v105
	v_rndne_f32_e32 v103, v103
	v_mul_f32_e32 v108, v8, v104
	v_mul_f32_e32 v109, v9, v104
	v_mul_f32_e32 v103, v106, v103
	v_cmp_lt_f32_e64 vcc, |v108|, 4.0
	v_min_f32_e32 v103, 0x40f00000, v103
	v_bfi_b32 v107, s10, v103, v111
	v_cndmask_b32_e32 v105, 0.5, v185, vcc
	v_cmp_nlt_f32_e64 vcc, |v108|, 2.0
	v_and_b32_e32 v103, 0x7fffffff, v108
	v_bfi_b32 v106, s10, v34, v110
	v_cndmask_b32_e32 v105, v197, v105, vcc
	v_mul_f32_e32 v106, v106, v102
	v_mul_f32_e32 v107, v107, v102
	v_fma_f32 v24, v24, 2.0, -v106
	v_fma_f32 v25, v25, 2.0, -v107
	v_cmp_lt_f32_e64 vcc, |v109|, 4.0
	v_and_b32_e32 v103, 0x7fffffff, v109
	v_sub_u32_e32 v106, 0x7f000000, v105
	v_mul_f32_e64 v34, |v108|, v106
	v_cndmask_b32_e32 v106, 0.5, v185, vcc
	v_cmp_nlt_f32_e64 vcc, |v109|, 2.0
	v_rndne_f32_e32 v34, v34
	v_mul_f32_e32 v34, v105, v34
	v_cndmask_b32_e32 v106, v197, v106, vcc
	v_min_f32_e32 v34, 0x40f00000, v34
	v_sub_u32_e32 v105, 0x7f000000, v106
	v_mul_f32_e64 v103, |v109|, v105
	v_rndne_f32_e32 v103, v103
	v_mul_f32_e32 v110, v26, v104
	v_mul_f32_e32 v111, v27, v104
	v_mul_f32_e32 v103, v106, v103
	v_cmp_lt_f32_e64 vcc, |v110|, 4.0
	v_min_f32_e32 v103, 0x40f00000, v103
	v_bfi_b32 v107, s10, v103, v109
	v_cndmask_b32_e32 v105, 0.5, v185, vcc
	v_cmp_nlt_f32_e64 vcc, |v110|, 2.0
	v_and_b32_e32 v103, 0x7fffffff, v110
	v_bfi_b32 v106, s10, v34, v108
	v_cndmask_b32_e32 v105, v197, v105, vcc
	v_mul_f32_e32 v106, v106, v102
	v_mul_f32_e32 v107, v107, v102
	v_fma_f32 v8, v8, 2.0, -v106
	v_fma_f32 v9, v9, 2.0, -v107
	v_cmp_lt_f32_e64 vcc, |v111|, 4.0
	v_and_b32_e32 v103, 0x7fffffff, v111
	v_sub_u32_e32 v106, 0x7f000000, v105
	v_mul_f32_e64 v34, |v110|, v106
	v_cndmask_b32_e32 v106, 0.5, v185, vcc
	v_cmp_nlt_f32_e64 vcc, |v111|, 2.0
	v_rndne_f32_e32 v34, v34
	v_mul_f32_e32 v34, v105, v34
	v_cndmask_b32_e32 v106, v197, v106, vcc
	v_min_f32_e32 v34, 0x40f00000, v34
	v_sub_u32_e32 v105, 0x7f000000, v106
	v_mul_f32_e64 v103, |v111|, v105
	v_rndne_f32_e32 v103, v103
	v_mul_f32_e32 v108, v10, v104
	v_mul_f32_e32 v109, v11, v104
	v_mul_f32_e32 v103, v106, v103
	v_cmp_lt_f32_e64 vcc, |v108|, 4.0
	v_min_f32_e32 v103, 0x40f00000, v103
	v_bfi_b32 v107, s10, v103, v111
	v_cndmask_b32_e32 v105, 0.5, v185, vcc
	v_cmp_nlt_f32_e64 vcc, |v108|, 2.0
	v_and_b32_e32 v103, 0x7fffffff, v108
	v_bfi_b32 v106, s10, v34, v110
	v_cndmask_b32_e32 v105, v197, v105, vcc
	v_mul_f32_e32 v106, v106, v102
	v_mul_f32_e32 v107, v107, v102
	v_fma_f32 v26, v26, 2.0, -v106
	v_fma_f32 v27, v27, 2.0, -v107
	v_cmp_lt_f32_e64 vcc, |v109|, 4.0
	v_and_b32_e32 v103, 0x7fffffff, v109
	v_sub_u32_e32 v106, 0x7f000000, v105
	v_mul_f32_e64 v34, |v108|, v106
	v_cndmask_b32_e32 v106, 0.5, v185, vcc
	v_cmp_nlt_f32_e64 vcc, |v109|, 2.0
	v_rndne_f32_e32 v34, v34
	v_mul_f32_e32 v34, v105, v34
	v_cndmask_b32_e32 v106, v197, v106, vcc
	v_min_f32_e32 v34, 0x40f00000, v34
	v_sub_u32_e32 v105, 0x7f000000, v106
	v_mul_f32_e64 v103, |v109|, v105
	v_rndne_f32_e32 v103, v103
	v_mul_f32_e32 v110, v28, v104
	v_mul_f32_e32 v111, v29, v104
	v_mul_f32_e32 v103, v106, v103
	v_cmp_lt_f32_e64 vcc, |v110|, 4.0
	v_min_f32_e32 v103, 0x40f00000, v103
	v_bfi_b32 v107, s10, v103, v109
	v_cndmask_b32_e32 v105, 0.5, v185, vcc
	v_cmp_nlt_f32_e64 vcc, |v110|, 2.0
	v_and_b32_e32 v103, 0x7fffffff, v110
	v_bfi_b32 v106, s10, v34, v108
	v_cndmask_b32_e32 v105, v197, v105, vcc
	v_mul_f32_e32 v106, v106, v102
	v_mul_f32_e32 v107, v107, v102
	v_fma_f32 v10, v10, 2.0, -v106
	v_fma_f32 v11, v11, 2.0, -v107
	v_cmp_lt_f32_e64 vcc, |v111|, 4.0
	v_and_b32_e32 v103, 0x7fffffff, v111
	v_sub_u32_e32 v106, 0x7f000000, v105
	v_mul_f32_e64 v34, |v110|, v106
	v_cndmask_b32_e32 v106, 0.5, v185, vcc
	v_cmp_nlt_f32_e64 vcc, |v111|, 2.0
	v_rndne_f32_e32 v34, v34
	v_mul_f32_e32 v34, v105, v34
	v_cndmask_b32_e32 v106, v197, v106, vcc
	v_min_f32_e32 v34, 0x40f00000, v34
	v_sub_u32_e32 v105, 0x7f000000, v106
	v_mul_f32_e64 v103, |v111|, v105
	v_rndne_f32_e32 v103, v103
	v_mul_f32_e32 v108, v12, v104
	v_mul_f32_e32 v109, v13, v104
	v_mul_f32_e32 v103, v106, v103
	v_cmp_lt_f32_e64 vcc, |v108|, 4.0
	v_min_f32_e32 v103, 0x40f00000, v103
	v_bfi_b32 v107, s10, v103, v111
	v_cndmask_b32_e32 v105, 0.5, v185, vcc
	v_cmp_nlt_f32_e64 vcc, |v108|, 2.0
	v_and_b32_e32 v103, 0x7fffffff, v108
	v_bfi_b32 v106, s10, v34, v110
	v_cndmask_b32_e32 v105, v197, v105, vcc
	v_mul_f32_e32 v106, v106, v102
	v_mul_f32_e32 v107, v107, v102
	v_fma_f32 v28, v28, 2.0, -v106
	v_fma_f32 v29, v29, 2.0, -v107
	v_cmp_lt_f32_e64 vcc, |v109|, 4.0
	v_and_b32_e32 v103, 0x7fffffff, v109
	v_sub_u32_e32 v106, 0x7f000000, v105
	v_mul_f32_e64 v34, |v108|, v106
	v_cndmask_b32_e32 v106, 0.5, v185, vcc
	v_cmp_nlt_f32_e64 vcc, |v109|, 2.0
	v_rndne_f32_e32 v34, v34
	v_mul_f32_e32 v34, v105, v34
	v_cndmask_b32_e32 v106, v197, v106, vcc
	v_min_f32_e32 v34, 0x40f00000, v34
	v_sub_u32_e32 v105, 0x7f000000, v106
	v_mul_f32_e64 v103, |v109|, v105
	v_rndne_f32_e32 v103, v103
	v_mul_f32_e32 v110, v30, v104
	v_mul_f32_e32 v111, v31, v104
	v_mul_f32_e32 v103, v106, v103
	v_cmp_lt_f32_e64 vcc, |v110|, 4.0
	v_min_f32_e32 v103, 0x40f00000, v103
	v_bfi_b32 v107, s10, v103, v109
	v_cndmask_b32_e32 v105, 0.5, v185, vcc
	v_cmp_nlt_f32_e64 vcc, |v110|, 2.0
	v_and_b32_e32 v103, 0x7fffffff, v110
	v_bfi_b32 v106, s10, v34, v108
	v_cndmask_b32_e32 v105, v197, v105, vcc
	v_mul_f32_e32 v106, v106, v102
	v_mul_f32_e32 v107, v107, v102
	v_fma_f32 v12, v12, 2.0, -v106
	v_fma_f32 v13, v13, 2.0, -v107
	v_cmp_lt_f32_e64 vcc, |v111|, 4.0
	v_and_b32_e32 v103, 0x7fffffff, v111
	v_sub_u32_e32 v106, 0x7f000000, v105
	v_mul_f32_e64 v34, |v110|, v106
	v_cndmask_b32_e32 v106, 0.5, v185, vcc
	v_cmp_nlt_f32_e64 vcc, |v111|, 2.0
	v_rndne_f32_e32 v34, v34
	v_mul_f32_e32 v34, v105, v34
	v_cndmask_b32_e32 v106, v197, v106, vcc
	v_min_f32_e32 v34, 0x40f00000, v34
	v_sub_u32_e32 v105, 0x7f000000, v106
	v_mul_f32_e64 v103, |v111|, v105
	v_rndne_f32_e32 v103, v103
	v_mul_f32_e32 v108, v14, v104
	v_mul_f32_e32 v109, v15, v104
	v_mul_f32_e32 v103, v106, v103
	v_cmp_lt_f32_e64 vcc, |v108|, 4.0
	v_min_f32_e32 v103, 0x40f00000, v103
	v_bfi_b32 v107, s10, v103, v111
	v_cndmask_b32_e32 v105, 0.5, v185, vcc
	v_cmp_nlt_f32_e64 vcc, |v108|, 2.0
	v_and_b32_e32 v103, 0x7fffffff, v108
	v_bfi_b32 v106, s10, v34, v110
	v_cndmask_b32_e32 v105, v197, v105, vcc
	v_mul_f32_e32 v106, v106, v102
	v_mul_f32_e32 v107, v107, v102
	v_fma_f32 v30, v30, 2.0, -v106
	v_fma_f32 v31, v31, 2.0, -v107
	v_cmp_lt_f32_e64 vcc, |v109|, 4.0
	v_and_b32_e32 v103, 0x7fffffff, v109
	v_sub_u32_e32 v106, 0x7f000000, v105
	v_mul_f32_e64 v34, |v108|, v106
	v_cndmask_b32_e32 v106, 0.5, v185, vcc
	v_cmp_nlt_f32_e64 vcc, |v109|, 2.0
	v_rndne_f32_e32 v34, v34
	v_mul_f32_e32 v34, v105, v34
	v_cndmask_b32_e32 v106, v197, v106, vcc
	v_min_f32_e32 v34, 0x40f00000, v34
	v_sub_u32_e32 v105, 0x7f000000, v106
	v_mul_f32_e64 v103, |v109|, v105
	v_rndne_f32_e32 v103, v103
	v_mul_f32_e32 v103, v106, v103
	v_bfi_b32 v106, s10, v34, v108
	v_mul_f32_e32 v34, v32, v104
	v_cmp_lt_f32_e64 vcc, |v34|, 4.0
	v_min_f32_e32 v103, 0x40f00000, v103
	v_bfi_b32 v107, s10, v103, v109
	v_cndmask_b32_e32 v105, 0.5, v185, vcc
	v_cmp_nlt_f32_e64 vcc, |v34|, 2.0
	v_and_b32_e32 v103, 0x7fffffff, v34
	v_mul_f32_e32 v106, v106, v102
	v_mul_f32_e32 v107, v107, v102
	v_cndmask_b32_e32 v105, v197, v105, vcc
	v_fma_f32 v14, v14, 2.0, -v106
	v_fma_f32 v15, v15, 2.0, -v107
	v_sub_u32_e32 v106, 0x7f000000, v105
	v_mul_f32_e64 v103, |v34|, v106
	v_rndne_f32_e32 v103, v103
	v_mul_f32_e32 v103, v105, v103
	v_mul_f32_e32 v105, v16, v104
	v_cmp_lt_f32_e64 vcc, |v105|, 4.0
	v_and_b32_e32 v107, 0x7fffffff, v105
	v_min_f32_e32 v103, 0x40f00000, v103
	v_cndmask_b32_e32 v106, 0.5, v185, vcc
	v_cmp_nlt_f32_e64 vcc, |v105|, 2.0
	v_bfi_b32 v34, s10, v103, v34
	v_add_f32_e32 v32, v32, v32
	v_cndmask_b32_e32 v108, v197, v106, vcc
	v_mul_f32_e32 v106, v34, v102
	v_add_f32_e32 v16, v16, v16
	v_sub_u32_e32 v103, 0x7f000000, v108
	v_mul_f32_e64 v34, |v105|, v103
	v_mul_f32_e32 v103, v33, v104
	v_rndne_f32_e32 v34, v34
	v_cmp_lt_f32_e64 vcc, |v103|, 4.0
	v_mul_f32_e32 v34, v108, v34
	v_and_b32_e32 v107, 0x7fffffff, v103
	v_cndmask_b32_e32 v108, 0.5, v185, vcc
	v_cmp_nlt_f32_e64 vcc, |v103|, 2.0
	v_min_f32_e32 v34, 0x40f00000, v34
	v_bfi_b32 v34, s10, v34, v105
	v_cndmask_b32_e32 v109, v197, v108, vcc
	v_mul_f32_e32 v108, v34, v102
	v_sub_u32_e32 v105, 0x7f000000, v109
	v_mul_f32_e64 v34, |v103|, v105
	v_rndne_f32_e32 v34, v34
	v_mul_f32_e32 v34, v109, v34
	v_min_f32_e32 v34, 0x40f00000, v34
	v_bfi_b32 v111, s10, v34, v103
	v_mul_f32_e32 v34, v17, v104
	v_cmp_lt_f32_e64 vcc, |v34|, 4.0
	v_mov_b32_e32 v110, v33
	v_and_b32_e32 v104, 0x7fffffff, v34
	v_cndmask_b32_e32 v33, 0.5, v185, vcc
	v_cmp_nlt_f32_e64 vcc, |v34|, 2.0
	v_mul_f32_e32 v102, v110, v138
	v_mul_f32_e32 v103, v111, v139
	s_nop 0
	v_cndmask_b32_e32 v105, v197, v33, vcc
	v_mov_b32_e32 v33, v102
	v_mov_b32_e32 v107, v103
	v_add_f32_e64 v32, v32, -v106
	v_add_f32_e64 v33, v33, -v107
	v_sub_u32_e32 v103, 0x7f000000, v105
	v_mul_f32_e64 v102, |v34|, v103
	v_rndne_f32_e32 v102, v102
	v_mul_f32_e32 v102, v105, v102
	v_min_f32_e32 v102, 0x40f00000, v102
	v_bfi_b32 v103, s10, v102, v34
	v_mov_b32_e32 v102, v17
	v_mul_f32_e32 v102, v102, v138
	v_mul_f32_e32 v103, v103, v139
	v_max_f32_e64 v34, |v18|, |v2|
	v_mov_b32_e32 v17, v102
	v_max_f32_e64 v102, |v19|, |v3|
	v_mov_b32_e32 v109, v103
	v_max3_f32 v34, v34, 0, v102
	v_max_f32_e64 v102, |v20|, |v4|
	v_max_f32_e64 v103, |v21|, |v5|
	v_max3_f32 v34, v34, v102, v103
	v_max_f32_e64 v102, |v22|, |v6|
	v_max_f32_e64 v103, |v23|, |v7|
	v_max3_f32 v34, v34, v102, v103
	v_max_f32_e64 v102, |v24|, |v8|
	v_max_f32_e64 v103, |v25|, |v9|
	v_max3_f32 v34, v34, v102, v103
	v_max_f32_e64 v102, |v26|, |v10|
	v_max_f32_e64 v103, |v27|, |v11|
	v_max3_f32 v34, v34, v102, v103
	v_max_f32_e64 v102, |v28|, |v12|
	v_max_f32_e64 v103, |v29|, |v13|
	v_add_f32_e64 v16, v16, -v108
	v_add_f32_e64 v17, v17, -v109
	v_max3_f32 v34, v34, v102, v103
	v_max_f32_e64 v102, |v30|, |v14|
	v_max_f32_e64 v103, |v31|, |v15|
	v_max3_f32 v34, v34, v102, v103
	v_max_f32_e64 v102, |v32|, |v16|
	v_max_f32_e64 v103, |v33|, |v17|
	v_max3_f32 v34, v34, v102, v103
	v_bfe_u32 v102, v34, 23, 8
	v_and_b32_e32 v34, 0x7fffff, v34
	v_cmp_gt_u32_e32 vcc, s1, v34
	s_nop 1
	v_cndmask_b32_e64 v34, -2, -3, vcc
	v_add3_u32 v34, v102, v34, s97
	v_max_i32_e32 v34, 0xffffff88, v34
	v_add_u32_e32 v34, 0x7f, v34
	v_lshlrev_b32_e32 v108, 23, v34
	v_cvt_scalef32_2xpk16_fp6_f32 v[102:107], v[18:33], v[2:17], v108
	v_lshl_add_u64 v[2:3], v[100:101], 0, v[190:191]
	v_mul_lo_u32 v34, v34, s3
	v_lshl_add_u64 v[2:3], v[2:3], 0, v[188:189]
	v_mov_b32_e32 v32, v106
	v_mov_b32_e32 v33, v107
	global_store_dwordx4 v[2:3], v[102:105], off
	global_store_dwordx4 v[2:3], v[32:35], off offset:16

.LBB0_1619:
	v_add_u32_e32 v2, 0xffffff80, v104
	v_lshrrev_b32_e32 v34, 1, v2
	v_lshlrev_b64 v[6:7], 2, v[34:35]
	v_lshl_add_u64 v[2:3], s[14:15], 0, v[6:7]
	v_lshl_add_u64 v[8:9], v[2:3], 0, v[186:187]
	global_load_dwordx4 v[10:13], v[8:9], off
	v_lshl_add_u64 v[8:9], s[12:13], 0, v[6:7]
	v_lshl_add_u64 v[6:7], v[8:9], 0, v[186:187]
	global_load_dwordx4 v[14:17], v[6:7], off
	v_mul_f32_e32 v24, v88, v184
	v_mul_f32_e32 v25, v89, v184
	v_mul_f32_e32 v20, v84, v184
	v_mul_f32_e32 v21, v85, v184
	v_mov_b32_e32 v32, v35
	v_mov_b32_e32 v33, v35
	v_mul_f32_e32 v22, v90, v184
	v_mul_f32_e32 v23, v91, v184
	v_mul_f32_e32 v18, v86, v184
	v_mul_f32_e32 v19, v87, v184
	v_sub_u32_e32 v4, v4, v104
	v_mov_b64_e32 v[6:7], s[22:23]
	v_ashrrev_i32_e32 v5, 31, v4
	v_mad_i64_i32 v[26:27], s[4:5], v140, s0, v[6:7]
	v_lshlrev_b64 v[4:5], 1, v[4:5]
	v_lshl_add_u64 v[26:27], v[26:27], 0, v[4:5]
	s_waitcnt vmcnt(1)
	v_mul_f32_e32 v30, v24, v10
	v_mul_f32_e32 v31, v25, v11
	v_mul_f32_e32 v10, v20, v10
	v_mul_f32_e32 v11, v21, v11
	v_mul_f32_e32 v28, v22, v12
	v_mul_f32_e32 v29, v23, v13
	s_waitcnt vmcnt(0)
	v_fma_f32 v20, v20, v14, -v30
	v_fma_f32 v21, v21, v15, -v31
	v_fmac_f32_e32 v10, v24, v14
	v_fmac_f32_e32 v11, v25, v15
	v_cvt_pk_fp8_f32 v32, v20, v21
	v_cvt_pk_fp8_f32 v33, v10, v11
	v_mul_f32_e32 v12, v18, v12
	v_mul_f32_e32 v13, v19, v13
	v_fma_f32 v10, v18, v16, -v28
	v_fma_f32 v11, v19, v17, -v29
	v_fmac_f32_e32 v12, v22, v16
	v_fmac_f32_e32 v13, v23, v17
	v_cvt_pk_fp8_f32 v32, v10, v11 op_sel:[0,0,1]
	v_cvt_pk_fp8_f32 v33, v12, v13 op_sel:[0,0,1]
	v_lshl_add_u64 v[10:11], v[26:27], 0, v[34:35]
	v_lshl_add_u64 v[12:13], v[2:3], 0, v[182:183]
	global_store_dword v[10:11], v32, off offset:256
	global_store_dword v[10:11], v33, off offset:288
	global_load_dwordx4 v[10:13], v[12:13], off
	v_lshl_add_u64 v[14:15], v[8:9], 0, v[182:183]
	global_load_dwordx4 v[14:17], v[14:15], off
	v_mul_f32_e32 v24, v96, v180
	v_mul_f32_e32 v25, v97, v180
	v_mul_f32_e32 v20, v92, v180
	v_mul_f32_e32 v21, v93, v180
	v_mov_b32_e32 v32, v35
	v_mov_b32_e32 v33, v35
	v_mul_f32_e32 v22, v98, v180
	v_mul_f32_e32 v23, v99, v180
	v_mul_f32_e32 v18, v94, v180
	v_mul_f32_e32 v19, v95, v180
	v_mad_i64_i32 v[26:27], s[4:5], v142, s0, v[6:7]
	v_lshl_add_u64 v[26:27], v[26:27], 0, v[4:5]
	s_waitcnt vmcnt(1)
	v_mul_f32_e32 v30, v24, v10
	v_mul_f32_e32 v31, v25, v11
	v_mul_f32_e32 v10, v20, v10
	v_mul_f32_e32 v11, v21, v11
	s_waitcnt vmcnt(0)
	v_fma_f32 v20, v20, v14, -v30
	v_fma_f32 v21, v21, v15, -v31
	v_fmac_f32_e32 v10, v24, v14
	v_fmac_f32_e32 v11, v25, v15
	v_cvt_pk_fp8_f32 v32, v20, v21
	v_cvt_pk_fp8_f32 v33, v10, v11
	v_mul_f32_e32 v28, v22, v12
	v_mul_f32_e32 v29, v23, v13
	v_mul_f32_e32 v12, v18, v12
	v_mul_f32_e32 v13, v19, v13
	v_fma_f32 v10, v18, v16, -v28
	v_fma_f32 v11, v19, v17, -v29
	v_fmac_f32_e32 v12, v22, v16
	v_fmac_f32_e32 v13, v23, v17
	v_cvt_pk_fp8_f32 v32, v10, v11 op_sel:[0,0,1]
	v_cvt_pk_fp8_f32 v33, v12, v13 op_sel:[0,0,1]
	v_lshl_add_u64 v[10:11], v[26:27], 0, v[34:35]
	v_lshl_add_u64 v[12:13], v[2:3], 0, v[178:179]
	global_store_dword v[10:11], v32, off offset:256
	global_store_dword v[10:11], v33, off offset:288
	global_load_dwordx4 v[10:13], v[12:13], off
	v_lshl_add_u64 v[14:15], v[8:9], 0, v[178:179]
	global_load_dwordx4 v[14:17], v[14:15], off
	v_mul_f32_e32 v24, v72, v176
	v_mul_f32_e32 v25, v73, v176
	v_mul_f32_e32 v20, v68, v176
	v_mul_f32_e32 v21, v69, v176
	v_mov_b32_e32 v32, v35
	v_mov_b32_e32 v33, v35
	v_mul_f32_e32 v22, v74, v176
	v_mul_f32_e32 v23, v75, v176
	v_mul_f32_e32 v18, v70, v176
	v_mul_f32_e32 v19, v71, v176
	v_mad_i64_i32 v[26:27], s[4:5], v144, s0, v[6:7]
	v_lshl_add_u64 v[26:27], v[26:27], 0, v[4:5]
	s_waitcnt vmcnt(1)
	v_mul_f32_e32 v30, v24, v10
	v_mul_f32_e32 v31, v25, v11
	v_mul_f32_e32 v10, v20, v10
	v_mul_f32_e32 v11, v21, v11
	s_waitcnt vmcnt(0)
	v_fma_f32 v20, v20, v14, -v30
	v_fma_f32 v21, v21, v15, -v31
	v_fmac_f32_e32 v10, v24, v14
	v_fmac_f32_e32 v11, v25, v15
	v_cvt_pk_fp8_f32 v32, v20, v21
	v_cvt_pk_fp8_f32 v33, v10, v11
	v_mul_f32_e32 v28, v22, v12
	v_mul_f32_e32 v29, v23, v13
	v_mul_f32_e32 v12, v18, v12
	v_mul_f32_e32 v13, v19, v13
	v_fma_f32 v10, v18, v16, -v28
	v_fma_f32 v11, v19, v17, -v29
	v_fmac_f32_e32 v12, v22, v16
	v_fmac_f32_e32 v13, v23, v17
	v_cvt_pk_fp8_f32 v32, v10, v11 op_sel:[0,0,1]
	v_cvt_pk_fp8_f32 v33, v12, v13 op_sel:[0,0,1]
	v_lshl_add_u64 v[10:11], v[26:27], 0, v[34:35]
	v_lshl_add_u64 v[12:13], v[2:3], 0, v[174:175]
	global_store_dword v[10:11], v32, off offset:256
	global_store_dword v[10:11], v33, off offset:288
	global_load_dwordx4 v[10:13], v[12:13], off
	v_lshl_add_u64 v[14:15], v[8:9], 0, v[174:175]
	global_load_dwordx4 v[14:17], v[14:15], off
	v_mul_f32_e32 v24, v80, v172
	v_mul_f32_e32 v25, v81, v172
	v_mul_f32_e32 v20, v76, v172
	v_mul_f32_e32 v21, v77, v172
	v_mov_b32_e32 v32, v35
	v_mov_b32_e32 v33, v35
	v_mul_f32_e32 v22, v82, v172
	v_mul_f32_e32 v23, v83, v172
	v_mul_f32_e32 v18, v78, v172
	v_mul_f32_e32 v19, v79, v172
	v_mad_i64_i32 v[26:27], s[4:5], v146, s0, v[6:7]
	v_lshl_add_u64 v[26:27], v[26:27], 0, v[4:5]
	s_waitcnt vmcnt(1)
	v_mul_f32_e32 v30, v24, v10
	v_mul_f32_e32 v31, v25, v11
	v_mul_f32_e32 v10, v20, v10
	v_mul_f32_e32 v11, v21, v11
	s_waitcnt vmcnt(0)
	v_fma_f32 v20, v20, v14, -v30
	v_fma_f32 v21, v21, v15, -v31
	v_fmac_f32_e32 v10, v24, v14
	v_fmac_f32_e32 v11, v25, v15
	v_cvt_pk_fp8_f32 v32, v20, v21
	v_cvt_pk_fp8_f32 v33, v10, v11
	v_mul_f32_e32 v28, v22, v12
	v_mul_f32_e32 v29, v23, v13
	v_mul_f32_e32 v12, v18, v12
	v_mul_f32_e32 v13, v19, v13
	v_fma_f32 v10, v18, v16, -v28
	v_fma_f32 v11, v19, v17, -v29
	v_fmac_f32_e32 v12, v22, v16
	v_fmac_f32_e32 v13, v23, v17
	v_cvt_pk_fp8_f32 v32, v10, v11 op_sel:[0,0,1]
	v_cvt_pk_fp8_f32 v33, v12, v13 op_sel:[0,0,1]
	v_lshl_add_u64 v[10:11], v[26:27], 0, v[34:35]
	v_lshl_add_u64 v[12:13], v[2:3], 0, v[170:171]
	global_store_dword v[10:11], v32, off offset:256
	global_store_dword v[10:11], v33, off offset:288
	global_load_dwordx4 v[10:13], v[12:13], off
	v_lshl_add_u64 v[14:15], v[8:9], 0, v[170:171]
	global_load_dwordx4 v[14:17], v[14:15], off
	v_mul_f32_e32 v24, v56, v168
	v_mul_f32_e32 v25, v57, v168
	v_mul_f32_e32 v20, v52, v168
	v_mul_f32_e32 v21, v53, v168
	v_mov_b32_e32 v32, v35
	v_mov_b32_e32 v33, v35
	v_mul_f32_e32 v22, v58, v168
	v_mul_f32_e32 v23, v59, v168
	v_mul_f32_e32 v18, v54, v168
	v_mul_f32_e32 v19, v55, v168
	v_mad_i64_i32 v[26:27], s[4:5], v148, s0, v[6:7]
	v_lshl_add_u64 v[26:27], v[26:27], 0, v[4:5]
	s_waitcnt vmcnt(1)
	v_mul_f32_e32 v30, v24, v10
	v_mul_f32_e32 v31, v25, v11
	v_mul_f32_e32 v10, v20, v10
	v_mul_f32_e32 v11, v21, v11
	s_waitcnt vmcnt(0)
	v_fma_f32 v20, v20, v14, -v30
	v_fma_f32 v21, v21, v15, -v31
	v_fmac_f32_e32 v10, v24, v14
	v_fmac_f32_e32 v11, v25, v15
	v_cvt_pk_fp8_f32 v32, v20, v21
	v_cvt_pk_fp8_f32 v33, v10, v11
	v_mul_f32_e32 v28, v22, v12
	v_mul_f32_e32 v29, v23, v13
	v_mul_f32_e32 v12, v18, v12
	v_mul_f32_e32 v13, v19, v13
	v_fma_f32 v10, v18, v16, -v28
	v_fma_f32 v11, v19, v17, -v29
	v_fmac_f32_e32 v12, v22, v16
	v_fmac_f32_e32 v13, v23, v17
	v_cvt_pk_fp8_f32 v32, v10, v11 op_sel:[0,0,1]
	v_cvt_pk_fp8_f32 v33, v12, v13 op_sel:[0,0,1]
	v_lshl_add_u64 v[10:11], v[26:27], 0, v[34:35]
	v_lshl_add_u64 v[12:13], v[2:3], 0, v[166:167]
	global_store_dword v[10:11], v32, off offset:256
	global_store_dword v[10:11], v33, off offset:288
	global_load_dwordx4 v[10:13], v[12:13], off
	v_lshl_add_u64 v[14:15], v[8:9], 0, v[166:167]
	global_load_dwordx4 v[14:17], v[14:15], off
	v_mul_f32_e32 v24, v64, v164
	v_mul_f32_e32 v25, v65, v164
	v_mul_f32_e32 v20, v60, v164
	v_mul_f32_e32 v21, v61, v164
	v_mov_b32_e32 v32, v35
	v_mov_b32_e32 v33, v35
	v_mul_f32_e32 v22, v66, v164
	v_mul_f32_e32 v23, v67, v164
	v_mul_f32_e32 v18, v62, v164
	v_mul_f32_e32 v19, v63, v164
	v_mad_i64_i32 v[26:27], s[4:5], v150, s0, v[6:7]
	v_lshl_add_u64 v[26:27], v[26:27], 0, v[4:5]
	s_waitcnt vmcnt(1)
	v_mul_f32_e32 v30, v24, v10
	v_mul_f32_e32 v31, v25, v11
	v_mul_f32_e32 v10, v20, v10
	v_mul_f32_e32 v11, v21, v11
	s_waitcnt vmcnt(0)
	v_fma_f32 v20, v20, v14, -v30
	v_fma_f32 v21, v21, v15, -v31
	v_fmac_f32_e32 v10, v24, v14
	v_fmac_f32_e32 v11, v25, v15
	v_cvt_pk_fp8_f32 v32, v20, v21
	v_cvt_pk_fp8_f32 v33, v10, v11
	v_mul_f32_e32 v28, v22, v12
	v_mul_f32_e32 v29, v23, v13
	v_mul_f32_e32 v12, v18, v12
	v_mul_f32_e32 v13, v19, v13
	v_fma_f32 v10, v18, v16, -v28
	v_fma_f32 v11, v19, v17, -v29
	v_fmac_f32_e32 v12, v22, v16
	v_fmac_f32_e32 v13, v23, v17
	v_cvt_pk_fp8_f32 v32, v10, v11 op_sel:[0,0,1]
	v_cvt_pk_fp8_f32 v33, v12, v13 op_sel:[0,0,1]
	v_lshl_add_u64 v[10:11], v[26:27], 0, v[34:35]
	v_lshl_add_u64 v[12:13], v[2:3], 0, v[162:163]
	global_store_dword v[10:11], v32, off offset:256
	global_store_dword v[10:11], v33, off offset:288
	global_load_dwordx4 v[10:13], v[12:13], off
	v_lshl_add_u64 v[14:15], v[8:9], 0, v[162:163]
	global_load_dwordx4 v[14:17], v[14:15], off
	v_mul_f32_e32 v24, v44, v160
	v_mul_f32_e32 v25, v45, v160
	v_mul_f32_e32 v20, v36, v160
	v_mul_f32_e32 v21, v37, v160
	v_mov_b32_e32 v32, v35
	v_mov_b32_e32 v33, v35
	v_mul_f32_e32 v22, v46, v160
	v_mul_f32_e32 v23, v47, v160
	v_mul_f32_e32 v18, v38, v160
	v_mul_f32_e32 v19, v39, v160
	v_mad_i64_i32 v[26:27], s[4:5], v152, s0, v[6:7]
	v_lshl_add_u64 v[26:27], v[26:27], 0, v[4:5]
	v_lshl_add_u64 v[2:3], v[2:3], 0, v[158:159]
	v_mad_i64_i32 v[6:7], s[4:5], v154, s0, v[6:7]
	s_waitcnt vmcnt(1)
	v_mul_f32_e32 v30, v24, v10
	v_mul_f32_e32 v31, v25, v11
	v_mul_f32_e32 v10, v20, v10
	v_mul_f32_e32 v11, v21, v11
	s_waitcnt vmcnt(0)
	v_fma_f32 v20, v20, v14, -v30
	v_fma_f32 v21, v21, v15, -v31
	v_fmac_f32_e32 v10, v24, v14
	v_fmac_f32_e32 v11, v25, v15
	v_cvt_pk_fp8_f32 v32, v20, v21
	v_cvt_pk_fp8_f32 v33, v10, v11
	v_mul_f32_e32 v28, v22, v12
	v_mul_f32_e32 v29, v23, v13
	v_mul_f32_e32 v12, v18, v12
	v_mul_f32_e32 v13, v19, v13
	v_fma_f32 v10, v18, v16, -v28
	v_fma_f32 v11, v19, v17, -v29
	v_fmac_f32_e32 v12, v22, v16
	v_fmac_f32_e32 v13, v23, v17
	v_cvt_pk_fp8_f32 v32, v10, v11 op_sel:[0,0,1]
	v_cvt_pk_fp8_f32 v33, v12, v13 op_sel:[0,0,1]
	v_lshl_add_u64 v[10:11], v[26:27], 0, v[34:35]
	global_store_dword v[10:11], v32, off offset:256
	global_store_dword v[10:11], v33, off offset:288
	global_load_dwordx4 v[10:13], v[2:3], off
	v_lshl_add_u64 v[2:3], v[8:9], 0, v[158:159]
	global_load_dwordx4 v[14:17], v[2:3], off
	v_mul_f32_e32 v20, v40, v156
	v_mul_f32_e32 v21, v41, v156
	v_mul_f32_e32 v8, v48, v156
	v_mul_f32_e32 v9, v49, v156
	v_mov_b32_e32 v26, v35
	v_mov_b32_e32 v27, v35
	v_mul_f32_e32 v18, v42, v156
	v_mul_f32_e32 v19, v43, v156
	v_mul_f32_e32 v2, v50, v156
	v_mul_f32_e32 v3, v51, v156
	s_waitcnt vmcnt(1)
	v_mul_f32_e32 v24, v20, v10
	v_mul_f32_e32 v25, v21, v11
	v_mul_f32_e32 v10, v8, v10
	v_mul_f32_e32 v11, v9, v11
	s_waitcnt vmcnt(0)
	v_fma_f32 v8, v8, v14, -v24
	v_fma_f32 v9, v9, v15, -v25
	v_fmac_f32_e32 v10, v20, v14
	v_fmac_f32_e32 v11, v21, v15
	v_cvt_pk_fp8_f32 v26, v8, v9
	v_cvt_pk_fp8_f32 v27, v10, v11
	v_mul_f32_e32 v22, v18, v12
	v_mul_f32_e32 v23, v19, v13
	v_mul_f32_e32 v12, v2, v12
	v_mul_f32_e32 v13, v3, v13
	v_fma_f32 v2, v2, v16, -v22
	v_fma_f32 v3, v3, v17, -v23
	v_fma_f32 v8, v18, v16, v12
	v_fma_f32 v9, v19, v17, v13
	v_cvt_pk_fp8_f32 v26, v2, v3 op_sel:[0,0,1]
	v_cvt_pk_fp8_f32 v27, v8, v9 op_sel:[0,0,1]
	v_lshl_add_u64 v[2:3], v[6:7], 0, v[4:5]
	v_lshl_add_u64 v[2:3], v[2:3], 0, v[34:35]
	global_store_dword v[2:3], v26, off offset:256
	global_store_dword v[2:3], v27, off offset:288
	s_andn2_saveexec_b64 s[6:7], s[6:7]
	s_cbranch_execz .LBB0_1618

.LBB0_1630:
	s_or_b64 exec, exec, s[56:57]
	v_mul_f32_e32 v2, 0x3dd53b94, v206
	v_mul_f32_e32 v32, v2, v98
	v_mul_f32_e32 v33, v2, v99
	v_mul_f32_e32 v30, v2, v96
	v_mul_f32_e32 v31, v2, v97
	v_mul_f32_e32 v28, v2, v94
	v_mul_f32_e32 v29, v2, v95
	v_mul_f32_e32 v26, v2, v92
	v_mul_f32_e32 v27, v2, v93
	v_mul_f32_e32 v24, v2, v90
	v_mul_f32_e32 v25, v2, v91
	v_mul_f32_e32 v22, v2, v88
	v_mul_f32_e32 v23, v2, v89
	v_mul_f32_e32 v20, v2, v86
	v_mul_f32_e32 v21, v2, v87
	v_mul_f32_e32 v18, v2, v84
	v_mul_f32_e32 v19, v2, v85
	v_mul_f32_e32 v16, v2, v82
	v_mul_f32_e32 v17, v2, v83
	v_mul_f32_e32 v14, v2, v80
	v_mul_f32_e32 v15, v2, v81
	v_mul_f32_e32 v12, v2, v78
	v_mul_f32_e32 v13, v2, v79
	v_mul_f32_e32 v10, v2, v76
	v_mul_f32_e32 v11, v2, v77
	v_mul_f32_e32 v8, v2, v74
	v_mul_f32_e32 v9, v2, v75
	v_mul_f32_e32 v6, v2, v72
	v_mul_f32_e32 v7, v2, v73
	v_mul_f32_e32 v4, v2, v70
	v_mul_f32_e32 v5, v2, v71
	v_mul_f32_e32 v3, v2, v69
	v_mul_f32_e32 v2, v2, v68
	v_max_f32_e64 v68, |v18|, |v2|
	v_max_f32_e64 v69, |v19|, |v3|
	v_max3_f32 v68, v68, 0, v69
	v_max_f32_e64 v69, |v20|, |v4|
	v_max_f32_e64 v70, |v21|, |v5|
	v_max3_f32 v68, v68, v69, v70
	v_max_f32_e64 v69, |v22|, |v6|
	v_max_f32_e64 v70, |v23|, |v7|
	v_max3_f32 v68, v68, v69, v70
	v_max_f32_e64 v69, |v24|, |v8|
	v_max_f32_e64 v70, |v25|, |v9|
	v_max3_f32 v68, v68, v69, v70
	v_max_f32_e64 v69, |v26|, |v10|
	v_max_f32_e64 v70, |v27|, |v11|
	v_max3_f32 v68, v68, v69, v70
	v_max_f32_e64 v69, |v28|, |v12|
	v_max_f32_e64 v70, |v29|, |v13|
	v_max3_f32 v68, v68, v69, v70
	v_max_f32_e64 v69, |v30|, |v14|
	v_max_f32_e64 v70, |v31|, |v15|
	v_max3_f32 v68, v68, v69, v70
	v_max_f32_e64 v69, |v32|, |v16|
	v_max_f32_e64 v70, |v33|, |v17|
	v_max3_f32 v68, v68, v69, v70
	v_cmp_gt_u32_e32 vcc, 64, v104
	v_bfe_u32 v69, v68, 23, 8
	v_and_b32_e32 v68, 0x7fffff, v68
	v_cndmask_b32_e32 v34, v177, v181, vcc
	v_cndmask_b32_e64 v102, 64, 0, vcc
	v_cmp_gt_u32_e32 vcc, s1, v68
	v_ashrrev_i32_e32 v73, 31, v208
	v_and_b32_e32 v100, 32, v104
	v_cndmask_b32_e64 v68, -2, -3, vcc
	v_add3_u32 v68, v69, v68, s97
	v_max_i32_e32 v68, 0xffffff88, v68
	v_add_u32_e32 v68, 0x7f, v68
	v_lshlrev_b32_e32 v72, 23, v68
	v_mul_lo_u32 v82, v68, s3
	v_mov_b64_e32 v[68:69], s[22:23]
	v_mad_i64_i32 v[70:71], s[4:5], v141, s0, v[68:69]
	v_ashrrev_i32_e32 v69, 31, v104
	v_sub_co_u32_e32 v68, vcc, v208, v104
	v_mov_b32_e32 v101, v35
	s_nop 0
	v_subb_co_u32_e32 v69, vcc, v73, v69, vcc
	v_lshl_add_u64 v[70:71], v[68:69], 1, v[70:71]
	v_lshl_add_u64 v[84:85], v[70:71], 0, v[34:35]
	v_cvt_scalef32_2xpk16_fp6_f32 v[76:81], v[18:33], v[2:17], v72
	v_sub_u32_e32 v74, 0x7f000000, v72
	v_lshl_add_u64 v[84:85], v[84:85], 0, v[100:101]
	global_store_dwordx4 v[84:85], v[76:79], off offset:256
	v_mov_b32_e32 v83, v35
	global_store_dwordx4 v[84:85], v[80:83], off offset:272
	v_mul_f32_e32 v76, v18, v74
	v_mul_f32_e32 v77, v19, v74
	v_mov_b32_e32 v103, v35
	v_cmp_lt_f32_e64 vcc, |v76|, 4.0
	v_and_b32_e32 v73, 0x7fffffff, v76
	v_permlane32_swap_b32_e32 v52, v36
	v_cndmask_b32_e32 v75, 0.5, v185, vcc
	v_cmp_nlt_f32_e64 vcc, |v76|, 2.0
	v_permlane32_swap_b32_e32 v53, v37
	s_nop 0
	v_cndmask_b32_e32 v75, v197, v75, vcc
	v_permlane32_swap_b32_e32 v54, v38
	v_cmp_lt_f32_e64 vcc, |v77|, 4.0
	v_and_b32_e32 v78, 0x7fffffff, v77
	v_sub_u32_e32 v79, 0x7f000000, v75
	v_mul_f32_e64 v73, |v76|, v79
	v_cndmask_b32_e32 v79, 0.5, v185, vcc
	v_cmp_nlt_f32_e64 vcc, |v77|, 2.0
	v_rndne_f32_e32 v73, v73
	v_mul_f32_e32 v73, v75, v73
	v_cndmask_b32_e32 v79, v197, v79, vcc
	v_min_f32_e32 v73, 0x40f00000, v73
	v_bfi_b32 v76, s10, v73, v76
	v_permlane32_swap_b32_e32 v55, v39
	v_sub_u32_e32 v78, 0x7f000000, v79
	v_mul_f32_e64 v75, |v77|, v78
	v_rndne_f32_e32 v75, v75
	v_mul_f32_e32 v75, v79, v75
	v_min_f32_e32 v75, 0x40f00000, v75
	v_mul_f32_e32 v78, v2, v74
	v_mul_f32_e32 v79, v3, v74
	v_bfi_b32 v77, s10, v75, v77
	v_cmp_lt_f32_e64 vcc, |v78|, 4.0
	v_and_b32_e32 v75, 0x7fffffff, v78
	v_mul_f32_e32 v76, v76, v72
	v_mul_f32_e32 v77, v77, v72
	v_cndmask_b32_e32 v80, 0.5, v185, vcc
	v_cmp_nlt_f32_e64 vcc, |v78|, 2.0
	v_fma_f32 v18, v18, 2.0, -v76
	v_fma_f32 v19, v19, 2.0, -v77
	v_permlane32_swap_b32_e32 v56, v44
	v_cndmask_b32_e32 v80, v197, v80, vcc
	v_permlane32_swap_b32_e32 v57, v45
	v_permlane32_swap_b32_e32 v58, v46
	v_cmp_lt_f32_e64 vcc, |v79|, 4.0
	v_and_b32_e32 v75, 0x7fffffff, v79
	v_sub_u32_e32 v76, 0x7f000000, v80
	v_mul_f32_e64 v73, |v78|, v76
	v_cndmask_b32_e32 v76, 0.5, v185, vcc
	v_cmp_nlt_f32_e64 vcc, |v79|, 2.0
	v_rndne_f32_e32 v73, v73
	v_mul_f32_e32 v73, v80, v73
	v_cndmask_b32_e32 v76, v197, v76, vcc
	v_min_f32_e32 v73, 0x40f00000, v73
	v_sub_u32_e32 v77, 0x7f000000, v76
	v_mul_f32_e64 v75, |v79|, v77
	v_rndne_f32_e32 v75, v75
	v_mul_f32_e32 v75, v76, v75
	v_min_f32_e32 v75, 0x40f00000, v75
	v_mul_f32_e32 v80, v20, v74
	v_mul_f32_e32 v81, v21, v74
	v_bfi_b32 v77, s10, v75, v79
	v_cmp_lt_f32_e64 vcc, |v80|, 4.0
	v_and_b32_e32 v75, 0x7fffffff, v80
	v_permlane32_swap_b32_e32 v59, v47
	v_cndmask_b32_e32 v76, 0.5, v185, vcc
	v_cmp_nlt_f32_e64 vcc, |v80|, 2.0
	v_permlane32_swap_b32_e32 v60, v48
	s_nop 0
	v_cndmask_b32_e32 v79, v197, v76, vcc
	v_bfi_b32 v76, s10, v73, v78
	v_mul_f32_e32 v76, v76, v72
	v_mul_f32_e32 v77, v77, v72
	v_permlane32_swap_b32_e32 v61, v49
	v_fma_f32 v2, v2, 2.0, -v76
	v_fma_f32 v3, v3, 2.0, -v77
	v_cmp_lt_f32_e64 vcc, |v81|, 4.0
	v_and_b32_e32 v75, 0x7fffffff, v81
	v_sub_u32_e32 v76, 0x7f000000, v79
	v_mul_f32_e64 v73, |v80|, v76
	v_cndmask_b32_e32 v76, 0.5, v185, vcc
	v_cmp_nlt_f32_e64 vcc, |v81|, 2.0
	v_rndne_f32_e32 v73, v73
	v_mul_f32_e32 v73, v79, v73
	v_cndmask_b32_e32 v76, v197, v76, vcc
	v_min_f32_e32 v73, 0x40f00000, v73
	v_sub_u32_e32 v77, 0x7f000000, v76
	v_mul_f32_e64 v75, |v81|, v77
	v_rndne_f32_e32 v75, v75
	v_mul_f32_e32 v75, v76, v75
	v_min_f32_e32 v75, 0x40f00000, v75
	v_mul_f32_e32 v78, v4, v74
	v_mul_f32_e32 v79, v5, v74
	v_bfi_b32 v77, s10, v75, v81
	v_cmp_lt_f32_e64 vcc, |v78|, 4.0
	v_and_b32_e32 v75, 0x7fffffff, v78
	v_permlane32_swap_b32_e32 v62, v50
	v_cndmask_b32_e32 v76, 0.5, v185, vcc
	v_cmp_nlt_f32_e64 vcc, |v78|, 2.0
	v_permlane32_swap_b32_e32 v63, v51
	s_nop 0
	v_cndmask_b32_e32 v81, v197, v76, vcc
	v_bfi_b32 v76, s10, v73, v80
	v_mul_f32_e32 v76, v76, v72
	v_mul_f32_e32 v77, v77, v72
	v_permlane32_swap_b32_e32 v64, v40
	v_fma_f32 v20, v20, 2.0, -v76
	v_fma_f32 v21, v21, 2.0, -v77
	v_cmp_lt_f32_e64 vcc, |v79|, 4.0
	v_and_b32_e32 v75, 0x7fffffff, v79
	v_sub_u32_e32 v76, 0x7f000000, v81
	v_mul_f32_e64 v73, |v78|, v76
	v_cndmask_b32_e32 v76, 0.5, v185, vcc
	v_cmp_nlt_f32_e64 vcc, |v79|, 2.0
	v_rndne_f32_e32 v73, v73
	v_mul_f32_e32 v73, v81, v73
	v_cndmask_b32_e32 v76, v197, v76, vcc
	v_min_f32_e32 v73, 0x40f00000, v73
	v_sub_u32_e32 v77, 0x7f000000, v76
	v_mul_f32_e64 v75, |v79|, v77
	v_rndne_f32_e32 v75, v75
	v_mul_f32_e32 v75, v76, v75
	v_min_f32_e32 v75, 0x40f00000, v75
	v_mul_f32_e32 v80, v22, v74
	v_mul_f32_e32 v81, v23, v74
	v_bfi_b32 v77, s10, v75, v79
	v_cmp_lt_f32_e64 vcc, |v80|, 4.0
	v_and_b32_e32 v75, 0x7fffffff, v80
	v_permlane32_swap_b32_e32 v65, v41
	v_cndmask_b32_e32 v76, 0.5, v185, vcc
	v_cmp_nlt_f32_e64 vcc, |v80|, 2.0
	v_permlane32_swap_b32_e32 v66, v42
	s_nop 0
	v_cndmask_b32_e32 v79, v197, v76, vcc
	v_bfi_b32 v76, s10, v73, v78
	v_mul_f32_e32 v76, v76, v72
	v_mul_f32_e32 v77, v77, v72
	v_permlane32_swap_b32_e32 v67, v43
	v_fma_f32 v4, v4, 2.0, -v76
	v_fma_f32 v5, v5, 2.0, -v77
	v_cmp_lt_f32_e64 vcc, |v81|, 4.0
	v_and_b32_e32 v75, 0x7fffffff, v81
	v_sub_u32_e32 v76, 0x7f000000, v79
	v_mul_f32_e64 v73, |v80|, v76
	v_cndmask_b32_e32 v76, 0.5, v185, vcc
	v_cmp_nlt_f32_e64 vcc, |v81|, 2.0
	v_rndne_f32_e32 v73, v73
	v_mul_f32_e32 v73, v79, v73
	v_cndmask_b32_e32 v76, v197, v76, vcc
	v_min_f32_e32 v73, 0x40f00000, v73
	v_sub_u32_e32 v77, 0x7f000000, v76
	v_mul_f32_e64 v75, |v81|, v77
	v_rndne_f32_e32 v75, v75
	v_mul_f32_e32 v75, v76, v75
	v_min_f32_e32 v75, 0x40f00000, v75
	v_mul_f32_e32 v78, v6, v74
	v_mul_f32_e32 v79, v7, v74
	v_bfi_b32 v77, s10, v75, v81
	v_cmp_lt_f32_e64 vcc, |v78|, 4.0
	v_and_b32_e32 v75, 0x7fffffff, v78
	v_permlane16_swap_b32_e32 v52, v60
	v_cndmask_b32_e32 v76, 0.5, v185, vcc
	v_cmp_nlt_f32_e64 vcc, |v78|, 2.0
	v_permlane16_swap_b32_e32 v53, v61
	s_nop 0
	v_cndmask_b32_e32 v81, v197, v76, vcc
	v_bfi_b32 v76, s10, v73, v80
	v_mul_f32_e32 v76, v76, v72
	v_mul_f32_e32 v77, v77, v72
	v_permlane16_swap_b32_e32 v54, v62
	v_fma_f32 v22, v22, 2.0, -v76
	v_fma_f32 v23, v23, 2.0, -v77
	v_cmp_lt_f32_e64 vcc, |v79|, 4.0
	v_and_b32_e32 v75, 0x7fffffff, v79
	v_sub_u32_e32 v76, 0x7f000000, v81
	v_mul_f32_e64 v73, |v78|, v76
	v_cndmask_b32_e32 v76, 0.5, v185, vcc
	v_cmp_nlt_f32_e64 vcc, |v79|, 2.0
	v_rndne_f32_e32 v73, v73
	v_mul_f32_e32 v73, v81, v73
	v_cndmask_b32_e32 v76, v197, v76, vcc
	v_min_f32_e32 v73, 0x40f00000, v73
	v_sub_u32_e32 v77, 0x7f000000, v76
	v_mul_f32_e64 v75, |v79|, v77
	v_rndne_f32_e32 v75, v75
	v_mul_f32_e32 v75, v76, v75
	v_min_f32_e32 v75, 0x40f00000, v75
	v_mul_f32_e32 v80, v24, v74
	v_mul_f32_e32 v81, v25, v74
	v_bfi_b32 v77, s10, v75, v79
	v_cmp_lt_f32_e64 vcc, |v80|, 4.0
	v_and_b32_e32 v75, 0x7fffffff, v80
	v_permlane16_swap_b32_e32 v55, v63
	v_cndmask_b32_e32 v76, 0.5, v185, vcc
	v_cmp_nlt_f32_e64 vcc, |v80|, 2.0
	v_permlane16_swap_b32_e32 v56, v64
	s_nop 0
	v_cndmask_b32_e32 v79, v197, v76, vcc
	v_bfi_b32 v76, s10, v73, v78
	v_mul_f32_e32 v76, v76, v72
	v_mul_f32_e32 v77, v77, v72
	v_permlane16_swap_b32_e32 v57, v65
	v_fma_f32 v6, v6, 2.0, -v76
	v_fma_f32 v7, v7, 2.0, -v77
	v_cmp_lt_f32_e64 vcc, |v81|, 4.0
	v_and_b32_e32 v75, 0x7fffffff, v81
	v_sub_u32_e32 v76, 0x7f000000, v79
	v_mul_f32_e64 v73, |v80|, v76
	v_cndmask_b32_e32 v76, 0.5, v185, vcc
	v_cmp_nlt_f32_e64 vcc, |v81|, 2.0
	v_rndne_f32_e32 v73, v73
	v_mul_f32_e32 v73, v79, v73
	v_cndmask_b32_e32 v76, v197, v76, vcc
	v_min_f32_e32 v73, 0x40f00000, v73
	v_sub_u32_e32 v77, 0x7f000000, v76
	v_mul_f32_e64 v75, |v81|, v77
	v_rndne_f32_e32 v75, v75
	v_mul_f32_e32 v75, v76, v75
	v_min_f32_e32 v75, 0x40f00000, v75
	v_mul_f32_e32 v78, v8, v74
	v_mul_f32_e32 v79, v9, v74
	v_bfi_b32 v77, s10, v75, v81
	v_cmp_lt_f32_e64 vcc, |v78|, 4.0
	v_and_b32_e32 v75, 0x7fffffff, v78
	v_permlane16_swap_b32_e32 v58, v66
	v_cndmask_b32_e32 v76, 0.5, v185, vcc
	v_cmp_nlt_f32_e64 vcc, |v78|, 2.0
	v_permlane16_swap_b32_e32 v59, v67
	s_nop 0
	v_cndmask_b32_e32 v81, v197, v76, vcc
	v_bfi_b32 v76, s10, v73, v80
	v_mul_f32_e32 v76, v76, v72
	v_mul_f32_e32 v77, v77, v72
	v_permlane16_swap_b32_e32 v36, v48
	v_fma_f32 v24, v24, 2.0, -v76
	v_fma_f32 v25, v25, 2.0, -v77
	v_cmp_lt_f32_e64 vcc, |v79|, 4.0
	v_and_b32_e32 v75, 0x7fffffff, v79
	v_sub_u32_e32 v76, 0x7f000000, v81
	v_mul_f32_e64 v73, |v78|, v76
	v_cndmask_b32_e32 v76, 0.5, v185, vcc
	v_cmp_nlt_f32_e64 vcc, |v79|, 2.0
	v_rndne_f32_e32 v73, v73
	v_mul_f32_e32 v73, v81, v73
	v_cndmask_b32_e32 v76, v197, v76, vcc
	v_min_f32_e32 v73, 0x40f00000, v73
	v_sub_u32_e32 v77, 0x7f000000, v76
	v_mul_f32_e64 v75, |v79|, v77
	v_rndne_f32_e32 v75, v75
	v_mul_f32_e32 v75, v76, v75
	v_min_f32_e32 v75, 0x40f00000, v75
	v_mul_f32_e32 v80, v26, v74
	v_mul_f32_e32 v81, v27, v74
	v_bfi_b32 v77, s10, v75, v79
	v_cmp_lt_f32_e64 vcc, |v80|, 4.0
	v_and_b32_e32 v75, 0x7fffffff, v80
	v_permlane16_swap_b32_e32 v37, v49
	v_cndmask_b32_e32 v76, 0.5, v185, vcc
	v_cmp_nlt_f32_e64 vcc, |v80|, 2.0
	v_permlane16_swap_b32_e32 v38, v50
	s_nop 0
	v_cndmask_b32_e32 v79, v197, v76, vcc
	v_bfi_b32 v76, s10, v73, v78
	v_mul_f32_e32 v76, v76, v72
	v_mul_f32_e32 v77, v77, v72
	v_permlane16_swap_b32_e32 v39, v51
	v_fma_f32 v8, v8, 2.0, -v76
	v_fma_f32 v9, v9, 2.0, -v77
	v_cmp_lt_f32_e64 vcc, |v81|, 4.0
	v_and_b32_e32 v75, 0x7fffffff, v81
	v_sub_u32_e32 v76, 0x7f000000, v79
	v_mul_f32_e64 v73, |v80|, v76
	v_cndmask_b32_e32 v76, 0.5, v185, vcc
	v_cmp_nlt_f32_e64 vcc, |v81|, 2.0
	v_rndne_f32_e32 v73, v73
	v_mul_f32_e32 v73, v79, v73
	v_cndmask_b32_e32 v76, v197, v76, vcc
	v_min_f32_e32 v73, 0x40f00000, v73
	v_sub_u32_e32 v77, 0x7f000000, v76
	v_mul_f32_e64 v75, |v81|, v77
	v_rndne_f32_e32 v75, v75
	v_mul_f32_e32 v75, v76, v75
	v_min_f32_e32 v75, 0x40f00000, v75
	v_mul_f32_e32 v78, v10, v74
	v_mul_f32_e32 v79, v11, v74
	v_bfi_b32 v77, s10, v75, v81
	v_cmp_lt_f32_e64 vcc, |v78|, 4.0
	v_and_b32_e32 v75, 0x7fffffff, v78
	v_permlane16_swap_b32_e32 v44, v40
	v_cndmask_b32_e32 v76, 0.5, v185, vcc
	v_cmp_nlt_f32_e64 vcc, |v78|, 2.0
	v_permlane16_swap_b32_e32 v45, v41
	s_nop 0
	v_cndmask_b32_e32 v81, v197, v76, vcc
	v_bfi_b32 v76, s10, v73, v80
	v_mul_f32_e32 v76, v76, v72
	v_mul_f32_e32 v77, v77, v72
	v_permlane16_swap_b32_e32 v46, v42
	v_fma_f32 v26, v26, 2.0, -v76
	v_fma_f32 v27, v27, 2.0, -v77
	v_cmp_lt_f32_e64 vcc, |v79|, 4.0
	v_and_b32_e32 v75, 0x7fffffff, v79
	v_sub_u32_e32 v76, 0x7f000000, v81
	v_mul_f32_e64 v73, |v78|, v76
	v_cndmask_b32_e32 v76, 0.5, v185, vcc
	v_cmp_nlt_f32_e64 vcc, |v79|, 2.0
	v_rndne_f32_e32 v73, v73
	v_mul_f32_e32 v73, v81, v73
	v_cndmask_b32_e32 v76, v197, v76, vcc
	v_min_f32_e32 v73, 0x40f00000, v73
	v_sub_u32_e32 v77, 0x7f000000, v76
	v_mul_f32_e64 v75, |v79|, v77
	v_rndne_f32_e32 v75, v75
	v_mul_f32_e32 v75, v76, v75
	v_min_f32_e32 v75, 0x40f00000, v75
	v_mul_f32_e32 v80, v28, v74
	v_mul_f32_e32 v81, v29, v74
	v_bfi_b32 v77, s10, v75, v79
	v_cmp_lt_f32_e64 vcc, |v80|, 4.0
	v_and_b32_e32 v75, 0x7fffffff, v80
	v_permlane16_swap_b32_e32 v47, v43
	v_cndmask_b32_e32 v76, 0.5, v185, vcc
	v_cmp_nlt_f32_e64 vcc, |v80|, 2.0
	s_nop 1
	v_cndmask_b32_e32 v79, v197, v76, vcc
	v_bfi_b32 v76, s10, v73, v78
	v_mul_f32_e32 v76, v76, v72
	v_mul_f32_e32 v77, v77, v72
	v_fma_f32 v10, v10, 2.0, -v76
	v_fma_f32 v11, v11, 2.0, -v77
	v_cmp_lt_f32_e64 vcc, |v81|, 4.0
	v_and_b32_e32 v75, 0x7fffffff, v81
	v_sub_u32_e32 v76, 0x7f000000, v79
	v_mul_f32_e64 v73, |v80|, v76
	v_cndmask_b32_e32 v76, 0.5, v185, vcc
	v_cmp_nlt_f32_e64 vcc, |v81|, 2.0
	v_rndne_f32_e32 v73, v73
	v_mul_f32_e32 v73, v79, v73
	v_cndmask_b32_e32 v76, v197, v76, vcc
	v_min_f32_e32 v73, 0x40f00000, v73
	v_sub_u32_e32 v77, 0x7f000000, v76
	v_mul_f32_e64 v75, |v81|, v77
	v_rndne_f32_e32 v75, v75
	v_mul_f32_e32 v75, v76, v75
	v_min_f32_e32 v75, 0x40f00000, v75
	v_mul_f32_e32 v78, v12, v74
	v_mul_f32_e32 v79, v13, v74
	v_bfi_b32 v77, s10, v75, v81
	v_cmp_lt_f32_e64 vcc, |v78|, 4.0
	v_and_b32_e32 v75, 0x7fffffff, v78
	s_nop 0
	v_cndmask_b32_e32 v76, 0.5, v185, vcc
	v_cmp_nlt_f32_e64 vcc, |v78|, 2.0
	s_nop 1
	v_cndmask_b32_e32 v81, v197, v76, vcc
	v_bfi_b32 v76, s10, v73, v80
	v_mul_f32_e32 v76, v76, v72
	v_mul_f32_e32 v77, v77, v72
	v_fma_f32 v28, v28, 2.0, -v76
	v_fma_f32 v29, v29, 2.0, -v77
	v_cmp_lt_f32_e64 vcc, |v79|, 4.0
	v_and_b32_e32 v75, 0x7fffffff, v79
	v_sub_u32_e32 v76, 0x7f000000, v81
	v_mul_f32_e64 v73, |v78|, v76
	v_cndmask_b32_e32 v76, 0.5, v185, vcc
	v_cmp_nlt_f32_e64 vcc, |v79|, 2.0
	v_rndne_f32_e32 v73, v73
	v_mul_f32_e32 v73, v81, v73
	v_cndmask_b32_e32 v76, v197, v76, vcc
	v_min_f32_e32 v73, 0x40f00000, v73
	v_sub_u32_e32 v77, 0x7f000000, v76
	v_mul_f32_e64 v75, |v79|, v77
	v_rndne_f32_e32 v75, v75
	v_mul_f32_e32 v75, v76, v75
	v_min_f32_e32 v75, 0x40f00000, v75
	v_mul_f32_e32 v80, v30, v74
	v_mul_f32_e32 v81, v31, v74
	v_bfi_b32 v77, s10, v75, v79
	v_cmp_lt_f32_e64 vcc, |v80|, 4.0
	v_and_b32_e32 v75, 0x7fffffff, v80
	s_nop 0
	v_cndmask_b32_e32 v76, 0.5, v185, vcc
	v_cmp_nlt_f32_e64 vcc, |v80|, 2.0
	s_nop 1
	v_cndmask_b32_e32 v79, v197, v76, vcc
	v_bfi_b32 v76, s10, v73, v78
	v_mul_f32_e32 v76, v76, v72
	v_mul_f32_e32 v77, v77, v72
	v_fma_f32 v12, v12, 2.0, -v76
	v_fma_f32 v13, v13, 2.0, -v77
	v_cmp_lt_f32_e64 vcc, |v81|, 4.0
	v_and_b32_e32 v75, 0x7fffffff, v81
	v_sub_u32_e32 v76, 0x7f000000, v79
	v_mul_f32_e64 v73, |v80|, v76
	v_cndmask_b32_e32 v76, 0.5, v185, vcc
	v_cmp_nlt_f32_e64 vcc, |v81|, 2.0
	v_rndne_f32_e32 v73, v73
	v_mul_f32_e32 v73, v79, v73
	v_cndmask_b32_e32 v76, v197, v76, vcc
	v_min_f32_e32 v73, 0x40f00000, v73
	v_sub_u32_e32 v77, 0x7f000000, v76
	v_mul_f32_e64 v75, |v81|, v77
	v_rndne_f32_e32 v75, v75
	v_mul_f32_e32 v75, v76, v75
	v_min_f32_e32 v75, 0x40f00000, v75
	v_mul_f32_e32 v78, v14, v74
	v_mul_f32_e32 v79, v15, v74
	v_bfi_b32 v77, s10, v75, v81
	v_cmp_lt_f32_e64 vcc, |v78|, 4.0
	v_and_b32_e32 v75, 0x7fffffff, v78
	s_nop 0
	v_cndmask_b32_e32 v76, 0.5, v185, vcc
	v_cmp_nlt_f32_e64 vcc, |v78|, 2.0
	s_nop 1
	v_cndmask_b32_e32 v81, v197, v76, vcc
	v_bfi_b32 v76, s10, v73, v80
	v_mul_f32_e32 v76, v76, v72
	v_mul_f32_e32 v77, v77, v72
	v_fma_f32 v30, v30, 2.0, -v76
	v_fma_f32 v31, v31, 2.0, -v77
	v_cmp_lt_f32_e64 vcc, |v79|, 4.0
	v_and_b32_e32 v75, 0x7fffffff, v79
	v_sub_u32_e32 v76, 0x7f000000, v81
	v_mul_f32_e64 v73, |v78|, v76
	v_cndmask_b32_e32 v76, 0.5, v185, vcc
	v_cmp_nlt_f32_e64 vcc, |v79|, 2.0
	v_rndne_f32_e32 v73, v73
	v_mul_f32_e32 v73, v81, v73
	v_cndmask_b32_e32 v76, v197, v76, vcc
	v_min_f32_e32 v73, 0x40f00000, v73
	v_sub_u32_e32 v77, 0x7f000000, v76
	v_mul_f32_e64 v75, |v79|, v77
	v_rndne_f32_e32 v75, v75
	v_mul_f32_e32 v75, v76, v75
	v_min_f32_e32 v75, 0x40f00000, v75
	v_mul_f32_e32 v80, v32, v74
	v_mul_f32_e32 v81, v33, v74
	v_bfi_b32 v77, s10, v75, v79
	v_cmp_lt_f32_e64 vcc, |v80|, 4.0
	v_and_b32_e32 v75, 0x7fffffff, v80
	s_nop 0
	v_cndmask_b32_e32 v76, 0.5, v185, vcc
	v_cmp_nlt_f32_e64 vcc, |v80|, 2.0
	s_nop 1
	v_cndmask_b32_e32 v79, v197, v76, vcc
	v_bfi_b32 v76, s10, v73, v78
	v_mul_f32_e32 v76, v76, v72
	v_mul_f32_e32 v77, v77, v72
	v_fma_f32 v14, v14, 2.0, -v76
	v_fma_f32 v15, v15, 2.0, -v77
	v_cmp_lt_f32_e64 vcc, |v81|, 4.0
	v_and_b32_e32 v75, 0x7fffffff, v81
	v_sub_u32_e32 v76, 0x7f000000, v79
	v_mul_f32_e64 v73, |v80|, v76
	v_cndmask_b32_e32 v76, 0.5, v185, vcc
	v_cmp_nlt_f32_e64 vcc, |v81|, 2.0
	v_rndne_f32_e32 v73, v73
	v_mul_f32_e32 v73, v79, v73
	v_cndmask_b32_e32 v76, v197, v76, vcc
	v_min_f32_e32 v73, 0x40f00000, v73
	v_sub_u32_e32 v77, 0x7f000000, v76
	v_mul_f32_e64 v75, |v81|, v77
	v_rndne_f32_e32 v75, v75
	v_mul_f32_e32 v75, v76, v75
	v_min_f32_e32 v75, 0x40f00000, v75
	v_bfi_b32 v75, s10, v75, v81
	v_mul_f32_e32 v76, v16, v74
	v_mul_f32_e32 v77, v17, v74
	s_nop 0
	v_cmp_lt_f32_e64 vcc, |v76|, 4.0
	v_and_b32_e32 v78, 0x7fffffff, v76
	s_nop 0
	v_cndmask_b32_e32 v74, 0.5, v185, vcc
	v_cmp_nlt_f32_e64 vcc, |v76|, 2.0
	s_nop 1
	v_cndmask_b32_e32 v79, v197, v74, vcc
	v_bfi_b32 v74, s10, v73, v80
	v_mul_f32_e32 v74, v74, v72
	v_mul_f32_e32 v75, v75, v72
	v_fma_f32 v32, v32, 2.0, -v74
	v_fma_f32 v33, v33, 2.0, -v75
	v_cmp_lt_f32_e64 vcc, |v77|, 4.0
	v_and_b32_e32 v74, 0x7fffffff, v77
	v_sub_u32_e32 v75, 0x7f000000, v79
	v_mul_f32_e64 v73, |v76|, v75
	v_cndmask_b32_e32 v75, 0.5, v185, vcc
	v_cmp_nlt_f32_e64 vcc, |v77|, 2.0
	v_rndne_f32_e32 v73, v73
	v_mul_f32_e32 v73, v79, v73
	v_cndmask_b32_e32 v75, v197, v75, vcc
	v_min_f32_e32 v73, 0x40f00000, v73
	v_sub_u32_e32 v78, 0x7f000000, v75
	v_mul_f32_e64 v74, |v77|, v78
	v_rndne_f32_e32 v74, v74
	v_mul_f32_e32 v74, v75, v74
	v_min_f32_e32 v74, 0x40f00000, v74
	v_bfi_b32 v75, s10, v74, v77
	v_bfi_b32 v74, s10, v73, v76
	v_mul_f32_e32 v73, v75, v72
	v_mul_f32_e32 v72, v74, v72
	v_max_f32_e64 v74, |v21|, |v5|
	v_fma_f32 v16, v16, 2.0, -v72
	v_fma_f32 v17, v17, 2.0, -v73
	v_max_f32_e64 v72, |v18|, |v2|
	v_max_f32_e64 v73, |v19|, |v3|
	v_max3_f32 v72, v72, 0, v73
	v_max_f32_e64 v73, |v20|, |v4|
	v_max3_f32 v72, v72, v73, v74
	v_max_f32_e64 v73, |v22|, |v6|
	v_max_f32_e64 v74, |v23|, |v7|
	v_max3_f32 v72, v72, v73, v74
	v_max_f32_e64 v73, |v24|, |v8|
	v_max_f32_e64 v74, |v25|, |v9|
	v_max3_f32 v72, v72, v73, v74
	v_max_f32_e64 v73, |v26|, |v10|
	v_max_f32_e64 v74, |v27|, |v11|
	v_max3_f32 v72, v72, v73, v74
	v_max_f32_e64 v73, |v28|, |v12|
	v_max_f32_e64 v74, |v29|, |v13|
	v_max3_f32 v72, v72, v73, v74
	v_max_f32_e64 v73, |v30|, |v14|
	v_max_f32_e64 v74, |v31|, |v15|
	v_max3_f32 v72, v72, v73, v74
	v_max_f32_e64 v73, |v32|, |v16|
	v_max_f32_e64 v74, |v33|, |v17|
	v_max3_f32 v72, v72, v73, v74
	v_bfe_u32 v73, v72, 23, 8
	v_and_b32_e32 v72, 0x7fffff, v72
	v_cmp_gt_u32_e32 vcc, s1, v72
	s_nop 1
	v_cndmask_b32_e64 v72, -2, -3, vcc
	v_add3_u32 v72, v73, v72, s97
	v_max_i32_e32 v72, 0xffffff88, v72
	v_add_u32_e32 v72, 0x7f, v72
	v_lshlrev_b32_e32 v79, 23, v72
	v_mul_lo_u32 v78, v72, s3
	v_cvt_scalef32_2xpk16_fp6_f32 v[72:77], v[18:33], v[2:17], v79
	v_lshl_add_u64 v[2:3], v[70:71], 0, v[102:103]
	v_lshl_add_u64 v[2:3], v[2:3], 0, v[100:101]
	v_mov_b32_e32 v79, v35
	v_cmp_lt_i32_e32 vcc, 1, v199
	global_store_dwordx4 v[2:3], v[72:75], off offset:256
	global_store_dwordx4 v[2:3], v[76:79], off offset:272
	s_and_saveexec_b64 s[4:5], vcc
	s_xor_b64 s[4:5], exec, s[4:5]
	s_cbranch_execz .LBB0_1634
	v_cmp_gt_i32_e32 vcc, 3, v199
	s_and_saveexec_b64 s[56:57], vcc
	v_mov_b32_e32 v207, v204
	s_or_b64 exec, exec, s[56:57]

.LBB0_1640:
	s_or_b64 exec, exec, s[56:57]
	v_mul_f32_e32 v2, 0x3dd53b94, v207
	v_mul_f32_e32 v32, v2, v66
	v_mul_f32_e32 v33, v2, v67
	v_mul_f32_e32 v30, v2, v64
	v_mul_f32_e32 v31, v2, v65
	v_mul_f32_e32 v28, v2, v62
	v_mul_f32_e32 v29, v2, v63
	v_mul_f32_e32 v26, v2, v60
	v_mul_f32_e32 v27, v2, v61
	v_mul_f32_e32 v24, v2, v58
	v_mul_f32_e32 v25, v2, v59
	v_mul_f32_e32 v22, v2, v56
	v_mul_f32_e32 v23, v2, v57
	v_mul_f32_e32 v20, v2, v54
	v_mul_f32_e32 v21, v2, v55
	v_mul_f32_e32 v18, v2, v52
	v_mul_f32_e32 v19, v2, v53
	v_mul_f32_e32 v16, v2, v42
	v_mul_f32_e32 v17, v2, v43
	v_mul_f32_e32 v14, v2, v40
	v_mul_f32_e32 v15, v2, v41
	v_mul_f32_e32 v12, v2, v50
	v_mul_f32_e32 v13, v2, v51
	v_mul_f32_e32 v10, v2, v48
	v_mul_f32_e32 v11, v2, v49
	v_mul_f32_e32 v8, v2, v46
	v_mul_f32_e32 v9, v2, v47
	v_mul_f32_e32 v6, v2, v44
	v_mul_f32_e32 v7, v2, v45
	v_mul_f32_e32 v4, v2, v38
	v_mul_f32_e32 v5, v2, v39
	v_mul_f32_e32 v3, v2, v37
	v_mul_f32_e32 v2, v2, v36
	v_max_f32_e64 v36, |v18|, |v2|
	v_max_f32_e64 v37, |v19|, |v3|
	v_max3_f32 v36, v36, 0, v37
	v_max_f32_e64 v37, |v20|, |v4|
	v_max_f32_e64 v38, |v21|, |v5|
	v_max3_f32 v36, v36, v37, v38
	v_max_f32_e64 v37, |v22|, |v6|
	v_max_f32_e64 v38, |v23|, |v7|
	v_max3_f32 v36, v36, v37, v38
	v_max_f32_e64 v37, |v24|, |v8|
	v_max_f32_e64 v38, |v25|, |v9|
	v_max3_f32 v36, v36, v37, v38
	v_max_f32_e64 v37, |v26|, |v10|
	v_max_f32_e64 v38, |v27|, |v11|
	v_max3_f32 v36, v36, v37, v38
	v_max_f32_e64 v37, |v28|, |v12|
	v_max_f32_e64 v38, |v29|, |v13|
	v_max3_f32 v36, v36, v37, v38
	v_max_f32_e64 v37, |v30|, |v14|
	v_max_f32_e64 v38, |v31|, |v15|
	v_max3_f32 v36, v36, v37, v38
	v_max_f32_e64 v37, |v32|, |v16|
	v_max_f32_e64 v38, |v33|, |v17|
	v_max3_f32 v36, v36, v37, v38
	v_bfe_u32 v37, v36, 23, 8
	v_and_b32_e32 v36, 0x7fffff, v36
	v_cmp_gt_u32_e32 vcc, s1, v36
	v_add_u32_e32 v39, 0x80, v141
	v_mov_b32_e32 v49, v35
	v_cndmask_b32_e64 v36, -2, -3, vcc
	v_add3_u32 v36, v37, v36, s97
	v_max_i32_e32 v36, 0xffffff88, v36
	v_add_u32_e32 v36, 0x7f, v36
	v_lshlrev_b32_e32 v38, 23, v36
	v_mul_lo_u32 v48, v36, s3
	v_mov_b64_e32 v[36:37], s[22:23]
	v_mad_i64_i32 v[36:37], s[4:5], v39, s0, v[36:37]
	v_lshl_add_u64 v[36:37], v[68:69], 1, v[36:37]
	v_lshl_add_u64 v[50:51], v[36:37], 0, v[34:35]
	v_cvt_scalef32_2xpk16_fp6_f32 v[42:47], v[18:33], v[2:17], v38
	v_sub_u32_e32 v40, 0x7f000000, v38
	v_lshl_add_u64 v[50:51], v[50:51], 0, v[100:101]
	global_store_dwordx4 v[50:51], v[42:45], off offset:256
	global_store_dwordx4 v[50:51], v[46:49], off offset:272
	s_nop 0
	v_mul_f32_e32 v42, v18, v40
	v_mul_f32_e32 v43, v19, v40
	s_nop 0
	v_cmp_lt_f32_e64 vcc, |v42|, 4.0
	v_and_b32_e32 v34, 0x7fffffff, v42
	s_nop 0
	v_cndmask_b32_e32 v39, 0.5, v185, vcc
	v_cmp_nlt_f32_e64 vcc, |v42|, 2.0
	s_nop 1
	v_cndmask_b32_e32 v39, v197, v39, vcc
	v_cmp_lt_f32_e64 vcc, |v43|, 4.0
	v_and_b32_e32 v41, 0x7fffffff, v43
	v_sub_u32_e32 v44, 0x7f000000, v39
	v_mul_f32_e64 v34, |v42|, v44
	v_cndmask_b32_e32 v44, 0.5, v185, vcc
	v_cmp_nlt_f32_e64 vcc, |v43|, 2.0
	v_rndne_f32_e32 v34, v34
	v_mul_f32_e32 v34, v39, v34
	v_cndmask_b32_e32 v44, v197, v44, vcc
	v_min_f32_e32 v34, 0x40f00000, v34
	v_bfi_b32 v42, s10, v34, v42
	v_sub_u32_e32 v41, 0x7f000000, v44
	v_mul_f32_e64 v39, |v43|, v41
	v_rndne_f32_e32 v39, v39
	v_mul_f32_e32 v39, v44, v39
	v_mul_f32_e32 v44, v2, v40
	v_mul_f32_e32 v45, v3, v40
	v_min_f32_e32 v39, 0x40f00000, v39
	v_cmp_lt_f32_e64 vcc, |v44|, 4.0
	v_bfi_b32 v43, s10, v39, v43
	v_and_b32_e32 v39, 0x7fffffff, v44
	v_cndmask_b32_e32 v41, 0.5, v185, vcc
	v_cmp_nlt_f32_e64 vcc, |v44|, 2.0
	v_mul_f32_e32 v42, v42, v38
	v_mul_f32_e32 v43, v43, v38
	s_nop 0
	v_cndmask_b32_e32 v41, v197, v41, vcc
	v_fma_f32 v18, v18, 2.0, -v42
	v_fma_f32 v19, v19, 2.0, -v43
	v_cmp_lt_f32_e64 vcc, |v45|, 4.0
	v_and_b32_e32 v39, 0x7fffffff, v45
	v_sub_u32_e32 v42, 0x7f000000, v41
	v_mul_f32_e64 v34, |v44|, v42
	v_cndmask_b32_e32 v42, 0.5, v185, vcc
	v_cmp_nlt_f32_e64 vcc, |v45|, 2.0
	v_rndne_f32_e32 v34, v34
	v_mul_f32_e32 v34, v41, v34
	v_cndmask_b32_e32 v42, v197, v42, vcc
	v_min_f32_e32 v34, 0x40f00000, v34
	v_sub_u32_e32 v41, 0x7f000000, v42
	v_mul_f32_e64 v39, |v45|, v41
	v_rndne_f32_e32 v39, v39
	v_mul_f32_e32 v46, v20, v40
	v_mul_f32_e32 v47, v21, v40
	v_mul_f32_e32 v39, v42, v39
	v_cmp_lt_f32_e64 vcc, |v46|, 4.0
	v_min_f32_e32 v39, 0x40f00000, v39
	v_bfi_b32 v43, s10, v39, v45
	v_cndmask_b32_e32 v41, 0.5, v185, vcc
	v_cmp_nlt_f32_e64 vcc, |v46|, 2.0
	v_and_b32_e32 v39, 0x7fffffff, v46
	v_bfi_b32 v42, s10, v34, v44
	v_cndmask_b32_e32 v41, v197, v41, vcc
	v_mul_f32_e32 v42, v42, v38
	v_mul_f32_e32 v43, v43, v38
	v_fma_f32 v2, v2, 2.0, -v42
	v_fma_f32 v3, v3, 2.0, -v43
	v_cmp_lt_f32_e64 vcc, |v47|, 4.0
	v_and_b32_e32 v39, 0x7fffffff, v47
	v_sub_u32_e32 v42, 0x7f000000, v41
	v_mul_f32_e64 v34, |v46|, v42
	v_cndmask_b32_e32 v42, 0.5, v185, vcc
	v_cmp_nlt_f32_e64 vcc, |v47|, 2.0
	v_rndne_f32_e32 v34, v34
	v_mul_f32_e32 v34, v41, v34
	v_cndmask_b32_e32 v42, v197, v42, vcc
	v_min_f32_e32 v34, 0x40f00000, v34
	v_sub_u32_e32 v41, 0x7f000000, v42
	v_mul_f32_e64 v39, |v47|, v41
	v_rndne_f32_e32 v39, v39
	v_mul_f32_e32 v44, v4, v40
	v_mul_f32_e32 v45, v5, v40
	v_mul_f32_e32 v39, v42, v39
	v_cmp_lt_f32_e64 vcc, |v44|, 4.0
	v_min_f32_e32 v39, 0x40f00000, v39
	v_bfi_b32 v43, s10, v39, v47
	v_cndmask_b32_e32 v41, 0.5, v185, vcc
	v_cmp_nlt_f32_e64 vcc, |v44|, 2.0
	v_and_b32_e32 v39, 0x7fffffff, v44
	v_bfi_b32 v42, s10, v34, v46
	v_cndmask_b32_e32 v41, v197, v41, vcc
	v_mul_f32_e32 v42, v42, v38
	v_mul_f32_e32 v43, v43, v38
	v_fma_f32 v20, v20, 2.0, -v42
	v_fma_f32 v21, v21, 2.0, -v43
	v_cmp_lt_f32_e64 vcc, |v45|, 4.0
	v_and_b32_e32 v39, 0x7fffffff, v45
	v_sub_u32_e32 v42, 0x7f000000, v41
	v_mul_f32_e64 v34, |v44|, v42
	v_cndmask_b32_e32 v42, 0.5, v185, vcc
	v_cmp_nlt_f32_e64 vcc, |v45|, 2.0
	v_rndne_f32_e32 v34, v34
	v_mul_f32_e32 v34, v41, v34
	v_cndmask_b32_e32 v42, v197, v42, vcc
	v_min_f32_e32 v34, 0x40f00000, v34
	v_sub_u32_e32 v41, 0x7f000000, v42
	v_mul_f32_e64 v39, |v45|, v41
	v_rndne_f32_e32 v39, v39
	v_mul_f32_e32 v46, v22, v40
	v_mul_f32_e32 v47, v23, v40
	v_mul_f32_e32 v39, v42, v39
	v_cmp_lt_f32_e64 vcc, |v46|, 4.0
	v_min_f32_e32 v39, 0x40f00000, v39
	v_bfi_b32 v43, s10, v39, v45
	v_cndmask_b32_e32 v41, 0.5, v185, vcc
	v_cmp_nlt_f32_e64 vcc, |v46|, 2.0
	v_and_b32_e32 v39, 0x7fffffff, v46
	v_bfi_b32 v42, s10, v34, v44
	v_cndmask_b32_e32 v41, v197, v41, vcc
	v_mul_f32_e32 v42, v42, v38
	v_mul_f32_e32 v43, v43, v38
	v_fma_f32 v4, v4, 2.0, -v42
	v_fma_f32 v5, v5, 2.0, -v43
	v_cmp_lt_f32_e64 vcc, |v47|, 4.0
	v_and_b32_e32 v39, 0x7fffffff, v47
	v_sub_u32_e32 v42, 0x7f000000, v41
	v_mul_f32_e64 v34, |v46|, v42
	v_cndmask_b32_e32 v42, 0.5, v185, vcc
	v_cmp_nlt_f32_e64 vcc, |v47|, 2.0
	v_rndne_f32_e32 v34, v34
	v_mul_f32_e32 v34, v41, v34
	v_cndmask_b32_e32 v42, v197, v42, vcc
	v_min_f32_e32 v34, 0x40f00000, v34
	v_sub_u32_e32 v41, 0x7f000000, v42
	v_mul_f32_e64 v39, |v47|, v41
	v_rndne_f32_e32 v39, v39
	v_mul_f32_e32 v44, v6, v40
	v_mul_f32_e32 v45, v7, v40
	v_mul_f32_e32 v39, v42, v39
	v_cmp_lt_f32_e64 vcc, |v44|, 4.0
	v_min_f32_e32 v39, 0x40f00000, v39
	v_bfi_b32 v43, s10, v39, v47
	v_cndmask_b32_e32 v41, 0.5, v185, vcc
	v_cmp_nlt_f32_e64 vcc, |v44|, 2.0
	v_and_b32_e32 v39, 0x7fffffff, v44
	v_bfi_b32 v42, s10, v34, v46
	v_cndmask_b32_e32 v41, v197, v41, vcc
	v_mul_f32_e32 v42, v42, v38
	v_mul_f32_e32 v43, v43, v38
	v_fma_f32 v22, v22, 2.0, -v42
	v_fma_f32 v23, v23, 2.0, -v43
	v_cmp_lt_f32_e64 vcc, |v45|, 4.0
	v_and_b32_e32 v39, 0x7fffffff, v45
	v_sub_u32_e32 v42, 0x7f000000, v41
	v_mul_f32_e64 v34, |v44|, v42
	v_cndmask_b32_e32 v42, 0.5, v185, vcc
	v_cmp_nlt_f32_e64 vcc, |v45|, 2.0
	v_rndne_f32_e32 v34, v34
	v_mul_f32_e32 v34, v41, v34
	v_cndmask_b32_e32 v42, v197, v42, vcc
	v_min_f32_e32 v34, 0x40f00000, v34
	v_sub_u32_e32 v41, 0x7f000000, v42
	v_mul_f32_e64 v39, |v45|, v41
	v_rndne_f32_e32 v39, v39
	v_mul_f32_e32 v46, v24, v40
	v_mul_f32_e32 v47, v25, v40
	v_mul_f32_e32 v39, v42, v39
	v_cmp_lt_f32_e64 vcc, |v46|, 4.0
	v_min_f32_e32 v39, 0x40f00000, v39
	v_bfi_b32 v43, s10, v39, v45
	v_cndmask_b32_e32 v41, 0.5, v185, vcc
	v_cmp_nlt_f32_e64 vcc, |v46|, 2.0
	v_and_b32_e32 v39, 0x7fffffff, v46
	v_bfi_b32 v42, s10, v34, v44
	v_cndmask_b32_e32 v41, v197, v41, vcc
	v_mul_f32_e32 v42, v42, v38
	v_mul_f32_e32 v43, v43, v38
	v_fma_f32 v6, v6, 2.0, -v42
	v_fma_f32 v7, v7, 2.0, -v43
	v_cmp_lt_f32_e64 vcc, |v47|, 4.0
	v_and_b32_e32 v39, 0x7fffffff, v47
	v_sub_u32_e32 v42, 0x7f000000, v41
	v_mul_f32_e64 v34, |v46|, v42
	v_cndmask_b32_e32 v42, 0.5, v185, vcc
	v_cmp_nlt_f32_e64 vcc, |v47|, 2.0
	v_rndne_f32_e32 v34, v34
	v_mul_f32_e32 v34, v41, v34
	v_cndmask_b32_e32 v42, v197, v42, vcc
	v_min_f32_e32 v34, 0x40f00000, v34
	v_sub_u32_e32 v41, 0x7f000000, v42
	v_mul_f32_e64 v39, |v47|, v41
	v_rndne_f32_e32 v39, v39
	v_mul_f32_e32 v44, v8, v40
	v_mul_f32_e32 v45, v9, v40
	v_mul_f32_e32 v39, v42, v39
	v_cmp_lt_f32_e64 vcc, |v44|, 4.0
	v_min_f32_e32 v39, 0x40f00000, v39
	v_bfi_b32 v43, s10, v39, v47
	v_cndmask_b32_e32 v41, 0.5, v185, vcc
	v_cmp_nlt_f32_e64 vcc, |v44|, 2.0
	v_and_b32_e32 v39, 0x7fffffff, v44
	v_bfi_b32 v42, s10, v34, v46
	v_cndmask_b32_e32 v41, v197, v41, vcc
	v_mul_f32_e32 v42, v42, v38
	v_mul_f32_e32 v43, v43, v38
	v_fma_f32 v24, v24, 2.0, -v42
	v_fma_f32 v25, v25, 2.0, -v43
	v_cmp_lt_f32_e64 vcc, |v45|, 4.0
	v_and_b32_e32 v39, 0x7fffffff, v45
	v_sub_u32_e32 v42, 0x7f000000, v41
	v_mul_f32_e64 v34, |v44|, v42
	v_cndmask_b32_e32 v42, 0.5, v185, vcc
	v_cmp_nlt_f32_e64 vcc, |v45|, 2.0
	v_rndne_f32_e32 v34, v34
	v_mul_f32_e32 v34, v41, v34
	v_cndmask_b32_e32 v42, v197, v42, vcc
	v_min_f32_e32 v34, 0x40f00000, v34
	v_sub_u32_e32 v41, 0x7f000000, v42
	v_mul_f32_e64 v39, |v45|, v41
	v_rndne_f32_e32 v39, v39
	v_mul_f32_e32 v46, v26, v40
	v_mul_f32_e32 v47, v27, v40
	v_mul_f32_e32 v39, v42, v39
	v_cmp_lt_f32_e64 vcc, |v46|, 4.0
	v_min_f32_e32 v39, 0x40f00000, v39
	v_bfi_b32 v43, s10, v39, v45
	v_cndmask_b32_e32 v41, 0.5, v185, vcc
	v_cmp_nlt_f32_e64 vcc, |v46|, 2.0
	v_and_b32_e32 v39, 0x7fffffff, v46
	v_bfi_b32 v42, s10, v34, v44
	v_cndmask_b32_e32 v41, v197, v41, vcc
	v_mul_f32_e32 v42, v42, v38
	v_mul_f32_e32 v43, v43, v38
	v_fma_f32 v8, v8, 2.0, -v42
	v_fma_f32 v9, v9, 2.0, -v43
	v_cmp_lt_f32_e64 vcc, |v47|, 4.0
	v_and_b32_e32 v39, 0x7fffffff, v47
	v_sub_u32_e32 v42, 0x7f000000, v41
	v_mul_f32_e64 v34, |v46|, v42
	v_cndmask_b32_e32 v42, 0.5, v185, vcc
	v_cmp_nlt_f32_e64 vcc, |v47|, 2.0
	v_rndne_f32_e32 v34, v34
	v_mul_f32_e32 v34, v41, v34
	v_cndmask_b32_e32 v42, v197, v42, vcc
	v_min_f32_e32 v34, 0x40f00000, v34
	v_sub_u32_e32 v41, 0x7f000000, v42
	v_mul_f32_e64 v39, |v47|, v41
	v_rndne_f32_e32 v39, v39
	v_mul_f32_e32 v44, v10, v40
	v_mul_f32_e32 v45, v11, v40
	v_mul_f32_e32 v39, v42, v39
	v_cmp_lt_f32_e64 vcc, |v44|, 4.0
	v_min_f32_e32 v39, 0x40f00000, v39
	v_bfi_b32 v43, s10, v39, v47
	v_cndmask_b32_e32 v41, 0.5, v185, vcc
	v_cmp_nlt_f32_e64 vcc, |v44|, 2.0
	v_and_b32_e32 v39, 0x7fffffff, v44
	v_bfi_b32 v42, s10, v34, v46
	v_cndmask_b32_e32 v41, v197, v41, vcc
	v_mul_f32_e32 v42, v42, v38
	v_mul_f32_e32 v43, v43, v38
	v_fma_f32 v26, v26, 2.0, -v42
	v_fma_f32 v27, v27, 2.0, -v43
	v_cmp_lt_f32_e64 vcc, |v45|, 4.0
	v_and_b32_e32 v39, 0x7fffffff, v45
	v_sub_u32_e32 v42, 0x7f000000, v41
	v_mul_f32_e64 v34, |v44|, v42
	v_cndmask_b32_e32 v42, 0.5, v185, vcc
	v_cmp_nlt_f32_e64 vcc, |v45|, 2.0
	v_rndne_f32_e32 v34, v34
	v_mul_f32_e32 v34, v41, v34
	v_cndmask_b32_e32 v42, v197, v42, vcc
	v_min_f32_e32 v34, 0x40f00000, v34
	v_sub_u32_e32 v41, 0x7f000000, v42
	v_mul_f32_e64 v39, |v45|, v41
	v_rndne_f32_e32 v39, v39
	v_mul_f32_e32 v46, v28, v40
	v_mul_f32_e32 v47, v29, v40
	v_mul_f32_e32 v39, v42, v39
	v_cmp_lt_f32_e64 vcc, |v46|, 4.0
	v_min_f32_e32 v39, 0x40f00000, v39
	v_bfi_b32 v43, s10, v39, v45
	v_cndmask_b32_e32 v41, 0.5, v185, vcc
	v_cmp_nlt_f32_e64 vcc, |v46|, 2.0
	v_and_b32_e32 v39, 0x7fffffff, v46
	v_bfi_b32 v42, s10, v34, v44
	v_cndmask_b32_e32 v41, v197, v41, vcc
	v_mul_f32_e32 v42, v42, v38
	v_mul_f32_e32 v43, v43, v38
	v_fma_f32 v10, v10, 2.0, -v42
	v_fma_f32 v11, v11, 2.0, -v43
	v_cmp_lt_f32_e64 vcc, |v47|, 4.0
	v_and_b32_e32 v39, 0x7fffffff, v47
	v_sub_u32_e32 v42, 0x7f000000, v41
	v_mul_f32_e64 v34, |v46|, v42
	v_cndmask_b32_e32 v42, 0.5, v185, vcc
	v_cmp_nlt_f32_e64 vcc, |v47|, 2.0
	v_rndne_f32_e32 v34, v34
	v_mul_f32_e32 v34, v41, v34
	v_cndmask_b32_e32 v42, v197, v42, vcc
	v_min_f32_e32 v34, 0x40f00000, v34
	v_sub_u32_e32 v41, 0x7f000000, v42
	v_mul_f32_e64 v39, |v47|, v41
	v_rndne_f32_e32 v39, v39
	v_mul_f32_e32 v44, v12, v40
	v_mul_f32_e32 v45, v13, v40
	v_mul_f32_e32 v39, v42, v39
	v_cmp_lt_f32_e64 vcc, |v44|, 4.0
	v_min_f32_e32 v39, 0x40f00000, v39
	v_bfi_b32 v43, s10, v39, v47
	v_cndmask_b32_e32 v41, 0.5, v185, vcc
	v_cmp_nlt_f32_e64 vcc, |v44|, 2.0
	v_and_b32_e32 v39, 0x7fffffff, v44
	v_bfi_b32 v42, s10, v34, v46
	v_cndmask_b32_e32 v41, v197, v41, vcc
	v_mul_f32_e32 v42, v42, v38
	v_mul_f32_e32 v43, v43, v38
	v_fma_f32 v28, v28, 2.0, -v42
	v_fma_f32 v29, v29, 2.0, -v43
	v_cmp_lt_f32_e64 vcc, |v45|, 4.0
	v_and_b32_e32 v39, 0x7fffffff, v45
	v_sub_u32_e32 v42, 0x7f000000, v41
	v_mul_f32_e64 v34, |v44|, v42
	v_cndmask_b32_e32 v42, 0.5, v185, vcc
	v_cmp_nlt_f32_e64 vcc, |v45|, 2.0
	v_rndne_f32_e32 v34, v34
	v_mul_f32_e32 v34, v41, v34
	v_cndmask_b32_e32 v42, v197, v42, vcc
	v_min_f32_e32 v34, 0x40f00000, v34
	v_sub_u32_e32 v41, 0x7f000000, v42
	v_mul_f32_e64 v39, |v45|, v41
	v_rndne_f32_e32 v39, v39
	v_mul_f32_e32 v46, v30, v40
	v_mul_f32_e32 v47, v31, v40
	v_mul_f32_e32 v39, v42, v39
	v_cmp_lt_f32_e64 vcc, |v46|, 4.0
	v_min_f32_e32 v39, 0x40f00000, v39
	v_bfi_b32 v43, s10, v39, v45
	v_cndmask_b32_e32 v41, 0.5, v185, vcc
	v_cmp_nlt_f32_e64 vcc, |v46|, 2.0
	v_and_b32_e32 v39, 0x7fffffff, v46
	v_bfi_b32 v42, s10, v34, v44
	v_cndmask_b32_e32 v41, v197, v41, vcc
	v_mul_f32_e32 v42, v42, v38
	v_mul_f32_e32 v43, v43, v38
	v_fma_f32 v12, v12, 2.0, -v42
	v_fma_f32 v13, v13, 2.0, -v43
	v_cmp_lt_f32_e64 vcc, |v47|, 4.0
	v_and_b32_e32 v39, 0x7fffffff, v47
	v_sub_u32_e32 v42, 0x7f000000, v41
	v_mul_f32_e64 v34, |v46|, v42
	v_cndmask_b32_e32 v42, 0.5, v185, vcc
	v_cmp_nlt_f32_e64 vcc, |v47|, 2.0
	v_rndne_f32_e32 v34, v34
	v_mul_f32_e32 v34, v41, v34
	v_cndmask_b32_e32 v42, v197, v42, vcc
	v_min_f32_e32 v34, 0x40f00000, v34
	v_sub_u32_e32 v41, 0x7f000000, v42
	v_mul_f32_e64 v39, |v47|, v41
	v_rndne_f32_e32 v39, v39
	v_mul_f32_e32 v44, v14, v40
	v_mul_f32_e32 v45, v15, v40
	v_mul_f32_e32 v39, v42, v39
	v_cmp_lt_f32_e64 vcc, |v44|, 4.0
	v_min_f32_e32 v39, 0x40f00000, v39
	v_bfi_b32 v43, s10, v39, v47
	v_cndmask_b32_e32 v41, 0.5, v185, vcc
	v_cmp_nlt_f32_e64 vcc, |v44|, 2.0
	v_and_b32_e32 v39, 0x7fffffff, v44
	v_bfi_b32 v42, s10, v34, v46
	v_cndmask_b32_e32 v41, v197, v41, vcc
	v_mul_f32_e32 v42, v42, v38
	v_mul_f32_e32 v43, v43, v38
	v_fma_f32 v30, v30, 2.0, -v42
	v_fma_f32 v31, v31, 2.0, -v43
	v_cmp_lt_f32_e64 vcc, |v45|, 4.0
	v_and_b32_e32 v39, 0x7fffffff, v45
	v_sub_u32_e32 v42, 0x7f000000, v41
	v_mul_f32_e64 v34, |v44|, v42
	v_cndmask_b32_e32 v42, 0.5, v185, vcc
	v_cmp_nlt_f32_e64 vcc, |v45|, 2.0
	v_rndne_f32_e32 v34, v34
	v_mul_f32_e32 v34, v41, v34
	v_cndmask_b32_e32 v42, v197, v42, vcc
	v_min_f32_e32 v34, 0x40f00000, v34
	v_sub_u32_e32 v41, 0x7f000000, v42
	v_mul_f32_e64 v39, |v45|, v41
	v_rndne_f32_e32 v39, v39
	v_mul_f32_e32 v46, v32, v40
	v_mul_f32_e32 v47, v33, v40
	v_mul_f32_e32 v39, v42, v39
	v_cmp_lt_f32_e64 vcc, |v46|, 4.0
	v_min_f32_e32 v39, 0x40f00000, v39
	v_bfi_b32 v43, s10, v39, v45
	v_cndmask_b32_e32 v41, 0.5, v185, vcc
	v_cmp_nlt_f32_e64 vcc, |v46|, 2.0
	v_and_b32_e32 v39, 0x7fffffff, v46
	v_bfi_b32 v42, s10, v34, v44
	v_cndmask_b32_e32 v41, v197, v41, vcc
	v_mul_f32_e32 v42, v42, v38
	v_mul_f32_e32 v43, v43, v38
	v_fma_f32 v14, v14, 2.0, -v42
	v_fma_f32 v15, v15, 2.0, -v43
	v_cmp_lt_f32_e64 vcc, |v47|, 4.0
	v_and_b32_e32 v39, 0x7fffffff, v47
	v_sub_u32_e32 v42, 0x7f000000, v41
	v_mul_f32_e64 v34, |v46|, v42
	v_cndmask_b32_e32 v42, 0.5, v185, vcc
	v_cmp_nlt_f32_e64 vcc, |v47|, 2.0
	v_rndne_f32_e32 v34, v34
	v_mul_f32_e32 v34, v41, v34
	v_cndmask_b32_e32 v42, v197, v42, vcc
	v_min_f32_e32 v34, 0x40f00000, v34
	v_sub_u32_e32 v41, 0x7f000000, v42
	v_mul_f32_e64 v39, |v47|, v41
	v_rndne_f32_e32 v39, v39
	v_mul_f32_e32 v39, v42, v39
	v_min_f32_e32 v39, 0x40f00000, v39
	v_bfi_b32 v41, s10, v39, v47
	v_mul_f32_e32 v42, v16, v40
	v_mul_f32_e32 v43, v17, v40
	s_nop 0
	v_cmp_lt_f32_e64 vcc, |v42|, 4.0
	v_and_b32_e32 v39, 0x7fffffff, v42
	s_nop 0
	v_cndmask_b32_e32 v40, 0.5, v185, vcc
	v_cmp_nlt_f32_e64 vcc, |v42|, 2.0
	s_nop 1
	v_cndmask_b32_e32 v44, v197, v40, vcc
	v_bfi_b32 v40, s10, v34, v46
	v_mul_f32_e32 v40, v40, v38
	v_mul_f32_e32 v41, v41, v38
	v_fma_f32 v32, v32, 2.0, -v40
	v_fma_f32 v33, v33, 2.0, -v41
	v_cmp_lt_f32_e64 vcc, |v43|, 4.0
	v_and_b32_e32 v39, 0x7fffffff, v43
	v_sub_u32_e32 v40, 0x7f000000, v44
	v_mul_f32_e64 v34, |v42|, v40
	v_cndmask_b32_e32 v40, 0.5, v185, vcc
	v_cmp_nlt_f32_e64 vcc, |v43|, 2.0
	v_rndne_f32_e32 v34, v34
	v_mul_f32_e32 v34, v44, v34
	v_cndmask_b32_e32 v40, v197, v40, vcc
	v_min_f32_e32 v34, 0x40f00000, v34
	v_sub_u32_e32 v41, 0x7f000000, v40
	v_mul_f32_e64 v39, |v43|, v41
	v_rndne_f32_e32 v39, v39
	v_mul_f32_e32 v39, v40, v39
	v_min_f32_e32 v39, 0x40f00000, v39
	v_bfi_b32 v41, s10, v39, v43
	v_bfi_b32 v40, s10, v34, v42
	v_mul_f32_e32 v39, v41, v38
	v_mul_f32_e32 v38, v40, v38
	v_max_f32_e64 v34, |v18|, |v2|
	v_fma_f32 v16, v16, 2.0, -v38
	v_fma_f32 v17, v17, 2.0, -v39
	v_max_f32_e64 v38, |v19|, |v3|
	v_max3_f32 v34, v34, 0, v38
	v_max_f32_e64 v38, |v20|, |v4|
	v_max_f32_e64 v39, |v21|, |v5|
	v_max3_f32 v34, v34, v38, v39
	v_max_f32_e64 v38, |v22|, |v6|
	v_max_f32_e64 v39, |v23|, |v7|
	v_max3_f32 v34, v34, v38, v39
	v_max_f32_e64 v38, |v24|, |v8|
	v_max_f32_e64 v39, |v25|, |v9|
	v_max3_f32 v34, v34, v38, v39
	v_max_f32_e64 v38, |v26|, |v10|
	v_max_f32_e64 v39, |v27|, |v11|
	v_max3_f32 v34, v34, v38, v39
	v_max_f32_e64 v38, |v28|, |v12|
	v_max_f32_e64 v39, |v29|, |v13|
	v_max3_f32 v34, v34, v38, v39
	v_max_f32_e64 v38, |v30|, |v14|
	v_max_f32_e64 v39, |v31|, |v15|
	v_max3_f32 v34, v34, v38, v39
	v_max_f32_e64 v38, |v32|, |v16|
	v_max_f32_e64 v39, |v33|, |v17|
	v_max3_f32 v34, v34, v38, v39
	v_bfe_u32 v38, v34, 23, 8
	v_and_b32_e32 v34, 0x7fffff, v34
	v_cmp_gt_u32_e32 vcc, s1, v34
	s_nop 1
	v_cndmask_b32_e64 v34, -2, -3, vcc
	v_add3_u32 v34, v38, v34, s97
	v_max_i32_e32 v34, 0xffffff88, v34
	v_add_u32_e32 v34, 0x7f, v34
	v_lshlrev_b32_e32 v44, 23, v34
	v_cvt_scalef32_2xpk16_fp6_f32 v[38:43], v[18:33], v[2:17], v44
	v_lshl_add_u64 v[2:3], v[36:37], 0, v[102:103]
	v_mul_lo_u32 v34, v34, s3
	v_lshl_add_u64 v[2:3], v[2:3], 0, v[100:101]
	v_mov_b32_e32 v32, v42
	v_mov_b32_e32 v33, v43
	global_store_dwordx4 v[2:3], v[38:41], off offset:256
	global_store_dwordx4 v[2:3], v[32:35], off offset:272
	s_or_b64 exec, exec, s[6:7]
	s_cmp_eq_u32 s87, s92
	s_mov_b64 s[4:5], -1
	s_cbranch_scc1 .LBB0_1589

.LBB0_1654:
	v_mov_b32_e32 v136, v0
	s_lshl_b32 s9, s6, 8
	v_readlane_b32 s6, v254, 48
	s_add_i32 s9, s9, s6
	v_and_b32_e32 v34, 15, v136
	v_or_b32_e32 v146, s9, v34
	v_ashrrev_i32_e32 v147, 31, v146
	v_lshlrev_b64 v[138:139], 5, v[146:147]
	v_lshl_add_u64 v[144:145], s[18:19], 0, v[138:139]
	global_load_dwordx4 v[138:141], v[144:145], off
	global_load_dwordx4 v[156:159], v[144:145], off offset:16
	s_lshl_b32 s88, s7, 7
	v_bfe_u32 v155, v136, 4, 2
	v_lshl_or_b32 v136, v155, 3, s88
	v_or_b32_e32 v136, s26, v136
	v_ashrrev_i32_e32 v137, 31, v136
	v_lshlrev_b64 v[136:137], 14, v[136:137]
	v_or_b32_e32 v148, 16, v146
	v_ashrrev_i32_e32 v149, 31, v148
	v_lshlrev_b64 v[148:149], 5, v[148:149]
	v_lshl_add_u64 v[148:149], s[18:19], 0, v[148:149]
	v_permlane32_swap_b32_e32 v2, v18
	v_permlane32_swap_b32_e32 v3, v19
	v_permlane32_swap_b32_e32 v10, v26
	v_permlane32_swap_b32_e32 v11, v27
	v_permlane32_swap_b32_e32 v4, v20
	v_permlane32_swap_b32_e32 v5, v21
	v_permlane32_swap_b32_e32 v6, v22
	v_permlane32_swap_b32_e32 v7, v23
	v_permlane32_swap_b32_e32 v8, v24
	v_permlane32_swap_b32_e32 v9, v25
	v_permlane32_swap_b32_e32 v12, v28
	v_permlane32_swap_b32_e32 v13, v29
	v_permlane32_swap_b32_e32 v14, v30
	v_permlane32_swap_b32_e32 v15, v31
	v_permlane32_swap_b32_e32 v16, v32
	v_permlane32_swap_b32_e32 v17, v33
	v_permlane16_swap_b32_e32 v2, v10
	v_permlane16_swap_b32_e32 v3, v11
	v_permlane16_swap_b32_e32 v18, v26
	v_permlane16_swap_b32_e32 v19, v27
	v_permlane16_swap_b32_e32 v4, v12
	v_permlane16_swap_b32_e32 v5, v13
	v_permlane16_swap_b32_e32 v6, v14
	v_permlane16_swap_b32_e32 v7, v15
	v_permlane16_swap_b32_e32 v8, v16
	v_permlane16_swap_b32_e32 v9, v17
	v_permlane16_swap_b32_e32 v20, v28
	v_permlane16_swap_b32_e32 v21, v29
	v_permlane16_swap_b32_e32 v22, v30
	v_permlane16_swap_b32_e32 v23, v31
	v_permlane16_swap_b32_e32 v24, v32
	v_permlane16_swap_b32_e32 v25, v33
	s_ashr_i32 s89, s88, 31
	v_permlane32_swap_b32_e32 v36, v40
	v_permlane32_swap_b32_e32 v37, v41
	s_waitcnt vmcnt(0)
	v_add_f32_e32 v140, v140, v158
	v_add_f32_e32 v141, v141, v159
	v_add_f32_e32 v138, v138, v156
	v_add_f32_e32 v139, v139, v157
	v_permlane32_swap_b32_e32 v38, v42
	v_pk_mov_b32 v[142:143], v[138:139], v[140:141] op_sel:[1,0]
	v_mov_b32_e32 v139, v141
	v_add_f32_e32 v138, v142, v138
	v_add_f32_e32 v139, v143, v139
	v_permlane32_swap_b32_e32 v39, v43
	v_add_f32_e32 v138, v138, v139
	v_fmamk_f32 v138, v138, 0x3b800000, v153
	v_cmp_gt_f32_e32 vcc, s16, v138
	v_mul_f32_e32 v139, 0x4f800000, v138
	v_permlane32_swap_b32_e32 v44, v48
	v_cndmask_b32_e32 v138, v138, v139, vcc
	v_sqrt_f32_e32 v139, v138
	v_permlane32_swap_b32_e32 v45, v49
	v_permlane32_swap_b32_e32 v46, v50
	v_add_u32_e32 v140, -1, v139
	v_fma_f32 v141, -v140, v139, v138
	v_cmp_ge_f32_e64 s[6:7], 0, v141
	v_add_u32_e32 v141, 1, v139
	v_permlane32_swap_b32_e32 v47, v51
	v_cndmask_b32_e64 v140, v139, v140, s[6:7]
	v_fma_f32 v139, -v141, v139, v138
	v_cmp_lt_f32_e64 s[6:7], 0, v139
	v_permlane32_swap_b32_e32 v52, v56
	s_nop 0
	v_cndmask_b32_e64 v139, v140, v141, s[6:7]
	v_mul_f32_e32 v140, 0x37800000, v139
	v_cndmask_b32_e32 v139, v139, v140, vcc
	v_cmp_class_f32_e32 vcc, v138, v154
	v_permlane32_swap_b32_e32 v53, v57
	s_nop 0
	v_cndmask_b32_e32 v138, v139, v138, vcc
	v_div_scale_f32 v139, s[6:7], v138, v138, 1.0
	v_rcp_f32_e32 v140, v139
	s_mov_b32 s6, 0x10000
	v_permlane32_swap_b32_e32 v54, v58
	v_fma_f32 v141, -v139, v140, 1.0
	v_fmac_f32_e32 v140, v141, v140
	v_div_scale_f32 v141, vcc, 1.0, v138, 1.0
	v_mul_f32_e32 v142, v141, v140
	v_fma_f32 v143, -v139, v142, v141
	v_fmac_f32_e32 v142, v143, v140
	v_fma_f32 v139, -v139, v142, v141
	v_div_fmas_f32 v139, v139, v140, v142
	v_div_fixup_f32 v138, v139, v138, 1.0
	v_mul_f32_e32 v124, v124, v138
	v_mul_f32_e32 v125, v125, v138
	v_mov_b32_e32 v140, 0
	v_cvt_pk_fp8_f32 v140, v124, v125
	v_mul_f32_e32 v128, v128, v138
	v_mul_f32_e32 v129, v129, v138
	v_mov_b32_e32 v142, 0
	v_cvt_pk_fp8_f32 v142, v128, v129
	v_mul_f32_e32 v126, v126, v138
	v_mul_f32_e32 v127, v127, v138
	v_lshl_add_u64 v[124:125], s[20:21], 0, v[136:137]
	v_cvt_pk_fp8_f32 v140, v126, v127 op_sel:[0,0,1]
	v_lshl_add_u64 v[124:125], v[124:125], 0, v[146:147]
	v_mul_f32_e32 v130, v130, v138
	v_mul_f32_e32 v131, v131, v138
	v_add_co_u32_e32 v126, vcc, s6, v124
	v_cvt_pk_fp8_f32 v142, v130, v131 op_sel:[0,0,1]
	s_nop 0
	v_addc_co_u32_e32 v127, vcc, 0, v125, vcc
	s_movk_i32 s6, 0x4000
	v_add_co_u32_e32 v128, vcc, s6, v124
	v_lshrrev_b32_e32 v130, 8, v140
	s_nop 0
	v_addc_co_u32_e32 v129, vcc, 0, v125, vcc
	s_mov_b32 s6, 0x14000
	global_store_byte v[128:129], v130, off
	v_add_co_u32_e32 v130, vcc, s6, v124
	v_lshrrev_b32_e32 v136, 8, v142
	s_nop 0
	v_addc_co_u32_e32 v131, vcc, 0, v125, vcc
	s_mov_b32 s6, 0x8000
	global_store_byte v[130:131], v136, off
	v_add_co_u32_e32 v136, vcc, s6, v124
	s_mov_b32 s6, 0x18000
	s_nop 0
	v_addc_co_u32_e32 v137, vcc, 0, v125, vcc
	v_add_co_u32_e32 v138, vcc, s6, v124
	s_mov_b32 s6, 0xc000
	s_nop 0
	v_addc_co_u32_e32 v139, vcc, 0, v125, vcc
	global_store_byte v[124:125], v140, off
	global_store_byte_d16_hi v[136:137], v140, off
	v_lshrrev_b32_e32 v143, 24, v140
	v_add_co_u32_e32 v140, vcc, s6, v124
	s_mov_b32 s6, 0x1c000
	s_nop 0
	v_addc_co_u32_e32 v141, vcc, 0, v125, vcc
	global_store_byte v[126:127], v142, off
	global_store_byte_d16_hi v[138:139], v142, off
	v_lshrrev_b32_e32 v147, 24, v142
	v_add_co_u32_e32 v142, vcc, s6, v124
	global_store_byte v[140:141], v143, off
	s_nop 0
	v_addc_co_u32_e32 v143, vcc, 0, v125, vcc
	global_store_byte v[142:143], v147, off
	global_load_dwordx4 v[156:159], v[148:149], off
	global_load_dwordx4 v[160:163], v[148:149], off offset:16
	v_permlane32_swap_b32_e32 v55, v59
	v_permlane32_swap_b32_e32 v60, v64
	v_permlane32_swap_b32_e32 v61, v65
	v_permlane32_swap_b32_e32 v62, v66
	v_permlane32_swap_b32_e32 v63, v67
	v_permlane16_swap_b32_e32 v36, v52
	v_permlane16_swap_b32_e32 v37, v53
	v_permlane16_swap_b32_e32 v38, v54
	v_permlane16_swap_b32_e32 v39, v55
	v_permlane16_swap_b32_e32 v44, v60
	v_permlane16_swap_b32_e32 v45, v61
	v_permlane16_swap_b32_e32 v46, v62
	v_permlane16_swap_b32_e32 v47, v63
	v_permlane16_swap_b32_e32 v40, v56
	v_permlane16_swap_b32_e32 v41, v57
	v_permlane16_swap_b32_e32 v42, v58
	v_permlane16_swap_b32_e32 v43, v59
	v_permlane16_swap_b32_e32 v48, v64
	v_permlane16_swap_b32_e32 v49, v65
	v_permlane16_swap_b32_e32 v50, v66
	v_permlane16_swap_b32_e32 v51, v67
	s_cmp_eq_u32 s0, s50
	s_waitcnt vmcnt(0)
	v_add_f32_e32 v148, v158, v162
	v_add_f32_e32 v149, v159, v163
	v_add_f32_e32 v156, v156, v160
	v_add_f32_e32 v157, v157, v161
	s_nop 0
	v_pk_mov_b32 v[158:159], v[156:157], v[148:149] op_sel:[1,0]
	v_mov_b32_e32 v157, v149
	v_add_f32_e32 v148, v158, v156
	v_add_f32_e32 v149, v159, v157
	s_nop 0
	v_add_f32_e32 v147, v148, v149
	v_fmamk_f32 v147, v147, 0x3b800000, v153
	v_cmp_gt_f32_e32 vcc, s16, v147
	v_mul_f32_e32 v148, 0x4f800000, v147
	s_nop 0
	v_cndmask_b32_e32 v147, v147, v148, vcc
	v_sqrt_f32_e32 v148, v147
	s_nop 0
	v_add_u32_e32 v149, -1, v148
	v_fma_f32 v156, -v149, v148, v147
	v_cmp_ge_f32_e64 s[6:7], 0, v156
	v_add_u32_e32 v156, 1, v148
	s_nop 0
	v_cndmask_b32_e64 v149, v148, v149, s[6:7]
	v_fma_f32 v148, -v156, v148, v147
	v_cmp_lt_f32_e64 s[6:7], 0, v148
	s_nop 1
	v_cndmask_b32_e64 v148, v149, v156, s[6:7]
	v_mul_f32_e32 v149, 0x37800000, v148
	v_cndmask_b32_e32 v148, v148, v149, vcc
	v_cmp_class_f32_e32 vcc, v147, v154
	s_nop 1
	v_cndmask_b32_e32 v147, v148, v147, vcc
	v_div_scale_f32 v148, s[6:7], v147, v147, 1.0
	v_rcp_f32_e32 v149, v148
	s_nop 0
	v_fma_f32 v156, -v148, v149, 1.0
	v_fmac_f32_e32 v149, v156, v149
	v_div_scale_f32 v156, vcc, 1.0, v147, 1.0
	v_mul_f32_e32 v157, v156, v149
	v_fma_f32 v158, -v148, v157, v156
	v_fmac_f32_e32 v157, v158, v149
	v_fma_f32 v148, -v148, v157, v156
	v_div_fmas_f32 v148, v148, v149, v157
	v_div_fixup_f32 v148, v148, v147, 1.0
	v_mul_f32_e32 v116, v116, v148
	v_mul_f32_e32 v117, v117, v148
	v_mov_b32_e32 v147, 0
	v_mul_f32_e32 v120, v120, v148
	v_mul_f32_e32 v121, v121, v148
	v_cvt_pk_fp8_f32 v147, v116, v117
	v_mov_b32_e32 v116, 0
	v_cvt_pk_fp8_f32 v116, v120, v121
	v_mul_f32_e32 v118, v118, v148
	v_mul_f32_e32 v119, v119, v148
	v_mul_f32_e32 v122, v122, v148
	v_mul_f32_e32 v123, v123, v148
	v_cvt_pk_fp8_f32 v147, v118, v119 op_sel:[0,0,1]
	v_cvt_pk_fp8_f32 v116, v122, v123 op_sel:[0,0,1]
	global_store_byte v[124:125], v147, off offset:16
	global_store_byte v[126:127], v116, off offset:16
	v_lshrrev_b32_e32 v117, 8, v147
	global_store_byte v[128:129], v117, off offset:16
	v_lshrrev_b32_e32 v117, 8, v116
	global_store_byte v[130:131], v117, off offset:16
	global_store_byte_d16_hi v[136:137], v147, off offset:16
	global_store_byte_d16_hi v[138:139], v116, off offset:16
	v_lshrrev_b32_e32 v116, 24, v116
	v_lshrrev_b32_e32 v117, 24, v147
	global_store_byte v[142:143], v116, off offset:16
	v_or_b32_e32 v116, 32, v146
	global_store_byte v[140:141], v117, off offset:16
	v_ashrrev_i32_e32 v117, 31, v116
	v_lshlrev_b64 v[116:117], 5, v[116:117]
	v_lshl_add_u64 v[120:121], s[18:19], 0, v[116:117]
	global_load_dwordx4 v[116:119], v[120:121], off
	s_nop 0
	global_load_dwordx4 v[120:123], v[120:121], off offset:16
	s_waitcnt vmcnt(0)
	v_add_f32_e32 v118, v118, v122
	v_add_f32_e32 v119, v119, v123
	v_add_f32_e32 v116, v116, v120
	v_add_f32_e32 v117, v117, v121
	s_nop 0
	v_pk_mov_b32 v[120:121], v[116:117], v[118:119] op_sel:[1,0]
	v_mov_b32_e32 v117, v119
	v_add_f32_e32 v116, v120, v116
	v_add_f32_e32 v117, v121, v117
	s_nop 0
	v_add_f32_e32 v116, v116, v117
	v_fmamk_f32 v116, v116, 0x3b800000, v153
	v_cmp_gt_f32_e32 vcc, s16, v116
	v_mul_f32_e32 v117, 0x4f800000, v116
	s_nop 0
	v_cndmask_b32_e32 v116, v116, v117, vcc
	v_sqrt_f32_e32 v117, v116
	s_nop 0
	v_add_u32_e32 v118, -1, v117
	v_fma_f32 v119, -v118, v117, v116
	v_cmp_ge_f32_e64 s[6:7], 0, v119
	v_add_u32_e32 v119, 1, v117
	s_nop 0
	v_cndmask_b32_e64 v118, v117, v118, s[6:7]
	v_fma_f32 v117, -v119, v117, v116
	v_cmp_lt_f32_e64 s[6:7], 0, v117
	s_nop 1
	v_cndmask_b32_e64 v117, v118, v119, s[6:7]
	v_mul_f32_e32 v118, 0x37800000, v117
	v_cndmask_b32_e32 v117, v117, v118, vcc
	v_cmp_class_f32_e32 vcc, v116, v154
	s_nop 1
	v_cndmask_b32_e32 v116, v117, v116, vcc
	v_div_scale_f32 v117, s[6:7], v116, v116, 1.0
	v_rcp_f32_e32 v118, v117
	s_nop 0
	v_fma_f32 v119, -v117, v118, 1.0
	v_fmac_f32_e32 v118, v119, v118
	v_div_scale_f32 v119, vcc, 1.0, v116, 1.0
	v_mul_f32_e32 v120, v119, v118
	v_fma_f32 v121, -v117, v120, v119
	v_fmac_f32_e32 v120, v121, v118
	v_fma_f32 v117, -v117, v120, v119
	v_div_fmas_f32 v117, v117, v118, v120
	v_div_fixup_f32 v116, v117, v116, 1.0
	v_mul_f32_e32 v110, v110, v116
	v_mul_f32_e32 v111, v111, v116
	v_mul_f32_e32 v108, v108, v116
	v_mul_f32_e32 v109, v109, v116
	v_mul_f32_e32 v114, v114, v116
	v_mul_f32_e32 v115, v115, v116
	v_mul_f32_e32 v112, v112, v116
	v_mul_f32_e32 v113, v113, v116
	v_mov_b32_e32 v116, 0
	v_cvt_pk_fp8_f32 v116, v108, v109
	v_mov_b32_e32 v108, 0
	v_cvt_pk_fp8_f32 v108, v112, v113
	v_cvt_pk_fp8_f32 v116, v110, v111 op_sel:[0,0,1]
	v_cvt_pk_fp8_f32 v108, v114, v115 op_sel:[0,0,1]
	global_store_byte v[124:125], v116, off offset:32
	global_store_byte v[126:127], v108, off offset:32
	v_lshrrev_b32_e32 v109, 8, v116
	global_store_byte v[128:129], v109, off offset:32
	v_lshrrev_b32_e32 v109, 8, v108
	global_store_byte v[130:131], v109, off offset:32
	global_store_byte_d16_hi v[136:137], v116, off offset:32
	global_store_byte_d16_hi v[138:139], v108, off offset:32
	v_lshrrev_b32_e32 v108, 24, v108
	v_lshrrev_b32_e32 v109, 24, v116
	global_store_byte v[142:143], v108, off offset:32
	v_or_b32_e32 v108, 48, v146
	global_store_byte v[140:141], v109, off offset:32
	v_ashrrev_i32_e32 v109, 31, v108
	v_lshlrev_b64 v[108:109], 5, v[108:109]
	v_lshl_add_u64 v[112:113], s[18:19], 0, v[108:109]
	global_load_dwordx4 v[108:111], v[112:113], off
	s_nop 0
	global_load_dwordx4 v[112:115], v[112:113], off offset:16
	s_waitcnt vmcnt(0)
	v_add_f32_e32 v110, v110, v114
	v_add_f32_e32 v111, v111, v115
	v_add_f32_e32 v108, v108, v112
	v_add_f32_e32 v109, v109, v113
	s_nop 0
	v_pk_mov_b32 v[112:113], v[108:109], v[110:111] op_sel:[1,0]
	v_mov_b32_e32 v109, v111
	v_add_f32_e32 v108, v112, v108
	v_add_f32_e32 v109, v113, v109
	s_nop 0
	v_add_f32_e32 v108, v108, v109
	v_fmamk_f32 v108, v108, 0x3b800000, v153
	v_cmp_gt_f32_e32 vcc, s16, v108
	v_mul_f32_e32 v109, 0x4f800000, v108
	s_nop 0
	v_cndmask_b32_e32 v108, v108, v109, vcc
	v_sqrt_f32_e32 v109, v108
	s_nop 0
	v_add_u32_e32 v110, -1, v109
	v_fma_f32 v111, -v110, v109, v108
	v_cmp_ge_f32_e64 s[6:7], 0, v111
	v_add_u32_e32 v111, 1, v109
	s_nop 0
	v_cndmask_b32_e64 v110, v109, v110, s[6:7]
	v_fma_f32 v109, -v111, v109, v108
	v_cmp_lt_f32_e64 s[6:7], 0, v109
	s_nop 1
	v_cndmask_b32_e64 v109, v110, v111, s[6:7]
	v_mul_f32_e32 v110, 0x37800000, v109
	v_cndmask_b32_e32 v109, v109, v110, vcc
	v_cmp_class_f32_e32 vcc, v108, v154
	s_nop 1
	v_cndmask_b32_e32 v108, v109, v108, vcc
	v_div_scale_f32 v109, s[6:7], v108, v108, 1.0
	v_rcp_f32_e32 v110, v109
	s_mov_b64 s[6:7], 0x1000
	v_fma_f32 v111, -v109, v110, 1.0
	v_fmac_f32_e32 v110, v111, v110
	v_div_scale_f32 v111, vcc, 1.0, v108, 1.0
	v_mul_f32_e32 v112, v111, v110
	v_fma_f32 v113, -v109, v112, v111
	v_fmac_f32_e32 v112, v113, v110
	v_fma_f32 v109, -v109, v112, v111
	v_div_fmas_f32 v109, v109, v110, v112
	v_div_fixup_f32 v108, v109, v108, 1.0
	v_mul_f32_e32 v102, v102, v108
	v_mul_f32_e32 v103, v103, v108
	v_mul_f32_e32 v100, v100, v108
	v_mul_f32_e32 v101, v101, v108
	v_mul_f32_e32 v106, v106, v108
	v_mul_f32_e32 v107, v107, v108
	v_mul_f32_e32 v104, v104, v108
	v_mul_f32_e32 v105, v105, v108
	v_mov_b32_e32 v108, 0
	v_cvt_pk_fp8_f32 v108, v100, v101
	v_mov_b32_e32 v100, 0
	v_cvt_pk_fp8_f32 v100, v104, v105
	v_cvt_pk_fp8_f32 v108, v102, v103 op_sel:[0,0,1]
	v_cvt_pk_fp8_f32 v100, v106, v107 op_sel:[0,0,1]
	global_store_byte v[124:125], v108, off offset:48
	global_store_byte v[126:127], v100, off offset:48
	v_lshrrev_b32_e32 v101, 8, v108
	global_store_byte v[128:129], v101, off offset:48
	v_lshrrev_b32_e32 v101, 8, v100
	global_store_byte v[130:131], v101, off offset:48
	global_store_byte_d16_hi v[136:137], v108, off offset:48
	global_store_byte_d16_hi v[138:139], v100, off offset:48
	v_lshrrev_b32_e32 v100, 24, v100
	v_lshl_add_u64 v[106:107], v[144:145], 0, s[6:7]
	s_movk_i32 s6, 0x1000
	v_lshrrev_b32_e32 v101, 24, v108
	global_store_byte v[142:143], v100, off offset:48
	v_add_co_u32_e32 v100, vcc, s6, v144
	global_store_byte v[140:141], v101, off offset:48
	s_nop 0
	v_addc_co_u32_e32 v101, vcc, 0, v145, vcc
	global_load_dwordx4 v[102:105], v[100:101], off
	s_nop 0
	global_load_dwordx4 v[106:109], v[106:107], off offset:16
	s_waitcnt vmcnt(0)
	v_add_f32_e32 v104, v104, v108
	v_add_f32_e32 v105, v105, v109
	v_add_f32_e32 v102, v102, v106
	v_add_f32_e32 v103, v103, v107
	s_nop 0
	v_pk_mov_b32 v[106:107], v[102:103], v[104:105] op_sel:[1,0]
	v_mov_b32_e32 v103, v105
	v_add_f32_e32 v102, v106, v102
	v_add_f32_e32 v103, v107, v103
	s_nop 0
	v_add_f32_e32 v102, v102, v103
	v_fmamk_f32 v102, v102, 0x3b800000, v153
	v_cmp_gt_f32_e32 vcc, s16, v102
	v_mul_f32_e32 v103, 0x4f800000, v102
	s_nop 0
	v_cndmask_b32_e32 v102, v102, v103, vcc
	v_sqrt_f32_e32 v103, v102
	s_nop 0
	v_add_u32_e32 v104, -1, v103
	v_fma_f32 v105, -v104, v103, v102
	v_cmp_ge_f32_e64 s[6:7], 0, v105
	v_add_u32_e32 v105, 1, v103
	s_nop 0
	v_cndmask_b32_e64 v104, v103, v104, s[6:7]
	v_fma_f32 v103, -v105, v103, v102
	v_cmp_lt_f32_e64 s[6:7], 0, v103
	s_nop 1
	v_cndmask_b32_e64 v103, v104, v105, s[6:7]
	v_mul_f32_e32 v104, 0x37800000, v103
	v_cndmask_b32_e32 v103, v103, v104, vcc
	v_cmp_class_f32_e32 vcc, v102, v154
	s_nop 1
	v_cndmask_b32_e32 v102, v103, v102, vcc
	v_div_scale_f32 v103, s[6:7], v102, v102, 1.0
	v_rcp_f32_e32 v104, v103
	s_mov_b64 s[6:7], 0x1200
	v_fma_f32 v105, -v103, v104, 1.0
	v_fmac_f32_e32 v104, v105, v104
	v_div_scale_f32 v105, vcc, 1.0, v102, 1.0
	v_mul_f32_e32 v106, v105, v104
	v_fma_f32 v107, -v103, v106, v105
	v_fmac_f32_e32 v106, v107, v104
	v_fma_f32 v103, -v103, v106, v105
	v_div_fmas_f32 v103, v103, v104, v106
	v_div_fixup_f32 v102, v103, v102, 1.0
	v_mul_f32_e32 v104, v92, v102
	v_mul_f32_e32 v105, v93, v102
	v_mul_f32_e32 v92, v98, v102
	v_mul_f32_e32 v93, v99, v102
	v_mov_b32_e32 v98, 0
	v_cvt_pk_fp8_f32 v98, v104, v105
	v_mul_f32_e32 v94, v94, v102
	v_mul_f32_e32 v95, v95, v102
	v_mul_f32_e32 v96, v96, v102
	v_mul_f32_e32 v97, v97, v102
	v_cvt_pk_fp8_f32 v98, v94, v95 op_sel:[0,0,1]
	v_mov_b32_e32 v94, 0
	v_cvt_pk_fp8_f32 v94, v96, v97
	v_lshl_add_u64 v[96:97], v[144:145], 0, s[6:7]
	v_cvt_pk_fp8_f32 v94, v92, v93 op_sel:[0,0,1]
	v_lshrrev_b32_e32 v92, 8, v98
	global_store_byte v[124:125], v98, off offset:128
	global_store_byte v[126:127], v94, off offset:128
	global_store_byte v[128:129], v92, off offset:128
	v_lshrrev_b32_e32 v92, 8, v94
	global_store_byte v[130:131], v92, off offset:128
	global_store_byte_d16_hi v[136:137], v98, off offset:128
	global_store_byte_d16_hi v[138:139], v94, off offset:128
	v_lshrrev_b32_e32 v92, 24, v98
	global_store_byte v[140:141], v92, off offset:128
	v_lshrrev_b32_e32 v92, 24, v94
	global_store_byte v[142:143], v92, off offset:128
	global_load_dwordx4 v[92:95], v[100:101], off offset:512
	s_nop 0
	global_load_dwordx4 v[96:99], v[96:97], off offset:16
	s_waitcnt vmcnt(0)
	v_add_f32_e32 v94, v94, v98
	v_add_f32_e32 v95, v95, v99
	v_add_f32_e32 v92, v92, v96
	v_add_f32_e32 v93, v93, v97
	s_nop 0
	v_pk_mov_b32 v[96:97], v[92:93], v[94:95] op_sel:[1,0]
	v_mov_b32_e32 v93, v95
	v_add_f32_e32 v92, v96, v92
	v_add_f32_e32 v93, v97, v93
	s_nop 0
	v_add_f32_e32 v92, v92, v93
	v_fmamk_f32 v92, v92, 0x3b800000, v153
	v_cmp_gt_f32_e32 vcc, s16, v92
	v_mul_f32_e32 v93, 0x4f800000, v92
	s_nop 0
	v_cndmask_b32_e32 v92, v92, v93, vcc
	v_sqrt_f32_e32 v93, v92
	s_nop 0
	v_add_u32_e32 v94, -1, v93
	v_fma_f32 v95, -v94, v93, v92
	v_cmp_ge_f32_e64 s[6:7], 0, v95
	v_add_u32_e32 v95, 1, v93
	s_nop 0
	v_cndmask_b32_e64 v94, v93, v94, s[6:7]
	v_fma_f32 v93, -v95, v93, v92
	v_cmp_lt_f32_e64 s[6:7], 0, v93
	s_nop 1
	v_cndmask_b32_e64 v93, v94, v95, s[6:7]
	v_mul_f32_e32 v94, 0x37800000, v93
	v_cndmask_b32_e32 v93, v93, v94, vcc
	v_cmp_class_f32_e32 vcc, v92, v154
	s_nop 1
	v_cndmask_b32_e32 v92, v93, v92, vcc
	v_div_scale_f32 v93, s[6:7], v92, v92, 1.0
	v_rcp_f32_e32 v94, v93
	s_mov_b64 s[6:7], 0x1400
	v_fma_f32 v95, -v93, v94, 1.0
	v_fmac_f32_e32 v94, v95, v94
	v_div_scale_f32 v95, vcc, 1.0, v92, 1.0
	v_mul_f32_e32 v96, v95, v94
	v_fma_f32 v97, -v93, v96, v95
	v_fmac_f32_e32 v96, v97, v94
	v_fma_f32 v93, -v93, v96, v95
	v_div_fmas_f32 v93, v93, v94, v96
	v_div_fixup_f32 v92, v93, v92, 1.0
	v_mul_f32_e32 v94, v84, v92
	v_mul_f32_e32 v95, v85, v92
	v_mul_f32_e32 v84, v90, v92
	v_mul_f32_e32 v85, v91, v92
	v_mov_b32_e32 v90, 0
	v_cvt_pk_fp8_f32 v90, v94, v95
	v_mul_f32_e32 v86, v86, v92
	v_mul_f32_e32 v87, v87, v92
	v_mul_f32_e32 v88, v88, v92
	v_mul_f32_e32 v89, v89, v92
	v_cvt_pk_fp8_f32 v90, v86, v87 op_sel:[0,0,1]
	v_mov_b32_e32 v86, 0
	v_cvt_pk_fp8_f32 v86, v88, v89
	v_lshl_add_u64 v[88:89], v[144:145], 0, s[6:7]
	v_cvt_pk_fp8_f32 v86, v84, v85 op_sel:[0,0,1]
	v_lshrrev_b32_e32 v84, 8, v90
	global_store_byte v[124:125], v90, off offset:144
	global_store_byte v[126:127], v86, off offset:144
	global_store_byte v[128:129], v84, off offset:144
	v_lshrrev_b32_e32 v84, 8, v86
	global_store_byte v[130:131], v84, off offset:144
	global_store_byte_d16_hi v[136:137], v90, off offset:144
	global_store_byte_d16_hi v[138:139], v86, off offset:144
	v_lshrrev_b32_e32 v84, 24, v90
	global_store_byte v[140:141], v84, off offset:144
	v_lshrrev_b32_e32 v84, 24, v86
	global_store_byte v[142:143], v84, off offset:144
	global_load_dwordx4 v[84:87], v[100:101], off offset:1024
	s_nop 0
	global_load_dwordx4 v[88:91], v[88:89], off offset:16
	s_waitcnt vmcnt(0)
	v_add_f32_e32 v86, v86, v90
	v_add_f32_e32 v87, v87, v91
	v_add_f32_e32 v84, v84, v88
	v_add_f32_e32 v85, v85, v89
	s_nop 0
	v_pk_mov_b32 v[88:89], v[84:85], v[86:87] op_sel:[1,0]
	v_mov_b32_e32 v85, v87
	v_add_f32_e32 v84, v88, v84
	v_add_f32_e32 v85, v89, v85
	s_nop 0
	v_add_f32_e32 v84, v84, v85
	v_fmamk_f32 v84, v84, 0x3b800000, v153
	v_cmp_gt_f32_e32 vcc, s16, v84
	v_mul_f32_e32 v85, 0x4f800000, v84
	s_nop 0
	v_cndmask_b32_e32 v84, v84, v85, vcc
	v_sqrt_f32_e32 v85, v84
	s_nop 0
	v_add_u32_e32 v86, -1, v85
	v_fma_f32 v87, -v86, v85, v84
	v_cmp_ge_f32_e64 s[6:7], 0, v87
	v_add_u32_e32 v87, 1, v85
	s_nop 0
	v_cndmask_b32_e64 v86, v85, v86, s[6:7]
	v_fma_f32 v85, -v87, v85, v84
	v_cmp_lt_f32_e64 s[6:7], 0, v85
	s_nop 1
	v_cndmask_b32_e64 v85, v86, v87, s[6:7]
	v_mul_f32_e32 v86, 0x37800000, v85
	v_cndmask_b32_e32 v85, v85, v86, vcc
	v_cmp_class_f32_e32 vcc, v84, v154
	s_nop 1
	v_cndmask_b32_e32 v84, v85, v84, vcc
	v_div_scale_f32 v85, s[6:7], v84, v84, 1.0
	v_rcp_f32_e32 v86, v85
	s_mov_b64 s[6:7], 0x1600
	v_fma_f32 v87, -v85, v86, 1.0
	v_fmac_f32_e32 v86, v87, v86
	v_div_scale_f32 v87, vcc, 1.0, v84, 1.0
	v_mul_f32_e32 v88, v87, v86
	v_fma_f32 v89, -v85, v88, v87
	v_fmac_f32_e32 v88, v89, v86
	v_fma_f32 v85, -v85, v88, v87
	v_div_fmas_f32 v85, v85, v86, v88
	v_div_fixup_f32 v84, v85, v84, 1.0
	v_mul_f32_e32 v86, v76, v84
	v_mul_f32_e32 v87, v77, v84
	v_mul_f32_e32 v76, v82, v84
	v_mul_f32_e32 v77, v83, v84
	v_mov_b32_e32 v82, 0
	v_cvt_pk_fp8_f32 v82, v86, v87
	v_mul_f32_e32 v78, v78, v84
	v_mul_f32_e32 v79, v79, v84
	v_mul_f32_e32 v80, v80, v84
	v_mul_f32_e32 v81, v81, v84
	v_cvt_pk_fp8_f32 v82, v78, v79 op_sel:[0,0,1]
	v_mov_b32_e32 v78, 0
	v_cvt_pk_fp8_f32 v78, v80, v81
	v_lshl_add_u64 v[80:81], v[144:145], 0, s[6:7]
	v_cvt_pk_fp8_f32 v78, v76, v77 op_sel:[0,0,1]
	v_lshrrev_b32_e32 v76, 8, v82
	global_store_byte v[124:125], v82, off offset:160
	global_store_byte v[126:127], v78, off offset:160
	global_store_byte v[128:129], v76, off offset:160
	v_lshrrev_b32_e32 v76, 8, v78
	global_store_byte v[130:131], v76, off offset:160
	global_store_byte_d16_hi v[136:137], v82, off offset:160
	global_store_byte_d16_hi v[138:139], v78, off offset:160
	v_lshrrev_b32_e32 v76, 24, v82
	global_store_byte v[140:141], v76, off offset:160
	v_lshrrev_b32_e32 v76, 24, v78
	global_store_byte v[142:143], v76, off offset:160
	global_load_dwordx4 v[76:79], v[100:101], off offset:1536
	s_nop 0
	global_load_dwordx4 v[80:83], v[80:81], off offset:16
	s_waitcnt vmcnt(0)
	v_add_f32_e32 v78, v78, v82
	v_add_f32_e32 v79, v79, v83
	v_add_f32_e32 v76, v76, v80
	v_add_f32_e32 v77, v77, v81
	s_nop 0
	v_pk_mov_b32 v[80:81], v[76:77], v[78:79] op_sel:[1,0]
	v_mov_b32_e32 v77, v79
	v_add_f32_e32 v76, v80, v76
	v_add_f32_e32 v77, v81, v77
	s_nop 0
	v_add_f32_e32 v76, v76, v77
	v_fmamk_f32 v76, v76, 0x3b800000, v153
	v_cmp_gt_f32_e32 vcc, s16, v76
	v_mul_f32_e32 v77, 0x4f800000, v76
	s_nop 0
	v_cndmask_b32_e32 v76, v76, v77, vcc
	v_sqrt_f32_e32 v77, v76
	s_nop 0
	v_add_u32_e32 v78, -1, v77
	v_fma_f32 v79, -v78, v77, v76
	v_cmp_ge_f32_e64 s[6:7], 0, v79
	v_add_u32_e32 v79, 1, v77
	s_nop 0
	v_cndmask_b32_e64 v78, v77, v78, s[6:7]
	v_fma_f32 v77, -v79, v77, v76
	v_cmp_lt_f32_e64 s[6:7], 0, v77
	s_nop 1
	v_cndmask_b32_e64 v77, v78, v79, s[6:7]
	v_mul_f32_e32 v78, 0x37800000, v77
	v_cndmask_b32_e32 v77, v77, v78, vcc
	v_cmp_class_f32_e32 vcc, v76, v154
	s_nop 1
	v_cndmask_b32_e32 v76, v77, v76, vcc
	v_div_scale_f32 v77, s[6:7], v76, v76, 1.0
	v_rcp_f32_e32 v78, v77
	s_nop 0
	v_fma_f32 v79, -v77, v78, 1.0
	v_fmac_f32_e32 v78, v79, v78
	v_div_scale_f32 v79, vcc, 1.0, v76, 1.0
	v_mul_f32_e32 v80, v79, v78
	v_fma_f32 v81, -v77, v80, v79
	v_fmac_f32_e32 v80, v81, v78
	v_fma_f32 v77, -v77, v80, v79
	v_div_fmas_f32 v77, v77, v78, v80
	v_div_fixup_f32 v76, v77, v76, 1.0
	v_mul_f32_e32 v70, v70, v76
	v_mul_f32_e32 v71, v71, v76
	v_mul_f32_e32 v68, v68, v76
	v_mul_f32_e32 v69, v69, v76
	v_mul_f32_e32 v74, v74, v76
	v_mul_f32_e32 v75, v75, v76
	v_mul_f32_e32 v72, v72, v76
	v_mul_f32_e32 v73, v73, v76
	v_mov_b32_e32 v76, 0
	v_cvt_pk_fp8_f32 v76, v68, v69
	v_mov_b32_e32 v68, 0
	v_cvt_pk_fp8_f32 v68, v72, v73
	v_cvt_pk_fp8_f32 v76, v70, v71 op_sel:[0,0,1]
	v_cvt_pk_fp8_f32 v68, v74, v75 op_sel:[0,0,1]
	global_store_byte v[124:125], v76, off offset:176
	global_store_byte v[126:127], v68, off offset:176
	v_lshrrev_b32_e32 v69, 8, v76
	global_store_byte v[128:129], v69, off offset:176
	v_lshrrev_b32_e32 v69, 8, v68
	global_store_byte v[130:131], v69, off offset:176
	global_store_byte_d16_hi v[136:137], v76, off offset:176
	global_store_byte_d16_hi v[138:139], v68, off offset:176
	v_lshrrev_b32_e32 v68, 24, v68
	global_store_byte v[142:143], v68, off offset:176
	v_lshlrev_b32_e32 v68, 4, v155
	v_lshrrev_b32_e32 v69, 24, v76
	v_or3_b32 v68, v68, s9, v34
	global_store_byte v[140:141], v69, off offset:176
	v_ashrrev_i32_e32 v69, 31, v68
	v_lshlrev_b64 v[70:71], 5, v[68:69]
	v_lshl_add_u64 v[74:75], s[18:19], 0, v[70:71]
	global_load_dwordx4 v[70:73], v[74:75], off
	s_nop 0
	global_load_dwordx4 v[74:77], v[74:75], off offset:16
	s_waitcnt vmcnt(0)
	v_add_f32_e32 v72, v72, v76
	v_add_f32_e32 v73, v73, v77
	v_add_f32_e32 v70, v70, v74
	v_add_f32_e32 v71, v71, v75
	s_nop 0
	v_pk_mov_b32 v[74:75], v[70:71], v[72:73] op_sel:[1,0]
	v_mov_b32_e32 v71, v73
	v_add_f32_e32 v70, v74, v70
	v_add_f32_e32 v71, v75, v71
	s_nop 0
	v_add_f32_e32 v34, v70, v71
	v_fmamk_f32 v34, v34, 0x3b800000, v153
	v_cmp_gt_f32_e32 vcc, s16, v34
	v_mul_f32_e32 v70, 0x4f800000, v34
	s_nop 0
	v_cndmask_b32_e32 v34, v34, v70, vcc
	v_sqrt_f32_e32 v70, v34
	s_nop 0
	v_add_u32_e32 v71, -1, v70
	v_fma_f32 v72, -v71, v70, v34
	v_cmp_ge_f32_e64 s[6:7], 0, v72
	v_add_u32_e32 v72, 1, v70
	s_nop 0
	v_cndmask_b32_e64 v71, v70, v71, s[6:7]
	v_fma_f32 v70, -v72, v70, v34
	v_cmp_lt_f32_e64 s[6:7], 0, v70
	s_nop 1
	v_cndmask_b32_e64 v70, v71, v72, s[6:7]
	v_mul_f32_e32 v71, 0x37800000, v70
	v_cndmask_b32_e32 v70, v70, v71, vcc
	v_cmp_class_f32_e32 vcc, v34, v154
	s_nop 1
	v_cndmask_b32_e32 v34, v70, v34, vcc
	v_div_scale_f32 v70, s[6:7], v34, v34, 1.0
	v_rcp_f32_e32 v71, v70
	s_nop 0
	v_fma_f32 v72, -v70, v71, 1.0
	v_fmac_f32_e32 v71, v72, v71
	v_div_scale_f32 v72, vcc, 1.0, v34, 1.0
	v_mul_f32_e32 v73, v72, v71
	v_fma_f32 v74, -v70, v73, v72
	v_fmac_f32_e32 v73, v74, v71
	v_fma_f32 v70, -v70, v73, v72
	v_div_fmas_f32 v70, v70, v71, v73
	v_div_fixup_f32 v34, v70, v34, 1.0
	v_mul_f32_e32 v2, v34, v2
	v_mul_f32_e32 v3, v34, v3
	v_mul_f32_e32 v18, v34, v18
	v_mul_f32_e32 v19, v34, v19
	v_mul_f32_e32 v16, v34, v16
	v_mul_f32_e32 v17, v34, v17
	v_mul_f32_e32 v14, v34, v14
	v_mul_f32_e32 v15, v34, v15
	v_mul_f32_e32 v12, v34, v12
	v_mul_f32_e32 v13, v34, v13
	v_mul_f32_e32 v10, v34, v10
	v_mul_f32_e32 v11, v34, v11
	v_mul_f32_e32 v8, v34, v8
	v_mul_f32_e32 v9, v34, v9
	v_mul_f32_e32 v6, v34, v6
	v_mul_f32_e32 v7, v34, v7
	v_mul_f32_e32 v4, v34, v4
	v_mul_f32_e32 v5, v34, v5
	v_mul_f32_e32 v32, v34, v32
	v_mul_f32_e32 v33, v34, v33
	v_mul_f32_e32 v30, v34, v30
	v_mul_f32_e32 v31, v34, v31
	v_mul_f32_e32 v28, v34, v28
	v_mul_f32_e32 v29, v34, v29
	v_mul_f32_e32 v26, v34, v26
	v_mul_f32_e32 v27, v34, v27
	v_mul_f32_e32 v24, v34, v24
	v_mul_f32_e32 v25, v34, v25
	v_mul_f32_e32 v22, v34, v22
	v_mul_f32_e32 v23, v34, v23
	v_mul_f32_e32 v20, v34, v20
	v_mul_f32_e32 v21, v34, v21
	v_max_f32_e64 v34, |v2|, |v18|
	v_max_f32_e64 v70, |v3|, |v19|
	v_max3_f32 v34, v34, 0, v70
	v_max_f32_e64 v70, |v4|, |v20|
	v_max_f32_e64 v71, |v5|, |v21|
	v_max3_f32 v34, v34, v70, v71
	v_max_f32_e64 v70, |v6|, |v22|
	v_max_f32_e64 v71, |v7|, |v23|
	v_max3_f32 v34, v34, v70, v71
	v_max_f32_e64 v70, |v8|, |v24|
	v_max_f32_e64 v71, |v9|, |v25|
	v_max3_f32 v34, v34, v70, v71
	v_max_f32_e64 v70, |v10|, |v26|
	v_max_f32_e64 v71, |v11|, |v27|
	v_max3_f32 v34, v34, v70, v71
	v_max_f32_e64 v70, |v12|, |v28|
	v_max_f32_e64 v71, |v13|, |v29|
	v_max3_f32 v34, v34, v70, v71
	v_max_f32_e64 v70, |v14|, |v30|
	v_max_f32_e64 v71, |v15|, |v31|
	v_max3_f32 v34, v34, v70, v71
	v_max_f32_e64 v70, |v16|, |v32|
	v_max_f32_e64 v71, |v17|, |v33|
	v_max3_f32 v34, v34, v70, v71
	v_bfe_u32 v70, v34, 23, 8
	v_and_b32_e32 v34, 0x7fffff, v34
	v_cmp_gt_u32_e32 vcc, s17, v34
	s_nop 1
	v_cndmask_b32_e64 v34, -2, -3, vcc
	v_add3_u32 v34, v70, v34, s2
	v_max_i32_e32 v34, 0xffffff88, v34
	v_add_u32_e32 v34, 0x7f, v34
	v_lshlrev_b32_e32 v76, 23, v34
	v_cvt_scalef32_2xpk16_fp6_f32 v[70:75], v[2:17], v[18:33], v76
	v_lshlrev_b64 v[2:3], 10, v[68:69]
	v_lshl_add_u64 v[2:3], s[22:23], 0, v[2:3]
	v_lshl_add_u64 v[2:3], v[2:3], 0, s[88:89]
	v_add_u32_e32 v68, 0x80, v68
	v_mul_lo_u32 v34, v34, s40
	v_lshl_add_u64 v[2:3], v[2:3], 0, s[26:27]
	v_mov_b32_e32 v32, v74
	v_mov_b32_e32 v33, v75
	v_ashrrev_i32_e32 v69, 31, v68
	global_store_dwordx4 v[2:3], v[70:73], off
	global_store_dwordx4 v[2:3], v[32:35], off offset:16
	v_lshlrev_b64 v[2:3], 5, v[68:69]
	v_lshl_add_u64 v[2:3], s[18:19], 0, v[2:3]
	global_load_dwordx4 v[4:7], v[2:3], off
	global_load_dwordx4 v[8:11], v[2:3], off offset:16
	s_waitcnt vmcnt(0)
	v_add_f32_e32 v2, v6, v10
	v_add_f32_e32 v3, v7, v11
	v_add_f32_e32 v4, v4, v8
	v_add_f32_e32 v5, v5, v9
	s_nop 0
	v_pk_mov_b32 v[6:7], v[4:5], v[2:3] op_sel:[1,0]
	v_mov_b32_e32 v5, v3
	v_add_f32_e32 v2, v6, v4
	v_add_f32_e32 v3, v7, v5
	s_nop 0
	v_add_f32_e32 v2, v2, v3
	v_fmamk_f32 v2, v2, 0x3b800000, v153
	v_cmp_gt_f32_e32 vcc, s16, v2
	v_mul_f32_e32 v3, 0x4f800000, v2
	s_nop 0
	v_cndmask_b32_e32 v2, v2, v3, vcc
	v_sqrt_f32_e32 v3, v2
	s_nop 0
	v_add_u32_e32 v4, -1, v3
	v_fma_f32 v5, -v4, v3, v2
	v_cmp_ge_f32_e64 s[6:7], 0, v5
	v_add_u32_e32 v5, 1, v3
	s_nop 0
	v_cndmask_b32_e64 v4, v3, v4, s[6:7]
	v_fma_f32 v3, -v5, v3, v2
	v_cmp_lt_f32_e64 s[6:7], 0, v3
	s_nop 1
	v_cndmask_b32_e64 v3, v4, v5, s[6:7]
	v_mul_f32_e32 v4, 0x37800000, v3
	v_cndmask_b32_e32 v3, v3, v4, vcc
	v_cmp_class_f32_e32 vcc, v2, v154
	s_nop 1
	v_cndmask_b32_e32 v2, v3, v2, vcc
	v_div_scale_f32 v3, s[6:7], v2, v2, 1.0
	v_rcp_f32_e32 v4, v3
	s_mov_b64 s[6:7], -1
	v_fma_f32 v5, -v3, v4, 1.0
	v_fmac_f32_e32 v4, v5, v4
	v_div_scale_f32 v5, vcc, 1.0, v2, 1.0
	v_mul_f32_e32 v6, v5, v4
	v_fma_f32 v7, -v3, v6, v5
	v_fmac_f32_e32 v6, v7, v4
	v_fma_f32 v3, -v3, v6, v5
	v_div_fmas_f32 v3, v3, v4, v6
	v_div_fixup_f32 v18, v3, v2, 1.0
	v_mul_f32_e32 v16, v18, v62
	v_mul_f32_e32 v17, v18, v63
	v_mul_f32_e32 v14, v18, v60
	v_mul_f32_e32 v15, v18, v61
	v_mul_f32_e32 v12, v18, v54
	v_mul_f32_e32 v13, v18, v55
	v_mul_f32_e32 v10, v18, v52
	v_mul_f32_e32 v11, v18, v53
	v_mul_f32_e32 v8, v18, v46
	v_mul_f32_e32 v9, v18, v47
	v_mul_f32_e32 v6, v18, v44
	v_mul_f32_e32 v7, v18, v45
	v_mul_f32_e32 v4, v18, v38
	v_mul_f32_e32 v5, v18, v39
	v_mul_f32_e32 v2, v18, v36
	v_mul_f32_e32 v3, v18, v37
	v_mul_f32_e32 v32, v18, v66
	v_mul_f32_e32 v33, v18, v67
	v_mul_f32_e32 v30, v18, v64
	v_mul_f32_e32 v31, v18, v65
	v_mul_f32_e32 v28, v18, v58
	v_mul_f32_e32 v29, v18, v59
	v_mul_f32_e32 v26, v18, v56
	v_mul_f32_e32 v27, v18, v57
	v_mul_f32_e32 v24, v18, v50
	v_mul_f32_e32 v25, v18, v51
	v_mul_f32_e32 v22, v18, v48
	v_mul_f32_e32 v23, v18, v49
	v_mul_f32_e32 v20, v18, v42
	v_mul_f32_e32 v21, v18, v43
	v_mul_f32_e32 v19, v18, v41
	v_mul_f32_e32 v18, v18, v40
	v_max_f32_e64 v34, |v2|, |v18|
	v_max_f32_e64 v36, |v3|, |v19|
	v_max3_f32 v34, v34, 0, v36
	v_max_f32_e64 v36, |v4|, |v20|
	v_max_f32_e64 v37, |v5|, |v21|
	v_max3_f32 v34, v34, v36, v37
	v_max_f32_e64 v36, |v6|, |v22|
	v_max_f32_e64 v37, |v7|, |v23|
	v_max3_f32 v34, v34, v36, v37
	v_max_f32_e64 v36, |v8|, |v24|
	v_max_f32_e64 v37, |v9|, |v25|
	v_max3_f32 v34, v34, v36, v37
	v_max_f32_e64 v36, |v10|, |v26|
	v_max_f32_e64 v37, |v11|, |v27|
	v_max3_f32 v34, v34, v36, v37
	v_max_f32_e64 v36, |v12|, |v28|
	v_max_f32_e64 v37, |v13|, |v29|
	v_max3_f32 v34, v34, v36, v37
	v_max_f32_e64 v36, |v14|, |v30|
	v_max_f32_e64 v37, |v15|, |v31|
	v_max3_f32 v34, v34, v36, v37
	v_max_f32_e64 v36, |v16|, |v32|
	v_max_f32_e64 v37, |v17|, |v33|
	v_max3_f32 v34, v34, v36, v37
	v_bfe_u32 v36, v34, 23, 8
	v_and_b32_e32 v34, 0x7fffff, v34
	v_cmp_gt_u32_e32 vcc, s17, v34
	s_nop 1
	v_cndmask_b32_e64 v34, -2, -3, vcc
	v_add3_u32 v34, v36, v34, s2
	v_max_i32_e32 v34, 0xffffff88, v34
	v_add_u32_e32 v34, 0x7f, v34
	v_lshlrev_b32_e32 v42, 23, v34
	v_cvt_scalef32_2xpk16_fp6_f32 v[36:41], v[2:17], v[18:33], v42
	v_lshlrev_b64 v[2:3], 10, v[68:69]
	v_lshl_add_u64 v[2:3], s[22:23], 0, v[2:3]
	v_lshl_add_u64 v[2:3], v[2:3], 0, s[88:89]
	v_mul_lo_u32 v34, v34, s40
	v_lshl_add_u64 v[2:3], v[2:3], 0, s[26:27]
	v_mov_b32_e32 v32, v40
	v_mov_b32_e32 v33, v41
	global_store_dwordx4 v[2:3], v[36:39], off
	global_store_dwordx4 v[2:3], v[32:35], off offset:16
	s_cbranch_scc1 .LBB0_1649
	v_readlane_b32 s6, v254, 50
	v_readlane_b32 s7, v254, 51
	s_andn2_b64 vcc, exec, s[6:7]
	s_cbranch_vccnz .LBB0_1648
	s_barrier
	s_branch .LBB0_1648

.LBB0_1747:
	v_add_f32_e32 v82, 0, v114
	v_add_f32_e32 v84, 0, v115
	v_add_f32_e32 v85, 0, v116
	v_add_f32_e32 v86, 0, v117
	v_add_f32_e32 v87, v118, v82
	s_lshl_b64 s[8:9], s[48:49], 20
	v_cvt_pk_fp8_f32 v82, v114, v115
	v_cvt_pk_fp8_f32 v83, v50, v51
	s_add_u32 s5, s42, s8
	s_addc_u32 s10, s43, s9
	v_cvt_pk_fp8_f32 v82, v116, v117 op_sel:[0,0,1]
	v_cvt_pk_fp8_f32 v83, v52, v53 op_sel:[0,0,1]
	s_lshl_b64 s[8:9], s[52:53], 1
	s_add_u32 s8, s5, s8
	v_add_f32_e32 v90, v99, v100
	v_permlane32_swap_b32_e32 v82, v83
	s_addc_u32 s9, s10, s9
	v_fmac_f32_e32 v90, v195, v138
	v_add_f32_e32 v84, v119, v84
	v_add_f32_e32 v85, v120, v85
	v_add_f32_e32 v86, v121, v86
	v_add_f32_e32 v87, v122, v87
	v_add_f32_e32 v84, v123, v84
	s_nop 0
	v_add_f32_e32 v85, v124, v85
	v_add_f32_e32 v86, v125, v86
	v_add_f32_e32 v87, v126, v87
	v_add_f32_e32 v88, v127, v84
	v_add_f32_e32 v89, v128, v85
	v_add_f32_e32 v86, v129, v86
	s_nop 0
	v_cvt_pk_fp8_f32 v84, v118, v119
	v_cvt_pk_fp8_f32 v85, v54, v55
	v_cvt_pk_fp8_f32 v84, v120, v121 op_sel:[0,0,1]
	v_cvt_pk_fp8_f32 v85, v56, v57 op_sel:[0,0,1]
	s_nop 1
	v_permlane32_swap_b32_e32 v84, v85
	v_add_f32_e32 v50, v50, v87
	v_add_f32_e32 v51, v51, v88
	v_add_f32_e32 v52, v52, v89
	v_add_f32_e32 v53, v53, v86
	v_add_f32_e32 v50, v54, v50
	s_nop 0
	v_cvt_pk_fp8_f32 v86, v122, v123
	v_cvt_pk_fp8_f32 v87, v58, v59
	v_cvt_pk_fp8_f32 v86, v124, v125 op_sel:[0,0,1]
	v_cvt_pk_fp8_f32 v87, v60, v61 op_sel:[0,0,1]
	s_nop 1
	v_permlane32_swap_b32_e32 v86, v87
	v_add_f32_e32 v51, v55, v51
	v_add_f32_e32 v52, v56, v52
	v_add_f32_e32 v53, v57, v53
	v_add_f32_e32 v50, v58, v50
	v_add_f32_e32 v51, v59, v51
	s_nop 0
	v_add_f32_e32 v52, v60, v52
	v_add_f32_e32 v53, v61, v53
	v_add_f32_e32 v58, v62, v50
	v_add_f32_e32 v60, v63, v51
	v_add_f32_e32 v59, v64, v52
	v_add_f32_e32 v61, v65, v53
	s_nop 0
	v_cvt_pk_fp8_f32 v88, v126, v127
	v_cvt_pk_fp8_f32 v89, v62, v63
	v_cvt_pk_fp8_f32 v88, v128, v129 op_sel:[0,0,1]
	v_cvt_pk_fp8_f32 v89, v64, v65 op_sel:[0,0,1]
	s_nop 1
	v_permlane32_swap_b32_e32 v88, v89
	v_add_u32_e32 v62, s4, v191
	ds_read_b128 v[50:53], v62
	ds_read_b128 v[54:57], v62 offset:16
	v_add_f32_e32 v58, v58, v60
	v_add_f32_e32 v59, v59, v61
	s_waitcnt lgkmcnt(0)
	v_mfma_scale_f32_32x32x64_f8f6f4 v[66:81], v[50:57], v[82:89], v[66:81], v220, v220 op_sel_hi:[0,0,0]
	v_pk_add_f32 v[58:59], v[58:59], v[58:59] op_sel:[0,1] op_sel_hi:[1,0]
	s_nop 0
	v_mov_b32_e32 v59, v58
	s_nop 1
	v_permlane32_swap_b32_e32 v58, v59
	v_add_f32_e32 v58, v58, v59
	v_fmac_f32_e32 v58, v90, v98
	ds_read_b128 v[50:53], v62 offset:2560
	ds_read_b128 v[54:57], v62 offset:2576
	s_waitcnt lgkmcnt(0)
	v_mfma_scale_f32_32x32x64_f8f6f4 v[34:49], v[50:57], v[82:89], v[34:49], v220, v220 op_sel_hi:[0,0,0]
	ds_read_b128 v[50:53], v62 offset:5120
	ds_read_b128 v[54:57], v62 offset:5136
	s_waitcnt lgkmcnt(0)
	v_mfma_scale_f32_32x32x64_f8f6f4 v[18:33], v[50:57], v[82:89], v[18:33], v220, v220 op_sel_hi:[0,0,0]
	ds_read_b128 v[50:53], v62 offset:7680
	ds_read_b128 v[54:57], v62 offset:7696
	s_waitcnt lgkmcnt(0)
	v_mfma_scale_f32_32x32x64_f8f6f4 v[2:17], v[50:57], v[82:89], v[2:17], v220, v220 op_sel_hi:[0,0,0]
	v_rcp_f32_e32 v54, v58
	v_lshlrev_b64 v[50:51], 12, v[212:213]
	v_lshl_add_u64 v[50:51], s[8:9], 0, v[50:51]
	v_lshlrev_b32_e32 v186, 3, v221
	v_mul_f32_e32 v53, v67, v54
	v_mul_f32_e32 v52, v66, v54
	v_mul_f32_e32 v56, v69, v54
	v_mul_f32_e32 v57, v53, v53
	v_lshl_add_u64 v[50:51], v[50:51], 0, v[186:187]
	v_mul_f32_e32 v55, v68, v54
	v_fmac_f32_e32 v57, v52, v52
	v_mul_f32_e32 v58, v56, v56
	v_cvt_pk_bf16_f32 v52, v52, v53
	v_cvt_pk_bf16_f32 v53, v55, v56
	v_fmac_f32_e32 v58, v55, v55
	global_store_dwordx2 v[50:51], v[52:53], off
	v_mul_f32_e32 v53, v71, v54
	v_mul_f32_e32 v56, v73, v54
	v_add_f32_e32 v57, v57, v58
	v_mul_f32_e32 v52, v70, v54
	v_mul_f32_e32 v55, v72, v54
	v_mul_f32_e32 v58, v53, v53
	v_mul_f32_e32 v59, v56, v56
	v_fmac_f32_e32 v58, v52, v52
	v_fmac_f32_e32 v59, v55, v55
	v_cvt_pk_bf16_f32 v52, v52, v53
	v_cvt_pk_bf16_f32 v53, v55, v56
	v_add_f32_e32 v58, v58, v59
	global_store_dwordx2 v[50:51], v[52:53], off offset:16
	v_mul_f32_e32 v53, v75, v54
	v_mul_f32_e32 v56, v77, v54
	v_add_f32_e32 v57, v57, v58
	v_mul_f32_e32 v52, v74, v54
	v_mul_f32_e32 v55, v76, v54
	v_mul_f32_e32 v58, v53, v53
	v_mul_f32_e32 v59, v56, v56
	v_fmac_f32_e32 v58, v52, v52
	v_fmac_f32_e32 v59, v55, v55
	v_cvt_pk_bf16_f32 v52, v52, v53
	v_cvt_pk_bf16_f32 v53, v55, v56
	v_add_f32_e32 v58, v58, v59
	global_store_dwordx2 v[50:51], v[52:53], off offset:32
	v_mul_f32_e32 v53, v79, v54
	v_add_f32_e32 v57, v58, v57
	v_mul_f32_e32 v52, v78, v54
	v_mul_f32_e32 v58, v53, v53
	v_fmac_f32_e32 v58, v52, v52
	v_cvt_pk_bf16_f32 v52, v52, v53
	v_mul_f32_e32 v35, v54, v35
	v_mul_f32_e32 v55, v80, v54
	v_mul_f32_e32 v56, v81, v54
	v_cvt_pk_bf16_f32 v53, v55, v56
	global_store_dwordx2 v[50:51], v[52:53], off offset:48
	v_mul_f32_e32 v34, v54, v34
	v_mul_f32_e32 v52, v35, v35
	v_mul_f32_e32 v36, v54, v36
	v_mul_f32_e32 v37, v54, v37
	v_fmac_f32_e32 v52, v34, v34
	v_cvt_pk_bf16_f32 v34, v34, v35
	v_cvt_pk_bf16_f32 v35, v36, v37
	global_store_dwordx2 v[50:51], v[34:35], off offset:64
	v_mul_f32_e32 v35, v54, v39
	v_mul_f32_e32 v59, v56, v56
	v_mul_f32_e32 v53, v37, v37
	v_mul_f32_e32 v34, v54, v38
	v_mul_f32_e32 v37, v54, v41
	v_mul_f32_e32 v38, v35, v35
	v_fmac_f32_e32 v59, v55, v55
	v_fmac_f32_e32 v53, v36, v36
	v_mul_f32_e32 v36, v54, v40
	v_fmac_f32_e32 v38, v34, v34
	v_mul_f32_e32 v39, v37, v37
	v_cvt_pk_bf16_f32 v34, v34, v35
	v_cvt_pk_bf16_f32 v35, v36, v37
	v_add_f32_e32 v58, v58, v59
	v_fmac_f32_e32 v39, v36, v36
	global_store_dwordx2 v[50:51], v[34:35], off offset:80
	v_mul_f32_e32 v35, v54, v43
	v_mul_f32_e32 v37, v54, v45
	v_add_f32_e32 v57, v58, v57
	v_add_f32_e32 v52, v52, v53
	v_add_f32_e32 v38, v38, v39
	v_mul_f32_e32 v34, v54, v42
	v_mul_f32_e32 v36, v54, v44
	v_mul_f32_e32 v39, v35, v35
	v_mul_f32_e32 v40, v37, v37
	v_add_f32_e32 v52, v57, v52
	v_fmac_f32_e32 v39, v34, v34
	v_fmac_f32_e32 v40, v36, v36
	v_cvt_pk_bf16_f32 v34, v34, v35
	v_cvt_pk_bf16_f32 v35, v36, v37
	v_add_f32_e32 v38, v38, v52
	v_add_f32_e32 v39, v39, v40
	global_store_dwordx2 v[50:51], v[34:35], off offset:96
	v_mul_f32_e32 v35, v54, v47
	v_add_f32_e32 v38, v39, v38
	v_mul_f32_e32 v34, v54, v46
	v_mul_f32_e32 v39, v35, v35
	v_fmac_f32_e32 v39, v34, v34
	v_cvt_pk_bf16_f32 v34, v34, v35
	v_mul_f32_e32 v19, v54, v19
	v_mul_f32_e32 v36, v54, v48
	v_mul_f32_e32 v37, v54, v49
	v_cvt_pk_bf16_f32 v35, v36, v37
	global_store_dwordx2 v[50:51], v[34:35], off offset:112
	v_mul_f32_e32 v18, v54, v18
	v_mul_f32_e32 v34, v19, v19
	v_mul_f32_e32 v20, v54, v20
	v_mul_f32_e32 v21, v54, v21
	v_fmac_f32_e32 v34, v18, v18
	v_cvt_pk_bf16_f32 v18, v18, v19
	v_cvt_pk_bf16_f32 v19, v20, v21
	global_store_dwordx2 v[50:51], v[18:19], off offset:128
	v_mul_f32_e32 v19, v54, v23
	v_mul_f32_e32 v40, v37, v37
	v_mul_f32_e32 v35, v21, v21
	v_mul_f32_e32 v18, v54, v22
	v_mul_f32_e32 v21, v54, v25
	v_mul_f32_e32 v22, v19, v19
	v_fmac_f32_e32 v40, v36, v36
	v_fmac_f32_e32 v35, v20, v20
	v_mul_f32_e32 v20, v54, v24
	v_fmac_f32_e32 v22, v18, v18
	v_mul_f32_e32 v23, v21, v21
	v_cvt_pk_bf16_f32 v18, v18, v19
	v_cvt_pk_bf16_f32 v19, v20, v21
	v_add_f32_e32 v39, v39, v40
	v_fmac_f32_e32 v23, v20, v20
	global_store_dwordx2 v[50:51], v[18:19], off offset:144
	v_mul_f32_e32 v19, v54, v27
	v_mul_f32_e32 v21, v54, v29
	v_add_f32_e32 v38, v39, v38
	v_add_f32_e32 v34, v34, v35
	v_add_f32_e32 v22, v22, v23
	v_mul_f32_e32 v18, v54, v26
	v_mul_f32_e32 v20, v54, v28
	v_mul_f32_e32 v23, v19, v19
	v_mul_f32_e32 v24, v21, v21
	v_add_f32_e32 v34, v38, v34
	v_fmac_f32_e32 v23, v18, v18
	v_fmac_f32_e32 v24, v20, v20
	v_cvt_pk_bf16_f32 v18, v18, v19
	v_cvt_pk_bf16_f32 v19, v20, v21
	v_add_f32_e32 v22, v22, v34
	v_add_f32_e32 v23, v23, v24
	global_store_dwordx2 v[50:51], v[18:19], off offset:160
	v_mul_f32_e32 v19, v54, v31
	v_add_f32_e32 v22, v23, v22
	v_mul_f32_e32 v18, v54, v30
	v_mul_f32_e32 v23, v19, v19
	v_fmac_f32_e32 v23, v18, v18
	v_cvt_pk_bf16_f32 v18, v18, v19
	v_mul_f32_e32 v3, v54, v3
	v_mul_f32_e32 v20, v54, v32
	v_mul_f32_e32 v21, v54, v33
	v_cvt_pk_bf16_f32 v19, v20, v21
	global_store_dwordx2 v[50:51], v[18:19], off offset:176
	v_mul_f32_e32 v2, v54, v2
	v_mul_f32_e32 v18, v3, v3
	v_mul_f32_e32 v4, v54, v4
	v_mul_f32_e32 v5, v54, v5
	v_fmac_f32_e32 v18, v2, v2
	v_cvt_pk_bf16_f32 v2, v2, v3
	v_cvt_pk_bf16_f32 v3, v4, v5
	global_store_dwordx2 v[50:51], v[2:3], off offset:192
	v_mul_f32_e32 v3, v54, v7
	v_mul_f32_e32 v24, v21, v21
	v_mul_f32_e32 v19, v5, v5
	v_mul_f32_e32 v2, v54, v6
	v_mul_f32_e32 v5, v54, v9
	v_mul_f32_e32 v6, v3, v3
	v_fmac_f32_e32 v24, v20, v20
	v_fmac_f32_e32 v19, v4, v4
	v_mul_f32_e32 v4, v54, v8
	v_fmac_f32_e32 v6, v2, v2
	v_mul_f32_e32 v7, v5, v5
	v_cvt_pk_bf16_f32 v2, v2, v3
	v_cvt_pk_bf16_f32 v3, v4, v5
	v_add_f32_e32 v23, v23, v24
	v_fmac_f32_e32 v7, v4, v4
	global_store_dwordx2 v[50:51], v[2:3], off offset:208
	v_mul_f32_e32 v3, v54, v11
	v_mul_f32_e32 v5, v54, v13
	v_add_f32_e32 v22, v23, v22
	v_add_f32_e32 v18, v18, v19
	v_add_f32_e32 v6, v6, v7
	v_mul_f32_e32 v2, v54, v10
	v_mul_f32_e32 v4, v54, v12
	v_mul_f32_e32 v7, v3, v3
	v_mul_f32_e32 v8, v5, v5
	v_add_f32_e32 v18, v22, v18
	v_fmac_f32_e32 v7, v2, v2
	v_fmac_f32_e32 v8, v4, v4
	v_add_f32_e32 v6, v6, v18
	v_add_f32_e32 v7, v7, v8
	v_add_f32_e32 v6, v7, v6
	v_cvt_pk_bf16_f32 v2, v2, v3
	v_cvt_pk_bf16_f32 v3, v4, v5
	v_mul_f32_e32 v4, v54, v15
	v_mul_f32_e32 v7, v54, v17
	global_store_dwordx2 v[50:51], v[2:3], off offset:224
	v_mul_f32_e32 v3, v54, v14
	v_mul_f32_e32 v5, v54, v16
	v_mul_f32_e32 v2, v4, v4
	v_mul_f32_e32 v8, v7, v7
	v_fmac_f32_e32 v2, v3, v3
	v_fmac_f32_e32 v8, v5, v5
	v_add_f32_e32 v2, v2, v8
	v_add_f32_e32 v2, v2, v6
	v_cvt_pk_bf16_f32 v4, v3, v4
	v_mov_b32_e32 v3, v2
	s_nop 1
	v_permlane32_swap_b32_e32 v2, v3
	v_cmp_eq_u32_e32 vcc, 0, v221
	v_cvt_pk_bf16_f32 v5, v5, v7
	global_store_dwordx2 v[50:51], v[4:5], off offset:240
	s_and_saveexec_b64 s[4:5], vcc
	s_cbranch_execz .LBB0_1714
	s_lshl_b64 s[8:9], s[48:49], 14
	s_add_u32 s10, s50, s8
	s_addc_u32 s11, s51, s9
	s_lshl_b64 s[8:9], s[46:47], 2
	s_add_u32 s8, s10, s8
	s_addc_u32 s9, s11, s9
	v_lshlrev_b64 v[4:5], 6, v[212:213]
	v_lshl_add_u64 v[4:5], s[8:9], 0, v[4:5]
	v_add_f32_e32 v2, v2, v3
	global_store_dword v[4:5], v2, off
	s_branch .LBB0_1714

.LBB0_1754:
	s_mov_b32 s47, s8
	s_mov_b32 s8, s4
	v_lshl_add_u64 v[98:99], v[198:199], 0, s[18:19]
	v_add_co_u32_e32 v100, vcc, s38, v98
	s_nop 1
	v_addc_co_u32_e32 v101, vcc, 0, v99, vcc
	global_load_dwordx4 v[162:165], v[100:101], off
	v_lshl_add_u64 v[100:101], v[200:201], 0, s[18:19]
	v_add_co_u32_e32 v102, vcc, s38, v100
	s_nop 1
	v_addc_co_u32_e32 v103, vcc, 0, v101, vcc
	v_add_co_u32_e32 v98, vcc, s39, v98
	global_load_dwordx4 v[166:169], v[102:103], off
	s_nop 0
	v_addc_co_u32_e32 v99, vcc, 0, v99, vcc
	global_load_dwordx4 v[170:173], v[98:99], off
	v_add_co_u32_e32 v98, vcc, s39, v100
	s_nop 1
	v_addc_co_u32_e32 v99, vcc, 0, v101, vcc
	global_load_dwordx4 v[174:177], v[98:99], off
	ds_read_b128 v[98:101], v216 offset:17408
	ds_read_b128 v[102:105], v216 offset:26112
	ds_read_b128 v[178:181], v216 offset:17440
	v_add_f32_e32 v190, 0, v82
	v_add_f32_e32 v191, 0, v83
	s_waitcnt lgkmcnt(2)
	v_mfma_f32_32x32x16_bf16 v[114:129], v[98:101], v[158:161], 0
	v_mov_b32_e32 v98, 0
	v_mov_b32_e32 v99, 0
	ds_read_b128 v[182:185], v216 offset:26144
	v_add_f32_e32 v226, v84, v98
	v_add_f32_e32 v227, v85, v99
	s_waitcnt lgkmcnt(2)
	v_mfma_f32_32x32x16_bf16 v[98:113], v[102:105], v[158:161], 0
	ds_read_b128 v[186:189], v216 offset:17472
	v_add_f32_e32 v228, v86, v190
	v_add_f32_e32 v229, v87, v191
	v_cvt_pk_bf16_f32 v190, v82, v83
	v_cvt_pk_bf16_f32 v191, v84, v85
	v_cvt_pk_bf16_f32 v192, v86, v87
	v_cvt_pk_bf16_f32 v193, v88, v89
	s_waitcnt lgkmcnt(2)
	v_mfma_f32_32x32x16_bf16 v[114:129], v[178:181], v[154:157], v[114:129]
	v_permlane32_swap_b32_e32 v190, v192
	v_permlane32_swap_b32_e32 v191, v193
	ds_read_b128 v[82:85], v216 offset:26176
	v_add_f32_e32 v226, v88, v226
	v_add_f32_e32 v227, v89, v227
	s_waitcnt lgkmcnt(2)
	v_mfma_f32_32x32x16_bf16 v[98:113], v[182:185], v[154:157], v[98:113]
	ds_read_b128 v[86:89], v216 offset:17504
	v_add_f32_e32 v182, v90, v228
	v_add_f32_e32 v183, v91, v229
	s_waitcnt lgkmcnt(2)
	v_mfma_f32_32x32x16_bf16 v[114:129], v[186:189], v[150:153], v[114:129]
	ds_read_b128 v[178:181], v216 offset:26208
	v_add_f32_e32 v184, v92, v226
	v_add_f32_e32 v185, v93, v227
	s_waitcnt lgkmcnt(2)
	v_mfma_f32_32x32x16_bf16 v[98:113], v[82:85], v[150:153], v[98:113]
	ds_read_b128 v[82:85], v216 offset:17536
	v_add_f32_e32 v182, v94, v182
	v_add_f32_e32 v183, v95, v183
	v_cvt_pk_bf16_f32 v186, v90, v91
	v_cvt_pk_bf16_f32 v187, v92, v93
	v_cvt_pk_bf16_f32 v188, v94, v95
	v_cvt_pk_bf16_f32 v189, v96, v97
	s_waitcnt lgkmcnt(2)
	v_mfma_f32_32x32x16_bf16 v[114:129], v[86:89], v[146:149], v[114:129]
	v_permlane32_swap_b32_e32 v186, v188
	v_permlane32_swap_b32_e32 v187, v189
	ds_read_b128 v[86:89], v216 offset:26240
	v_add_f32_e32 v94, v96, v184
	v_add_f32_e32 v95, v97, v185
	s_waitcnt lgkmcnt(2)
	v_mfma_f32_32x32x16_bf16 v[98:113], v[178:181], v[146:149], v[98:113]
	ds_read_b128 v[90:93], v216 offset:17568
	v_add_f32_e32 v96, v66, v182
	v_add_f32_e32 v97, v67, v183
	s_waitcnt lgkmcnt(2)
	v_mfma_f32_32x32x16_bf16 v[114:129], v[82:85], v[142:145], v[114:129]
	ds_read_b128 v[82:85], v216 offset:26272
	v_add_f32_e32 v94, v68, v94
	v_add_f32_e32 v95, v69, v95
	s_waitcnt lgkmcnt(2)
	v_mfma_f32_32x32x16_bf16 v[98:113], v[86:89], v[142:145], v[98:113]
	ds_read_b128 v[86:89], v216 offset:17600
	v_add_f32_e32 v96, v70, v96
	v_add_f32_e32 v97, v71, v97
	v_cvt_pk_bf16_f32 v182, v66, v67
	v_cvt_pk_bf16_f32 v183, v68, v69
	v_cvt_pk_bf16_f32 v184, v70, v71
	v_cvt_pk_bf16_f32 v185, v72, v73
	s_waitcnt lgkmcnt(2)
	v_mfma_f32_32x32x16_bf16 v[114:129], v[90:93], v[138:141], v[114:129]
	v_permlane32_swap_b32_e32 v182, v184
	v_permlane32_swap_b32_e32 v183, v185
	ds_read_b128 v[66:69], v216 offset:26304
	v_add_f32_e32 v90, v72, v94
	v_add_f32_e32 v91, v73, v95
	s_waitcnt lgkmcnt(2)
	v_mfma_f32_32x32x16_bf16 v[98:113], v[82:85], v[138:141], v[98:113]
	ds_read_b128 v[70:73], v216 offset:17632
	v_add_f32_e32 v92, v74, v96
	v_add_f32_e32 v93, v75, v97
	s_waitcnt lgkmcnt(2)
	v_mfma_f32_32x32x16_bf16 v[114:129], v[86:89], v[134:137], v[114:129]
	ds_read_b128 v[82:85], v216 offset:26336
	v_add_f32_e32 v86, v76, v90
	v_add_f32_e32 v87, v77, v91
	s_waitcnt lgkmcnt(2)
	v_mfma_f32_32x32x16_bf16 v[98:113], v[66:69], v[134:137], v[98:113]
	v_add_f32_e32 v66, v78, v92
	v_add_f32_e32 v67, v79, v93
	v_cvt_pk_bf16_f32 v178, v74, v75
	v_cvt_pk_bf16_f32 v179, v76, v77
	v_cvt_pk_bf16_f32 v180, v78, v79
	v_cvt_pk_bf16_f32 v181, v80, v81
	s_waitcnt lgkmcnt(1)
	v_mfma_f32_32x32x16_bf16 v[114:129], v[70:73], v[130:133], v[114:129]
	v_permlane32_swap_b32_e32 v178, v180
	v_permlane32_swap_b32_e32 v179, v181
	v_add_f32_e32 v68, v80, v86
	v_add_f32_e32 v69, v81, v87
	s_waitcnt lgkmcnt(0)
	v_mfma_f32_32x32x16_bf16 v[98:113], v[82:85], v[130:133], v[98:113]
	v_add_f32_e32 v66, v66, v67
	v_add_f32_e32 v67, v68, v69
	s_add_i32 s4, s45, 0
	v_add_f32_e32 v226, v66, v67
	v_add_u32_e32 v66, s4, v219
	s_waitcnt vmcnt(0)
	s_waitcnt vmcnt(3)
	ds_write_b128 v66, v[162:165]
	v_add_u32_e32 v66, s4, v220
	s_waitcnt vmcnt(2)
	ds_write_b128 v66, v[166:169]
	s_waitcnt vmcnt(1)
	ds_write_b128 v218, v[170:173] offset:49152
	s_waitcnt vmcnt(0)
	ds_write_b128 v218, v[174:177] offset:57856
	v_add_u32_e32 v230, s8, v211
	ds_read_b64_tr_b16 v[66:67], v230
	ds_read_b64_tr_b16 v[68:69], v230 offset:2048
	ds_read_b64_tr_b16 v[70:71], v230 offset:512
	ds_read_b64_tr_b16 v[74:75], v230 offset:1024
	ds_read_b64_tr_b16 v[72:73], v230 offset:2560
	ds_read_b64_tr_b16 v[76:77], v230 offset:3072
	s_waitcnt lgkmcnt(4)
	v_mfma_f32_32x32x16_bf16 v[2:17], v[190:193], v[66:69], v[2:17]
	v_add_u32_e32 v66, 0x7b, v224
	v_cmp_lt_u32_e32 vcc, s31, v66
	v_add_u32_e32 v67, 0xffffffa0, v223
	v_add_u32_e32 v68, 0x79, v224
	v_cndmask_b32_e32 v66, v1, v114, vcc
	v_cmp_gt_u32_e32 vcc, s34, v67
	v_mov_b32_e32 v227, v226
	s_nop 1
	v_permlane32_swap_b32_e32 v226, v227
	v_cndmask_b32_e32 v83, v1, v115, vcc
	v_cmp_lt_u32_e32 vcc, s31, v68
	v_add_u32_e32 v68, 0x78, v224
	v_max3_f32 v67, v66, s35, v83
	v_cndmask_b32_e32 v84, v1, v116, vcc
	v_cmp_lt_u32_e32 vcc, s31, v68
	v_add_u32_e32 v68, 0x73, v224
	s_nop 0
	v_cndmask_b32_e32 v85, v1, v117, vcc
	v_cmp_lt_u32_e32 vcc, s31, v68
	v_add_u32_e32 v68, 0x72, v224
	v_max3_f32 v67, v67, v84, v85
	v_cndmask_b32_e32 v86, v1, v118, vcc
	v_cmp_lt_u32_e32 vcc, s31, v68
	v_add_u32_e32 v68, 0x71, v224
	s_nop 0
	v_cndmask_b32_e32 v87, v1, v119, vcc
	v_cmp_lt_u32_e32 vcc, s31, v68
	v_add_u32_e32 v68, 0x70, v224
	v_max3_f32 v67, v67, v86, v87
	v_cndmask_b32_e32 v88, v1, v120, vcc
	v_cmp_lt_u32_e32 vcc, s31, v68
	s_nop 1
	v_cndmask_b32_e32 v89, v1, v121, vcc
	v_max3_f32 v67, v67, v88, v89
	v_add_u32_e32 v68, 0x6b, v224
	v_cmp_lt_u32_e32 vcc, s31, v68
	v_add_u32_e32 v68, 0x6a, v224
	s_waitcnt lgkmcnt(1)
	v_mfma_f32_32x32x16_bf16 v[50:65], v[190:193], v[70:73], v[50:65]
	v_cndmask_b32_e32 v90, v1, v122, vcc
	v_cmp_lt_u32_e32 vcc, s31, v68
	v_add_u32_e32 v68, 0x69, v224
	ds_read_b64_tr_b16 v[78:79], v230 offset:1536
	ds_read_b64_tr_b16 v[80:81], v230 offset:3584
	v_cndmask_b32_e32 v91, v1, v123, vcc
	v_cmp_lt_u32_e32 vcc, s31, v68
	v_add_u32_e32 v68, 0x68, v224
	v_max3_f32 v67, v67, v90, v91
	v_cndmask_b32_e32 v92, v1, v124, vcc
	v_cmp_lt_u32_e32 vcc, s31, v68
	v_add_u32_e32 v68, 0x63, v224
	s_nop 0
	v_cndmask_b32_e32 v93, v1, v125, vcc
	v_cmp_lt_u32_e32 vcc, s31, v68
	v_add_u32_e32 v68, 0x62, v224
	v_max3_f32 v67, v67, v92, v93
	v_cndmask_b32_e32 v94, v1, v126, vcc
	v_cmp_lt_u32_e32 vcc, s31, v68
	v_add_u32_e32 v68, 0x61, v224
	s_nop 0
	v_cndmask_b32_e32 v95, v1, v127, vcc
	v_cmp_lt_u32_e32 vcc, s31, v68
	v_add_u32_e32 v68, 0x60, v224
	v_max3_f32 v67, v67, v94, v95
	v_cndmask_b32_e32 v96, v1, v128, vcc
	v_cmp_lt_u32_e32 vcc, s31, v68
	s_nop 1
	v_cndmask_b32_e32 v97, v1, v129, vcc
	v_max3_f32 v68, v67, v96, v97
	v_add_u32_e32 v67, 0x5b, v224
	v_cmp_lt_u32_e32 vcc, s31, v67
	v_subrev_u32_e32 v67, 64, v223
	v_add_u32_e32 v69, 0x58, v224
	v_cndmask_b32_e32 v118, v1, v98, vcc
	v_cmp_gt_u32_e32 vcc, s34, v67
	s_waitcnt lgkmcnt(2)
	v_mfma_f32_32x32x16_bf16 v[34:49], v[190:193], v[74:77], v[34:49]
	v_add_u32_e32 v71, 0x52, v224
	v_cndmask_b32_e32 v67, v1, v99, vcc
	v_max3_f32 v70, v68, v118, v67
	v_add_u32_e32 v68, 0x59, v224
	v_cmp_lt_u32_e32 vcc, s31, v68
	ds_read_b64_tr_b16 v[114:115], v230 offset:4096
	ds_read_b64_tr_b16 v[116:117], v230 offset:6144
	v_cndmask_b32_e32 v68, v1, v100, vcc
	v_cmp_lt_u32_e32 vcc, s31, v69
	v_add_u32_e32 v73, 0x50, v224
	s_nop 0
	v_cndmask_b32_e32 v69, v1, v101, vcc
	v_max3_f32 v72, v70, v68, v69
	v_add_u32_e32 v70, 0x53, v224
	v_cmp_lt_u32_e32 vcc, s31, v70
	s_nop 1
	v_cndmask_b32_e32 v70, v1, v102, vcc
	v_cmp_lt_u32_e32 vcc, s31, v71
	s_nop 1
	v_cndmask_b32_e32 v71, v1, v103, vcc
	v_max3_f32 v74, v72, v70, v71
	v_add_u32_e32 v72, 0x51, v224
	v_cmp_lt_u32_e32 vcc, s31, v72
	s_nop 1
	v_cndmask_b32_e32 v72, v1, v104, vcc
	v_cmp_lt_u32_e32 vcc, s31, v73
	s_nop 1
	v_cndmask_b32_e32 v73, v1, v105, vcc
	v_max3_f32 v82, v74, v72, v73
	v_add_u32_e32 v74, 0x4b, v224
	v_cmp_lt_u32_e32 vcc, s31, v74
	v_add_u32_e32 v75, 0x4a, v224
	v_add_u32_e32 v76, 0x49, v224
	v_cndmask_b32_e32 v74, v1, v106, vcc
	v_cmp_lt_u32_e32 vcc, s31, v75
	s_waitcnt lgkmcnt(2)
	v_mfma_f32_32x32x16_bf16 v[18:33], v[190:193], v[78:81], v[18:33]
	v_add_u32_e32 v77, 0x48, v224
	v_cndmask_b32_e32 v75, v1, v107, vcc
	v_cmp_lt_u32_e32 vcc, s31, v76
	v_add_u32_e32 v78, 0x43, v224
	v_add_u32_e32 v79, 0x42, v224
	v_cndmask_b32_e32 v76, v1, v108, vcc
	v_cmp_lt_u32_e32 vcc, s31, v77
	ds_read_b64_tr_b16 v[98:99], v230 offset:4608
	ds_read_b64_tr_b16 v[100:101], v230 offset:6656
	v_cndmask_b32_e32 v77, v1, v109, vcc
	v_cmp_lt_u32_e32 vcc, s31, v78
	v_add_u32_e32 v80, 0x41, v224
	v_add_u32_e32 v81, 64, v224
	v_cndmask_b32_e32 v78, v1, v110, vcc
	v_cmp_lt_u32_e32 vcc, s31, v79
	v_max3_f32 v82, v82, v74, v75
	v_max3_f32 v82, v82, v76, v77
	v_cndmask_b32_e32 v79, v1, v111, vcc
	v_cmp_lt_u32_e32 vcc, s31, v80
	v_max3_f32 v82, v82, v78, v79
	s_nop 0
	v_cndmask_b32_e32 v80, v1, v112, vcc
	v_cmp_lt_u32_e32 vcc, s31, v81
	s_nop 1
	v_cndmask_b32_e32 v81, v1, v113, vcc
	v_max3_f32 v82, v82, v80, v81
	s_nop 0
	v_mov_b32_e32 v106, v82
	s_nop 1
	v_permlane32_swap_b32_e32 v82, v106
	v_max_f32_e32 v106, v106, v106
	v_max_f32_e32 v82, v82, v82
	v_max_f32_e32 v82, v82, v106
	v_sub_f32_e32 v106, v82, v225
	s_waitcnt lgkmcnt(2)
	v_mfma_f32_32x32x16_bf16 v[2:17], v[186:189], v[114:117], v[2:17]
	v_cmp_ge_f32_e32 vcc, s36, v106
	s_cmp_eq_u64 vcc, exec
	v_max_f32_e32 v106, v225, v225
	ds_read_b64_tr_b16 v[102:103], v230 offset:5120
	ds_read_b64_tr_b16 v[104:105], v230 offset:7168
	v_max_f32_e32 v82, v106, v82
	s_cselect_b64 vcc, -1, 0
	v_cndmask_b32_e32 v229, v82, v225, vcc
	v_sub_f32_e32 v82, v225, v229
	v_mul_f32_e32 v82, 0x3e0293ee, v82
	v_exp_f32_e32 v228, v82
	v_fma_f32 v110, v229, s37, 0
	s_waitcnt lgkmcnt(2)
	v_mfma_f32_32x32x16_bf16 v[50:65], v[186:189], v[98:101], v[50:65]
	ds_read_b64_tr_b16 v[106:107], v230 offset:5632
	ds_read_b64_tr_b16 v[108:109], v230 offset:7680
	v_fmamk_f32 v66, v66, 0x3e0293ee, v110
	v_exp_f32_e32 v82, v66
	v_fmamk_f32 v66, v83, 0x3e0293ee, v110
	v_exp_f32_e32 v83, v66
	s_waitcnt lgkmcnt(2)
	v_mfma_f32_32x32x16_bf16 v[34:49], v[186:189], v[102:105], v[34:49]
	ds_read_b64_tr_b16 v[98:99], v230 offset:8192
	ds_read_b64_tr_b16 v[100:101], v230 offset:10240
	v_fmamk_f32 v66, v84, 0x3e0293ee, v110
	v_exp_f32_e32 v84, v66
	v_fmamk_f32 v66, v85, 0x3e0293ee, v110
	v_exp_f32_e32 v85, v66
	v_fmamk_f32 v66, v86, 0x3e0293ee, v110
	v_exp_f32_e32 v86, v66
	s_waitcnt lgkmcnt(2)
	v_mfma_f32_32x32x16_bf16 v[18:33], v[186:189], v[106:109], v[18:33]
	ds_read_b64_tr_b16 v[102:103], v230 offset:8704
	ds_read_b64_tr_b16 v[104:105], v230 offset:10752
	v_fmamk_f32 v66, v87, 0x3e0293ee, v110
	v_exp_f32_e32 v87, v66
	v_fmamk_f32 v66, v88, 0x3e0293ee, v110
	v_exp_f32_e32 v88, v66
	v_fmamk_f32 v66, v89, 0x3e0293ee, v110
	v_exp_f32_e32 v89, v66
	s_waitcnt lgkmcnt(2)
	v_mfma_f32_32x32x16_bf16 v[2:17], v[182:185], v[98:101], v[2:17]
	ds_read_b64_tr_b16 v[106:107], v230 offset:9216
	ds_read_b64_tr_b16 v[108:109], v230 offset:11264
	v_fmamk_f32 v66, v90, 0x3e0293ee, v110
	v_exp_f32_e32 v90, v66
	v_fmamk_f32 v66, v91, 0x3e0293ee, v110
	v_exp_f32_e32 v91, v66
	v_fmamk_f32 v66, v92, 0x3e0293ee, v110
	v_exp_f32_e32 v92, v66
	s_waitcnt lgkmcnt(2)
	v_mfma_f32_32x32x16_bf16 v[50:65], v[182:185], v[102:105], v[50:65]
	ds_read_b64_tr_b16 v[98:99], v230 offset:9728
	ds_read_b64_tr_b16 v[100:101], v230 offset:11776
	v_fmamk_f32 v66, v93, 0x3e0293ee, v110
	v_exp_f32_e32 v93, v66
	v_fmamk_f32 v66, v94, 0x3e0293ee, v110
	v_exp_f32_e32 v94, v66
	v_fmamk_f32 v66, v95, 0x3e0293ee, v110
	v_exp_f32_e32 v95, v66
	s_waitcnt lgkmcnt(2)
	v_mfma_f32_32x32x16_bf16 v[34:49], v[182:185], v[106:109], v[34:49]
	ds_read_b64_tr_b16 v[102:103], v230 offset:12288
	ds_read_b64_tr_b16 v[104:105], v230 offset:14336
	v_fmamk_f32 v66, v96, 0x3e0293ee, v110
	v_exp_f32_e32 v96, v66
	v_fmamk_f32 v66, v97, 0x3e0293ee, v110
	v_exp_f32_e32 v97, v66
	v_fmamk_f32 v66, v118, 0x3e0293ee, v110
	v_exp_f32_e32 v66, v66
	s_waitcnt lgkmcnt(2)
	v_mfma_f32_32x32x16_bf16 v[18:33], v[182:185], v[98:101], v[18:33]
	ds_read_b64_tr_b16 v[106:107], v230 offset:12800
	ds_read_b64_tr_b16 v[108:109], v230 offset:14848
	v_fmamk_f32 v67, v67, 0x3e0293ee, v110
	v_fmamk_f32 v68, v68, 0x3e0293ee, v110
	v_fmamk_f32 v69, v69, 0x3e0293ee, v110
	v_exp_f32_e32 v67, v67
	v_exp_f32_e32 v68, v68
	v_exp_f32_e32 v69, v69
	s_waitcnt lgkmcnt(2)
	v_mfma_f32_32x32x16_bf16 v[2:17], v[178:181], v[102:105], v[2:17]
	ds_read_b64_tr_b16 v[98:99], v230 offset:13312
	ds_read_b64_tr_b16 v[100:101], v230 offset:15360
	v_fmamk_f32 v70, v70, 0x3e0293ee, v110
	v_fmamk_f32 v71, v71, 0x3e0293ee, v110
	v_fmamk_f32 v72, v72, 0x3e0293ee, v110
	v_exp_f32_e32 v70, v70
	v_exp_f32_e32 v71, v71
	v_exp_f32_e32 v72, v72
	s_waitcnt lgkmcnt(2)
	v_mfma_f32_32x32x16_bf16 v[50:65], v[178:181], v[106:109], v[50:65]
	ds_read_b64_tr_b16 v[102:103], v230 offset:13824
	ds_read_b64_tr_b16 v[104:105], v230 offset:15872
	v_fmamk_f32 v73, v73, 0x3e0293ee, v110
	v_fmamk_f32 v74, v74, 0x3e0293ee, v110
	v_fmamk_f32 v75, v75, 0x3e0293ee, v110
	v_exp_f32_e32 v73, v73
	v_exp_f32_e32 v74, v74
	v_exp_f32_e32 v75, v75
	s_waitcnt lgkmcnt(2)
	v_mfma_f32_32x32x16_bf16 v[34:49], v[178:181], v[98:101], v[34:49]
	v_fmamk_f32 v76, v76, 0x3e0293ee, v110
	v_fmamk_f32 v77, v77, 0x3e0293ee, v110
	v_fmamk_f32 v78, v78, 0x3e0293ee, v110
	v_exp_f32_e32 v76, v76
	v_exp_f32_e32 v77, v77
	v_exp_f32_e32 v78, v78
	s_waitcnt lgkmcnt(0)
	v_mfma_f32_32x32x16_bf16 v[18:33], v[178:181], v[102:105], v[18:33]
	v_fmamk_f32 v79, v79, 0x3e0293ee, v110
	v_fmamk_f32 v80, v80, 0x3e0293ee, v110
	v_fmac_f32_e32 v110, 0x3e0293ee, v81
	v_exp_f32_e32 v79, v79
	v_exp_f32_e32 v80, v80
	v_exp_f32_e32 v81, v110
	v_cmp_gt_f32_e32 vcc, 1.0, v228
	s_cbranch_vccz .LBB0_1758
	s_and_saveexec_b64 s[4:5], s[6:7]
	ds_write_b32 v213, v228 offset:128
	s_or_b64 exec, exec, s[4:5]
	s_waitcnt lgkmcnt(0)
	ds_read_b128 v[98:101], v208 offset:224
	ds_read_b128 v[102:105], v208 offset:192
	ds_read_b128 v[106:109], v208 offset:160
	ds_read_b128 v[110:113], v208 offset:128
	s_waitcnt lgkmcnt(3)
	v_mul_f32_e32 v16, v16, v100
	v_mul_f32_e32 v17, v17, v101
	s_waitcnt lgkmcnt(2)
	v_mul_f32_e32 v12, v12, v104
	v_mul_f32_e32 v13, v13, v105
	s_waitcnt lgkmcnt(1)
	v_mul_f32_e32 v8, v8, v108
	v_mul_f32_e32 v9, v9, v109
	s_waitcnt lgkmcnt(0)
	v_mul_f32_e32 v4, v4, v112
	v_mul_f32_e32 v5, v5, v113
	v_mul_f32_e32 v14, v14, v98
	v_mul_f32_e32 v15, v15, v99
	v_mul_f32_e32 v10, v10, v102
	v_mul_f32_e32 v11, v11, v103
	v_mul_f32_e32 v6, v6, v106
	v_mul_f32_e32 v7, v7, v107
	v_mul_f32_e32 v2, v2, v110
	v_mul_f32_e32 v3, v3, v111
	v_mul_f32_e32 v64, v64, v100
	v_mul_f32_e32 v65, v65, v101
	v_mul_f32_e32 v60, v60, v104
	v_mul_f32_e32 v61, v61, v105
	v_mul_f32_e32 v56, v56, v108
	v_mul_f32_e32 v57, v57, v109
	v_mul_f32_e32 v52, v52, v112
	v_mul_f32_e32 v53, v53, v113
	v_mul_f32_e32 v62, v62, v98
	v_mul_f32_e32 v63, v63, v99
	v_mul_f32_e32 v58, v58, v102
	v_mul_f32_e32 v59, v59, v103
	v_mul_f32_e32 v54, v54, v106
	v_mul_f32_e32 v55, v55, v107
	v_mul_f32_e32 v50, v50, v110
	v_mul_f32_e32 v51, v51, v111
	v_mul_f32_e32 v48, v48, v100
	v_mul_f32_e32 v49, v49, v101
	v_mul_f32_e32 v44, v44, v104
	v_mul_f32_e32 v45, v45, v105
	v_mul_f32_e32 v40, v40, v108
	v_mul_f32_e32 v41, v41, v109
	v_mul_f32_e32 v36, v36, v112
	v_mul_f32_e32 v37, v37, v113
	v_mul_f32_e32 v46, v46, v98
	v_mul_f32_e32 v47, v47, v99
	v_mul_f32_e32 v42, v42, v102
	v_mul_f32_e32 v43, v43, v103
	v_mul_f32_e32 v38, v38, v106
	v_mul_f32_e32 v39, v39, v107
	v_mul_f32_e32 v34, v34, v110
	v_mul_f32_e32 v35, v35, v111
	v_mul_f32_e32 v32, v32, v100
	v_mul_f32_e32 v33, v33, v101
	v_mul_f32_e32 v28, v28, v104
	v_mul_f32_e32 v29, v29, v105
	v_mul_f32_e32 v24, v24, v108
	v_mul_f32_e32 v25, v25, v109
	v_mul_f32_e32 v20, v20, v112
	v_mul_f32_e32 v21, v21, v113
	v_mul_f32_e32 v30, v30, v98
	v_mul_f32_e32 v31, v31, v99
	v_mul_f32_e32 v26, v26, v102
	v_mul_f32_e32 v27, v27, v103
	v_mul_f32_e32 v22, v22, v106
	v_mul_f32_e32 v23, v23, v107
	v_mul_f32_e32 v18, v18, v110
	v_mul_f32_e32 v19, v19, v111

.LBB0_1762:
	s_waitcnt vmcnt(3)
	v_add_u32_e32 v162, s47, v211
	ds_read_b64_tr_b16 v[66:67], v162
	ds_read_b64_tr_b16 v[68:69], v162 offset:2048
	ds_read_b64_tr_b16 v[70:71], v162 offset:512
	ds_read_b64_tr_b16 v[74:75], v162 offset:1024
	ds_read_b64_tr_b16 v[72:73], v162 offset:2560
	ds_read_b64_tr_b16 v[76:77], v162 offset:3072
	s_waitcnt lgkmcnt(4)
	v_mfma_f32_32x32x16_bf16 v[2:17], v[190:193], v[66:69], v[2:17]
	v_add_u32_e32 v66, 59, v224
	v_cmp_lt_u32_e32 vcc, s31, v66
	v_subrev_u32_e32 v67, 32, v223
	v_add_u32_e32 v68, 57, v224
	v_cndmask_b32_e32 v66, v1, v114, vcc
	v_cmp_gt_u32_e32 vcc, s34, v67
	s_nop 1
	v_cndmask_b32_e32 v83, v1, v115, vcc
	v_cmp_lt_u32_e32 vcc, s31, v68
	v_add_u32_e32 v68, 56, v224
	v_max3_f32 v67, v66, s35, v83
	v_cndmask_b32_e32 v84, v1, v116, vcc
	v_cmp_lt_u32_e32 vcc, s31, v68
	v_add_u32_e32 v68, 51, v224
	s_nop 0
	v_cndmask_b32_e32 v85, v1, v117, vcc
	v_cmp_lt_u32_e32 vcc, s31, v68
	v_add_u32_e32 v68, 50, v224
	v_max3_f32 v67, v67, v84, v85
	v_cndmask_b32_e32 v86, v1, v118, vcc
	v_cmp_lt_u32_e32 vcc, s31, v68
	v_add_u32_e32 v68, 49, v224
	s_nop 0
	v_cndmask_b32_e32 v87, v1, v119, vcc
	v_cmp_lt_u32_e32 vcc, s31, v68
	v_add_u32_e32 v68, 48, v224
	v_max3_f32 v67, v67, v86, v87
	v_cndmask_b32_e32 v88, v1, v120, vcc
	v_cmp_lt_u32_e32 vcc, s31, v68
	s_nop 1
	v_cndmask_b32_e32 v89, v1, v121, vcc
	v_max3_f32 v67, v67, v88, v89
	v_add_u32_e32 v68, 43, v224
	v_cmp_lt_u32_e32 vcc, s31, v68
	v_add_u32_e32 v68, 42, v224
	s_waitcnt lgkmcnt(1)
	v_mfma_f32_32x32x16_bf16 v[50:65], v[190:193], v[70:73], v[50:65]
	v_cndmask_b32_e32 v90, v1, v122, vcc
	v_cmp_lt_u32_e32 vcc, s31, v68
	v_add_u32_e32 v68, 41, v224
	ds_read_b64_tr_b16 v[78:79], v162 offset:1536
	ds_read_b64_tr_b16 v[80:81], v162 offset:3584
	v_cndmask_b32_e32 v91, v1, v123, vcc
	v_cmp_lt_u32_e32 vcc, s31, v68
	v_add_u32_e32 v68, 40, v224
	v_max3_f32 v67, v67, v90, v91
	v_cndmask_b32_e32 v92, v1, v124, vcc
	v_cmp_lt_u32_e32 vcc, s31, v68
	v_add_u32_e32 v68, 35, v224
	s_nop 0
	v_cndmask_b32_e32 v93, v1, v125, vcc
	v_cmp_lt_u32_e32 vcc, s31, v68
	v_add_u32_e32 v68, 34, v224
	v_max3_f32 v67, v67, v92, v93
	v_cndmask_b32_e32 v94, v1, v126, vcc
	v_cmp_lt_u32_e32 vcc, s31, v68
	v_add_u32_e32 v68, 33, v224
	s_nop 0
	v_cndmask_b32_e32 v95, v1, v127, vcc
	v_cmp_lt_u32_e32 vcc, s31, v68
	v_add_u32_e32 v68, 32, v224
	v_max3_f32 v67, v67, v94, v95
	v_cndmask_b32_e32 v96, v1, v128, vcc
	v_cmp_lt_u32_e32 vcc, s31, v68
	s_nop 1
	v_cndmask_b32_e32 v97, v1, v129, vcc
	v_max3_f32 v68, v67, v96, v97
	v_add_u32_e32 v67, 27, v224
	v_cmp_lt_u32_e32 vcc, s31, v67
	v_add_u32_e32 v69, 24, v224
	s_waitcnt lgkmcnt(2)
	v_mfma_f32_32x32x16_bf16 v[34:49], v[190:193], v[74:77], v[34:49]
	v_cndmask_b32_e32 v118, v1, v98, vcc
	v_cmp_gt_u32_e32 vcc, s34, v223
	v_add_u32_e32 v71, 18, v224
	ds_read_b64_tr_b16 v[114:115], v162 offset:4096
	ds_read_b64_tr_b16 v[116:117], v162 offset:6144
	v_cndmask_b32_e32 v67, v1, v99, vcc
	v_max3_f32 v70, v68, v118, v67
	v_add_u32_e32 v68, 25, v224
	v_cmp_lt_u32_e32 vcc, s31, v68
	v_add_u32_e32 v73, 16, v224
	s_nop 0
	v_cndmask_b32_e32 v68, v1, v100, vcc
	v_cmp_lt_u32_e32 vcc, s31, v69
	s_nop 1
	v_cndmask_b32_e32 v69, v1, v101, vcc
	v_max3_f32 v72, v70, v68, v69
	v_add_u32_e32 v70, 19, v224
	v_cmp_lt_u32_e32 vcc, s31, v70
	s_nop 1
	v_cndmask_b32_e32 v70, v1, v102, vcc
	v_cmp_lt_u32_e32 vcc, s31, v71
	s_nop 1
	v_cndmask_b32_e32 v71, v1, v103, vcc
	v_max3_f32 v74, v72, v70, v71
	v_add_u32_e32 v72, 17, v224
	v_cmp_lt_u32_e32 vcc, s31, v72
	s_nop 1
	v_cndmask_b32_e32 v72, v1, v104, vcc
	v_cmp_lt_u32_e32 vcc, s31, v73
	s_nop 1
	v_cndmask_b32_e32 v73, v1, v105, vcc
	v_max3_f32 v82, v74, v72, v73
	v_add_u32_e32 v74, 11, v224
	v_cmp_lt_u32_e32 vcc, s31, v74
	v_add_u32_e32 v75, 10, v224
	v_add_u32_e32 v76, 9, v224
	v_cndmask_b32_e32 v74, v1, v106, vcc
	v_cmp_lt_u32_e32 vcc, s31, v75
	s_waitcnt lgkmcnt(2)
	v_mfma_f32_32x32x16_bf16 v[18:33], v[190:193], v[78:81], v[18:33]
	v_add_u32_e32 v77, 8, v224
	v_cndmask_b32_e32 v75, v1, v107, vcc
	v_cmp_lt_u32_e32 vcc, s31, v76
	v_add_u32_e32 v78, 3, v224
	v_add_u32_e32 v79, 2, v224
	v_cndmask_b32_e32 v76, v1, v108, vcc
	v_cmp_lt_u32_e32 vcc, s31, v77
	ds_read_b64_tr_b16 v[100:101], v162 offset:4608
	ds_read_b64_tr_b16 v[102:103], v162 offset:6656
	v_cndmask_b32_e32 v77, v1, v109, vcc
	v_cmp_lt_u32_e32 vcc, s31, v78
	v_add_u32_e32 v80, 1, v224
	v_max3_f32 v82, v82, v74, v75
	v_cndmask_b32_e32 v78, v1, v110, vcc
	v_cmp_lt_u32_e32 vcc, s31, v79
	v_max3_f32 v82, v82, v76, v77
	s_nop 0
	v_cndmask_b32_e32 v79, v1, v111, vcc
	v_cmp_lt_u32_e32 vcc, s31, v80
	v_max3_f32 v82, v82, v78, v79
	s_nop 0
	v_cndmask_b32_e32 v80, v1, v112, vcc
	v_cmp_lt_u32_e32 vcc, s31, v224
	s_nop 1
	v_cndmask_b32_e32 v81, v1, v113, vcc
	v_max3_f32 v82, v82, v80, v81
	s_nop 0
	v_mov_b32_e32 v98, v82
	s_nop 1
	v_permlane32_swap_b32_e32 v82, v98
	v_max_f32_e32 v98, v98, v98
	v_max_f32_e32 v82, v82, v82
	v_max_f32_e32 v82, v82, v98
	v_sub_f32_e32 v98, v82, v229
	s_waitcnt lgkmcnt(2)
	v_mfma_f32_32x32x16_bf16 v[2:17], v[186:189], v[114:117], v[2:17]
	v_cmp_ge_f32_e32 vcc, s36, v98
	s_cmp_eq_u64 vcc, exec
	v_max_f32_e32 v98, v229, v229
	ds_read_b64_tr_b16 v[104:105], v162 offset:5120
	ds_read_b64_tr_b16 v[106:107], v162 offset:7168
	v_max_f32_e32 v82, v98, v82
	s_cselect_b64 vcc, -1, 0
	v_cndmask_b32_e32 v225, v82, v229, vcc
	v_sub_f32_e32 v82, v229, v225
	v_mul_f32_e32 v82, 0x3e0293ee, v82
	v_exp_f32_e32 v98, v82
	v_fma_f32 v99, v225, s37, 0
	s_waitcnt lgkmcnt(2)
	v_mfma_f32_32x32x16_bf16 v[50:65], v[186:189], v[100:103], v[50:65]
	ds_read_b64_tr_b16 v[108:109], v162 offset:5632
	ds_read_b64_tr_b16 v[110:111], v162 offset:7680
	v_fmamk_f32 v66, v66, 0x3e0293ee, v99
	v_exp_f32_e32 v82, v66
	v_fmamk_f32 v66, v83, 0x3e0293ee, v99
	v_exp_f32_e32 v83, v66
	s_waitcnt lgkmcnt(2)
	v_mfma_f32_32x32x16_bf16 v[34:49], v[186:189], v[104:107], v[34:49]
	ds_read_b64_tr_b16 v[100:101], v162 offset:8192
	ds_read_b64_tr_b16 v[102:103], v162 offset:10240
	v_fmamk_f32 v66, v84, 0x3e0293ee, v99
	v_exp_f32_e32 v84, v66
	v_fmamk_f32 v66, v85, 0x3e0293ee, v99
	v_exp_f32_e32 v85, v66
	v_fmamk_f32 v66, v86, 0x3e0293ee, v99
	v_exp_f32_e32 v86, v66
	s_waitcnt lgkmcnt(2)
	v_mfma_f32_32x32x16_bf16 v[18:33], v[186:189], v[108:111], v[18:33]
	ds_read_b64_tr_b16 v[104:105], v162 offset:8704
	ds_read_b64_tr_b16 v[106:107], v162 offset:10752
	v_fmamk_f32 v66, v87, 0x3e0293ee, v99
	v_exp_f32_e32 v87, v66
	v_fmamk_f32 v66, v88, 0x3e0293ee, v99
	v_exp_f32_e32 v88, v66
	v_fmamk_f32 v66, v89, 0x3e0293ee, v99
	v_exp_f32_e32 v89, v66
	s_waitcnt lgkmcnt(2)
	v_mfma_f32_32x32x16_bf16 v[2:17], v[182:185], v[100:103], v[2:17]
	ds_read_b64_tr_b16 v[108:109], v162 offset:9216
	ds_read_b64_tr_b16 v[110:111], v162 offset:11264
	v_fmamk_f32 v66, v90, 0x3e0293ee, v99
	v_exp_f32_e32 v90, v66
	v_fmamk_f32 v66, v91, 0x3e0293ee, v99
	v_exp_f32_e32 v91, v66
	v_fmamk_f32 v66, v92, 0x3e0293ee, v99
	v_exp_f32_e32 v92, v66
	s_waitcnt lgkmcnt(2)
	v_mfma_f32_32x32x16_bf16 v[50:65], v[182:185], v[104:107], v[50:65]
	ds_read_b64_tr_b16 v[100:101], v162 offset:9728
	ds_read_b64_tr_b16 v[102:103], v162 offset:11776
	v_fmamk_f32 v66, v93, 0x3e0293ee, v99
	v_exp_f32_e32 v93, v66
	v_fmamk_f32 v66, v94, 0x3e0293ee, v99
	v_exp_f32_e32 v94, v66
	v_fmamk_f32 v66, v95, 0x3e0293ee, v99
	v_exp_f32_e32 v95, v66
	s_waitcnt lgkmcnt(2)
	v_mfma_f32_32x32x16_bf16 v[34:49], v[182:185], v[108:111], v[34:49]
	ds_read_b64_tr_b16 v[104:105], v162 offset:12288
	ds_read_b64_tr_b16 v[106:107], v162 offset:14336
	v_fmamk_f32 v66, v96, 0x3e0293ee, v99
	v_exp_f32_e32 v96, v66
	v_fmamk_f32 v66, v97, 0x3e0293ee, v99
	v_exp_f32_e32 v97, v66
	v_fmamk_f32 v66, v118, 0x3e0293ee, v99
	v_exp_f32_e32 v66, v66
	s_waitcnt lgkmcnt(2)
	v_mfma_f32_32x32x16_bf16 v[18:33], v[182:185], v[100:103], v[18:33]
	ds_read_b64_tr_b16 v[108:109], v162 offset:12800
	ds_read_b64_tr_b16 v[110:111], v162 offset:14848
	v_fmamk_f32 v67, v67, 0x3e0293ee, v99
	v_fmamk_f32 v68, v68, 0x3e0293ee, v99
	v_fmamk_f32 v69, v69, 0x3e0293ee, v99
	v_exp_f32_e32 v67, v67
	v_exp_f32_e32 v68, v68
	v_exp_f32_e32 v69, v69
	s_waitcnt lgkmcnt(2)
	v_mfma_f32_32x32x16_bf16 v[2:17], v[178:181], v[104:107], v[2:17]
	ds_read_b64_tr_b16 v[100:101], v162 offset:13312
	ds_read_b64_tr_b16 v[102:103], v162 offset:15360
	v_fmamk_f32 v70, v70, 0x3e0293ee, v99
	v_fmamk_f32 v71, v71, 0x3e0293ee, v99
	v_fmamk_f32 v72, v72, 0x3e0293ee, v99
	v_exp_f32_e32 v70, v70
	v_exp_f32_e32 v71, v71
	v_exp_f32_e32 v72, v72
	s_waitcnt lgkmcnt(2)
	v_mfma_f32_32x32x16_bf16 v[50:65], v[178:181], v[108:111], v[50:65]
	ds_read_b64_tr_b16 v[104:105], v162 offset:13824
	ds_read_b64_tr_b16 v[106:107], v162 offset:15872
	v_fmamk_f32 v73, v73, 0x3e0293ee, v99
	v_fmamk_f32 v74, v74, 0x3e0293ee, v99
	v_fmamk_f32 v75, v75, 0x3e0293ee, v99
	v_exp_f32_e32 v73, v73
	v_exp_f32_e32 v74, v74
	v_exp_f32_e32 v75, v75
	s_waitcnt lgkmcnt(2)
	v_mfma_f32_32x32x16_bf16 v[34:49], v[178:181], v[100:103], v[34:49]
	v_fmamk_f32 v76, v76, 0x3e0293ee, v99
	v_fmamk_f32 v77, v77, 0x3e0293ee, v99
	v_fmamk_f32 v78, v78, 0x3e0293ee, v99
	v_exp_f32_e32 v76, v76
	v_exp_f32_e32 v77, v77
	v_exp_f32_e32 v78, v78
	s_waitcnt lgkmcnt(0)
	v_mfma_f32_32x32x16_bf16 v[18:33], v[178:181], v[104:107], v[18:33]
	v_fmamk_f32 v79, v79, 0x3e0293ee, v99
	v_fmamk_f32 v80, v80, 0x3e0293ee, v99
	v_fmac_f32_e32 v99, 0x3e0293ee, v81
	v_exp_f32_e32 v79, v79
	v_exp_f32_e32 v80, v80
	v_exp_f32_e32 v81, v99
	v_cmp_gt_f32_e32 vcc, 1.0, v98
	s_cbranch_vccz .LBB0_1766
	s_and_saveexec_b64 s[4:5], s[6:7]
	ds_write_b32 v213, v98 offset:128
	s_or_b64 exec, exec, s[4:5]
	s_waitcnt lgkmcnt(0)
	ds_read_b128 v[100:103], v208 offset:224
	ds_read_b128 v[104:107], v208 offset:192
	ds_read_b128 v[108:111], v208 offset:160
	ds_read_b128 v[112:115], v208 offset:128
	s_waitcnt lgkmcnt(3)
	v_mul_f32_e32 v16, v16, v102
	v_mul_f32_e32 v17, v17, v103
	s_waitcnt lgkmcnt(2)
	v_mul_f32_e32 v12, v12, v106
	v_mul_f32_e32 v13, v13, v107
	s_waitcnt lgkmcnt(1)
	v_mul_f32_e32 v8, v8, v110
	v_mul_f32_e32 v9, v9, v111
	s_waitcnt lgkmcnt(0)
	v_mul_f32_e32 v4, v4, v114
	v_mul_f32_e32 v5, v5, v115
	v_mul_f32_e32 v14, v14, v100
	v_mul_f32_e32 v15, v15, v101
	v_mul_f32_e32 v10, v10, v104
	v_mul_f32_e32 v11, v11, v105
	v_mul_f32_e32 v6, v6, v108
	v_mul_f32_e32 v7, v7, v109
	v_mul_f32_e32 v2, v2, v112
	v_mul_f32_e32 v3, v3, v113
	v_mul_f32_e32 v64, v64, v102
	v_mul_f32_e32 v65, v65, v103
	v_mul_f32_e32 v60, v60, v106
	v_mul_f32_e32 v61, v61, v107
	v_mul_f32_e32 v56, v56, v110
	v_mul_f32_e32 v57, v57, v111
	v_mul_f32_e32 v52, v52, v114
	v_mul_f32_e32 v53, v53, v115
	v_mul_f32_e32 v62, v62, v100
	v_mul_f32_e32 v63, v63, v101
	v_mul_f32_e32 v58, v58, v104
	v_mul_f32_e32 v59, v59, v105
	v_mul_f32_e32 v54, v54, v108
	v_mul_f32_e32 v55, v55, v109
	v_mul_f32_e32 v50, v50, v112
	v_mul_f32_e32 v51, v51, v113
	v_mul_f32_e32 v48, v48, v102
	v_mul_f32_e32 v49, v49, v103
	v_mul_f32_e32 v44, v44, v106
	v_mul_f32_e32 v45, v45, v107
	v_mul_f32_e32 v40, v40, v110
	v_mul_f32_e32 v41, v41, v111
	v_mul_f32_e32 v36, v36, v114
	v_mul_f32_e32 v37, v37, v115
	v_mul_f32_e32 v46, v46, v100
	v_mul_f32_e32 v47, v47, v101
	v_mul_f32_e32 v42, v42, v104
	v_mul_f32_e32 v43, v43, v105
	v_mul_f32_e32 v38, v38, v108
	v_mul_f32_e32 v39, v39, v109
	v_mul_f32_e32 v34, v34, v112
	v_mul_f32_e32 v35, v35, v113
	v_mul_f32_e32 v32, v32, v102
	v_mul_f32_e32 v33, v33, v103
	v_mul_f32_e32 v28, v28, v106
	v_mul_f32_e32 v29, v29, v107
	v_mul_f32_e32 v24, v24, v110
	v_mul_f32_e32 v25, v25, v111
	v_mul_f32_e32 v20, v20, v114
	v_mul_f32_e32 v21, v21, v115
	v_mul_f32_e32 v30, v30, v100
	v_mul_f32_e32 v31, v31, v101
	v_mul_f32_e32 v26, v26, v104
	v_mul_f32_e32 v27, v27, v105
	v_mul_f32_e32 v22, v22, v108
	v_mul_f32_e32 v23, v23, v109
	v_mul_f32_e32 v18, v18, v112
	v_mul_f32_e32 v19, v19, v113

.LBB0_1770:
	ds_read_b128 v[98:101], v216 offset:17408
	ds_read_b128 v[102:105], v216 offset:26112
	ds_read_b128 v[162:165], v216 offset:17440
	s_waitcnt vmcnt(0)
	v_add_f32_e32 v174, 0, v82
	v_add_f32_e32 v175, 0, v83
	s_waitcnt lgkmcnt(2)
	v_mfma_f32_32x32x16_bf16 v[114:129], v[98:101], v[158:161], 0
	v_mov_b32_e32 v98, v195
	v_mov_b32_e32 v99, v195
	s_nop 0
	v_add_f32_e32 v176, v84, v98
	v_add_f32_e32 v177, v85, v99
	s_waitcnt lgkmcnt(1)
	v_mfma_f32_32x32x16_bf16 v[98:113], v[102:105], v[158:161], 0
	ds_read_b128 v[166:169], v216 offset:26144
	ds_read_b128 v[170:173], v216 offset:17472
	v_add_f32_e32 v174, v86, v174
	v_add_f32_e32 v175, v87, v175
	v_cvt_pk_bf16_f32 v158, v82, v83
	v_cvt_pk_bf16_f32 v159, v84, v85
	v_cvt_pk_bf16_f32 v160, v86, v87
	v_cvt_pk_bf16_f32 v161, v88, v89
	s_waitcnt lgkmcnt(2)
	v_mfma_f32_32x32x16_bf16 v[114:129], v[162:165], v[154:157], v[114:129]
	v_permlane32_swap_b32_e32 v158, v160
	v_permlane32_swap_b32_e32 v159, v161
	s_waitcnt lgkmcnt(1)
	v_mfma_f32_32x32x16_bf16 v[98:113], v[166:169], v[154:157], v[98:113]
	ds_read_b128 v[82:85], v216 offset:26176
	v_add_f32_e32 v162, v88, v176
	v_add_f32_e32 v163, v89, v177
	ds_read_b128 v[86:89], v216 offset:17504
	v_add_f32_e32 v164, v90, v174
	v_add_f32_e32 v165, v91, v175
	s_waitcnt lgkmcnt(2)
	v_mfma_f32_32x32x16_bf16 v[114:129], v[170:173], v[150:153], v[114:129]
	s_waitcnt lgkmcnt(1)
	v_mfma_f32_32x32x16_bf16 v[98:113], v[82:85], v[150:153], v[98:113]
	ds_read_b128 v[154:157], v216 offset:26208
	v_add_f32_e32 v162, v92, v162
	v_add_f32_e32 v163, v93, v163
	ds_read_b128 v[82:85], v216 offset:17536
	v_add_f32_e32 v164, v94, v164
	v_add_f32_e32 v165, v95, v165
	v_cvt_pk_bf16_f32 v150, v90, v91
	v_cvt_pk_bf16_f32 v151, v92, v93
	v_cvt_pk_bf16_f32 v152, v94, v95
	v_cvt_pk_bf16_f32 v153, v96, v97
	s_waitcnt lgkmcnt(2)
	v_mfma_f32_32x32x16_bf16 v[114:129], v[86:89], v[146:149], v[114:129]
	v_permlane32_swap_b32_e32 v150, v152
	v_permlane32_swap_b32_e32 v151, v153
	s_waitcnt lgkmcnt(1)
	v_mfma_f32_32x32x16_bf16 v[98:113], v[154:157], v[146:149], v[98:113]
	ds_read_b128 v[86:89], v216 offset:26240
	v_add_f32_e32 v94, v96, v162
	v_add_f32_e32 v95, v97, v163
	ds_read_b128 v[90:93], v216 offset:17568
	v_add_f32_e32 v96, v66, v164
	v_add_f32_e32 v97, v67, v165
	s_waitcnt lgkmcnt(2)
	v_mfma_f32_32x32x16_bf16 v[114:129], v[82:85], v[142:145], v[114:129]
	s_waitcnt lgkmcnt(1)
	v_mfma_f32_32x32x16_bf16 v[98:113], v[86:89], v[142:145], v[98:113]
	ds_read_b128 v[82:85], v216 offset:26272
	v_add_f32_e32 v94, v68, v94
	v_add_f32_e32 v95, v69, v95
	ds_read_b128 v[86:89], v216 offset:17600
	v_add_f32_e32 v96, v70, v96
	v_add_f32_e32 v97, v71, v97
	v_cvt_pk_bf16_f32 v142, v66, v67
	v_cvt_pk_bf16_f32 v143, v68, v69
	v_cvt_pk_bf16_f32 v144, v70, v71
	v_cvt_pk_bf16_f32 v145, v72, v73
	s_waitcnt lgkmcnt(2)
	v_mfma_f32_32x32x16_bf16 v[114:129], v[90:93], v[138:141], v[114:129]
	v_permlane32_swap_b32_e32 v142, v144
	v_permlane32_swap_b32_e32 v143, v145
	s_waitcnt lgkmcnt(1)
	v_mfma_f32_32x32x16_bf16 v[98:113], v[82:85], v[138:141], v[98:113]
	ds_read_b128 v[66:69], v216 offset:26304
	v_add_f32_e32 v90, v72, v94
	v_add_f32_e32 v91, v73, v95
	ds_read_b128 v[70:73], v216 offset:17632
	v_add_f32_e32 v92, v74, v96
	v_add_f32_e32 v93, v75, v97
	s_waitcnt lgkmcnt(2)
	v_mfma_f32_32x32x16_bf16 v[114:129], v[86:89], v[134:137], v[114:129]
	s_waitcnt lgkmcnt(1)
	v_mfma_f32_32x32x16_bf16 v[98:113], v[66:69], v[134:137], v[98:113]
	ds_read_b128 v[82:85], v216 offset:26336
	v_add_f32_e32 v86, v76, v90
	v_add_f32_e32 v87, v77, v91
	s_nop 0
	v_add_f32_e32 v66, v78, v92
	v_add_f32_e32 v67, v79, v93
	v_cvt_pk_bf16_f32 v134, v74, v75
	v_cvt_pk_bf16_f32 v135, v76, v77
	v_cvt_pk_bf16_f32 v136, v78, v79
	v_cvt_pk_bf16_f32 v137, v80, v81
	s_waitcnt lgkmcnt(1)
	v_mfma_f32_32x32x16_bf16 v[114:129], v[70:73], v[130:133], v[114:129]
	v_permlane32_swap_b32_e32 v134, v136
	v_permlane32_swap_b32_e32 v135, v137
	s_waitcnt lgkmcnt(0)
	v_mfma_f32_32x32x16_bf16 v[98:113], v[82:85], v[130:133], v[98:113]
	v_add_f32_e32 v68, v80, v86
	v_add_f32_e32 v69, v81, v87
	s_nop 0
	v_add_f32_e32 v66, v66, v67
	v_add_f32_e32 v67, v68, v69
	v_add_u32_e32 v132, s45, v211
	v_add_f32_e32 v130, v66, v67
	v_lshl_or_b32 v82, s43, 6, v207
	ds_read_b64_tr_b16 v[66:67], v132
	ds_read_b64_tr_b16 v[68:69], v132 offset:2048
	ds_read_b64_tr_b16 v[70:71], v132 offset:512
	ds_read_b64_tr_b16 v[74:75], v132 offset:1024
	ds_read_b64_tr_b16 v[72:73], v132 offset:2560
	ds_read_b64_tr_b16 v[76:77], v132 offset:3072
	s_waitcnt lgkmcnt(4)
	v_mfma_f32_32x32x16_bf16 v[2:17], v[158:161], v[66:69], v[2:17]
	v_sub_u32_e32 v66, v214, v82
	v_cmp_lt_u32_e32 vcc, s31, v66
	v_sub_u32_e32 v67, v82, v214
	v_or_b32_e32 v68, 2, v82
	v_cndmask_b32_e32 v66, v1, v114, vcc
	v_cmp_gt_u32_e32 vcc, s34, v67
	v_sub_u32_e32 v69, v214, v68
	v_or_b32_e32 v133, 8, v82
	v_cndmask_b32_e32 v83, v1, v115, vcc
	v_cmp_lt_u32_e32 vcc, s31, v69
	v_or_b32_e32 v69, 3, v82
	v_sub_u32_e32 v78, v214, v69
	v_cndmask_b32_e32 v84, v1, v116, vcc
	v_cmp_lt_u32_e32 vcc, s31, v78
	v_sub_u32_e32 v78, v214, v133
	v_max3_f32 v67, v66, s35, v83
	v_cndmask_b32_e32 v85, v1, v117, vcc
	v_cmp_lt_u32_e32 vcc, s31, v78
	v_max3_f32 v67, v67, v84, v85
	v_mov_b32_e32 v131, v130
	v_cndmask_b32_e32 v86, v1, v118, vcc
	v_or_b32_e32 v118, 9, v82
	v_sub_u32_e32 v78, v214, v118
	v_cmp_lt_u32_e32 vcc, s31, v78
	v_permlane32_swap_b32_e32 v130, v131
	s_nop 0
	v_cndmask_b32_e32 v87, v1, v119, vcc
	v_or_b32_e32 v119, 10, v82
	v_sub_u32_e32 v78, v214, v119
	v_cmp_lt_u32_e32 vcc, s31, v78
	v_max3_f32 v67, v67, v86, v87
	s_nop 0
	v_cndmask_b32_e32 v88, v1, v120, vcc
	v_or_b32_e32 v120, 11, v82
	v_sub_u32_e32 v78, v214, v120
	v_cmp_lt_u32_e32 vcc, s31, v78
	s_nop 1
	v_cndmask_b32_e32 v89, v1, v121, vcc
	v_max3_f32 v67, v67, v88, v89
	v_or_b32_e32 v121, 16, v82
	v_sub_u32_e32 v90, v214, v121
	v_cmp_lt_u32_e32 vcc, s31, v90
	s_waitcnt lgkmcnt(1)
	v_mfma_f32_32x32x16_bf16 v[50:65], v[158:161], v[70:73], v[50:65]
	ds_read_b64_tr_b16 v[78:79], v132 offset:1536
	ds_read_b64_tr_b16 v[80:81], v132 offset:3584
	v_cndmask_b32_e32 v90, v1, v122, vcc
	v_or_b32_e32 v122, 17, v82
	v_sub_u32_e32 v70, v214, v122
	v_cmp_lt_u32_e32 vcc, s31, v70
	s_nop 1
	v_cndmask_b32_e32 v91, v1, v123, vcc
	v_or_b32_e32 v123, 18, v82
	v_sub_u32_e32 v70, v214, v123
	v_cmp_lt_u32_e32 vcc, s31, v70
	v_max3_f32 v67, v67, v90, v91
	s_nop 0
	v_cndmask_b32_e32 v92, v1, v124, vcc
	v_or_b32_e32 v124, 19, v82
	v_sub_u32_e32 v70, v214, v124
	v_cmp_lt_u32_e32 vcc, s31, v70
	s_nop 1
	v_cndmask_b32_e32 v93, v1, v125, vcc
	v_or_b32_e32 v125, 24, v82
	v_sub_u32_e32 v70, v214, v125
	v_cmp_lt_u32_e32 vcc, s31, v70
	v_max3_f32 v67, v67, v92, v93
	s_nop 0
	v_cndmask_b32_e32 v94, v1, v126, vcc
	v_or_b32_e32 v126, 25, v82
	v_sub_u32_e32 v70, v214, v126
	v_cmp_lt_u32_e32 vcc, s31, v70
	s_nop 1
	v_cndmask_b32_e32 v95, v1, v127, vcc
	v_or_b32_e32 v127, 26, v82
	v_sub_u32_e32 v70, v214, v127
	v_cmp_lt_u32_e32 vcc, s31, v70
	v_max3_f32 v67, v67, v94, v95
	s_nop 0
	v_cndmask_b32_e32 v96, v1, v128, vcc
	v_or_b32_e32 v128, 27, v82
	v_sub_u32_e32 v70, v214, v128
	v_cmp_lt_u32_e32 vcc, s31, v70
	s_nop 1
	v_cndmask_b32_e32 v97, v1, v129, vcc
	v_max3_f32 v70, v67, v96, v97
	v_sub_u32_e32 v67, v215, v82
	v_cmp_lt_u32_e32 vcc, s31, v67
	v_sub_u32_e32 v67, v82, v215
	v_sub_u32_e32 v68, v215, v68
	v_cndmask_b32_e32 v129, v1, v98, vcc
	v_cmp_gt_u32_e32 vcc, s34, v67
	v_sub_u32_e32 v69, v215, v69
	s_waitcnt lgkmcnt(2)
	v_mfma_f32_32x32x16_bf16 v[34:49], v[158:161], v[74:77], v[34:49]
	v_cndmask_b32_e32 v67, v1, v99, vcc
	v_cmp_lt_u32_e32 vcc, s31, v68
	v_max3_f32 v70, v70, v129, v67
	v_sub_u32_e32 v71, v215, v118
	v_cndmask_b32_e32 v68, v1, v100, vcc
	v_cmp_lt_u32_e32 vcc, s31, v69
	ds_read_b64_tr_b16 v[114:115], v132 offset:4096
	ds_read_b64_tr_b16 v[116:117], v132 offset:6144
	v_cndmask_b32_e32 v69, v1, v101, vcc
	v_max3_f32 v72, v70, v68, v69
	v_sub_u32_e32 v70, v215, v133
	v_cmp_lt_u32_e32 vcc, s31, v70
	v_sub_u32_e32 v73, v215, v120
	s_nop 0
	v_cndmask_b32_e32 v70, v1, v102, vcc
	v_cmp_lt_u32_e32 vcc, s31, v71
	s_nop 1
	v_cndmask_b32_e32 v71, v1, v103, vcc
	v_max3_f32 v74, v72, v70, v71
	v_sub_u32_e32 v72, v215, v119
	v_cmp_lt_u32_e32 vcc, s31, v72
	s_nop 1
	v_cndmask_b32_e32 v72, v1, v104, vcc
	v_cmp_lt_u32_e32 vcc, s31, v73
	s_nop 1
	v_cndmask_b32_e32 v73, v1, v105, vcc
	v_max3_f32 v82, v74, v72, v73
	v_sub_u32_e32 v74, v215, v121
	v_cmp_lt_u32_e32 vcc, s31, v74
	v_sub_u32_e32 v75, v215, v122
	v_sub_u32_e32 v76, v215, v123
	v_cndmask_b32_e32 v74, v1, v106, vcc
	v_cmp_lt_u32_e32 vcc, s31, v75
	s_waitcnt lgkmcnt(2)
	v_mfma_f32_32x32x16_bf16 v[18:33], v[158:161], v[78:81], v[18:33]
	v_sub_u32_e32 v77, v215, v124
	v_cndmask_b32_e32 v75, v1, v107, vcc
	v_cmp_lt_u32_e32 vcc, s31, v76
	v_sub_u32_e32 v78, v215, v125
	v_sub_u32_e32 v79, v215, v126
	v_cndmask_b32_e32 v76, v1, v108, vcc
	v_cmp_lt_u32_e32 vcc, s31, v77
	ds_read_b64_tr_b16 v[100:101], v132 offset:4608
	ds_read_b64_tr_b16 v[102:103], v132 offset:6656
	v_cndmask_b32_e32 v77, v1, v109, vcc
	v_cmp_lt_u32_e32 vcc, s31, v78
	v_sub_u32_e32 v80, v215, v127
	v_sub_u32_e32 v81, v215, v128
	v_cndmask_b32_e32 v78, v1, v110, vcc
	v_cmp_lt_u32_e32 vcc, s31, v79
	v_max3_f32 v82, v82, v74, v75
	v_max3_f32 v82, v82, v76, v77
	v_cndmask_b32_e32 v79, v1, v111, vcc
	v_cmp_lt_u32_e32 vcc, s31, v80
	v_max3_f32 v82, v82, v78, v79
	s_nop 0
	v_cndmask_b32_e32 v80, v1, v112, vcc
	v_cmp_lt_u32_e32 vcc, s31, v81
	s_nop 1
	v_cndmask_b32_e32 v81, v1, v113, vcc
	v_max3_f32 v82, v82, v80, v81
	s_nop 0
	v_mov_b32_e32 v98, v82
	s_nop 1
	v_permlane32_swap_b32_e32 v82, v98
	v_max_f32_e32 v98, v98, v98
	v_max_f32_e32 v82, v82, v82
	v_max_f32_e32 v82, v82, v98
	v_sub_f32_e32 v98, v82, v225
	s_waitcnt lgkmcnt(2)
	v_mfma_f32_32x32x16_bf16 v[2:17], v[150:153], v[114:117], v[2:17]
	v_cmp_ge_f32_e32 vcc, s36, v98
	s_cmp_eq_u64 vcc, exec
	v_max_f32_e32 v98, v225, v225
	ds_read_b64_tr_b16 v[104:105], v132 offset:5120
	ds_read_b64_tr_b16 v[106:107], v132 offset:7168
	v_max_f32_e32 v82, v98, v82
	s_cselect_b64 vcc, -1, 0
	v_cndmask_b32_e32 v82, v82, v225, vcc
	v_sub_f32_e32 v98, v225, v82
	v_mul_f32_e32 v98, 0x3e0293ee, v98
	v_exp_f32_e32 v98, v98
	v_fma_f32 v99, v82, s37, 0
	s_waitcnt lgkmcnt(2)
	v_mfma_f32_32x32x16_bf16 v[50:65], v[150:153], v[100:103], v[50:65]
	ds_read_b64_tr_b16 v[108:109], v132 offset:5632
	ds_read_b64_tr_b16 v[110:111], v132 offset:7680
	v_fmamk_f32 v66, v66, 0x3e0293ee, v99
	v_exp_f32_e32 v82, v66
	v_fmamk_f32 v66, v83, 0x3e0293ee, v99
	v_exp_f32_e32 v83, v66
	s_waitcnt lgkmcnt(2)
	v_mfma_f32_32x32x16_bf16 v[34:49], v[150:153], v[104:107], v[34:49]
	ds_read_b64_tr_b16 v[100:101], v132 offset:8192
	ds_read_b64_tr_b16 v[102:103], v132 offset:10240
	v_fmamk_f32 v66, v84, 0x3e0293ee, v99
	v_exp_f32_e32 v84, v66
	v_fmamk_f32 v66, v85, 0x3e0293ee, v99
	v_exp_f32_e32 v85, v66
	v_fmamk_f32 v66, v86, 0x3e0293ee, v99
	v_exp_f32_e32 v86, v66
	s_waitcnt lgkmcnt(2)
	v_mfma_f32_32x32x16_bf16 v[18:33], v[150:153], v[108:111], v[18:33]
	ds_read_b64_tr_b16 v[104:105], v132 offset:8704
	ds_read_b64_tr_b16 v[106:107], v132 offset:10752
	v_fmamk_f32 v66, v87, 0x3e0293ee, v99
	v_exp_f32_e32 v87, v66
	v_fmamk_f32 v66, v88, 0x3e0293ee, v99
	v_exp_f32_e32 v88, v66
	v_fmamk_f32 v66, v89, 0x3e0293ee, v99
	v_exp_f32_e32 v89, v66
	s_waitcnt lgkmcnt(2)
	v_mfma_f32_32x32x16_bf16 v[2:17], v[142:145], v[100:103], v[2:17]
	ds_read_b64_tr_b16 v[108:109], v132 offset:9216
	ds_read_b64_tr_b16 v[110:111], v132 offset:11264
	v_fmamk_f32 v66, v90, 0x3e0293ee, v99
	v_exp_f32_e32 v90, v66
	v_fmamk_f32 v66, v91, 0x3e0293ee, v99
	v_exp_f32_e32 v91, v66
	v_fmamk_f32 v66, v92, 0x3e0293ee, v99
	v_exp_f32_e32 v92, v66
	s_waitcnt lgkmcnt(2)
	v_mfma_f32_32x32x16_bf16 v[50:65], v[142:145], v[104:107], v[50:65]
	ds_read_b64_tr_b16 v[100:101], v132 offset:9728
	ds_read_b64_tr_b16 v[102:103], v132 offset:11776
	v_fmamk_f32 v66, v93, 0x3e0293ee, v99
	v_exp_f32_e32 v93, v66
	v_fmamk_f32 v66, v94, 0x3e0293ee, v99
	v_exp_f32_e32 v94, v66
	v_fmamk_f32 v66, v95, 0x3e0293ee, v99
	v_exp_f32_e32 v95, v66
	s_waitcnt lgkmcnt(2)
	v_mfma_f32_32x32x16_bf16 v[34:49], v[142:145], v[108:111], v[34:49]
	ds_read_b64_tr_b16 v[104:105], v132 offset:12288
	ds_read_b64_tr_b16 v[106:107], v132 offset:14336
	v_fmamk_f32 v66, v96, 0x3e0293ee, v99
	v_exp_f32_e32 v96, v66
	v_fmamk_f32 v66, v97, 0x3e0293ee, v99
	v_exp_f32_e32 v97, v66
	v_fmamk_f32 v66, v129, 0x3e0293ee, v99
	v_exp_f32_e32 v66, v66
	s_waitcnt lgkmcnt(2)
	v_mfma_f32_32x32x16_bf16 v[18:33], v[142:145], v[100:103], v[18:33]
	ds_read_b64_tr_b16 v[108:109], v132 offset:12800
	ds_read_b64_tr_b16 v[110:111], v132 offset:14848
	v_fmamk_f32 v67, v67, 0x3e0293ee, v99
	v_fmamk_f32 v68, v68, 0x3e0293ee, v99
	v_fmamk_f32 v69, v69, 0x3e0293ee, v99
	v_exp_f32_e32 v67, v67
	v_exp_f32_e32 v68, v68
	v_exp_f32_e32 v69, v69
	s_waitcnt lgkmcnt(2)
	v_mfma_f32_32x32x16_bf16 v[2:17], v[134:137], v[104:107], v[2:17]
	ds_read_b64_tr_b16 v[100:101], v132 offset:13312
	ds_read_b64_tr_b16 v[102:103], v132 offset:15360
	v_fmamk_f32 v70, v70, 0x3e0293ee, v99
	v_fmamk_f32 v71, v71, 0x3e0293ee, v99
	v_fmamk_f32 v72, v72, 0x3e0293ee, v99
	v_exp_f32_e32 v70, v70
	v_exp_f32_e32 v71, v71
	v_exp_f32_e32 v72, v72
	s_waitcnt lgkmcnt(2)
	v_mfma_f32_32x32x16_bf16 v[50:65], v[134:137], v[108:111], v[50:65]
	ds_read_b64_tr_b16 v[104:105], v132 offset:13824
	ds_read_b64_tr_b16 v[106:107], v132 offset:15872
	v_fmamk_f32 v73, v73, 0x3e0293ee, v99
	v_fmamk_f32 v74, v74, 0x3e0293ee, v99
	v_fmamk_f32 v75, v75, 0x3e0293ee, v99
	v_exp_f32_e32 v73, v73
	v_exp_f32_e32 v74, v74
	v_exp_f32_e32 v75, v75
	s_waitcnt lgkmcnt(2)
	v_mfma_f32_32x32x16_bf16 v[34:49], v[134:137], v[100:103], v[34:49]
	v_fmamk_f32 v76, v76, 0x3e0293ee, v99
	v_fmamk_f32 v77, v77, 0x3e0293ee, v99
	v_fmamk_f32 v78, v78, 0x3e0293ee, v99
	v_exp_f32_e32 v76, v76
	v_exp_f32_e32 v77, v77
	v_exp_f32_e32 v78, v78
	s_waitcnt lgkmcnt(0)
	v_mfma_f32_32x32x16_bf16 v[18:33], v[134:137], v[104:107], v[18:33]
	v_fmamk_f32 v79, v79, 0x3e0293ee, v99
	v_fmamk_f32 v80, v80, 0x3e0293ee, v99
	v_fmac_f32_e32 v99, 0x3e0293ee, v81
	v_exp_f32_e32 v79, v79
	v_exp_f32_e32 v80, v80
	v_exp_f32_e32 v81, v99
	v_cmp_gt_f32_e32 vcc, 1.0, v98
	s_cbranch_vccz .LBB0_1774
	v_cmp_gt_u32_e32 vcc, 32, v194
	s_and_saveexec_b64 s[4:5], vcc
	ds_write_b32 v213, v98 offset:128
	s_or_b64 exec, exec, s[4:5]
	s_waitcnt lgkmcnt(0)
	ds_read_b128 v[100:103], v208 offset:224
	ds_read_b128 v[104:107], v208 offset:192
	ds_read_b128 v[108:111], v208 offset:160
	ds_read_b128 v[112:115], v208 offset:128
	s_waitcnt lgkmcnt(3)
	v_mul_f32_e32 v16, v16, v102
	v_mul_f32_e32 v17, v17, v103
	s_waitcnt lgkmcnt(2)
	v_mul_f32_e32 v12, v12, v106
	v_mul_f32_e32 v13, v13, v107
	s_waitcnt lgkmcnt(1)
	v_mul_f32_e32 v8, v8, v110
	v_mul_f32_e32 v9, v9, v111
	s_waitcnt lgkmcnt(0)
	v_mul_f32_e32 v4, v4, v114
	v_mul_f32_e32 v5, v5, v115
	v_mul_f32_e32 v14, v14, v100
	v_mul_f32_e32 v15, v15, v101
	v_mul_f32_e32 v10, v10, v104
	v_mul_f32_e32 v11, v11, v105
	v_mul_f32_e32 v6, v6, v108
	v_mul_f32_e32 v7, v7, v109
	v_mul_f32_e32 v2, v2, v112
	v_mul_f32_e32 v3, v3, v113
	v_mul_f32_e32 v64, v64, v102
	v_mul_f32_e32 v65, v65, v103
	v_mul_f32_e32 v60, v60, v106
	v_mul_f32_e32 v61, v61, v107
	v_mul_f32_e32 v56, v56, v110
	v_mul_f32_e32 v57, v57, v111
	v_mul_f32_e32 v52, v52, v114
	v_mul_f32_e32 v53, v53, v115
	v_mul_f32_e32 v62, v62, v100
	v_mul_f32_e32 v63, v63, v101
	v_mul_f32_e32 v58, v58, v104
	v_mul_f32_e32 v59, v59, v105
	v_mul_f32_e32 v54, v54, v108
	v_mul_f32_e32 v55, v55, v109
	v_mul_f32_e32 v50, v50, v112
	v_mul_f32_e32 v51, v51, v113
	v_mul_f32_e32 v48, v48, v102
	v_mul_f32_e32 v49, v49, v103
	v_mul_f32_e32 v44, v44, v106
	v_mul_f32_e32 v45, v45, v107
	v_mul_f32_e32 v40, v40, v110
	v_mul_f32_e32 v41, v41, v111
	v_mul_f32_e32 v36, v36, v114
	v_mul_f32_e32 v37, v37, v115
	v_mul_f32_e32 v46, v46, v100
	v_mul_f32_e32 v47, v47, v101
	v_mul_f32_e32 v42, v42, v104
	v_mul_f32_e32 v43, v43, v105
	v_mul_f32_e32 v38, v38, v108
	v_mul_f32_e32 v39, v39, v109
	v_mul_f32_e32 v34, v34, v112
	v_mul_f32_e32 v35, v35, v113
	v_mul_f32_e32 v32, v32, v102
	v_mul_f32_e32 v33, v33, v103
	v_mul_f32_e32 v28, v28, v106
	v_mul_f32_e32 v29, v29, v107
	v_mul_f32_e32 v24, v24, v110
	v_mul_f32_e32 v25, v25, v111
	v_mul_f32_e32 v20, v20, v114
	v_mul_f32_e32 v21, v21, v115
	v_mul_f32_e32 v30, v30, v100
	v_mul_f32_e32 v31, v31, v101
	v_mul_f32_e32 v26, v26, v104
	v_mul_f32_e32 v27, v27, v105
	v_mul_f32_e32 v22, v22, v108
	v_mul_f32_e32 v23, v23, v109
	v_mul_f32_e32 v18, v18, v112
	v_mul_f32_e32 v19, v19, v113

.LBB0_1881:
	s_cmpk_lg_i32 s64, 0x800
	s_cbranch_scc1 .LBB0_1880
	v_mov_b32_e32 v3, v0
	s_mov_b32 s8, 0x358637bd
	v_and_or_b32 v136, v3, 15, s4
	v_ashrrev_i32_e32 v137, 31, v136
	v_lshlrev_b64 v[4:5], 6, v[136:137]
	v_lshl_add_u64 v[134:135], s[22:23], 0, v[4:5]
	global_load_dwordx4 v[138:141], v[134:135], off offset:32
	global_load_dwordx4 v[142:145], v[134:135], off offset:48
	global_load_dwordx4 v[146:149], v[134:135], off
	global_load_dwordx4 v[152:155], v[134:135], off offset:16
	s_waitcnt vmcnt(0)
	v_add_f32_e32 v138, v138, v142
	v_add_f32_e32 v139, v139, v143
	v_add_f32_e32 v140, v140, v144
	v_add_f32_e32 v141, v141, v145
	v_add_f32_e32 v146, v146, v152
	v_add_f32_e32 v147, v147, v153
	v_add_f32_e32 v4, v148, v154
	v_add_f32_e32 v5, v149, v155
	v_mov_b32_e32 v142, v138
	v_mov_b32_e32 v143, v146
	v_mov_b32_e32 v146, v139
	v_add_f32_e32 v138, v142, v146
	v_add_f32_e32 v139, v143, v147
	v_mov_b32_e32 v142, v140
	v_mov_b32_e32 v143, v4
	v_mov_b32_e32 v4, v141
	v_add_f32_e32 v4, v142, v4
	v_add_f32_e32 v5, v143, v5
	s_nop 0
	v_add_f32_e32 v138, v138, v4
	v_add_f32_e32 v139, v139, v5
	v_mov_b64_e32 v[4:5], s[8:9]
	v_fma_f32 v138, v138, s44, v4
	v_fma_f32 v139, v139, s44, v4
	s_nop 0
	v_div_scale_f32 v3, s[8:9], v139, v139, v138
	v_rcp_f32_e32 v137, v3
	s_nop 0
	v_fma_f32 v140, -v3, v137, 1.0
	v_fmac_f32_e32 v137, v140, v137
	v_div_scale_f32 v140, vcc, v138, v139, v138
	v_mul_f32_e32 v141, v140, v137
	v_fma_f32 v142, -v3, v141, v140
	v_fmac_f32_e32 v141, v142, v137
	v_fma_f32 v3, -v3, v141, v140
	v_div_fmas_f32 v3, v3, v137, v141
	v_div_fixup_f32 v3, v3, v139, v138
	v_cmp_gt_f32_e32 vcc, s76, v3
	v_mul_f32_e32 v137, 0x4f800000, v3
	s_nop 0
	v_cndmask_b32_e32 v3, v3, v137, vcc
	v_sqrt_f32_e32 v137, v3
	s_nop 0
	v_add_u32_e32 v138, -1, v137
	v_fma_f32 v139, -v138, v137, v3
	v_cmp_ge_f32_e64 s[8:9], 0, v139
	v_add_u32_e32 v139, 1, v137
	s_nop 0
	v_cndmask_b32_e64 v138, v137, v138, s[8:9]
	v_fma_f32 v137, -v139, v137, v3
	v_cmp_lt_f32_e64 s[8:9], 0, v137
	s_nop 1
	v_cndmask_b32_e64 v137, v138, v139, s[8:9]
	v_mul_f32_e32 v138, 0x37800000, v137
	v_cndmask_b32_e32 v137, v137, v138, vcc
	v_cmp_class_f32_e32 vcc, v3, v178
	s_nop 1
	v_cndmask_b32_e32 v138, v137, v3, vcc
	v_mul_f32_e32 v132, v132, v138
	v_mul_f32_e32 v133, v133, v138
	v_mul_f32_e32 v130, v130, v138
	v_mul_f32_e32 v131, v131, v138
	v_mul_f32_e32 v128, v128, v138
	v_mul_f32_e32 v129, v129, v138
	v_mul_f32_e32 v126, v126, v138
	v_mul_f32_e32 v127, v127, v138
	v_mul_f32_e32 v124, v124, v138
	v_mul_f32_e32 v125, v125, v138
	v_mul_f32_e32 v122, v122, v138
	v_mul_f32_e32 v123, v123, v138
	v_mul_f32_e32 v120, v120, v138
	v_mul_f32_e32 v121, v121, v138
	v_mul_f32_e32 v118, v118, v138
	v_mul_f32_e32 v119, v119, v138
	v_or_b32_e32 v138, 16, v136
	v_ashrrev_i32_e32 v139, 31, v138
	v_lshlrev_b64 v[138:139], 6, v[138:139]
	v_lshl_add_u64 v[152:153], s[22:23], 0, v[138:139]
	global_load_dwordx4 v[138:141], v[152:153], off offset:32
	global_load_dwordx4 v[142:145], v[152:153], off offset:48
	global_load_dwordx4 v[146:149], v[152:153], off
	s_nop 0
	global_load_dwordx4 v[152:155], v[152:153], off offset:16
	s_waitcnt vmcnt(2)
	v_add_f32_e32 v138, v138, v142
	v_add_f32_e32 v139, v139, v143
	v_add_f32_e32 v140, v140, v144
	v_add_f32_e32 v141, v141, v145
	s_waitcnt vmcnt(0)
	v_add_f32_e32 v146, v146, v152
	v_add_f32_e32 v147, v147, v153
	v_add_f32_e32 v148, v148, v154
	v_add_f32_e32 v149, v149, v155
	v_mov_b32_e32 v142, v138
	v_mov_b32_e32 v143, v146
	v_mov_b32_e32 v146, v139
	v_add_f32_e32 v138, v142, v146
	v_add_f32_e32 v139, v143, v147
	v_mov_b32_e32 v142, v140
	v_mov_b32_e32 v143, v148
	v_mov_b32_e32 v148, v141
	v_add_f32_e32 v140, v142, v148
	v_add_f32_e32 v141, v143, v149
	s_nop 0
	v_add_f32_e32 v138, v138, v140
	v_add_f32_e32 v139, v139, v141
	s_nop 0
	v_fma_f32 v138, v138, s44, v4
	v_fma_f32 v139, v139, s44, v4
	s_nop 0
	v_div_scale_f32 v3, s[8:9], v139, v139, v138
	v_rcp_f32_e32 v137, v3
	s_nop 0
	v_fma_f32 v140, -v3, v137, 1.0
	v_fmac_f32_e32 v137, v140, v137
	v_div_scale_f32 v140, vcc, v138, v139, v138
	v_mul_f32_e32 v141, v140, v137
	v_fma_f32 v142, -v3, v141, v140
	v_fmac_f32_e32 v141, v142, v137
	v_fma_f32 v3, -v3, v141, v140
	v_div_fmas_f32 v3, v3, v137, v141
	v_div_fixup_f32 v3, v3, v139, v138
	v_cmp_gt_f32_e32 vcc, s76, v3
	v_mul_f32_e32 v137, 0x4f800000, v3
	s_nop 0
	v_cndmask_b32_e32 v3, v3, v137, vcc
	v_sqrt_f32_e32 v137, v3
	s_nop 0
	v_add_u32_e32 v138, -1, v137
	v_fma_f32 v139, -v138, v137, v3
	v_cmp_ge_f32_e64 s[8:9], 0, v139
	v_add_u32_e32 v139, 1, v137
	s_nop 0
	v_cndmask_b32_e64 v138, v137, v138, s[8:9]
	v_fma_f32 v137, -v139, v137, v3
	v_cmp_lt_f32_e64 s[8:9], 0, v137
	s_nop 1
	v_cndmask_b32_e64 v137, v138, v139, s[8:9]
	v_mul_f32_e32 v138, 0x37800000, v137
	v_cndmask_b32_e32 v137, v137, v138, vcc
	v_cmp_class_f32_e32 vcc, v3, v178
	s_nop 1
	v_cndmask_b32_e32 v138, v137, v3, vcc
	v_mul_f32_e32 v116, v116, v138
	v_mul_f32_e32 v117, v117, v138
	v_mul_f32_e32 v114, v114, v138
	v_mul_f32_e32 v115, v115, v138
	v_mul_f32_e32 v112, v112, v138
	v_mul_f32_e32 v113, v113, v138
	v_mul_f32_e32 v110, v110, v138
	v_mul_f32_e32 v111, v111, v138
	v_mul_f32_e32 v108, v108, v138
	v_mul_f32_e32 v109, v109, v138
	v_mul_f32_e32 v106, v106, v138
	v_mul_f32_e32 v107, v107, v138
	v_mul_f32_e32 v104, v104, v138
	v_mul_f32_e32 v105, v105, v138
	v_mul_f32_e32 v102, v102, v138
	v_mul_f32_e32 v103, v103, v138
	v_or_b32_e32 v138, 32, v136
	v_ashrrev_i32_e32 v139, 31, v138
	v_lshlrev_b64 v[138:139], 6, v[138:139]
	v_lshl_add_u64 v[152:153], s[22:23], 0, v[138:139]
	global_load_dwordx4 v[138:141], v[152:153], off offset:32
	global_load_dwordx4 v[142:145], v[152:153], off offset:48
	global_load_dwordx4 v[146:149], v[152:153], off
	s_nop 0
	global_load_dwordx4 v[152:155], v[152:153], off offset:16
	v_or_b32_e32 v136, 48, v136
	s_waitcnt vmcnt(2)
	v_add_f32_e32 v138, v138, v142
	v_add_f32_e32 v139, v139, v143
	v_add_f32_e32 v140, v140, v144
	v_add_f32_e32 v141, v141, v145
	s_waitcnt vmcnt(0)
	v_add_f32_e32 v146, v146, v152
	v_add_f32_e32 v147, v147, v153
	v_add_f32_e32 v148, v148, v154
	v_add_f32_e32 v149, v149, v155
	v_mov_b32_e32 v142, v138
	v_mov_b32_e32 v143, v146
	v_mov_b32_e32 v146, v139
	v_add_f32_e32 v138, v142, v146
	v_add_f32_e32 v139, v143, v147
	v_mov_b32_e32 v142, v140
	v_mov_b32_e32 v143, v148
	v_mov_b32_e32 v148, v141
	v_add_f32_e32 v140, v142, v148
	v_add_f32_e32 v141, v143, v149
	s_nop 0
	v_add_f32_e32 v138, v138, v140
	v_add_f32_e32 v139, v139, v141
	s_nop 0
	v_fma_f32 v138, v138, s44, v4
	v_fma_f32 v139, v139, s44, v4
	s_nop 0
	v_div_scale_f32 v3, s[8:9], v139, v139, v138
	v_rcp_f32_e32 v137, v3
	s_nop 0
	v_fma_f32 v140, -v3, v137, 1.0
	v_fmac_f32_e32 v137, v140, v137
	v_div_scale_f32 v140, vcc, v138, v139, v138
	v_mul_f32_e32 v141, v140, v137
	v_fma_f32 v142, -v3, v141, v140
	v_fmac_f32_e32 v141, v142, v137
	v_fma_f32 v3, -v3, v141, v140
	v_div_fmas_f32 v3, v3, v137, v141
	v_div_fixup_f32 v3, v3, v139, v138
	v_cmp_gt_f32_e32 vcc, s76, v3
	v_mul_f32_e32 v137, 0x4f800000, v3
	s_nop 0
	v_cndmask_b32_e32 v3, v3, v137, vcc
	v_sqrt_f32_e32 v137, v3
	s_nop 0
	v_add_u32_e32 v138, -1, v137
	v_fma_f32 v139, -v138, v137, v3
	v_cmp_ge_f32_e64 s[8:9], 0, v139
	v_add_u32_e32 v139, 1, v137
	s_nop 0
	v_cndmask_b32_e64 v138, v137, v138, s[8:9]
	v_fma_f32 v137, -v139, v137, v3
	v_cmp_lt_f32_e64 s[8:9], 0, v137
	s_nop 1
	v_cndmask_b32_e64 v137, v138, v139, s[8:9]
	v_mul_f32_e32 v138, 0x37800000, v137
	v_cndmask_b32_e32 v137, v137, v138, vcc
	v_cmp_class_f32_e32 vcc, v3, v178
	s_nop 1
	v_cndmask_b32_e32 v138, v137, v3, vcc
	v_ashrrev_i32_e32 v137, 31, v136
	v_lshlrev_b64 v[136:137], 6, v[136:137]
	v_lshl_add_u64 v[148:149], s[22:23], 0, v[136:137]
	v_mul_f32_e32 v100, v100, v138
	v_mul_f32_e32 v101, v101, v138
	v_mul_f32_e32 v98, v98, v138
	v_mul_f32_e32 v99, v99, v138
	v_mul_f32_e32 v96, v96, v138
	v_mul_f32_e32 v97, v97, v138
	v_mul_f32_e32 v94, v94, v138
	v_mul_f32_e32 v95, v95, v138
	v_mul_f32_e32 v92, v92, v138
	v_mul_f32_e32 v93, v93, v138
	v_mul_f32_e32 v90, v90, v138
	v_mul_f32_e32 v91, v91, v138
	v_mul_f32_e32 v88, v88, v138
	v_mul_f32_e32 v89, v89, v138
	v_mul_f32_e32 v86, v86, v138
	v_mul_f32_e32 v87, v87, v138
	global_load_dwordx4 v[136:139], v[148:149], off offset:32
	global_load_dwordx4 v[140:143], v[148:149], off offset:48
	global_load_dwordx4 v[144:147], v[148:149], off
	global_load_dwordx4 v[152:155], v[148:149], off offset:16
	s_waitcnt vmcnt(2)
	v_add_f32_e32 v136, v136, v140
	v_add_f32_e32 v137, v137, v141
	v_add_f32_e32 v138, v138, v142
	v_add_f32_e32 v139, v139, v143
	s_waitcnt vmcnt(0)
	v_add_f32_e32 v144, v144, v152
	v_add_f32_e32 v145, v145, v153
	v_add_f32_e32 v146, v146, v154
	v_add_f32_e32 v147, v147, v155
	v_mov_b32_e32 v140, v136
	v_mov_b32_e32 v141, v144
	v_mov_b32_e32 v144, v137
	v_add_f32_e32 v136, v140, v144
	v_add_f32_e32 v137, v141, v145
	v_mov_b32_e32 v140, v138
	v_mov_b32_e32 v141, v146
	v_mov_b32_e32 v146, v139
	v_add_f32_e32 v138, v140, v146
	v_add_f32_e32 v139, v141, v147
	s_nop 0
	v_add_f32_e32 v136, v136, v138
	v_add_f32_e32 v137, v137, v139
	s_nop 0
	v_fma_f32 v136, v136, s44, v4
	v_fma_f32 v137, v137, s44, v4
	s_nop 0
	v_div_scale_f32 v3, s[8:9], v137, v137, v136
	v_rcp_f32_e32 v138, v3
	s_nop 0
	v_fma_f32 v139, -v3, v138, 1.0
	v_fmac_f32_e32 v138, v139, v138
	v_div_scale_f32 v139, vcc, v136, v137, v136
	v_mul_f32_e32 v140, v139, v138
	v_fma_f32 v141, -v3, v140, v139
	v_fmac_f32_e32 v140, v141, v138
	v_fma_f32 v3, -v3, v140, v139
	v_div_fmas_f32 v3, v3, v138, v140
	v_div_fixup_f32 v3, v3, v137, v136
	v_cmp_gt_f32_e32 vcc, s76, v3
	v_mul_f32_e32 v136, 0x4f800000, v3
	s_nop 0
	v_cndmask_b32_e32 v3, v3, v136, vcc
	v_sqrt_f32_e32 v136, v3
	s_nop 0
	v_add_u32_e32 v137, -1, v136
	v_fma_f32 v138, -v137, v136, v3
	v_cmp_ge_f32_e64 s[8:9], 0, v138
	v_add_u32_e32 v138, 1, v136
	s_nop 0
	v_cndmask_b32_e64 v137, v136, v137, s[8:9]
	v_fma_f32 v136, -v138, v136, v3
	v_cmp_lt_f32_e64 s[8:9], 0, v136
	s_nop 1
	v_cndmask_b32_e64 v136, v137, v138, s[8:9]
	v_mul_f32_e32 v137, 0x37800000, v136
	v_cndmask_b32_e32 v136, v136, v137, vcc
	v_cmp_class_f32_e32 vcc, v3, v178
	s_mov_b64 s[8:9], 0x2000
	v_lshl_add_u64 v[152:153], v[134:135], 0, s[8:9]
	v_cndmask_b32_e32 v136, v136, v3, vcc
	s_movk_i32 s8, 0x2000
	v_mul_f32_e32 v84, v84, v136
	v_mul_f32_e32 v85, v85, v136
	v_mul_f32_e32 v82, v82, v136
	v_mul_f32_e32 v83, v83, v136
	v_mul_f32_e32 v80, v80, v136
	v_mul_f32_e32 v81, v81, v136
	v_mul_f32_e32 v78, v78, v136
	v_mul_f32_e32 v79, v79, v136
	v_mul_f32_e32 v76, v76, v136
	v_mul_f32_e32 v77, v77, v136
	v_mul_f32_e32 v74, v74, v136
	v_mul_f32_e32 v75, v75, v136
	v_mul_f32_e32 v72, v72, v136
	v_mul_f32_e32 v73, v73, v136
	v_mul_f32_e32 v70, v70, v136
	v_mul_f32_e32 v71, v71, v136
	v_add_co_u32_e32 v136, vcc, s8, v134
	s_nop 1
	v_addc_co_u32_e32 v137, vcc, 0, v135, vcc
	global_load_dwordx4 v[138:141], v[136:137], off
	global_load_dwordx4 v[142:145], v[152:153], off offset:32
	global_load_dwordx4 v[146:149], v[152:153], off offset:48
	s_nop 0
	global_load_dwordx4 v[152:155], v[152:153], off offset:16
	s_waitcnt vmcnt(1)
	v_add_f32_e32 v144, v144, v148
	v_add_f32_e32 v145, v145, v149
	s_waitcnt vmcnt(0)
	v_add_f32_e32 v140, v140, v154
	v_add_f32_e32 v141, v141, v155
	v_add_f32_e32 v138, v138, v152
	v_add_f32_e32 v139, v139, v153
	v_add_f32_e32 v142, v142, v146
	v_add_f32_e32 v143, v143, v147
	v_mov_b32_e32 v147, v138
	v_mov_b32_e32 v146, v142
	v_mov_b32_e32 v138, v143
	v_mov_b32_e32 v142, v144
	v_mov_b32_e32 v143, v140
	v_mov_b32_e32 v140, v145
	v_add_f32_e32 v138, v146, v138
	v_add_f32_e32 v139, v147, v139
	v_add_f32_e32 v140, v142, v140
	v_add_f32_e32 v141, v143, v141
	s_nop 0
	v_add_f32_e32 v138, v138, v140
	v_add_f32_e32 v139, v139, v141
	s_nop 0
	v_fma_f32 v138, v138, s44, v4
	v_fma_f32 v139, v139, s44, v4
	s_nop 0
	v_div_scale_f32 v3, s[8:9], v139, v139, v138
	v_rcp_f32_e32 v140, v3
	s_nop 0
	v_fma_f32 v141, -v3, v140, 1.0
	v_fmac_f32_e32 v140, v141, v140
	v_div_scale_f32 v141, vcc, v138, v139, v138
	v_mul_f32_e32 v142, v141, v140
	v_fma_f32 v143, -v3, v142, v141
	v_fmac_f32_e32 v142, v143, v140
	v_fma_f32 v3, -v3, v142, v141
	v_div_fmas_f32 v3, v3, v140, v142
	v_div_fixup_f32 v3, v3, v139, v138
	v_cmp_gt_f32_e32 vcc, s76, v3
	v_mul_f32_e32 v138, 0x4f800000, v3
	s_nop 0
	v_cndmask_b32_e32 v3, v3, v138, vcc
	v_sqrt_f32_e32 v138, v3
	s_nop 0
	v_add_u32_e32 v139, -1, v138
	v_fma_f32 v140, -v139, v138, v3
	v_cmp_ge_f32_e64 s[8:9], 0, v140
	v_add_u32_e32 v140, 1, v138
	s_nop 0
	v_cndmask_b32_e64 v139, v138, v139, s[8:9]
	v_fma_f32 v138, -v140, v138, v3
	v_cmp_lt_f32_e64 s[8:9], 0, v138
	s_nop 1
	v_cndmask_b32_e64 v138, v139, v140, s[8:9]
	v_mul_f32_e32 v139, 0x37800000, v138
	v_cndmask_b32_e32 v138, v138, v139, vcc
	v_cmp_class_f32_e32 vcc, v3, v178
	s_mov_b64 s[8:9], 0x2400
	v_lshl_add_u64 v[152:153], v[134:135], 0, s[8:9]
	v_cndmask_b32_e32 v138, v138, v3, vcc
	v_mul_f32_e32 v68, v68, v138
	v_mul_f32_e32 v69, v69, v138
	v_mul_f32_e32 v66, v66, v138
	v_mul_f32_e32 v67, v67, v138
	v_mul_f32_e32 v64, v64, v138
	v_mul_f32_e32 v65, v65, v138
	v_mul_f32_e32 v62, v62, v138
	v_mul_f32_e32 v63, v63, v138
	v_mul_f32_e32 v60, v60, v138
	v_mul_f32_e32 v61, v61, v138
	v_mul_f32_e32 v58, v58, v138
	v_mul_f32_e32 v59, v59, v138
	v_mul_f32_e32 v56, v56, v138
	v_mul_f32_e32 v57, v57, v138
	v_mul_f32_e32 v54, v54, v138
	v_mul_f32_e32 v55, v55, v138
	global_load_dwordx4 v[138:141], v[136:137], off offset:1024
	global_load_dwordx4 v[142:145], v[152:153], off offset:32
	global_load_dwordx4 v[146:149], v[152:153], off offset:48
	s_nop 0
	global_load_dwordx4 v[152:155], v[152:153], off offset:16
	s_waitcnt vmcnt(1)
	v_add_f32_e32 v144, v144, v148
	v_add_f32_e32 v145, v145, v149
	s_waitcnt vmcnt(0)
	v_add_f32_e32 v140, v140, v154
	v_add_f32_e32 v141, v141, v155
	v_add_f32_e32 v138, v138, v152
	v_add_f32_e32 v139, v139, v153
	v_add_f32_e32 v142, v142, v146
	v_add_f32_e32 v143, v143, v147
	v_mov_b32_e32 v147, v138
	v_mov_b32_e32 v146, v142
	v_mov_b32_e32 v138, v143
	v_mov_b32_e32 v142, v144
	v_mov_b32_e32 v143, v140
	v_mov_b32_e32 v140, v145
	v_add_f32_e32 v138, v146, v138
	v_add_f32_e32 v139, v147, v139
	v_add_f32_e32 v140, v142, v140
	v_add_f32_e32 v141, v143, v141
	v_lshl_add_u64 v[152:153], v[134:135], 0, s[46:47]
	v_add_f32_e32 v138, v138, v140
	v_add_f32_e32 v139, v139, v141
	s_nop 0
	v_fma_f32 v138, v138, s44, v4
	v_fma_f32 v139, v139, s44, v4
	s_nop 0
	v_div_scale_f32 v3, s[8:9], v139, v139, v138
	v_rcp_f32_e32 v140, v3
	s_nop 0
	v_fma_f32 v141, -v3, v140, 1.0
	v_fmac_f32_e32 v140, v141, v140
	v_div_scale_f32 v141, vcc, v138, v139, v138
	v_mul_f32_e32 v142, v141, v140
	v_fma_f32 v143, -v3, v142, v141
	v_fmac_f32_e32 v142, v143, v140
	v_fma_f32 v3, -v3, v142, v141
	v_div_fmas_f32 v3, v3, v140, v142
	v_div_fixup_f32 v3, v3, v139, v138
	v_cmp_gt_f32_e32 vcc, s76, v3
	v_mul_f32_e32 v138, 0x4f800000, v3
	s_nop 0
	v_cndmask_b32_e32 v3, v3, v138, vcc
	v_sqrt_f32_e32 v138, v3
	s_nop 0
	v_add_u32_e32 v139, -1, v138
	v_fma_f32 v140, -v139, v138, v3
	v_cmp_ge_f32_e64 s[8:9], 0, v140
	v_add_u32_e32 v140, 1, v138
	s_nop 0
	v_cndmask_b32_e64 v139, v138, v139, s[8:9]
	v_fma_f32 v138, -v140, v138, v3
	v_cmp_lt_f32_e64 s[8:9], 0, v138
	s_nop 1
	v_cndmask_b32_e64 v138, v139, v140, s[8:9]
	v_mul_f32_e32 v139, 0x37800000, v138
	v_cndmask_b32_e32 v138, v138, v139, vcc
	v_cmp_class_f32_e32 vcc, v3, v178
	s_nop 1
	v_cndmask_b32_e32 v138, v138, v3, vcc
	v_mul_f32_e32 v52, v52, v138
	v_mul_f32_e32 v53, v53, v138
	v_mul_f32_e32 v50, v50, v138
	v_mul_f32_e32 v51, v51, v138
	v_mul_f32_e32 v48, v48, v138
	v_mul_f32_e32 v49, v49, v138
	v_mul_f32_e32 v46, v46, v138
	v_mul_f32_e32 v47, v47, v138
	v_mul_f32_e32 v44, v44, v138
	v_mul_f32_e32 v45, v45, v138
	v_mul_f32_e32 v42, v42, v138
	v_mul_f32_e32 v43, v43, v138
	v_mul_f32_e32 v40, v40, v138
	v_mul_f32_e32 v41, v41, v138
	v_mul_f32_e32 v38, v38, v138
	v_mul_f32_e32 v39, v39, v138
	global_load_dwordx4 v[138:141], v[136:137], off offset:2048
	global_load_dwordx4 v[142:145], v[152:153], off offset:32
	global_load_dwordx4 v[146:149], v[152:153], off offset:48
	s_nop 0
	global_load_dwordx4 v[152:155], v[152:153], off offset:16
	s_waitcnt vmcnt(1)
	v_add_f32_e32 v144, v144, v148
	v_add_f32_e32 v145, v145, v149
	s_waitcnt vmcnt(0)
	v_add_f32_e32 v140, v140, v154
	v_add_f32_e32 v141, v141, v155
	v_add_f32_e32 v138, v138, v152
	v_add_f32_e32 v139, v139, v153
	v_add_f32_e32 v142, v142, v146
	v_add_f32_e32 v143, v143, v147
	v_mov_b32_e32 v147, v138
	v_mov_b32_e32 v146, v142
	v_mov_b32_e32 v138, v143
	v_mov_b32_e32 v142, v144
	v_mov_b32_e32 v143, v140
	v_mov_b32_e32 v140, v145
	v_add_f32_e32 v138, v146, v138
	v_add_f32_e32 v139, v147, v139
	v_add_f32_e32 v140, v142, v140
	v_add_f32_e32 v141, v143, v141
	v_lshl_add_u64 v[146:147], v[134:135], 0, s[48:49]
	v_add_f32_e32 v138, v138, v140
	v_add_f32_e32 v139, v139, v141
	s_nop 0
	v_fma_f32 v138, v138, s44, v4
	v_fma_f32 v139, v139, s44, v4
	s_nop 0
	v_div_scale_f32 v3, s[8:9], v139, v139, v138
	v_rcp_f32_e32 v140, v3
	s_nop 0
	v_fma_f32 v141, -v3, v140, 1.0
	v_fmac_f32_e32 v140, v141, v140
	v_div_scale_f32 v141, vcc, v138, v139, v138
	v_mul_f32_e32 v142, v141, v140
	v_fma_f32 v143, -v3, v142, v141
	v_fmac_f32_e32 v142, v143, v140
	v_fma_f32 v3, -v3, v142, v141
	v_div_fmas_f32 v3, v3, v140, v142
	v_div_fixup_f32 v3, v3, v139, v138
	v_cmp_gt_f32_e32 vcc, s76, v3
	v_mul_f32_e32 v138, 0x4f800000, v3
	s_nop 0
	v_cndmask_b32_e32 v3, v3, v138, vcc
	v_sqrt_f32_e32 v138, v3
	s_nop 0
	v_add_u32_e32 v139, -1, v138
	v_fma_f32 v140, -v139, v138, v3
	v_cmp_ge_f32_e64 s[8:9], 0, v140
	v_add_u32_e32 v140, 1, v138
	s_nop 0
	v_cndmask_b32_e64 v139, v138, v139, s[8:9]
	v_fma_f32 v138, -v140, v138, v3
	v_cmp_lt_f32_e64 s[8:9], 0, v138
	s_nop 1
	v_cndmask_b32_e64 v138, v139, v140, s[8:9]
	v_mul_f32_e32 v139, 0x37800000, v138
	v_cndmask_b32_e32 v138, v138, v139, vcc
	v_cmp_class_f32_e32 vcc, v3, v178
	s_nop 1
	v_cndmask_b32_e32 v138, v138, v3, vcc
	v_mul_f32_e32 v36, v36, v138
	v_mul_f32_e32 v37, v37, v138
	v_mul_f32_e32 v34, v34, v138
	v_mul_f32_e32 v35, v35, v138
	v_mul_f32_e32 v32, v32, v138
	v_mul_f32_e32 v33, v33, v138
	v_mul_f32_e32 v30, v30, v138
	v_mul_f32_e32 v31, v31, v138
	v_mul_f32_e32 v28, v28, v138
	v_mul_f32_e32 v29, v29, v138
	v_mul_f32_e32 v26, v26, v138
	v_mul_f32_e32 v27, v27, v138
	v_mul_f32_e32 v24, v24, v138
	v_mul_f32_e32 v25, v25, v138
	v_mul_f32_e32 v22, v22, v138
	v_mul_f32_e32 v23, v23, v138
	global_load_dwordx4 v[142:145], v[136:137], off offset:3072
	s_nop 0
	global_load_dwordx4 v[134:137], v[146:147], off offset:32
	global_load_dwordx4 v[138:141], v[146:147], off offset:48
	s_nop 0
	global_load_dwordx4 v[146:149], v[146:147], off offset:16
	s_waitcnt vmcnt(1)
	v_add_f32_e32 v134, v134, v138
	v_add_f32_e32 v135, v135, v139
	s_waitcnt vmcnt(0)
	v_add_f32_e32 v142, v142, v146
	v_add_f32_e32 v143, v143, v147
	v_add_f32_e32 v144, v144, v148
	v_add_f32_e32 v145, v145, v149
	v_add_f32_e32 v136, v136, v140
	v_add_f32_e32 v137, v137, v141
	v_mov_b32_e32 v138, v134
	v_mov_b32_e32 v139, v142
	v_mov_b32_e32 v142, v135
	v_add_f32_e32 v134, v138, v142
	v_add_f32_e32 v135, v139, v143
	v_mov_b32_e32 v138, v136
	v_mov_b32_e32 v139, v144
	v_mov_b32_e32 v144, v137
	v_add_f32_e32 v136, v138, v144
	v_add_f32_e32 v137, v139, v145
	s_nop 0
	v_add_f32_e32 v134, v134, v136
	v_add_f32_e32 v135, v135, v137
	s_nop 0
	v_fma_f32 v5, v135, s44, v4
	v_fmac_f32_e32 v4, s44, v134
	s_nop 0
	v_div_scale_f32 v3, s[8:9], v5, v5, v4
	v_rcp_f32_e32 v134, v3
	s_nop 0
	v_fma_f32 v135, -v3, v134, 1.0
	v_fmac_f32_e32 v134, v135, v134
	v_div_scale_f32 v135, vcc, v4, v5, v4
	v_mul_f32_e32 v136, v135, v134
	v_fma_f32 v137, -v3, v136, v135
	v_fmac_f32_e32 v136, v137, v134
	v_fma_f32 v3, -v3, v136, v135
	v_div_fmas_f32 v3, v3, v134, v136
	v_div_fixup_f32 v3, v3, v5, v4
	v_cmp_gt_f32_e32 vcc, s76, v3
	v_mul_f32_e32 v4, 0x4f800000, v3
	s_nop 0
	v_cndmask_b32_e32 v3, v3, v4, vcc
	v_sqrt_f32_e32 v4, v3
	s_nop 0
	v_add_u32_e32 v5, -1, v4
	v_fma_f32 v134, -v5, v4, v3
	v_cmp_ge_f32_e64 s[8:9], 0, v134
	v_add_u32_e32 v134, 1, v4
	s_nop 0
	v_cndmask_b32_e64 v5, v4, v5, s[8:9]
	v_fma_f32 v4, -v134, v4, v3
	v_cmp_lt_f32_e64 s[8:9], 0, v4
	s_nop 1
	v_cndmask_b32_e64 v4, v5, v134, s[8:9]
	v_mul_f32_e32 v5, 0x37800000, v4
	v_cndmask_b32_e32 v4, v4, v5, vcc
	v_cmp_class_f32_e32 vcc, v3, v178
	s_nop 1
	v_cndmask_b32_e32 v4, v4, v3, vcc
	v_mul_f32_e32 v20, v20, v4
	v_mul_f32_e32 v21, v21, v4
	v_mul_f32_e32 v18, v18, v4
	v_mul_f32_e32 v19, v19, v4
	v_mul_f32_e32 v16, v16, v4
	v_mul_f32_e32 v17, v17, v4
	v_mul_f32_e32 v14, v14, v4
	v_mul_f32_e32 v15, v15, v4
	v_mul_f32_e32 v12, v12, v4
	v_mul_f32_e32 v13, v13, v4
	v_mul_f32_e32 v10, v10, v4
	v_mul_f32_e32 v11, v11, v4
	v_mul_f32_e32 v8, v8, v4
	v_mul_f32_e32 v9, v9, v4
	v_mul_f32_e32 v6, v6, v4
	v_mul_f32_e32 v7, v7, v4
	s_branch .LBB0_1880

.LBB0_1885:
	v_mov_b32_e32 v3, v0
	s_lshl_b32 s5, s79, 8
	v_and_or_b32 v176, v3, 15, s4
	v_ashrrev_i32_e32 v177, 31, v176
	v_lshlrev_b64 v[134:135], 6, v[176:177]
	v_lshl_add_u64 v[134:135], s[22:23], 0, v[134:135]
	global_load_dwordx4 v[182:185], v[134:135], off offset:32
	global_load_dwordx4 v[186:189], v[134:135], off offset:48
	v_lshrrev_b32_e32 v4, 1, v3
	v_and_or_b32 v4, v4, 24, s5
	v_or_b32_e32 v4, s66, v4
	v_lshlrev_b32_e32 v134, 1, v176
	v_ashrrev_i32_e32 v5, 31, v4
	v_ashrrev_i32_e32 v135, 31, v134
	v_lshlrev_b64 v[136:137], 13, v[176:177]
	v_lshlrev_b64 v[4:5], 2, v[4:5]
	v_lshl_add_u64 v[134:135], v[134:135], 2, s[24:25]
	v_lshl_add_u64 v[136:137], s[20:21], 0, v[136:137]
	v_lshl_add_u64 v[206:207], v[136:137], 0, v[4:5]
	global_load_dwordx2 v[208:209], v[134:135], off
	global_load_dwordx4 v[190:193], v[206:207], off
	global_load_dwordx4 v[194:197], v[206:207], off offset:16
	global_load_dwordx4 v[198:201], v[206:207], off offset:512
	global_load_dwordx4 v[202:205], v[206:207], off offset:528
	v_readlane_b32 s80, v254, 6
	v_readlane_b32 s86, v254, 12
	v_readlane_b32 s87, v254, 13
	v_lshl_add_u64 v[162:163], s[68:69], 0, v[4:5]
	v_readlane_b32 s81, v254, 7
	v_lshl_add_u64 v[142:143], s[86:87], 0, v[4:5]
	global_load_dwordx4 v[138:141], v[162:163], off
	global_load_dwordx4 v[150:153], v[142:143], off
	global_load_dwordx4 v[134:137], v[142:143], off offset:16
	global_load_dwordx4 v[154:157], v[162:163], off offset:16
	global_load_dwordx4 v[146:149], v[162:163], off offset:512
	global_load_dwordx4 v[158:161], v[142:143], off offset:512
	s_nop 0
	global_load_dwordx4 v[142:145], v[142:143], off offset:528
	s_nop 0
	global_load_dwordx4 v[162:165], v[162:163], off offset:528
	v_readlane_b32 s82, v254, 8
	v_readlane_b32 s83, v254, 9
	v_readlane_b32 s84, v254, 10
	v_readlane_b32 s85, v254, 11
	s_waitcnt vmcnt(0)
	v_add_f32_e32 v184, v184, v188
	v_add_f32_e32 v185, v185, v189
	v_add_f32_e32 v182, v182, v186
	v_add_f32_e32 v183, v183, v187
	v_sub_f32_e32 v189, v195, v208
	v_pk_mov_b32 v[186:187], v[182:183], v[184:185] op_sel:[1,0]
	v_mov_b32_e32 v183, v185
	v_add_f32_e32 v182, v186, v182
	v_add_f32_e32 v183, v187, v183
	v_sub_f32_e32 v185, v191, v208
	v_add_f32_e32 v3, v182, v183
	v_fmamk_f32 v3, v3, 0x3a800000, v180
	v_mul_f32_e32 v177, 0x4f800000, v3
	v_cmp_gt_f32_e32 vcc, s76, v3
	v_sub_f32_e32 v184, v190, v208
	v_sub_f32_e32 v187, v193, v208
	v_cndmask_b32_e32 v3, v3, v177, vcc
	v_sqrt_f32_e32 v177, v3
	v_sub_f32_e32 v186, v192, v208
	v_sub_f32_e32 v188, v194, v208
	v_sub_f32_e32 v191, v197, v208
	v_sub_f32_e32 v190, v196, v208
	v_sub_f32_e32 v195, v199, v208
	v_sub_f32_e32 v194, v198, v208
	v_sub_f32_e32 v199, v203, v208
	v_sub_f32_e32 v198, v202, v208
	v_add_u32_e32 v181, -1, v177
	v_mul_f32_e32 v182, v209, v186
	v_mul_f32_e32 v183, v209, v187
	v_mul_f32_e32 v186, v209, v190
	v_mul_f32_e32 v187, v209, v191
	v_mul_f32_e32 v190, v209, v194
	v_mul_f32_e32 v191, v209, v195
	v_mul_f32_e32 v194, v209, v198
	v_mul_f32_e32 v195, v209, v199
	v_add_u32_e32 v198, 1, v177
	v_fma_f32 v199, -v181, v177, v3
	v_sub_f32_e32 v192, v200, v208
	v_fma_f32 v200, -v198, v177, v3
	v_cmp_ge_f32_e64 s[8:9], 0, v199
	v_sub_f32_e32 v193, v201, v208
	v_mul_f32_e32 v192, v209, v192
	v_mul_f32_e32 v193, v209, v193
	v_cndmask_b32_e64 v177, v177, v181, s[8:9]
	v_cmp_lt_f32_e64 s[8:9], 0, v200
	v_sub_f32_e32 v197, v205, v208
	v_sub_f32_e32 v196, v204, v208
	v_cndmask_b32_e64 v177, v177, v198, s[8:9]
	v_mul_f32_e32 v181, 0x37800000, v177
	v_cndmask_b32_e32 v177, v177, v181, vcc
	v_cmp_class_f32_e32 vcc, v3, v178
	v_mul_f32_e32 v184, v209, v184
	v_mul_f32_e32 v185, v209, v185
	v_fma_f32 v192, v160, v192, v148
	v_fma_f32 v193, v161, v193, v149
	v_cndmask_b32_e32 v3, v177, v3, vcc
	v_div_scale_f32 v177, s[4:5], v3, v3, 1.0
	v_rcp_f32_e32 v181, v177
	v_div_scale_f32 v198, vcc, 1.0, v3, 1.0
	v_fma_f32 v190, v158, v190, v146
	v_fma_f32 v191, v159, v191, v147
	v_fma_f32 v199, -v177, v181, 1.0
	v_fmac_f32_e32 v181, v199, v181
	v_mul_f32_e32 v199, v198, v181
	v_fma_f32 v200, -v177, v199, v198
	v_fmac_f32_e32 v199, v200, v181
	v_fma_f32 v177, -v177, v199, v198
	v_div_fmas_f32 v177, v177, v181, v199
	v_div_fixup_f32 v198, v177, v3, 1.0
	v_mul_f32_e32 v188, v209, v188
	v_mul_f32_e32 v189, v209, v189
	v_mul_f32_e32 v196, v209, v196
	v_mul_f32_e32 v197, v209, v197
	v_fma_f32 v184, v150, v184, v138
	v_fma_f32 v185, v151, v185, v139
	v_mul_f32_e32 v190, s52, v190
	v_mul_f32_e32 v191, s52, v191
	v_mul_f32_e32 v192, s52, v192
	v_mul_f32_e32 v193, s52, v193
	v_mul_f32_e32 v130, v130, v198
	v_mul_f32_e32 v131, v131, v198
	v_fma_f32 v182, v152, v182, v140
	v_fma_f32 v183, v153, v183, v141
	v_fma_f32 v188, v134, v188, v154
	v_fma_f32 v189, v135, v189, v155
	v_fma_f32 v186, v136, v186, v156
	v_fma_f32 v187, v137, v187, v157
	v_fma_f32 v196, v144, v196, v164
	v_fma_f32 v197, v145, v197, v165
	v_fma_f32 v194, v142, v194, v162
	v_fma_f32 v195, v143, v195, v163
	v_mul_f32_e32 v132, v132, v198
	v_mul_f32_e32 v133, v133, v198
	v_mul_f32_e32 v200, v126, v198
	v_mul_f32_e32 v201, v127, v198
	v_mul_f32_e32 v202, v128, v198
	v_mul_f32_e32 v203, v129, v198
	v_fma_f32 v124, v124, v198, v192
	v_fma_f32 v125, v125, v198, v193
	v_fma_f32 v122, v122, v198, v190
	v_fma_f32 v123, v123, v198, v191
	v_fma_f32 v126, v184, s52, v130
	v_fma_f32 v127, v185, s52, v131
	v_mul_f32_e32 v194, s52, v194
	v_mul_f32_e32 v195, s52, v195
	v_fma_f32 v128, v182, s52, v132
	v_fma_f32 v129, v183, s52, v133
	v_fma_f32 v132, v186, s52, v202
	v_fma_f32 v133, v187, s52, v203
	v_fma_f32 v130, v188, s52, v200
	v_fma_f32 v131, v189, s52, v201
	global_store_dwordx4 v[206:207], v[122:125], off offset:512
	global_store_dwordx4 v[206:207], v[126:129], off
	global_store_dwordx4 v[206:207], v[130:133], off offset:16
	v_mul_f32_e32 v122, s52, v196
	v_mul_f32_e32 v123, s52, v197
	v_or_b32_e32 v126, 16, v176
	v_fma_f32 v120, v120, v198, v122
	v_fma_f32 v121, v121, v198, v123
	v_fma_f32 v118, v118, v198, v194
	v_fma_f32 v119, v119, v198, v195
	v_ashrrev_i32_e32 v127, 31, v126
	global_store_dwordx4 v[206:207], v[118:121], off offset:528
	v_lshlrev_b32_e32 v128, 1, v126
	v_ashrrev_i32_e32 v129, 31, v128
	v_lshlrev_b64 v[118:119], 6, v[126:127]
	v_lshl_add_u64 v[122:123], s[22:23], 0, v[118:119]
	v_lshlrev_b64 v[126:127], 13, v[126:127]
	global_load_dwordx4 v[118:121], v[122:123], off offset:32
	s_nop 0
	global_load_dwordx4 v[122:125], v[122:123], off offset:48
	v_lshl_add_u64 v[128:129], v[128:129], 2, s[24:25]
	v_lshl_add_u64 v[126:127], s[20:21], 0, v[126:127]
	v_lshl_add_u64 v[190:191], v[126:127], 0, v[4:5]
	global_load_dwordx2 v[192:193], v[128:129], off
	s_nop 0
	global_load_dwordx4 v[126:129], v[190:191], off
	global_load_dwordx4 v[130:133], v[190:191], off offset:16
	global_load_dwordx4 v[182:185], v[190:191], off offset:512
	global_load_dwordx4 v[186:189], v[190:191], off offset:528
	v_or_b32_e32 v194, 32, v176
	v_ashrrev_i32_e32 v195, 31, v194
	v_lshlrev_b64 v[196:197], 6, v[194:195]
	v_lshl_add_u64 v[196:197], s[22:23], 0, v[196:197]
	s_waitcnt vmcnt(5)
	v_add_f32_e32 v120, v120, v124
	v_add_f32_e32 v121, v121, v125
	v_add_f32_e32 v118, v118, v122
	v_add_f32_e32 v119, v119, v123
	s_waitcnt vmcnt(3)
	v_sub_f32_e32 v123, v127, v192
	v_sub_f32_e32 v122, v126, v192
	s_waitcnt vmcnt(2)
	v_sub_f32_e32 v127, v131, v192
	v_sub_f32_e32 v126, v130, v192
	s_waitcnt vmcnt(1)
	v_sub_f32_e32 v131, v185, v192
	v_sub_f32_e32 v130, v184, v192
	s_waitcnt vmcnt(0)
	v_sub_f32_e32 v185, v187, v192
	v_sub_f32_e32 v184, v186, v192
	v_pk_mov_b32 v[186:187], v[118:119], v[120:121] op_sel:[1,0]
	v_mov_b32_e32 v119, v121
	v_add_f32_e32 v118, v186, v118
	v_add_f32_e32 v119, v187, v119
	v_sub_f32_e32 v125, v129, v192
	v_add_f32_e32 v3, v118, v119
	v_fmamk_f32 v3, v3, 0x3a800000, v180
	v_mul_f32_e32 v118, 0x4f800000, v3
	v_cmp_gt_f32_e32 vcc, s76, v3
	v_sub_f32_e32 v124, v128, v192
	v_sub_f32_e32 v129, v133, v192
	v_cndmask_b32_e32 v3, v3, v118, vcc
	v_sqrt_f32_e32 v177, v3
	v_sub_f32_e32 v128, v132, v192
	v_sub_f32_e32 v133, v183, v192
	v_sub_f32_e32 v132, v182, v192
	v_mul_f32_e32 v120, v193, v124
	v_mul_f32_e32 v121, v193, v125
	v_mul_f32_e32 v124, v193, v128
	v_mul_f32_e32 v125, v193, v129
	v_mul_f32_e32 v128, v193, v132
	v_mul_f32_e32 v129, v193, v133
	v_mul_f32_e32 v130, v193, v130
	v_mul_f32_e32 v131, v193, v131
	v_mul_f32_e32 v132, v193, v184
	v_mul_f32_e32 v133, v193, v185
	v_fma_f32 v130, v160, v130, v148
	v_fma_f32 v131, v161, v131, v149
	v_fma_f32 v128, v158, v128, v146
	v_fma_f32 v129, v159, v129, v147
	v_fma_f32 v132, v142, v132, v162
	v_fma_f32 v133, v143, v133, v163
	v_mul_f32_e32 v118, s52, v128
	v_mul_f32_e32 v119, s52, v129
	v_mul_f32_e32 v128, s52, v130
	v_mul_f32_e32 v129, s52, v131
	v_mul_f32_e32 v130, s52, v132
	v_mul_f32_e32 v131, s52, v133
	v_add_u32_e32 v132, -1, v177
	v_add_u32_e32 v133, 1, v177
	v_fma_f32 v181, -v132, v177, v3
	v_fma_f32 v184, -v133, v177, v3
	v_cmp_ge_f32_e64 s[8:9], 0, v181
	v_sub_f32_e32 v183, v189, v192
	v_sub_f32_e32 v182, v188, v192
	v_cndmask_b32_e64 v132, v177, v132, s[8:9]
	v_cmp_lt_f32_e64 s[8:9], 0, v184
	v_mul_f32_e32 v182, v193, v182
	v_mul_f32_e32 v183, v193, v183
	v_mul_f32_e32 v122, v193, v122
	v_mul_f32_e32 v123, v193, v123
	v_cndmask_b32_e64 v132, v132, v133, s[8:9]
	v_mul_f32_e32 v133, 0x37800000, v132
	v_cndmask_b32_e32 v132, v132, v133, vcc
	v_cmp_class_f32_e32 vcc, v3, v178
	v_fma_f32 v182, v144, v182, v164
	v_fma_f32 v183, v145, v183, v165
	v_mul_f32_e32 v126, v193, v126
	v_mul_f32_e32 v127, v193, v127
	v_cndmask_b32_e32 v3, v132, v3, vcc
	v_div_scale_f32 v177, s[4:5], v3, v3, 1.0
	v_rcp_f32_e32 v181, v177
	v_mul_f32_e32 v132, s52, v182
	v_mul_f32_e32 v133, s52, v183
	v_div_scale_f32 v182, vcc, 1.0, v3, 1.0
	v_fma_f32 v183, -v177, v181, 1.0
	v_fmac_f32_e32 v181, v183, v181
	v_mul_f32_e32 v183, v182, v181
	v_fma_f32 v184, -v177, v183, v182
	v_fmac_f32_e32 v183, v184, v181
	v_fma_f32 v177, -v177, v183, v182
	v_div_fmas_f32 v177, v177, v181, v183
	v_div_fixup_f32 v182, v177, v3, 1.0
	v_fma_f32 v122, v150, v122, v138
	v_fma_f32 v123, v151, v123, v139
	v_fma_f32 v120, v152, v120, v140
	v_fma_f32 v121, v153, v121, v141
	v_fma_f32 v126, v134, v126, v154
	v_fma_f32 v127, v135, v127, v155
	v_fma_f32 v124, v136, v124, v156
	v_fma_f32 v125, v137, v125, v157
	v_mul_f32_e32 v114, v114, v182
	v_mul_f32_e32 v115, v115, v182
	v_mul_f32_e32 v116, v116, v182
	v_mul_f32_e32 v117, v117, v182
	v_mul_f32_e32 v184, v110, v182
	v_mul_f32_e32 v185, v111, v182
	v_mul_f32_e32 v186, v112, v182
	v_mul_f32_e32 v187, v113, v182
	v_fma_f32 v108, v108, v182, v128
	v_fma_f32 v109, v109, v182, v129
	v_fma_f32 v106, v106, v182, v118
	v_fma_f32 v107, v107, v182, v119
	v_fma_f32 v102, v102, v182, v130
	v_fma_f32 v103, v103, v182, v131
	v_fma_f32 v104, v104, v182, v132
	v_fma_f32 v105, v105, v182, v133
	v_fma_f32 v112, v120, s52, v116
	v_fma_f32 v113, v121, s52, v117
	v_fma_f32 v110, v122, s52, v114
	v_fma_f32 v111, v123, s52, v115
	v_fma_f32 v116, v124, s52, v186
	v_fma_f32 v117, v125, s52, v187
	v_fma_f32 v114, v126, s52, v184
	v_fma_f32 v115, v127, s52, v185
	global_store_dwordx4 v[190:191], v[106:109], off offset:512
	global_store_dwordx4 v[190:191], v[102:105], off offset:528
	global_store_dwordx4 v[190:191], v[110:113], off
	global_store_dwordx4 v[190:191], v[114:117], off offset:16
	v_lshlrev_b32_e32 v102, 1, v194
	v_ashrrev_i32_e32 v103, 31, v102
	v_lshlrev_b64 v[112:113], 13, v[194:195]
	global_load_dwordx4 v[104:107], v[196:197], off offset:32
	global_load_dwordx4 v[108:111], v[196:197], off offset:48
	v_lshl_add_u64 v[102:103], v[102:103], 2, s[24:25]
	v_lshl_add_u64 v[112:113], s[20:21], 0, v[112:113]
	v_lshl_add_u64 v[128:129], v[112:113], 0, v[4:5]
	global_load_dwordx2 v[130:131], v[102:103], off
	global_load_dwordx4 v[112:115], v[128:129], off
	global_load_dwordx4 v[116:119], v[128:129], off offset:16
	global_load_dwordx4 v[120:123], v[128:129], off offset:512
	global_load_dwordx4 v[124:127], v[128:129], off offset:528
	v_or_b32_e32 v102, 48, v176
	v_ashrrev_i32_e32 v103, 31, v102
	v_lshlrev_b32_e32 v132, 1, v102
	v_lshlrev_b64 v[182:183], 6, v[102:103]
	v_lshlrev_b64 v[102:103], 13, v[102:103]
	v_ashrrev_i32_e32 v133, 31, v132
	v_lshl_add_u64 v[182:183], s[22:23], 0, v[182:183]
	v_lshl_add_u64 v[102:103], s[20:21], 0, v[102:103]
	v_lshl_add_u64 v[132:133], v[132:133], 2, s[24:25]
	v_lshl_add_u64 v[102:103], v[102:103], 0, v[4:5]
	s_waitcnt vmcnt(5)
	v_add_f32_e32 v106, v106, v110
	v_add_f32_e32 v107, v107, v111
	v_add_f32_e32 v104, v104, v108
	v_add_f32_e32 v105, v105, v109
	s_waitcnt vmcnt(3)
	v_sub_f32_e32 v109, v113, v130
	v_sub_f32_e32 v108, v112, v130
	s_waitcnt vmcnt(2)
	v_sub_f32_e32 v113, v117, v130
	v_sub_f32_e32 v112, v116, v130
	s_waitcnt vmcnt(1)
	v_sub_f32_e32 v117, v123, v130
	v_sub_f32_e32 v116, v122, v130
	s_waitcnt vmcnt(0)
	v_sub_f32_e32 v123, v125, v130
	v_sub_f32_e32 v122, v124, v130
	v_pk_mov_b32 v[124:125], v[104:105], v[106:107] op_sel:[1,0]
	v_mov_b32_e32 v105, v107
	v_add_f32_e32 v104, v124, v104
	v_add_f32_e32 v105, v125, v105
	v_sub_f32_e32 v111, v115, v130
	v_add_f32_e32 v3, v104, v105
	v_fmamk_f32 v3, v3, 0x3a800000, v180
	v_mul_f32_e32 v104, 0x4f800000, v3
	v_cmp_gt_f32_e32 vcc, s76, v3
	v_sub_f32_e32 v110, v114, v130
	v_sub_f32_e32 v115, v119, v130
	v_sub_f32_e32 v114, v118, v130
	v_sub_f32_e32 v119, v121, v130
	v_sub_f32_e32 v118, v120, v130
	v_cndmask_b32_e32 v3, v3, v104, vcc
	v_mul_f32_e32 v106, v131, v110
	v_mul_f32_e32 v107, v131, v111
	v_mul_f32_e32 v110, v131, v114
	v_mul_f32_e32 v111, v131, v115
	v_mul_f32_e32 v114, v131, v118
	v_mul_f32_e32 v115, v131, v119
	v_mul_f32_e32 v118, v131, v122
	v_mul_f32_e32 v119, v131, v123
	v_sqrt_f32_e32 v122, v3
	v_mul_f32_e32 v116, v131, v116
	v_mul_f32_e32 v117, v131, v117
	v_fma_f32 v114, v158, v114, v146
	v_fma_f32 v115, v159, v115, v147
	v_fma_f32 v116, v160, v116, v148
	v_fma_f32 v117, v161, v117, v149
	v_fma_f32 v118, v142, v118, v162
	v_fma_f32 v119, v143, v119, v163
	v_mul_f32_e32 v104, s52, v114
	v_mul_f32_e32 v105, s52, v115
	v_mul_f32_e32 v114, s52, v116
	v_mul_f32_e32 v115, s52, v117
	v_mul_f32_e32 v116, s52, v118
	v_mul_f32_e32 v117, s52, v119
	v_add_u32_e32 v118, -1, v122
	v_add_u32_e32 v119, 1, v122
	v_fma_f32 v123, -v118, v122, v3
	v_fma_f32 v124, -v119, v122, v3
	v_cmp_ge_f32_e64 s[8:9], 0, v123
	v_sub_f32_e32 v121, v127, v130
	v_sub_f32_e32 v120, v126, v130
	v_cndmask_b32_e64 v118, v122, v118, s[8:9]
	v_cmp_lt_f32_e64 s[8:9], 0, v124
	v_mul_f32_e32 v120, v131, v120
	v_mul_f32_e32 v121, v131, v121
	v_mul_f32_e32 v108, v131, v108
	v_mul_f32_e32 v109, v131, v109
	v_cndmask_b32_e64 v118, v118, v119, s[8:9]
	v_mul_f32_e32 v119, 0x37800000, v118
	v_cndmask_b32_e32 v118, v118, v119, vcc
	v_cmp_class_f32_e32 vcc, v3, v178
	v_fma_f32 v120, v144, v120, v164
	v_fma_f32 v121, v145, v121, v165
	v_mul_f32_e32 v112, v131, v112
	v_mul_f32_e32 v113, v131, v113
	v_cndmask_b32_e32 v3, v118, v3, vcc
	v_div_scale_f32 v122, s[4:5], v3, v3, 1.0
	v_rcp_f32_e32 v123, v122
	v_mul_f32_e32 v118, s52, v120
	v_mul_f32_e32 v119, s52, v121
	v_div_scale_f32 v120, vcc, 1.0, v3, 1.0
	v_fma_f32 v121, -v122, v123, 1.0
	v_fmac_f32_e32 v123, v121, v123
	v_mul_f32_e32 v121, v120, v123
	v_fma_f32 v124, -v122, v121, v120
	v_fmac_f32_e32 v121, v124, v123
	v_fma_f32 v120, -v122, v121, v120
	v_div_fmas_f32 v120, v120, v123, v121
	v_div_fixup_f32 v120, v120, v3, 1.0
	v_fma_f32 v108, v150, v108, v138
	v_fma_f32 v109, v151, v109, v139
	v_fma_f32 v106, v152, v106, v140
	v_fma_f32 v107, v153, v107, v141
	v_fma_f32 v112, v134, v112, v154
	v_fma_f32 v113, v135, v113, v155
	v_fma_f32 v110, v136, v110, v156
	v_fma_f32 v111, v137, v111, v157
	v_mul_f32_e32 v98, v98, v120
	v_mul_f32_e32 v99, v99, v120
	v_mul_f32_e32 v100, v100, v120
	v_mul_f32_e32 v101, v101, v120
	v_mul_f32_e32 v122, v94, v120
	v_mul_f32_e32 v123, v95, v120
	v_mul_f32_e32 v124, v96, v120
	v_mul_f32_e32 v125, v97, v120
	v_fma_f32 v92, v92, v120, v114
	v_fma_f32 v93, v93, v120, v115
	v_fma_f32 v90, v90, v120, v104
	v_fma_f32 v91, v91, v120, v105
	v_fma_f32 v88, v88, v120, v118
	v_fma_f32 v89, v89, v120, v119
	v_fma_f32 v86, v86, v120, v116
	v_fma_f32 v87, v87, v120, v117
	v_fma_f32 v96, v106, s52, v100
	v_fma_f32 v97, v107, s52, v101
	v_fma_f32 v94, v108, s52, v98
	v_fma_f32 v95, v109, s52, v99
	v_fma_f32 v100, v110, s52, v124
	v_fma_f32 v101, v111, s52, v125
	v_fma_f32 v98, v112, s52, v122
	v_fma_f32 v99, v113, s52, v123
	global_store_dwordx4 v[128:129], v[90:93], off offset:512
	global_store_dwordx4 v[128:129], v[86:89], off offset:528
	global_store_dwordx4 v[128:129], v[94:97], off
	global_store_dwordx4 v[128:129], v[98:101], off offset:16
	global_load_dwordx4 v[88:91], v[182:183], off offset:32
	global_load_dwordx4 v[92:95], v[182:183], off offset:48
	global_load_dwordx2 v[100:101], v[132:133], off
	global_load_dwordx4 v[96:99], v[102:103], off
	global_load_dwordx4 v[104:107], v[102:103], off offset:16
	global_load_dwordx4 v[108:111], v[102:103], off offset:512
	global_load_dwordx4 v[112:115], v[102:103], off offset:528
	v_add_u32_e32 v86, 0x80, v176
	v_ashrrev_i32_e32 v87, 31, v86
	v_lshlrev_b32_e32 v116, 1, v86
	v_lshlrev_b64 v[118:119], 6, v[86:87]
	v_lshlrev_b64 v[86:87], 13, v[86:87]
	v_ashrrev_i32_e32 v117, 31, v116
	v_lshl_add_u64 v[118:119], s[22:23], 0, v[118:119]
	v_lshl_add_u64 v[86:87], s[20:21], 0, v[86:87]
	v_lshl_add_u64 v[116:117], v[116:117], 2, s[24:25]
	v_lshl_add_u64 v[86:87], v[86:87], 0, v[4:5]
	s_waitcnt vmcnt(5)
	v_add_f32_e32 v90, v90, v94
	v_add_f32_e32 v91, v91, v95
	v_add_f32_e32 v88, v88, v92
	v_add_f32_e32 v89, v89, v93
	s_waitcnt vmcnt(3)
	v_sub_f32_e32 v93, v97, v100
	v_sub_f32_e32 v92, v96, v100
	s_waitcnt vmcnt(2)
	v_sub_f32_e32 v97, v105, v100
	v_sub_f32_e32 v96, v104, v100
	s_waitcnt vmcnt(1)
	v_sub_f32_e32 v105, v111, v100
	v_sub_f32_e32 v104, v110, v100
	s_waitcnt vmcnt(0)
	v_sub_f32_e32 v111, v113, v100
	v_sub_f32_e32 v110, v112, v100
	v_pk_mov_b32 v[112:113], v[88:89], v[90:91] op_sel:[1,0]
	v_mov_b32_e32 v89, v91
	v_add_f32_e32 v88, v112, v88
	v_add_f32_e32 v89, v113, v89
	v_sub_f32_e32 v95, v99, v100
	v_add_f32_e32 v3, v88, v89
	v_fmamk_f32 v3, v3, 0x3a800000, v180
	v_mul_f32_e32 v88, 0x4f800000, v3
	v_cmp_gt_f32_e32 vcc, s76, v3
	v_sub_f32_e32 v94, v98, v100
	v_sub_f32_e32 v99, v107, v100
	v_sub_f32_e32 v98, v106, v100
	v_sub_f32_e32 v107, v109, v100
	v_sub_f32_e32 v106, v108, v100
	v_sub_f32_e32 v109, v115, v100
	v_sub_f32_e32 v108, v114, v100
	v_cndmask_b32_e32 v3, v3, v88, vcc
	v_mul_f32_e32 v90, v101, v94
	v_mul_f32_e32 v91, v101, v95
	v_mul_f32_e32 v92, v101, v92
	v_mul_f32_e32 v93, v101, v93
	v_mul_f32_e32 v94, v101, v98
	v_mul_f32_e32 v95, v101, v99
	v_mul_f32_e32 v96, v101, v96
	v_mul_f32_e32 v97, v101, v97
	v_mul_f32_e32 v98, v101, v106
	v_mul_f32_e32 v99, v101, v107
	v_mul_f32_e32 v104, v101, v104
	v_mul_f32_e32 v105, v101, v105
	v_mul_f32_e32 v106, v101, v110
	v_mul_f32_e32 v107, v101, v111
	v_mul_f32_e32 v100, v101, v108
	v_mul_f32_e32 v101, v101, v109
	v_sqrt_f32_e32 v108, v3
	v_fma_f32 v104, v160, v104, v148
	v_fma_f32 v105, v161, v105, v149
	v_fma_f32 v98, v158, v98, v146
	v_fma_f32 v99, v159, v99, v147
	v_fma_f32 v106, v142, v106, v162
	v_fma_f32 v107, v143, v107, v163
	v_mul_f32_e32 v88, s52, v98
	v_mul_f32_e32 v89, s52, v99
	v_mul_f32_e32 v98, s52, v104
	v_mul_f32_e32 v99, s52, v105
	v_mul_f32_e32 v104, s52, v106
	v_mul_f32_e32 v105, s52, v107
	v_add_u32_e32 v106, -1, v108
	v_add_u32_e32 v107, 1, v108
	v_fma_f32 v109, -v106, v108, v3
	v_fma_f32 v110, -v107, v108, v3
	v_cmp_ge_f32_e64 s[8:9], 0, v109
	v_fma_f32 v100, v144, v100, v164
	v_fma_f32 v101, v145, v101, v165
	v_fma_f32 v92, v150, v92, v138
	v_fma_f32 v93, v151, v93, v139
	v_cndmask_b32_e64 v106, v108, v106, s[8:9]
	v_cmp_lt_f32_e64 s[8:9], 0, v110
	v_fma_f32 v90, v152, v90, v140
	v_fma_f32 v91, v153, v91, v141
	v_fma_f32 v96, v134, v96, v154
	v_fma_f32 v97, v135, v97, v155
	v_cndmask_b32_e64 v106, v106, v107, s[8:9]
	v_mul_f32_e32 v107, 0x37800000, v106
	v_cndmask_b32_e32 v106, v106, v107, vcc
	v_cmp_class_f32_e32 vcc, v3, v178
	v_fma_f32 v94, v136, v94, v156
	v_fma_f32 v95, v137, v95, v157
	v_mul_f32_e32 v100, s52, v100
	v_mul_f32_e32 v101, s52, v101
	v_cndmask_b32_e32 v3, v106, v3, vcc
	v_div_scale_f32 v106, s[4:5], v3, v3, 1.0
	v_rcp_f32_e32 v107, v106
	v_div_scale_f32 v108, vcc, 1.0, v3, 1.0
	v_fma_f32 v109, -v106, v107, 1.0
	v_fmac_f32_e32 v107, v109, v107
	v_mul_f32_e32 v109, v108, v107
	v_fma_f32 v110, -v106, v109, v108
	v_fmac_f32_e32 v109, v110, v107
	v_fma_f32 v106, -v106, v109, v108
	v_div_fmas_f32 v106, v106, v107, v109
	v_div_fixup_f32 v106, v106, v3, 1.0
	v_mul_f32_e32 v82, v82, v106
	v_mul_f32_e32 v83, v83, v106
	v_mul_f32_e32 v84, v84, v106
	v_mul_f32_e32 v85, v85, v106
	v_mul_f32_e32 v108, v78, v106
	v_mul_f32_e32 v109, v79, v106
	v_mul_f32_e32 v110, v80, v106
	v_mul_f32_e32 v111, v81, v106
	v_fma_f32 v76, v76, v106, v98
	v_fma_f32 v77, v77, v106, v99
	v_fma_f32 v74, v74, v106, v88
	v_fma_f32 v75, v75, v106, v89
	v_fma_f32 v72, v72, v106, v100
	v_fma_f32 v73, v73, v106, v101
	v_fma_f32 v70, v70, v106, v104
	v_fma_f32 v71, v71, v106, v105
	v_fma_f32 v80, v90, s52, v84
	v_fma_f32 v81, v91, s52, v85
	v_fma_f32 v78, v92, s52, v82
	v_fma_f32 v79, v93, s52, v83
	v_fma_f32 v84, v94, s52, v110
	v_fma_f32 v85, v95, s52, v111
	v_fma_f32 v82, v96, s52, v108
	v_fma_f32 v83, v97, s52, v109
	global_store_dwordx4 v[102:103], v[74:77], off offset:512
	global_store_dwordx4 v[102:103], v[70:73], off offset:528
	global_store_dwordx4 v[102:103], v[78:81], off
	global_store_dwordx4 v[102:103], v[82:85], off offset:16
	global_load_dwordx4 v[72:75], v[118:119], off offset:32
	global_load_dwordx4 v[76:79], v[118:119], off offset:48
	global_load_dwordx2 v[84:85], v[116:117], off
	global_load_dwordx4 v[80:83], v[86:87], off
	global_load_dwordx4 v[88:91], v[86:87], off offset:16
	global_load_dwordx4 v[92:95], v[86:87], off offset:512
	global_load_dwordx4 v[96:99], v[86:87], off offset:528
	v_add_u32_e32 v70, 0x90, v176
	v_ashrrev_i32_e32 v71, 31, v70
	v_lshlrev_b32_e32 v100, 1, v70
	v_lshlrev_b64 v[102:103], 6, v[70:71]
	v_lshlrev_b64 v[70:71], 13, v[70:71]
	v_ashrrev_i32_e32 v101, 31, v100
	v_lshl_add_u64 v[102:103], s[22:23], 0, v[102:103]
	v_lshl_add_u64 v[70:71], s[20:21], 0, v[70:71]
	v_lshl_add_u64 v[100:101], v[100:101], 2, s[24:25]
	v_lshl_add_u64 v[70:71], v[70:71], 0, v[4:5]
	s_waitcnt vmcnt(5)
	v_add_f32_e32 v74, v74, v78
	v_add_f32_e32 v75, v75, v79
	v_add_f32_e32 v72, v72, v76
	v_add_f32_e32 v73, v73, v77
	s_waitcnt vmcnt(3)
	v_sub_f32_e32 v77, v81, v84
	v_sub_f32_e32 v76, v80, v84
	s_waitcnt vmcnt(2)
	v_sub_f32_e32 v81, v89, v84
	v_sub_f32_e32 v80, v88, v84
	s_waitcnt vmcnt(1)
	v_sub_f32_e32 v89, v95, v84
	v_sub_f32_e32 v88, v94, v84
	s_waitcnt vmcnt(0)
	v_sub_f32_e32 v95, v97, v84
	v_sub_f32_e32 v94, v96, v84
	v_pk_mov_b32 v[96:97], v[72:73], v[74:75] op_sel:[1,0]
	v_mov_b32_e32 v73, v75
	v_add_f32_e32 v72, v96, v72
	v_add_f32_e32 v73, v97, v73
	v_sub_f32_e32 v79, v83, v84
	v_add_f32_e32 v3, v72, v73
	v_fmamk_f32 v3, v3, 0x3a800000, v180
	v_mul_f32_e32 v72, 0x4f800000, v3
	v_cmp_gt_f32_e32 vcc, s76, v3
	v_sub_f32_e32 v78, v82, v84
	v_sub_f32_e32 v83, v91, v84
	v_sub_f32_e32 v82, v90, v84
	v_sub_f32_e32 v91, v93, v84
	v_sub_f32_e32 v90, v92, v84
	v_sub_f32_e32 v93, v99, v84
	v_sub_f32_e32 v92, v98, v84
	v_cndmask_b32_e32 v3, v3, v72, vcc
	v_mul_f32_e32 v74, v85, v78
	v_mul_f32_e32 v75, v85, v79
	v_mul_f32_e32 v76, v85, v76
	v_mul_f32_e32 v77, v85, v77
	v_mul_f32_e32 v78, v85, v82
	v_mul_f32_e32 v79, v85, v83
	v_mul_f32_e32 v80, v85, v80
	v_mul_f32_e32 v81, v85, v81
	v_mul_f32_e32 v82, v85, v90
	v_mul_f32_e32 v83, v85, v91
	v_mul_f32_e32 v88, v85, v88
	v_mul_f32_e32 v89, v85, v89
	v_mul_f32_e32 v90, v85, v94
	v_mul_f32_e32 v91, v85, v95
	v_mul_f32_e32 v84, v85, v92
	v_mul_f32_e32 v85, v85, v93
	v_sqrt_f32_e32 v92, v3
	v_fma_f32 v88, v160, v88, v148
	v_fma_f32 v89, v161, v89, v149
	v_fma_f32 v82, v158, v82, v146
	v_fma_f32 v83, v159, v83, v147
	v_fma_f32 v90, v142, v90, v162
	v_fma_f32 v91, v143, v91, v163
	v_mul_f32_e32 v72, s52, v82
	v_mul_f32_e32 v73, s52, v83
	v_mul_f32_e32 v82, s52, v88
	v_mul_f32_e32 v83, s52, v89
	v_mul_f32_e32 v88, s52, v90
	v_mul_f32_e32 v89, s52, v91
	v_add_u32_e32 v90, -1, v92
	v_add_u32_e32 v91, 1, v92
	v_fma_f32 v93, -v90, v92, v3
	v_fma_f32 v94, -v91, v92, v3
	v_cmp_ge_f32_e64 s[8:9], 0, v93
	v_fma_f32 v84, v144, v84, v164
	v_fma_f32 v85, v145, v85, v165
	v_fma_f32 v76, v150, v76, v138
	v_fma_f32 v77, v151, v77, v139
	v_cndmask_b32_e64 v90, v92, v90, s[8:9]
	v_cmp_lt_f32_e64 s[8:9], 0, v94
	v_fma_f32 v74, v152, v74, v140
	v_fma_f32 v75, v153, v75, v141
	v_fma_f32 v80, v134, v80, v154
	v_fma_f32 v81, v135, v81, v155
	v_cndmask_b32_e64 v90, v90, v91, s[8:9]
	v_mul_f32_e32 v91, 0x37800000, v90
	v_cndmask_b32_e32 v90, v90, v91, vcc
	v_cmp_class_f32_e32 vcc, v3, v178
	v_fma_f32 v78, v136, v78, v156
	v_fma_f32 v79, v137, v79, v157
	v_mul_f32_e32 v84, s52, v84
	v_mul_f32_e32 v85, s52, v85
	v_cndmask_b32_e32 v3, v90, v3, vcc
	v_div_scale_f32 v90, s[4:5], v3, v3, 1.0
	v_rcp_f32_e32 v91, v90
	v_div_scale_f32 v92, vcc, 1.0, v3, 1.0
	v_fma_f32 v93, -v90, v91, 1.0
	v_fmac_f32_e32 v91, v93, v91
	v_mul_f32_e32 v93, v92, v91
	v_fma_f32 v94, -v90, v93, v92
	v_fmac_f32_e32 v93, v94, v91
	v_fma_f32 v90, -v90, v93, v92
	v_div_fmas_f32 v90, v90, v91, v93
	v_div_fixup_f32 v90, v90, v3, 1.0
	v_mul_f32_e32 v66, v66, v90
	v_mul_f32_e32 v67, v67, v90
	v_mul_f32_e32 v68, v68, v90
	v_mul_f32_e32 v69, v69, v90
	v_mul_f32_e32 v92, v62, v90
	v_mul_f32_e32 v93, v63, v90
	v_mul_f32_e32 v94, v64, v90
	v_mul_f32_e32 v95, v65, v90
	v_fma_f32 v60, v60, v90, v82
	v_fma_f32 v61, v61, v90, v83
	v_fma_f32 v58, v58, v90, v72
	v_fma_f32 v59, v59, v90, v73
	v_fma_f32 v56, v56, v90, v84
	v_fma_f32 v57, v57, v90, v85
	v_fma_f32 v54, v54, v90, v88
	v_fma_f32 v55, v55, v90, v89
	v_fma_f32 v64, v74, s52, v68
	v_fma_f32 v65, v75, s52, v69
	v_fma_f32 v62, v76, s52, v66
	v_fma_f32 v63, v77, s52, v67
	v_fma_f32 v68, v78, s52, v94
	v_fma_f32 v69, v79, s52, v95
	v_fma_f32 v66, v80, s52, v92
	v_fma_f32 v67, v81, s52, v93
	global_store_dwordx4 v[86:87], v[58:61], off offset:512
	global_store_dwordx4 v[86:87], v[54:57], off offset:528
	global_store_dwordx4 v[86:87], v[62:65], off
	global_store_dwordx4 v[86:87], v[66:69], off offset:16
	global_load_dwordx4 v[56:59], v[102:103], off offset:32
	global_load_dwordx4 v[60:63], v[102:103], off offset:48
	global_load_dwordx2 v[68:69], v[100:101], off
	global_load_dwordx4 v[64:67], v[70:71], off
	global_load_dwordx4 v[72:75], v[70:71], off offset:16
	global_load_dwordx4 v[76:79], v[70:71], off offset:512
	global_load_dwordx4 v[80:83], v[70:71], off offset:528
	v_add_u32_e32 v54, 0xa0, v176
	v_ashrrev_i32_e32 v55, 31, v54
	v_lshlrev_b32_e32 v84, 1, v54
	v_lshlrev_b64 v[86:87], 6, v[54:55]
	v_lshlrev_b64 v[54:55], 13, v[54:55]
	v_ashrrev_i32_e32 v85, 31, v84
	v_lshl_add_u64 v[86:87], s[22:23], 0, v[86:87]
	v_lshl_add_u64 v[54:55], s[20:21], 0, v[54:55]
	v_lshl_add_u64 v[84:85], v[84:85], 2, s[24:25]
	v_lshl_add_u64 v[54:55], v[54:55], 0, v[4:5]
	s_waitcnt vmcnt(5)
	v_add_f32_e32 v58, v58, v62
	v_add_f32_e32 v59, v59, v63
	v_add_f32_e32 v56, v56, v60
	v_add_f32_e32 v57, v57, v61
	s_waitcnt vmcnt(3)
	v_sub_f32_e32 v61, v65, v68
	v_sub_f32_e32 v60, v64, v68
	s_waitcnt vmcnt(2)
	v_sub_f32_e32 v65, v73, v68
	v_sub_f32_e32 v64, v72, v68
	s_waitcnt vmcnt(1)
	v_sub_f32_e32 v73, v79, v68
	v_sub_f32_e32 v72, v78, v68
	s_waitcnt vmcnt(0)
	v_sub_f32_e32 v79, v81, v68
	v_sub_f32_e32 v78, v80, v68
	v_pk_mov_b32 v[80:81], v[56:57], v[58:59] op_sel:[1,0]
	v_mov_b32_e32 v57, v59
	v_add_f32_e32 v56, v80, v56
	v_add_f32_e32 v57, v81, v57
	v_sub_f32_e32 v63, v67, v68
	v_add_f32_e32 v3, v56, v57
	v_fmamk_f32 v3, v3, 0x3a800000, v180
	v_mul_f32_e32 v56, 0x4f800000, v3
	v_cmp_gt_f32_e32 vcc, s76, v3
	v_sub_f32_e32 v62, v66, v68
	v_sub_f32_e32 v67, v75, v68
	v_sub_f32_e32 v66, v74, v68
	v_sub_f32_e32 v75, v77, v68
	v_sub_f32_e32 v74, v76, v68
	v_sub_f32_e32 v77, v83, v68
	v_sub_f32_e32 v76, v82, v68
	v_cndmask_b32_e32 v3, v3, v56, vcc
	v_mul_f32_e32 v58, v69, v62
	v_mul_f32_e32 v59, v69, v63
	v_mul_f32_e32 v60, v69, v60
	v_mul_f32_e32 v61, v69, v61
	v_mul_f32_e32 v62, v69, v66
	v_mul_f32_e32 v63, v69, v67
	v_mul_f32_e32 v64, v69, v64
	v_mul_f32_e32 v65, v69, v65
	v_mul_f32_e32 v66, v69, v74
	v_mul_f32_e32 v67, v69, v75
	v_mul_f32_e32 v72, v69, v72
	v_mul_f32_e32 v73, v69, v73
	v_mul_f32_e32 v74, v69, v78
	v_mul_f32_e32 v75, v69, v79
	v_mul_f32_e32 v68, v69, v76
	v_mul_f32_e32 v69, v69, v77
	v_sqrt_f32_e32 v76, v3
	v_fma_f32 v72, v160, v72, v148
	v_fma_f32 v73, v161, v73, v149
	v_fma_f32 v66, v158, v66, v146
	v_fma_f32 v67, v159, v67, v147
	v_fma_f32 v74, v142, v74, v162
	v_fma_f32 v75, v143, v75, v163
	v_mul_f32_e32 v56, s52, v66
	v_mul_f32_e32 v57, s52, v67
	v_mul_f32_e32 v66, s52, v72
	v_mul_f32_e32 v67, s52, v73
	v_mul_f32_e32 v72, s52, v74
	v_mul_f32_e32 v73, s52, v75
	v_add_u32_e32 v74, -1, v76
	v_add_u32_e32 v75, 1, v76
	v_fma_f32 v77, -v74, v76, v3
	v_fma_f32 v78, -v75, v76, v3
	v_cmp_ge_f32_e64 s[8:9], 0, v77
	v_fma_f32 v68, v144, v68, v164
	v_fma_f32 v69, v145, v69, v165
	v_fma_f32 v60, v150, v60, v138
	v_fma_f32 v61, v151, v61, v139
	v_cndmask_b32_e64 v74, v76, v74, s[8:9]
	v_cmp_lt_f32_e64 s[8:9], 0, v78
	v_fma_f32 v58, v152, v58, v140
	v_fma_f32 v59, v153, v59, v141
	v_fma_f32 v64, v134, v64, v154
	v_fma_f32 v65, v135, v65, v155
	v_cndmask_b32_e64 v74, v74, v75, s[8:9]
	v_mul_f32_e32 v75, 0x37800000, v74
	v_cndmask_b32_e32 v74, v74, v75, vcc
	v_cmp_class_f32_e32 vcc, v3, v178
	v_fma_f32 v62, v136, v62, v156
	v_fma_f32 v63, v137, v63, v157
	v_mul_f32_e32 v68, s52, v68
	v_mul_f32_e32 v69, s52, v69
	v_cndmask_b32_e32 v3, v74, v3, vcc
	v_div_scale_f32 v74, s[4:5], v3, v3, 1.0
	v_rcp_f32_e32 v75, v74
	v_div_scale_f32 v76, vcc, 1.0, v3, 1.0
	v_fma_f32 v77, -v74, v75, 1.0
	v_fmac_f32_e32 v75, v77, v75
	v_mul_f32_e32 v77, v76, v75
	v_fma_f32 v78, -v74, v77, v76
	v_fmac_f32_e32 v77, v78, v75
	v_fma_f32 v74, -v74, v77, v76
	v_div_fmas_f32 v74, v74, v75, v77
	v_div_fixup_f32 v74, v74, v3, 1.0
	v_mul_f32_e32 v50, v50, v74
	v_mul_f32_e32 v51, v51, v74
	v_mul_f32_e32 v52, v52, v74
	v_mul_f32_e32 v53, v53, v74
	v_mul_f32_e32 v76, v46, v74
	v_mul_f32_e32 v77, v47, v74
	v_mul_f32_e32 v78, v48, v74
	v_mul_f32_e32 v79, v49, v74
	v_fma_f32 v44, v44, v74, v66
	v_fma_f32 v45, v45, v74, v67
	v_fma_f32 v42, v42, v74, v56
	v_fma_f32 v43, v43, v74, v57
	v_fma_f32 v40, v40, v74, v68
	v_fma_f32 v41, v41, v74, v69
	v_fma_f32 v38, v38, v74, v72
	v_fma_f32 v39, v39, v74, v73
	v_fma_f32 v48, v58, s52, v52
	v_fma_f32 v49, v59, s52, v53
	v_fma_f32 v46, v60, s52, v50
	v_fma_f32 v47, v61, s52, v51
	v_fma_f32 v52, v62, s52, v78
	v_fma_f32 v53, v63, s52, v79
	v_fma_f32 v50, v64, s52, v76
	v_fma_f32 v51, v65, s52, v77
	global_store_dwordx4 v[70:71], v[42:45], off offset:512
	global_store_dwordx4 v[70:71], v[38:41], off offset:528
	global_store_dwordx4 v[70:71], v[46:49], off
	global_store_dwordx4 v[70:71], v[50:53], off offset:16
	global_load_dwordx4 v[38:41], v[86:87], off offset:32
	global_load_dwordx4 v[42:45], v[86:87], off offset:48
	global_load_dwordx2 v[64:65], v[84:85], off
	global_load_dwordx4 v[46:49], v[54:55], off
	global_load_dwordx4 v[50:53], v[54:55], off offset:16
	global_load_dwordx4 v[56:59], v[54:55], off offset:512
	global_load_dwordx4 v[60:63], v[54:55], off offset:528
	v_add_u32_e32 v66, 0xb0, v176
	v_ashrrev_i32_e32 v67, 31, v66
	v_lshlrev_b32_e32 v68, 1, v66
	v_lshlrev_b64 v[70:71], 6, v[66:67]
	v_lshlrev_b64 v[66:67], 13, v[66:67]
	v_ashrrev_i32_e32 v69, 31, v68
	v_lshl_add_u64 v[70:71], s[22:23], 0, v[70:71]
	v_lshl_add_u64 v[66:67], s[20:21], 0, v[66:67]
	v_lshl_add_u64 v[68:69], v[68:69], 2, s[24:25]
	v_lshl_add_u64 v[4:5], v[66:67], 0, v[4:5]
	s_waitcnt vmcnt(5)
	v_add_f32_e32 v40, v40, v44
	v_add_f32_e32 v41, v41, v45
	v_add_f32_e32 v38, v38, v42
	v_add_f32_e32 v39, v39, v43
	s_waitcnt vmcnt(3)
	v_sub_f32_e32 v43, v47, v64
	v_sub_f32_e32 v42, v46, v64
	s_waitcnt vmcnt(2)
	v_sub_f32_e32 v47, v51, v64
	v_sub_f32_e32 v46, v50, v64
	s_waitcnt vmcnt(1)
	v_sub_f32_e32 v51, v59, v64
	v_sub_f32_e32 v50, v58, v64
	s_waitcnt vmcnt(0)
	v_sub_f32_e32 v59, v61, v64
	v_sub_f32_e32 v58, v60, v64
	v_pk_mov_b32 v[60:61], v[38:39], v[40:41] op_sel:[1,0]
	v_mov_b32_e32 v39, v41
	v_add_f32_e32 v38, v60, v38
	v_add_f32_e32 v39, v61, v39
	v_sub_f32_e32 v45, v49, v64
	v_add_f32_e32 v3, v38, v39
	v_fmamk_f32 v3, v3, 0x3a800000, v180
	v_mul_f32_e32 v38, 0x4f800000, v3
	v_cmp_gt_f32_e32 vcc, s76, v3
	v_sub_f32_e32 v44, v48, v64
	v_sub_f32_e32 v49, v53, v64
	v_sub_f32_e32 v48, v52, v64
	v_sub_f32_e32 v53, v57, v64
	v_sub_f32_e32 v52, v56, v64
	v_cndmask_b32_e32 v3, v3, v38, vcc
	v_mul_f32_e32 v40, v65, v44
	v_mul_f32_e32 v41, v65, v45
	v_mul_f32_e32 v44, v65, v48
	v_mul_f32_e32 v45, v65, v49
	v_mul_f32_e32 v48, v65, v52
	v_mul_f32_e32 v49, v65, v53
	v_mul_f32_e32 v52, v65, v58
	v_mul_f32_e32 v53, v65, v59
	v_sqrt_f32_e32 v58, v3
	v_mul_f32_e32 v50, v65, v50
	v_mul_f32_e32 v51, v65, v51
	v_fma_f32 v48, v158, v48, v146
	v_fma_f32 v49, v159, v49, v147
	v_fma_f32 v50, v160, v50, v148
	v_fma_f32 v51, v161, v51, v149
	v_fma_f32 v52, v142, v52, v162
	v_fma_f32 v53, v143, v53, v163
	v_mul_f32_e32 v38, s52, v48
	v_mul_f32_e32 v39, s52, v49
	v_mul_f32_e32 v48, s52, v50
	v_mul_f32_e32 v49, s52, v51
	v_mul_f32_e32 v50, s52, v52
	v_mul_f32_e32 v51, s52, v53
	v_add_u32_e32 v52, -1, v58
	v_add_u32_e32 v53, 1, v58
	v_fma_f32 v59, -v52, v58, v3
	v_fma_f32 v60, -v53, v58, v3
	v_cmp_ge_f32_e64 s[8:9], 0, v59
	v_sub_f32_e32 v57, v63, v64
	v_sub_f32_e32 v56, v62, v64
	v_cndmask_b32_e64 v52, v58, v52, s[8:9]
	v_cmp_lt_f32_e64 s[8:9], 0, v60
	v_mul_f32_e32 v56, v65, v56
	v_mul_f32_e32 v57, v65, v57
	v_mul_f32_e32 v42, v65, v42
	v_mul_f32_e32 v43, v65, v43
	v_cndmask_b32_e64 v52, v52, v53, s[8:9]
	v_mul_f32_e32 v53, 0x37800000, v52
	v_cndmask_b32_e32 v52, v52, v53, vcc
	v_cmp_class_f32_e32 vcc, v3, v178
	v_fma_f32 v56, v144, v56, v164
	v_fma_f32 v57, v145, v57, v165
	v_mul_f32_e32 v46, v65, v46
	v_mul_f32_e32 v47, v65, v47
	v_cndmask_b32_e32 v3, v52, v3, vcc
	v_div_scale_f32 v58, s[4:5], v3, v3, 1.0
	v_rcp_f32_e32 v59, v58
	v_mul_f32_e32 v52, s52, v56
	v_mul_f32_e32 v53, s52, v57
	v_div_scale_f32 v56, vcc, 1.0, v3, 1.0
	v_fma_f32 v57, -v58, v59, 1.0
	v_fmac_f32_e32 v59, v57, v59
	v_mul_f32_e32 v57, v56, v59
	v_fma_f32 v60, -v58, v57, v56
	v_fmac_f32_e32 v57, v60, v59
	v_fma_f32 v56, -v58, v57, v56
	v_div_fmas_f32 v56, v56, v59, v57
	v_div_fixup_f32 v56, v56, v3, 1.0
	v_fma_f32 v42, v150, v42, v138
	v_fma_f32 v43, v151, v43, v139
	v_fma_f32 v40, v152, v40, v140
	v_fma_f32 v41, v153, v41, v141
	v_fma_f32 v46, v134, v46, v154
	v_fma_f32 v47, v135, v47, v155
	v_fma_f32 v44, v136, v44, v156
	v_fma_f32 v45, v137, v45, v157
	v_mul_f32_e32 v34, v34, v56
	v_mul_f32_e32 v35, v35, v56
	v_mul_f32_e32 v36, v36, v56
	v_mul_f32_e32 v37, v37, v56
	v_mul_f32_e32 v58, v30, v56
	v_mul_f32_e32 v59, v31, v56
	v_mul_f32_e32 v60, v32, v56
	v_mul_f32_e32 v61, v33, v56
	v_fma_f32 v28, v28, v56, v48
	v_fma_f32 v29, v29, v56, v49
	v_fma_f32 v26, v26, v56, v38
	v_fma_f32 v27, v27, v56, v39
	v_fma_f32 v24, v24, v56, v52
	v_fma_f32 v25, v25, v56, v53
	v_fma_f32 v22, v22, v56, v50
	v_fma_f32 v23, v23, v56, v51
	v_fma_f32 v32, v40, s52, v36
	v_fma_f32 v33, v41, s52, v37
	v_fma_f32 v30, v42, s52, v34
	v_fma_f32 v31, v43, s52, v35
	v_fma_f32 v36, v44, s52, v60
	v_fma_f32 v37, v45, s52, v61
	v_fma_f32 v34, v46, s52, v58
	v_fma_f32 v35, v47, s52, v59
	global_store_dwordx4 v[54:55], v[26:29], off offset:512
	global_store_dwordx4 v[54:55], v[22:25], off offset:528
	global_store_dwordx4 v[54:55], v[30:33], off
	global_store_dwordx4 v[54:55], v[34:37], off offset:16
	global_load_dwordx4 v[22:25], v[70:71], off offset:32
	global_load_dwordx4 v[26:29], v[70:71], off offset:48
	global_load_dwordx2 v[46:47], v[68:69], off
	global_load_dwordx4 v[30:33], v[4:5], off
	global_load_dwordx4 v[34:37], v[4:5], off offset:16
	global_load_dwordx4 v[38:41], v[4:5], off offset:512
	global_load_dwordx4 v[42:45], v[4:5], off offset:528
	s_waitcnt vmcnt(5)
	v_add_f32_e32 v24, v24, v28
	v_add_f32_e32 v25, v25, v29
	v_add_f32_e32 v22, v22, v26
	v_add_f32_e32 v23, v23, v27
	s_waitcnt vmcnt(3)
	v_sub_f32_e32 v27, v31, v46
	v_sub_f32_e32 v26, v30, v46
	s_waitcnt vmcnt(2)
	v_sub_f32_e32 v31, v35, v46
	v_sub_f32_e32 v30, v34, v46
	s_waitcnt vmcnt(1)
	v_sub_f32_e32 v35, v41, v46
	v_sub_f32_e32 v34, v40, v46
	s_waitcnt vmcnt(0)
	v_sub_f32_e32 v41, v43, v46
	v_sub_f32_e32 v40, v42, v46
	v_pk_mov_b32 v[42:43], v[22:23], v[24:25] op_sel:[1,0]
	v_mov_b32_e32 v23, v25
	v_add_f32_e32 v22, v42, v22
	v_add_f32_e32 v23, v43, v23
	v_sub_f32_e32 v29, v33, v46
	v_add_f32_e32 v3, v22, v23
	v_fmamk_f32 v3, v3, 0x3a800000, v180
	v_mul_f32_e32 v22, 0x4f800000, v3
	v_cmp_gt_f32_e32 vcc, s76, v3
	v_sub_f32_e32 v28, v32, v46
	v_sub_f32_e32 v33, v37, v46
	v_sub_f32_e32 v32, v36, v46
	v_sub_f32_e32 v37, v39, v46
	v_sub_f32_e32 v36, v38, v46
	v_cndmask_b32_e32 v3, v3, v22, vcc
	v_mul_f32_e32 v24, v47, v28
	v_mul_f32_e32 v25, v47, v29
	v_mul_f32_e32 v28, v47, v32
	v_mul_f32_e32 v29, v47, v33
	v_mul_f32_e32 v32, v47, v36
	v_mul_f32_e32 v33, v47, v37
	v_mul_f32_e32 v36, v47, v40
	v_mul_f32_e32 v37, v47, v41
	v_sqrt_f32_e32 v40, v3
	v_mul_f32_e32 v34, v47, v34
	v_mul_f32_e32 v35, v47, v35
	v_fma_f32 v32, v158, v32, v146
	v_fma_f32 v33, v159, v33, v147
	v_fma_f32 v34, v160, v34, v148
	v_fma_f32 v35, v161, v35, v149
	v_fma_f32 v36, v142, v36, v162
	v_fma_f32 v37, v143, v37, v163
	v_mul_f32_e32 v22, s52, v32
	v_mul_f32_e32 v23, s52, v33
	v_mul_f32_e32 v32, s52, v34
	v_mul_f32_e32 v33, s52, v35
	v_mul_f32_e32 v34, s52, v36
	v_mul_f32_e32 v35, s52, v37
	v_add_u32_e32 v36, -1, v40
	v_add_u32_e32 v37, 1, v40
	v_fma_f32 v41, -v36, v40, v3
	v_fma_f32 v42, -v37, v40, v3
	v_cmp_ge_f32_e64 s[8:9], 0, v41
	v_sub_f32_e32 v39, v45, v46
	v_sub_f32_e32 v38, v44, v46
	v_cndmask_b32_e64 v36, v40, v36, s[8:9]
	v_cmp_lt_f32_e64 s[8:9], 0, v42
	v_mul_f32_e32 v38, v47, v38
	v_mul_f32_e32 v39, v47, v39
	v_mul_f32_e32 v26, v47, v26
	v_mul_f32_e32 v27, v47, v27
	v_cndmask_b32_e64 v36, v36, v37, s[8:9]
	v_mul_f32_e32 v37, 0x37800000, v36
	v_cndmask_b32_e32 v36, v36, v37, vcc
	v_cmp_class_f32_e32 vcc, v3, v178
	v_fma_f32 v38, v144, v38, v164
	v_fma_f32 v39, v145, v39, v165
	v_mul_f32_e32 v30, v47, v30
	v_mul_f32_e32 v31, v47, v31
	v_cndmask_b32_e32 v3, v36, v3, vcc
	v_div_scale_f32 v40, s[4:5], v3, v3, 1.0
	v_rcp_f32_e32 v41, v40
	v_mul_f32_e32 v36, s52, v38
	v_mul_f32_e32 v37, s52, v39
	v_div_scale_f32 v38, vcc, 1.0, v3, 1.0
	v_fma_f32 v39, -v40, v41, 1.0
	v_fmac_f32_e32 v41, v39, v41
	v_mul_f32_e32 v39, v38, v41
	v_fma_f32 v42, -v40, v39, v38
	v_fmac_f32_e32 v39, v42, v41
	v_fma_f32 v38, -v40, v39, v38
	v_div_fmas_f32 v38, v38, v41, v39
	v_div_fixup_f32 v38, v38, v3, 1.0
	v_fma_f32 v26, v150, v26, v138
	v_fma_f32 v27, v151, v27, v139
	v_fma_f32 v24, v152, v24, v140
	v_fma_f32 v25, v153, v25, v141
	v_fma_f32 v30, v134, v30, v154
	v_fma_f32 v31, v135, v31, v155
	v_fma_f32 v28, v136, v28, v156
	v_fma_f32 v29, v137, v29, v157
	v_mul_f32_e32 v18, v18, v38
	v_mul_f32_e32 v19, v19, v38
	v_mul_f32_e32 v20, v20, v38
	v_mul_f32_e32 v21, v21, v38
	v_mul_f32_e32 v40, v14, v38
	v_mul_f32_e32 v41, v15, v38
	v_mul_f32_e32 v42, v16, v38
	v_mul_f32_e32 v43, v17, v38
	v_fma_f32 v12, v12, v38, v32
	v_fma_f32 v13, v13, v38, v33
	v_fma_f32 v10, v10, v38, v22
	v_fma_f32 v11, v11, v38, v23
	v_fma_f32 v8, v8, v38, v36
	v_fma_f32 v9, v9, v38, v37
	v_fma_f32 v6, v6, v38, v34
	v_fma_f32 v7, v7, v38, v35
	v_fma_f32 v16, v24, s52, v20
	v_fma_f32 v17, v25, s52, v21
	v_fma_f32 v14, v26, s52, v18
	v_fma_f32 v15, v27, s52, v19
	v_fma_f32 v20, v28, s52, v42
	v_fma_f32 v21, v29, s52, v43
	v_fma_f32 v18, v30, s52, v40
	v_fma_f32 v19, v31, s52, v41
	global_store_dwordx4 v[4:5], v[10:13], off offset:512
	global_store_dwordx4 v[4:5], v[6:9], off offset:528
	global_store_dwordx4 v[4:5], v[14:17], off
	global_store_dwordx4 v[4:5], v[18:21], off offset:16
	s_andn2_b64 vcc, exec, s[6:7]
	s_mov_b64 s[4:5], -1
	s_cbranch_vccnz .LBB0_1872
	s_andn2_b64 vcc, exec, s[18:19]
	s_cbranch_vccnz .LBB0_1871
	s_barrier
	s_branch .LBB0_1871

.LBB0_1962:
	v_lshl_add_u64 v[2:3], s[72:73], 0, v[128:129]
	v_add_co_u32_e32 v4, vcc, 0x1ab00000, v2
	s_nop 1
	v_addc_co_u32_e32 v5, vcc, 0, v3, vcc
	global_load_dwordx4 v[22:25], v[4:5], off offset:1024
	global_load_dwordx4 v[18:21], v[4:5], off
	global_load_dwordx4 v[26:29], v[4:5], off offset:2048
	global_load_dwordx4 v[30:33], v[4:5], off offset:3072
	v_add_co_u32_e32 v34, vcc, 0x1ab01000, v2
	s_waitcnt vmcnt(3)
	v_mov_b32_e32 v36, v23
	v_addc_co_u32_e32 v35, vcc, 0, v3, vcc
	global_load_dwordx4 v[2:5], v[34:35], off
	global_load_dwordx4 v[6:9], v[34:35], off offset:1024
	s_waitcnt lgkmcnt(2)
	global_load_dwordx4 v[10:13], v[34:35], off offset:2048
	s_waitcnt lgkmcnt(0)
	global_load_dwordx4 v[14:17], v[34:35], off offset:3072
	v_mov_b32_e32 v34, v22
	s_waitcnt vmcnt(6)
	v_mov_b32_e32 v35, v18
	v_mov_b32_e32 v37, v19
	v_mov_b32_e32 v38, v24
	v_mov_b32_e32 v39, v20
	v_mov_b32_e32 v42, v25
	v_mov_b32_e32 v43, v21
	s_waitcnt vmcnt(5)
	v_mov_b32_e32 v44, v27
	v_mov_b32_e32 v45, v28
	v_mov_b32_e32 v46, v26
	v_mov_b32_e32 v47, v29
	v_add_f32_e32 v34, v34, v36
	v_add_f32_e32 v35, v35, v37
	v_add_f32_e32 v36, v38, v42
	v_add_f32_e32 v37, v39, v43
	v_add_f32_e32 v38, v44, v46
	v_add_f32_e32 v39, v45, v47
	v_add_f32_e32 v34, v34, v36
	v_add_f32_e32 v35, v35, v37
	v_add_f32_e32 v36, v38, v38
	v_add_f32_e32 v37, v38, v39
	v_add_f32_e32 v35, 0, v35
	s_waitcnt vmcnt(4)
	v_add_f32_e32 v49, v30, v31
	v_add_f32_e32 v51, v32, v33
	v_add_f32_e32 v43, v34, v35
	s_waitcnt vmcnt(3)
	v_mov_b32_e32 v48, v2
	v_mov_b32_e32 v50, v3
	v_mov_b32_e32 v42, v5
	v_mov_b32_e32 v36, v4
	s_waitcnt vmcnt(2)
	v_mov_b32_e32 v44, v7
	v_mov_b32_e32 v45, v8
	v_mov_b32_e32 v46, v6
	v_mov_b32_e32 v47, v9
	v_add_f32_e32 v38, v48, v50
	v_add_f32_e32 v39, v49, v51
	v_add_f32_e32 v34, v36, v42
	v_add_f32_e32 v35, v37, v43
	v_add_f32_e32 v44, v44, v46
	v_add_f32_e32 v45, v45, v47
	v_add_f32_e32 v34, v38, v34
	v_add_f32_e32 v35, v39, v35
	v_add_f32_e32 v45, v44, v45
	v_add_f32_e32 v44, v44, v44
	v_add_f32_e32 v35, v34, v35
	v_add_f32_e32 v34, v34, v34
	s_waitcnt vmcnt(1)
	v_add_f32_e32 v53, v10, v11
	v_add_f32_e32 v55, v12, v13
	s_waitcnt vmcnt(0)
	v_mov_b32_e32 v52, v14
	v_mov_b32_e32 v54, v15
	v_mov_b32_e32 v44, v16
	v_mov_b32_e32 v34, v17
	v_add_f32_e32 v46, v52, v54
	v_add_f32_e32 v47, v53, v55
	v_add_f32_e32 v34, v44, v34
	v_add_f32_e32 v35, v45, v35
	s_nop 0
	v_add_f32_e32 v34, v46, v34
	v_add_f32_e32 v35, v47, v35
	s_nop 0
	v_add_f32_e32 v34, v34, v35
	ds_bpermute_b32 v35, v103, v34
	s_waitcnt lgkmcnt(0)
	v_add_f32_e32 v34, v34, v35
	ds_bpermute_b32 v35, v134, v34
	s_waitcnt lgkmcnt(0)
	v_add_f32_e32 v34, v34, v35
	ds_bpermute_b32 v35, v135, v34
	s_waitcnt lgkmcnt(0)
	v_add_f32_e32 v34, v34, v35
	ds_bpermute_b32 v35, v136, v34
	s_waitcnt lgkmcnt(0)
	v_add_f32_e32 v34, v34, v35
	ds_bpermute_b32 v35, v137, v34
	s_waitcnt lgkmcnt(0)
	v_add_f32_e32 v34, v34, v35
	ds_bpermute_b32 v35, v138, v34
	s_waitcnt lgkmcnt(0)
	v_add_f32_e32 v143, v34, v35
	v_fmamk_f32 v38, v143, 0xba000000, v21
	v_fmamk_f32 v132, v143, 0xba000000, v20
	v_fmamk_f32 v20, v143, 0xba000000, v19
	v_fmamk_f32 v39, v143, 0xba000000, v25
	v_fmamk_f32 v21, v143, 0xba000000, v23
	v_fmac_f32_e32 v22, 0xba000000, v143
	v_fmamk_f32 v29, v143, 0xba000000, v29
	v_fmamk_f32 v28, v143, 0xba000000, v28
	v_fmamk_f32 v27, v143, 0xba000000, v27
	v_fmac_f32_e32 v26, 0xba000000, v143
	v_fmac_f32_e32 v18, 0xba000000, v143
	v_fmamk_f32 v133, v143, 0xba000000, v24
	v_mov_b32_e32 v19, v22
	v_mul_f32_e32 v24, v20, v20
	v_mul_f32_e32 v25, v21, v21
	v_mul_f32_e32 v34, v38, v38
	v_mul_f32_e32 v35, v39, v39
	v_mul_f32_e32 v36, v28, v28
	v_mul_f32_e32 v37, v29, v29
	v_mul_f32_e32 v42, v26, v26
	v_mul_f32_e32 v43, v27, v27
	v_fmamk_f32 v32, v143, 0xba000000, v32
	v_fmac_f32_e32 v30, 0xba000000, v143
	v_fmac_f32_e32 v24, v18, v18
	v_fmac_f32_e32 v25, v19, v19
	v_fmac_f32_e32 v34, v132, v132
	v_fmac_f32_e32 v35, v133, v133
	v_pk_mov_b32 v[54:55], v[42:43], v[36:37] op_sel:[1,0]
	v_mov_b32_e32 v43, v37
	v_fmamk_f32 v33, v143, 0xba000000, v33
	v_fmamk_f32 v31, v143, 0xba000000, v31
	v_fmamk_f32 v9, v143, 0xba000000, v9
	v_fmamk_f32 v8, v143, 0xba000000, v8
	v_fmamk_f32 v7, v143, 0xba000000, v7
	v_fmac_f32_e32 v6, 0xba000000, v143
	v_mul_f32_e32 v40, v30, v30
	v_mul_f32_e32 v44, v32, v32
	v_add_f32_e32 v24, v24, v34
	v_add_f32_e32 v25, v25, v35
	v_add_f32_e32 v34, v54, v42
	v_add_f32_e32 v35, v55, v43
	v_fmamk_f32 v5, v143, 0xba000000, v5
	v_fmamk_f32 v4, v143, 0xba000000, v4
	v_fmamk_f32 v3, v143, 0xba000000, v3
	v_fmac_f32_e32 v2, 0xba000000, v143
	v_mul_f32_e32 v46, v8, v8
	v_mul_f32_e32 v47, v9, v9
	v_mul_f32_e32 v48, v6, v6
	v_mul_f32_e32 v49, v7, v7
	v_fma_f32 v36, v30, v30, v40
	v_fma_f32 v37, v31, v31, v40
	v_fma_f32 v45, v33, v33, v44
	v_fmac_f32_e32 v44, v32, v32
	v_add_f32_e32 v25, v24, v25
	v_add_f32_e32 v24, v24, v24
	v_add_f32_e32 v35, v34, v35
	v_add_f32_e32 v34, v34, v34
	v_fmamk_f32 v12, v143, 0xba000000, v12
	v_fmac_f32_e32 v10, 0xba000000, v143
	v_pk_mov_b32 v[56:57], v[48:49], v[46:47] op_sel:[1,0]
	v_mov_b32_e32 v49, v47
	v_mul_f32_e32 v36, v2, v2
	v_mul_f32_e32 v44, v3, v3
	v_mul_f32_e32 v34, v4, v4
	v_mul_f32_e32 v24, v5, v5
	v_fmamk_f32 v13, v143, 0xba000000, v13
	v_fmamk_f32 v11, v143, 0xba000000, v11
	v_mul_f32_e32 v50, v10, v10
	v_mul_f32_e32 v52, v12, v12
	v_add_f32_e32 v42, v56, v48
	v_add_f32_e32 v43, v57, v49
	v_add_f32_e32 v36, v36, v44
	v_add_f32_e32 v37, v37, v45
	v_add_f32_e32 v24, v34, v24
	v_add_f32_e32 v25, v35, v25
	v_fma_f32 v144, v10, v10, v50
	v_fma_f32 v145, v11, v11, v50
	v_fma_f32 v146, v12, v12, v52
	v_fma_f32 v147, v13, v13, v52
	v_add_f32_e32 v148, v42, v42
	v_add_f32_e32 v149, v42, v43
	v_add_f32_e32 v24, v36, v24
	v_add_f32_e32 v25, v37, v25
	global_load_dwordx4 v[94:97], v[106:107], off
	global_load_dwordx4 v[86:89], v[106:107], off offset:1024
	global_load_dwordx4 v[98:101], v[108:109], off
	global_load_dwordx4 v[90:93], v[108:109], off offset:1024
	global_load_dwordx4 v[78:81], v[106:107], off offset:2048
	global_load_dwordx4 v[70:73], v[106:107], off offset:3072
	global_load_dwordx4 v[82:85], v[108:109], off offset:2048
	global_load_dwordx4 v[74:77], v[108:109], off offset:3072
	global_load_dwordx4 v[62:65], v[110:111], off
	global_load_dwordx4 v[66:69], v[112:113], off
	global_load_dwordx4 v[54:57], v[114:115], off
	global_load_dwordx4 v[58:61], v[116:117], off
	global_load_dwordx4 v[46:49], v[118:119], off
	global_load_dwordx4 v[50:53], v[120:121], off
	global_load_dwordx4 v[34:37], v[122:123], off
	global_load_dwordx4 v[42:45], v[124:125], off
	v_fmamk_f32 v17, v143, 0xba000000, v17
	v_add_f32_e32 v25, v24, v25
	v_add_f32_e32 v24, v24, v24
	v_fmamk_f32 v16, v143, 0xba000000, v16
	v_fmamk_f32 v15, v143, 0xba000000, v15
	v_fmac_f32_e32 v14, 0xba000000, v143
	v_mul_f32_e32 v144, v14, v14
	v_mul_f32_e32 v146, v15, v15
	v_mul_f32_e32 v148, v16, v16
	v_mul_f32_e32 v24, v17, v17
	v_add_f32_e32 v144, v144, v146
	v_add_f32_e32 v145, v145, v147
	v_add_f32_e32 v24, v148, v24
	v_add_f32_e32 v25, v149, v25
	s_nop 0
	v_add_f32_e32 v24, v144, v24
	v_add_f32_e32 v25, v145, v25
	s_nop 0
	v_add_f32_e32 v19, v24, v25
	ds_bpermute_b32 v23, v103, v19
	s_waitcnt lgkmcnt(0)
	v_add_f32_e32 v19, v19, v23
	ds_bpermute_b32 v23, v134, v19
	s_waitcnt lgkmcnt(0)
	v_add_f32_e32 v19, v19, v23
	ds_bpermute_b32 v23, v135, v19
	s_waitcnt lgkmcnt(0)
	v_add_f32_e32 v19, v19, v23
	ds_bpermute_b32 v23, v136, v19
	s_waitcnt lgkmcnt(0)
	v_add_f32_e32 v19, v19, v23
	ds_bpermute_b32 v23, v137, v19
	s_waitcnt lgkmcnt(0)
	v_add_f32_e32 v19, v19, v23
	ds_bpermute_b32 v23, v138, v19
	s_waitcnt lgkmcnt(0)
	v_add_f32_e32 v19, v19, v23
	v_fmamk_f32 v19, v19, 0x3a000000, v105
	v_mul_f32_e32 v23, 0x4f800000, v19
	v_cmp_gt_f32_e32 vcc, s1, v19
	s_nop 1
	v_cndmask_b32_e32 v19, v19, v23, vcc
	v_sqrt_f32_e32 v23, v19
	s_nop 0
	v_add_u32_e32 v24, -1, v23
	v_add_u32_e32 v25, 1, v23
	v_fma_f32 v40, -v24, v23, v19
	v_fma_f32 v127, -v25, v23, v19
	v_cmp_ge_f32_e64 s[10:11], 0, v40
	s_nop 1
	v_cndmask_b32_e64 v23, v23, v24, s[10:11]
	v_cmp_lt_f32_e64 s[10:11], 0, v127
	s_nop 1
	v_cndmask_b32_e64 v23, v23, v25, s[10:11]
	v_mul_f32_e32 v24, 0x37800000, v23
	v_cndmask_b32_e32 v23, v23, v24, vcc
	v_cmp_class_f32_e32 vcc, v19, v140
	s_nop 1
	v_cndmask_b32_e32 v19, v23, v19, vcc
	v_div_scale_f32 v23, s[4:5], v19, v19, 1.0
	v_rcp_f32_e32 v24, v23
	s_nop 0
	v_fma_f32 v25, -v23, v24, 1.0
	v_fmac_f32_e32 v24, v25, v24
	v_div_scale_f32 v25, vcc, 1.0, v19, 1.0
	v_mul_f32_e32 v40, v25, v24
	v_fma_f32 v127, -v23, v40, v25
	v_fmac_f32_e32 v40, v127, v24
	v_fma_f32 v23, -v23, v40, v25
	v_div_fmas_f32 v23, v23, v24, v40
	v_div_fixup_f32 v40, v23, v19, 1.0
	v_ashrrev_i32_e32 v127, 31, v126
	s_and_saveexec_b64 s[4:5], s[8:9]
	s_cbranch_execz .LBB0_1964
	v_mul_f32_e32 v24, 0x3a000000, v143
	v_lshl_add_u64 v[144:145], v[126:127], 2, s[34:35]
	v_mov_b32_e32 v25, v40
	global_store_dwordx2 v[144:145], v[24:25], off
.LBB0_1964:
	s_or_b64 exec, exec, s[4:5]
	v_mov_b32_e32 v19, v20
	v_mov_b32_e32 v23, v21
	v_mov_b32_e32 v20, v132
	v_mov_b32_e32 v21, v38
	v_mul_f32_e32 v18, v18, v40
	v_mul_f32_e32 v19, v19, v40
	v_mul_f32_e32 v2, v2, v40
	v_mul_f32_e32 v3, v3, v40
	v_mul_f32_e32 v20, v20, v40
	v_mul_f32_e32 v21, v21, v40
	s_waitcnt vmcnt(13)
	v_fma_f32 v18, v94, v18, v98
	v_fma_f32 v19, v95, v19, v99
	v_mul_f32_e32 v4, v4, v40
	v_mul_f32_e32 v5, v5, v40
	s_waitcnt vmcnt(6)
	v_fma_f32 v2, v62, v2, v66
	v_fma_f32 v3, v63, v3, v67
	v_mul_f32_e32 v14, v14, v40
	v_mul_f32_e32 v15, v15, v40
	v_fma_f32 v20, v96, v20, v100
	v_fma_f32 v21, v97, v21, v101
	v_mov_b32_e32 v38, v133
	v_mul_f32_e32 v22, v22, v40
	v_mul_f32_e32 v23, v23, v40
	v_fma_f32 v4, v64, v4, v68
	v_fma_f32 v5, v65, v5, v69
	v_mul_f32_e32 v6, v6, v40
	v_mul_f32_e32 v7, v7, v40
	v_mul_f32_e32 v16, v16, v40
	v_mul_f32_e32 v17, v17, v40
	s_waitcnt vmcnt(0)
	v_fma_f32 v14, v34, v14, v42
	v_fma_f32 v15, v35, v15, v43
	v_max_f32_e64 v34, |v18|, |v2|
	v_max_f32_e64 v35, |v19|, |v3|
	v_mul_f32_e32 v24, v38, v40
	v_mul_f32_e32 v25, v39, v40
	v_fma_f32 v22, v86, v22, v90
	v_fma_f32 v23, v87, v23, v91
	v_mul_f32_e32 v8, v8, v40
	v_mul_f32_e32 v9, v9, v40
	v_fma_f32 v6, v54, v6, v58
	v_fma_f32 v7, v55, v7, v59
	v_mul_f32_e32 v12, v12, v40
	v_mul_f32_e32 v13, v13, v40
	v_mul_f32_e32 v10, v10, v40
	v_mul_f32_e32 v11, v11, v40
	v_fma_f32 v16, v36, v16, v44
	v_fma_f32 v17, v37, v17, v45
	v_max3_f32 v34, v34, 0, v35
	v_max_f32_e64 v35, |v20|, |v4|
	v_max_f32_e64 v36, |v21|, |v5|
	v_fma_f32 v24, v88, v24, v92
	v_fma_f32 v25, v89, v25, v93
	v_mul_f32_e32 v26, v26, v40
	v_mul_f32_e32 v27, v27, v40
	v_fma_f32 v8, v56, v8, v60
	v_fma_f32 v9, v57, v9, v61
	v_fma_f32 v12, v48, v12, v52
	v_fma_f32 v13, v49, v13, v53
	v_fma_f32 v10, v46, v10, v50
	v_fma_f32 v11, v47, v11, v51
	v_max3_f32 v34, v34, v35, v36
	v_max_f32_e64 v35, |v22|, |v6|
	v_max_f32_e64 v36, |v23|, |v7|
	ds_read_b128 v[50:53], v139
	v_mul_f32_e32 v28, v28, v40
	v_mul_f32_e32 v29, v29, v40
	v_fma_f32 v26, v78, v26, v82
	v_fma_f32 v27, v79, v27, v83
	v_max3_f32 v34, v34, v35, v36
	v_max_f32_e64 v35, |v24|, |v8|
	v_max_f32_e64 v36, |v25|, |v9|
	ds_read_b128 v[54:57], v139 offset:16
	ds_read_b128 v[58:61], v139 offset:32
	ds_read_b128 v[62:65], v139 offset:48
	v_fma_f32 v28, v80, v28, v84
	v_fma_f32 v29, v81, v29, v85
	v_mul_f32_e32 v30, v30, v40
	v_mul_f32_e32 v31, v31, v40
	v_max3_f32 v34, v34, v35, v36
	v_max_f32_e64 v35, |v26|, |v10|
	v_max_f32_e64 v36, |v27|, |v11|
	v_mul_f32_e32 v32, v32, v40
	v_mul_f32_e32 v33, v33, v40
	v_fma_f32 v30, v70, v30, v74
	v_fma_f32 v31, v71, v31, v75
	v_max3_f32 v34, v34, v35, v36
	v_max_f32_e64 v35, |v28|, |v12|
	v_max_f32_e64 v36, |v29|, |v13|
	v_fma_f32 v32, v72, v32, v76
	v_fma_f32 v33, v73, v33, v77
	v_max3_f32 v34, v34, v35, v36
	v_max_f32_e64 v35, |v30|, |v14|
	v_max_f32_e64 v36, |v31|, |v15|
	v_max3_f32 v34, v34, v35, v36
	v_max_f32_e64 v35, |v32|, |v16|
	v_max_f32_e64 v36, |v33|, |v17|
	s_waitcnt lgkmcnt(3)
	v_fma_f32 v49, v18, v52, 0
	v_fma_f32 v48, v18, v53, 0
	s_waitcnt lgkmcnt(2)
	v_fma_f32 v47, v18, v54, 0
	v_fma_f32 v46, v18, v55, 0
	v_max3_f32 v34, v34, v35, v36
	s_waitcnt lgkmcnt(1)
	v_fmac_f32_e32 v49, v19, v60
	v_fmac_f32_e32 v48, v19, v61
	s_waitcnt lgkmcnt(0)
	v_fmac_f32_e32 v47, v19, v62
	ds_read_b128 v[52:55], v139 offset:64
	v_fmac_f32_e32 v46, v19, v63
	ds_read_b128 v[60:63], v139 offset:80
	v_bfe_u32 v35, v34, 23, 8
	v_and_b32_e32 v34, 0x7fffff, v34
	v_cmp_gt_u32_e32 vcc, s2, v34
	v_fma_f32 v45, v18, v56, 0
	v_fma_f32 v44, v18, v57, 0
	v_cndmask_b32_e64 v34, -2, -3, vcc
	v_add3_u32 v34, v35, v34, s3
	v_fmac_f32_e32 v45, v19, v64
	v_fmac_f32_e32 v44, v19, v65
	v_max_i32_e32 v34, 0xffffff88, v34
	s_waitcnt lgkmcnt(1)
	v_fmac_f32_e32 v49, v20, v54
	v_fmac_f32_e32 v48, v20, v55
	s_waitcnt lgkmcnt(0)
	v_fmac_f32_e32 v47, v20, v60
	v_fmac_f32_e32 v46, v20, v61
	v_fmac_f32_e32 v45, v20, v62
	v_fmac_f32_e32 v44, v20, v63
	ds_read_b128 v[54:57], v139 offset:96
	ds_read_b128 v[60:63], v139 offset:112
	v_add_u32_e32 v34, 0x7f, v34
	v_fma_f32 v50, v18, v50, 0
	v_fma_f32 v51, v18, v51, 0
	v_lshlrev_b32_e32 v42, 23, v34
	v_mul_lo_u32 v40, v34, s28
	v_cvt_scalef32_2xpk16_fp6_f32 v[34:39], v[18:33], v[2:17], v42
	v_fma_f32 v18, v19, v58, v50
	v_fma_f32 v19, v19, v59, v51
	s_waitcnt lgkmcnt(1)
	v_fmac_f32_e32 v49, v21, v56
	v_fmac_f32_e32 v18, v20, v52
	v_fmac_f32_e32 v19, v20, v53
	v_fma_f32 v84, v21, v54, v18
	v_fma_f32 v85, v21, v55, v19
	v_fmac_f32_e32 v48, v21, v57
	ds_read_b128 v[50:53], v139 offset:9216
	ds_read_b128 v[54:57], v139 offset:9232
	s_waitcnt lgkmcnt(2)
	v_fmac_f32_e32 v47, v21, v60
	v_fmac_f32_e32 v46, v21, v61
	v_fmac_f32_e32 v45, v21, v62
	v_fmac_f32_e32 v44, v21, v63
	s_waitcnt lgkmcnt(1)
	v_fmac_f32_e32 v49, v22, v52
	v_fmac_f32_e32 v48, v22, v53
	s_waitcnt lgkmcnt(0)
	v_fmac_f32_e32 v47, v22, v54
	ds_read_b128 v[18:21], v139 offset:9248
	v_fmac_f32_e32 v46, v22, v55
	ds_read_b128 v[52:55], v139 offset:9264
	v_fmac_f32_e32 v45, v22, v56
	v_fmac_f32_e32 v44, v22, v57
	ds_read_b128 v[56:59], v139 offset:9280
	ds_read_b128 v[60:63], v139 offset:9296
	s_waitcnt lgkmcnt(3)
	v_fmac_f32_e32 v49, v23, v20
	v_fmac_f32_e32 v48, v23, v21
	s_waitcnt lgkmcnt(2)
	v_fmac_f32_e32 v47, v23, v52
	v_fmac_f32_e32 v46, v23, v53
	v_fmac_f32_e32 v45, v23, v54
	v_fmac_f32_e32 v44, v23, v55
	s_waitcnt lgkmcnt(1)
	v_fmac_f32_e32 v49, v24, v58
	v_fmac_f32_e32 v48, v24, v59
	s_waitcnt lgkmcnt(0)
	v_fmac_f32_e32 v47, v24, v60
	ds_read_b128 v[52:55], v139 offset:9312
	v_fmac_f32_e32 v46, v24, v61
	ds_read_b128 v[58:61], v139 offset:9328
	v_fmac_f32_e32 v45, v24, v62
	v_fmac_f32_e32 v44, v24, v63
	ds_read_b128 v[62:65], v139 offset:18432
	ds_read_b128 v[66:69], v139 offset:18448
	s_waitcnt lgkmcnt(3)
	v_fmac_f32_e32 v49, v25, v54
	v_fmac_f32_e32 v48, v25, v55
	s_waitcnt lgkmcnt(2)
	v_fmac_f32_e32 v47, v25, v58
	v_fmac_f32_e32 v46, v25, v59
	v_fmac_f32_e32 v45, v25, v60
	v_fmac_f32_e32 v44, v25, v61
	s_waitcnt lgkmcnt(1)
	v_fmac_f32_e32 v49, v26, v64
	v_fmac_f32_e32 v48, v26, v65
	s_waitcnt lgkmcnt(0)
	v_fmac_f32_e32 v47, v26, v66
	ds_read_b128 v[58:61], v139 offset:18464
	v_fmac_f32_e32 v46, v26, v67
	ds_read_b128 v[64:67], v139 offset:18480
	v_fmac_f32_e32 v45, v26, v68
	v_fmac_f32_e32 v44, v26, v69
	ds_read_b128 v[68:71], v139 offset:18496
	ds_read_b128 v[72:75], v139 offset:18512
	s_waitcnt lgkmcnt(3)
	v_fmac_f32_e32 v49, v27, v60
	v_fmac_f32_e32 v48, v27, v61
	s_waitcnt lgkmcnt(2)
	v_fmac_f32_e32 v47, v27, v64
	v_fmac_f32_e32 v46, v27, v65
	v_fmac_f32_e32 v45, v27, v66
	v_fmac_f32_e32 v44, v27, v67
	s_waitcnt lgkmcnt(1)
	v_fmac_f32_e32 v49, v28, v70
	v_fmac_f32_e32 v48, v28, v71
	s_waitcnt lgkmcnt(0)
	v_fmac_f32_e32 v47, v28, v72
	ds_read_b128 v[64:67], v139 offset:18528
	v_fmac_f32_e32 v46, v28, v73
	ds_read_b128 v[70:73], v139 offset:18544
	v_fmac_f32_e32 v45, v28, v74
	v_fmac_f32_e32 v44, v28, v75
	ds_read_b128 v[74:77], v139 offset:27648
	ds_read_b128 v[78:81], v139 offset:27664
	s_waitcnt lgkmcnt(3)
	v_fmac_f32_e32 v49, v29, v66
	v_fmac_f32_e32 v48, v29, v67
	s_waitcnt lgkmcnt(2)
	v_fmac_f32_e32 v47, v29, v70
	v_fmac_f32_e32 v46, v29, v71
	v_fma_f32 v20, v22, v50, v84
	v_fma_f32 v21, v22, v51, v85
	v_fmac_f32_e32 v45, v29, v72
	v_fmac_f32_e32 v44, v29, v73
	s_waitcnt lgkmcnt(1)
	v_fmac_f32_e32 v49, v30, v76
	v_fmac_f32_e32 v48, v30, v77
	s_waitcnt lgkmcnt(0)
	v_fmac_f32_e32 v47, v30, v78
	ds_read_b128 v[70:73], v139 offset:27680
	v_fmac_f32_e32 v46, v30, v79
	ds_read_b128 v[76:79], v139 offset:27696
	v_fma_f32 v18, v23, v18, v20
	v_fma_f32 v19, v23, v19, v21
	v_fmac_f32_e32 v45, v30, v80
	v_fmac_f32_e32 v18, v24, v56
	v_fmac_f32_e32 v19, v24, v57
	v_fmac_f32_e32 v18, v25, v52
	v_fmac_f32_e32 v19, v25, v53
	v_fmac_f32_e32 v44, v30, v81
	v_fmac_f32_e32 v18, v26, v62
	v_fmac_f32_e32 v19, v26, v63
	v_fmac_f32_e32 v18, v27, v58
	v_fmac_f32_e32 v19, v27, v59
	s_waitcnt lgkmcnt(0)
	v_fmac_f32_e32 v47, v31, v76
	v_fmac_f32_e32 v46, v31, v77
	v_fmac_f32_e32 v45, v31, v78
	v_fmac_f32_e32 v44, v31, v79
	ds_read_b128 v[76:79], v139 offset:27712
	ds_read_b128 v[80:83], v139 offset:27728
	v_fmac_f32_e32 v18, v28, v68
	v_fmac_f32_e32 v19, v28, v69
	v_fmac_f32_e32 v18, v29, v64
	v_fmac_f32_e32 v19, v29, v65
	ds_read_b128 v[22:25], v139 offset:27760
	v_fmac_f32_e32 v18, v30, v74
	v_fmac_f32_e32 v19, v30, v75
	v_fmac_f32_e32 v18, v31, v70
	v_fmac_f32_e32 v19, v31, v71
	v_fmac_f32_e32 v49, v31, v72
	s_waitcnt lgkmcnt(2)
	v_fma_f32 v74, v32, v76, v18
	v_fma_f32 v75, v32, v77, v19
	ds_read_b128 v[18:21], v139 offset:27744
	v_fmac_f32_e32 v48, v31, v73
	v_fmac_f32_e32 v49, v32, v78
	v_fmac_f32_e32 v48, v32, v79
	s_waitcnt lgkmcnt(2)
	v_fmac_f32_e32 v47, v32, v80
	v_fmac_f32_e32 v46, v32, v81
	ds_read_b128 v[26:29], v139 offset:36864
	s_waitcnt lgkmcnt(1)
	v_fmac_f32_e32 v49, v33, v20
	v_fmac_f32_e32 v48, v33, v21
	v_fmac_f32_e32 v47, v33, v22
	v_fmac_f32_e32 v46, v33, v23
	ds_read_b128 v[20:23], v139 offset:36880
	v_fmac_f32_e32 v45, v32, v82
	v_fmac_f32_e32 v44, v32, v83
	v_fmac_f32_e32 v45, v33, v24
	v_fmac_f32_e32 v44, v33, v25
	s_waitcnt lgkmcnt(1)
	v_fmac_f32_e32 v49, v2, v28
	v_fmac_f32_e32 v48, v2, v29
	ds_read_b128 v[28:31], v139 offset:36896
	ds_read_b128 v[50:53], v139 offset:36912
	s_waitcnt lgkmcnt(2)
	v_fmac_f32_e32 v47, v2, v20
	v_fmac_f32_e32 v46, v2, v21
	v_fmac_f32_e32 v45, v2, v22
	v_fmac_f32_e32 v44, v2, v23
	ds_read_b128 v[20:23], v139 offset:36928
	ds_read_b128 v[54:57], v139 offset:36944
	s_waitcnt lgkmcnt(3)
	v_fmac_f32_e32 v49, v3, v30
	v_fmac_f32_e32 v48, v3, v31
	s_waitcnt lgkmcnt(2)
	v_fmac_f32_e32 v47, v3, v50
	v_fmac_f32_e32 v46, v3, v51
	v_fmac_f32_e32 v45, v3, v52
	v_fmac_f32_e32 v44, v3, v53
	s_waitcnt lgkmcnt(1)
	v_fmac_f32_e32 v49, v4, v22
	v_fmac_f32_e32 v48, v4, v23
	ds_read_b128 v[22:25], v139 offset:36960
	ds_read_b128 v[50:53], v139 offset:36976
	s_waitcnt lgkmcnt(2)
	v_fmac_f32_e32 v47, v4, v54
	v_fmac_f32_e32 v46, v4, v55
	v_fmac_f32_e32 v45, v4, v56
	v_fmac_f32_e32 v44, v4, v57
	ds_read_b128 v[54:57], v139 offset:46080
	ds_read_b128 v[58:61], v139 offset:46096
	s_waitcnt lgkmcnt(3)
	v_fmac_f32_e32 v49, v5, v24
	v_fmac_f32_e32 v48, v5, v25
	s_waitcnt lgkmcnt(2)
	v_fmac_f32_e32 v47, v5, v50
	v_fmac_f32_e32 v46, v5, v51
	v_fmac_f32_e32 v45, v5, v52
	v_fmac_f32_e32 v44, v5, v53
	s_waitcnt lgkmcnt(1)
	v_fmac_f32_e32 v49, v6, v56
	v_fmac_f32_e32 v48, v6, v57
	s_waitcnt lgkmcnt(0)
	v_fmac_f32_e32 v47, v6, v58
	ds_read_b128 v[50:53], v139 offset:46112
	v_fmac_f32_e32 v46, v6, v59
	ds_read_b128 v[56:59], v139 offset:46128
	v_fmac_f32_e32 v45, v6, v60
	v_fmac_f32_e32 v44, v6, v61
	ds_read_b128 v[60:63], v139 offset:46144
	ds_read_b128 v[64:67], v139 offset:46160
	s_waitcnt lgkmcnt(3)
	v_fmac_f32_e32 v49, v7, v52
	v_fmac_f32_e32 v48, v7, v53
	s_waitcnt lgkmcnt(2)
	v_fmac_f32_e32 v47, v7, v56
	v_fmac_f32_e32 v46, v7, v57
	v_fmac_f32_e32 v45, v7, v58
	v_fmac_f32_e32 v44, v7, v59
	s_waitcnt lgkmcnt(1)
	v_fmac_f32_e32 v49, v8, v62
	v_fmac_f32_e32 v48, v8, v63
	s_waitcnt lgkmcnt(0)
	v_fmac_f32_e32 v47, v8, v64
	ds_read_b128 v[56:59], v139 offset:46176
	v_fmac_f32_e32 v46, v8, v65
	ds_read_b128 v[62:65], v139 offset:46192
	v_fma_f32 v18, v33, v18, v74
	v_fma_f32 v19, v33, v19, v75
	v_fmac_f32_e32 v45, v8, v66
	v_fmac_f32_e32 v44, v8, v67
	ds_read_b128 v[66:69], v139 offset:55296
	ds_read_b128 v[70:73], v139 offset:55312
	v_fmac_f32_e32 v18, v2, v26
	v_fmac_f32_e32 v19, v2, v27
	v_fma_f32 v2, v3, v28, v18
	v_fma_f32 v3, v3, v29, v19
	s_waitcnt lgkmcnt(3)
	v_fmac_f32_e32 v49, v9, v58
	v_fmac_f32_e32 v2, v4, v20
	v_fmac_f32_e32 v3, v4, v21
	v_fmac_f32_e32 v2, v5, v22
	v_fmac_f32_e32 v3, v5, v23
	v_fmac_f32_e32 v48, v9, v59
	s_waitcnt lgkmcnt(2)
	v_fmac_f32_e32 v47, v9, v62
	v_fmac_f32_e32 v46, v9, v63
	v_fmac_f32_e32 v2, v6, v54
	v_fmac_f32_e32 v3, v6, v55
	v_fmac_f32_e32 v45, v9, v64
	v_fmac_f32_e32 v44, v9, v65
	s_waitcnt lgkmcnt(1)
	v_fmac_f32_e32 v49, v10, v68
	v_fmac_f32_e32 v48, v10, v69
	s_waitcnt lgkmcnt(0)
	v_fmac_f32_e32 v47, v10, v70
	v_fmac_f32_e32 v46, v10, v71
	ds_read_b128 v[62:65], v139 offset:55328
	ds_read_b128 v[68:71], v139 offset:55344
	v_fmac_f32_e32 v2, v7, v50
	v_fmac_f32_e32 v3, v7, v51
	ds_read_b128 v[18:21], v139 offset:55392
	v_fmac_f32_e32 v2, v8, v60
	v_fmac_f32_e32 v3, v8, v61
	v_fmac_f32_e32 v2, v9, v56
	v_fmac_f32_e32 v3, v9, v57
	ds_read_b128 v[6:9], v139 offset:55376
	v_fmac_f32_e32 v2, v10, v66
	v_fmac_f32_e32 v3, v10, v67
	s_waitcnt lgkmcnt(3)
	v_fma_f32 v32, v11, v62, v2
	v_fma_f32 v33, v11, v63, v3
	ds_read_b128 v[2:5], v139 offset:55360
	v_fmac_f32_e32 v49, v11, v64
	v_fmac_f32_e32 v48, v11, v65
	s_waitcnt lgkmcnt(3)
	v_fmac_f32_e32 v47, v11, v68
	v_fmac_f32_e32 v46, v11, v69
	s_waitcnt lgkmcnt(0)
	v_fmac_f32_e32 v49, v12, v4
	v_fmac_f32_e32 v48, v12, v5
	v_fmac_f32_e32 v47, v12, v6
	v_fmac_f32_e32 v46, v12, v7
	ds_read_b128 v[4:7], v139 offset:55408
	v_fmac_f32_e32 v45, v10, v72
	v_fmac_f32_e32 v44, v10, v73
	v_fmac_f32_e32 v45, v11, v70
	v_fmac_f32_e32 v44, v11, v71
	v_fmac_f32_e32 v45, v12, v8
	v_fmac_f32_e32 v44, v12, v9
	v_fmac_f32_e32 v49, v13, v20
	v_fmac_f32_e32 v48, v13, v21
	ds_read_b128 v[8:11], v139 offset:64512
	ds_read_b128 v[20:23], v139 offset:64528
	s_waitcnt lgkmcnt(2)
	v_fmac_f32_e32 v47, v13, v4
	v_fmac_f32_e32 v46, v13, v5
	v_fmac_f32_e32 v45, v13, v6
	v_fmac_f32_e32 v44, v13, v7
	ds_read_b128 v[4:7], v139 offset:64544
	ds_read_b128 v[24:27], v139 offset:64560
	v_fma_f32 v2, v12, v2, v32
	v_fma_f32 v3, v12, v3, v33
	s_waitcnt lgkmcnt(2)
	v_fmac_f32_e32 v47, v14, v20
	v_fmac_f32_e32 v46, v14, v21
	v_fmac_f32_e32 v45, v14, v22
	v_fmac_f32_e32 v44, v14, v23
	ds_read_b128 v[20:23], v139 offset:64576
	ds_read_b128 v[28:31], v139 offset:64592
	ds_read_b128 v[50:53], v139 offset:64608
	ds_read_b128 v[54:57], v139 offset:64624
	v_fmac_f32_e32 v2, v13, v18
	v_fmac_f32_e32 v3, v13, v19
	v_fmac_f32_e32 v49, v14, v10
	v_fmac_f32_e32 v2, v14, v8
	v_fmac_f32_e32 v3, v14, v9
	s_waitcnt lgkmcnt(5)
	v_fmac_f32_e32 v2, v15, v4
	v_fmac_f32_e32 v3, v15, v5
	v_fmac_f32_e32 v49, v15, v6
	s_waitcnt lgkmcnt(3)
	v_fmac_f32_e32 v2, v16, v20
	v_fmac_f32_e32 v3, v16, v21
	s_waitcnt lgkmcnt(1)
	v_fmac_f32_e32 v2, v17, v50
	v_fmac_f32_e32 v3, v17, v51
	ds_bpermute_b32 v4, v103, v2
	ds_bpermute_b32 v5, v103, v3
	v_fmac_f32_e32 v49, v16, v22
	v_fmac_f32_e32 v49, v17, v52
	ds_bpermute_b32 v6, v103, v49
	v_fmac_f32_e32 v48, v14, v11
	s_waitcnt lgkmcnt(1)
	v_add_f32_e32 v2, v2, v4
	v_add_f32_e32 v3, v3, v5
	ds_bpermute_b32 v4, v134, v2
	ds_bpermute_b32 v5, v134, v3
	s_waitcnt lgkmcnt(2)
	v_add_f32_e32 v6, v49, v6
	v_fmac_f32_e32 v48, v15, v7
	ds_bpermute_b32 v7, v134, v6
	v_fmac_f32_e32 v47, v15, v24
	s_waitcnt lgkmcnt(1)
	v_add_f32_e32 v2, v2, v4
	v_add_f32_e32 v3, v3, v5
	ds_bpermute_b32 v4, v135, v2
	ds_bpermute_b32 v5, v135, v3
	v_fmac_f32_e32 v48, v16, v23
	v_fmac_f32_e32 v47, v16, v28
	v_fmac_f32_e32 v48, v17, v53
	v_fmac_f32_e32 v47, v17, v54
	s_waitcnt lgkmcnt(0)
	v_add_f32_e32 v2, v2, v4
	v_add_f32_e32 v3, v3, v5
	ds_bpermute_b32 v4, v136, v2
	ds_bpermute_b32 v5, v136, v3
	v_add_f32_e32 v6, v6, v7
	ds_bpermute_b32 v8, v103, v48
	ds_bpermute_b32 v7, v135, v6
	ds_bpermute_b32 v9, v103, v47
	s_waitcnt lgkmcnt(3)
	v_add_f32_e32 v2, v2, v4
	v_add_f32_e32 v3, v3, v5
	ds_bpermute_b32 v4, v137, v2
	ds_bpermute_b32 v5, v137, v3
	s_waitcnt lgkmcnt(3)
	v_add_f32_e32 v6, v6, v7
	s_waitcnt lgkmcnt(2)
	v_add_f32_e32 v7, v47, v9
	ds_bpermute_b32 v9, v136, v6
	v_fmac_f32_e32 v46, v15, v25
	s_waitcnt lgkmcnt(1)
	v_add_f32_e32 v2, v2, v4
	v_add_f32_e32 v3, v3, v5
	v_add_f32_e32 v4, v48, v8
	ds_bpermute_b32 v5, v134, v4
	ds_bpermute_b32 v8, v134, v7
	s_waitcnt lgkmcnt(2)
	v_add_f32_e32 v6, v6, v9
	ds_bpermute_b32 v11, v137, v6
	v_fmac_f32_e32 v45, v15, v26
	s_waitcnt lgkmcnt(2)
	v_add_f32_e32 v5, v4, v5
	s_waitcnt lgkmcnt(1)
	v_add_f32_e32 v7, v7, v8
	ds_bpermute_b32 v10, v135, v5
	ds_bpermute_b32 v8, v135, v7
	s_waitcnt lgkmcnt(2)
	v_add_f32_e32 v6, v6, v11
	v_fmac_f32_e32 v44, v15, v27
	v_fmac_f32_e32 v46, v16, v29
	s_waitcnt lgkmcnt(1)
	v_add_f32_e32 v9, v5, v10
	s_waitcnt lgkmcnt(0)
	v_add_f32_e32 v7, v7, v8
	ds_bpermute_b32 v10, v136, v9
	ds_bpermute_b32 v8, v136, v7
	v_fmac_f32_e32 v45, v16, v30
	v_fmac_f32_e32 v44, v16, v31
	v_fmac_f32_e32 v46, v17, v55
	s_waitcnt lgkmcnt(1)
	v_add_f32_e32 v9, v9, v10
	s_waitcnt lgkmcnt(0)
	v_add_f32_e32 v11, v7, v8
	ds_bpermute_b32 v10, v137, v9
	ds_bpermute_b32 v12, v137, v11
	v_fmac_f32_e32 v45, v17, v56
	v_fmac_f32_e32 v44, v17, v57
	ds_bpermute_b32 v13, v103, v46
	s_waitcnt lgkmcnt(2)
	v_add_f32_e32 v8, v9, v10
	s_waitcnt lgkmcnt(1)
	v_add_f32_e32 v10, v11, v12
	ds_bpermute_b32 v12, v103, v45
	ds_bpermute_b32 v14, v103, v44
	s_waitcnt lgkmcnt(2)
	v_add_f32_e32 v13, v46, v13
	ds_bpermute_b32 v15, v134, v13
	ds_bpermute_b32 v4, v138, v2
	s_waitcnt lgkmcnt(3)
	v_add_f32_e32 v12, v45, v12
	s_waitcnt lgkmcnt(2)
	v_add_f32_e32 v14, v44, v14
	ds_bpermute_b32 v16, v134, v12
	ds_bpermute_b32 v17, v134, v14
	s_waitcnt lgkmcnt(3)
	v_add_f32_e32 v13, v13, v15
	ds_bpermute_b32 v15, v135, v13
	ds_bpermute_b32 v5, v138, v3
	s_waitcnt lgkmcnt(3)
	v_add_f32_e32 v12, v12, v16
	s_waitcnt lgkmcnt(2)
	v_add_f32_e32 v14, v14, v17
	ds_bpermute_b32 v16, v135, v12
	ds_bpermute_b32 v17, v135, v14
	s_waitcnt lgkmcnt(3)
	v_add_f32_e32 v13, v13, v15
	ds_bpermute_b32 v15, v136, v13
	ds_bpermute_b32 v7, v138, v6
	s_waitcnt lgkmcnt(3)
	v_add_f32_e32 v12, v12, v16
	s_waitcnt lgkmcnt(2)
	v_add_f32_e32 v14, v14, v17
	ds_bpermute_b32 v16, v136, v12
	ds_bpermute_b32 v17, v136, v14
	s_waitcnt lgkmcnt(3)
	v_add_f32_e32 v13, v13, v15
	ds_bpermute_b32 v15, v137, v13
	ds_bpermute_b32 v9, v138, v8
	s_waitcnt lgkmcnt(3)
	v_add_f32_e32 v16, v12, v16
	s_waitcnt lgkmcnt(2)
	v_add_f32_e32 v17, v14, v17
	ds_bpermute_b32 v18, v137, v16
	ds_bpermute_b32 v19, v137, v17
	s_waitcnt lgkmcnt(3)
	v_add_f32_e32 v12, v13, v15
	ds_bpermute_b32 v11, v138, v10
	ds_bpermute_b32 v13, v138, v12
	s_waitcnt lgkmcnt(3)
	v_add_f32_e32 v14, v16, v18
	s_waitcnt lgkmcnt(2)
	v_add_f32_e32 v16, v17, v19
	ds_bpermute_b32 v15, v138, v14
	ds_bpermute_b32 v17, v138, v16
	v_lshl_add_u64 v[42:43], s[72:73], 0, v[130:131]
	v_add_co_u32_e32 v42, vcc, s29, v42
	s_nop 1
	v_addc_co_u32_e32 v43, vcc, 0, v43, vcc
	global_store_dwordx4 v[42:43], v[34:37], off
	global_store_dwordx4 v[42:43], v[38:41], off offset:64
	s_and_saveexec_b64 s[50:51], s[8:9]
	s_cbranch_execz .LBB0_1961
	v_add_f32_e32 v2, v2, v4
	v_add_f32_e32 v3, v3, v5
	v_add_f32_e32 v6, v6, v7
	v_cmp_gt_f32_e32 vcc, v3, v2
	v_add_f32_e32 v8, v8, v9
	s_waitcnt lgkmcnt(3)
	v_add_f32_e32 v10, v10, v11
	v_cndmask_b32_e32 v4, v2, v3, vcc
	v_cmp_gt_f32_e64 s[10:11], v6, v4
	s_waitcnt lgkmcnt(2)
	v_add_f32_e32 v12, v12, v13
	s_waitcnt lgkmcnt(1)
	v_add_f32_e32 v14, v14, v15
	v_cndmask_b32_e64 v4, v4, v6, s[10:11]
	v_cmp_gt_f32_e64 s[12:13], v8, v4
	s_waitcnt lgkmcnt(0)
	v_add_f32_e32 v16, v16, v17
	v_cmp_nlt_f32_e64 s[24:25], s33, v2
	v_cndmask_b32_e64 v4, v4, v8, s[12:13]
	v_cmp_gt_f32_e64 s[14:15], v10, v4
	s_nop 1
	v_cndmask_b32_e64 v4, v4, v10, s[14:15]
	v_cmp_gt_f32_e64 s[16:17], v12, v4
	s_nop 1
	v_cndmask_b32_e64 v4, v4, v12, s[16:17]
	v_cmp_gt_f32_e64 s[18:19], v14, v4
	s_nop 1
	v_cndmask_b32_e64 v5, v4, v14, s[18:19]
	v_cndmask_b32_e64 v4, 0, 1, vcc
	v_cndmask_b32_e64 v4, v4, 2, s[10:11]
	v_cndmask_b32_e64 v4, v4, 3, s[12:13]
	v_cndmask_b32_e64 v4, v4, 4, s[14:15]
	v_cndmask_b32_e64 v4, v4, 5, s[16:17]
	v_cndmask_b32_e64 v4, v4, 6, s[18:19]
	v_cmp_ngt_f32_e32 vcc, v16, v5
	s_nop 1
	v_cndmask_b32_e32 v4, 7, v4, vcc
	v_cmp_eq_u32_e64 s[22:23], 0, v4
	s_or_b64 s[22:23], s[24:25], s[22:23]
	v_cmp_ne_u32_e64 s[20:21], 1, v4
	v_cndmask_b32_e64 v2, v2, v142, s[22:23]
	v_cmp_gt_f32_e64 s[24:25], v3, v2
	s_and_b64 s[20:21], s[20:21], s[24:25]
	v_cndmask_b32_e64 v2, v2, v3, s[20:21]
	v_cmp_ne_u32_e64 s[18:19], 2, v4
	v_cmp_gt_f32_e64 s[24:25], v6, v2
	s_and_b64 s[18:19], s[18:19], s[24:25]
	v_cndmask_b32_e64 v2, v2, v6, s[18:19]
	v_cmp_ne_u32_e64 s[16:17], 3, v4
	v_cmp_gt_f32_e64 s[24:25], v8, v2
	s_and_b64 s[16:17], s[16:17], s[24:25]
	v_cndmask_b32_e64 v2, v2, v8, s[16:17]
	v_cmp_ne_u32_e64 s[14:15], 4, v4
	v_cmp_gt_f32_e64 s[24:25], v10, v2
	s_and_b64 s[14:15], s[14:15], s[24:25]
	v_cndmask_b32_e64 v2, v2, v10, s[14:15]
	v_cmp_ne_u32_e64 s[12:13], 5, v4
	v_cmp_gt_f32_e64 s[24:25], v12, v2
	s_and_b64 s[12:13], s[12:13], s[24:25]
	v_cndmask_b32_e64 v2, v2, v12, s[12:13]
	v_cmp_ne_u32_e64 s[10:11], 6, v4
	v_cmp_gt_f32_e64 s[24:25], v14, v2
	s_and_b64 s[10:11], s[10:11], s[24:25]
	v_cndmask_b32_e64 v2, v2, v14, s[10:11]
	v_cmp_gt_f32_e64 s[24:25], v16, v2
	s_and_b64 s[24:25], vcc, s[24:25]
	v_cndmask_b32_e32 v3, v16, v5, vcc
	v_cndmask_b32_e64 v2, v2, v16, s[24:25]
	v_sub_f32_e32 v2, v2, v3
	v_mul_f32_e32 v2, 0x3fb8aa3b, v2
	v_exp_f32_e32 v2, v2
	v_cndmask_b32_e64 v3, 0, -1, s[22:23]
	v_cndmask_b32_e64 v3, v3, 1, s[20:21]
	v_cndmask_b32_e64 v3, v3, 2, s[18:19]
	v_add_f32_e32 v6, 1.0, v2
	v_div_scale_f32 v7, s[4:5], v6, v6, v2
	v_cndmask_b32_e64 v3, v3, 3, s[16:17]
	v_rcp_f32_e32 v8, v7
	v_cndmask_b32_e64 v3, v3, 4, s[14:15]
	v_cndmask_b32_e64 v3, v3, 5, s[12:13]
	v_cndmask_b32_e64 v3, v3, 6, s[10:11]
	v_cndmask_b32_e64 v5, v3, 7, s[24:25]
	v_fma_f32 v3, -v7, v8, 1.0
	v_fmac_f32_e32 v8, v3, v8
	v_div_scale_f32 v3, vcc, v2, v6, v2
	v_mul_f32_e32 v9, v3, v8
	v_fma_f32 v10, -v7, v9, v3
	v_fmac_f32_e32 v9, v10, v8
	v_fma_f32 v3, -v7, v9, v3
	v_div_scale_f32 v7, s[4:5], v6, v6, 1.0
	v_rcp_f32_e32 v10, v7
	v_div_fmas_f32 v3, v3, v8, v9
	v_div_fixup_f32 v11, v3, v6, v2
	v_fma_f32 v2, -v7, v10, 1.0
	v_fmac_f32_e32 v10, v2, v10
	v_div_scale_f32 v2, vcc, 1.0, v6, 1.0
	v_mul_f32_e32 v3, v2, v10
	v_fma_f32 v8, -v7, v3, v2
	v_fmac_f32_e32 v3, v8, v10
	v_fma_f32 v2, -v7, v3, v2
	v_div_fmas_f32 v2, v2, v10, v3
	v_div_fixup_f32 v10, v2, v6, 1.0
	v_lshlrev_b64 v[2:3], 2, v[126:127]
	v_add_u32_e32 v8, 1, v126
	v_lshl_add_u64 v[6:7], s[36:37], 0, v[2:3]
	v_ashrrev_i32_e32 v9, 31, v8
	v_lshl_add_u64 v[2:3], s[38:39], 0, v[2:3]
	global_store_dword v[2:3], v10, off
	v_lshl_add_u64 v[2:3], v[8:9], 2, s[38:39]
	global_store_dwordx2 v[6:7], v[4:5], off
	global_store_dword v[2:3], v11, off
	v_lshl_add_u32 v2, v4, 2, s40
	ds_add_u32 v2, v141
	v_lshl_add_u32 v2, v5, 2, s40
	ds_add_u32 v2, v141
	s_branch .LBB0_1961

.LBB0_2372:
	s_or_b64 exec, exec, s[16:17]
	v_sub_f32_e32 v21, v21, v232
	v_sub_f32_e32 v20, v20, v232
	v_sub_f32_e32 v23, v23, v232
	v_sub_f32_e32 v22, v22, v232
	v_sub_f32_e32 v11, v11, v232
	v_sub_f32_e32 v10, v10, v232
	v_mul_f32_e32 v22, v150, v22
	v_mul_f32_e32 v23, v150, v23
	v_mul_f32_e32 v20, v150, v20
	v_mul_f32_e32 v21, v150, v21
	v_sub_f32_e32 v9, v9, v232
	v_sub_f32_e32 v8, v8, v232
	v_mul_f32_e32 v10, v150, v10
	v_mul_f32_e32 v11, v150, v11
	v_fmac_f32_e32 v16, v12, v20
	v_fmac_f32_e32 v17, v13, v21
	v_fma_f32 v12, v14, v22, v18
	v_fma_f32 v13, v15, v23, v19
	v_mul_f32_e32 v14, v148, v172
	v_mul_f32_e32 v15, v148, v173
	v_mul_f32_e32 v18, v148, v170
	v_mul_f32_e32 v19, v148, v171
	v_mul_f32_e32 v8, v150, v8
	v_mul_f32_e32 v9, v150, v9
	v_fma_f32 v2, v2, v10, v6
	v_fma_f32 v3, v3, v11, v7
	v_mul_f32_e32 v6, v148, v158
	v_mul_f32_e32 v7, v148, v159
	v_sub_f32_e32 v33, v33, v232
	v_sub_f32_e32 v32, v32, v232
	v_sub_f32_e32 v35, v35, v232
	v_sub_f32_e32 v34, v34, v232
	v_fmac_f32_e32 v18, v152, v164
	v_fmac_f32_e32 v19, v152, v165
	v_fmac_f32_e32 v14, v152, v166
	v_fmac_f32_e32 v15, v152, v167
	v_fma_f32 v0, v0, v8, v4
	v_fma_f32 v1, v1, v9, v5
	v_mul_f32_e32 v4, v148, v160
	v_mul_f32_e32 v5, v148, v161
	v_fmac_f32_e32 v6, v152, v154
	v_fmac_f32_e32 v7, v152, v155
	v_mul_f32_e32 v34, v150, v34
	v_mul_f32_e32 v35, v150, v35
	v_mul_f32_e32 v32, v150, v32
	v_mul_f32_e32 v33, v150, v33
	v_fma_f32 v12, v12, s14, v14
	v_fma_f32 v13, v13, s14, v15
	v_fma_f32 v14, v16, s14, v18
	v_fma_f32 v15, v17, s14, v19
	v_fmac_f32_e32 v4, v152, v156
	v_fmac_f32_e32 v5, v152, v157
	v_fmac_f32_e32 v6, s14, v0
	v_fmac_f32_e32 v7, s14, v1
	v_fmac_f32_e32 v28, v24, v32
	v_fmac_f32_e32 v29, v25, v33
	v_fma_f32 v24, v26, v34, v30
	v_fma_f32 v25, v27, v35, v31
	v_mul_f32_e32 v26, v148, v184
	v_mul_f32_e32 v27, v148, v185
	v_mul_f32_e32 v30, v148, v182
	v_mul_f32_e32 v31, v148, v183
	v_fmac_f32_e32 v4, s14, v2
	v_fmac_f32_e32 v5, s14, v3
	v_mov_b32_e32 v8, v6
	v_mov_b32_e32 v9, v14
	v_mov_b32_e32 v10, v7
	v_mov_b32_e32 v11, v15
	v_sub_f32_e32 v57, v57, v232
	v_sub_f32_e32 v56, v56, v232
	v_sub_f32_e32 v59, v59, v232
	v_sub_f32_e32 v58, v58, v232
	v_sub_f32_e32 v45, v45, v232
	v_sub_f32_e32 v44, v44, v232
	v_sub_f32_e32 v47, v47, v232
	v_sub_f32_e32 v46, v46, v232
	v_fmac_f32_e32 v30, v152, v178
	v_fmac_f32_e32 v31, v152, v179
	v_fmac_f32_e32 v26, v152, v180
	v_fmac_f32_e32 v27, v152, v181
	v_add_f32_e32 v8, v8, v10
	v_add_f32_e32 v9, v9, v11
	v_mov_b32_e32 v10, v4
	v_mov_b32_e32 v11, v12
	v_mov_b32_e32 v16, v5
	v_mov_b32_e32 v17, v13
	v_mul_f32_e32 v58, v150, v58
	v_mul_f32_e32 v59, v150, v59
	v_mul_f32_e32 v56, v150, v56
	v_mul_f32_e32 v57, v150, v57
	v_mul_f32_e32 v46, v150, v46
	v_mul_f32_e32 v47, v150, v47
	v_mul_f32_e32 v44, v150, v44
	v_mul_f32_e32 v45, v150, v45
	v_fma_f32 v24, v24, s14, v26
	v_fma_f32 v25, v25, s14, v27
	v_fma_f32 v26, v28, s14, v30
	v_fma_f32 v27, v29, s14, v31
	v_add_f32_e32 v10, v10, v16
	v_add_f32_e32 v11, v11, v17
	v_sub_f32_e32 v81, v81, v232
	v_sub_f32_e32 v80, v80, v232
	v_sub_f32_e32 v83, v83, v232
	v_sub_f32_e32 v82, v82, v232
	v_sub_f32_e32 v69, v69, v232
	v_sub_f32_e32 v68, v68, v232
	v_sub_f32_e32 v71, v71, v232
	v_sub_f32_e32 v70, v70, v232
	v_fmac_f32_e32 v52, v48, v56
	v_fmac_f32_e32 v53, v49, v57
	v_fma_f32 v48, v50, v58, v54
	v_fma_f32 v49, v51, v59, v55
	v_mul_f32_e32 v50, v148, v200
	v_mul_f32_e32 v51, v148, v201
	v_mul_f32_e32 v54, v148, v198
	v_mul_f32_e32 v55, v148, v199
	v_fmac_f32_e32 v40, v36, v44
	v_fmac_f32_e32 v41, v37, v45
	v_fma_f32 v36, v38, v46, v42
	v_fma_f32 v37, v39, v47, v43
	v_mul_f32_e32 v38, v148, v192
	v_mul_f32_e32 v39, v148, v193
	v_mul_f32_e32 v42, v148, v190
	v_mul_f32_e32 v43, v148, v191
	v_add_f32_e32 v8, v8, v10
	v_add_f32_e32 v9, v9, v11
	v_pk_mov_b32 v[10:11], v[26:27], v[24:25] op_sel:[1,0]
	v_mov_b32_e32 v16, v26
	v_mov_b32_e32 v17, v25
	v_mul_f32_e32 v82, v150, v82
	v_mul_f32_e32 v83, v150, v83
	v_mul_f32_e32 v80, v150, v80
	v_mul_f32_e32 v81, v150, v81
	v_mul_f32_e32 v70, v150, v70
	v_mul_f32_e32 v71, v150, v71
	v_mul_f32_e32 v68, v150, v68
	v_mul_f32_e32 v69, v150, v69
	v_fmac_f32_e32 v54, v152, v194
	v_fmac_f32_e32 v55, v152, v195
	v_fmac_f32_e32 v50, v152, v196
	v_fmac_f32_e32 v51, v152, v197
	v_fmac_f32_e32 v42, v152, v186
	v_fmac_f32_e32 v43, v152, v187
	v_fmac_f32_e32 v38, v152, v188
	v_fmac_f32_e32 v39, v152, v189
	v_add_f32_e32 v10, v10, v16
	v_add_f32_e32 v11, v11, v17
	v_fmac_f32_e32 v76, v72, v80
	v_fmac_f32_e32 v77, v73, v81
	v_fma_f32 v72, v74, v82, v78
	v_fma_f32 v73, v75, v83, v79
	v_mul_f32_e32 v74, v148, v216
	v_mul_f32_e32 v75, v148, v217
	v_mul_f32_e32 v78, v148, v214
	v_mul_f32_e32 v79, v148, v215
	v_fmac_f32_e32 v64, v60, v68
	v_fmac_f32_e32 v65, v61, v69
	v_fma_f32 v60, v62, v70, v66
	v_fma_f32 v61, v63, v71, v67
	v_mul_f32_e32 v62, v148, v208
	v_mul_f32_e32 v63, v148, v209
	v_mul_f32_e32 v66, v148, v206
	v_mul_f32_e32 v67, v148, v207
	v_fma_f32 v48, v48, s14, v50
	v_fma_f32 v49, v49, s14, v51
	v_fma_f32 v50, v52, s14, v54
	v_fma_f32 v51, v53, s14, v55
	v_fma_f32 v36, v36, s14, v38
	v_fma_f32 v37, v37, s14, v39
	v_fma_f32 v38, v40, s14, v42
	v_fma_f32 v39, v41, s14, v43
	v_add_f32_e32 v8, 0, v8
	v_pk_add_f32 v[10:11], v[10:11], v[10:11] op_sel:[0,1] op_sel_hi:[1,0]
	v_fmac_f32_e32 v78, v152, v210
	v_fmac_f32_e32 v79, v152, v211
	v_fmac_f32_e32 v74, v152, v212
	v_fmac_f32_e32 v75, v152, v213
	v_fmac_f32_e32 v66, v152, v202
	v_fmac_f32_e32 v67, v152, v203
	v_fmac_f32_e32 v62, v152, v204
	v_fmac_f32_e32 v63, v152, v205
	v_add_f32_e32 v8, v8, v9
	v_add_f32_e32 v16, v38, v39
	v_add_f32_e32 v18, v36, v37
	v_mov_b32_e32 v9, v50
	v_mov_b32_e32 v11, v51
	v_mov_b32_e32 v17, v48
	v_mov_b32_e32 v19, v49
	v_fma_f32 v72, v72, s14, v74
	v_fma_f32 v73, v73, s14, v75
	v_fma_f32 v74, v76, s14, v78
	v_fma_f32 v75, v77, s14, v79
	s_waitcnt vmcnt(0)
	v_sub_f32_e32 v77, v93, v232
	v_sub_f32_e32 v76, v92, v232
	v_sub_f32_e32 v79, v95, v232
	v_sub_f32_e32 v78, v94, v232
	v_fma_f32 v60, v60, s14, v62
	v_fma_f32 v61, v61, s14, v63
	v_fma_f32 v62, v64, s14, v66
	v_fma_f32 v63, v65, s14, v67
	v_add_f32_e32 v8, v8, v10
	v_add_f32_e32 v9, v9, v11
	v_add_f32_e32 v10, v16, v18
	v_add_f32_e32 v11, v17, v19
	v_mul_f32_e32 v78, v150, v78
	v_mul_f32_e32 v79, v150, v79
	v_mul_f32_e32 v76, v150, v76
	v_mul_f32_e32 v77, v150, v77
	v_mul_f32_e32 v0, v148, v224
	v_mul_f32_e32 v1, v148, v225
	v_mul_f32_e32 v2, v148, v222
	v_mul_f32_e32 v3, v148, v223
	v_add_f32_e32 v8, v8, v10
	v_add_f32_e32 v9, v9, v11
	v_pk_mov_b32 v[10:11], v[62:63], v[60:61] op_sel:[1,0]
	v_mov_b32_e32 v16, v62
	v_mov_b32_e32 v17, v61
	v_fma_f32 v76, v84, v76, v88
	v_fma_f32 v77, v85, v77, v89
	v_fma_f32 v78, v86, v78, v90
	v_fma_f32 v79, v87, v79, v91
	v_fmac_f32_e32 v2, v152, v218
	v_fmac_f32_e32 v3, v152, v219
	v_fmac_f32_e32 v0, v152, v220
	v_fmac_f32_e32 v1, v152, v221
	v_add_f32_e32 v10, v10, v16
	v_add_f32_e32 v11, v11, v17
	v_fmac_f32_e32 v0, s14, v78
	v_fmac_f32_e32 v1, s14, v79
	v_fmac_f32_e32 v2, s14, v76
	v_fmac_f32_e32 v3, s14, v77
	v_pk_add_f32 v[8:9], v[8:9], v[8:9] op_sel:[0,1] op_sel_hi:[1,0]
	v_pk_add_f32 v[10:11], v[10:11], v[10:11] op_sel:[0,1] op_sel_hi:[1,0]
	v_add_f32_e32 v16, v74, v75
	v_add_f32_e32 v18, v72, v73
	v_mov_b32_e32 v9, v2
	v_mov_b32_e32 v11, v3
	v_mov_b32_e32 v17, v0
	v_mov_b32_e32 v19, v1
	v_add_f32_e32 v8, v8, v10
	v_add_f32_e32 v9, v9, v11
	v_add_f32_e32 v10, v16, v18
	v_add_f32_e32 v11, v17, v19
	v_lshlrev_b64 v[154:155], 11, v[96:97]
	v_add_f32_e32 v8, v8, v10
	v_add_f32_e32 v9, v9, v11
	v_add_u32_e32 v96, s22, v96
	v_add_f32_e32 v8, v8, v9
	ds_bpermute_b32 v9, v149, v8
	s_waitcnt lgkmcnt(0)
	v_add_f32_e32 v8, v8, v9
	ds_bpermute_b32 v9, v151, v8
	s_waitcnt lgkmcnt(0)
	v_add_f32_e32 v8, v8, v9
	ds_bpermute_b32 v9, v153, v8
	s_waitcnt lgkmcnt(0)
	v_add_f32_e32 v8, v8, v9
	ds_bpermute_b32 v9, v226, v8
	s_waitcnt lgkmcnt(0)
	v_add_f32_e32 v8, v8, v9
	ds_bpermute_b32 v9, v227, v8
	s_waitcnt lgkmcnt(0)
	v_add_f32_e32 v8, v8, v9
	ds_bpermute_b32 v9, v228, v8
	s_waitcnt lgkmcnt(0)
	v_add_f32_e32 v20, v8, v9
	v_fmamk_f32 v7, v20, 0xba000000, v7
	v_fmamk_f32 v15, v20, 0xba000000, v15
	v_fmamk_f32 v5, v20, 0xba000000, v5
	v_fmac_f32_e32 v6, 0xba000000, v20
	v_fmamk_f32 v13, v20, 0xba000000, v13
	v_fmac_f32_e32 v14, 0xba000000, v20
	v_mov_b32_e32 v10, v7
	v_mov_b32_e32 v11, v15
	v_fmac_f32_e32 v4, 0xba000000, v20
	v_fmac_f32_e32 v12, 0xba000000, v20
	v_mov_b32_e32 v8, v6
	v_mov_b32_e32 v9, v14
	v_mul_f32_e32 v10, v10, v10
	v_mul_f32_e32 v11, v11, v11
	v_mov_b32_e32 v16, v5
	v_mov_b32_e32 v17, v13
	v_fma_f32 v8, v8, v8, v10
	v_fma_f32 v9, v9, v9, v11
	v_mov_b32_e32 v10, v4
	v_mov_b32_e32 v11, v12
	v_mul_f32_e32 v16, v16, v16
	v_mul_f32_e32 v17, v17, v17
	v_fmamk_f32 v27, v20, 0xba000000, v27
	v_fma_f32 v10, v10, v10, v16
	v_fma_f32 v11, v11, v11, v17
	v_fmac_f32_e32 v26, 0xba000000, v20
	v_add_f32_e32 v8, v8, v10
	v_add_f32_e32 v9, v9, v11
	v_fmamk_f32 v25, v20, 0xba000000, v25
	v_fmac_f32_e32 v24, 0xba000000, v20
	v_add_f32_e32 v9, v8, v9
	v_add_f32_e32 v8, v8, v8
	v_mul_f32_e32 v10, v24, v24
	v_mul_f32_e32 v11, v25, v25
	v_mul_f32_e32 v16, v26, v26
	v_mul_f32_e32 v17, v27, v27
	v_fmac_f32_e32 v38, 0xba000000, v20
	v_pk_mov_b32 v[18:19], v[16:17], v[10:11] op_sel:[1,0]
	v_mov_b32_e32 v17, v11
	v_fmamk_f32 v39, v20, 0xba000000, v39
	v_fmac_f32_e32 v36, 0xba000000, v20
	v_mul_f32_e32 v8, v38, v38
	v_add_f32_e32 v10, v18, v16
	v_add_f32_e32 v11, v19, v17
	v_fmamk_f32 v37, v20, 0xba000000, v37
	v_fma_f32 v16, v38, v38, v8
	v_fma_f32 v17, v39, v39, v8
	v_mul_f32_e32 v8, v36, v36
	v_add_f32_e32 v11, v10, v11
	v_add_f32_e32 v10, v10, v10
	v_fma_f32 v18, v36, v36, v8
	v_fma_f32 v19, v37, v37, v8
	v_fmamk_f32 v49, v20, 0xba000000, v49
	v_fmac_f32_e32 v48, 0xba000000, v20
	v_fmamk_f32 v51, v20, 0xba000000, v51
	v_fmac_f32_e32 v50, 0xba000000, v20
	v_mul_f32_e32 v16, v50, v50
	v_mul_f32_e32 v18, v51, v51
	v_mul_f32_e32 v10, v48, v48
	v_mul_f32_e32 v8, v49, v49
	v_add_f32_e32 v16, v16, v18
	v_add_f32_e32 v17, v17, v19
	v_add_f32_e32 v8, v10, v8
	v_add_f32_e32 v9, v11, v9
	v_fmamk_f32 v63, v20, 0xba000000, v63
	v_add_f32_e32 v8, v16, v8
	v_add_f32_e32 v9, v17, v9
	v_fmac_f32_e32 v62, 0xba000000, v20
	v_fmamk_f32 v61, v20, 0xba000000, v61
	v_fmac_f32_e32 v60, 0xba000000, v20
	v_add_f32_e32 v9, v8, v9
	v_add_f32_e32 v8, v8, v8
	v_mul_f32_e32 v10, v60, v60
	v_mul_f32_e32 v11, v61, v61
	v_mul_f32_e32 v16, v62, v62
	v_mul_f32_e32 v17, v63, v63
	v_fmac_f32_e32 v74, 0xba000000, v20
	v_pk_mov_b32 v[18:19], v[16:17], v[10:11] op_sel:[1,0]
	v_mov_b32_e32 v17, v11
	v_fmamk_f32 v75, v20, 0xba000000, v75
	v_fmac_f32_e32 v72, 0xba000000, v20
	v_mul_f32_e32 v8, v74, v74
	v_add_f32_e32 v10, v18, v16
	v_add_f32_e32 v11, v19, v17
	v_fmamk_f32 v73, v20, 0xba000000, v73
	v_fma_f32 v16, v74, v74, v8
	v_fma_f32 v17, v75, v75, v8
	v_mul_f32_e32 v8, v72, v72
	v_add_f32_e32 v11, v10, v11
	v_add_f32_e32 v10, v10, v10
	v_fma_f32 v18, v72, v72, v8
	v_fma_f32 v19, v73, v73, v8
	v_fmamk_f32 v1, v20, 0xba000000, v1
	v_fmac_f32_e32 v0, 0xba000000, v20
	v_fmamk_f32 v3, v20, 0xba000000, v3
	v_fmac_f32_e32 v2, 0xba000000, v20
	v_mul_f32_e32 v16, v2, v2
	v_mul_f32_e32 v18, v3, v3
	v_mul_f32_e32 v10, v0, v0
	v_mul_f32_e32 v8, v1, v1
	v_add_f32_e32 v16, v16, v18
	v_add_f32_e32 v17, v17, v19
	v_add_f32_e32 v8, v10, v8
	v_add_f32_e32 v9, v11, v9
	s_nop 0
	v_add_f32_e32 v8, v16, v8
	v_add_f32_e32 v9, v17, v9
	s_nop 0
	v_add_f32_e32 v20, v8, v9
	ds_bpermute_b32 v21, v149, v20
	global_load_dwordx4 v[8:11], v[106:107], off
	global_load_dwordx4 v[16:19], v[108:109], off
	s_waitcnt lgkmcnt(0)
	v_add_f32_e32 v44, v20, v21
	ds_bpermute_b32 v45, v151, v44
	global_load_dwordx4 v[20:23], v[106:107], off offset:1024
	global_load_dwordx4 v[28:31], v[108:109], off offset:1024
	global_load_dwordx4 v[32:35], v[106:107], off offset:2048
	global_load_dwordx4 v[40:43], v[108:109], off offset:2048
	s_waitcnt lgkmcnt(0)
	v_add_f32_e32 v68, v44, v45
	ds_bpermute_b32 v69, v153, v68
	global_load_dwordx4 v[44:47], v[106:107], off offset:3072
	global_load_dwordx4 v[52:55], v[108:109], off offset:3072
	global_load_dwordx4 v[56:59], v[110:111], off
	global_load_dwordx4 v[64:67], v[112:113], off
	s_waitcnt lgkmcnt(0)
	v_add_f32_e32 v88, v68, v69
	ds_bpermute_b32 v89, v226, v88
	global_load_dwordx4 v[68:71], v[114:115], off
	global_load_dwordx4 v[76:79], v[116:117], off
	global_load_dwordx4 v[80:83], v[118:119], off
	global_load_dwordx4 v[84:87], v[120:121], off
	s_waitcnt lgkmcnt(0)
	v_add_f32_e32 v98, v88, v89
	global_load_dwordx4 v[88:91], v[122:123], off
	global_load_dwordx4 v[92:95], v[124:125], off
	ds_bpermute_b32 v148, v227, v98
	s_waitcnt lgkmcnt(0)
	v_add_f32_e32 v98, v98, v148
	ds_bpermute_b32 v148, v228, v98
	s_waitcnt lgkmcnt(0)
	v_add_f32_e32 v98, v98, v148
	v_fmamk_f32 v98, v98, 0x3a000000, v229
	v_mul_f32_e32 v148, 0x4f800000, v98
	v_cmp_gt_f32_e32 vcc, s28, v98
	s_nop 1
	v_cndmask_b32_e32 v98, v98, v148, vcc
	v_sqrt_f32_e32 v148, v98
	s_nop 0
	v_add_u32_e32 v150, -1, v148
	v_fma_f32 v152, -v150, v148, v98
	v_cmp_ge_f32_e64 s[0:1], 0, v152
	v_add_u32_e32 v152, 1, v148
	s_nop 0
	v_cndmask_b32_e64 v150, v148, v150, s[0:1]
	v_fma_f32 v148, -v152, v148, v98
	v_cmp_lt_f32_e64 s[0:1], 0, v148
	s_nop 1
	v_cndmask_b32_e64 v148, v150, v152, s[0:1]
	v_mul_f32_e32 v150, 0x37800000, v148
	v_cndmask_b32_e32 v148, v148, v150, vcc
	v_cmp_class_f32_e32 vcc, v98, v230
	s_nop 1
	v_cndmask_b32_e32 v98, v148, v98, vcc
	v_div_scale_f32 v148, s[0:1], v98, v98, 1.0
	v_rcp_f32_e32 v150, v148
	s_nop 0
	v_fma_f32 v97, -v148, v150, 1.0
	v_fmac_f32_e32 v150, v97, v150
	v_div_scale_f32 v97, vcc, 1.0, v98, 1.0
	v_mul_f32_e32 v152, v97, v150
	v_fma_f32 v156, -v148, v152, v97
	v_fmac_f32_e32 v152, v156, v150
	v_fma_f32 v97, -v148, v152, v97
	v_div_fmas_f32 v97, v97, v150, v152
	v_div_fixup_f32 v98, v97, v98, 1.0
	v_mul_f32_e32 v4, v4, v98
	v_mul_f32_e32 v5, v5, v98
	v_mul_f32_e32 v156, v6, v98
	v_mul_f32_e32 v157, v7, v98
	s_waitcnt vmcnt(14)
	v_fma_f32 v6, v10, v4, v18
	v_fma_f32 v7, v11, v5, v19
	v_mul_f32_e32 v10, v12, v98
	v_mul_f32_e32 v11, v13, v98
	v_mul_f32_e32 v12, v26, v98
	v_mul_f32_e32 v13, v27, v98
	v_mul_f32_e32 v0, v0, v98
	v_mul_f32_e32 v1, v1, v98
	v_fma_f32 v4, v8, v156, v16
	v_fma_f32 v5, v9, v157, v17
	v_mul_f32_e32 v8, v14, v98
	v_mul_f32_e32 v9, v15, v98
	s_waitcnt vmcnt(10)
	v_fma_f32 v12, v32, v12, v40
	v_fma_f32 v13, v33, v13, v41
	v_mul_f32_e32 v32, v2, v98
	v_mul_f32_e32 v33, v3, v98
	v_mul_f32_e32 v14, v24, v98
	v_mul_f32_e32 v15, v25, v98
	v_mul_f32_e32 v16, v38, v98
	v_mul_f32_e32 v17, v39, v98
	v_mul_f32_e32 v18, v36, v98
	v_mul_f32_e32 v19, v37, v98
	v_fma_f32 v10, v22, v10, v30
	v_fma_f32 v11, v23, v11, v31
	v_fma_f32 v8, v20, v8, v28
	v_fma_f32 v9, v21, v9, v29
	v_fma_f32 v14, v34, v14, v42
	v_fma_f32 v15, v35, v15, v43
	s_waitcnt vmcnt(8)
	v_fma_f32 v18, v46, v18, v54
	v_fma_f32 v19, v47, v19, v55
	v_fma_f32 v16, v44, v16, v52
	v_fma_f32 v17, v45, v17, v53
	v_mul_f32_e32 v20, v50, v98
	v_mul_f32_e32 v21, v51, v98
	v_mul_f32_e32 v22, v48, v98
	v_mul_f32_e32 v23, v49, v98
	s_waitcnt vmcnt(6)
	v_fma_f32 v20, v56, v20, v64
	v_fma_f32 v21, v57, v21, v65
	v_fma_f32 v22, v58, v22, v66
	v_fma_f32 v23, v59, v23, v67
	v_mul_f32_e32 v24, v62, v98
	v_mul_f32_e32 v25, v63, v98
	v_mul_f32_e32 v26, v60, v98
	v_mul_f32_e32 v27, v61, v98
	s_waitcnt vmcnt(0)
	v_fma_f32 v2, v90, v0, v94
	v_fma_f32 v3, v91, v1, v95
	v_fma_f32 v0, v88, v32, v92
	v_fma_f32 v1, v89, v33, v93
	v_lshl_add_u64 v[32:33], v[154:155], 2, v[144:145]
	global_store_dwordx4 v[32:33], v[4:7], off
	global_store_dwordx4 v[32:33], v[8:11], off offset:1024
	global_store_dwordx4 v[32:33], v[12:15], off offset:2048
	global_store_dwordx4 v[32:33], v[16:19], off offset:3072
	v_add_co_u32_e32 v4, vcc, s27, v32
	v_mul_f32_e32 v28, v74, v98
	v_mul_f32_e32 v29, v75, v98
	s_nop 0
	v_addc_co_u32_e32 v5, vcc, 0, v33, vcc
	v_cmp_lt_i32_e32 vcc, s29, v96
	v_mul_f32_e32 v30, v72, v98
	v_mul_f32_e32 v31, v73, v98
	s_or_b64 s[12:13], vcc, s[12:13]
	v_fma_f32 v26, v70, v26, v78
	v_fma_f32 v27, v71, v27, v79
	v_fma_f32 v24, v68, v24, v76
	v_fma_f32 v25, v69, v25, v77
	v_fma_f32 v30, v82, v30, v86
	v_fma_f32 v31, v83, v31, v87
	v_fma_f32 v28, v80, v28, v84
	v_fma_f32 v29, v81, v29, v85
	global_store_dwordx4 v[4:5], v[20:23], off
	global_store_dwordx4 v[4:5], v[24:27], off offset:1024
	global_store_dwordx4 v[4:5], v[28:31], off offset:2048
	global_store_dwordx4 v[4:5], v[0:3], off offset:3072
	s_andn2_b64 exec, exec, s[12:13]
	s_cbranch_execz .LBB0_2451

.LBB0_2377:
	v_ashrrev_i32_e32 v13, 31, v12
	v_lshlrev_b64 v[14:15], 17, v[12:13]
	v_lshl_add_u64 v[14:15], v[174:175], 0, v[14:15]
	global_load_dwordx2 v[14:15], v[14:15], off
	s_add_i32 s31, s31, -1
	s_cmp_lg_u32 s31, 0
	v_add_u32_e32 v12, 0x80, v12
	s_waitcnt vmcnt(0)
	v_lshlrev_b32_e32 v16, 16, v14
	v_and_b32_e32 v17, 0xffff0000, v14
	v_lshlrev_b32_e32 v14, 16, v15
	v_and_b32_e32 v15, 0xffff0000, v15
	v_add_f32_e32 v156, v156, v14
	v_add_f32_e32 v157, v157, v15
	v_add_f32_e32 v154, v154, v16
	v_add_f32_e32 v155, v155, v17
	s_cbranch_scc1 .LBB0_2377

.LBB0_2380:
	v_ashrrev_i32_e32 v13, 31, v12
	v_lshlrev_b64 v[14:15], 17, v[12:13]
	v_lshl_add_u64 v[14:15], v[162:163], 0, v[14:15]
	global_load_dwordx2 v[14:15], v[14:15], off
	s_add_i32 s30, s30, -1
	s_cmp_lg_u32 s30, 0
	v_add_u32_e32 v12, 0x80, v12
	s_waitcnt vmcnt(0)
	v_lshlrev_b32_e32 v16, 16, v14
	v_and_b32_e32 v17, 0xffff0000, v14
	v_lshlrev_b32_e32 v14, 16, v15
	v_and_b32_e32 v15, 0xffff0000, v15
	v_add_f32_e32 v160, v160, v14
	v_add_f32_e32 v161, v161, v15
	v_add_f32_e32 v158, v158, v16
	v_add_f32_e32 v159, v159, v17
	s_cbranch_scc1 .LBB0_2380

.LBB0_2387:
	v_ashrrev_i32_e32 v25, 31, v24
	v_lshlrev_b64 v[26:27], 17, v[24:25]
	v_lshl_add_u64 v[26:27], v[174:175], 0, v[26:27]
	global_load_dwordx2 v[26:27], v[26:27], off
	s_add_i32 s31, s31, -1
	s_cmp_lg_u32 s31, 0
	v_add_u32_e32 v24, 0x80, v24
	s_waitcnt vmcnt(0)
	v_lshlrev_b32_e32 v28, 16, v26
	v_and_b32_e32 v29, 0xffff0000, v26
	v_lshlrev_b32_e32 v26, 16, v27
	v_and_b32_e32 v27, 0xffff0000, v27
	v_add_f32_e32 v166, v166, v26
	v_add_f32_e32 v167, v167, v27
	v_add_f32_e32 v164, v164, v28
	v_add_f32_e32 v165, v165, v29
	s_cbranch_scc1 .LBB0_2387

.LBB0_2390:
	v_ashrrev_i32_e32 v25, 31, v24
	v_lshlrev_b64 v[26:27], 17, v[24:25]
	v_lshl_add_u64 v[26:27], v[162:163], 0, v[26:27]
	global_load_dwordx2 v[26:27], v[26:27], off
	s_add_i32 s30, s30, -1
	s_cmp_lg_u32 s30, 0
	v_add_u32_e32 v24, 0x80, v24
	s_waitcnt vmcnt(0)
	v_lshlrev_b32_e32 v28, 16, v26
	v_and_b32_e32 v29, 0xffff0000, v26
	v_lshlrev_b32_e32 v26, 16, v27
	v_and_b32_e32 v27, 0xffff0000, v27
	v_add_f32_e32 v172, v172, v26
	v_add_f32_e32 v173, v173, v27
	v_add_f32_e32 v170, v170, v28
	v_add_f32_e32 v171, v171, v29
	s_cbranch_scc1 .LBB0_2390

.LBB0_2397:
	v_ashrrev_i32_e32 v37, 31, v36
	v_lshlrev_b64 v[38:39], 17, v[36:37]
	v_lshl_add_u64 v[38:39], v[174:175], 0, v[38:39]
	global_load_dwordx2 v[38:39], v[38:39], off
	s_add_i32 s31, s31, -1
	s_cmp_lg_u32 s31, 0
	v_add_u32_e32 v36, 0x80, v36
	s_waitcnt vmcnt(0)
	v_lshlrev_b32_e32 v40, 16, v38
	v_and_b32_e32 v41, 0xffff0000, v38
	v_lshlrev_b32_e32 v38, 16, v39
	v_and_b32_e32 v39, 0xffff0000, v39
	v_add_f32_e32 v180, v180, v38
	v_add_f32_e32 v181, v181, v39
	v_add_f32_e32 v178, v178, v40
	v_add_f32_e32 v179, v179, v41
	s_cbranch_scc1 .LBB0_2397

.LBB0_2400:
	v_ashrrev_i32_e32 v37, 31, v36
	v_lshlrev_b64 v[38:39], 17, v[36:37]
	v_lshl_add_u64 v[38:39], v[162:163], 0, v[38:39]
	global_load_dwordx2 v[38:39], v[38:39], off
	s_add_i32 s30, s30, -1
	s_cmp_lg_u32 s30, 0
	v_add_u32_e32 v36, 0x80, v36
	s_waitcnt vmcnt(0)
	v_lshlrev_b32_e32 v40, 16, v38
	v_and_b32_e32 v41, 0xffff0000, v38
	v_lshlrev_b32_e32 v38, 16, v39
	v_and_b32_e32 v39, 0xffff0000, v39
	v_add_f32_e32 v184, v184, v38
	v_add_f32_e32 v185, v185, v39
	v_add_f32_e32 v182, v182, v40
	v_add_f32_e32 v183, v183, v41
	s_cbranch_scc1 .LBB0_2400

.LBB0_2407:
	v_ashrrev_i32_e32 v49, 31, v48
	v_lshlrev_b64 v[50:51], 17, v[48:49]
	v_lshl_add_u64 v[50:51], v[174:175], 0, v[50:51]
	global_load_dwordx2 v[50:51], v[50:51], off
	s_add_i32 s31, s31, -1
	s_cmp_lg_u32 s31, 0
	v_add_u32_e32 v48, 0x80, v48
	s_waitcnt vmcnt(0)
	v_lshlrev_b32_e32 v52, 16, v50
	v_and_b32_e32 v53, 0xffff0000, v50
	v_lshlrev_b32_e32 v50, 16, v51
	v_and_b32_e32 v51, 0xffff0000, v51
	v_add_f32_e32 v188, v188, v50
	v_add_f32_e32 v189, v189, v51
	v_add_f32_e32 v186, v186, v52
	v_add_f32_e32 v187, v187, v53
	s_cbranch_scc1 .LBB0_2407

.LBB0_2410:
	v_ashrrev_i32_e32 v49, 31, v48
	v_lshlrev_b64 v[50:51], 17, v[48:49]
	v_lshl_add_u64 v[50:51], v[162:163], 0, v[50:51]
	global_load_dwordx2 v[50:51], v[50:51], off
	s_add_i32 s30, s30, -1
	s_cmp_lg_u32 s30, 0
	v_add_u32_e32 v48, 0x80, v48
	s_waitcnt vmcnt(0)
	v_lshlrev_b32_e32 v52, 16, v50
	v_and_b32_e32 v53, 0xffff0000, v50
	v_lshlrev_b32_e32 v50, 16, v51
	v_and_b32_e32 v51, 0xffff0000, v51
	v_add_f32_e32 v192, v192, v50
	v_add_f32_e32 v193, v193, v51
	v_add_f32_e32 v190, v190, v52
	v_add_f32_e32 v191, v191, v53
	s_cbranch_scc1 .LBB0_2410

.LBB0_2417:
	v_ashrrev_i32_e32 v61, 31, v60
	v_lshlrev_b64 v[62:63], 17, v[60:61]
	v_lshl_add_u64 v[62:63], v[174:175], 0, v[62:63]
	global_load_dwordx2 v[62:63], v[62:63], off
	s_add_i32 s31, s31, -1
	s_cmp_lg_u32 s31, 0
	v_add_u32_e32 v60, 0x80, v60
	s_waitcnt vmcnt(0)
	v_lshlrev_b32_e32 v64, 16, v62
	v_and_b32_e32 v65, 0xffff0000, v62
	v_lshlrev_b32_e32 v62, 16, v63
	v_and_b32_e32 v63, 0xffff0000, v63
	v_add_f32_e32 v196, v196, v62
	v_add_f32_e32 v197, v197, v63
	v_add_f32_e32 v194, v194, v64
	v_add_f32_e32 v195, v195, v65
	s_cbranch_scc1 .LBB0_2417

.LBB0_2420:
	v_ashrrev_i32_e32 v61, 31, v60
	v_lshlrev_b64 v[62:63], 17, v[60:61]
	v_lshl_add_u64 v[62:63], v[162:163], 0, v[62:63]
	global_load_dwordx2 v[62:63], v[62:63], off
	s_add_i32 s30, s30, -1
	s_cmp_lg_u32 s30, 0
	v_add_u32_e32 v60, 0x80, v60
	s_waitcnt vmcnt(0)
	v_lshlrev_b32_e32 v64, 16, v62
	v_and_b32_e32 v65, 0xffff0000, v62
	v_lshlrev_b32_e32 v62, 16, v63
	v_and_b32_e32 v63, 0xffff0000, v63
	v_add_f32_e32 v200, v200, v62
	v_add_f32_e32 v201, v201, v63
	v_add_f32_e32 v198, v198, v64
	v_add_f32_e32 v199, v199, v65
	s_cbranch_scc1 .LBB0_2420

.LBB0_2427:
	v_ashrrev_i32_e32 v73, 31, v72
	v_lshlrev_b64 v[74:75], 17, v[72:73]
	v_lshl_add_u64 v[74:75], v[174:175], 0, v[74:75]
	global_load_dwordx2 v[74:75], v[74:75], off
	s_add_i32 s31, s31, -1
	s_cmp_lg_u32 s31, 0
	v_add_u32_e32 v72, 0x80, v72
	s_waitcnt vmcnt(0)
	v_lshlrev_b32_e32 v76, 16, v74
	v_and_b32_e32 v77, 0xffff0000, v74
	v_lshlrev_b32_e32 v74, 16, v75
	v_and_b32_e32 v75, 0xffff0000, v75
	v_add_f32_e32 v204, v204, v74
	v_add_f32_e32 v205, v205, v75
	v_add_f32_e32 v202, v202, v76
	v_add_f32_e32 v203, v203, v77
	s_cbranch_scc1 .LBB0_2427

.LBB0_2430:
	v_ashrrev_i32_e32 v73, 31, v72
	v_lshlrev_b64 v[74:75], 17, v[72:73]
	v_lshl_add_u64 v[74:75], v[162:163], 0, v[74:75]
	global_load_dwordx2 v[74:75], v[74:75], off
	s_add_i32 s30, s30, -1
	s_cmp_lg_u32 s30, 0
	v_add_u32_e32 v72, 0x80, v72
	s_waitcnt vmcnt(0)
	v_lshlrev_b32_e32 v76, 16, v74
	v_and_b32_e32 v77, 0xffff0000, v74
	v_lshlrev_b32_e32 v74, 16, v75
	v_and_b32_e32 v75, 0xffff0000, v75
	v_add_f32_e32 v208, v208, v74
	v_add_f32_e32 v209, v209, v75
	v_add_f32_e32 v206, v206, v76
	v_add_f32_e32 v207, v207, v77
	s_cbranch_scc1 .LBB0_2430

.LBB0_2437:
	v_ashrrev_i32_e32 v91, 31, v90
	v_lshlrev_b64 v[92:93], 17, v[90:91]
	v_lshl_add_u64 v[92:93], v[174:175], 0, v[92:93]
	global_load_dwordx2 v[92:93], v[92:93], off
	s_add_i32 s31, s31, -1
	s_cmp_lg_u32 s31, 0
	v_add_u32_e32 v90, 0x80, v90
	s_waitcnt vmcnt(0)
	v_lshlrev_b32_e32 v94, 16, v92
	v_and_b32_e32 v95, 0xffff0000, v92
	v_lshlrev_b32_e32 v92, 16, v93
	v_and_b32_e32 v93, 0xffff0000, v93
	v_add_f32_e32 v212, v212, v92
	v_add_f32_e32 v213, v213, v93
	v_add_f32_e32 v210, v210, v94
	v_add_f32_e32 v211, v211, v95
	s_cbranch_scc1 .LBB0_2437

.LBB0_2440:
	v_ashrrev_i32_e32 v91, 31, v90
	v_lshlrev_b64 v[92:93], 17, v[90:91]
	v_lshl_add_u64 v[92:93], v[162:163], 0, v[92:93]
	global_load_dwordx2 v[92:93], v[92:93], off
	s_add_i32 s30, s30, -1
	s_cmp_lg_u32 s30, 0
	v_add_u32_e32 v90, 0x80, v90
	s_waitcnt vmcnt(0)
	v_lshlrev_b32_e32 v94, 16, v92
	v_and_b32_e32 v95, 0xffff0000, v92
	v_lshlrev_b32_e32 v92, 16, v93
	v_and_b32_e32 v93, 0xffff0000, v93
	v_add_f32_e32 v216, v216, v92
	v_add_f32_e32 v217, v217, v93
	v_add_f32_e32 v214, v214, v94
	v_add_f32_e32 v215, v215, v95
	s_cbranch_scc1 .LBB0_2440

.LBB0_2447:
	v_ashrrev_i32_e32 v177, 31, v176
	v_lshlrev_b64 v[234:235], 17, v[176:177]
	v_lshl_add_u64 v[234:235], v[174:175], 0, v[234:235]
	global_load_dwordx2 v[234:235], v[234:235], off
	s_add_i32 s21, s21, -1
	s_cmp_lg_u32 s21, 0
	v_add_u32_e32 v176, 0x80, v176
	s_waitcnt vmcnt(0)
	v_lshlrev_b32_e32 v236, 16, v234
	v_and_b32_e32 v237, 0xffff0000, v234
	v_lshlrev_b32_e32 v234, 16, v235
	v_and_b32_e32 v235, 0xffff0000, v235
	v_add_f32_e32 v220, v220, v234
	v_add_f32_e32 v221, v221, v235
	v_add_f32_e32 v218, v218, v236
	v_add_f32_e32 v219, v219, v237
	s_cbranch_scc1 .LBB0_2447

.LBB0_2450:
	v_ashrrev_i32_e32 v169, 31, v168
	v_lshlrev_b64 v[174:175], 17, v[168:169]
	v_lshl_add_u64 v[174:175], v[162:163], 0, v[174:175]
	global_load_dwordx2 v[174:175], v[174:175], off
	s_add_i32 s20, s20, -1
	s_cmp_lg_u32 s20, 0
	v_add_u32_e32 v168, 0x80, v168
	s_waitcnt vmcnt(0)
	v_lshlrev_b32_e32 v176, 16, v174
	v_and_b32_e32 v177, 0xffff0000, v174
	v_lshlrev_b32_e32 v174, 16, v175
	v_and_b32_e32 v175, 0xffff0000, v175
	v_add_f32_e32 v224, v224, v174
	v_add_f32_e32 v225, v225, v175
	v_add_f32_e32 v222, v222, v176
	v_add_f32_e32 v223, v223, v177
	s_cbranch_scc1 .LBB0_2450
	s_branch .LBB0_2370
